# agent-scope (sc1 only) instead of system-scope write-through on the dwordx4 global stores
# baseline (speedup 1.0000x reference)
; #define LAS __attribute__((address_space(3)))
; __device__ __forceinline__ unsigned cvtpk(float lo, float hi) { f32x2 v = {lo, hi}; bf16x2_t b = __builtin_convertvector(v, bf16x2_t); return __builtin_bit_cast(unsigned, b); }
; __device__ __forceinline__ void witem_store(const WItem& w, int K, bf16_t* WT, int kvperm, LAS float* scr, int item, int nblk, int lane) {
;     ...
;     for (int i = 0; i < 8; ++i) { LAS float* d = scr + (8 * i + rr) * 33 + col; const float g = w.g[i]; d[0] = w.v[i].x * g; d[1] = w.v[i].y * g; d[2] = w.v[i].z * g; d[3] = w.v[i].w * g; }
;     asm volatile("s_waitcnt lgkmcnt(0)" ::: "memory");
;     const int c = lane & 7;
; #pragma unroll
;     for (int j = 0; j < 4; ++j) { const int n = (lane >> 3) + 8 * j; const LAS float* s = scr + (8 * c) * 33 + n;
;         u32x4 o; o.x = cvtpk(s[0 * 33], s[1 * 33]); o.y = cvtpk(s[2 * 33], s[3 * 33]); o.z = cvtpk(s[4 * 33], s[5 * 33]); o.w = cvtpk(s[6 * 33], s[7 * 33]);
;         int nr = n0 + n; if (kvperm == 1) { const int hh = nr >> 8, ww = nr & 255; nr = (ww < 128) ? hh * 128 + ww : 2048 + hh * 128 + (ww - 128); }
;         else if (kvperm == 2) { const int isv = nr >= 5632, f = isv ? nr - 5632 : nr; nr = (f >> 7) * 256 + isv * 128 + (f & 127); }
;         *(u32x4*)(WT + (size_t)nr * K + k0 + 8 * c) = o; }
;     ...
;     while (it < i1) {
;         cur = nxt;
;         const int nit = it + NGW;
;         if (nit < i1) witem_load(nxt, W, N, gk, nit, nblk, lane);
;         witem_store(cur, K, WT, kvperm, scr, it, nblk, lane);
;         it = nit;
.LBB0_51:
	v_pk_mul_f32 v[2:3], v[2:3], v[72:73] op_sel_hi:[1,0]
	ds_write2_b32 v79, v2, v3 offset1:1
	v_pk_mul_f32 v[2:3], v[4:5], v[72:73] op_sel_hi:[1,0]
	ds_write2_b32 v79, v2, v3 offset0:2 offset1:3
	v_pk_mul_f32 v[2:3], v[6:7], v[74:75] op_sel_hi:[1,0]
	v_add_u32_e32 v4, 0x420, v79
	ds_write2_b32 v4, v2, v3 offset1:1
	v_pk_mul_f32 v[2:3], v[8:9], v[74:75] op_sel_hi:[1,0]
	v_add_u32_e32 v4, 0x428, v79
	ds_write2_b32 v4, v2, v3 offset1:1
	v_pk_mul_f32 v[2:3], v[10:11], v[76:77] op_sel_hi:[1,0]
	v_add_u32_e32 v4, 0x840, v79
	ds_write2_b32 v4, v2, v3 offset1:1
	v_pk_mul_f32 v[2:3], v[12:13], v[76:77] op_sel_hi:[1,0]
	v_add_u32_e32 v4, 0x848, v79
	ds_write2_b32 v4, v2, v3 offset1:1
	v_pk_mul_f32 v[2:3], v[14:15], v[78:79] op_sel_hi:[1,0]
	v_add_u32_e32 v4, 0xc60, v79
	ds_write2_b32 v4, v2, v3 offset1:1
	v_pk_mul_f32 v[2:3], v[16:17], v[78:79] op_sel_hi:[1,0]
	v_add_u32_e32 v4, 0xc68, v79
	ds_write2_b32 v4, v2, v3 offset1:1
	v_pk_mul_f32 v[2:3], v[18:19], v[80:81] op_sel_hi:[1,0]
	v_add_u32_e32 v4, 0x1080, v79
	ds_write2_b32 v4, v2, v3 offset1:1
	v_pk_mul_f32 v[2:3], v[20:21], v[80:81] op_sel_hi:[1,0]
	v_add_u32_e32 v4, 0x1088, v79
	ds_write2_b32 v4, v2, v3 offset1:1
	s_waitcnt vmcnt(0)
	v_pk_mul_f32 v[2:3], v[22:23], v[84:85] op_sel_hi:[1,0]
	v_add_u32_e32 v4, 0x14a0, v79
	ds_write2_b32 v4, v2, v3 offset1:1
	v_pk_mul_f32 v[2:3], v[24:25], v[84:85] op_sel_hi:[1,0]
	v_add_u32_e32 v4, 0x14a8, v79
	ds_write2_b32 v4, v2, v3 offset1:1
	v_pk_mul_f32 v[2:3], v[26:27], v[88:89] op_sel_hi:[1,0]
	v_add_u32_e32 v4, 0x18c0, v79
	s_mul_hi_i32 s4, s20, 0x66666667
	ds_write2_b32 v4, v2, v3 offset1:1
	v_pk_mul_f32 v[2:3], v[28:29], v[88:89] op_sel_hi:[1,0]
	v_add_u32_e32 v4, 0x18c8, v79
	s_lshr_b32 s5, s4, 31
	s_ashr_i32 s4, s4, 4
	ds_write2_b32 v4, v2, v3 offset1:1
	v_pk_mul_f32 v[2:3], v[34:35], v[90:91] op_sel_hi:[1,0]
	v_add_u32_e32 v4, 0x1ce0, v79
	s_add_i32 s6, s4, s5
	ds_write2_b32 v4, v2, v3 offset1:1
	v_pk_mul_f32 v[2:3], v[36:37], v[90:91] op_sel_hi:[1,0]
	v_add_u32_e32 v4, 0x1ce8, v79
	s_lshl_b32 s4, s6, 6
	ds_write2_b32 v4, v2, v3 offset1:1
	s_waitcnt lgkmcnt(0)
	s_ashr_i32 s5, s4, 31
	ds_read2_b32 v[6:7], v77 offset0:33 offset1:41
	ds_read2_b32 v[8:9], v77 offset1:8
	ds_read2_b32 v[10:11], v77 offset0:66 offset1:74
	ds_read2_b32 v[12:13], v77 offset0:99 offset1:107
	ds_read2_b32 v[14:15], v77 offset0:132 offset1:140
	ds_read2_b32 v[16:17], v77 offset0:165 offset1:173
	ds_read2_b32 v[18:19], v77 offset0:198 offset1:206
	ds_read2_b32 v[20:21], v77 offset0:231 offset1:239
	v_lshl_add_u64 v[22:23], s[4:5], 1, v[86:87]
	s_mul_i32 s4, s6, 0xfffffb00
	s_add_i32 s4, s4, s21
	v_add_u32_e32 v24, s4, v81
	v_ashrrev_i32_e32 v25, 31, v24
	v_lshlrev_b64 v[26:27], 12, v[24:25]
	s_waitcnt lgkmcnt(6)
	v_cvt_pk_bf16_f32 v2, v8, v6
	s_waitcnt lgkmcnt(4)
	v_cvt_pk_bf16_f32 v3, v10, v12
	s_waitcnt lgkmcnt(2)
	v_cvt_pk_bf16_f32 v4, v14, v16
	s_waitcnt lgkmcnt(0)
	v_cvt_pk_bf16_f32 v5, v18, v20
	v_lshl_add_u64 v[26:27], v[22:23], 0, v[26:27]
	v_add_u32_e32 v6, 8, v24
	global_store_dwordx4 v[26:27], v[2:5], off sc1
	v_mov_b64_e32 v[34:35], v[66:67]
	v_add_u32_e32 v81, s25, v81
	v_cvt_pk_bf16_f32 v2, v9, v7
	v_ashrrev_i32_e32 v7, 31, v6
	v_cvt_pk_bf16_f32 v3, v11, v13
	v_cvt_pk_bf16_f32 v4, v15, v17
	v_cvt_pk_bf16_f32 v5, v19, v21
	v_lshlrev_b64 v[6:7], 12, v[6:7]
	ds_read2_b32 v[8:9], v77 offset0:49 offset1:57
	ds_read2_b32 v[10:11], v77 offset0:16 offset1:24
	ds_read2_b32 v[12:13], v77 offset0:82 offset1:90
	ds_read2_b32 v[14:15], v77 offset0:115 offset1:123
	ds_read2_b32 v[16:17], v77 offset0:148 offset1:156
	ds_read2_b32 v[18:19], v77 offset0:181 offset1:189
	ds_read2_b32 v[20:21], v77 offset0:214 offset1:222
	ds_read2_b32 v[26:27], v77 offset0:247 offset1:255
	v_lshl_add_u64 v[6:7], v[22:23], 0, v[6:7]
	global_store_dwordx4 v[6:7], v[2:5], off sc1
	v_add_u32_e32 v6, 16, v24
	v_ashrrev_i32_e32 v7, 31, v6
	v_lshlrev_b64 v[6:7], 12, v[6:7]
	s_waitcnt lgkmcnt(6)
	v_cvt_pk_bf16_f32 v2, v10, v8
	s_waitcnt lgkmcnt(4)
	v_cvt_pk_bf16_f32 v3, v12, v14
	s_waitcnt lgkmcnt(2)
	v_cvt_pk_bf16_f32 v4, v16, v18
	s_waitcnt lgkmcnt(0)
	v_cvt_pk_bf16_f32 v5, v20, v26
	v_lshl_add_u64 v[6:7], v[22:23], 0, v[6:7]
	global_store_dwordx4 v[6:7], v[2:5], off sc1
	v_add_u32_e32 v6, 24, v24
	v_ashrrev_i32_e32 v7, 31, v6
	v_lshlrev_b64 v[6:7], 12, v[6:7]
	v_cvt_pk_bf16_f32 v2, v11, v9
	v_cvt_pk_bf16_f32 v3, v13, v15
	v_cvt_pk_bf16_f32 v4, v17, v19
	v_cvt_pk_bf16_f32 v5, v21, v27
	v_lshl_add_u64 v[6:7], v[22:23], 0, v[6:7]
	global_store_dwordx4 v[6:7], v[2:5], off sc1
	s_waitcnt lgkmcnt(0)
	v_mov_b64_e32 v[6:7], v[42:43]
	v_mov_b64_e32 v[10:11], v[46:47]
	v_mov_b64_e32 v[2:3], v[38:39]
	v_mov_b64_e32 v[14:15], v[50:51]
	v_mov_b64_e32 v[18:19], v[54:55]
	v_mov_b64_e32 v[22:23], v[58:59]
	v_mov_b64_e32 v[26:27], v[62:63]
	s_add_i32 s29, s29, s25
	v_add_u32_e32 v73, s25, v73
	s_andn2_b64 vcc, exec, s[16:17]
	s_mov_b32 s20, s30
	v_mov_b64_e32 v[4:5], v[40:41]
	v_mov_b64_e32 v[8:9], v[44:45]
	v_mov_b64_e32 v[12:13], v[48:49]
	v_mov_b64_e32 v[16:17], v[52:53]
	v_mov_b64_e32 v[20:21], v[56:57]
	v_mov_b64_e32 v[24:25], v[60:61]
	v_mov_b64_e32 v[28:29], v[64:65]
	v_mov_b64_e32 v[36:37], v[68:69]
	v_mov_b32_e32 v72, v85
	v_mov_b32_e32 v74, v91
	v_mov_b32_e32 v76, v96
	v_mov_b32_e32 v78, v97
	v_mov_b32_e32 v80, v98
	v_mov_b32_e32 v84, v99
	v_mov_b32_e32 v88, v100
	v_mov_b32_e32 v90, v31
	s_cbranch_vccz .LBB0_91

; #define LAS __attribute__((address_space(3)))
; __device__ __forceinline__ unsigned cvtpk(float lo, float hi) { f32x2 v = {lo, hi}; bf16x2_t b = __builtin_convertvector(v, bf16x2_t); return __builtin_bit_cast(unsigned, b); }
; __device__ __forceinline__ void witem_store(const WItem& w, int K, bf16_t* WT, int kvperm, LAS float* scr, int item, int nblk, int lane) {
;     ...
;     for (int i = 0; i < 8; ++i) { LAS float* d = scr + (8 * i + rr) * 33 + col; const float g = w.g[i]; d[0] = w.v[i].x * g; d[1] = w.v[i].y * g; d[2] = w.v[i].z * g; d[3] = w.v[i].w * g; }
;     asm volatile("s_waitcnt lgkmcnt(0)" ::: "memory");
;     const int c = lane & 7;
; #pragma unroll
;     for (int j = 0; j < 4; ++j) { const int n = (lane >> 3) + 8 * j; const LAS float* s = scr + (8 * c) * 33 + n;
;         u32x4 o; o.x = cvtpk(s[0 * 33], s[1 * 33]); o.y = cvtpk(s[2 * 33], s[3 * 33]); o.z = cvtpk(s[4 * 33], s[5 * 33]); o.w = cvtpk(s[6 * 33], s[7 * 33]);
;         int nr = n0 + n; if (kvperm == 1) { const int hh = nr >> 8, ww = nr & 255; nr = (ww < 128) ? hh * 128 + ww : 2048 + hh * 128 + (ww - 128); }
;         else if (kvperm == 2) { const int isv = nr >= 5632, f = isv ? nr - 5632 : nr; nr = (f >> 7) * 256 + isv * 128 + (f & 127); }
;         *(u32x4*)(WT + (size_t)nr * K + k0 + 8 * c) = o; }
;     asm volatile("s_waitcnt lgkmcnt(0)" ::: "memory");
.LBB0_136:
	v_pk_mul_f32 v[2:3], v[2:3], v[72:73] op_sel_hi:[1,0]
	ds_write2_b32 v79, v2, v3 offset1:1
	v_pk_mul_f32 v[2:3], v[4:5], v[72:73] op_sel_hi:[1,0]
	ds_write2_b32 v79, v2, v3 offset0:2 offset1:3
	v_pk_mul_f32 v[2:3], v[6:7], v[74:75] op_sel_hi:[1,0]
	v_add_u32_e32 v4, 0x420, v79
	ds_write2_b32 v4, v2, v3 offset1:1
	v_pk_mul_f32 v[2:3], v[8:9], v[74:75] op_sel_hi:[1,0]
	v_add_u32_e32 v4, 0x428, v79
	ds_write2_b32 v4, v2, v3 offset1:1
	v_pk_mul_f32 v[2:3], v[10:11], v[76:77] op_sel_hi:[1,0]
	v_add_u32_e32 v4, 0x840, v79
	ds_write2_b32 v4, v2, v3 offset1:1
	v_pk_mul_f32 v[2:3], v[12:13], v[76:77] op_sel_hi:[1,0]
	v_add_u32_e32 v4, 0x848, v79
	ds_write2_b32 v4, v2, v3 offset1:1
	v_pk_mul_f32 v[2:3], v[14:15], v[78:79] op_sel_hi:[1,0]
	v_add_u32_e32 v4, 0xc60, v79
	ds_write2_b32 v4, v2, v3 offset1:1
	v_pk_mul_f32 v[2:3], v[16:17], v[78:79] op_sel_hi:[1,0]
	v_add_u32_e32 v4, 0xc68, v79
	ds_write2_b32 v4, v2, v3 offset1:1
	v_pk_mul_f32 v[2:3], v[18:19], v[80:81] op_sel_hi:[1,0]
	v_add_u32_e32 v4, 0x1080, v79
	ds_write2_b32 v4, v2, v3 offset1:1
	v_pk_mul_f32 v[2:3], v[20:21], v[80:81] op_sel_hi:[1,0]
	v_add_u32_e32 v4, 0x1088, v79
	ds_write2_b32 v4, v2, v3 offset1:1
	s_waitcnt vmcnt(0)
	v_pk_mul_f32 v[2:3], v[22:23], v[84:85] op_sel_hi:[1,0]
	v_add_u32_e32 v4, 0x14a0, v79
	ds_write2_b32 v4, v2, v3 offset1:1
	v_pk_mul_f32 v[2:3], v[24:25], v[84:85] op_sel_hi:[1,0]
	v_add_u32_e32 v4, 0x14a8, v79
	ds_write2_b32 v4, v2, v3 offset1:1
	v_pk_mul_f32 v[2:3], v[26:27], v[88:89] op_sel_hi:[1,0]
	v_add_u32_e32 v4, 0x18c0, v79
	s_mul_hi_i32 s4, s26, 0x2aaaaaab
	ds_write2_b32 v4, v2, v3 offset1:1
	v_pk_mul_f32 v[2:3], v[28:29], v[88:89] op_sel_hi:[1,0]
	v_add_u32_e32 v4, 0x18c8, v79
	s_lshr_b32 s5, s4, 31
	s_ashr_i32 s4, s4, 4
	ds_write2_b32 v4, v2, v3 offset1:1
	v_pk_mul_f32 v[2:3], v[34:35], v[90:91] op_sel_hi:[1,0]
	v_add_u32_e32 v4, 0x1ce0, v79
	s_add_i32 s6, s4, s5
	ds_write2_b32 v4, v2, v3 offset1:1
	v_pk_mul_f32 v[2:3], v[36:37], v[90:91] op_sel_hi:[1,0]
	v_add_u32_e32 v4, 0x1ce8, v79
	s_lshl_b32 s4, s6, 6
	ds_write2_b32 v4, v2, v3 offset1:1
	s_waitcnt lgkmcnt(0)
	s_ashr_i32 s5, s4, 31
	ds_read2_b32 v[6:7], v77 offset0:33 offset1:41
	ds_read2_b32 v[8:9], v77 offset1:8
	ds_read2_b32 v[10:11], v77 offset0:66 offset1:74
	ds_read2_b32 v[12:13], v77 offset0:99 offset1:107
	ds_read2_b32 v[14:15], v77 offset0:132 offset1:140
	ds_read2_b32 v[16:17], v77 offset0:165 offset1:173
	ds_read2_b32 v[18:19], v77 offset0:198 offset1:206
	ds_read2_b32 v[20:21], v77 offset0:231 offset1:239
	v_lshl_add_u64 v[22:23], s[4:5], 1, v[86:87]
	s_mul_i32 s4, s6, 0xfffff400
	s_add_i32 s4, s4, s28
	v_add_u32_e32 v24, s4, v81
	v_ashrrev_i32_e32 v25, 31, v24
	v_lshlrev_b64 v[26:27], 10, v[24:25]
	s_waitcnt lgkmcnt(6)
	v_cvt_pk_bf16_f32 v2, v8, v6
	s_waitcnt lgkmcnt(4)
	v_cvt_pk_bf16_f32 v3, v10, v12
	s_waitcnt lgkmcnt(2)
	v_cvt_pk_bf16_f32 v4, v14, v16
	s_waitcnt lgkmcnt(0)
	v_cvt_pk_bf16_f32 v5, v18, v20
	v_lshl_add_u64 v[26:27], v[22:23], 0, v[26:27]
	v_add_u32_e32 v6, 8, v24
	global_store_dwordx4 v[26:27], v[2:5], off sc1
	v_mov_b64_e32 v[34:35], v[66:67]
	v_add_u32_e32 v81, s29, v81
	v_cvt_pk_bf16_f32 v2, v9, v7
	v_ashrrev_i32_e32 v7, 31, v6
	v_cvt_pk_bf16_f32 v3, v11, v13
	v_cvt_pk_bf16_f32 v4, v15, v17
	v_cvt_pk_bf16_f32 v5, v19, v21
	v_lshlrev_b64 v[6:7], 10, v[6:7]
	ds_read2_b32 v[8:9], v77 offset0:49 offset1:57
	ds_read2_b32 v[10:11], v77 offset0:16 offset1:24
	ds_read2_b32 v[12:13], v77 offset0:82 offset1:90
	ds_read2_b32 v[14:15], v77 offset0:115 offset1:123
	ds_read2_b32 v[16:17], v77 offset0:148 offset1:156
	ds_read2_b32 v[18:19], v77 offset0:181 offset1:189
	ds_read2_b32 v[20:21], v77 offset0:214 offset1:222
	ds_read2_b32 v[26:27], v77 offset0:247 offset1:255
	v_lshl_add_u64 v[6:7], v[22:23], 0, v[6:7]
	global_store_dwordx4 v[6:7], v[2:5], off sc1
	v_add_u32_e32 v6, 16, v24
	v_ashrrev_i32_e32 v7, 31, v6
	v_lshlrev_b64 v[6:7], 10, v[6:7]
	s_waitcnt lgkmcnt(6)
	v_cvt_pk_bf16_f32 v2, v10, v8
	s_waitcnt lgkmcnt(4)
	v_cvt_pk_bf16_f32 v3, v12, v14
	s_waitcnt lgkmcnt(2)
	v_cvt_pk_bf16_f32 v4, v16, v18
	s_waitcnt lgkmcnt(0)
	v_cvt_pk_bf16_f32 v5, v20, v26
	v_lshl_add_u64 v[6:7], v[22:23], 0, v[6:7]
	global_store_dwordx4 v[6:7], v[2:5], off sc1
	v_add_u32_e32 v6, 24, v24
	v_ashrrev_i32_e32 v7, 31, v6
	v_lshlrev_b64 v[6:7], 10, v[6:7]
	v_cvt_pk_bf16_f32 v2, v11, v9
	v_cvt_pk_bf16_f32 v3, v13, v15
	v_cvt_pk_bf16_f32 v4, v17, v19
	v_cvt_pk_bf16_f32 v5, v21, v27
	v_lshl_add_u64 v[6:7], v[22:23], 0, v[6:7]
	global_store_dwordx4 v[6:7], v[2:5], off sc1
	s_waitcnt lgkmcnt(0)
	v_mov_b64_e32 v[6:7], v[42:43]
	v_mov_b64_e32 v[10:11], v[46:47]
	v_mov_b64_e32 v[2:3], v[38:39]
	v_mov_b64_e32 v[14:15], v[50:51]
	v_mov_b64_e32 v[18:19], v[54:55]
	v_mov_b64_e32 v[22:23], v[58:59]
	v_mov_b64_e32 v[26:27], v[62:63]
	s_add_i32 s34, s34, s29
	v_add_u32_e32 v73, s29, v73
	s_andn2_b64 vcc, exec, s[18:19]
	s_mov_b32 s26, s35
	v_mov_b64_e32 v[4:5], v[40:41]
	v_mov_b64_e32 v[8:9], v[44:45]
	v_mov_b64_e32 v[12:13], v[48:49]
	v_mov_b64_e32 v[16:17], v[52:53]
	v_mov_b64_e32 v[20:21], v[56:57]
	v_mov_b64_e32 v[24:25], v[60:61]
	v_mov_b64_e32 v[28:29], v[64:65]
	v_mov_b64_e32 v[36:37], v[68:69]
	v_mov_b32_e32 v72, v85
	v_mov_b32_e32 v74, v91
	v_mov_b32_e32 v76, v96
	v_mov_b32_e32 v78, v97
	v_mov_b32_e32 v80, v98
	v_mov_b32_e32 v84, v99
	v_mov_b32_e32 v88, v100
	v_mov_b32_e32 v90, v31
	s_cbranch_vccz .LBB0_176

; #define LAS __attribute__((address_space(3)))
; __device__ __forceinline__ unsigned cvtpk(float lo, float hi) { f32x2 v = {lo, hi}; bf16x2_t b = __builtin_convertvector(v, bf16x2_t); return __builtin_bit_cast(unsigned, b); }
; __device__ __forceinline__ void witem_store(const WItem& w, int K, bf16_t* WT, int kvperm, LAS float* scr, int item, int nblk, int lane) {
;     ...
;     for (int i = 0; i < 8; ++i) { LAS float* d = scr + (8 * i + rr) * 33 + col; const float g = w.g[i]; d[0] = w.v[i].x * g; d[1] = w.v[i].y * g; d[2] = w.v[i].z * g; d[3] = w.v[i].w * g; }
;     asm volatile("s_waitcnt lgkmcnt(0)" ::: "memory");
;     const int c = lane & 7;
; #pragma unroll
;     for (int j = 0; j < 4; ++j) { const int n = (lane >> 3) + 8 * j; const LAS float* s = scr + (8 * c) * 33 + n;
;         u32x4 o; o.x = cvtpk(s[0 * 33], s[1 * 33]); o.y = cvtpk(s[2 * 33], s[3 * 33]); o.z = cvtpk(s[4 * 33], s[5 * 33]); o.w = cvtpk(s[6 * 33], s[7 * 33]);
;         int nr = n0 + n; if (kvperm == 1) { const int hh = nr >> 8, ww = nr & 255; nr = (ww < 128) ? hh * 128 + ww : 2048 + hh * 128 + (ww - 128); }
;         else if (kvperm == 2) { const int isv = nr >= 5632, f = isv ? nr - 5632 : nr; nr = (f >> 7) * 256 + isv * 128 + (f & 127); }
;         *(u32x4*)(WT + (size_t)nr * K + k0 + 8 * c) = o; }
;     asm volatile("s_waitcnt lgkmcnt(0)" ::: "memory");
.LBB0_221:
	v_pk_mul_f32 v[2:3], v[2:3], v[72:73] op_sel_hi:[1,0]
	ds_write2_b32 v91, v2, v3 offset1:1
	v_pk_mul_f32 v[2:3], v[4:5], v[72:73] op_sel_hi:[1,0]
	ds_write2_b32 v91, v2, v3 offset0:2 offset1:3
	v_pk_mul_f32 v[2:3], v[6:7], v[74:75] op_sel_hi:[1,0]
	v_add_u32_e32 v4, 0x420, v91
	ds_write2_b32 v4, v2, v3 offset1:1
	v_pk_mul_f32 v[2:3], v[8:9], v[74:75] op_sel_hi:[1,0]
	v_add_u32_e32 v4, 0x428, v91
	ds_write2_b32 v4, v2, v3 offset1:1
	v_pk_mul_f32 v[2:3], v[10:11], v[76:77] op_sel_hi:[1,0]
	v_add_u32_e32 v4, 0x840, v91
	ds_write2_b32 v4, v2, v3 offset1:1
	v_pk_mul_f32 v[2:3], v[12:13], v[76:77] op_sel_hi:[1,0]
	v_add_u32_e32 v4, 0x848, v91
	ds_write2_b32 v4, v2, v3 offset1:1
	v_pk_mul_f32 v[2:3], v[14:15], v[78:79] op_sel_hi:[1,0]
	v_add_u32_e32 v4, 0xc60, v91
	ds_write2_b32 v4, v2, v3 offset1:1
	v_pk_mul_f32 v[2:3], v[16:17], v[78:79] op_sel_hi:[1,0]
	v_add_u32_e32 v4, 0xc68, v91
	ds_write2_b32 v4, v2, v3 offset1:1
	v_pk_mul_f32 v[2:3], v[18:19], v[80:81] op_sel_hi:[1,0]
	v_add_u32_e32 v4, 0x1080, v91
	s_ashr_i32 s4, s26, 31
	ds_write2_b32 v4, v2, v3 offset1:1
	v_pk_mul_f32 v[2:3], v[20:21], v[80:81] op_sel_hi:[1,0]
	v_add_u32_e32 v4, 0x1088, v91
	s_lshr_b32 s4, s4, 25
	ds_write2_b32 v4, v2, v3 offset1:1
	v_pk_mul_f32 v[2:3], v[22:23], v[86:87] op_sel_hi:[1,0]
	v_add_u32_e32 v4, 0x14a0, v91
	s_add_i32 s4, s26, s4
	ds_write2_b32 v4, v2, v3 offset1:1
	v_pk_mul_f32 v[2:3], v[24:25], v[86:87] op_sel_hi:[1,0]
	v_add_u32_e32 v4, 0x14a8, v91
	s_ashr_i32 s6, s4, 7
	ds_write2_b32 v4, v2, v3 offset1:1
	v_pk_mul_f32 v[2:3], v[30:31], v[88:89] op_sel_hi:[1,0]
	v_add_u32_e32 v4, 0x18c0, v91
	s_lshl_b32 s4, s6, 6
	ds_write2_b32 v4, v2, v3 offset1:1
	v_pk_mul_f32 v[2:3], v[32:33], v[88:89] op_sel_hi:[1,0]
	v_add_u32_e32 v4, 0x18c8, v91
	ds_write2_b32 v4, v2, v3 offset1:1
	v_pk_mul_f32 v[2:3], v[34:35], v[90:91] op_sel_hi:[1,0]
	v_add_u32_e32 v4, 0x1ce0, v91
	s_ashr_i32 s5, s4, 31
	ds_write2_b32 v4, v2, v3 offset1:1
	v_pk_mul_f32 v[2:3], v[36:37], v[90:91] op_sel_hi:[1,0]
	v_add_u32_e32 v4, 0x1ce8, v91
	v_lshl_add_u64 v[6:7], s[4:5], 1, v[84:85]
	s_lshl_b32 s4, s6, 11
	ds_write2_b32 v4, v2, v3 offset1:1
	s_sub_i32 s4, s29, s4
	s_waitcnt lgkmcnt(0)
	s_and_b32 s4, s4, 0xffffff80
	ds_read2_b32 v[8:9], v81 offset0:33 offset1:41
	ds_read2_b32 v[10:11], v81 offset1:8
	ds_read2_b32 v[12:13], v81 offset0:66 offset1:74
	ds_read2_b32 v[14:15], v81 offset0:99 offset1:107
	ds_read2_b32 v[16:17], v81 offset0:132 offset1:140
	ds_read2_b32 v[18:19], v81 offset0:165 offset1:173
	ds_read2_b32 v[20:21], v81 offset0:198 offset1:206
	ds_read2_b32 v[22:23], v81 offset0:231 offset1:239
	s_add_i32 s5, s4, 0x780
	s_and_b32 s6, s35, 0xe0
	s_waitcnt lgkmcnt(6)
	v_cvt_pk_bf16_f32 v2, v10, v8
	v_or_b32_e32 v8, s6, v73
	s_cmpk_lt_u32 s6, 0x80
	v_or_b32_e32 v10, s4, v8
	v_add_u32_e32 v8, s5, v8
	s_cselect_b64 vcc, -1, 0
	v_cndmask_b32_e32 v24, v8, v10, vcc
	v_ashrrev_i32_e32 v25, 31, v24
	v_lshlrev_b64 v[24:25], 10, v[24:25]
	s_waitcnt lgkmcnt(4)
	v_cvt_pk_bf16_f32 v3, v12, v14
	s_waitcnt lgkmcnt(2)
	v_cvt_pk_bf16_f32 v4, v16, v18
	s_waitcnt lgkmcnt(0)
	v_cvt_pk_bf16_f32 v5, v20, v22
	v_lshl_add_u64 v[24:25], v[6:7], 0, v[24:25]
	v_or_b32_e32 v8, s6, v75
	global_store_dwordx4 v[24:25], v[2:5], off sc1
	s_waitcnt vmcnt(1)
	v_mov_b64_e32 v[30:31], v[62:63]
	v_mov_b64_e32 v[34:35], v[66:67]
	v_cvt_pk_bf16_f32 v2, v11, v9
	v_or_b32_e32 v9, s4, v8
	v_add_u32_e32 v8, s5, v8
	v_cndmask_b32_e32 v8, v8, v9, vcc
	v_ashrrev_i32_e32 v9, 31, v8
	v_lshlrev_b64 v[8:9], 10, v[8:9]
	v_cvt_pk_bf16_f32 v3, v13, v15
	v_cvt_pk_bf16_f32 v4, v17, v19
	v_cvt_pk_bf16_f32 v5, v21, v23
	v_lshl_add_u64 v[8:9], v[6:7], 0, v[8:9]
	ds_read2_b32 v[10:11], v81 offset0:49 offset1:57
	ds_read2_b32 v[12:13], v81 offset0:16 offset1:24
	ds_read2_b32 v[14:15], v81 offset0:82 offset1:90
	ds_read2_b32 v[16:17], v81 offset0:115 offset1:123
	ds_read2_b32 v[18:19], v81 offset0:148 offset1:156
	ds_read2_b32 v[20:21], v81 offset0:181 offset1:189
	ds_read2_b32 v[22:23], v81 offset0:214 offset1:222
	ds_read2_b32 v[24:25], v81 offset0:247 offset1:255
	global_store_dwordx4 v[8:9], v[2:5], off sc1
	v_or_b32_e32 v8, s6, v77
	v_or_b32_e32 v9, s4, v8
	v_add_u32_e32 v8, s5, v8
	v_cndmask_b32_e32 v8, v8, v9, vcc
	v_ashrrev_i32_e32 v9, 31, v8
	v_lshlrev_b64 v[8:9], 10, v[8:9]
	s_waitcnt lgkmcnt(6)
	v_cvt_pk_bf16_f32 v2, v12, v10
	s_waitcnt lgkmcnt(4)
	v_cvt_pk_bf16_f32 v3, v14, v16
	s_waitcnt lgkmcnt(2)
	v_cvt_pk_bf16_f32 v4, v18, v20
	s_waitcnt lgkmcnt(0)
	v_cvt_pk_bf16_f32 v5, v22, v24
	v_lshl_add_u64 v[8:9], v[6:7], 0, v[8:9]
	global_store_dwordx4 v[8:9], v[2:5], off sc1
	s_add_i32 s29, s29, s30
	s_mov_b32 s35, s34
	v_or_b32_e32 v2, s6, v79
	v_or_b32_e32 v3, s4, v2
	v_add_u32_e32 v2, s5, v2
	v_cndmask_b32_e32 v8, v2, v3, vcc
	v_ashrrev_i32_e32 v9, 31, v8
	v_lshlrev_b64 v[8:9], 10, v[8:9]
	v_cvt_pk_bf16_f32 v2, v13, v11
	v_cvt_pk_bf16_f32 v3, v15, v17
	v_cvt_pk_bf16_f32 v4, v19, v21
	v_cvt_pk_bf16_f32 v5, v23, v25
	v_lshl_add_u64 v[6:7], v[6:7], 0, v[8:9]
	global_store_dwordx4 v[6:7], v[2:5], off sc1
	s_waitcnt lgkmcnt(0)
	v_mov_b64_e32 v[6:7], v[42:43]
	v_mov_b64_e32 v[10:11], v[46:47]
	v_mov_b64_e32 v[2:3], v[38:39]
	v_mov_b64_e32 v[14:15], v[50:51]
	v_mov_b64_e32 v[18:19], v[54:55]
	v_mov_b64_e32 v[22:23], v[58:59]
	s_andn2_b64 vcc, exec, s[18:19]
	s_mov_b32 s26, s33
	v_mov_b64_e32 v[4:5], v[40:41]
	v_mov_b64_e32 v[8:9], v[44:45]
	v_mov_b64_e32 v[12:13], v[48:49]
	v_mov_b64_e32 v[16:17], v[52:53]
	v_mov_b64_e32 v[20:21], v[56:57]
	v_mov_b64_e32 v[24:25], v[60:61]
	v_mov_b64_e32 v[32:33], v[64:65]
	v_mov_b64_e32 v[36:37], v[68:69]
	v_mov_b32_e32 v72, v96
	v_mov_b32_e32 v74, v97
	v_mov_b32_e32 v76, v98
	v_mov_b32_e32 v78, v99
	v_mov_b32_e32 v80, v100
	v_mov_b32_e32 v86, v101
	v_mov_b32_e32 v88, v102
	v_mov_b32_e32 v90, v27
	s_cbranch_vccz .LBB0_263

; #define LAS __attribute__((address_space(3)))
; __device__ __forceinline__ unsigned cvtpk(float lo, float hi) { f32x2 v = {lo, hi}; bf16x2_t b = __builtin_convertvector(v, bf16x2_t); return __builtin_bit_cast(unsigned, b); }
; __device__ __forceinline__ void witem_store(const WItem& w, int K, bf16_t* WT, int kvperm, LAS float* scr, int item, int nblk, int lane) {
;     ...
; #pragma unroll
;     for (int j = 0; j < 4; ++j) { const int n = (lane >> 3) + 8 * j; const LAS float* s = scr + (8 * c) * 33 + n;
;         u32x4 o; o.x = cvtpk(s[0 * 33], s[1 * 33]); o.y = cvtpk(s[2 * 33], s[3 * 33]); o.z = cvtpk(s[4 * 33], s[5 * 33]); o.w = cvtpk(s[6 * 33], s[7 * 33]);
;         int nr = n0 + n; if (kvperm == 1) { const int hh = nr >> 8, ww = nr & 255; nr = (ww < 128) ? hh * 128 + ww : 2048 + hh * 128 + (ww - 128); }
;         else if (kvperm == 2) { const int isv = nr >= 5632, f = isv ? nr - 5632 : nr; nr = (f >> 7) * 256 + isv * 128 + (f & 127); }
;         *(u32x4*)(WT + (size_t)nr * K + k0 + 8 * c) = o; }
;     asm volatile("s_waitcnt lgkmcnt(0)" ::: "memory");
.LBB0_282:
	ds_write2_b32 v83, v6, v7 offset1:1
	ds_write2_b32 v83, v8, v9 offset0:2 offset1:3
	v_add_u32_e32 v6, 0x420, v83
	ds_write2_b32 v6, v2, v3 offset1:1
	v_add_u32_e32 v2, 0x428, v83
	ds_write2_b32 v2, v4, v5 offset1:1
	v_add_u32_e32 v2, 0x840, v83
	ds_write2_b32 v2, v14, v15 offset1:1
	v_add_u32_e32 v2, 0x848, v83
	ds_write2_b32 v2, v16, v17 offset1:1
	v_add_u32_e32 v2, 0xc60, v83
	ds_write2_b32 v2, v10, v11 offset1:1
	v_add_u32_e32 v2, 0xc68, v83
	ds_write2_b32 v2, v12, v13 offset1:1
	v_add_u32_e32 v2, 0x1080, v83
	ds_write2_b32 v2, v26, v27 offset1:1
	v_add_u32_e32 v2, 0x1088, v83
	ds_write2_b32 v2, v28, v29 offset1:1
	v_add_u32_e32 v2, 0x14a0, v83
	ds_write2_b32 v2, v22, v23 offset1:1
	v_add_u32_e32 v2, 0x14a8, v83
	ds_write2_b32 v2, v24, v25 offset1:1
	v_add_u32_e32 v2, 0x18c0, v83
	s_ashr_i32 s6, s16, 31
	ds_write2_b32 v2, v38, v39 offset1:1
	v_add_u32_e32 v2, 0x18c8, v83
	s_lshr_b32 s6, s6, 26
	ds_write2_b32 v2, v40, v41 offset1:1
	v_add_u32_e32 v2, 0x1ce0, v83
	s_add_i32 s16, s16, s6
	ds_write2_b32 v2, v42, v43 offset1:1
	v_add_u32_e32 v2, 0x1ce8, v83
	s_and_b32 s6, s16, 0xffffffc0
	ds_write2_b32 v2, v44, v45 offset1:1
	s_waitcnt lgkmcnt(0)
	s_ashr_i32 s7, s6, 31
	ds_read2_b32 v[6:7], v82 offset0:33 offset1:41
	ds_read2_b32 v[8:9], v82 offset1:8
	ds_read2_b32 v[10:11], v82 offset0:66 offset1:74
	ds_read2_b32 v[12:13], v82 offset0:99 offset1:107
	ds_read2_b32 v[14:15], v82 offset0:132 offset1:140
	ds_read2_b32 v[16:17], v82 offset0:165 offset1:173
	ds_read2_b32 v[20:21], v82 offset0:198 offset1:206
	ds_read2_b32 v[22:23], v82 offset0:231 offset1:239
	v_lshl_add_u64 v[24:25], s[6:7], 1, v[74:75]
	s_lshl_b32 s6, s16, 5
	s_waitcnt lgkmcnt(6)
	v_cvt_pk_bf16_f32 v2, v8, v6
	v_add_u32_e32 v6, s17, v84
	s_and_b32 s6, s6, 0xfffff800
	v_subrev_u32_e32 v26, s6, v6
	v_ashrrev_i32_e32 v27, 31, v26
	v_lshlrev_b64 v[28:29], 12, v[26:27]
	s_waitcnt lgkmcnt(4)
	v_cvt_pk_bf16_f32 v3, v10, v12
	s_waitcnt lgkmcnt(2)
	v_cvt_pk_bf16_f32 v4, v14, v16
	s_waitcnt lgkmcnt(0)
	v_cvt_pk_bf16_f32 v5, v20, v22
	v_lshl_add_u64 v[28:29], v[24:25], 0, v[28:29]
	v_add_u32_e32 v6, 8, v26
	global_store_dwordx4 v[28:29], v[2:5], off sc1
	s_waitcnt vmcnt(1)
	v_mov_b64_e32 v[38:39], v[62:63]
	v_add_u32_e32 v84, s18, v84
	v_cvt_pk_bf16_f32 v2, v9, v7
	v_ashrrev_i32_e32 v7, 31, v6
	v_cvt_pk_bf16_f32 v3, v11, v13
	v_cvt_pk_bf16_f32 v4, v15, v17
	v_cvt_pk_bf16_f32 v5, v21, v23
	v_lshlrev_b64 v[6:7], 12, v[6:7]
	ds_read2_b32 v[8:9], v82 offset0:49 offset1:57
	ds_read2_b32 v[10:11], v82 offset0:16 offset1:24
	ds_read2_b32 v[12:13], v82 offset0:82 offset1:90
	ds_read2_b32 v[14:15], v82 offset0:115 offset1:123
	ds_read2_b32 v[16:17], v82 offset0:148 offset1:156
	ds_read2_b32 v[20:21], v82 offset0:181 offset1:189
	ds_read2_b32 v[22:23], v82 offset0:214 offset1:222
	ds_read2_b32 v[28:29], v82 offset0:247 offset1:255
	v_lshl_add_u64 v[6:7], v[24:25], 0, v[6:7]
	global_store_dwordx4 v[6:7], v[2:5], off sc1
	v_add_u32_e32 v6, 16, v26
	v_ashrrev_i32_e32 v7, 31, v6
	v_lshlrev_b64 v[6:7], 12, v[6:7]
	s_waitcnt lgkmcnt(6)
	v_cvt_pk_bf16_f32 v2, v10, v8
	s_waitcnt lgkmcnt(4)
	v_cvt_pk_bf16_f32 v3, v12, v14
	s_waitcnt lgkmcnt(2)
	v_cvt_pk_bf16_f32 v4, v16, v20
	s_waitcnt lgkmcnt(0)
	v_cvt_pk_bf16_f32 v5, v22, v28
	v_lshl_add_u64 v[6:7], v[24:25], 0, v[6:7]
	global_store_dwordx4 v[6:7], v[2:5], off sc1
	v_add_u32_e32 v6, 24, v26
	v_ashrrev_i32_e32 v7, 31, v6
	v_lshlrev_b64 v[6:7], 12, v[6:7]
	v_cvt_pk_bf16_f32 v2, v11, v9
	v_cvt_pk_bf16_f32 v3, v13, v15
	v_cvt_pk_bf16_f32 v4, v17, v21
	v_cvt_pk_bf16_f32 v5, v23, v29
	v_lshl_add_u64 v[6:7], v[24:25], 0, v[6:7]
	global_store_dwordx4 v[6:7], v[2:5], off sc1
	s_waitcnt lgkmcnt(0)
	v_mov_b64_e32 v[6:7], v[34:35]
	v_mov_b64_e32 v[14:15], v[46:47]
	v_mov_b64_e32 v[2:3], v[30:31]
	v_mov_b64_e32 v[10:11], v[50:51]
	v_mov_b64_e32 v[26:27], v[54:55]
	v_mov_b64_e32 v[22:23], v[58:59]
	s_add_i32 s21, s21, s18
	v_add_u32_e32 v80, s18, v80
	s_andn2_b64 vcc, exec, s[4:5]
	s_mov_b32 s16, s25
	v_mov_b64_e32 v[8:9], v[36:37]
	v_mov_b64_e32 v[4:5], v[32:33]
	v_mov_b64_e32 v[16:17], v[48:49]
	v_mov_b64_e32 v[12:13], v[52:53]
	v_mov_b64_e32 v[28:29], v[56:57]
	v_mov_b64_e32 v[24:25], v[60:61]
	v_mov_b64_e32 v[40:41], v[64:65]
	v_mov_b32_e32 v42, v66
	v_mov_b32_e32 v43, v67
	v_mov_b32_e32 v44, v68
	v_mov_b32_e32 v45, v69
	s_cbranch_vccz .LBB0_300

; #define LAS __attribute__((address_space(3)))
; __device__ __forceinline__ unsigned cvtpk(float lo, float hi) { f32x2 v = {lo, hi}; bf16x2_t b = __builtin_convertvector(v, bf16x2_t); return __builtin_bit_cast(unsigned, b); }
; __device__ __forceinline__ void witem_store(const WItem& w, int K, bf16_t* WT, int kvperm, LAS float* scr, int item, int nblk, int lane) {
;     ...
;     for (int i = 0; i < 8; ++i) { LAS float* d = scr + (8 * i + rr) * 33 + col; const float g = w.g[i]; d[0] = w.v[i].x * g; d[1] = w.v[i].y * g; d[2] = w.v[i].z * g; d[3] = w.v[i].w * g; }
;     asm volatile("s_waitcnt lgkmcnt(0)" ::: "memory");
;     const int c = lane & 7;
; #pragma unroll
;     for (int j = 0; j < 4; ++j) { const int n = (lane >> 3) + 8 * j; const LAS float* s = scr + (8 * c) * 33 + n;
;         u32x4 o; o.x = cvtpk(s[0 * 33], s[1 * 33]); o.y = cvtpk(s[2 * 33], s[3 * 33]); o.z = cvtpk(s[4 * 33], s[5 * 33]); o.w = cvtpk(s[6 * 33], s[7 * 33]);
;         int nr = n0 + n; if (kvperm == 1) { const int hh = nr >> 8, ww = nr & 255; nr = (ww < 128) ? hh * 128 + ww : 2048 + hh * 128 + (ww - 128); }
;         else if (kvperm == 2) { const int isv = nr >= 5632, f = isv ? nr - 5632 : nr; nr = (f >> 7) * 256 + isv * 128 + (f & 127); }
;         *(u32x4*)(WT + (size_t)nr * K + k0 + 8 * c) = o; }
;     asm volatile("s_waitcnt lgkmcnt(0)" ::: "memory");
.LBB0_319:
	v_pk_mul_f32 v[4:5], v[10:11], v[76:77] op_sel_hi:[1,0]
	ds_write2_b32 v83, v4, v5 offset1:1
	v_pk_mul_f32 v[4:5], v[12:13], v[76:77] op_sel_hi:[1,0]
	ds_write2_b32 v83, v4, v5 offset0:2 offset1:3
	v_pk_mul_f32 v[4:5], v[6:7], v[78:79] op_sel_hi:[1,0]
	v_add_u32_e32 v6, 0x420, v83
	ds_write2_b32 v6, v4, v5 offset1:1
	v_pk_mul_f32 v[4:5], v[8:9], v[78:79] op_sel_hi:[1,0]
	v_add_u32_e32 v6, 0x428, v83
	ds_write2_b32 v6, v4, v5 offset1:1
	v_pk_mul_f32 v[4:5], v[22:23], v[80:81] op_sel_hi:[1,0]
	v_add_u32_e32 v6, 0x840, v83
	ds_write2_b32 v6, v4, v5 offset1:1
	v_pk_mul_f32 v[4:5], v[24:25], v[80:81] op_sel_hi:[1,0]
	v_add_u32_e32 v6, 0x848, v83
	ds_write2_b32 v6, v4, v5 offset1:1
	v_pk_mul_f32 v[4:5], v[14:15], v[82:83] op_sel_hi:[1,0]
	v_add_u32_e32 v6, 0xc60, v83
	ds_write2_b32 v6, v4, v5 offset1:1
	v_pk_mul_f32 v[4:5], v[16:17], v[82:83] op_sel_hi:[1,0]
	v_add_u32_e32 v6, 0xc68, v83
	ds_write2_b32 v6, v4, v5 offset1:1
	v_pk_mul_f32 v[4:5], v[34:35], v[84:85] op_sel_hi:[1,0]
	v_add_u32_e32 v6, 0x1080, v83
	ds_write2_b32 v6, v4, v5 offset1:1
	v_pk_mul_f32 v[4:5], v[36:37], v[84:85] op_sel_hi:[1,0]
	v_add_u32_e32 v6, 0x1088, v83
	ds_write2_b32 v6, v4, v5 offset1:1
	s_waitcnt vmcnt(7)
	v_pk_mul_f32 v[4:5], v[30:31], v[86:87] op_sel_hi:[1,0]
	v_add_u32_e32 v6, 0x14a0, v83
	ds_write2_b32 v6, v4, v5 offset1:1
	v_pk_mul_f32 v[4:5], v[32:33], v[86:87] op_sel_hi:[1,0]
	v_add_u32_e32 v6, 0x14a8, v83
	ds_write2_b32 v6, v4, v5 offset1:1
	v_pk_mul_f32 v[4:5], v[46:47], v[88:89] op_sel_hi:[1,0]
	v_add_u32_e32 v6, 0x18c0, v83
	s_mul_hi_i32 s12, s16, 0x51eb851f
	ds_write2_b32 v6, v4, v5 offset1:1
	v_pk_mul_f32 v[4:5], v[48:49], v[88:89] op_sel_hi:[1,0]
	v_add_u32_e32 v6, 0x18c8, v83
	s_lshr_b32 s13, s12, 31
	s_ashr_i32 s12, s12, 6
	ds_write2_b32 v6, v4, v5 offset1:1
	s_waitcnt vmcnt(6)
	v_pk_mul_f32 v[4:5], v[38:39], v[90:91] op_sel_hi:[1,0]
	v_add_u32_e32 v6, 0x1ce0, v83
	s_add_i32 s16, s12, s13
	ds_write2_b32 v6, v4, v5 offset1:1
	v_pk_mul_f32 v[4:5], v[40:41], v[90:91] op_sel_hi:[1,0]
	v_add_u32_e32 v6, 0x1ce8, v83
	s_lshl_b32 s12, s16, 6
	ds_write2_b32 v6, v4, v5 offset1:1
	s_waitcnt lgkmcnt(0)
	s_ashr_i32 s13, s12, 31
	ds_read2_b32 v[8:9], v81 offset0:33 offset1:41
	ds_read2_b32 v[10:11], v81 offset1:8
	ds_read2_b32 v[12:13], v81 offset0:66 offset1:74
	ds_read2_b32 v[14:15], v81 offset0:99 offset1:107
	ds_read2_b32 v[16:17], v81 offset0:132 offset1:140
	ds_read2_b32 v[22:23], v81 offset0:165 offset1:173
	ds_read2_b32 v[24:25], v81 offset0:198 offset1:206
	ds_read2_b32 v[30:31], v81 offset0:231 offset1:239
	v_lshl_add_u64 v[32:33], s[12:13], 1, v[74:75]
	s_mul_i32 s12, s16, 0xffffe700
	s_add_i32 s12, s12, s17
	v_add_u32_e32 v34, s12, v85
	v_ashrrev_i32_e32 v35, 31, v34
	v_lshlrev_b64 v[36:37], 12, v[34:35]
	s_waitcnt lgkmcnt(6)
	v_cvt_pk_bf16_f32 v4, v10, v8
	s_waitcnt lgkmcnt(4)
	v_cvt_pk_bf16_f32 v5, v12, v14
	s_waitcnt lgkmcnt(2)
	v_cvt_pk_bf16_f32 v6, v16, v22
	s_waitcnt lgkmcnt(0)
	v_cvt_pk_bf16_f32 v7, v24, v30
	v_lshl_add_u64 v[36:37], v[32:33], 0, v[36:37]
	v_add_u32_e32 v8, 8, v34
	global_store_dwordx4 v[36:37], v[4:7], off sc1
	s_waitcnt vmcnt(3)
	v_mov_b64_e32 v[46:47], v[62:63]
	s_waitcnt vmcnt(2)
	v_mov_b64_e32 v[38:39], v[66:67]
	v_cvt_pk_bf16_f32 v4, v11, v9
	v_ashrrev_i32_e32 v9, 31, v8
	v_cvt_pk_bf16_f32 v5, v13, v15
	v_cvt_pk_bf16_f32 v6, v17, v23
	v_cvt_pk_bf16_f32 v7, v25, v31
	v_lshlrev_b64 v[8:9], 12, v[8:9]
	ds_read2_b32 v[10:11], v81 offset0:49 offset1:57
	ds_read2_b32 v[12:13], v81 offset0:16 offset1:24
	ds_read2_b32 v[14:15], v81 offset0:82 offset1:90
	ds_read2_b32 v[16:17], v81 offset0:115 offset1:123
	ds_read2_b32 v[22:23], v81 offset0:148 offset1:156
	ds_read2_b32 v[24:25], v81 offset0:181 offset1:189
	ds_read2_b32 v[30:31], v81 offset0:214 offset1:222
	ds_read2_b32 v[36:37], v81 offset0:247 offset1:255
	v_lshl_add_u64 v[8:9], v[32:33], 0, v[8:9]
	global_store_dwordx4 v[8:9], v[4:7], off sc1
	v_add_u32_e32 v8, 16, v34
	v_ashrrev_i32_e32 v9, 31, v8
	v_lshlrev_b64 v[8:9], 12, v[8:9]
	s_waitcnt lgkmcnt(6)
	v_cvt_pk_bf16_f32 v4, v12, v10
	s_waitcnt lgkmcnt(4)
	v_cvt_pk_bf16_f32 v5, v14, v16
	s_waitcnt lgkmcnt(2)
	v_cvt_pk_bf16_f32 v6, v22, v24
	s_waitcnt lgkmcnt(0)
	v_cvt_pk_bf16_f32 v7, v30, v36
	v_lshl_add_u64 v[8:9], v[32:33], 0, v[8:9]
	global_store_dwordx4 v[8:9], v[4:7], off sc1
	v_add_u32_e32 v8, 24, v34
	v_ashrrev_i32_e32 v9, 31, v8
	v_lshlrev_b64 v[8:9], 12, v[8:9]
	v_cvt_pk_bf16_f32 v4, v13, v11
	v_cvt_pk_bf16_f32 v5, v15, v17
	v_cvt_pk_bf16_f32 v6, v23, v25
	v_cvt_pk_bf16_f32 v7, v31, v37
	v_lshl_add_u64 v[8:9], v[32:33], 0, v[8:9]
	global_store_dwordx4 v[8:9], v[4:7], off sc1
	s_waitcnt lgkmcnt(0)
	v_mov_b64_e32 v[10:11], v[26:27]
	v_mov_b64_e32 v[22:23], v[42:43]
	v_mov_b64_e32 v[6:7], v[18:19]
	v_mov_b64_e32 v[14:15], v[50:51]
	v_mov_b64_e32 v[34:35], v[54:55]
	v_mov_b64_e32 v[30:31], v[58:59]
	v_add_u32_e32 v85, s18, v85
	s_add_i32 s25, s25, s18
	v_add_u32_e32 v77, s18, v77
	s_andn2_b64 vcc, exec, s[6:7]
	s_mov_b32 s16, s26
	v_mov_b64_e32 v[12:13], v[28:29]
	v_mov_b64_e32 v[8:9], v[20:21]
	v_mov_b64_e32 v[24:25], v[44:45]
	v_mov_b64_e32 v[16:17], v[52:53]
	v_mov_b64_e32 v[36:37], v[56:57]
	v_mov_b64_e32 v[32:33], v[60:61]
	v_mov_b64_e32 v[48:49], v[64:65]
	v_mov_b64_e32 v[40:41], v[68:69]
	v_mov_b32_e32 v76, v87
	v_mov_b32_e32 v78, v91
	v_mov_b32_e32 v80, v93
	v_mov_b32_e32 v82, v98
	v_mov_b32_e32 v84, v99
	v_mov_b32_e32 v86, v100
	v_mov_b32_e32 v88, v101
	s_waitcnt vmcnt(4)
	v_mov_b32_e32 v90, v3
	s_cbranch_vccz .LBB0_337

; #define LAS __attribute__((address_space(3)))
; __device__ __forceinline__ unsigned cvtpk(float lo, float hi) { f32x2 v = {lo, hi}; bf16x2_t b = __builtin_convertvector(v, bf16x2_t); return __builtin_bit_cast(unsigned, b); }
; __device__ __forceinline__ void witem_store(const WItem& w, int K, bf16_t* WT, int kvperm, LAS float* scr, int item, int nblk, int lane) {
;     ...
;     for (int i = 0; i < 8; ++i) { LAS float* d = scr + (8 * i + rr) * 33 + col; const float g = w.g[i]; d[0] = w.v[i].x * g; d[1] = w.v[i].y * g; d[2] = w.v[i].z * g; d[3] = w.v[i].w * g; }
;     asm volatile("s_waitcnt lgkmcnt(0)" ::: "memory");
;     const int c = lane & 7;
; #pragma unroll
;     for (int j = 0; j < 4; ++j) { const int n = (lane >> 3) + 8 * j; const LAS float* s = scr + (8 * c) * 33 + n;
;         u32x4 o; o.x = cvtpk(s[0 * 33], s[1 * 33]); o.y = cvtpk(s[2 * 33], s[3 * 33]); o.z = cvtpk(s[4 * 33], s[5 * 33]); o.w = cvtpk(s[6 * 33], s[7 * 33]);
;         int nr = n0 + n; if (kvperm == 1) { const int hh = nr >> 8, ww = nr & 255; nr = (ww < 128) ? hh * 128 + ww : 2048 + hh * 128 + (ww - 128); }
;         else if (kvperm == 2) { const int isv = nr >= 5632, f = isv ? nr - 5632 : nr; nr = (f >> 7) * 256 + isv * 128 + (f & 127); }
;         *(u32x4*)(WT + (size_t)nr * K + k0 + 8 * c) = o; }
;     asm volatile("s_waitcnt lgkmcnt(0)" ::: "memory");
.LBB0_382:
	v_pk_mul_f32 v[2:3], v[2:3], v[72:73] op_sel_hi:[1,0]
	ds_write2_b32 v79, v2, v3 offset1:1
	v_pk_mul_f32 v[2:3], v[4:5], v[72:73] op_sel_hi:[1,0]
	ds_write2_b32 v79, v2, v3 offset0:2 offset1:3
	v_pk_mul_f32 v[2:3], v[6:7], v[74:75] op_sel_hi:[1,0]
	v_add_u32_e32 v4, 0x420, v79
	ds_write2_b32 v4, v2, v3 offset1:1
	v_pk_mul_f32 v[2:3], v[8:9], v[74:75] op_sel_hi:[1,0]
	v_add_u32_e32 v4, 0x428, v79
	ds_write2_b32 v4, v2, v3 offset1:1
	v_pk_mul_f32 v[2:3], v[10:11], v[76:77] op_sel_hi:[1,0]
	v_add_u32_e32 v4, 0x840, v79
	ds_write2_b32 v4, v2, v3 offset1:1
	v_pk_mul_f32 v[2:3], v[12:13], v[76:77] op_sel_hi:[1,0]
	v_add_u32_e32 v4, 0x848, v79
	ds_write2_b32 v4, v2, v3 offset1:1
	v_pk_mul_f32 v[2:3], v[14:15], v[78:79] op_sel_hi:[1,0]
	v_add_u32_e32 v4, 0xc60, v79
	ds_write2_b32 v4, v2, v3 offset1:1
	v_pk_mul_f32 v[2:3], v[16:17], v[78:79] op_sel_hi:[1,0]
	v_add_u32_e32 v4, 0xc68, v79
	ds_write2_b32 v4, v2, v3 offset1:1
	v_pk_mul_f32 v[2:3], v[18:19], v[84:85] op_sel_hi:[1,0]
	v_add_u32_e32 v4, 0x1080, v79
	ds_write2_b32 v4, v2, v3 offset1:1
	v_pk_mul_f32 v[2:3], v[20:21], v[84:85] op_sel_hi:[1,0]
	v_add_u32_e32 v4, 0x1088, v79
	ds_write2_b32 v4, v2, v3 offset1:1
	v_pk_mul_f32 v[2:3], v[26:27], v[86:87] op_sel_hi:[1,0]
	v_add_u32_e32 v4, 0x14a0, v79
	s_mul_hi_i32 s4, s26, 0x2e8ba2e9
	ds_write2_b32 v4, v2, v3 offset1:1
	v_pk_mul_f32 v[2:3], v[28:29], v[86:87] op_sel_hi:[1,0]
	v_add_u32_e32 v4, 0x14a8, v79
	s_lshr_b32 s5, s4, 31
	s_ashr_i32 s4, s4, 6
	ds_write2_b32 v4, v2, v3 offset1:1
	v_pk_mul_f32 v[2:3], v[30:31], v[88:89] op_sel_hi:[1,0]
	v_add_u32_e32 v4, 0x18c0, v79
	s_add_i32 s6, s4, s5
	ds_write2_b32 v4, v2, v3 offset1:1
	v_pk_mul_f32 v[2:3], v[32:33], v[88:89] op_sel_hi:[1,0]
	v_add_u32_e32 v4, 0x18c8, v79
	s_lshl_b32 s4, s6, 6
	ds_write2_b32 v4, v2, v3 offset1:1
	s_waitcnt vmcnt(0)
	v_pk_mul_f32 v[2:3], v[38:39], v[90:91] op_sel_hi:[1,0]
	v_add_u32_e32 v4, 0x1ce0, v79
	ds_write2_b32 v4, v2, v3 offset1:1
	v_pk_mul_f32 v[2:3], v[40:41], v[90:91] op_sel_hi:[1,0]
	v_add_u32_e32 v4, 0x1ce8, v79
	s_ashr_i32 s5, s4, 31
	ds_write2_b32 v4, v2, v3 offset1:1
	v_lshl_add_u64 v[24:25], s[4:5], 1, v[82:83]
	s_mul_i32 s4, s6, 0xffffd400
	s_waitcnt lgkmcnt(0)
	s_add_i32 s4, s4, s28
	ds_read2_b32 v[6:7], v77 offset0:33 offset1:41
	ds_read2_b32 v[8:9], v77 offset1:8
	ds_read2_b32 v[10:11], v77 offset0:66 offset1:74
	ds_read2_b32 v[12:13], v77 offset0:99 offset1:107
	ds_read2_b32 v[14:15], v77 offset0:132 offset1:140
	ds_read2_b32 v[16:17], v77 offset0:165 offset1:173
	ds_read2_b32 v[18:19], v77 offset0:198 offset1:206
	ds_read2_b32 v[20:21], v77 offset0:231 offset1:239
	v_add_u32_e32 v28, s4, v87
	s_waitcnt lgkmcnt(6)
	v_cvt_pk_bf16_f32 v2, v8, v6
	v_add_u32_e32 v6, 0xffffea00, v28
	v_cmp_lt_i32_e32 vcc, s34, v28
	s_waitcnt lgkmcnt(4)
	v_cvt_pk_bf16_f32 v3, v10, v12
	s_waitcnt lgkmcnt(2)
	v_cvt_pk_bf16_f32 v4, v14, v16
	v_cndmask_b32_e32 v6, v28, v6, vcc
	v_lshlrev_b32_e32 v8, 1, v6
	v_and_b32_e32 v8, 0xffffff00, v8
	v_cndmask_b32_e32 v10, 0, v85, vcc
	v_and_b32_e32 v6, 0x67, v6
	v_or3_b32 v26, v6, v10, v8
	v_ashrrev_i32_e32 v27, 31, v26
	v_lshlrev_b64 v[26:27], 12, v[26:27]
	s_waitcnt lgkmcnt(0)
	v_cvt_pk_bf16_f32 v5, v18, v20
	v_lshl_add_u64 v[26:27], v[24:25], 0, v[26:27]
	v_add_u32_e32 v6, 8, v28
	global_store_dwordx4 v[26:27], v[2:5], off sc1
	v_cmp_lt_i32_e32 vcc, s34, v6
	v_mov_b64_e32 v[30:31], v[62:63]
	v_cvt_pk_bf16_f32 v2, v9, v7
	v_add_u32_e32 v7, 0xffffea08, v28
	v_cndmask_b32_e32 v6, v6, v7, vcc
	v_lshlrev_b32_e32 v7, 1, v6
	v_and_b32_e32 v7, 0xffffff00, v7
	v_cndmask_b32_e32 v8, 0, v85, vcc
	v_and_b32_e32 v6, 0x6f, v6
	v_or3_b32 v6, v6, v8, v7
	v_ashrrev_i32_e32 v7, 31, v6
	v_lshlrev_b64 v[6:7], 12, v[6:7]
	v_cvt_pk_bf16_f32 v3, v11, v13
	v_cvt_pk_bf16_f32 v4, v15, v17
	v_cvt_pk_bf16_f32 v5, v19, v21
	v_lshl_add_u64 v[6:7], v[24:25], 0, v[6:7]
	ds_read2_b32 v[8:9], v77 offset0:16 offset1:24
	ds_read2_b32 v[10:11], v77 offset0:49 offset1:57
	ds_read2_b32 v[12:13], v77 offset0:82 offset1:90
	ds_read2_b32 v[14:15], v77 offset0:115 offset1:123
	ds_read2_b32 v[16:17], v77 offset0:148 offset1:156
	ds_read2_b32 v[18:19], v77 offset0:181 offset1:189
	ds_read2_b32 v[20:21], v77 offset0:214 offset1:222
	ds_read2_b32 v[26:27], v77 offset0:247 offset1:255
	global_store_dwordx4 v[6:7], v[2:5], off sc1
	v_add_u32_e32 v6, 16, v28
	v_add_u32_e32 v7, 0xffffea10, v28
	v_cmp_lt_i32_e32 vcc, s34, v6
	s_waitcnt lgkmcnt(6)
	v_cvt_pk_bf16_f32 v2, v8, v10
	s_waitcnt lgkmcnt(4)
	v_cvt_pk_bf16_f32 v3, v12, v14
	v_cndmask_b32_e32 v6, v6, v7, vcc
	v_lshlrev_b32_e32 v7, 1, v6
	v_and_b32_e32 v7, 0xffffff00, v7
	v_cndmask_b32_e32 v8, 0, v85, vcc
	v_and_b32_e32 v6, 0x77, v6
	v_or3_b32 v6, v6, v8, v7
	v_ashrrev_i32_e32 v7, 31, v6
	v_lshlrev_b64 v[6:7], 12, v[6:7]
	s_waitcnt lgkmcnt(2)
	v_cvt_pk_bf16_f32 v4, v16, v18
	s_waitcnt lgkmcnt(0)
	v_cvt_pk_bf16_f32 v5, v20, v26
	v_lshl_add_u64 v[6:7], v[24:25], 0, v[6:7]
	global_store_dwordx4 v[6:7], v[2:5], off sc1
	v_mov_b64_e32 v[38:39], v[66:67]
	v_add_u32_e32 v87, s29, v87
	v_add_u32_e32 v2, 24, v28
	v_add_u32_e32 v3, 0xffffea18, v28
	v_cmp_lt_i32_e32 vcc, s34, v2
	v_cvt_pk_bf16_f32 v5, v21, v27
	v_mov_b64_e32 v[26:27], v[58:59]
	v_cndmask_b32_e32 v2, v2, v3, vcc
	v_lshlrev_b32_e32 v3, 1, v2
	v_and_b32_e32 v3, 0xffffff00, v3
	v_cndmask_b32_e32 v4, 0, v85, vcc
	v_and_b32_e32 v2, 0x7f, v2
	v_or3_b32 v6, v2, v4, v3
	v_ashrrev_i32_e32 v7, 31, v6
	v_lshlrev_b64 v[6:7], 12, v[6:7]
	v_cvt_pk_bf16_f32 v2, v9, v11
	v_cvt_pk_bf16_f32 v3, v13, v15
	v_cvt_pk_bf16_f32 v4, v17, v19
	v_lshl_add_u64 v[6:7], v[24:25], 0, v[6:7]
	global_store_dwordx4 v[6:7], v[2:5], off sc1
	s_waitcnt lgkmcnt(0)
	v_mov_b64_e32 v[6:7], v[42:43]
	v_mov_b64_e32 v[10:11], v[46:47]
	v_mov_b64_e32 v[2:3], v[34:35]
	v_mov_b64_e32 v[14:15], v[50:51]
	v_mov_b64_e32 v[18:19], v[54:55]
	s_add_i32 s35, s35, s29
	v_add_u32_e32 v73, s29, v73
	s_andn2_b64 vcc, exec, s[18:19]
	s_mov_b32 s26, s36
	v_mov_b64_e32 v[4:5], v[36:37]
	v_mov_b64_e32 v[8:9], v[44:45]
	v_mov_b64_e32 v[12:13], v[48:49]
	v_mov_b64_e32 v[16:17], v[52:53]
	v_mov_b64_e32 v[20:21], v[56:57]
	v_mov_b64_e32 v[28:29], v[60:61]
	v_mov_b64_e32 v[32:33], v[64:65]
	v_mov_b64_e32 v[40:41], v[68:69]
	v_mov_b32_e32 v72, v91
	v_mov_b32_e32 v74, v96
	v_mov_b32_e32 v76, v97
	v_mov_b32_e32 v78, v98
	v_mov_b32_e32 v84, v99
	v_mov_b32_e32 v86, v100
	v_mov_b32_e32 v88, v101
	v_mov_b32_e32 v90, v23
	s_cbranch_vccz .LBB0_422

; #define LAS __attribute__((address_space(3)))
; __device__ __forceinline__ unsigned cvtpk(float lo, float hi) { f32x2 v = {lo, hi}; bf16x2_t b = __builtin_convertvector(v, bf16x2_t); return __builtin_bit_cast(unsigned, b); }
; __device__ __forceinline__ void witem_store(const WItem& w, int K, bf16_t* WT, int kvperm, LAS float* scr, int item, int nblk, int lane) {
;     ...
; #pragma unroll
;     for (int j = 0; j < 4; ++j) { const int n = (lane >> 3) + 8 * j; const LAS float* s = scr + (8 * c) * 33 + n;
;         u32x4 o; o.x = cvtpk(s[0 * 33], s[1 * 33]); o.y = cvtpk(s[2 * 33], s[3 * 33]); o.z = cvtpk(s[4 * 33], s[5 * 33]); o.w = cvtpk(s[6 * 33], s[7 * 33]);
;         int nr = n0 + n; if (kvperm == 1) { const int hh = nr >> 8, ww = nr & 255; nr = (ww < 128) ? hh * 128 + ww : 2048 + hh * 128 + (ww - 128); }
;         else if (kvperm == 2) { const int isv = nr >= 5632, f = isv ? nr - 5632 : nr; nr = (f >> 7) * 256 + isv * 128 + (f & 127); }
;         *(u32x4*)(WT + (size_t)nr * K + k0 + 8 * c) = o; }
;     asm volatile("s_waitcnt lgkmcnt(0)" ::: "memory");
.LBB0_441:
	ds_write2_b32 v84, v6, v7 offset1:1
	ds_write2_b32 v84, v8, v9 offset0:2 offset1:3
	v_add_u32_e32 v6, 0x420, v84
	ds_write2_b32 v6, v2, v3 offset1:1
	v_add_u32_e32 v2, 0x428, v84
	ds_write2_b32 v2, v4, v5 offset1:1
	v_add_u32_e32 v2, 0x840, v84
	ds_write2_b32 v2, v14, v15 offset1:1
	v_add_u32_e32 v2, 0x848, v84
	ds_write2_b32 v2, v16, v17 offset1:1
	v_add_u32_e32 v2, 0xc60, v84
	ds_write2_b32 v2, v10, v11 offset1:1
	v_add_u32_e32 v2, 0xc68, v84
	ds_write2_b32 v2, v12, v13 offset1:1
	v_add_u32_e32 v2, 0x1080, v84
	ds_write2_b32 v2, v26, v27 offset1:1
	v_add_u32_e32 v2, 0x1088, v84
	ds_write2_b32 v2, v28, v29 offset1:1
	v_add_u32_e32 v2, 0x14a0, v84
	ds_write2_b32 v2, v18, v19 offset1:1
	v_add_u32_e32 v2, 0x14a8, v84
	ds_write2_b32 v2, v20, v21 offset1:1
	v_add_u32_e32 v2, 0x18c0, v84
	ds_write2_b32 v2, v38, v39 offset1:1
	v_add_u32_e32 v2, 0x18c8, v84
	ds_write2_b32 v2, v40, v41 offset1:1
	v_add_u32_e32 v2, 0x1ce0, v84
	ds_write2_b32 v2, v42, v43 offset1:1
	v_add_u32_e32 v2, 0x1ce8, v84
	s_ashr_i32 s16, s21, 31
	ds_write2_b32 v2, v44, v45 offset1:1
	s_lshr_b32 s16, s16, 26
	s_waitcnt lgkmcnt(0)
	s_add_i32 s16, s21, s16
	ds_read2_b32 v[6:7], v82 offset0:33 offset1:41
	ds_read2_b32 v[8:9], v82 offset1:8
	ds_read2_b32 v[10:11], v82 offset0:66 offset1:74
	ds_read2_b32 v[12:13], v82 offset0:99 offset1:107
	ds_read2_b32 v[14:15], v82 offset0:132 offset1:140
	ds_read2_b32 v[16:17], v82 offset0:165 offset1:173
	ds_read2_b32 v[18:19], v82 offset0:198 offset1:206
	ds_read2_b32 v[20:21], v82 offset0:231 offset1:239
	s_lshr_b32 s21, s16, 6
	s_andn2_b32 s16, s16, 63
	s_mul_i32 s21, s21, 0xff500000
	s_ashr_i32 s17, s16, 31
	v_add_u32_e32 v26, s21, v83
	v_lshl_add_u64 v[24:25], s[16:17], 1, v[74:75]
	v_ashrrev_i32_e32 v27, 31, v26
	s_waitcnt lgkmcnt(6)
	v_cvt_pk_bf16_f32 v2, v8, v6
	s_waitcnt lgkmcnt(4)
	v_cvt_pk_bf16_f32 v3, v10, v12
	s_waitcnt lgkmcnt(2)
	v_cvt_pk_bf16_f32 v4, v14, v16
	s_waitcnt lgkmcnt(0)
	v_cvt_pk_bf16_f32 v5, v18, v20
	v_lshl_add_u64 v[28:29], v[26:27], 1, v[24:25]
	global_store_dwordx4 v[28:29], v[2:5], off sc1
	v_add_u32_e32 v6, 0xb000, v26
	s_waitcnt vmcnt(1)
	v_mov_b64_e32 v[38:39], v[62:63]
	v_cvt_pk_bf16_f32 v2, v9, v7
	v_cvt_pk_bf16_f32 v3, v11, v13
	v_cvt_pk_bf16_f32 v4, v15, v17
	v_cvt_pk_bf16_f32 v5, v19, v21
	ds_read2_b32 v[8:9], v82 offset0:49 offset1:57
	ds_read2_b32 v[10:11], v82 offset0:16 offset1:24
	ds_read2_b32 v[12:13], v82 offset0:82 offset1:90
	ds_read2_b32 v[14:15], v82 offset0:115 offset1:123
	ds_read2_b32 v[16:17], v82 offset0:148 offset1:156
	ds_read2_b32 v[18:19], v82 offset0:181 offset1:189
	ds_read2_b32 v[20:21], v82 offset0:214 offset1:222
	ds_read2_b32 v[28:29], v82 offset0:247 offset1:255
	v_ashrrev_i32_e32 v7, 31, v6
	v_lshl_add_u64 v[6:7], v[6:7], 1, v[24:25]
	global_store_dwordx4 v[6:7], v[2:5], off sc1
	v_add_u32_e32 v6, 0x16000, v26
	v_ashrrev_i32_e32 v7, 31, v6
	s_waitcnt lgkmcnt(6)
	v_cvt_pk_bf16_f32 v2, v10, v8
	s_waitcnt lgkmcnt(4)
	v_cvt_pk_bf16_f32 v3, v12, v14
	s_waitcnt lgkmcnt(2)
	v_cvt_pk_bf16_f32 v4, v16, v18
	s_waitcnt lgkmcnt(0)
	v_cvt_pk_bf16_f32 v5, v20, v28
	v_lshl_add_u64 v[6:7], v[6:7], 1, v[24:25]
	global_store_dwordx4 v[6:7], v[2:5], off sc1
	v_add_u32_e32 v6, 0x21000, v26
	v_ashrrev_i32_e32 v7, 31, v6
	v_cvt_pk_bf16_f32 v2, v11, v9
	v_cvt_pk_bf16_f32 v3, v13, v15
	v_cvt_pk_bf16_f32 v4, v17, v19
	v_cvt_pk_bf16_f32 v5, v21, v29
	v_lshl_add_u64 v[6:7], v[6:7], 1, v[24:25]
	global_store_dwordx4 v[6:7], v[2:5], off sc1
	s_waitcnt lgkmcnt(0)
	v_mov_b64_e32 v[6:7], v[34:35]
	v_mov_b64_e32 v[14:15], v[46:47]
	v_mov_b64_e32 v[2:3], v[30:31]
	v_mov_b64_e32 v[10:11], v[50:51]
	v_mov_b64_e32 v[26:27], v[54:55]
	v_mov_b64_e32 v[18:19], v[58:59]
	v_add_u32_e32 v83, s2, v83
	s_add_i32 s25, s25, s26
	s_andn2_b64 vcc, exec, s[6:7]
	s_mov_b32 s21, s28
	v_mov_b64_e32 v[8:9], v[36:37]
	v_mov_b64_e32 v[4:5], v[32:33]
	v_mov_b64_e32 v[16:17], v[48:49]
	v_mov_b64_e32 v[12:13], v[52:53]
	v_mov_b64_e32 v[28:29], v[56:57]
	v_mov_b64_e32 v[20:21], v[60:61]
	v_mov_b64_e32 v[40:41], v[64:65]
	v_mov_b32_e32 v42, v66
	v_mov_b32_e32 v43, v67
	v_mov_b32_e32 v44, v68
	v_mov_b32_e32 v45, v69
	s_cbranch_vccz .LBB0_459

; #define LAS __attribute__((address_space(3)))
; __device__ __forceinline__ unsigned cvtpk(float lo, float hi) { f32x2 v = {lo, hi}; bf16x2_t b = __builtin_convertvector(v, bf16x2_t); return __builtin_bit_cast(unsigned, b); }
; __device__ __forceinline__ void witem_store(const WItem& w, int K, bf16_t* WT, int kvperm, LAS float* scr, int item, int nblk, int lane) {
;     ...
; #pragma unroll
;     for (int j = 0; j < 4; ++j) { const int n = (lane >> 3) + 8 * j; const LAS float* s = scr + (8 * c) * 33 + n;
;         u32x4 o; o.x = cvtpk(s[0 * 33], s[1 * 33]); o.y = cvtpk(s[2 * 33], s[3 * 33]); o.z = cvtpk(s[4 * 33], s[5 * 33]); o.w = cvtpk(s[6 * 33], s[7 * 33]);
;         int nr = n0 + n; if (kvperm == 1) { const int hh = nr >> 8, ww = nr & 255; nr = (ww < 128) ? hh * 128 + ww : 2048 + hh * 128 + (ww - 128); }
;         else if (kvperm == 2) { const int isv = nr >= 5632, f = isv ? nr - 5632 : nr; nr = (f >> 7) * 256 + isv * 128 + (f & 127); }
;         *(u32x4*)(WT + (size_t)nr * K + k0 + 8 * c) = o; }
;     asm volatile("s_waitcnt lgkmcnt(0)" ::: "memory");
.LBB0_478:
	ds_write2_b32 v84, v6, v7 offset1:1
	ds_write2_b32 v84, v8, v9 offset0:2 offset1:3
	v_add_u32_e32 v6, 0x420, v84
	ds_write2_b32 v6, v2, v3 offset1:1
	v_add_u32_e32 v2, 0x428, v84
	ds_write2_b32 v2, v4, v5 offset1:1
	v_add_u32_e32 v2, 0x840, v84
	ds_write2_b32 v2, v14, v15 offset1:1
	v_add_u32_e32 v2, 0x848, v84
	ds_write2_b32 v2, v16, v17 offset1:1
	v_add_u32_e32 v2, 0xc60, v84
	ds_write2_b32 v2, v10, v11 offset1:1
	v_add_u32_e32 v2, 0xc68, v84
	ds_write2_b32 v2, v12, v13 offset1:1
	v_add_u32_e32 v2, 0x1080, v84
	ds_write2_b32 v2, v26, v27 offset1:1
	v_add_u32_e32 v2, 0x1088, v84
	ds_write2_b32 v2, v28, v29 offset1:1
	v_add_u32_e32 v2, 0x14a0, v84
	ds_write2_b32 v2, v18, v19 offset1:1
	v_add_u32_e32 v2, 0x14a8, v84
	ds_write2_b32 v2, v20, v21 offset1:1
	v_add_u32_e32 v2, 0x18c0, v84
	ds_write2_b32 v2, v38, v39 offset1:1
	v_add_u32_e32 v2, 0x18c8, v84
	ds_write2_b32 v2, v40, v41 offset1:1
	v_add_u32_e32 v2, 0x1ce0, v84
	ds_write2_b32 v2, v42, v43 offset1:1
	v_add_u32_e32 v2, 0x1ce8, v84
	s_ashr_i32 s6, s19, 31
	ds_write2_b32 v2, v44, v45 offset1:1
	s_lshr_b32 s6, s6, 26
	s_waitcnt lgkmcnt(0)
	s_add_i32 s6, s19, s6
	ds_read2_b32 v[6:7], v82 offset0:33 offset1:41
	ds_read2_b32 v[8:9], v82 offset1:8
	ds_read2_b32 v[10:11], v82 offset0:66 offset1:74
	ds_read2_b32 v[12:13], v82 offset0:99 offset1:107
	ds_read2_b32 v[14:15], v82 offset0:132 offset1:140
	ds_read2_b32 v[16:17], v82 offset0:165 offset1:173
	ds_read2_b32 v[18:19], v82 offset0:198 offset1:206
	ds_read2_b32 v[20:21], v82 offset0:231 offset1:239
	s_lshr_b32 s19, s6, 6
	s_andn2_b32 s6, s6, 63
	s_mul_i32 s19, s19, 0xff500000
	s_ashr_i32 s7, s6, 31
	v_add_u32_e32 v26, s19, v83
	v_lshl_add_u64 v[24:25], s[6:7], 1, v[74:75]
	v_ashrrev_i32_e32 v27, 31, v26
	s_waitcnt lgkmcnt(6)
	v_cvt_pk_bf16_f32 v2, v8, v6
	s_waitcnt lgkmcnt(4)
	v_cvt_pk_bf16_f32 v3, v10, v12
	s_waitcnt lgkmcnt(2)
	v_cvt_pk_bf16_f32 v4, v14, v16
	s_waitcnt lgkmcnt(0)
	v_cvt_pk_bf16_f32 v5, v18, v20
	v_lshl_add_u64 v[28:29], v[26:27], 1, v[24:25]
	global_store_dwordx4 v[28:29], v[2:5], off sc1
	v_add_u32_e32 v6, 0xb000, v26
	s_waitcnt vmcnt(1)
	v_mov_b64_e32 v[38:39], v[62:63]
	v_cvt_pk_bf16_f32 v2, v9, v7
	v_cvt_pk_bf16_f32 v3, v11, v13
	v_cvt_pk_bf16_f32 v4, v15, v17
	v_cvt_pk_bf16_f32 v5, v19, v21
	ds_read2_b32 v[8:9], v82 offset0:49 offset1:57
	ds_read2_b32 v[10:11], v82 offset0:16 offset1:24
	ds_read2_b32 v[12:13], v82 offset0:82 offset1:90
	ds_read2_b32 v[14:15], v82 offset0:115 offset1:123
	ds_read2_b32 v[16:17], v82 offset0:148 offset1:156
	ds_read2_b32 v[18:19], v82 offset0:181 offset1:189
	ds_read2_b32 v[20:21], v82 offset0:214 offset1:222
	ds_read2_b32 v[28:29], v82 offset0:247 offset1:255
	v_ashrrev_i32_e32 v7, 31, v6
	v_lshl_add_u64 v[6:7], v[6:7], 1, v[24:25]
	global_store_dwordx4 v[6:7], v[2:5], off sc1
	v_add_u32_e32 v6, 0x16000, v26
	v_ashrrev_i32_e32 v7, 31, v6
	s_waitcnt lgkmcnt(6)
	v_cvt_pk_bf16_f32 v2, v10, v8
	s_waitcnt lgkmcnt(4)
	v_cvt_pk_bf16_f32 v3, v12, v14
	s_waitcnt lgkmcnt(2)
	v_cvt_pk_bf16_f32 v4, v16, v18
	s_waitcnt lgkmcnt(0)
	v_cvt_pk_bf16_f32 v5, v20, v28
	v_lshl_add_u64 v[6:7], v[6:7], 1, v[24:25]
	global_store_dwordx4 v[6:7], v[2:5], off sc1
	v_add_u32_e32 v6, 0x21000, v26
	v_ashrrev_i32_e32 v7, 31, v6
	v_cvt_pk_bf16_f32 v2, v11, v9
	v_cvt_pk_bf16_f32 v3, v13, v15
	v_cvt_pk_bf16_f32 v4, v17, v19
	v_cvt_pk_bf16_f32 v5, v21, v29
	v_lshl_add_u64 v[6:7], v[6:7], 1, v[24:25]
	global_store_dwordx4 v[6:7], v[2:5], off sc1
	s_waitcnt lgkmcnt(0)
	v_mov_b64_e32 v[6:7], v[34:35]
	v_mov_b64_e32 v[14:15], v[46:47]
	v_mov_b64_e32 v[2:3], v[30:31]
	v_mov_b64_e32 v[10:11], v[50:51]
	v_mov_b64_e32 v[26:27], v[54:55]
	v_mov_b64_e32 v[18:19], v[58:59]
	v_add_u32_e32 v83, s2, v83
	s_add_i32 s20, s20, s21
	s_andn2_b64 vcc, exec, s[4:5]
	s_mov_b32 s19, s25
	v_mov_b64_e32 v[8:9], v[36:37]
	v_mov_b64_e32 v[4:5], v[32:33]
	v_mov_b64_e32 v[16:17], v[48:49]
	v_mov_b64_e32 v[12:13], v[52:53]
	v_mov_b64_e32 v[28:29], v[56:57]
	v_mov_b64_e32 v[20:21], v[60:61]
	v_mov_b64_e32 v[40:41], v[64:65]
	v_mov_b32_e32 v42, v66
	v_mov_b32_e32 v43, v67
	v_mov_b32_e32 v44, v68
	v_mov_b32_e32 v45, v69
	s_cbranch_vccz .LBB0_496

; #define LAS __attribute__((address_space(3)))
; __device__ __forceinline__ unsigned cvtpk(float lo, float hi) { f32x2 v = {lo, hi}; bf16x2_t b = __builtin_convertvector(v, bf16x2_t); return __builtin_bit_cast(unsigned, b); }
; __device__ __forceinline__ void witem_store(const WItem& w, int K, bf16_t* WT, int kvperm, LAS float* scr, int item, int nblk, int lane) {
;     ...
;     for (int i = 0; i < 8; ++i) { LAS float* d = scr + (8 * i + rr) * 33 + col; const float g = w.g[i]; d[0] = w.v[i].x * g; d[1] = w.v[i].y * g; d[2] = w.v[i].z * g; d[3] = w.v[i].w * g; }
;     asm volatile("s_waitcnt lgkmcnt(0)" ::: "memory");
;     const int c = lane & 7;
; #pragma unroll
;     for (int j = 0; j < 4; ++j) { const int n = (lane >> 3) + 8 * j; const LAS float* s = scr + (8 * c) * 33 + n;
;         u32x4 o; o.x = cvtpk(s[0 * 33], s[1 * 33]); o.y = cvtpk(s[2 * 33], s[3 * 33]); o.z = cvtpk(s[4 * 33], s[5 * 33]); o.w = cvtpk(s[6 * 33], s[7 * 33]);
;         int nr = n0 + n; if (kvperm == 1) { const int hh = nr >> 8, ww = nr & 255; nr = (ww < 128) ? hh * 128 + ww : 2048 + hh * 128 + (ww - 128); }
;         else if (kvperm == 2) { const int isv = nr >= 5632, f = isv ? nr - 5632 : nr; nr = (f >> 7) * 256 + isv * 128 + (f & 127); }
;         *(u32x4*)(WT + (size_t)nr * K + k0 + 8 * c) = o; }
;     asm volatile("s_waitcnt lgkmcnt(0)" ::: "memory");
.LBB0_515:
	v_pk_mul_f32 v[4:5], v[18:19], v[76:77] op_sel_hi:[1,0]
	ds_write2_b32 v81, v4, v5 offset1:1
	v_pk_mul_f32 v[4:5], v[20:21], v[76:77] op_sel_hi:[1,0]
	ds_write2_b32 v81, v4, v5 offset0:2 offset1:3
	v_pk_mul_f32 v[4:5], v[6:7], v[78:79] op_sel_hi:[1,0]
	v_add_u32_e32 v6, 0x420, v81
	ds_write2_b32 v6, v4, v5 offset1:1
	v_pk_mul_f32 v[4:5], v[8:9], v[78:79] op_sel_hi:[1,0]
	v_add_u32_e32 v6, 0x428, v81
	ds_write2_b32 v6, v4, v5 offset1:1
	v_pk_mul_f32 v[4:5], v[26:27], v[80:81] op_sel_hi:[1,0]
	v_add_u32_e32 v6, 0x840, v81
	ds_write2_b32 v6, v4, v5 offset1:1
	v_pk_mul_f32 v[4:5], v[28:29], v[80:81] op_sel_hi:[1,0]
	v_add_u32_e32 v6, 0x848, v81
	ds_write2_b32 v6, v4, v5 offset1:1
	v_pk_mul_f32 v[4:5], v[22:23], v[82:83] op_sel_hi:[1,0]
	v_add_u32_e32 v6, 0xc60, v81
	ds_write2_b32 v6, v4, v5 offset1:1
	v_pk_mul_f32 v[4:5], v[24:25], v[82:83] op_sel_hi:[1,0]
	v_add_u32_e32 v6, 0xc68, v81
	ds_write2_b32 v6, v4, v5 offset1:1
	v_pk_mul_f32 v[4:5], v[42:43], v[84:85] op_sel_hi:[1,0]
	v_add_u32_e32 v6, 0x1080, v81
	ds_write2_b32 v6, v4, v5 offset1:1
	v_pk_mul_f32 v[4:5], v[44:45], v[84:85] op_sel_hi:[1,0]
	v_add_u32_e32 v6, 0x1088, v81
	ds_write2_b32 v6, v4, v5 offset1:1
	s_waitcnt vmcnt(7)
	v_pk_mul_f32 v[4:5], v[34:35], v[86:87] op_sel_hi:[1,0]
	v_add_u32_e32 v6, 0x14a0, v81
	s_mul_hi_i32 s12, s19, 0x2e8ba2e9
	ds_write2_b32 v6, v4, v5 offset1:1
	v_pk_mul_f32 v[4:5], v[36:37], v[86:87] op_sel_hi:[1,0]
	v_add_u32_e32 v6, 0x14a8, v81
	s_lshr_b32 s13, s12, 31
	s_ashr_i32 s12, s12, 6
	ds_write2_b32 v6, v4, v5 offset1:1
	s_waitcnt vmcnt(6)
	v_pk_mul_f32 v[4:5], v[54:55], v[88:89] op_sel_hi:[1,0]
	v_add_u32_e32 v6, 0x18c0, v81
	s_add_i32 s19, s12, s13
	ds_write2_b32 v6, v4, v5 offset1:1
	v_pk_mul_f32 v[4:5], v[56:57], v[88:89] op_sel_hi:[1,0]
	v_add_u32_e32 v6, 0x18c8, v81
	s_lshl_b32 s12, s19, 6
	ds_write2_b32 v6, v4, v5 offset1:1
	s_waitcnt vmcnt(5)
	v_pk_mul_f32 v[4:5], v[46:47], v[90:91] op_sel_hi:[1,0]
	v_add_u32_e32 v6, 0x1ce0, v81
	ds_write2_b32 v6, v4, v5 offset1:1
	v_pk_mul_f32 v[4:5], v[48:49], v[90:91] op_sel_hi:[1,0]
	v_add_u32_e32 v6, 0x1ce8, v81
	s_ashr_i32 s13, s12, 31
	ds_write2_b32 v6, v4, v5 offset1:1
	v_lshl_add_u64 v[36:37], s[12:13], 1, v[74:75]
	s_mul_i32 s12, s19, 0xffffd400
	s_waitcnt lgkmcnt(0)
	s_add_i32 s12, s12, s2
	ds_read2_b32 v[8:9], v79 offset0:33 offset1:41
	ds_read2_b32 v[18:19], v79 offset1:8
	ds_read2_b32 v[20:21], v79 offset0:66 offset1:74
	ds_read2_b32 v[22:23], v79 offset0:99 offset1:107
	ds_read2_b32 v[24:25], v79 offset0:132 offset1:140
	ds_read2_b32 v[26:27], v79 offset0:165 offset1:173
	ds_read2_b32 v[28:29], v79 offset0:198 offset1:206
	ds_read2_b32 v[34:35], v79 offset0:231 offset1:239
	v_add_u32_e32 v44, s12, v85
	s_waitcnt lgkmcnt(6)
	v_cvt_pk_bf16_f32 v4, v18, v8
	v_add_u32_e32 v8, 0xffffea00, v44
	v_cmp_lt_i32_e32 vcc, s18, v44
	s_waitcnt lgkmcnt(4)
	v_cvt_pk_bf16_f32 v5, v20, v22
	s_waitcnt lgkmcnt(2)
	v_cvt_pk_bf16_f32 v6, v24, v26
	v_cndmask_b32_e32 v8, v44, v8, vcc
	v_lshlrev_b32_e32 v18, 1, v8
	v_and_b32_e32 v18, 0xffffff00, v18
	v_cndmask_b32_e32 v20, 0, v83, vcc
	v_and_b32_e32 v8, 0x67, v8
	v_or3_b32 v42, v8, v20, v18
	v_ashrrev_i32_e32 v43, 31, v42
	v_lshlrev_b64 v[42:43], 12, v[42:43]
	s_waitcnt lgkmcnt(0)
	v_cvt_pk_bf16_f32 v7, v28, v34
	v_lshl_add_u64 v[42:43], v[36:37], 0, v[42:43]
	v_add_u32_e32 v8, 8, v44
	global_store_dwordx4 v[42:43], v[4:7], off sc1
	v_cmp_lt_i32_e32 vcc, s18, v8
	s_waitcnt vmcnt(3)
	v_mov_b64_e32 v[54:55], v[62:63]
	v_cvt_pk_bf16_f32 v4, v19, v9
	v_add_u32_e32 v9, 0xffffea08, v44
	v_cndmask_b32_e32 v8, v8, v9, vcc
	v_lshlrev_b32_e32 v9, 1, v8
	v_and_b32_e32 v9, 0xffffff00, v9
	v_cndmask_b32_e32 v18, 0, v83, vcc
	v_and_b32_e32 v8, 0x6f, v8
	v_or3_b32 v8, v8, v18, v9
	v_ashrrev_i32_e32 v9, 31, v8
	v_lshlrev_b64 v[8:9], 12, v[8:9]
	v_cvt_pk_bf16_f32 v5, v21, v23
	v_cvt_pk_bf16_f32 v6, v25, v27
	v_cvt_pk_bf16_f32 v7, v29, v35
	v_lshl_add_u64 v[8:9], v[36:37], 0, v[8:9]
	ds_read2_b32 v[18:19], v79 offset0:16 offset1:24
	ds_read2_b32 v[20:21], v79 offset0:49 offset1:57
	ds_read2_b32 v[22:23], v79 offset0:82 offset1:90
	ds_read2_b32 v[24:25], v79 offset0:115 offset1:123
	ds_read2_b32 v[26:27], v79 offset0:148 offset1:156
	ds_read2_b32 v[28:29], v79 offset0:181 offset1:189
	ds_read2_b32 v[34:35], v79 offset0:214 offset1:222
	ds_read2_b32 v[42:43], v79 offset0:247 offset1:255
	global_store_dwordx4 v[8:9], v[4:7], off sc1
	v_add_u32_e32 v8, 16, v44
	v_add_u32_e32 v9, 0xffffea10, v44
	v_cmp_lt_i32_e32 vcc, s18, v8
	s_waitcnt lgkmcnt(6)
	v_cvt_pk_bf16_f32 v4, v18, v20
	s_waitcnt lgkmcnt(4)
	v_cvt_pk_bf16_f32 v5, v22, v24
	v_cndmask_b32_e32 v8, v8, v9, vcc
	v_lshlrev_b32_e32 v9, 1, v8
	v_and_b32_e32 v9, 0xffffff00, v9
	v_cndmask_b32_e32 v18, 0, v83, vcc
	v_and_b32_e32 v8, 0x77, v8
	v_or3_b32 v8, v8, v18, v9
	v_ashrrev_i32_e32 v9, 31, v8
	v_lshlrev_b64 v[8:9], 12, v[8:9]
	s_waitcnt lgkmcnt(2)
	v_cvt_pk_bf16_f32 v6, v26, v28
	s_waitcnt lgkmcnt(0)
	v_cvt_pk_bf16_f32 v7, v34, v42
	v_lshl_add_u64 v[8:9], v[36:37], 0, v[8:9]
	global_store_dwordx4 v[8:9], v[4:7], off sc1
	s_waitcnt vmcnt(4)
	v_mov_b64_e32 v[46:47], v[66:67]
	v_add_u32_e32 v85, s14, v85
	v_add_u32_e32 v4, 24, v44
	v_add_u32_e32 v5, 0xffffea18, v44
	v_cmp_lt_i32_e32 vcc, s18, v4
	v_cvt_pk_bf16_f32 v7, v35, v43
	v_mov_b64_e32 v[42:43], v[50:51]
	v_cndmask_b32_e32 v4, v4, v5, vcc
	v_lshlrev_b32_e32 v5, 1, v4
	v_and_b32_e32 v5, 0xffffff00, v5
	v_cndmask_b32_e32 v6, 0, v83, vcc
	v_and_b32_e32 v4, 0x7f, v4
	v_or3_b32 v8, v4, v6, v5
	v_ashrrev_i32_e32 v9, 31, v8
	v_lshlrev_b64 v[8:9], 12, v[8:9]
	v_cvt_pk_bf16_f32 v4, v19, v21
	v_cvt_pk_bf16_f32 v5, v23, v25
	v_cvt_pk_bf16_f32 v6, v27, v29
	v_lshl_add_u64 v[8:9], v[36:37], 0, v[8:9]
	global_store_dwordx4 v[8:9], v[4:7], off sc1
	s_waitcnt lgkmcnt(0)
	v_mov_b64_e32 v[20:21], v[16:17]
	v_mov_b64_e32 v[26:27], v[30:31]
	v_mov_b64_e32 v[6:7], v[10:11]
	v_mov_b64_e32 v[22:23], v[38:39]
	v_mov_b64_e32 v[34:35], v[58:59]
	s_add_i32 s20, s20, s14
	v_add_u32_e32 v77, s14, v77
	s_andn2_b64 vcc, exec, s[6:7]
	s_mov_b32 s19, s21
	v_mov_b64_e32 v[18:19], v[14:15]
	v_mov_b64_e32 v[8:9], v[12:13]
	v_mov_b64_e32 v[28:29], v[32:33]
	v_mov_b64_e32 v[24:25], v[40:41]
	v_mov_b64_e32 v[44:45], v[52:53]
	v_mov_b64_e32 v[36:37], v[60:61]
	v_mov_b64_e32 v[56:57], v[64:65]
	v_mov_b64_e32 v[48:49], v[68:69]
	v_mov_b32_e32 v76, v87
	v_mov_b32_e32 v78, v89
	v_mov_b32_e32 v80, v91
	v_mov_b32_e32 v82, v93
	v_mov_b32_e32 v84, v98
	v_mov_b32_e32 v86, v99
	v_mov_b32_e32 v88, v100
	s_waitcnt vmcnt(4)
	v_mov_b32_e32 v90, v3
	s_cbranch_vccz .LBB0_533

; #define LAS __attribute__((address_space(3)))
; __device__ __forceinline__ unsigned cvtpk(float lo, float hi) { f32x2 v = {lo, hi}; bf16x2_t b = __builtin_convertvector(v, bf16x2_t); return __builtin_bit_cast(unsigned, b); }
; __device__ __forceinline__ void witem_store(const WItem& w, int K, bf16_t* WT, int kvperm, LAS float* scr, int item, int nblk, int lane) {
;     ...
;     for (int i = 0; i < 8; ++i) { LAS float* d = scr + (8 * i + rr) * 33 + col; const float g = w.g[i]; d[0] = w.v[i].x * g; d[1] = w.v[i].y * g; d[2] = w.v[i].z * g; d[3] = w.v[i].w * g; }
;     asm volatile("s_waitcnt lgkmcnt(0)" ::: "memory");
;     const int c = lane & 7;
; #pragma unroll
;     for (int j = 0; j < 4; ++j) { const int n = (lane >> 3) + 8 * j; const LAS float* s = scr + (8 * c) * 33 + n;
;         u32x4 o; o.x = cvtpk(s[0 * 33], s[1 * 33]); o.y = cvtpk(s[2 * 33], s[3 * 33]); o.z = cvtpk(s[4 * 33], s[5 * 33]); o.w = cvtpk(s[6 * 33], s[7 * 33]);
;         int nr = n0 + n; if (kvperm == 1) { const int hh = nr >> 8, ww = nr & 255; nr = (ww < 128) ? hh * 128 + ww : 2048 + hh * 128 + (ww - 128); }
;         else if (kvperm == 2) { const int isv = nr >= 5632, f = isv ? nr - 5632 : nr; nr = (f >> 7) * 256 + isv * 128 + (f & 127); }
;         *(u32x4*)(WT + (size_t)nr * K + k0 + 8 * c) = o; }
;     asm volatile("s_waitcnt lgkmcnt(0)" ::: "memory");
.LBB0_663:
	v_pk_mul_f32 v[2:3], v[8:9], v[72:73] op_sel_hi:[1,0]
	ds_write2_b32 v87, v2, v3 offset1:1
	v_pk_mul_f32 v[2:3], v[10:11], v[72:73] op_sel_hi:[1,0]
	ds_write2_b32 v87, v2, v3 offset0:2 offset1:3
	v_pk_mul_f32 v[2:3], v[4:5], v[74:75] op_sel_hi:[1,0]
	v_add_u32_e32 v4, 0x420, v87
	ds_write2_b32 v4, v2, v3 offset1:1
	v_pk_mul_f32 v[2:3], v[6:7], v[74:75] op_sel_hi:[1,0]
	v_add_u32_e32 v4, 0x428, v87
	ds_write2_b32 v4, v2, v3 offset1:1
	v_pk_mul_f32 v[2:3], v[20:21], v[76:77] op_sel_hi:[1,0]
	v_add_u32_e32 v4, 0x840, v87
	ds_write2_b32 v4, v2, v3 offset1:1
	v_pk_mul_f32 v[2:3], v[22:23], v[76:77] op_sel_hi:[1,0]
	v_add_u32_e32 v4, 0x848, v87
	ds_write2_b32 v4, v2, v3 offset1:1
	v_pk_mul_f32 v[2:3], v[12:13], v[78:79] op_sel_hi:[1,0]
	v_add_u32_e32 v4, 0xc60, v87
	ds_write2_b32 v4, v2, v3 offset1:1
	v_pk_mul_f32 v[2:3], v[14:15], v[78:79] op_sel_hi:[1,0]
	v_add_u32_e32 v4, 0xc68, v87
	ds_write2_b32 v4, v2, v3 offset1:1
	v_pk_mul_f32 v[2:3], v[32:33], v[80:81] op_sel_hi:[1,0]
	v_add_u32_e32 v4, 0x1080, v87
	ds_write2_b32 v4, v2, v3 offset1:1
	v_pk_mul_f32 v[2:3], v[34:35], v[80:81] op_sel_hi:[1,0]
	v_add_u32_e32 v4, 0x1088, v87
	ds_write2_b32 v4, v2, v3 offset1:1
	v_pk_mul_f32 v[2:3], v[28:29], v[82:83] op_sel_hi:[1,0]
	v_add_u32_e32 v4, 0x14a0, v87
	ds_write2_b32 v4, v2, v3 offset1:1
	v_pk_mul_f32 v[2:3], v[30:31], v[82:83] op_sel_hi:[1,0]
	v_add_u32_e32 v4, 0x14a8, v87
	ds_write2_b32 v4, v2, v3 offset1:1
	v_pk_mul_f32 v[2:3], v[44:45], v[84:85] op_sel_hi:[1,0]
	v_add_u32_e32 v4, 0x18c0, v87
	s_mul_hi_i32 s10, s17, 0x66666667
	ds_write2_b32 v4, v2, v3 offset1:1
	v_pk_mul_f32 v[2:3], v[46:47], v[84:85] op_sel_hi:[1,0]
	v_add_u32_e32 v4, 0x18c8, v87
	s_lshr_b32 s11, s10, 31
	s_ashr_i32 s10, s10, 5
	ds_write2_b32 v4, v2, v3 offset1:1
	v_pk_mul_f32 v[2:3], v[36:37], v[86:87] op_sel_hi:[1,0]
	v_add_u32_e32 v4, 0x1ce0, v87
	s_add_i32 s17, s10, s11
	ds_write2_b32 v4, v2, v3 offset1:1
	v_pk_mul_f32 v[2:3], v[38:39], v[86:87] op_sel_hi:[1,0]
	v_add_u32_e32 v4, 0x1ce8, v87
	s_lshl_b32 s10, s17, 6
	ds_write2_b32 v4, v2, v3 offset1:1
	s_waitcnt lgkmcnt(0)
	s_ashr_i32 s11, s10, 31
	ds_read2_b32 v[6:7], v85 offset0:33 offset1:41
	ds_read2_b32 v[8:9], v85 offset1:8
	ds_read2_b32 v[10:11], v85 offset0:66 offset1:74
	ds_read2_b32 v[12:13], v85 offset0:99 offset1:107
	ds_read2_b32 v[14:15], v85 offset0:132 offset1:140
	ds_read2_b32 v[20:21], v85 offset0:165 offset1:173
	ds_read2_b32 v[22:23], v85 offset0:198 offset1:206
	ds_read2_b32 v[28:29], v85 offset0:231 offset1:239
	v_lshl_add_u64 v[30:31], s[10:11], 1, v[70:71]
	s_mul_i32 s10, s17, 0xfffff600
	s_add_i32 s10, s10, s18
	v_add_u32_e32 v32, s10, v94
	v_ashrrev_i32_e32 v33, 31, v32
	v_lshlrev_b64 v[34:35], 12, v[32:33]
	s_waitcnt lgkmcnt(6)
	v_cvt_pk_bf16_f32 v2, v8, v6
	s_waitcnt lgkmcnt(4)
	v_cvt_pk_bf16_f32 v3, v10, v12
	s_waitcnt lgkmcnt(2)
	v_cvt_pk_bf16_f32 v4, v14, v20
	s_waitcnt lgkmcnt(0)
	v_cvt_pk_bf16_f32 v5, v22, v28
	v_lshl_add_u64 v[34:35], v[30:31], 0, v[34:35]
	v_add_u32_e32 v6, 8, v32
	global_store_dwordx4 v[34:35], v[2:5], off sc1
	s_waitcnt vmcnt(3)
	v_mov_b64_e32 v[44:45], v[60:61]
	s_waitcnt vmcnt(2)
	v_mov_b64_e32 v[36:37], v[64:65]
	v_cvt_pk_bf16_f32 v2, v9, v7
	v_ashrrev_i32_e32 v7, 31, v6
	v_cvt_pk_bf16_f32 v3, v11, v13
	v_cvt_pk_bf16_f32 v4, v15, v21
	v_cvt_pk_bf16_f32 v5, v23, v29
	v_lshlrev_b64 v[6:7], 12, v[6:7]
	ds_read2_b32 v[8:9], v85 offset0:49 offset1:57
	ds_read2_b32 v[10:11], v85 offset0:16 offset1:24
	ds_read2_b32 v[12:13], v85 offset0:82 offset1:90
	ds_read2_b32 v[14:15], v85 offset0:115 offset1:123
	ds_read2_b32 v[20:21], v85 offset0:148 offset1:156
	ds_read2_b32 v[22:23], v85 offset0:181 offset1:189
	ds_read2_b32 v[28:29], v85 offset0:214 offset1:222
	ds_read2_b32 v[34:35], v85 offset0:247 offset1:255
	v_lshl_add_u64 v[6:7], v[30:31], 0, v[6:7]
	global_store_dwordx4 v[6:7], v[2:5], off sc1
	v_add_u32_e32 v6, 16, v32
	v_ashrrev_i32_e32 v7, 31, v6
	v_lshlrev_b64 v[6:7], 12, v[6:7]
	s_waitcnt lgkmcnt(6)
	v_cvt_pk_bf16_f32 v2, v10, v8
	s_waitcnt lgkmcnt(4)
	v_cvt_pk_bf16_f32 v3, v12, v14
	s_waitcnt lgkmcnt(2)
	v_cvt_pk_bf16_f32 v4, v20, v22
	s_waitcnt lgkmcnt(0)
	v_cvt_pk_bf16_f32 v5, v28, v34
	v_lshl_add_u64 v[6:7], v[30:31], 0, v[6:7]
	global_store_dwordx4 v[6:7], v[2:5], off sc1
	v_add_u32_e32 v6, 24, v32
	v_ashrrev_i32_e32 v7, 31, v6
	v_lshlrev_b64 v[6:7], 12, v[6:7]
	v_cvt_pk_bf16_f32 v2, v11, v9
	v_cvt_pk_bf16_f32 v3, v13, v15
	v_cvt_pk_bf16_f32 v4, v21, v23
	v_cvt_pk_bf16_f32 v5, v29, v35
	v_lshl_add_u64 v[6:7], v[30:31], 0, v[6:7]
	global_store_dwordx4 v[6:7], v[2:5], off sc1
	s_waitcnt lgkmcnt(0)
	v_mov_b64_e32 v[8:9], v[24:25]
	v_mov_b64_e32 v[20:21], v[40:41]
	v_mov_b64_e32 v[4:5], v[16:17]
	v_mov_b64_e32 v[12:13], v[48:49]
	v_mov_b64_e32 v[32:33], v[52:53]
	v_mov_b64_e32 v[28:29], v[56:57]
	v_add_u32_e32 v94, s19, v94
	s_add_i32 s23, s23, s19
	v_add_u32_e32 v75, s19, v75
	s_andn2_b64 vcc, exec, s[8:9]
	s_mov_b32 s17, s24
	v_mov_b64_e32 v[10:11], v[26:27]
	v_mov_b64_e32 v[6:7], v[18:19]
	v_mov_b64_e32 v[22:23], v[42:43]
	v_mov_b64_e32 v[14:15], v[50:51]
	v_mov_b64_e32 v[34:35], v[54:55]
	v_mov_b64_e32 v[30:31], v[58:59]
	v_mov_b64_e32 v[46:47], v[62:63]
	v_mov_b64_e32 v[38:39], v[66:67]
	v_mov_b32_e32 v72, v89
	v_mov_b32_e32 v74, v95
	v_mov_b32_e32 v76, v96
	v_mov_b32_e32 v78, v97
	v_mov_b32_e32 v80, v98
	v_mov_b32_e32 v82, v99
	v_mov_b32_e32 v84, v100
	s_waitcnt vmcnt(4)
	v_mov_b32_e32 v86, v1
	s_cbranch_vccz .LBB0_681

; #define LAS __attribute__((address_space(3)))
; __device__ __forceinline__ unsigned cvtpk(float lo, float hi) { f32x2 v = {lo, hi}; bf16x2_t b = __builtin_convertvector(v, bf16x2_t); return __builtin_bit_cast(unsigned, b); }
; __device__ __forceinline__ void witem_store(const WItem& w, int K, bf16_t* WT, int kvperm, LAS float* scr, int item, int nblk, int lane) {
;     ...
; #pragma unroll
;     for (int j = 0; j < 4; ++j) { const int n = (lane >> 3) + 8 * j; const LAS float* s = scr + (8 * c) * 33 + n;
;         u32x4 o; o.x = cvtpk(s[0 * 33], s[1 * 33]); o.y = cvtpk(s[2 * 33], s[3 * 33]); o.z = cvtpk(s[4 * 33], s[5 * 33]); o.w = cvtpk(s[6 * 33], s[7 * 33]);
;         int nr = n0 + n; if (kvperm == 1) { const int hh = nr >> 8, ww = nr & 255; nr = (ww < 128) ? hh * 128 + ww : 2048 + hh * 128 + (ww - 128); }
;         else if (kvperm == 2) { const int isv = nr >= 5632, f = isv ? nr - 5632 : nr; nr = (f >> 7) * 256 + isv * 128 + (f & 127); }
;         *(u32x4*)(WT + (size_t)nr * K + k0 + 8 * c) = o; }
;     asm volatile("s_waitcnt lgkmcnt(0)" ::: "memory");
.LBB0_700:
	ds_write2_b32 v82, v4, v5 offset1:1
	ds_write2_b32 v82, v6, v7 offset0:2 offset1:3
	v_add_u32_e32 v4, 0x420, v82
	ds_write2_b32 v4, v0, v1 offset1:1
	v_add_u32_e32 v0, 0x428, v82
	ds_write2_b32 v0, v2, v3 offset1:1
	v_add_u32_e32 v0, 0x840, v82
	ds_write2_b32 v0, v12, v13 offset1:1
	v_add_u32_e32 v0, 0x848, v82
	ds_write2_b32 v0, v14, v15 offset1:1
	v_add_u32_e32 v0, 0xc60, v82
	ds_write2_b32 v0, v8, v9 offset1:1
	v_add_u32_e32 v0, 0xc68, v82
	ds_write2_b32 v0, v10, v11 offset1:1
	v_add_u32_e32 v0, 0x1080, v82
	ds_write2_b32 v0, v24, v25 offset1:1
	v_add_u32_e32 v0, 0x1088, v82
	ds_write2_b32 v0, v26, v27 offset1:1
	v_add_u32_e32 v0, 0x14a0, v82
	ds_write2_b32 v0, v20, v21 offset1:1
	v_add_u32_e32 v0, 0x14a8, v82
	ds_write2_b32 v0, v22, v23 offset1:1
	v_add_u32_e32 v0, 0x18c0, v82
	s_ashr_i32 s8, s16, 31
	ds_write2_b32 v0, v36, v37 offset1:1
	v_add_u32_e32 v0, 0x18c8, v82
	s_lshr_b32 s8, s8, 26
	ds_write2_b32 v0, v38, v39 offset1:1
	v_add_u32_e32 v0, 0x1ce0, v82
	s_add_i32 s16, s16, s8
	ds_write2_b32 v0, v40, v41 offset1:1
	v_add_u32_e32 v0, 0x1ce8, v82
	s_and_b32 s8, s16, 0xffffffc0
	ds_write2_b32 v0, v42, v43 offset1:1
	s_waitcnt lgkmcnt(0)
	s_ashr_i32 s9, s8, 31
	ds_read2_b32 v[4:5], v80 offset0:33 offset1:41
	ds_read2_b32 v[6:7], v80 offset1:8
	ds_read2_b32 v[8:9], v80 offset0:66 offset1:74
	ds_read2_b32 v[10:11], v80 offset0:99 offset1:107
	ds_read2_b32 v[12:13], v80 offset0:132 offset1:140
	ds_read2_b32 v[14:15], v80 offset0:165 offset1:173
	ds_read2_b32 v[18:19], v80 offset0:198 offset1:206
	ds_read2_b32 v[20:21], v80 offset0:231 offset1:239
	v_lshl_add_u64 v[22:23], s[8:9], 1, v[70:71]
	s_lshl_b32 s8, s16, 5
	s_waitcnt lgkmcnt(6)
	v_cvt_pk_bf16_f32 v0, v6, v4
	v_add_u32_e32 v4, s17, v83
	s_and_b32 s8, s8, 0xfffff800
	v_subrev_u32_e32 v24, s8, v4
	v_ashrrev_i32_e32 v25, 31, v24
	v_lshlrev_b64 v[26:27], 12, v[24:25]
	s_waitcnt lgkmcnt(4)
	v_cvt_pk_bf16_f32 v1, v8, v10
	s_waitcnt lgkmcnt(2)
	v_cvt_pk_bf16_f32 v2, v12, v14
	s_waitcnt lgkmcnt(0)
	v_cvt_pk_bf16_f32 v3, v18, v20
	v_lshl_add_u64 v[26:27], v[22:23], 0, v[26:27]
	v_add_u32_e32 v4, 8, v24
	global_store_dwordx4 v[26:27], v[0:3], off sc1
	s_waitcnt vmcnt(1)
	v_mov_b64_e32 v[36:37], v[60:61]
	v_add_u32_e32 v83, s18, v83
	v_cvt_pk_bf16_f32 v0, v7, v5
	v_ashrrev_i32_e32 v5, 31, v4
	v_cvt_pk_bf16_f32 v1, v9, v11
	v_cvt_pk_bf16_f32 v2, v13, v15
	v_cvt_pk_bf16_f32 v3, v19, v21
	v_lshlrev_b64 v[4:5], 12, v[4:5]
	ds_read2_b32 v[6:7], v80 offset0:49 offset1:57
	ds_read2_b32 v[8:9], v80 offset0:16 offset1:24
	ds_read2_b32 v[10:11], v80 offset0:82 offset1:90
	ds_read2_b32 v[12:13], v80 offset0:115 offset1:123
	ds_read2_b32 v[14:15], v80 offset0:148 offset1:156
	ds_read2_b32 v[18:19], v80 offset0:181 offset1:189
	ds_read2_b32 v[20:21], v80 offset0:214 offset1:222
	ds_read2_b32 v[26:27], v80 offset0:247 offset1:255
	v_lshl_add_u64 v[4:5], v[22:23], 0, v[4:5]
	global_store_dwordx4 v[4:5], v[0:3], off sc1
	v_add_u32_e32 v4, 16, v24
	v_ashrrev_i32_e32 v5, 31, v4
	v_lshlrev_b64 v[4:5], 12, v[4:5]
	s_waitcnt lgkmcnt(6)
	v_cvt_pk_bf16_f32 v0, v8, v6
	s_waitcnt lgkmcnt(4)
	v_cvt_pk_bf16_f32 v1, v10, v12
	s_waitcnt lgkmcnt(2)
	v_cvt_pk_bf16_f32 v2, v14, v18
	s_waitcnt lgkmcnt(0)
	v_cvt_pk_bf16_f32 v3, v20, v26
	v_lshl_add_u64 v[4:5], v[22:23], 0, v[4:5]
	global_store_dwordx4 v[4:5], v[0:3], off sc1
	v_add_u32_e32 v4, 24, v24
	v_ashrrev_i32_e32 v5, 31, v4
	v_lshlrev_b64 v[4:5], 12, v[4:5]
	v_cvt_pk_bf16_f32 v0, v9, v7
	v_cvt_pk_bf16_f32 v1, v11, v13
	v_cvt_pk_bf16_f32 v2, v15, v19
	v_cvt_pk_bf16_f32 v3, v21, v27
	v_lshl_add_u64 v[4:5], v[22:23], 0, v[4:5]
	global_store_dwordx4 v[4:5], v[0:3], off sc1
	s_waitcnt lgkmcnt(0)
	v_mov_b64_e32 v[4:5], v[32:33]
	v_mov_b64_e32 v[12:13], v[44:45]
	v_mov_b64_e32 v[0:1], v[28:29]
	v_mov_b64_e32 v[8:9], v[48:49]
	v_mov_b64_e32 v[24:25], v[52:53]
	v_mov_b64_e32 v[20:21], v[56:57]
	s_add_i32 s21, s21, s18
	v_add_u32_e32 v76, s18, v76
	s_andn2_b64 vcc, exec, s[6:7]
	s_mov_b32 s16, s22
	v_mov_b64_e32 v[6:7], v[34:35]
	v_mov_b64_e32 v[2:3], v[30:31]
	v_mov_b64_e32 v[14:15], v[46:47]
	v_mov_b64_e32 v[10:11], v[50:51]
	v_mov_b64_e32 v[26:27], v[54:55]
	v_mov_b64_e32 v[22:23], v[58:59]
	v_mov_b64_e32 v[38:39], v[62:63]
	v_mov_b32_e32 v40, v64
	v_mov_b32_e32 v41, v65
	v_mov_b32_e32 v42, v66
	v_mov_b32_e32 v43, v67
	s_cbranch_vccz .LBB0_718

; #define LAS __attribute__((address_space(3)))
; __device__ __forceinline__ unsigned cvtpk(float lo, float hi) { f32x2 v = {lo, hi}; bf16x2_t b = __builtin_convertvector(v, bf16x2_t); return __builtin_bit_cast(unsigned, b); }
; __device__ __forceinline__ void witem_store(const WItem& w, int K, bf16_t* WT, int kvperm, LAS float* scr, int item, int nblk, int lane) {
;     ...
;     for (int i = 0; i < 8; ++i) { LAS float* d = scr + (8 * i + rr) * 33 + col; const float g = w.g[i]; d[0] = w.v[i].x * g; d[1] = w.v[i].y * g; d[2] = w.v[i].z * g; d[3] = w.v[i].w * g; }
;     asm volatile("s_waitcnt lgkmcnt(0)" ::: "memory");
;     const int c = lane & 7;
; #pragma unroll
;     for (int j = 0; j < 4; ++j) { const int n = (lane >> 3) + 8 * j; const LAS float* s = scr + (8 * c) * 33 + n;
;         u32x4 o; o.x = cvtpk(s[0 * 33], s[1 * 33]); o.y = cvtpk(s[2 * 33], s[3 * 33]); o.z = cvtpk(s[4 * 33], s[5 * 33]); o.w = cvtpk(s[6 * 33], s[7 * 33]);
;         int nr = n0 + n; if (kvperm == 1) { const int hh = nr >> 8, ww = nr & 255; nr = (ww < 128) ? hh * 128 + ww : 2048 + hh * 128 + (ww - 128); }
;         else if (kvperm == 2) { const int isv = nr >= 5632, f = isv ? nr - 5632 : nr; nr = (f >> 7) * 256 + isv * 128 + (f & 127); }
;         *(u32x4*)(WT + (size_t)nr * K + k0 + 8 * c) = o; }
;     asm volatile("s_waitcnt lgkmcnt(0)" ::: "memory");
.LBB0_737:
	v_pk_mul_f32 v[2:3], v[16:17], v[72:73] op_sel_hi:[1,0]
	ds_write2_b32 v79, v2, v3 offset1:1
	v_pk_mul_f32 v[2:3], v[18:19], v[72:73] op_sel_hi:[1,0]
	ds_write2_b32 v79, v2, v3 offset0:2 offset1:3
	v_pk_mul_f32 v[2:3], v[4:5], v[74:75] op_sel_hi:[1,0]
	v_add_u32_e32 v4, 0x420, v79
	ds_write2_b32 v4, v2, v3 offset1:1
	v_pk_mul_f32 v[2:3], v[6:7], v[74:75] op_sel_hi:[1,0]
	v_add_u32_e32 v4, 0x428, v79
	ds_write2_b32 v4, v2, v3 offset1:1
	v_pk_mul_f32 v[2:3], v[24:25], v[76:77] op_sel_hi:[1,0]
	v_add_u32_e32 v4, 0x840, v79
	ds_write2_b32 v4, v2, v3 offset1:1
	v_pk_mul_f32 v[2:3], v[26:27], v[76:77] op_sel_hi:[1,0]
	v_add_u32_e32 v4, 0x848, v79
	ds_write2_b32 v4, v2, v3 offset1:1
	v_pk_mul_f32 v[2:3], v[20:21], v[78:79] op_sel_hi:[1,0]
	v_add_u32_e32 v4, 0xc60, v79
	ds_write2_b32 v4, v2, v3 offset1:1
	v_pk_mul_f32 v[2:3], v[22:23], v[78:79] op_sel_hi:[1,0]
	v_add_u32_e32 v4, 0xc68, v79
	ds_write2_b32 v4, v2, v3 offset1:1
	v_pk_mul_f32 v[2:3], v[36:37], v[80:81] op_sel_hi:[1,0]
	v_add_u32_e32 v4, 0x1080, v79
	ds_write2_b32 v4, v2, v3 offset1:1
	v_pk_mul_f32 v[2:3], v[38:39], v[80:81] op_sel_hi:[1,0]
	v_add_u32_e32 v4, 0x1088, v79
	ds_write2_b32 v4, v2, v3 offset1:1
	v_pk_mul_f32 v[2:3], v[32:33], v[82:83] op_sel_hi:[1,0]
	v_add_u32_e32 v4, 0x14a0, v79
	s_mul_hi_i32 s6, s11, 0x2e8ba2e9
	ds_write2_b32 v4, v2, v3 offset1:1
	v_pk_mul_f32 v[2:3], v[34:35], v[82:83] op_sel_hi:[1,0]
	v_add_u32_e32 v4, 0x14a8, v79
	s_lshr_b32 s7, s6, 31
	s_ashr_i32 s6, s6, 6
	ds_write2_b32 v4, v2, v3 offset1:1
	s_waitcnt vmcnt(7)
	v_pk_mul_f32 v[2:3], v[52:53], v[84:85] op_sel_hi:[1,0]
	v_add_u32_e32 v4, 0x18c0, v79
	s_add_i32 s11, s6, s7
	ds_write2_b32 v4, v2, v3 offset1:1
	v_pk_mul_f32 v[2:3], v[54:55], v[84:85] op_sel_hi:[1,0]
	v_add_u32_e32 v4, 0x18c8, v79
	s_lshl_b32 s6, s11, 6
	ds_write2_b32 v4, v2, v3 offset1:1
	s_waitcnt vmcnt(6)
	v_pk_mul_f32 v[2:3], v[44:45], v[86:87] op_sel_hi:[1,0]
	v_add_u32_e32 v4, 0x1ce0, v79
	ds_write2_b32 v4, v2, v3 offset1:1
	v_pk_mul_f32 v[2:3], v[46:47], v[86:87] op_sel_hi:[1,0]
	v_add_u32_e32 v4, 0x1ce8, v79
	s_ashr_i32 s7, s6, 31
	ds_write2_b32 v4, v2, v3 offset1:1
	v_lshl_add_u64 v[34:35], s[6:7], 1, v[70:71]
	s_mul_i32 s6, s11, 0xffffd400
	s_waitcnt lgkmcnt(0)
	s_add_i32 s6, s6, s8
	ds_read2_b32 v[6:7], v75 offset0:33 offset1:41
	ds_read2_b32 v[16:17], v75 offset1:8
	ds_read2_b32 v[18:19], v75 offset0:66 offset1:74
	ds_read2_b32 v[20:21], v75 offset0:99 offset1:107
	ds_read2_b32 v[22:23], v75 offset0:132 offset1:140
	ds_read2_b32 v[24:25], v75 offset0:165 offset1:173
	ds_read2_b32 v[26:27], v75 offset0:198 offset1:206
	ds_read2_b32 v[32:33], v75 offset0:231 offset1:239
	v_add_u32_e32 v38, s6, v83
	s_waitcnt lgkmcnt(6)
	v_cvt_pk_bf16_f32 v2, v16, v6
	v_add_u32_e32 v6, 0xffffea00, v38
	v_cmp_lt_i32_e32 vcc, s14, v38
	s_waitcnt lgkmcnt(4)
	v_cvt_pk_bf16_f32 v3, v18, v20
	s_waitcnt lgkmcnt(2)
	v_cvt_pk_bf16_f32 v4, v22, v24
	v_cndmask_b32_e32 v6, v38, v6, vcc
	v_lshlrev_b32_e32 v16, 1, v6
	v_and_b32_e32 v16, 0xffffff00, v16
	v_cndmask_b32_e32 v18, 0, v81, vcc
	v_and_b32_e32 v6, 0x67, v6
	v_or3_b32 v36, v6, v18, v16
	v_ashrrev_i32_e32 v37, 31, v36
	v_lshlrev_b64 v[36:37], 12, v[36:37]
	s_waitcnt lgkmcnt(0)
	v_cvt_pk_bf16_f32 v5, v26, v32
	v_lshl_add_u64 v[36:37], v[34:35], 0, v[36:37]
	v_add_u32_e32 v6, 8, v38
	global_store_dwordx4 v[36:37], v[2:5], off sc1
	v_cmp_lt_i32_e32 vcc, s14, v6
	s_waitcnt vmcnt(3)
	v_mov_b64_e32 v[52:53], v[60:61]
	v_cvt_pk_bf16_f32 v2, v17, v7
	v_add_u32_e32 v7, 0xffffea08, v38
	v_cndmask_b32_e32 v6, v6, v7, vcc
	v_lshlrev_b32_e32 v7, 1, v6
	v_and_b32_e32 v7, 0xffffff00, v7
	v_cndmask_b32_e32 v16, 0, v81, vcc
	v_and_b32_e32 v6, 0x6f, v6
	v_or3_b32 v6, v6, v16, v7
	v_ashrrev_i32_e32 v7, 31, v6
	v_lshlrev_b64 v[6:7], 12, v[6:7]
	v_cvt_pk_bf16_f32 v3, v19, v21
	v_cvt_pk_bf16_f32 v4, v23, v25
	v_cvt_pk_bf16_f32 v5, v27, v33
	v_lshl_add_u64 v[6:7], v[34:35], 0, v[6:7]
	ds_read2_b32 v[16:17], v75 offset0:16 offset1:24
	ds_read2_b32 v[18:19], v75 offset0:49 offset1:57
	ds_read2_b32 v[20:21], v75 offset0:82 offset1:90
	ds_read2_b32 v[22:23], v75 offset0:115 offset1:123
	ds_read2_b32 v[24:25], v75 offset0:148 offset1:156
	ds_read2_b32 v[26:27], v75 offset0:181 offset1:189
	ds_read2_b32 v[32:33], v75 offset0:214 offset1:222
	ds_read2_b32 v[36:37], v75 offset0:247 offset1:255
	global_store_dwordx4 v[6:7], v[2:5], off sc1
	v_add_u32_e32 v6, 16, v38
	v_add_u32_e32 v7, 0xffffea10, v38
	v_cmp_lt_i32_e32 vcc, s14, v6
	s_waitcnt lgkmcnt(6)
	v_cvt_pk_bf16_f32 v2, v16, v18
	s_waitcnt lgkmcnt(4)
	v_cvt_pk_bf16_f32 v3, v20, v22
	v_cndmask_b32_e32 v6, v6, v7, vcc
	v_lshlrev_b32_e32 v7, 1, v6
	v_and_b32_e32 v7, 0xffffff00, v7
	v_cndmask_b32_e32 v16, 0, v81, vcc
	v_and_b32_e32 v6, 0x77, v6
	v_or3_b32 v6, v6, v16, v7
	v_ashrrev_i32_e32 v7, 31, v6
	v_lshlrev_b64 v[6:7], 12, v[6:7]
	s_waitcnt lgkmcnt(2)
	v_cvt_pk_bf16_f32 v4, v24, v26
	s_waitcnt lgkmcnt(0)
	v_cvt_pk_bf16_f32 v5, v32, v36
	v_lshl_add_u64 v[6:7], v[34:35], 0, v[6:7]
	global_store_dwordx4 v[6:7], v[2:5], off sc1
	s_waitcnt vmcnt(4)
	v_mov_b64_e32 v[44:45], v[64:65]
	v_add_u32_e32 v83, s9, v83
	v_add_u32_e32 v2, 24, v38
	v_add_u32_e32 v3, 0xffffea18, v38
	v_cmp_lt_i32_e32 vcc, s14, v2
	v_cvt_pk_bf16_f32 v5, v33, v37
	v_mov_b64_e32 v[36:37], v[48:49]
	v_cndmask_b32_e32 v2, v2, v3, vcc
	v_lshlrev_b32_e32 v3, 1, v2
	v_and_b32_e32 v3, 0xffffff00, v3
	v_cndmask_b32_e32 v4, 0, v81, vcc
	v_and_b32_e32 v2, 0x7f, v2
	v_or3_b32 v6, v2, v4, v3
	v_ashrrev_i32_e32 v7, 31, v6
	v_lshlrev_b64 v[6:7], 12, v[6:7]
	v_cvt_pk_bf16_f32 v2, v17, v19
	v_cvt_pk_bf16_f32 v3, v21, v23
	v_cvt_pk_bf16_f32 v4, v25, v27
	v_lshl_add_u64 v[6:7], v[34:35], 0, v[6:7]
	global_store_dwordx4 v[6:7], v[2:5], off sc1
	s_waitcnt lgkmcnt(0)
	v_mov_b64_e32 v[18:19], v[14:15]
	v_mov_b64_e32 v[24:25], v[28:29]
	v_mov_b64_e32 v[4:5], v[8:9]
	v_mov_b64_e32 v[20:21], v[40:41]
	v_mov_b64_e32 v[32:33], v[56:57]
	s_add_i32 s15, s15, s9
	v_add_u32_e32 v73, s9, v73
	s_andn2_b64 vcc, exec, s[0:1]
	s_mov_b32 s11, s16
	v_mov_b64_e32 v[16:17], v[12:13]
	v_mov_b64_e32 v[6:7], v[10:11]
	v_mov_b64_e32 v[26:27], v[30:31]
	v_mov_b64_e32 v[22:23], v[42:43]
	v_mov_b64_e32 v[38:39], v[50:51]
	v_mov_b64_e32 v[34:35], v[58:59]
	v_mov_b64_e32 v[54:55], v[62:63]
	v_mov_b64_e32 v[46:47], v[66:67]
	v_mov_b32_e32 v72, v85
	v_mov_b32_e32 v74, v87
	v_mov_b32_e32 v76, v89
	v_mov_b32_e32 v78, v94
	v_mov_b32_e32 v80, v95
	v_mov_b32_e32 v82, v96
	v_mov_b32_e32 v84, v97
	s_waitcnt vmcnt(4)
	v_mov_b32_e32 v86, v1
	s_cbranch_vccz .LBB0_755

; __device__ __forceinline__ unsigned cvt_pk_bf16(float lo, float hi) { unsigned r; asm volatile("v_cvt_pk_bf16_f32 %0, %1, %2" : "=v"(r) : "v"(lo), "v"(hi)); return r; }
; __device__ __forceinline__ float row_ss(const float* part, int row, int fq, int nf4) {
;     const f32x4* p = (const f32x4*)(part + (size_t)row * 32);
;     float s = 0.f;
; #pragma unroll
;     for (int j = 0; j < 2; ++j) { const int idx = fq + 4 * j; if (idx < nf4) { const f32x4 v = p[idx]; s += (v[0] + v[1]) + (v[2] + v[3]); } }
;     s += __shfl_xor(s, 16); s += __shfl_xor(s, 32);
;     return s;
;     __device__ __forceinline__ void operator()(const f32x4 (&acc)[2][2][4][2], const Unit& u, int wr, int wc, int fr, int fq) const {
;     ...
;             for (int m = 0; m < 4; ++m) { const int row = row0 + ai * HALF + m * 16; bf16_t* rowp = base + (size_t)row * ldc + col0;
;                 const float rs = rss ? __builtin_amdgcn_rsqf(row_ss(rss, row, fq, nf4) * rinv + 1e-6f) : 1.f;
; #pragma unroll
;                 for (int bj = 0; bj < 2; ++bj) { f32x4 v0 = acc[ai][bj][m][0] * rs + bv[bj][0], v1 = acc[ai][bj][m][1] * rs + bv[bj][1];
;                     v0 = v0 * sc; v1 = v1 * sc; u32x4 w; w.x = cvt_pk_bf16(v0[0], v0[1]); w.y = cvt_pk_bf16(v0[2], v0[3]); w.z = cvt_pk_bf16(v1[0], v1[1]); w.w = cvt_pk_bf16(v1[2], v1[3]);
;                     *(u32x4*)(rowp + bj * HALF) = w; } }
.LBB0_823:
	s_or_b64 exec, exec, s[26:27]
	v_and_b32_e32 v149, 64, v156
	v_xor_b32_e32 v147, 16, v156
	v_add_u32_e32 v149, 64, v149
	v_cmp_lt_i32_e32 vcc, v147, v149
	v_xor_b32_e32 v160, 32, v156
	s_nop 0
	v_cndmask_b32_e32 v147, v156, v147, vcc
	v_lshlrev_b32_e32 v147, 2, v147
	ds_bpermute_b32 v158, v147, v148
	v_cmp_lt_i32_e32 vcc, v160, v149
	s_waitcnt lgkmcnt(0)
	v_add_f32_e32 v161, v148, v158
	v_cndmask_b32_e32 v148, v156, v160, vcc
	v_lshlrev_b32_e32 v158, 2, v148
	ds_bpermute_b32 v160, v158, v161
	v_lshl_or_b32 v148, s24, 8, v152
	v_ashrrev_i32_e32 v149, 31, v148
	v_lshl_add_u64 v[148:149], v[148:149], 1, s[8:9]
	v_mad_i64_i32 v[162:163], s[24:25], v146, s50, v[148:149]
	s_waitcnt lgkmcnt(0)
	v_add_f32_e32 v160, v161, v160
	v_fmamk_f32 v160, v160, 0x3b000000, v157
	v_rsq_f32_e32 v160, v160
	s_nop 0
	v_pk_fma_f32 v[124:125], v[124:125], v[160:161], 0 op_sel_hi:[1,0,0]
	v_pk_fma_f32 v[126:127], v[126:127], v[160:161], 0 op_sel_hi:[1,0,0]
	v_pk_fma_f32 v[120:121], v[120:121], v[160:161], 0 op_sel_hi:[1,0,0]
	v_pk_fma_f32 v[122:123], v[122:123], v[160:161], 0 op_sel_hi:[1,0,0]
	v_pk_mul_f32 v[126:127], v[126:127], s[14:15] op_sel_hi:[1,0]
	v_pk_mul_f32 v[124:125], v[124:125], s[14:15] op_sel_hi:[1,0]
	v_pk_mul_f32 v[164:165], v[122:123], s[14:15] op_sel_hi:[1,0]
	v_pk_mul_f32 v[122:123], v[120:121], s[14:15] op_sel_hi:[1,0]
	v_cvt_pk_bf16_f32 v120, v124, v125
	v_cvt_pk_bf16_f32 v121, v126, v127
	v_pk_fma_f32 v[116:117], v[116:117], v[160:161], 0 op_sel_hi:[1,0,0]
	v_pk_fma_f32 v[112:113], v[112:113], v[160:161], 0 op_sel_hi:[1,0,0]
	v_pk_fma_f32 v[114:115], v[114:115], v[160:161], 0 op_sel_hi:[1,0,0]
	v_cvt_pk_bf16_f32 v122, v122, v123
	v_cvt_pk_bf16_f32 v123, v164, v165
	global_store_dwordx4 v[162:163], v[120:123], off sc1
	v_pk_fma_f32 v[118:119], v[118:119], v[160:161], 0 op_sel_hi:[1,0,0]
	v_pk_mul_f32 v[116:117], v[116:117], s[14:15] op_sel_hi:[1,0]
	v_pk_mul_f32 v[120:121], v[114:115], s[14:15] op_sel_hi:[1,0]
	v_pk_mul_f32 v[114:115], v[112:113], s[14:15] op_sel_hi:[1,0]
	v_cvt_pk_bf16_f32 v112, v116, v117
	v_pk_mul_f32 v[118:119], v[118:119], s[14:15] op_sel_hi:[1,0]
	s_nop 0
	v_cvt_pk_bf16_f32 v113, v118, v119
	v_cvt_pk_bf16_f32 v114, v114, v115
	v_cvt_pk_bf16_f32 v115, v120, v121
	global_store_dwordx4 v[162:163], v[112:115], off offset:256 sc1
	s_nop 1
	v_or_b32_e32 v112, 16, v146
	v_ashrrev_i32_e32 v113, 31, v112
	s_and_saveexec_b64 s[24:25], s[4:5]
	s_cbranch_execz .LBB0_825
	v_lshlrev_b64 v[114:115], 7, v[112:113]
	v_lshl_add_u64 v[114:115], v[136:137], 0, v[114:115]
	global_load_dwordx4 v[114:117], v[114:115], off
	s_waitcnt vmcnt(0)
	v_mov_b32_e32 v118, v115
	v_mov_b32_e32 v119, v116
	v_mov_b32_e32 v115, v117
	v_pk_add_f32 v[114:115], v[118:119], v[114:115]
	s_nop 0
	v_add_f32_e32 v113, v114, v115
	v_add_f32_e32 v159, 0, v113
.LBB0_825:
	s_or_b64 exec, exec, s[24:25]
	ds_bpermute_b32 v113, v147, v159
	s_waitcnt lgkmcnt(0)
	v_add_f32_e32 v113, v159, v113
	ds_bpermute_b32 v114, v158, v113
	s_waitcnt lgkmcnt(0)
	v_add_f32_e32 v113, v113, v114
	v_fmamk_f32 v113, v113, 0x3b000000, v157
	v_rsq_f32_e32 v114, v113
	v_mad_i64_i32 v[112:113], s[24:25], v112, s50, v[148:149]
	v_pk_fma_f32 v[108:109], v[108:109], v[114:115], 0 op_sel_hi:[1,0,0]
	v_pk_fma_f32 v[110:111], v[110:111], v[114:115], 0 op_sel_hi:[1,0,0]
	v_pk_fma_f32 v[104:105], v[104:105], v[114:115], 0 op_sel_hi:[1,0,0]
	v_pk_fma_f32 v[106:107], v[106:107], v[114:115], 0 op_sel_hi:[1,0,0]
	v_pk_mul_f32 v[110:111], v[110:111], s[14:15] op_sel_hi:[1,0]
	v_pk_mul_f32 v[108:109], v[108:109], s[14:15] op_sel_hi:[1,0]
	v_pk_mul_f32 v[116:117], v[106:107], s[14:15] op_sel_hi:[1,0]
	v_pk_mul_f32 v[106:107], v[104:105], s[14:15] op_sel_hi:[1,0]
	v_cvt_pk_bf16_f32 v104, v108, v109
	v_cvt_pk_bf16_f32 v105, v110, v111
	v_pk_fma_f32 v[100:101], v[100:101], v[114:115], 0 op_sel_hi:[1,0,0]
	v_pk_fma_f32 v[96:97], v[96:97], v[114:115], 0 op_sel_hi:[1,0,0]
	v_pk_fma_f32 v[98:99], v[98:99], v[114:115], 0 op_sel_hi:[1,0,0]
	v_cvt_pk_bf16_f32 v106, v106, v107
	v_cvt_pk_bf16_f32 v107, v116, v117
	global_store_dwordx4 v[112:113], v[104:107], off sc1
	v_pk_fma_f32 v[102:103], v[102:103], v[114:115], 0 op_sel_hi:[1,0,0]
	v_pk_mul_f32 v[100:101], v[100:101], s[14:15] op_sel_hi:[1,0]
	v_pk_mul_f32 v[104:105], v[98:99], s[14:15] op_sel_hi:[1,0]
	v_pk_mul_f32 v[98:99], v[96:97], s[14:15] op_sel_hi:[1,0]
	v_cvt_pk_bf16_f32 v96, v100, v101
	v_pk_mul_f32 v[102:103], v[102:103], s[14:15] op_sel_hi:[1,0]
	s_nop 0
	v_cvt_pk_bf16_f32 v97, v102, v103
	v_cvt_pk_bf16_f32 v98, v98, v99
	v_cvt_pk_bf16_f32 v99, v104, v105
	global_store_dwordx4 v[112:113], v[96:99], off offset:256 sc1
	s_nop 1
	v_or_b32_e32 v96, 32, v146
	v_ashrrev_i32_e32 v97, 31, v96
	v_mov_b32_e32 v98, 0
	v_mov_b32_e32 v99, 0
	s_and_saveexec_b64 s[24:25], s[4:5]
	s_cbranch_execz .LBB0_827
	v_lshlrev_b64 v[100:101], 7, v[96:97]
	v_lshl_add_u64 v[100:101], v[136:137], 0, v[100:101]
	global_load_dwordx4 v[100:103], v[100:101], off
	s_waitcnt vmcnt(0)
	v_mov_b32_e32 v104, v101
	v_mov_b32_e32 v105, v102
	v_mov_b32_e32 v101, v103
	v_pk_add_f32 v[100:101], v[104:105], v[100:101]
	s_nop 0
	v_add_f32_e32 v97, v100, v101
	v_add_f32_e32 v99, 0, v97
; __device__ __forceinline__ unsigned cvt_pk_bf16(float lo, float hi) { unsigned r; asm volatile("v_cvt_pk_bf16_f32 %0, %1, %2" : "=v"(r) : "v"(lo), "v"(hi)); return r; }
; __device__ __forceinline__ float row_ss(const float* part, int row, int fq, int nf4) {
;     const f32x4* p = (const f32x4*)(part + (size_t)row * 32);
;     float s = 0.f;
; #pragma unroll
;     for (int j = 0; j < 2; ++j) { const int idx = fq + 4 * j; if (idx < nf4) { const f32x4 v = p[idx]; s += (v[0] + v[1]) + (v[2] + v[3]); } }
;     s += __shfl_xor(s, 16); s += __shfl_xor(s, 32);
;     return s;
;     __device__ __forceinline__ void operator()(const f32x4 (&acc)[2][2][4][2], const Unit& u, int wr, int wc, int fr, int fq) const {
;     ...
;             for (int m = 0; m < 4; ++m) { const int row = row0 + ai * HALF + m * 16; bf16_t* rowp = base + (size_t)row * ldc + col0;
;                 const float rs = rss ? __builtin_amdgcn_rsqf(row_ss(rss, row, fq, nf4) * rinv + 1e-6f) : 1.f;
; #pragma unroll
;                 for (int bj = 0; bj < 2; ++bj) { f32x4 v0 = acc[ai][bj][m][0] * rs + bv[bj][0], v1 = acc[ai][bj][m][1] * rs + bv[bj][1];
;                     v0 = v0 * sc; v1 = v1 * sc; u32x4 w; w.x = cvt_pk_bf16(v0[0], v0[1]); w.y = cvt_pk_bf16(v0[2], v0[3]); w.z = cvt_pk_bf16(v1[0], v1[1]); w.w = cvt_pk_bf16(v1[2], v1[3]);
;                     *(u32x4*)(rowp + bj * HALF) = w; } }
.LBB0_827:
	s_or_b64 exec, exec, s[24:25]
	ds_bpermute_b32 v97, v147, v99
	s_waitcnt lgkmcnt(0)
	v_add_f32_e32 v97, v99, v97
	ds_bpermute_b32 v99, v158, v97
	s_waitcnt lgkmcnt(0)
	v_add_f32_e32 v97, v97, v99
	v_fmamk_f32 v97, v97, 0x3b000000, v157
	v_rsq_f32_e32 v100, v97
	v_mad_i64_i32 v[96:97], s[24:25], v96, s50, v[148:149]
	v_pk_fma_f32 v[92:93], v[92:93], v[100:101], 0 op_sel_hi:[1,0,0]
	v_pk_fma_f32 v[94:95], v[94:95], v[100:101], 0 op_sel_hi:[1,0,0]
	v_pk_fma_f32 v[88:89], v[88:89], v[100:101], 0 op_sel_hi:[1,0,0]
	v_pk_fma_f32 v[90:91], v[90:91], v[100:101], 0 op_sel_hi:[1,0,0]
	v_pk_mul_f32 v[94:95], v[94:95], s[14:15] op_sel_hi:[1,0]
	v_pk_mul_f32 v[92:93], v[92:93], s[14:15] op_sel_hi:[1,0]
	v_pk_mul_f32 v[102:103], v[90:91], s[14:15] op_sel_hi:[1,0]
	v_pk_mul_f32 v[90:91], v[88:89], s[14:15] op_sel_hi:[1,0]
	v_cvt_pk_bf16_f32 v88, v92, v93
	v_cvt_pk_bf16_f32 v89, v94, v95
	v_pk_fma_f32 v[84:85], v[84:85], v[100:101], 0 op_sel_hi:[1,0,0]
	v_pk_fma_f32 v[80:81], v[80:81], v[100:101], 0 op_sel_hi:[1,0,0]
	v_pk_fma_f32 v[82:83], v[82:83], v[100:101], 0 op_sel_hi:[1,0,0]
	v_cvt_pk_bf16_f32 v90, v90, v91
	v_cvt_pk_bf16_f32 v91, v102, v103
	global_store_dwordx4 v[96:97], v[88:91], off sc1
	v_pk_fma_f32 v[86:87], v[86:87], v[100:101], 0 op_sel_hi:[1,0,0]
	v_pk_mul_f32 v[84:85], v[84:85], s[14:15] op_sel_hi:[1,0]
	v_pk_mul_f32 v[88:89], v[82:83], s[14:15] op_sel_hi:[1,0]
	v_pk_mul_f32 v[82:83], v[80:81], s[14:15] op_sel_hi:[1,0]
	v_cvt_pk_bf16_f32 v80, v84, v85
	v_pk_mul_f32 v[86:87], v[86:87], s[14:15] op_sel_hi:[1,0]
	s_nop 0
	v_cvt_pk_bf16_f32 v81, v86, v87
	v_cvt_pk_bf16_f32 v82, v82, v83
	v_cvt_pk_bf16_f32 v83, v88, v89
	global_store_dwordx4 v[96:97], v[80:83], off offset:256 sc1
	s_nop 1
	v_or_b32_e32 v80, 48, v146
	v_ashrrev_i32_e32 v81, 31, v80
	s_and_saveexec_b64 s[24:25], s[4:5]
	s_cbranch_execz .LBB0_829
	v_lshlrev_b64 v[82:83], 7, v[80:81]
	v_lshl_add_u64 v[82:83], v[136:137], 0, v[82:83]
	global_load_dwordx4 v[82:85], v[82:83], off
	s_waitcnt vmcnt(0)
	v_mov_b32_e32 v86, v83
	v_mov_b32_e32 v87, v84
	v_mov_b32_e32 v83, v85
	v_pk_add_f32 v[82:83], v[86:87], v[82:83]
	s_nop 0
	v_add_f32_e32 v81, v82, v83
	v_add_f32_e32 v98, 0, v81
.LBB0_829:
	s_or_b64 exec, exec, s[24:25]
	ds_bpermute_b32 v81, v147, v98
	s_waitcnt lgkmcnt(0)
	v_add_f32_e32 v81, v98, v81
	ds_bpermute_b32 v82, v158, v81
	s_waitcnt lgkmcnt(0)
	v_add_f32_e32 v81, v81, v82
	v_fmamk_f32 v81, v81, 0x3b000000, v157
	v_rsq_f32_e32 v82, v81
	v_mad_i64_i32 v[80:81], s[24:25], v80, s50, v[148:149]
	v_pk_fma_f32 v[76:77], v[76:77], v[82:83], 0 op_sel_hi:[1,0,0]
	v_pk_fma_f32 v[78:79], v[78:79], v[82:83], 0 op_sel_hi:[1,0,0]
	v_pk_fma_f32 v[72:73], v[72:73], v[82:83], 0 op_sel_hi:[1,0,0]
	v_pk_fma_f32 v[74:75], v[74:75], v[82:83], 0 op_sel_hi:[1,0,0]
	v_pk_mul_f32 v[78:79], v[78:79], s[14:15] op_sel_hi:[1,0]
	v_pk_mul_f32 v[76:77], v[76:77], s[14:15] op_sel_hi:[1,0]
	v_pk_mul_f32 v[84:85], v[74:75], s[14:15] op_sel_hi:[1,0]
	v_pk_mul_f32 v[74:75], v[72:73], s[14:15] op_sel_hi:[1,0]
	v_cvt_pk_bf16_f32 v72, v76, v77
	v_cvt_pk_bf16_f32 v73, v78, v79
	v_pk_fma_f32 v[68:69], v[68:69], v[82:83], 0 op_sel_hi:[1,0,0]
	v_pk_fma_f32 v[64:65], v[64:65], v[82:83], 0 op_sel_hi:[1,0,0]
	v_pk_fma_f32 v[66:67], v[66:67], v[82:83], 0 op_sel_hi:[1,0,0]
	v_cvt_pk_bf16_f32 v74, v74, v75
	v_cvt_pk_bf16_f32 v75, v84, v85
	global_store_dwordx4 v[80:81], v[72:75], off sc1
	v_pk_fma_f32 v[70:71], v[70:71], v[82:83], 0 op_sel_hi:[1,0,0]
	v_pk_mul_f32 v[68:69], v[68:69], s[14:15] op_sel_hi:[1,0]
	v_pk_mul_f32 v[72:73], v[66:67], s[14:15] op_sel_hi:[1,0]
	v_pk_mul_f32 v[66:67], v[64:65], s[14:15] op_sel_hi:[1,0]
	v_cvt_pk_bf16_f32 v64, v68, v69
	v_pk_mul_f32 v[70:71], v[70:71], s[14:15] op_sel_hi:[1,0]
	s_nop 0
	v_cvt_pk_bf16_f32 v65, v70, v71
	v_cvt_pk_bf16_f32 v66, v66, v67
	v_cvt_pk_bf16_f32 v67, v72, v73
	global_store_dwordx4 v[80:81], v[64:67], off offset:256 sc1
	s_nop 1
	v_add_u32_e32 v64, 0x80, v146
	v_ashrrev_i32_e32 v65, 31, v64
	v_mov_b32_e32 v66, 0
	v_mov_b32_e32 v67, 0
	s_and_saveexec_b64 s[24:25], s[4:5]
	s_cbranch_execz .LBB0_831
	v_lshlrev_b64 v[68:69], 7, v[64:65]
	v_lshl_add_u64 v[68:69], v[136:137], 0, v[68:69]
	global_load_dwordx4 v[68:71], v[68:69], off
	s_waitcnt vmcnt(0)
	v_mov_b32_e32 v72, v69
	v_mov_b32_e32 v73, v70
	v_mov_b32_e32 v69, v71
	v_pk_add_f32 v[68:69], v[72:73], v[68:69]
	s_nop 0
	v_add_f32_e32 v65, v68, v69
	v_add_f32_e32 v67, 0, v65
.LBB0_831:
	s_or_b64 exec, exec, s[24:25]
	ds_bpermute_b32 v65, v147, v67
	s_waitcnt lgkmcnt(0)
	v_add_f32_e32 v65, v67, v65
	ds_bpermute_b32 v67, v158, v65
	s_waitcnt lgkmcnt(0)
	v_add_f32_e32 v65, v65, v67
	v_fmamk_f32 v65, v65, 0x3b000000, v157
	v_rsq_f32_e32 v68, v65
	v_mad_i64_i32 v[64:65], s[24:25], v64, s50, v[148:149]
	v_pk_fma_f32 v[60:61], v[60:61], v[68:69], 0 op_sel_hi:[1,0,0]
	v_pk_fma_f32 v[62:63], v[62:63], v[68:69], 0 op_sel_hi:[1,0,0]
	v_pk_fma_f32 v[56:57], v[56:57], v[68:69], 0 op_sel_hi:[1,0,0]
	v_pk_fma_f32 v[58:59], v[58:59], v[68:69], 0 op_sel_hi:[1,0,0]
	v_pk_mul_f32 v[62:63], v[62:63], s[14:15] op_sel_hi:[1,0]
	v_pk_mul_f32 v[60:61], v[60:61], s[14:15] op_sel_hi:[1,0]
	v_pk_mul_f32 v[70:71], v[58:59], s[14:15] op_sel_hi:[1,0]
	v_pk_mul_f32 v[58:59], v[56:57], s[14:15] op_sel_hi:[1,0]
	v_cvt_pk_bf16_f32 v56, v60, v61
	v_cvt_pk_bf16_f32 v57, v62, v63
	v_pk_fma_f32 v[52:53], v[52:53], v[68:69], 0 op_sel_hi:[1,0,0]
	v_pk_fma_f32 v[48:49], v[48:49], v[68:69], 0 op_sel_hi:[1,0,0]
	v_pk_fma_f32 v[50:51], v[50:51], v[68:69], 0 op_sel_hi:[1,0,0]
	v_cvt_pk_bf16_f32 v58, v58, v59
	v_cvt_pk_bf16_f32 v59, v70, v71
	global_store_dwordx4 v[64:65], v[56:59], off sc1
	v_pk_fma_f32 v[54:55], v[54:55], v[68:69], 0 op_sel_hi:[1,0,0]
	v_pk_mul_f32 v[52:53], v[52:53], s[14:15] op_sel_hi:[1,0]
	v_pk_mul_f32 v[56:57], v[50:51], s[14:15] op_sel_hi:[1,0]
	v_pk_mul_f32 v[50:51], v[48:49], s[14:15] op_sel_hi:[1,0]
	v_cvt_pk_bf16_f32 v48, v52, v53
	v_pk_mul_f32 v[54:55], v[54:55], s[14:15] op_sel_hi:[1,0]
	s_nop 0
	v_cvt_pk_bf16_f32 v49, v54, v55
	v_cvt_pk_bf16_f32 v50, v50, v51
	v_cvt_pk_bf16_f32 v51, v56, v57
	global_store_dwordx4 v[64:65], v[48:51], off offset:256 sc1
	s_nop 1
	v_add_u32_e32 v48, 0x90, v146
	v_ashrrev_i32_e32 v49, 31, v48
	s_and_saveexec_b64 s[24:25], s[4:5]
	s_cbranch_execz .LBB0_833
	v_lshlrev_b64 v[50:51], 7, v[48:49]
	v_lshl_add_u64 v[50:51], v[136:137], 0, v[50:51]
	global_load_dwordx4 v[50:53], v[50:51], off
	s_waitcnt vmcnt(0)
	v_mov_b32_e32 v54, v51
	v_mov_b32_e32 v55, v52
	v_mov_b32_e32 v51, v53
	v_pk_add_f32 v[50:51], v[54:55], v[50:51]
	s_nop 0
	v_add_f32_e32 v49, v50, v51
	v_add_f32_e32 v66, 0, v49
; __device__ __forceinline__ unsigned cvt_pk_bf16(float lo, float hi) { unsigned r; asm volatile("v_cvt_pk_bf16_f32 %0, %1, %2" : "=v"(r) : "v"(lo), "v"(hi)); return r; }
; __device__ __forceinline__ float row_ss(const float* part, int row, int fq, int nf4) {
;     const f32x4* p = (const f32x4*)(part + (size_t)row * 32);
;     float s = 0.f;
; #pragma unroll
;     for (int j = 0; j < 2; ++j) { const int idx = fq + 4 * j; if (idx < nf4) { const f32x4 v = p[idx]; s += (v[0] + v[1]) + (v[2] + v[3]); } }
;     s += __shfl_xor(s, 16); s += __shfl_xor(s, 32);
;     return s;
;     __device__ __forceinline__ void operator()(const f32x4 (&acc)[2][2][4][2], const Unit& u, int wr, int wc, int fr, int fq) const {
;     ...
;             for (int m = 0; m < 4; ++m) { const int row = row0 + ai * HALF + m * 16; bf16_t* rowp = base + (size_t)row * ldc + col0;
;                 const float rs = rss ? __builtin_amdgcn_rsqf(row_ss(rss, row, fq, nf4) * rinv + 1e-6f) : 1.f;
; #pragma unroll
;                 for (int bj = 0; bj < 2; ++bj) { f32x4 v0 = acc[ai][bj][m][0] * rs + bv[bj][0], v1 = acc[ai][bj][m][1] * rs + bv[bj][1];
;                     v0 = v0 * sc; v1 = v1 * sc; u32x4 w; w.x = cvt_pk_bf16(v0[0], v0[1]); w.y = cvt_pk_bf16(v0[2], v0[3]); w.z = cvt_pk_bf16(v1[0], v1[1]); w.w = cvt_pk_bf16(v1[2], v1[3]);
;                     *(u32x4*)(rowp + bj * HALF) = w; } }
.LBB0_833:
	s_or_b64 exec, exec, s[24:25]
	ds_bpermute_b32 v49, v147, v66
	s_waitcnt lgkmcnt(0)
	v_add_f32_e32 v49, v66, v49
	ds_bpermute_b32 v50, v158, v49
	s_waitcnt lgkmcnt(0)
	v_add_f32_e32 v49, v49, v50
	v_fmamk_f32 v49, v49, 0x3b000000, v157
	v_rsq_f32_e32 v50, v49
	v_mad_i64_i32 v[48:49], s[24:25], v48, s50, v[148:149]
	v_pk_fma_f32 v[44:45], v[44:45], v[50:51], 0 op_sel_hi:[1,0,0]
	v_pk_fma_f32 v[46:47], v[46:47], v[50:51], 0 op_sel_hi:[1,0,0]
	v_pk_fma_f32 v[40:41], v[40:41], v[50:51], 0 op_sel_hi:[1,0,0]
	v_pk_fma_f32 v[42:43], v[42:43], v[50:51], 0 op_sel_hi:[1,0,0]
	v_pk_mul_f32 v[46:47], v[46:47], s[14:15] op_sel_hi:[1,0]
	v_pk_mul_f32 v[44:45], v[44:45], s[14:15] op_sel_hi:[1,0]
	v_pk_mul_f32 v[52:53], v[42:43], s[14:15] op_sel_hi:[1,0]
	v_pk_mul_f32 v[42:43], v[40:41], s[14:15] op_sel_hi:[1,0]
	v_cvt_pk_bf16_f32 v40, v44, v45
	v_cvt_pk_bf16_f32 v41, v46, v47
	v_pk_fma_f32 v[36:37], v[36:37], v[50:51], 0 op_sel_hi:[1,0,0]
	v_pk_fma_f32 v[32:33], v[32:33], v[50:51], 0 op_sel_hi:[1,0,0]
	v_pk_fma_f32 v[34:35], v[34:35], v[50:51], 0 op_sel_hi:[1,0,0]
	v_cvt_pk_bf16_f32 v42, v42, v43
	v_cvt_pk_bf16_f32 v43, v52, v53
	global_store_dwordx4 v[48:49], v[40:43], off sc1
	v_pk_fma_f32 v[38:39], v[38:39], v[50:51], 0 op_sel_hi:[1,0,0]
	v_pk_mul_f32 v[36:37], v[36:37], s[14:15] op_sel_hi:[1,0]
	v_pk_mul_f32 v[40:41], v[34:35], s[14:15] op_sel_hi:[1,0]
	v_pk_mul_f32 v[34:35], v[32:33], s[14:15] op_sel_hi:[1,0]
	v_cvt_pk_bf16_f32 v32, v36, v37
	v_pk_mul_f32 v[38:39], v[38:39], s[14:15] op_sel_hi:[1,0]
	s_nop 0
	v_cvt_pk_bf16_f32 v33, v38, v39
	v_cvt_pk_bf16_f32 v34, v34, v35
	v_cvt_pk_bf16_f32 v35, v40, v41
	global_store_dwordx4 v[48:49], v[32:35], off offset:256 sc1
	s_nop 1
	v_add_u32_e32 v32, 0xa0, v146
	v_ashrrev_i32_e32 v33, 31, v32
	v_mov_b32_e32 v34, 0
	v_mov_b32_e32 v35, 0
	s_and_saveexec_b64 s[24:25], s[4:5]
	s_cbranch_execz .LBB0_835
	v_lshlrev_b64 v[36:37], 7, v[32:33]
	v_lshl_add_u64 v[36:37], v[136:137], 0, v[36:37]
	global_load_dwordx4 v[36:39], v[36:37], off
	s_waitcnt vmcnt(0)
	v_mov_b32_e32 v40, v37
	v_mov_b32_e32 v41, v38
	v_mov_b32_e32 v37, v39
	v_pk_add_f32 v[36:37], v[40:41], v[36:37]
	s_nop 0
	v_add_f32_e32 v33, v36, v37
	v_add_f32_e32 v35, 0, v33
.LBB0_835:
	s_or_b64 exec, exec, s[24:25]
	ds_bpermute_b32 v33, v147, v35
	s_waitcnt lgkmcnt(0)
	v_add_f32_e32 v33, v35, v33
	ds_bpermute_b32 v35, v158, v33
	s_waitcnt lgkmcnt(0)
	v_add_f32_e32 v33, v33, v35
	v_fmamk_f32 v33, v33, 0x3b000000, v157
	v_rsq_f32_e32 v36, v33
	v_mad_i64_i32 v[32:33], s[24:25], v32, s50, v[148:149]
	v_pk_fma_f32 v[28:29], v[28:29], v[36:37], 0 op_sel_hi:[1,0,0]
	v_pk_fma_f32 v[30:31], v[30:31], v[36:37], 0 op_sel_hi:[1,0,0]
	v_pk_fma_f32 v[24:25], v[24:25], v[36:37], 0 op_sel_hi:[1,0,0]
	v_pk_fma_f32 v[26:27], v[26:27], v[36:37], 0 op_sel_hi:[1,0,0]
	v_pk_mul_f32 v[30:31], v[30:31], s[14:15] op_sel_hi:[1,0]
	v_pk_mul_f32 v[28:29], v[28:29], s[14:15] op_sel_hi:[1,0]
	v_pk_mul_f32 v[38:39], v[26:27], s[14:15] op_sel_hi:[1,0]
	v_pk_mul_f32 v[26:27], v[24:25], s[14:15] op_sel_hi:[1,0]
	v_cvt_pk_bf16_f32 v24, v28, v29
	v_cvt_pk_bf16_f32 v25, v30, v31
	v_pk_fma_f32 v[20:21], v[20:21], v[36:37], 0 op_sel_hi:[1,0,0]
	v_pk_fma_f32 v[16:17], v[16:17], v[36:37], 0 op_sel_hi:[1,0,0]
	v_pk_fma_f32 v[18:19], v[18:19], v[36:37], 0 op_sel_hi:[1,0,0]
	v_cvt_pk_bf16_f32 v26, v26, v27
	v_cvt_pk_bf16_f32 v27, v38, v39
	global_store_dwordx4 v[32:33], v[24:27], off sc1
	v_pk_fma_f32 v[22:23], v[22:23], v[36:37], 0 op_sel_hi:[1,0,0]
	v_pk_mul_f32 v[20:21], v[20:21], s[14:15] op_sel_hi:[1,0]
	v_pk_mul_f32 v[24:25], v[18:19], s[14:15] op_sel_hi:[1,0]
	v_pk_mul_f32 v[18:19], v[16:17], s[14:15] op_sel_hi:[1,0]
	v_cvt_pk_bf16_f32 v16, v20, v21
	v_pk_mul_f32 v[22:23], v[22:23], s[14:15] op_sel_hi:[1,0]
	s_nop 0
	v_cvt_pk_bf16_f32 v17, v22, v23
	v_cvt_pk_bf16_f32 v18, v18, v19
	v_cvt_pk_bf16_f32 v19, v24, v25
	global_store_dwordx4 v[32:33], v[16:19], off offset:256 sc1
	s_nop 1
	v_add_u32_e32 v16, 0xb0, v146
	v_ashrrev_i32_e32 v17, 31, v16
	s_and_saveexec_b64 s[24:25], s[4:5]
	s_cbranch_execz .LBB0_837
	v_lshlrev_b64 v[18:19], 7, v[16:17]
	v_lshl_add_u64 v[18:19], v[136:137], 0, v[18:19]
	global_load_dwordx4 v[18:21], v[18:19], off
	s_waitcnt vmcnt(0)
	v_mov_b32_e32 v22, v19
	v_mov_b32_e32 v23, v20
	v_mov_b32_e32 v19, v21
	v_pk_add_f32 v[18:19], v[22:23], v[18:19]
	s_nop 0
	v_add_f32_e32 v17, v18, v19
	v_add_f32_e32 v34, 0, v17
.LBB0_837:
	s_or_b64 exec, exec, s[24:25]
	ds_bpermute_b32 v17, v147, v34
	s_andn2_b64 vcc, exec, s[6:7]
	s_mov_b64 s[6:7], -1
	s_waitcnt lgkmcnt(0)
	v_add_f32_e32 v17, v34, v17
	ds_bpermute_b32 v18, v158, v17
	s_waitcnt lgkmcnt(0)
	v_add_f32_e32 v17, v17, v18
	v_fmamk_f32 v17, v17, 0x3b000000, v157
	v_rsq_f32_e32 v18, v17
	v_mad_i64_i32 v[16:17], s[24:25], v16, s50, v[148:149]
	v_pk_fma_f32 v[12:13], v[12:13], v[18:19], 0 op_sel_hi:[1,0,0]
	v_pk_fma_f32 v[14:15], v[14:15], v[18:19], 0 op_sel_hi:[1,0,0]
	v_pk_fma_f32 v[8:9], v[8:9], v[18:19], 0 op_sel_hi:[1,0,0]
	v_pk_fma_f32 v[10:11], v[10:11], v[18:19], 0 op_sel_hi:[1,0,0]
	v_pk_mul_f32 v[14:15], v[14:15], s[14:15] op_sel_hi:[1,0]
	v_pk_mul_f32 v[12:13], v[12:13], s[14:15] op_sel_hi:[1,0]
	v_pk_mul_f32 v[20:21], v[10:11], s[14:15] op_sel_hi:[1,0]
	v_pk_mul_f32 v[10:11], v[8:9], s[14:15] op_sel_hi:[1,0]
	v_cvt_pk_bf16_f32 v8, v12, v13
	v_cvt_pk_bf16_f32 v9, v14, v15
	v_pk_fma_f32 v[0:1], v[0:1], v[18:19], 0 op_sel_hi:[1,0,0]
	v_pk_fma_f32 v[2:3], v[2:3], v[18:19], 0 op_sel_hi:[1,0,0]
	v_cvt_pk_bf16_f32 v10, v10, v11
	v_cvt_pk_bf16_f32 v11, v20, v21
	global_store_dwordx4 v[16:17], v[8:11], off sc1
	v_pk_fma_f32 v[4:5], v[4:5], v[18:19], 0 op_sel_hi:[1,0,0]
	v_pk_fma_f32 v[6:7], v[6:7], v[18:19], 0 op_sel_hi:[1,0,0]
	v_pk_mul_f32 v[8:9], v[2:3], s[14:15] op_sel_hi:[1,0]
	v_pk_mul_f32 v[2:3], v[0:1], s[14:15] op_sel_hi:[1,0]
	v_pk_mul_f32 v[6:7], v[6:7], s[14:15] op_sel_hi:[1,0]
	v_pk_mul_f32 v[4:5], v[4:5], s[14:15] op_sel_hi:[1,0]
	s_nop 0
	v_cvt_pk_bf16_f32 v0, v4, v5
	v_cvt_pk_bf16_f32 v1, v6, v7
	v_cvt_pk_bf16_f32 v2, v2, v3
	v_cvt_pk_bf16_f32 v3, v8, v9
	global_store_dwordx4 v[16:17], v[0:3], off offset:256 sc1
	s_cbranch_vccnz .LBB0_814
	s_andn2_b64 vcc, exec, s[0:1]
	s_cbranch_vccnz .LBB0_813
	s_barrier
	s_branch .LBB0_813

; __device__ __forceinline__ unsigned cvt_pk_bf16(float lo, float hi) { unsigned r; asm volatile("v_cvt_pk_bf16_f32 %0, %1, %2" : "=v"(r) : "v"(lo), "v"(hi)); return r; }
; __device__ __forceinline__ float row_ss(const float* part, int row, int fq, int nf4) {
;     const f32x4* p = (const f32x4*)(part + (size_t)row * 32);
;     float s = 0.f;
; #pragma unroll
;     for (int j = 0; j < 2; ++j) { const int idx = fq + 4 * j; if (idx < nf4) { const f32x4 v = p[idx]; s += (v[0] + v[1]) + (v[2] + v[3]); } }
;     s += __shfl_xor(s, 16); s += __shfl_xor(s, 32);
;     return s;
;     __device__ __forceinline__ void operator()(const f32x4 (&acc)[2][2][4][2], const Unit& u, int wr, int wc, int fr, int fq) const {
;     ...
;         float sc = 1.f; if (split_cols) { const int t = colt / split_cols; base += (size_t)t * split_stride; colt -= t * split_cols; if (t == 0) sc = scale0; } else sc = scale0;
;         const int col0 = colt + wc * 32 + 8 * fq, bcol0 = u.pn * BM + wc * 32 + 8 * fq;
;     ...
;             for (int m = 0; m < 4; ++m) { const int row = row0 + ai * HALF + m * 16; bf16_t* rowp = base + (size_t)row * ldc + col0;
;                 const float rs = rss ? __builtin_amdgcn_rsqf(row_ss(rss, row, fq, nf4) * rinv + 1e-6f) : 1.f;
; #pragma unroll
;                 for (int bj = 0; bj < 2; ++bj) { f32x4 v0 = acc[ai][bj][m][0] * rs + bv[bj][0], v1 = acc[ai][bj][m][1] * rs + bv[bj][1];
;                     v0 = v0 * sc; v1 = v1 * sc; u32x4 w; w.x = cvt_pk_bf16(v0[0], v0[1]); w.y = cvt_pk_bf16(v0[2], v0[3]); w.z = cvt_pk_bf16(v1[0], v1[1]); w.w = cvt_pk_bf16(v1[2], v1[3]);
;                     *(u32x4*)(rowp + bj * HALF) = w; } }
.LBB0_865:
	s_or_b64 exec, exec, s[24:25]
	v_and_b32_e32 v158, 64, v156
	v_xor_b32_e32 v149, 16, v156
	v_add_u32_e32 v159, 64, v158
	v_cmp_lt_i32_e32 vcc, v149, v159
	s_ashr_i32 s6, s22, 31
	s_lshr_b32 s6, s6, 29
	v_cndmask_b32_e32 v149, v156, v149, vcc
	v_lshlrev_b32_e32 v158, 2, v149
	ds_bpermute_b32 v149, v158, v148
	s_add_i32 s6, s22, s6
	s_ashr_i32 s17, s6, 3
	s_lshl_b32 s15, s22, 8
	s_mul_i32 s6, s17, 0x3000000
	s_waitcnt lgkmcnt(0)
	v_add_f32_e32 v161, v148, v149
	v_xor_b32_e32 v148, 32, v156
	v_cmp_lt_i32_e32 vcc, v148, v159
	s_mul_hi_i32 s7, s17, 0x3000000
	s_add_u32 s6, s42, s6
	v_cndmask_b32_e32 v148, v156, v148, vcc
	v_lshlrev_b32_e32 v159, 2, v148
	ds_bpermute_b32 v162, v159, v161
	s_addc_u32 s7, s43, s7
	s_lshl_b32 s17, s17, 11
	s_sub_i32 s15, s15, s17
	v_or_b32_e32 v148, s15, v152
	s_waitcnt lgkmcnt(0)
	v_add_f32_e32 v161, v161, v162
	v_fmamk_f32 v161, v161, 0x3b000000, v157
	v_rsq_f32_e32 v162, v161
	v_ashrrev_i32_e32 v149, 31, v148
	v_lshl_add_u64 v[148:149], v[148:149], 1, s[6:7]
	v_lshlrev_b64 v[164:165], 12, v[146:147]
	v_lshl_add_u64 v[164:165], v[148:149], 0, v[164:165]
	v_pk_fma_f32 v[126:127], v[126:127], v[162:163], 0 op_sel_hi:[1,0,0]
	v_pk_fma_f32 v[124:125], v[124:125], v[162:163], 0 op_sel_hi:[1,0,0]
	v_pk_fma_f32 v[166:167], v[122:123], v[162:163], 0 op_sel_hi:[1,0,0]
	v_pk_fma_f32 v[122:123], v[120:121], v[162:163], 0 op_sel_hi:[1,0,0]
	v_cvt_pk_bf16_f32 v120, v124, v125
	v_cvt_pk_bf16_f32 v121, v126, v127
	v_pk_fma_f32 v[116:117], v[116:117], v[162:163], 0 op_sel_hi:[1,0,0]
	v_cvt_pk_bf16_f32 v122, v122, v123
	v_cvt_pk_bf16_f32 v123, v166, v167
	global_store_dwordx4 v[164:165], v[120:123], off sc1
	v_pk_fma_f32 v[118:119], v[118:119], v[162:163], 0 op_sel_hi:[1,0,0]
	s_nop 0
	v_pk_fma_f32 v[120:121], v[114:115], v[162:163], 0 op_sel_hi:[1,0,0]
	v_pk_fma_f32 v[114:115], v[112:113], v[162:163], 0 op_sel_hi:[1,0,0]
	v_cvt_pk_bf16_f32 v112, v116, v117
	v_cvt_pk_bf16_f32 v113, v118, v119
	s_nop 0
	v_cvt_pk_bf16_f32 v114, v114, v115
	v_cvt_pk_bf16_f32 v115, v120, v121
	global_store_dwordx4 v[164:165], v[112:115], off offset:256 sc1
	s_nop 1
	v_or_b32_e32 v112, 16, v146
	v_ashrrev_i32_e32 v113, 31, v112
	s_and_saveexec_b64 s[22:23], s[4:5]
	s_cbranch_execz .LBB0_867
	v_lshlrev_b64 v[114:115], 7, v[112:113]
	v_lshl_add_u64 v[114:115], v[136:137], 0, v[114:115]
	global_load_dwordx4 v[114:117], v[114:115], off
	s_waitcnt vmcnt(0)
	v_mov_b32_e32 v118, v115
	v_mov_b32_e32 v119, v116
	v_mov_b32_e32 v115, v117
	v_pk_add_f32 v[114:115], v[118:119], v[114:115]
	s_nop 0
	v_add_f32_e32 v114, v114, v115
	v_add_f32_e32 v160, 0, v114
.LBB0_867:
	s_or_b64 exec, exec, s[22:23]
	ds_bpermute_b32 v114, v158, v160
	v_lshlrev_b64 v[112:113], 12, v[112:113]
	v_lshl_add_u64 v[112:113], v[148:149], 0, v[112:113]
	s_waitcnt lgkmcnt(0)
	v_add_f32_e32 v114, v160, v114
	ds_bpermute_b32 v115, v159, v114
	s_waitcnt lgkmcnt(0)
	v_add_f32_e32 v114, v114, v115
	v_fmamk_f32 v114, v114, 0x3b000000, v157
	v_rsq_f32_e32 v114, v114
	s_nop 0
	v_pk_fma_f32 v[110:111], v[110:111], v[114:115], 0 op_sel_hi:[1,0,0]
	v_pk_fma_f32 v[108:109], v[108:109], v[114:115], 0 op_sel_hi:[1,0,0]
	v_pk_fma_f32 v[118:119], v[98:99], v[114:115], 0 op_sel_hi:[1,0,0]
	v_cvt_pk_bf16_f32 v98, v108, v109
	v_cvt_pk_bf16_f32 v99, v110, v111
	v_pk_fma_f32 v[106:107], v[106:107], v[114:115], 0 op_sel_hi:[1,0,0]
	v_pk_fma_f32 v[104:105], v[104:105], v[114:115], 0 op_sel_hi:[1,0,0]
	v_pk_fma_f32 v[116:117], v[100:101], v[114:115], 0 op_sel_hi:[1,0,0]
	v_cvt_pk_bf16_f32 v100, v104, v105
	v_cvt_pk_bf16_f32 v101, v106, v107
	global_store_dwordx4 v[112:113], v[98:101], off sc1
	v_pk_fma_f32 v[102:103], v[102:103], v[114:115], 0 op_sel_hi:[1,0,0]
	s_nop 0
	v_pk_fma_f32 v[98:99], v[96:97], v[114:115], 0 op_sel_hi:[1,0,0]
	v_cvt_pk_bf16_f32 v96, v116, v117
	v_cvt_pk_bf16_f32 v97, v102, v103
	s_nop 0
	v_cvt_pk_bf16_f32 v98, v98, v99
	v_cvt_pk_bf16_f32 v99, v118, v119
	global_store_dwordx4 v[112:113], v[96:99], off offset:256 sc1
	s_nop 1
	v_or_b32_e32 v96, 32, v146
	v_ashrrev_i32_e32 v97, 31, v96
	v_mov_b32_e32 v98, 0
	v_mov_b32_e32 v99, 0
	s_and_saveexec_b64 s[22:23], s[4:5]
	s_cbranch_execz .LBB0_869
	v_lshlrev_b64 v[100:101], 7, v[96:97]
	v_lshl_add_u64 v[100:101], v[136:137], 0, v[100:101]
	global_load_dwordx4 v[100:103], v[100:101], off
	s_waitcnt vmcnt(0)
	v_mov_b32_e32 v104, v101
	v_mov_b32_e32 v105, v102
	v_mov_b32_e32 v101, v103
	v_pk_add_f32 v[100:101], v[104:105], v[100:101]
	s_nop 0
	v_add_f32_e32 v99, v100, v101
	v_add_f32_e32 v99, 0, v99
.LBB0_869:
	s_or_b64 exec, exec, s[22:23]
	ds_bpermute_b32 v100, v158, v99
	v_lshlrev_b64 v[96:97], 12, v[96:97]
	v_lshl_add_u64 v[96:97], v[148:149], 0, v[96:97]
	s_waitcnt lgkmcnt(0)
	v_add_f32_e32 v99, v99, v100
	ds_bpermute_b32 v100, v159, v99
	s_waitcnt lgkmcnt(0)
	v_add_f32_e32 v99, v99, v100
	v_fmamk_f32 v99, v99, 0x3b000000, v157
	v_rsq_f32_e32 v100, v99
	s_nop 0
	v_pk_fma_f32 v[94:95], v[94:95], v[100:101], 0 op_sel_hi:[1,0,0]
	v_pk_fma_f32 v[92:93], v[92:93], v[100:101], 0 op_sel_hi:[1,0,0]
	v_pk_fma_f32 v[104:105], v[82:83], v[100:101], 0 op_sel_hi:[1,0,0]
	v_cvt_pk_bf16_f32 v82, v92, v93
	v_cvt_pk_bf16_f32 v83, v94, v95
	v_pk_fma_f32 v[90:91], v[90:91], v[100:101], 0 op_sel_hi:[1,0,0]
	v_pk_fma_f32 v[88:89], v[88:89], v[100:101], 0 op_sel_hi:[1,0,0]
	v_pk_fma_f32 v[102:103], v[84:85], v[100:101], 0 op_sel_hi:[1,0,0]
	v_cvt_pk_bf16_f32 v84, v88, v89
	v_cvt_pk_bf16_f32 v85, v90, v91
	global_store_dwordx4 v[96:97], v[82:85], off sc1
	v_pk_fma_f32 v[86:87], v[86:87], v[100:101], 0 op_sel_hi:[1,0,0]
	s_nop 0
	v_pk_fma_f32 v[82:83], v[80:81], v[100:101], 0 op_sel_hi:[1,0,0]
	v_cvt_pk_bf16_f32 v80, v102, v103
	v_cvt_pk_bf16_f32 v81, v86, v87
	s_nop 0
	v_cvt_pk_bf16_f32 v82, v82, v83
	v_cvt_pk_bf16_f32 v83, v104, v105
	global_store_dwordx4 v[96:97], v[80:83], off offset:256 sc1
	s_nop 1
	v_or_b32_e32 v80, 48, v146
	v_ashrrev_i32_e32 v81, 31, v80
	s_and_saveexec_b64 s[22:23], s[4:5]
	s_cbranch_execz .LBB0_871
	v_lshlrev_b64 v[82:83], 7, v[80:81]
	v_lshl_add_u64 v[82:83], v[136:137], 0, v[82:83]
	global_load_dwordx4 v[82:85], v[82:83], off
	s_waitcnt vmcnt(0)
	v_mov_b32_e32 v86, v83
	v_mov_b32_e32 v87, v84
	v_mov_b32_e32 v83, v85
	v_pk_add_f32 v[82:83], v[86:87], v[82:83]
	s_nop 0
	v_add_f32_e32 v82, v82, v83
	v_add_f32_e32 v98, 0, v82
; __device__ __forceinline__ unsigned cvt_pk_bf16(float lo, float hi) { unsigned r; asm volatile("v_cvt_pk_bf16_f32 %0, %1, %2" : "=v"(r) : "v"(lo), "v"(hi)); return r; }
; __device__ __forceinline__ float row_ss(const float* part, int row, int fq, int nf4) {
;     const f32x4* p = (const f32x4*)(part + (size_t)row * 32);
;     float s = 0.f;
; #pragma unroll
;     for (int j = 0; j < 2; ++j) { const int idx = fq + 4 * j; if (idx < nf4) { const f32x4 v = p[idx]; s += (v[0] + v[1]) + (v[2] + v[3]); } }
;     s += __shfl_xor(s, 16); s += __shfl_xor(s, 32);
;     return s;
;     __device__ __forceinline__ void operator()(const f32x4 (&acc)[2][2][4][2], const Unit& u, int wr, int wc, int fr, int fq) const {
;     ...
;             for (int m = 0; m < 4; ++m) { const int row = row0 + ai * HALF + m * 16; bf16_t* rowp = base + (size_t)row * ldc + col0;
;                 const float rs = rss ? __builtin_amdgcn_rsqf(row_ss(rss, row, fq, nf4) * rinv + 1e-6f) : 1.f;
; #pragma unroll
;                 for (int bj = 0; bj < 2; ++bj) { f32x4 v0 = acc[ai][bj][m][0] * rs + bv[bj][0], v1 = acc[ai][bj][m][1] * rs + bv[bj][1];
;                     v0 = v0 * sc; v1 = v1 * sc; u32x4 w; w.x = cvt_pk_bf16(v0[0], v0[1]); w.y = cvt_pk_bf16(v0[2], v0[3]); w.z = cvt_pk_bf16(v1[0], v1[1]); w.w = cvt_pk_bf16(v1[2], v1[3]);
;                     *(u32x4*)(rowp + bj * HALF) = w; } }
.LBB0_871:
	s_or_b64 exec, exec, s[22:23]
	ds_bpermute_b32 v82, v158, v98
	v_lshlrev_b64 v[80:81], 12, v[80:81]
	v_lshl_add_u64 v[80:81], v[148:149], 0, v[80:81]
	s_waitcnt lgkmcnt(0)
	v_add_f32_e32 v82, v98, v82
	ds_bpermute_b32 v83, v159, v82
	s_waitcnt lgkmcnt(0)
	v_add_f32_e32 v82, v82, v83
	v_fmamk_f32 v82, v82, 0x3b000000, v157
	v_rsq_f32_e32 v82, v82
	s_nop 0
	v_pk_fma_f32 v[78:79], v[78:79], v[82:83], 0 op_sel_hi:[1,0,0]
	v_pk_fma_f32 v[76:77], v[76:77], v[82:83], 0 op_sel_hi:[1,0,0]
	v_pk_fma_f32 v[86:87], v[66:67], v[82:83], 0 op_sel_hi:[1,0,0]
	v_cvt_pk_bf16_f32 v66, v76, v77
	v_cvt_pk_bf16_f32 v67, v78, v79
	v_pk_fma_f32 v[74:75], v[74:75], v[82:83], 0 op_sel_hi:[1,0,0]
	v_pk_fma_f32 v[72:73], v[72:73], v[82:83], 0 op_sel_hi:[1,0,0]
	v_pk_fma_f32 v[84:85], v[68:69], v[82:83], 0 op_sel_hi:[1,0,0]
	v_cvt_pk_bf16_f32 v68, v72, v73
	v_cvt_pk_bf16_f32 v69, v74, v75
	global_store_dwordx4 v[80:81], v[66:69], off sc1
	v_pk_fma_f32 v[70:71], v[70:71], v[82:83], 0 op_sel_hi:[1,0,0]
	s_nop 0
	v_pk_fma_f32 v[66:67], v[64:65], v[82:83], 0 op_sel_hi:[1,0,0]
	v_cvt_pk_bf16_f32 v64, v84, v85
	v_cvt_pk_bf16_f32 v65, v70, v71
	s_nop 0
	v_cvt_pk_bf16_f32 v66, v66, v67
	v_cvt_pk_bf16_f32 v67, v86, v87
	global_store_dwordx4 v[80:81], v[64:67], off offset:256 sc1
	s_nop 1
	v_add_u32_e32 v64, 0x80, v146
	v_ashrrev_i32_e32 v65, 31, v64
	v_mov_b32_e32 v66, 0
	v_mov_b32_e32 v67, 0
	s_and_saveexec_b64 s[22:23], s[4:5]
	s_cbranch_execz .LBB0_873
	v_lshlrev_b64 v[68:69], 7, v[64:65]
	v_lshl_add_u64 v[68:69], v[136:137], 0, v[68:69]
	global_load_dwordx4 v[68:71], v[68:69], off
	s_waitcnt vmcnt(0)
	v_mov_b32_e32 v72, v69
	v_mov_b32_e32 v73, v70
	v_mov_b32_e32 v69, v71
	v_pk_add_f32 v[68:69], v[72:73], v[68:69]
	s_nop 0
	v_add_f32_e32 v67, v68, v69
	v_add_f32_e32 v67, 0, v67
.LBB0_873:
	s_or_b64 exec, exec, s[22:23]
	ds_bpermute_b32 v68, v158, v67
	v_lshlrev_b64 v[64:65], 12, v[64:65]
	v_lshl_add_u64 v[64:65], v[148:149], 0, v[64:65]
	s_waitcnt lgkmcnt(0)
	v_add_f32_e32 v67, v67, v68
	ds_bpermute_b32 v68, v159, v67
	s_waitcnt lgkmcnt(0)
	v_add_f32_e32 v67, v67, v68
	v_fmamk_f32 v67, v67, 0x3b000000, v157
	v_rsq_f32_e32 v68, v67
	s_nop 0
	v_pk_fma_f32 v[62:63], v[62:63], v[68:69], 0 op_sel_hi:[1,0,0]
	v_pk_fma_f32 v[60:61], v[60:61], v[68:69], 0 op_sel_hi:[1,0,0]
	v_pk_fma_f32 v[72:73], v[50:51], v[68:69], 0 op_sel_hi:[1,0,0]
	v_cvt_pk_bf16_f32 v50, v60, v61
	v_cvt_pk_bf16_f32 v51, v62, v63
	v_pk_fma_f32 v[58:59], v[58:59], v[68:69], 0 op_sel_hi:[1,0,0]
	v_pk_fma_f32 v[56:57], v[56:57], v[68:69], 0 op_sel_hi:[1,0,0]
	v_pk_fma_f32 v[70:71], v[52:53], v[68:69], 0 op_sel_hi:[1,0,0]
	v_cvt_pk_bf16_f32 v52, v56, v57
	v_cvt_pk_bf16_f32 v53, v58, v59
	global_store_dwordx4 v[64:65], v[50:53], off sc1
	v_pk_fma_f32 v[54:55], v[54:55], v[68:69], 0 op_sel_hi:[1,0,0]
	s_nop 0
	v_pk_fma_f32 v[50:51], v[48:49], v[68:69], 0 op_sel_hi:[1,0,0]
	v_cvt_pk_bf16_f32 v48, v70, v71
	v_cvt_pk_bf16_f32 v49, v54, v55
	s_nop 0
	v_cvt_pk_bf16_f32 v50, v50, v51
	v_cvt_pk_bf16_f32 v51, v72, v73
	global_store_dwordx4 v[64:65], v[48:51], off offset:256 sc1
	s_nop 1
	v_add_u32_e32 v48, 0x90, v146
	v_ashrrev_i32_e32 v49, 31, v48
	s_and_saveexec_b64 s[22:23], s[4:5]
	s_cbranch_execz .LBB0_875
	v_lshlrev_b64 v[50:51], 7, v[48:49]
	v_lshl_add_u64 v[50:51], v[136:137], 0, v[50:51]
	global_load_dwordx4 v[50:53], v[50:51], off
	s_waitcnt vmcnt(0)
	v_mov_b32_e32 v54, v51
	v_mov_b32_e32 v55, v52
	v_mov_b32_e32 v51, v53
	v_pk_add_f32 v[50:51], v[54:55], v[50:51]
	s_nop 0
	v_add_f32_e32 v50, v50, v51
	v_add_f32_e32 v66, 0, v50
; __device__ __forceinline__ unsigned cvt_pk_bf16(float lo, float hi) { unsigned r; asm volatile("v_cvt_pk_bf16_f32 %0, %1, %2" : "=v"(r) : "v"(lo), "v"(hi)); return r; }
; __device__ __forceinline__ float row_ss(const float* part, int row, int fq, int nf4) {
;     const f32x4* p = (const f32x4*)(part + (size_t)row * 32);
;     float s = 0.f;
; #pragma unroll
;     for (int j = 0; j < 2; ++j) { const int idx = fq + 4 * j; if (idx < nf4) { const f32x4 v = p[idx]; s += (v[0] + v[1]) + (v[2] + v[3]); } }
;     s += __shfl_xor(s, 16); s += __shfl_xor(s, 32);
;     return s;
;     __device__ __forceinline__ void operator()(const f32x4 (&acc)[2][2][4][2], const Unit& u, int wr, int wc, int fr, int fq) const {
;     ...
;             for (int m = 0; m < 4; ++m) { const int row = row0 + ai * HALF + m * 16; bf16_t* rowp = base + (size_t)row * ldc + col0;
;                 const float rs = rss ? __builtin_amdgcn_rsqf(row_ss(rss, row, fq, nf4) * rinv + 1e-6f) : 1.f;
; #pragma unroll
;                 for (int bj = 0; bj < 2; ++bj) { f32x4 v0 = acc[ai][bj][m][0] * rs + bv[bj][0], v1 = acc[ai][bj][m][1] * rs + bv[bj][1];
;                     v0 = v0 * sc; v1 = v1 * sc; u32x4 w; w.x = cvt_pk_bf16(v0[0], v0[1]); w.y = cvt_pk_bf16(v0[2], v0[3]); w.z = cvt_pk_bf16(v1[0], v1[1]); w.w = cvt_pk_bf16(v1[2], v1[3]);
;                     *(u32x4*)(rowp + bj * HALF) = w; } }
.LBB0_875:
	s_or_b64 exec, exec, s[22:23]
	ds_bpermute_b32 v50, v158, v66
	v_lshlrev_b64 v[48:49], 12, v[48:49]
	v_lshl_add_u64 v[48:49], v[148:149], 0, v[48:49]
	s_waitcnt lgkmcnt(0)
	v_add_f32_e32 v50, v66, v50
	ds_bpermute_b32 v51, v159, v50
	s_waitcnt lgkmcnt(0)
	v_add_f32_e32 v50, v50, v51
	v_fmamk_f32 v50, v50, 0x3b000000, v157
	v_rsq_f32_e32 v50, v50
	s_nop 0
	v_pk_fma_f32 v[46:47], v[46:47], v[50:51], 0 op_sel_hi:[1,0,0]
	v_pk_fma_f32 v[44:45], v[44:45], v[50:51], 0 op_sel_hi:[1,0,0]
	v_pk_fma_f32 v[54:55], v[34:35], v[50:51], 0 op_sel_hi:[1,0,0]
	v_cvt_pk_bf16_f32 v34, v44, v45
	v_cvt_pk_bf16_f32 v35, v46, v47
	v_pk_fma_f32 v[42:43], v[42:43], v[50:51], 0 op_sel_hi:[1,0,0]
	v_pk_fma_f32 v[40:41], v[40:41], v[50:51], 0 op_sel_hi:[1,0,0]
	v_pk_fma_f32 v[52:53], v[36:37], v[50:51], 0 op_sel_hi:[1,0,0]
	v_cvt_pk_bf16_f32 v36, v40, v41
	v_cvt_pk_bf16_f32 v37, v42, v43
	global_store_dwordx4 v[48:49], v[34:37], off sc1
	v_pk_fma_f32 v[38:39], v[38:39], v[50:51], 0 op_sel_hi:[1,0,0]
	s_nop 0
	v_pk_fma_f32 v[34:35], v[32:33], v[50:51], 0 op_sel_hi:[1,0,0]
	v_cvt_pk_bf16_f32 v32, v52, v53
	v_cvt_pk_bf16_f32 v33, v38, v39
	s_nop 0
	v_cvt_pk_bf16_f32 v34, v34, v35
	v_cvt_pk_bf16_f32 v35, v54, v55
	global_store_dwordx4 v[48:49], v[32:35], off offset:256 sc1
	s_nop 1
	v_add_u32_e32 v32, 0xa0, v146
	v_ashrrev_i32_e32 v33, 31, v32
	v_mov_b32_e32 v34, 0
	v_mov_b32_e32 v35, 0
	s_and_saveexec_b64 s[22:23], s[4:5]
	s_cbranch_execz .LBB0_877
	v_lshlrev_b64 v[36:37], 7, v[32:33]
	v_lshl_add_u64 v[36:37], v[136:137], 0, v[36:37]
	global_load_dwordx4 v[36:39], v[36:37], off
	s_waitcnt vmcnt(0)
	v_mov_b32_e32 v40, v37
	v_mov_b32_e32 v41, v38
	v_mov_b32_e32 v37, v39
	v_pk_add_f32 v[36:37], v[40:41], v[36:37]
	s_nop 0
	v_add_f32_e32 v35, v36, v37
	v_add_f32_e32 v35, 0, v35
.LBB0_877:
	s_or_b64 exec, exec, s[22:23]
	ds_bpermute_b32 v36, v158, v35
	v_lshlrev_b64 v[32:33], 12, v[32:33]
	v_lshl_add_u64 v[32:33], v[148:149], 0, v[32:33]
	s_waitcnt lgkmcnt(0)
	v_add_f32_e32 v35, v35, v36
	ds_bpermute_b32 v36, v159, v35
	s_waitcnt lgkmcnt(0)
	v_add_f32_e32 v35, v35, v36
	v_fmamk_f32 v35, v35, 0x3b000000, v157
	v_rsq_f32_e32 v36, v35
	s_nop 0
	v_pk_fma_f32 v[30:31], v[30:31], v[36:37], 0 op_sel_hi:[1,0,0]
	v_pk_fma_f32 v[28:29], v[28:29], v[36:37], 0 op_sel_hi:[1,0,0]
	v_pk_fma_f32 v[40:41], v[18:19], v[36:37], 0 op_sel_hi:[1,0,0]
	v_cvt_pk_bf16_f32 v18, v28, v29
	v_cvt_pk_bf16_f32 v19, v30, v31
	v_pk_fma_f32 v[26:27], v[26:27], v[36:37], 0 op_sel_hi:[1,0,0]
	v_pk_fma_f32 v[24:25], v[24:25], v[36:37], 0 op_sel_hi:[1,0,0]
	v_pk_fma_f32 v[38:39], v[20:21], v[36:37], 0 op_sel_hi:[1,0,0]
	v_cvt_pk_bf16_f32 v20, v24, v25
	v_cvt_pk_bf16_f32 v21, v26, v27
	global_store_dwordx4 v[32:33], v[18:21], off sc1
	v_pk_fma_f32 v[22:23], v[22:23], v[36:37], 0 op_sel_hi:[1,0,0]
	s_nop 0
	v_pk_fma_f32 v[18:19], v[16:17], v[36:37], 0 op_sel_hi:[1,0,0]
	v_cvt_pk_bf16_f32 v16, v38, v39
	v_cvt_pk_bf16_f32 v17, v22, v23
	s_nop 0
	v_cvt_pk_bf16_f32 v18, v18, v19
	v_cvt_pk_bf16_f32 v19, v40, v41
	global_store_dwordx4 v[32:33], v[16:19], off offset:256 sc1
	s_nop 1
	v_add_u32_e32 v16, 0xb0, v146
	v_ashrrev_i32_e32 v17, 31, v16
	s_and_saveexec_b64 s[22:23], s[4:5]
	s_cbranch_execz .LBB0_879
	v_lshlrev_b64 v[18:19], 7, v[16:17]
	v_lshl_add_u64 v[18:19], v[136:137], 0, v[18:19]
	global_load_dwordx4 v[18:21], v[18:19], off
	s_waitcnt vmcnt(0)
	v_mov_b32_e32 v22, v19
	v_mov_b32_e32 v23, v20
	v_mov_b32_e32 v19, v21
	v_pk_add_f32 v[18:19], v[22:23], v[18:19]
	s_nop 0
	v_add_f32_e32 v18, v18, v19
	v_add_f32_e32 v34, 0, v18
.LBB0_879:
	s_or_b64 exec, exec, s[22:23]
	ds_bpermute_b32 v18, v158, v34
	v_lshlrev_b64 v[16:17], 12, v[16:17]
	v_lshl_add_u64 v[16:17], v[148:149], 0, v[16:17]
	s_andn2_b64 vcc, exec, s[8:9]
	s_mov_b64 s[8:9], -1
	s_waitcnt lgkmcnt(0)
	v_add_f32_e32 v18, v34, v18
	ds_bpermute_b32 v19, v159, v18
	s_waitcnt lgkmcnt(0)
	v_add_f32_e32 v18, v18, v19
	v_fmamk_f32 v18, v18, 0x3b000000, v157
	v_rsq_f32_e32 v18, v18
	s_nop 0
	v_pk_fma_f32 v[14:15], v[14:15], v[18:19], 0 op_sel_hi:[1,0,0]
	v_pk_fma_f32 v[12:13], v[12:13], v[18:19], 0 op_sel_hi:[1,0,0]
	v_pk_fma_f32 v[22:23], v[2:3], v[18:19], 0 op_sel_hi:[1,0,0]
	v_cvt_pk_bf16_f32 v2, v12, v13
	v_cvt_pk_bf16_f32 v3, v14, v15
	v_pk_fma_f32 v[10:11], v[10:11], v[18:19], 0 op_sel_hi:[1,0,0]
	v_pk_fma_f32 v[8:9], v[8:9], v[18:19], 0 op_sel_hi:[1,0,0]
	v_pk_fma_f32 v[20:21], v[4:5], v[18:19], 0 op_sel_hi:[1,0,0]
	v_cvt_pk_bf16_f32 v4, v8, v9
	v_cvt_pk_bf16_f32 v5, v10, v11
	global_store_dwordx4 v[16:17], v[2:5], off sc1
	v_pk_fma_f32 v[6:7], v[6:7], v[18:19], 0 op_sel_hi:[1,0,0]
	s_nop 0
	v_pk_fma_f32 v[2:3], v[0:1], v[18:19], 0 op_sel_hi:[1,0,0]
	v_cvt_pk_bf16_f32 v0, v20, v21
	v_cvt_pk_bf16_f32 v1, v6, v7
	s_nop 0
	v_cvt_pk_bf16_f32 v2, v2, v3
	v_cvt_pk_bf16_f32 v3, v22, v23
	global_store_dwordx4 v[16:17], v[0:3], off offset:256 sc1
	s_cbranch_vccnz .LBB0_852
	s_andn2_b64 vcc, exec, s[0:1]
	s_cbranch_vccnz .LBB0_851
	s_barrier
	s_branch .LBB0_851

; #define LAS __attribute__((address_space(3)))
; __device__ __forceinline__ unsigned cvtpk(float lo, float hi) { f32x2 v = {lo, hi}; bf16x2_t b = __builtin_convertvector(v, bf16x2_t); return __builtin_bit_cast(unsigned, b); }
; __device__ __forceinline__ void witem_store(const WItem& w, int K, bf16_t* WT, int kvperm, LAS float* scr, int item, int nblk, int lane) {
;     ...
; #pragma unroll
;     for (int j = 0; j < 4; ++j) { const int n = (lane >> 3) + 8 * j; const LAS float* s = scr + (8 * c) * 33 + n;
;         u32x4 o; o.x = cvtpk(s[0 * 33], s[1 * 33]); o.y = cvtpk(s[2 * 33], s[3 * 33]); o.z = cvtpk(s[4 * 33], s[5 * 33]); o.w = cvtpk(s[6 * 33], s[7 * 33]);
;         int nr = n0 + n; if (kvperm == 1) { const int hh = nr >> 8, ww = nr & 255; nr = (ww < 128) ? hh * 128 + ww : 2048 + hh * 128 + (ww - 128); }
;         else if (kvperm == 2) { const int isv = nr >= 5632, f = isv ? nr - 5632 : nr; nr = (f >> 7) * 256 + isv * 128 + (f & 127); }
;         *(u32x4*)(WT + (size_t)nr * K + k0 + 8 * c) = o; }
;     asm volatile("s_waitcnt lgkmcnt(0)" ::: "memory");
.LBB0_906:
	ds_write2_b32 v79, v4, v5 offset1:1
	ds_write2_b32 v79, v6, v7 offset0:2 offset1:3
	v_add_u32_e32 v4, 0x420, v79
	ds_write2_b32 v4, v0, v1 offset1:1
	v_add_u32_e32 v0, 0x428, v79
	ds_write2_b32 v0, v2, v3 offset1:1
	v_add_u32_e32 v0, 0x840, v79
	ds_write2_b32 v0, v12, v13 offset1:1
	v_add_u32_e32 v0, 0x848, v79
	ds_write2_b32 v0, v14, v15 offset1:1
	v_add_u32_e32 v0, 0xc60, v79
	ds_write2_b32 v0, v8, v9 offset1:1
	v_add_u32_e32 v0, 0xc68, v79
	ds_write2_b32 v0, v10, v11 offset1:1
	v_add_u32_e32 v0, 0x1080, v79
	ds_write2_b32 v0, v24, v25 offset1:1
	v_add_u32_e32 v0, 0x1088, v79
	ds_write2_b32 v0, v26, v27 offset1:1
	v_add_u32_e32 v0, 0x14a0, v79
	ds_write2_b32 v0, v20, v21 offset1:1
	v_add_u32_e32 v0, 0x14a8, v79
	ds_write2_b32 v0, v22, v23 offset1:1
	v_add_u32_e32 v0, 0x18c0, v79
	s_ashr_i32 s4, s6, 31
	ds_write2_b32 v0, v36, v37 offset1:1
	v_add_u32_e32 v0, 0x18c8, v79
	s_lshr_b32 s4, s4, 26
	ds_write2_b32 v0, v38, v39 offset1:1
	v_add_u32_e32 v0, 0x1ce0, v79
	s_add_i32 s6, s6, s4
	ds_write2_b32 v0, v40, v41 offset1:1
	v_add_u32_e32 v0, 0x1ce8, v79
	s_and_b32 s4, s6, 0xffffffc0
	ds_write2_b32 v0, v42, v43 offset1:1
	s_waitcnt lgkmcnt(0)
	s_ashr_i32 s5, s4, 31
	ds_read2_b32 v[4:5], v78 offset0:33 offset1:41
	ds_read2_b32 v[6:7], v78 offset1:8
	ds_read2_b32 v[8:9], v78 offset0:66 offset1:74
	ds_read2_b32 v[10:11], v78 offset0:99 offset1:107
	ds_read2_b32 v[12:13], v78 offset0:132 offset1:140
	ds_read2_b32 v[14:15], v78 offset0:165 offset1:173
	ds_read2_b32 v[18:19], v78 offset0:198 offset1:206
	ds_read2_b32 v[20:21], v78 offset0:231 offset1:239
	v_lshl_add_u64 v[22:23], s[4:5], 1, v[70:71]
	s_lshl_b32 s4, s6, 5
	s_waitcnt lgkmcnt(6)
	v_cvt_pk_bf16_f32 v0, v6, v4
	v_add_u32_e32 v4, s7, v80
	s_and_b32 s4, s4, 0xfffff800
	v_subrev_u32_e32 v24, s4, v4
	v_ashrrev_i32_e32 v25, 31, v24
	v_lshlrev_b64 v[26:27], 12, v[24:25]
	s_waitcnt lgkmcnt(4)
	v_cvt_pk_bf16_f32 v1, v8, v10
	s_waitcnt lgkmcnt(2)
	v_cvt_pk_bf16_f32 v2, v12, v14
	s_waitcnt lgkmcnt(0)
	v_cvt_pk_bf16_f32 v3, v18, v20
	v_lshl_add_u64 v[26:27], v[22:23], 0, v[26:27]
	v_add_u32_e32 v4, 8, v24
	global_store_dwordx4 v[26:27], v[0:3], off sc1
	s_waitcnt vmcnt(1)
	v_mov_b64_e32 v[36:37], v[60:61]
	v_add_u32_e32 v80, s8, v80
	v_cvt_pk_bf16_f32 v0, v7, v5
	v_ashrrev_i32_e32 v5, 31, v4
	v_cvt_pk_bf16_f32 v1, v9, v11
	v_cvt_pk_bf16_f32 v2, v13, v15
	v_cvt_pk_bf16_f32 v3, v19, v21
	v_lshlrev_b64 v[4:5], 12, v[4:5]
	ds_read2_b32 v[6:7], v78 offset0:49 offset1:57
	ds_read2_b32 v[8:9], v78 offset0:16 offset1:24
	ds_read2_b32 v[10:11], v78 offset0:82 offset1:90
	ds_read2_b32 v[12:13], v78 offset0:115 offset1:123
	ds_read2_b32 v[14:15], v78 offset0:148 offset1:156
	ds_read2_b32 v[18:19], v78 offset0:181 offset1:189
	ds_read2_b32 v[20:21], v78 offset0:214 offset1:222
	ds_read2_b32 v[26:27], v78 offset0:247 offset1:255
	v_lshl_add_u64 v[4:5], v[22:23], 0, v[4:5]
	global_store_dwordx4 v[4:5], v[0:3], off sc1
	v_add_u32_e32 v4, 16, v24
	v_ashrrev_i32_e32 v5, 31, v4
	v_lshlrev_b64 v[4:5], 12, v[4:5]
	s_waitcnt lgkmcnt(6)
	v_cvt_pk_bf16_f32 v0, v8, v6
	s_waitcnt lgkmcnt(4)
	v_cvt_pk_bf16_f32 v1, v10, v12
	s_waitcnt lgkmcnt(2)
	v_cvt_pk_bf16_f32 v2, v14, v18
	s_waitcnt lgkmcnt(0)
	v_cvt_pk_bf16_f32 v3, v20, v26
	v_lshl_add_u64 v[4:5], v[22:23], 0, v[4:5]
	global_store_dwordx4 v[4:5], v[0:3], off sc1
	v_add_u32_e32 v4, 24, v24
	v_ashrrev_i32_e32 v5, 31, v4
	v_lshlrev_b64 v[4:5], 12, v[4:5]
	v_cvt_pk_bf16_f32 v0, v9, v7
	v_cvt_pk_bf16_f32 v1, v11, v13
	v_cvt_pk_bf16_f32 v2, v15, v19
	v_cvt_pk_bf16_f32 v3, v21, v27
	v_lshl_add_u64 v[4:5], v[22:23], 0, v[4:5]
	global_store_dwordx4 v[4:5], v[0:3], off sc1
	s_waitcnt lgkmcnt(0)
	v_mov_b64_e32 v[4:5], v[32:33]
	v_mov_b64_e32 v[12:13], v[44:45]
	v_mov_b64_e32 v[0:1], v[28:29]
	v_mov_b64_e32 v[8:9], v[48:49]
	v_mov_b64_e32 v[24:25], v[52:53]
	v_mov_b64_e32 v[20:21], v[56:57]
	s_add_i32 s11, s11, s8
	v_add_u32_e32 v76, s8, v76
	s_andn2_b64 vcc, exec, s[0:1]
	s_mov_b32 s6, s12
	v_mov_b64_e32 v[6:7], v[34:35]
	v_mov_b64_e32 v[2:3], v[30:31]
	v_mov_b64_e32 v[14:15], v[46:47]
	v_mov_b64_e32 v[10:11], v[50:51]
	v_mov_b64_e32 v[26:27], v[54:55]
	v_mov_b64_e32 v[22:23], v[58:59]
	v_mov_b64_e32 v[38:39], v[62:63]
	v_mov_b32_e32 v40, v64
	v_mov_b32_e32 v41, v65
	v_mov_b32_e32 v42, v66
	v_mov_b32_e32 v43, v67
	s_cbranch_vccz .LBB0_924

; __device__ __forceinline__ unsigned cvt_pk_bf16(float lo, float hi) { unsigned r; asm volatile("v_cvt_pk_bf16_f32 %0, %1, %2" : "=v"(r) : "v"(lo), "v"(hi)); return r; }
;     __device__ __forceinline__ void operator()(const f32x4 (&acc)[2][2][4][2], const Unit& u, int wr, int wc, int fr, int fq) const {
;     ...
;         for (int ai = 0; ai < 2; ++ai) {
;             u32x4 old[4][2];
; #pragma unroll
;             for (int m = 0; m < 4; ++m)
; #pragma unroll
;                 for (int bj = 0; bj < 2; ++bj) old[m][bj] = *(const u32x4*)(HB + (size_t)(row0 + ai * HALF + m * 16) * ldc + col0 + bj * HALF);
; #pragma unroll
;             for (int m = 0; m < 4; ++m) { const int row = row0 + ai * HALF + m * 16; float ss = 0.f;
; #pragma unroll
;                 for (int bj = 0; bj < 2; ++bj) { const u32x4 ow = old[m][bj];
;                     f32x4 v0 = (acc[ai][bj][m][0] + bv[bj][0]) * accs, v1 = (acc[ai][bj][m][1] + bv[bj][1]) * accs;
;                     v0[0] += __uint_as_float(ow.x << 16); v0[1] += __uint_as_float(ow.x & 0xffff0000u); v0[2] += __uint_as_float(ow.y << 16); v0[3] += __uint_as_float(ow.y & 0xffff0000u);
;                     v1[0] += __uint_as_float(ow.z << 16); v1[1] += __uint_as_float(ow.z & 0xffff0000u); v1[2] += __uint_as_float(ow.w << 16); v1[3] += __uint_as_float(ow.w & 0xffff0000u);
;                     ss += (v0[0] * v0[0] + v0[1] * v0[1]) + (v0[2] * v0[2] + v0[3] * v0[3]) + (v1[0] * v1[0] + v1[1] * v1[1]) + (v1[2] * v1[2] + v1[3] * v1[3]);
;                     u32x4 w; w.x = cvt_pk_bf16(v0[0], v0[1]); w.y = cvt_pk_bf16(v0[2], v0[3]); w.z = cvt_pk_bf16(v1[0], v1[1]); w.w = cvt_pk_bf16(v1[2], v1[3]);
;                     *(u32x4*)(HB + (size_t)row * ldc + col0 + bj * HALF) = w; }
;                 ss += __shfl_xor(ss, 16); ss += __shfl_xor(ss, 32);
;                 if (fq == 0) ssp[(size_t)row * 32] = ss; }
.LBB0_1069:
	v_lshl_or_b32 v152, s24, 8, v166
	v_ashrrev_i32_e32 v153, 31, v152
	v_lshl_add_u32 v154, s26, 8, v164
	v_lshlrev_b64 v[180:181], 1, v[152:153]
	v_ashrrev_i32_e32 v155, 31, v154
	v_lshl_add_u64 v[156:157], s[4:5], 0, v[180:181]
	v_lshlrev_b64 v[182:183], 12, v[154:155]
	v_lshl_add_u64 v[128:129], v[156:157], 0, v[182:183]
	global_load_dwordx4 v[172:175], v[128:129], off
	global_load_dwordx4 v[176:179], v[128:129], off offset:256
	v_or_b32_e32 v162, 16, v154
	v_or_b32_e32 v160, 32, v154
	v_or_b32_e32 v158, 48, v154
	v_ashrrev_i32_e32 v163, 31, v162
	v_ashrrev_i32_e32 v161, 31, v160
	v_pk_add_f32 v[196:197], v[114:115], 0 op_sel_hi:[1,0]
	v_pk_add_f32 v[198:199], v[112:113], 0 op_sel_hi:[1,0]
	v_ashrrev_i32_e32 v159, 31, v158
	v_lshlrev_b64 v[112:113], 12, v[162:163]
	v_lshlrev_b64 v[114:115], 12, v[160:161]
	v_pk_add_f32 v[194:195], v[116:117], 0 op_sel_hi:[1,0]
	v_lshlrev_b64 v[116:117], 12, v[158:159]
	v_lshl_add_u64 v[112:113], v[156:157], 0, v[112:113]
	v_lshl_add_u64 v[114:115], v[156:157], 0, v[114:115]
	v_pk_add_f32 v[184:185], v[126:127], 0 op_sel_hi:[1,0]
	v_pk_add_f32 v[186:187], v[124:125], 0 op_sel_hi:[1,0]
	v_pk_add_f32 v[188:189], v[122:123], 0 op_sel_hi:[1,0]
	v_pk_add_f32 v[190:191], v[120:121], 0 op_sel_hi:[1,0]
	v_pk_add_f32 v[192:193], v[118:119], 0 op_sel_hi:[1,0]
	v_lshl_add_u64 v[200:201], v[156:157], 0, v[116:117]
	global_load_dwordx4 v[132:135], v[112:113], off
	global_load_dwordx4 v[128:131], v[112:113], off offset:256
	global_load_dwordx4 v[124:127], v[114:115], off
	global_load_dwordx4 v[120:123], v[114:115], off offset:256
	global_load_dwordx4 v[116:119], v[200:201], off
	s_nop 0
	global_load_dwordx4 v[112:115], v[200:201], off offset:256
	s_lshl_b32 s6, s24, 2
	s_or_b32 s6, s6, s46
	s_ashr_i32 s7, s6, 31
	s_lshl_b64 s[6:7], s[6:7], 2
	s_add_u32 s24, s44, s6
	s_addc_u32 s25, s45, s7
	s_waitcnt vmcnt(0)
	v_lshlrev_b32_e32 v171, 16, v172
	v_and_b32_e32 v172, 0xffff0000, v172
	v_lshlrev_b32_e32 v200, 16, v173
	v_and_b32_e32 v173, 0xffff0000, v173
	v_lshlrev_b32_e32 v201, 16, v174
	v_lshlrev_b32_e32 v202, 16, v175
	v_lshlrev_b32_e32 v203, 16, v176
	v_and_b32_e32 v176, 0xffff0000, v176
	v_lshlrev_b32_e32 v206, 16, v177
	v_and_b32_e32 v177, 0xffff0000, v177
	v_add_f32_e32 v172, v187, v172
	v_add_f32_e32 v173, v185, v173
	v_and_b32_e32 v175, 0xffff0000, v175
	v_lshlrev_b32_e32 v207, 16, v178
	v_and_b32_e32 v178, 0xffff0000, v178
	v_lshlrev_b32_e32 v208, 16, v179
	v_add_f32_e32 v171, v186, v171
	v_add_f32_e32 v184, v184, v200
	v_add_f32_e32 v185, v190, v201
	v_add_f32_e32 v186, v188, v202
	v_add_f32_e32 v188, v195, v176
	v_add_f32_e32 v190, v193, v177
	v_mul_f32_e32 v176, v172, v172
	v_mul_f32_e32 v177, v173, v173
	v_and_b32_e32 v174, 0xffff0000, v174
	v_add_f32_e32 v175, v189, v175
	v_add_f32_e32 v187, v194, v203
	v_add_f32_e32 v189, v192, v206
	v_add_f32_e32 v178, v199, v178
	v_add_f32_e32 v192, v196, v208
	v_mul_f32_e32 v195, v188, v188
	v_mul_f32_e32 v196, v190, v190
	v_fmac_f32_e32 v176, v171, v171
	v_fmac_f32_e32 v177, v184, v184
	v_and_b32_e32 v179, 0xffff0000, v179
	v_add_f32_e32 v174, v191, v174
	v_add_f32_e32 v191, v198, v207
	v_cvt_pk_bf16_f32 v172, v171, v172
	v_fmac_f32_e32 v195, v187, v187
	v_add_f32_e32 v171, v176, v177
	v_fmac_f32_e32 v196, v189, v189
	v_mul_f32_e32 v177, v178, v178
	v_add_f32_e32 v179, v197, v179
	v_mul_f32_e32 v193, v174, v174
	v_add_f32_e32 v176, v195, v196
	v_fmac_f32_e32 v177, v191, v191
	v_mul_f32_e32 v194, v175, v175
	v_fmac_f32_e32 v193, v185, v185
	v_add_f32_e32 v176, v177, v176
	v_mul_f32_e32 v177, v179, v179
	v_fmac_f32_e32 v194, v186, v186
	v_add_f32_e32 v171, v193, v171
	v_fmac_f32_e32 v177, v192, v192
	v_add_f32_e32 v171, v194, v171
	v_add_f32_e32 v176, v177, v176
	v_cvt_pk_bf16_f32 v173, v184, v173
	v_add_f32_e32 v184, v171, v176
	v_and_b32_e32 v176, 64, v170
	v_cvt_pk_bf16_f32 v174, v185, v174
	v_xor_b32_e32 v171, 16, v170
	v_add_u32_e32 v185, 64, v176
	v_cmp_lt_i32_e32 vcc, v171, v185
	v_cvt_pk_bf16_f32 v175, v186, v175
	v_lshl_add_u64 v[176:177], s[4:5], 0, v[182:183]
	v_lshl_add_u64 v[180:181], v[176:177], 0, v[180:181]
	v_cndmask_b32_e32 v171, v170, v171, vcc
	v_lshlrev_b32_e32 v171, 2, v171
	ds_bpermute_b32 v186, v171, v184
	global_store_dwordx4 v[180:181], v[172:175], off sc1
	v_cvt_pk_bf16_f32 v176, v187, v188
	v_cvt_pk_bf16_f32 v177, v189, v190
	v_cvt_pk_bf16_f32 v178, v191, v178
	v_cvt_pk_bf16_f32 v179, v192, v179
	global_store_dwordx4 v[180:181], v[176:179], off offset:256 sc1
	s_nop 0
	v_xor_b32_e32 v172, 32, v170
	v_cmp_lt_i32_e32 vcc, v172, v185
	s_waitcnt lgkmcnt(0)
	v_add_f32_e32 v173, v184, v186
	v_cndmask_b32_e32 v172, v170, v172, vcc
	v_lshlrev_b32_e32 v172, 2, v172
	ds_bpermute_b32 v174, v172, v173
	s_and_saveexec_b64 s[26:27], s[8:9]
	s_cbranch_execz .LBB0_1071
	v_lshlrev_b64 v[176:177], 7, v[154:155]
	v_lshl_add_u64 v[176:177], s[24:25], 0, v[176:177]
	s_waitcnt lgkmcnt(0)
	v_add_f32_e32 v155, v173, v174
	global_store_dword v[176:177], v155, off
; __device__ __forceinline__ unsigned cvt_pk_bf16(float lo, float hi) { unsigned r; asm volatile("v_cvt_pk_bf16_f32 %0, %1, %2" : "=v"(r) : "v"(lo), "v"(hi)); return r; }
;     __device__ __forceinline__ void operator()(const f32x4 (&acc)[2][2][4][2], const Unit& u, int wr, int wc, int fr, int fq) const {
;     ...
;             for (int m = 0; m < 4; ++m) { const int row = row0 + ai * HALF + m * 16; float ss = 0.f;
; #pragma unroll
;                 for (int bj = 0; bj < 2; ++bj) { const u32x4 ow = old[m][bj];
;                     f32x4 v0 = (acc[ai][bj][m][0] + bv[bj][0]) * accs, v1 = (acc[ai][bj][m][1] + bv[bj][1]) * accs;
;                     v0[0] += __uint_as_float(ow.x << 16); v0[1] += __uint_as_float(ow.x & 0xffff0000u); v0[2] += __uint_as_float(ow.y << 16); v0[3] += __uint_as_float(ow.y & 0xffff0000u);
;                     v1[0] += __uint_as_float(ow.z << 16); v1[1] += __uint_as_float(ow.z & 0xffff0000u); v1[2] += __uint_as_float(ow.w << 16); v1[3] += __uint_as_float(ow.w & 0xffff0000u);
;                     ss += (v0[0] * v0[0] + v0[1] * v0[1]) + (v0[2] * v0[2] + v0[3] * v0[3]) + (v1[0] * v1[0] + v1[1] * v1[1]) + (v1[2] * v1[2] + v1[3] * v1[3]);
;                     u32x4 w; w.x = cvt_pk_bf16(v0[0], v0[1]); w.y = cvt_pk_bf16(v0[2], v0[3]); w.z = cvt_pk_bf16(v1[0], v1[1]); w.w = cvt_pk_bf16(v1[2], v1[3]);
;                     *(u32x4*)(HB + (size_t)row * ldc + col0 + bj * HALF) = w; }
;                 ss += __shfl_xor(ss, 16); ss += __shfl_xor(ss, 32);
;                 if (fq == 0) ssp[(size_t)row * 32] = ss; }
.LBB0_1071:
	s_or_b64 exec, exec, s[26:27]
	v_pk_add_f32 v[108:109], v[108:109], 0 op_sel_hi:[1,0]
	v_lshlrev_b32_e32 v155, 16, v132
	v_and_b32_e32 v132, 0xffff0000, v132
	v_pk_add_f32 v[110:111], v[110:111], 0 op_sel_hi:[1,0]
	v_add_f32_e32 v109, v109, v132
	v_lshlrev_b32_e32 v132, 16, v133
	v_add_f32_e32 v110, v110, v132
	v_and_b32_e32 v132, 0xffff0000, v133
	v_pk_add_f32 v[104:105], v[104:105], 0 op_sel_hi:[1,0]
	v_add_f32_e32 v111, v111, v132
	v_lshlrev_b32_e32 v132, 16, v134
	v_add_f32_e32 v132, v104, v132
	v_and_b32_e32 v104, 0xffff0000, v134
	v_pk_add_f32 v[106:107], v[106:107], 0 op_sel_hi:[1,0]
	v_add_f32_e32 v133, v105, v104
	v_lshlrev_b32_e32 v104, 16, v135
	v_add_f32_e32 v134, v106, v104
	v_and_b32_e32 v104, 0xffff0000, v135
	v_add_f32_e32 v108, v108, v155
	v_add_f32_e32 v107, v107, v104
	v_mul_f32_e32 v104, v109, v109
	v_mul_f32_e32 v105, v111, v111
	v_fmac_f32_e32 v104, v108, v108
	v_fmac_f32_e32 v105, v110, v110
	v_add_f32_e32 v104, v104, v105
	v_mul_f32_e32 v105, v133, v133
	v_fmac_f32_e32 v105, v132, v132
	v_add_f32_e32 v104, v105, v104
	v_mul_f32_e32 v105, v107, v107
	v_fmac_f32_e32 v105, v134, v134
	v_add_f32_e32 v135, v105, v104
	v_cvt_pk_bf16_f32 v104, v108, v109
	v_pk_add_f32 v[100:101], v[100:101], 0 op_sel_hi:[1,0]
	v_lshlrev_b32_e32 v108, 16, v128
	v_add_f32_e32 v100, v100, v108
	v_and_b32_e32 v108, 0xffff0000, v128
	v_pk_add_f32 v[102:103], v[102:103], 0 op_sel_hi:[1,0]
	v_add_f32_e32 v101, v101, v108
	v_lshlrev_b32_e32 v108, 16, v129
	v_add_f32_e32 v108, v102, v108
	v_and_b32_e32 v102, 0xffff0000, v129
	v_pk_add_f32 v[96:97], v[96:97], 0 op_sel_hi:[1,0]
	v_add_f32_e32 v109, v103, v102
	v_lshlrev_b32_e32 v102, 16, v130
	v_cvt_pk_bf16_f32 v105, v110, v111
	v_add_f32_e32 v110, v96, v102
	v_and_b32_e32 v96, 0xffff0000, v130
	v_pk_add_f32 v[98:99], v[98:99], 0 op_sel_hi:[1,0]
	v_add_f32_e32 v111, v97, v96
	v_lshlrev_b32_e32 v96, 16, v131
	v_add_f32_e32 v128, v98, v96
	v_and_b32_e32 v96, 0xffff0000, v131
	v_add_f32_e32 v129, v99, v96
	v_mul_f32_e32 v96, v101, v101
	v_mul_f32_e32 v97, v109, v109
	v_fmac_f32_e32 v96, v100, v100
	v_fmac_f32_e32 v97, v108, v108
	v_add_f32_e32 v96, v96, v97
	v_mul_f32_e32 v97, v111, v111
	v_fmac_f32_e32 v97, v110, v110
	v_add_f32_e32 v96, v97, v96
	v_mul_f32_e32 v97, v129, v129
	v_fmac_f32_e32 v97, v128, v128
	v_add_f32_e32 v96, v97, v96
	v_add_f32_e32 v99, v135, v96
	ds_bpermute_b32 v130, v171, v99
	s_waitcnt lgkmcnt(1)
	v_lshlrev_b64 v[174:175], 11, v[162:163]
	v_lshl_add_u64 v[96:97], v[174:175], 1, s[4:5]
	v_lshl_add_u64 v[102:103], v[152:153], 1, v[96:97]
	v_cvt_pk_bf16_f32 v106, v132, v133
	s_waitcnt lgkmcnt(0)
	v_add_f32_e32 v96, v99, v130
	ds_bpermute_b32 v97, v172, v96
	v_cvt_pk_bf16_f32 v107, v134, v107
	global_store_dwordx4 v[102:103], v[104:107], off sc1
	v_cvt_pk_bf16_f32 v98, v100, v101
	v_cvt_pk_bf16_f32 v99, v108, v109
	v_cvt_pk_bf16_f32 v100, v110, v111
	v_cvt_pk_bf16_f32 v101, v128, v129
	global_store_dwordx4 v[102:103], v[98:101], off offset:256 sc1
	s_and_saveexec_b64 s[26:27], s[8:9]
	s_cbranch_execz .LBB0_1073
	v_lshlrev_b64 v[98:99], 7, v[162:163]
	v_lshl_add_u64 v[98:99], s[24:25], 0, v[98:99]
	s_waitcnt lgkmcnt(0)
	v_add_f32_e32 v96, v96, v97
	global_store_dword v[98:99], v96, off
.LBB0_1073:
	s_or_b64 exec, exec, s[26:27]
	v_pk_add_f32 v[92:93], v[92:93], 0 op_sel_hi:[1,0]
	v_lshlrev_b32_e32 v98, 16, v124
	v_add_f32_e32 v92, v92, v98
	v_and_b32_e32 v98, 0xffff0000, v124
	v_pk_add_f32 v[94:95], v[94:95], 0 op_sel_hi:[1,0]
	v_add_f32_e32 v93, v93, v98
	v_lshlrev_b32_e32 v98, 16, v125
	v_add_f32_e32 v94, v94, v98
	v_and_b32_e32 v98, 0xffff0000, v125
	v_pk_add_f32 v[88:89], v[88:89], 0 op_sel_hi:[1,0]
	v_add_f32_e32 v95, v95, v98
	v_lshlrev_b32_e32 v98, 16, v126
	v_add_f32_e32 v98, v88, v98
	v_and_b32_e32 v88, 0xffff0000, v126
	v_pk_add_f32 v[90:91], v[90:91], 0 op_sel_hi:[1,0]
	v_add_f32_e32 v99, v89, v88
	v_lshlrev_b32_e32 v88, 16, v127
	v_add_f32_e32 v100, v90, v88
	v_and_b32_e32 v88, 0xffff0000, v127
	v_add_f32_e32 v91, v91, v88
	v_mul_f32_e32 v88, v93, v93
	v_mul_f32_e32 v89, v95, v95
	v_fmac_f32_e32 v88, v92, v92
	v_fmac_f32_e32 v89, v94, v94
	v_add_f32_e32 v88, v88, v89
	v_mul_f32_e32 v89, v99, v99
	v_fmac_f32_e32 v89, v98, v98
	v_add_f32_e32 v88, v89, v88
	v_mul_f32_e32 v89, v91, v91
	v_fmac_f32_e32 v89, v100, v100
	v_add_f32_e32 v101, v89, v88
	v_cvt_pk_bf16_f32 v88, v92, v93
	v_pk_add_f32 v[84:85], v[84:85], 0 op_sel_hi:[1,0]
	v_lshlrev_b32_e32 v92, 16, v120
	v_add_f32_e32 v84, v84, v92
	v_and_b32_e32 v92, 0xffff0000, v120
	v_pk_add_f32 v[86:87], v[86:87], 0 op_sel_hi:[1,0]
	v_add_f32_e32 v85, v85, v92
	v_lshlrev_b32_e32 v92, 16, v121
	v_add_f32_e32 v92, v86, v92
	v_and_b32_e32 v86, 0xffff0000, v121
	v_pk_add_f32 v[80:81], v[80:81], 0 op_sel_hi:[1,0]
	v_add_f32_e32 v93, v87, v86
	v_lshlrev_b32_e32 v86, 16, v122
	v_cvt_pk_bf16_f32 v89, v94, v95
	v_add_f32_e32 v94, v80, v86
	v_and_b32_e32 v80, 0xffff0000, v122
	v_pk_add_f32 v[82:83], v[82:83], 0 op_sel_hi:[1,0]
	v_add_f32_e32 v95, v81, v80
	v_lshlrev_b32_e32 v80, 16, v123
	v_cvt_pk_bf16_f32 v90, v98, v99
	v_add_f32_e32 v98, v82, v80
	v_and_b32_e32 v80, 0xffff0000, v123
	v_add_f32_e32 v99, v83, v80
	v_mul_f32_e32 v80, v85, v85
	v_mul_f32_e32 v81, v93, v93
	v_fmac_f32_e32 v80, v84, v84
	v_fmac_f32_e32 v81, v92, v92
	v_add_f32_e32 v80, v80, v81
	v_mul_f32_e32 v81, v95, v95
	v_fmac_f32_e32 v81, v94, v94
	v_add_f32_e32 v80, v81, v80
	v_mul_f32_e32 v81, v99, v99
	v_fmac_f32_e32 v81, v98, v98
	v_add_f32_e32 v80, v81, v80
	v_add_f32_e32 v83, v101, v80
	v_cvt_pk_bf16_f32 v91, v100, v91
	ds_bpermute_b32 v100, v171, v83
	s_waitcnt lgkmcnt(1)
	v_lshlrev_b64 v[96:97], 11, v[160:161]
	v_lshl_add_u64 v[80:81], v[96:97], 1, s[4:5]
	v_lshl_add_u64 v[86:87], v[152:153], 1, v[80:81]
	global_store_dwordx4 v[86:87], v[88:91], off sc1
	s_waitcnt lgkmcnt(0)
	v_add_f32_e32 v80, v83, v100
	ds_bpermute_b32 v81, v172, v80
	v_cvt_pk_bf16_f32 v82, v84, v85
	v_cvt_pk_bf16_f32 v83, v92, v93
	v_cvt_pk_bf16_f32 v84, v94, v95
	v_cvt_pk_bf16_f32 v85, v98, v99
	global_store_dwordx4 v[86:87], v[82:85], off offset:256 sc1
	s_and_saveexec_b64 s[26:27], s[8:9]
	s_cbranch_execz .LBB0_1075
	v_lshlrev_b64 v[82:83], 7, v[160:161]
	v_lshl_add_u64 v[82:83], s[24:25], 0, v[82:83]
	s_waitcnt lgkmcnt(0)
	v_add_f32_e32 v80, v80, v81
	global_store_dword v[82:83], v80, off
; __device__ __forceinline__ unsigned cvt_pk_bf16(float lo, float hi) { unsigned r; asm volatile("v_cvt_pk_bf16_f32 %0, %1, %2" : "=v"(r) : "v"(lo), "v"(hi)); return r; }
;     __device__ __forceinline__ void operator()(const f32x4 (&acc)[2][2][4][2], const Unit& u, int wr, int wc, int fr, int fq) const {
;     ...
;         for (int ai = 0; ai < 2; ++ai) {
;             u32x4 old[4][2];
; #pragma unroll
;             for (int m = 0; m < 4; ++m)
; #pragma unroll
;                 for (int bj = 0; bj < 2; ++bj) old[m][bj] = *(const u32x4*)(HB + (size_t)(row0 + ai * HALF + m * 16) * ldc + col0 + bj * HALF);
; #pragma unroll
;             for (int m = 0; m < 4; ++m) { const int row = row0 + ai * HALF + m * 16; float ss = 0.f;
; #pragma unroll
;                 for (int bj = 0; bj < 2; ++bj) { const u32x4 ow = old[m][bj];
;                     f32x4 v0 = (acc[ai][bj][m][0] + bv[bj][0]) * accs, v1 = (acc[ai][bj][m][1] + bv[bj][1]) * accs;
;                     v0[0] += __uint_as_float(ow.x << 16); v0[1] += __uint_as_float(ow.x & 0xffff0000u); v0[2] += __uint_as_float(ow.y << 16); v0[3] += __uint_as_float(ow.y & 0xffff0000u);
;                     v1[0] += __uint_as_float(ow.z << 16); v1[1] += __uint_as_float(ow.z & 0xffff0000u); v1[2] += __uint_as_float(ow.w << 16); v1[3] += __uint_as_float(ow.w & 0xffff0000u);
;                     ss += (v0[0] * v0[0] + v0[1] * v0[1]) + (v0[2] * v0[2] + v0[3] * v0[3]) + (v1[0] * v1[0] + v1[1] * v1[1]) + (v1[2] * v1[2] + v1[3] * v1[3]);
;                     u32x4 w; w.x = cvt_pk_bf16(v0[0], v0[1]); w.y = cvt_pk_bf16(v0[2], v0[3]); w.z = cvt_pk_bf16(v1[0], v1[1]); w.w = cvt_pk_bf16(v1[2], v1[3]);
;                     *(u32x4*)(HB + (size_t)row * ldc + col0 + bj * HALF) = w; }
;                 ss += __shfl_xor(ss, 16); ss += __shfl_xor(ss, 32);
;                 if (fq == 0) ssp[(size_t)row * 32] = ss; }
.LBB0_1075:
	s_or_b64 exec, exec, s[26:27]
	v_pk_add_f32 v[76:77], v[76:77], 0 op_sel_hi:[1,0]
	v_lshlrev_b32_e32 v82, 16, v116
	v_add_f32_e32 v76, v76, v82
	v_and_b32_e32 v82, 0xffff0000, v116
	v_pk_add_f32 v[78:79], v[78:79], 0 op_sel_hi:[1,0]
	v_add_f32_e32 v77, v77, v82
	v_lshlrev_b32_e32 v82, 16, v117
	v_add_f32_e32 v78, v78, v82
	v_and_b32_e32 v82, 0xffff0000, v117
	v_pk_add_f32 v[72:73], v[72:73], 0 op_sel_hi:[1,0]
	v_add_f32_e32 v79, v79, v82
	v_lshlrev_b32_e32 v82, 16, v118
	v_add_f32_e32 v82, v72, v82
	v_and_b32_e32 v72, 0xffff0000, v118
	v_pk_add_f32 v[74:75], v[74:75], 0 op_sel_hi:[1,0]
	v_add_f32_e32 v83, v73, v72
	v_lshlrev_b32_e32 v72, 16, v119
	v_add_f32_e32 v84, v74, v72
	v_and_b32_e32 v72, 0xffff0000, v119
	v_add_f32_e32 v75, v75, v72
	v_mul_f32_e32 v72, v77, v77
	v_mul_f32_e32 v73, v79, v79
	v_fmac_f32_e32 v72, v76, v76
	v_fmac_f32_e32 v73, v78, v78
	v_add_f32_e32 v72, v72, v73
	v_mul_f32_e32 v73, v83, v83
	v_fmac_f32_e32 v73, v82, v82
	v_add_f32_e32 v72, v73, v72
	v_mul_f32_e32 v73, v75, v75
	v_fmac_f32_e32 v73, v84, v84
	v_add_f32_e32 v85, v73, v72
	v_cvt_pk_bf16_f32 v72, v76, v77
	v_pk_add_f32 v[68:69], v[68:69], 0 op_sel_hi:[1,0]
	v_lshlrev_b32_e32 v76, 16, v112
	v_add_f32_e32 v68, v68, v76
	v_and_b32_e32 v76, 0xffff0000, v112
	v_pk_add_f32 v[70:71], v[70:71], 0 op_sel_hi:[1,0]
	v_add_f32_e32 v69, v69, v76
	v_lshlrev_b32_e32 v76, 16, v113
	v_add_f32_e32 v76, v70, v76
	v_and_b32_e32 v70, 0xffff0000, v113
	v_pk_add_f32 v[64:65], v[64:65], 0 op_sel_hi:[1,0]
	v_add_f32_e32 v77, v71, v70
	v_lshlrev_b32_e32 v70, 16, v114
	v_cvt_pk_bf16_f32 v73, v78, v79
	v_add_f32_e32 v78, v64, v70
	v_and_b32_e32 v64, 0xffff0000, v114
	v_pk_add_f32 v[66:67], v[66:67], 0 op_sel_hi:[1,0]
	v_add_f32_e32 v79, v65, v64
	v_lshlrev_b32_e32 v64, 16, v115
	v_cvt_pk_bf16_f32 v74, v82, v83
	v_add_f32_e32 v82, v66, v64
	v_and_b32_e32 v64, 0xffff0000, v115
	v_add_f32_e32 v83, v67, v64
	v_mul_f32_e32 v64, v69, v69
	v_mul_f32_e32 v65, v77, v77
	v_fmac_f32_e32 v64, v68, v68
	v_fmac_f32_e32 v65, v76, v76
	v_add_f32_e32 v64, v64, v65
	v_mul_f32_e32 v65, v79, v79
	v_fmac_f32_e32 v65, v78, v78
	v_add_f32_e32 v64, v65, v64
	v_mul_f32_e32 v65, v83, v83
	v_fmac_f32_e32 v65, v82, v82
	v_add_f32_e32 v64, v65, v64
	v_add_f32_e32 v67, v85, v64
	v_cvt_pk_bf16_f32 v75, v84, v75
	ds_bpermute_b32 v84, v171, v67
	s_waitcnt lgkmcnt(1)
	v_lshlrev_b64 v[80:81], 11, v[158:159]
	v_lshl_add_u64 v[64:65], v[80:81], 1, s[4:5]
	v_lshl_add_u64 v[70:71], v[152:153], 1, v[64:65]
	global_store_dwordx4 v[70:71], v[72:75], off sc1
	s_waitcnt lgkmcnt(0)
	v_add_f32_e32 v64, v67, v84
	ds_bpermute_b32 v65, v172, v64
	v_cvt_pk_bf16_f32 v66, v68, v69
	v_cvt_pk_bf16_f32 v67, v76, v77
	v_cvt_pk_bf16_f32 v68, v78, v79
	v_cvt_pk_bf16_f32 v69, v82, v83
	global_store_dwordx4 v[70:71], v[66:69], off offset:256 sc1
	s_and_saveexec_b64 s[26:27], s[8:9]
	s_cbranch_execz .LBB0_1077
	v_lshlrev_b64 v[66:67], 7, v[158:159]
	v_lshl_add_u64 v[66:67], s[24:25], 0, v[66:67]
	s_waitcnt lgkmcnt(0)
	v_add_f32_e32 v64, v64, v65
	global_store_dword v[66:67], v64, off
.LBB0_1077:
	s_or_b64 exec, exec, s[26:27]
	v_add_u32_e32 v94, 0x80, v154
	v_ashrrev_i32_e32 v95, 31, v94
	v_lshlrev_b64 v[104:105], 12, v[94:95]
	s_waitcnt lgkmcnt(0)
	v_lshl_add_u64 v[64:65], v[156:157], 0, v[104:105]
	global_load_dwordx4 v[96:99], v[64:65], off
	global_load_dwordx4 v[100:103], v[64:65], off offset:256
	v_add_u32_e32 v92, 0x90, v154
	v_add_u32_e32 v90, 0xa0, v154
	v_add_u32_e32 v88, 0xb0, v154
	v_ashrrev_i32_e32 v93, 31, v92
	v_ashrrev_i32_e32 v91, 31, v90
	v_ashrrev_i32_e32 v89, 31, v88
	v_lshlrev_b64 v[64:65], 12, v[92:93]
	v_lshlrev_b64 v[66:67], 12, v[90:91]
	v_lshlrev_b64 v[68:69], 12, v[88:89]
	v_lshl_add_u64 v[64:65], v[156:157], 0, v[64:65]
	v_lshl_add_u64 v[66:67], v[156:157], 0, v[66:67]
	v_lshl_add_u64 v[106:107], v[156:157], 0, v[68:69]
	global_load_dwordx4 v[84:87], v[64:65], off
	global_load_dwordx4 v[80:83], v[64:65], off offset:256
	global_load_dwordx4 v[76:79], v[66:67], off
	global_load_dwordx4 v[72:75], v[66:67], off offset:256
	global_load_dwordx4 v[68:71], v[106:107], off
	s_nop 0
	global_load_dwordx4 v[64:67], v[106:107], off offset:256
	v_pk_add_f32 v[62:63], v[62:63], 0 op_sel_hi:[1,0]
	v_pk_add_f32 v[60:61], v[60:61], 0 op_sel_hi:[1,0]
	v_pk_add_f32 v[58:59], v[58:59], 0 op_sel_hi:[1,0]
	v_pk_add_f32 v[56:57], v[56:57], 0 op_sel_hi:[1,0]
	v_pk_add_f32 v[54:55], v[54:55], 0 op_sel_hi:[1,0]
	v_pk_add_f32 v[52:53], v[52:53], 0 op_sel_hi:[1,0]
	v_pk_add_f32 v[50:51], v[50:51], 0 op_sel_hi:[1,0]
	v_pk_add_f32 v[48:49], v[48:49], 0 op_sel_hi:[1,0]
	s_waitcnt vmcnt(7)
	v_lshlrev_b32_e32 v106, 16, v96
	v_and_b32_e32 v96, 0xffff0000, v96
	v_lshlrev_b32_e32 v107, 16, v97
	v_and_b32_e32 v97, 0xffff0000, v97
	v_lshlrev_b32_e32 v108, 16, v98
	v_and_b32_e32 v98, 0xffff0000, v98
	v_lshlrev_b32_e32 v109, 16, v99
	v_and_b32_e32 v99, 0xffff0000, v99
	s_waitcnt vmcnt(6)
	v_lshlrev_b32_e32 v110, 16, v100
	v_and_b32_e32 v100, 0xffff0000, v100
	v_lshlrev_b32_e32 v111, 16, v101
	v_and_b32_e32 v101, 0xffff0000, v101
	v_lshlrev_b32_e32 v112, 16, v102
	v_and_b32_e32 v102, 0xffff0000, v102
	v_lshlrev_b32_e32 v113, 16, v103
	v_and_b32_e32 v103, 0xffff0000, v103
	v_add_f32_e32 v61, v61, v96
	v_add_f32_e32 v63, v63, v97
	v_add_f32_e32 v57, v57, v98
	v_add_f32_e32 v59, v59, v99
	v_add_f32_e32 v97, v53, v100
	v_add_f32_e32 v99, v55, v101
	v_add_f32_e32 v60, v60, v106
	v_add_f32_e32 v62, v62, v107
	v_add_f32_e32 v56, v56, v108
	v_add_f32_e32 v58, v58, v109
	v_add_f32_e32 v96, v52, v110
	v_add_f32_e32 v98, v54, v111
	v_add_f32_e32 v100, v48, v112
	v_add_f32_e32 v101, v49, v102
	v_add_f32_e32 v102, v50, v113
	v_add_f32_e32 v103, v51, v103
	v_mul_f32_e32 v52, v61, v61
	v_mul_f32_e32 v53, v63, v63
	v_mul_f32_e32 v54, v57, v57
	v_mul_f32_e32 v55, v59, v59
	v_cvt_pk_bf16_f32 v48, v60, v61
	v_cvt_pk_bf16_f32 v49, v62, v63
	v_cvt_pk_bf16_f32 v50, v56, v57
	v_cvt_pk_bf16_f32 v51, v58, v59
	v_mul_f32_e32 v57, v97, v97
	v_mul_f32_e32 v59, v99, v99
	v_mul_f32_e32 v61, v101, v101
	v_fmac_f32_e32 v52, v60, v60
	v_fmac_f32_e32 v53, v62, v62
	v_fmac_f32_e32 v57, v96, v96
	v_fmac_f32_e32 v59, v98, v98
	v_mul_f32_e32 v63, v103, v103
	v_fmac_f32_e32 v54, v56, v56
	v_fmac_f32_e32 v61, v100, v100
	v_add_f32_e32 v52, v52, v53
	v_add_f32_e32 v53, v57, v59
	v_fmac_f32_e32 v55, v58, v58
	v_fmac_f32_e32 v63, v102, v102
	v_add_f32_e32 v52, v54, v52
	v_add_f32_e32 v53, v61, v53
	v_add_f32_e32 v52, v55, v52
	v_add_f32_e32 v53, v63, v53
	v_add_f32_e32 v56, v52, v53
	ds_bpermute_b32 v57, v171, v56
	v_lshl_add_u64 v[52:53], s[4:5], 0, v[104:105]
	v_lshl_add_u64 v[54:55], v[152:153], 1, v[52:53]
	global_store_dwordx4 v[54:55], v[48:51], off sc1
	s_waitcnt lgkmcnt(0)
	s_nop 0
	v_add_f32_e32 v48, v56, v57
	ds_bpermute_b32 v49, v172, v48
	v_cvt_pk_bf16_f32 v50, v96, v97
	v_cvt_pk_bf16_f32 v51, v98, v99
	v_cvt_pk_bf16_f32 v52, v100, v101
	v_cvt_pk_bf16_f32 v53, v102, v103
	global_store_dwordx4 v[54:55], v[50:53], off offset:256 sc1
	s_and_saveexec_b64 s[26:27], s[8:9]
	s_cbranch_execz .LBB0_1079
; __device__ __forceinline__ unsigned cvt_pk_bf16(float lo, float hi) { unsigned r; asm volatile("v_cvt_pk_bf16_f32 %0, %1, %2" : "=v"(r) : "v"(lo), "v"(hi)); return r; }
;     __device__ __forceinline__ void operator()(const f32x4 (&acc)[2][2][4][2], const Unit& u, int wr, int wc, int fr, int fq) const {
;     ...
;             for (int m = 0; m < 4; ++m) { const int row = row0 + ai * HALF + m * 16; float ss = 0.f;
; #pragma unroll
;                 for (int bj = 0; bj < 2; ++bj) { const u32x4 ow = old[m][bj];
;                     f32x4 v0 = (acc[ai][bj][m][0] + bv[bj][0]) * accs, v1 = (acc[ai][bj][m][1] + bv[bj][1]) * accs;
;                     v0[0] += __uint_as_float(ow.x << 16); v0[1] += __uint_as_float(ow.x & 0xffff0000u); v0[2] += __uint_as_float(ow.y << 16); v0[3] += __uint_as_float(ow.y & 0xffff0000u);
;                     v1[0] += __uint_as_float(ow.z << 16); v1[1] += __uint_as_float(ow.z & 0xffff0000u); v1[2] += __uint_as_float(ow.w << 16); v1[3] += __uint_as_float(ow.w & 0xffff0000u);
;                     ss += (v0[0] * v0[0] + v0[1] * v0[1]) + (v0[2] * v0[2] + v0[3] * v0[3]) + (v1[0] * v1[0] + v1[1] * v1[1]) + (v1[2] * v1[2] + v1[3] * v1[3]);
;                     u32x4 w; w.x = cvt_pk_bf16(v0[0], v0[1]); w.y = cvt_pk_bf16(v0[2], v0[3]); w.z = cvt_pk_bf16(v1[0], v1[1]); w.w = cvt_pk_bf16(v1[2], v1[3]);
;                     *(u32x4*)(HB + (size_t)row * ldc + col0 + bj * HALF) = w; }
;                 ss += __shfl_xor(ss, 16); ss += __shfl_xor(ss, 32);
;                 if (fq == 0) ssp[(size_t)row * 32] = ss; }
	v_lshlrev_b64 v[50:51], 7, v[94:95]
	v_lshl_add_u64 v[50:51], s[24:25], 0, v[50:51]
	s_waitcnt lgkmcnt(0)
	v_add_f32_e32 v48, v48, v49
	global_store_dword v[50:51], v48, off
.LBB0_1079:
	s_or_b64 exec, exec, s[26:27]
	v_pk_add_f32 v[44:45], v[44:45], 0 op_sel_hi:[1,0]
	s_waitcnt vmcnt(7)
	v_lshlrev_b32_e32 v50, 16, v84
	v_add_f32_e32 v44, v44, v50
	v_and_b32_e32 v50, 0xffff0000, v84
	v_pk_add_f32 v[46:47], v[46:47], 0 op_sel_hi:[1,0]
	v_add_f32_e32 v45, v45, v50
	v_lshlrev_b32_e32 v50, 16, v85
	v_add_f32_e32 v46, v46, v50
	v_and_b32_e32 v50, 0xffff0000, v85
	v_pk_add_f32 v[40:41], v[40:41], 0 op_sel_hi:[1,0]
	v_add_f32_e32 v47, v47, v50
	v_lshlrev_b32_e32 v50, 16, v86
	v_add_f32_e32 v50, v40, v50
	v_and_b32_e32 v40, 0xffff0000, v86
	v_pk_add_f32 v[42:43], v[42:43], 0 op_sel_hi:[1,0]
	v_add_f32_e32 v51, v41, v40
	v_lshlrev_b32_e32 v40, 16, v87
	v_add_f32_e32 v52, v42, v40
	v_and_b32_e32 v40, 0xffff0000, v87
	v_add_f32_e32 v43, v43, v40
	v_mul_f32_e32 v40, v45, v45
	v_mul_f32_e32 v41, v47, v47
	v_fmac_f32_e32 v40, v44, v44
	v_fmac_f32_e32 v41, v46, v46
	v_add_f32_e32 v40, v40, v41
	v_mul_f32_e32 v41, v51, v51
	v_fmac_f32_e32 v41, v50, v50
	v_add_f32_e32 v40, v41, v40
	v_mul_f32_e32 v41, v43, v43
	v_fmac_f32_e32 v41, v52, v52
	v_add_f32_e32 v53, v41, v40
	v_cvt_pk_bf16_f32 v40, v44, v45
	v_pk_add_f32 v[36:37], v[36:37], 0 op_sel_hi:[1,0]
	s_waitcnt vmcnt(6)
	v_lshlrev_b32_e32 v44, 16, v80
	v_add_f32_e32 v36, v36, v44
	v_and_b32_e32 v44, 0xffff0000, v80
	v_pk_add_f32 v[38:39], v[38:39], 0 op_sel_hi:[1,0]
	v_add_f32_e32 v37, v37, v44
	v_lshlrev_b32_e32 v44, 16, v81
	v_add_f32_e32 v44, v38, v44
	v_and_b32_e32 v38, 0xffff0000, v81
	v_pk_add_f32 v[32:33], v[32:33], 0 op_sel_hi:[1,0]
	v_add_f32_e32 v45, v39, v38
	v_lshlrev_b32_e32 v38, 16, v82
	v_cvt_pk_bf16_f32 v41, v46, v47
	v_add_f32_e32 v46, v32, v38
	v_and_b32_e32 v32, 0xffff0000, v82
	v_pk_add_f32 v[34:35], v[34:35], 0 op_sel_hi:[1,0]
	v_add_f32_e32 v47, v33, v32
	v_lshlrev_b32_e32 v32, 16, v83
	v_cvt_pk_bf16_f32 v42, v50, v51
	v_add_f32_e32 v50, v34, v32
	v_and_b32_e32 v32, 0xffff0000, v83
	v_add_f32_e32 v51, v35, v32
	v_mul_f32_e32 v32, v37, v37
	v_mul_f32_e32 v33, v45, v45
	v_fmac_f32_e32 v32, v36, v36
	v_fmac_f32_e32 v33, v44, v44
	v_add_f32_e32 v32, v32, v33
	v_mul_f32_e32 v33, v47, v47
	v_fmac_f32_e32 v33, v46, v46
	v_add_f32_e32 v32, v33, v32
	v_mul_f32_e32 v33, v51, v51
	v_fmac_f32_e32 v33, v50, v50
	v_add_f32_e32 v32, v33, v32
	v_add_f32_e32 v35, v53, v32
	v_cvt_pk_bf16_f32 v43, v52, v43
	ds_bpermute_b32 v52, v171, v35
	s_waitcnt lgkmcnt(1)
	v_lshlrev_b64 v[48:49], 11, v[92:93]
	v_lshl_add_u64 v[32:33], v[48:49], 1, s[4:5]
	v_lshl_add_u64 v[38:39], v[152:153], 1, v[32:33]
	global_store_dwordx4 v[38:39], v[40:43], off sc1
	s_waitcnt lgkmcnt(0)
	v_add_f32_e32 v32, v35, v52
	ds_bpermute_b32 v33, v172, v32
	v_cvt_pk_bf16_f32 v34, v36, v37
	v_cvt_pk_bf16_f32 v35, v44, v45
	v_cvt_pk_bf16_f32 v36, v46, v47
	v_cvt_pk_bf16_f32 v37, v50, v51
	global_store_dwordx4 v[38:39], v[34:37], off offset:256 sc1
	s_and_saveexec_b64 s[26:27], s[8:9]
	s_cbranch_execz .LBB0_1081
	v_lshlrev_b64 v[34:35], 7, v[92:93]
	v_lshl_add_u64 v[34:35], s[24:25], 0, v[34:35]
	s_waitcnt lgkmcnt(0)
	v_add_f32_e32 v32, v32, v33
	global_store_dword v[34:35], v32, off
; __device__ __forceinline__ unsigned cvt_pk_bf16(float lo, float hi) { unsigned r; asm volatile("v_cvt_pk_bf16_f32 %0, %1, %2" : "=v"(r) : "v"(lo), "v"(hi)); return r; }
;     __device__ __forceinline__ void operator()(const f32x4 (&acc)[2][2][4][2], const Unit& u, int wr, int wc, int fr, int fq) const {
;     ...
;             for (int m = 0; m < 4; ++m) { const int row = row0 + ai * HALF + m * 16; float ss = 0.f;
; #pragma unroll
;                 for (int bj = 0; bj < 2; ++bj) { const u32x4 ow = old[m][bj];
;                     f32x4 v0 = (acc[ai][bj][m][0] + bv[bj][0]) * accs, v1 = (acc[ai][bj][m][1] + bv[bj][1]) * accs;
;                     v0[0] += __uint_as_float(ow.x << 16); v0[1] += __uint_as_float(ow.x & 0xffff0000u); v0[2] += __uint_as_float(ow.y << 16); v0[3] += __uint_as_float(ow.y & 0xffff0000u);
;                     v1[0] += __uint_as_float(ow.z << 16); v1[1] += __uint_as_float(ow.z & 0xffff0000u); v1[2] += __uint_as_float(ow.w << 16); v1[3] += __uint_as_float(ow.w & 0xffff0000u);
;                     ss += (v0[0] * v0[0] + v0[1] * v0[1]) + (v0[2] * v0[2] + v0[3] * v0[3]) + (v1[0] * v1[0] + v1[1] * v1[1]) + (v1[2] * v1[2] + v1[3] * v1[3]);
;                     u32x4 w; w.x = cvt_pk_bf16(v0[0], v0[1]); w.y = cvt_pk_bf16(v0[2], v0[3]); w.z = cvt_pk_bf16(v1[0], v1[1]); w.w = cvt_pk_bf16(v1[2], v1[3]);
;                     *(u32x4*)(HB + (size_t)row * ldc + col0 + bj * HALF) = w; }
;                 ss += __shfl_xor(ss, 16); ss += __shfl_xor(ss, 32);
;                 if (fq == 0) ssp[(size_t)row * 32] = ss; }
.LBB0_1081:
	s_or_b64 exec, exec, s[26:27]
	v_pk_add_f32 v[28:29], v[28:29], 0 op_sel_hi:[1,0]
	s_waitcnt vmcnt(7)
	v_lshlrev_b32_e32 v34, 16, v76
	v_add_f32_e32 v28, v28, v34
	v_and_b32_e32 v34, 0xffff0000, v76
	v_pk_add_f32 v[30:31], v[30:31], 0 op_sel_hi:[1,0]
	v_add_f32_e32 v29, v29, v34
	v_lshlrev_b32_e32 v34, 16, v77
	v_add_f32_e32 v30, v30, v34
	v_and_b32_e32 v34, 0xffff0000, v77
	v_pk_add_f32 v[24:25], v[24:25], 0 op_sel_hi:[1,0]
	v_add_f32_e32 v31, v31, v34
	v_lshlrev_b32_e32 v34, 16, v78
	v_add_f32_e32 v34, v24, v34
	v_and_b32_e32 v24, 0xffff0000, v78
	v_pk_add_f32 v[26:27], v[26:27], 0 op_sel_hi:[1,0]
	v_add_f32_e32 v35, v25, v24
	v_lshlrev_b32_e32 v24, 16, v79
	v_add_f32_e32 v36, v26, v24
	v_and_b32_e32 v24, 0xffff0000, v79
	v_add_f32_e32 v27, v27, v24
	v_mul_f32_e32 v24, v29, v29
	v_mul_f32_e32 v25, v31, v31
	v_fmac_f32_e32 v24, v28, v28
	v_fmac_f32_e32 v25, v30, v30
	v_add_f32_e32 v24, v24, v25
	v_mul_f32_e32 v25, v35, v35
	v_fmac_f32_e32 v25, v34, v34
	v_add_f32_e32 v24, v25, v24
	v_mul_f32_e32 v25, v27, v27
	v_fmac_f32_e32 v25, v36, v36
	v_add_f32_e32 v37, v25, v24
	v_cvt_pk_bf16_f32 v24, v28, v29
	v_pk_add_f32 v[20:21], v[20:21], 0 op_sel_hi:[1,0]
	s_waitcnt vmcnt(6)
	v_lshlrev_b32_e32 v28, 16, v72
	v_add_f32_e32 v20, v20, v28
	v_and_b32_e32 v28, 0xffff0000, v72
	v_pk_add_f32 v[22:23], v[22:23], 0 op_sel_hi:[1,0]
	v_add_f32_e32 v21, v21, v28
	v_lshlrev_b32_e32 v28, 16, v73
	v_add_f32_e32 v28, v22, v28
	v_and_b32_e32 v22, 0xffff0000, v73
	v_pk_add_f32 v[16:17], v[16:17], 0 op_sel_hi:[1,0]
	v_add_f32_e32 v29, v23, v22
	v_lshlrev_b32_e32 v22, 16, v74
	v_cvt_pk_bf16_f32 v25, v30, v31
	v_add_f32_e32 v30, v16, v22
	v_and_b32_e32 v16, 0xffff0000, v74
	v_pk_add_f32 v[18:19], v[18:19], 0 op_sel_hi:[1,0]
	v_add_f32_e32 v31, v17, v16
	v_lshlrev_b32_e32 v16, 16, v75
	v_cvt_pk_bf16_f32 v26, v34, v35
	v_add_f32_e32 v34, v18, v16
	v_and_b32_e32 v16, 0xffff0000, v75
	v_add_f32_e32 v35, v19, v16
	v_mul_f32_e32 v16, v21, v21
	v_mul_f32_e32 v17, v29, v29
	v_fmac_f32_e32 v16, v20, v20
	v_fmac_f32_e32 v17, v28, v28
	v_add_f32_e32 v16, v16, v17
	v_mul_f32_e32 v17, v31, v31
	v_fmac_f32_e32 v17, v30, v30
	v_add_f32_e32 v16, v17, v16
	v_mul_f32_e32 v17, v35, v35
	v_fmac_f32_e32 v17, v34, v34
	v_add_f32_e32 v16, v17, v16
	v_add_f32_e32 v19, v37, v16
	v_cvt_pk_bf16_f32 v27, v36, v27
	ds_bpermute_b32 v36, v171, v19
	s_waitcnt lgkmcnt(1)
	v_lshlrev_b64 v[32:33], 11, v[90:91]
	v_lshl_add_u64 v[16:17], v[32:33], 1, s[4:5]
	v_lshl_add_u64 v[22:23], v[152:153], 1, v[16:17]
	global_store_dwordx4 v[22:23], v[24:27], off sc1
	s_waitcnt lgkmcnt(0)
	v_add_f32_e32 v16, v19, v36
	ds_bpermute_b32 v17, v172, v16
	v_cvt_pk_bf16_f32 v18, v20, v21
	v_cvt_pk_bf16_f32 v19, v28, v29
	v_cvt_pk_bf16_f32 v20, v30, v31
	v_cvt_pk_bf16_f32 v21, v34, v35
	global_store_dwordx4 v[22:23], v[18:21], off offset:256 sc1
	s_and_saveexec_b64 s[26:27], s[8:9]
	s_cbranch_execz .LBB0_1083
	v_lshlrev_b64 v[18:19], 7, v[90:91]
	v_lshl_add_u64 v[18:19], s[24:25], 0, v[18:19]
	s_waitcnt lgkmcnt(0)
	v_add_f32_e32 v16, v16, v17
	global_store_dword v[18:19], v16, off
.LBB0_1083:
	s_or_b64 exec, exec, s[26:27]
	v_pk_add_f32 v[12:13], v[12:13], 0 op_sel_hi:[1,0]
	s_waitcnt vmcnt(7)
	v_lshlrev_b32_e32 v18, 16, v68
	v_add_f32_e32 v12, v12, v18
	v_and_b32_e32 v18, 0xffff0000, v68
	v_pk_add_f32 v[14:15], v[14:15], 0 op_sel_hi:[1,0]
	v_add_f32_e32 v13, v13, v18
	v_lshlrev_b32_e32 v18, 16, v69
	v_add_f32_e32 v14, v14, v18
	v_and_b32_e32 v18, 0xffff0000, v69
	v_pk_add_f32 v[8:9], v[8:9], 0 op_sel_hi:[1,0]
	v_add_f32_e32 v15, v15, v18
	v_lshlrev_b32_e32 v18, 16, v70
	v_add_f32_e32 v18, v8, v18
	v_and_b32_e32 v8, 0xffff0000, v70
	v_pk_add_f32 v[10:11], v[10:11], 0 op_sel_hi:[1,0]
	v_add_f32_e32 v19, v9, v8
	v_lshlrev_b32_e32 v8, 16, v71
	v_add_f32_e32 v20, v10, v8
	v_and_b32_e32 v8, 0xffff0000, v71
	v_add_f32_e32 v11, v11, v8
	v_mul_f32_e32 v8, v13, v13
	v_mul_f32_e32 v9, v15, v15
	v_fmac_f32_e32 v8, v12, v12
	v_fmac_f32_e32 v9, v14, v14
	v_add_f32_e32 v8, v8, v9
	v_mul_f32_e32 v9, v19, v19
	v_fmac_f32_e32 v9, v18, v18
	v_add_f32_e32 v8, v9, v8
	v_mul_f32_e32 v9, v11, v11
	v_fmac_f32_e32 v9, v20, v20
	v_add_f32_e32 v21, v9, v8
	v_cvt_pk_bf16_f32 v8, v12, v13
	v_pk_add_f32 v[4:5], v[4:5], 0 op_sel_hi:[1,0]
	s_waitcnt vmcnt(6)
	v_lshlrev_b32_e32 v12, 16, v64
	v_add_f32_e32 v4, v4, v12
	v_and_b32_e32 v12, 0xffff0000, v64
	v_pk_add_f32 v[6:7], v[6:7], 0 op_sel_hi:[1,0]
	v_add_f32_e32 v5, v5, v12
	v_lshlrev_b32_e32 v12, 16, v65
	v_add_f32_e32 v12, v6, v12
	v_and_b32_e32 v6, 0xffff0000, v65
	v_pk_add_f32 v[0:1], v[0:1], 0 op_sel_hi:[1,0]
	v_add_f32_e32 v13, v7, v6
	v_lshlrev_b32_e32 v6, 16, v66
	v_cvt_pk_bf16_f32 v9, v14, v15
	v_add_f32_e32 v14, v0, v6
	v_and_b32_e32 v0, 0xffff0000, v66
	v_pk_add_f32 v[2:3], v[2:3], 0 op_sel_hi:[1,0]
	v_add_f32_e32 v15, v1, v0
	v_lshlrev_b32_e32 v0, 16, v67
	v_cvt_pk_bf16_f32 v10, v18, v19
	v_add_f32_e32 v18, v2, v0
	v_and_b32_e32 v0, 0xffff0000, v67
	v_add_f32_e32 v19, v3, v0
	v_mul_f32_e32 v0, v5, v5
	v_mul_f32_e32 v1, v13, v13
	v_fmac_f32_e32 v0, v4, v4
	v_fmac_f32_e32 v1, v12, v12
	v_add_f32_e32 v0, v0, v1
	v_mul_f32_e32 v1, v15, v15
	v_fmac_f32_e32 v1, v14, v14
	v_add_f32_e32 v0, v1, v0
	v_mul_f32_e32 v1, v19, v19
	v_fmac_f32_e32 v1, v18, v18
	v_add_f32_e32 v0, v1, v0
	v_add_f32_e32 v3, v21, v0
	v_cvt_pk_bf16_f32 v11, v20, v11
	ds_bpermute_b32 v20, v171, v3
	s_waitcnt lgkmcnt(1)
	v_lshlrev_b64 v[16:17], 11, v[88:89]
	v_lshl_add_u64 v[0:1], v[16:17], 1, s[4:5]
	v_lshl_add_u64 v[6:7], v[152:153], 1, v[0:1]
	global_store_dwordx4 v[6:7], v[8:11], off sc1
	s_waitcnt lgkmcnt(0)
	v_add_f32_e32 v0, v3, v20
	ds_bpermute_b32 v1, v172, v0
	v_cvt_pk_bf16_f32 v2, v4, v5
	v_cvt_pk_bf16_f32 v3, v12, v13
	v_cvt_pk_bf16_f32 v4, v14, v15
	v_cvt_pk_bf16_f32 v5, v18, v19
	global_store_dwordx4 v[6:7], v[2:5], off offset:256 sc1
	s_and_saveexec_b64 s[26:27], s[8:9]
	s_cbranch_execz .LBB0_1085
	v_lshlrev_b64 v[2:3], 7, v[88:89]
	v_lshl_add_u64 v[2:3], s[24:25], 0, v[2:3]
	s_waitcnt lgkmcnt(0)
	v_add_f32_e32 v0, v0, v1
	global_store_dword v[2:3], v0, off

; __device__ __forceinline__ unsigned cvt_pk_bf16(float lo, float hi) { unsigned r; asm volatile("v_cvt_pk_bf16_f32 %0, %1, %2" : "=v"(r) : "v"(lo), "v"(hi)); return r; }
; __device__ __forceinline__ float dpp_up1(float x) { return __builtin_bit_cast(float, __builtin_amdgcn_update_dpp(0, __builtin_bit_cast(int, x), 0x111, 0xf, 0xf, true)); }
;     __device__ __forceinline__ void operator()(const f32x4 (&acc)[2][2][4][2], const Unit& u, int wr, int wc, int fr, int fq) const {
;     ...
;                 for (int e = 0; e < 4; ++e) { pg2[e] = dpp_up1(xg[2][e]); pg3[e] = dpp_up1(xg[3][e]); pv2[e] = dpp_up1(xv[2][e]); pv3[e] = dpp_up1(xv[3][e]); }
; #pragma unroll
;                 for (int m = 0; m < 4; ++m) {
;                     u32x2_t w; float o[4];
; #pragma unroll
;                     for (int e = 0; e < 4; ++e) {
;                         const float g1 = m >= 1 ? xg[m - (m >= 1 ? 1 : 0)][e] : pg3[e], g2 = m >= 2 ? xg[m - (m >= 2 ? 2 : 0)][e] : (m == 1 ? pg3[e] : pg2[e]);
;                         const float v1 = m >= 1 ? xv[m - (m >= 1 ? 1 : 0)][e] : pv3[e], v2 = m >= 2 ? xv[m - (m >= 2 ? 2 : 0)][e] : (m == 1 ? pv3[e] : pv2[e]);
;                         const float cg_ = bg[e] + w0g[e] * g2 + w1g[e] * g1 + w2g[e] * xg[m][e];
;                         const float cv_ = bv[e] + w0v[e] * v2 + w1v[e] * v1 + w2v[e] * xv[m][e];
;                         o[e] = cg_ * __builtin_amdgcn_rcpf(1.0f + __expf(-cg_)) * cv_;
;                     }
;                     w.x = cvt_pk_bf16(o[0], o[1]); w.y = cvt_pk_bf16(o[2], o[3]);
;                     const int g = g0 + m;
;                     if (n == 0) stash[ai][m] = w;
;                     else if ((fr > 0 || m >= 2) && g < TT) { u32x4 ww; ww.x = stash[ai][m].x; ww.y = stash[ai][m].y; ww.z = w.x; ww.w = w.y; *(u32x4*)(G + (size_t)g * DFF_ + f0 - 4) = ww; }
.LBB0_1163:
	v_mov_b32_dpp v46, v58 row_shr:1 row_mask:0xf bank_mask:0xf bound_ctrl:1
	v_mov_b32_dpp v113, v44 row_shr:1 row_mask:0xf bank_mask:0xf bound_ctrl:1
	s_waitcnt vmcnt(4)
	v_fma_f32 v123, v94, v46, v70
	v_fmac_f32_e32 v123, v102, v113
	v_fmac_f32_e32 v123, v98, v76
	v_mul_f32_e32 v46, 0xbfb8aa3b, v123
	v_exp_f32_e32 v124, v46
	v_mov_b32_dpp v115, v59 row_shr:1 row_mask:0xf bank_mask:0xf bound_ctrl:1
	v_mov_b32_dpp v111, v45 row_shr:1 row_mask:0xf bank_mask:0xf bound_ctrl:1
	v_fma_f32 v115, v95, v115, v71
	v_fmac_f32_e32 v115, v103, v111
	v_add_f32_e32 v124, 1.0, v124
	v_fmac_f32_e32 v115, v99, v77
	v_rcp_f32_e32 v124, v124
	v_mul_f32_e32 v125, 0xbfb8aa3b, v115
	v_mov_b32_dpp v114, v52 row_shr:1 row_mask:0xf bank_mask:0xf bound_ctrl:1
	v_exp_f32_e32 v125, v125
	v_mov_b32_dpp v112, v38 row_shr:1 row_mask:0xf bank_mask:0xf bound_ctrl:1
	s_waitcnt vmcnt(0)
	v_fma_f32 v114, v78, v114, v90
	v_fmac_f32_e32 v114, v82, v112
	v_fmac_f32_e32 v114, v86, v68
	v_mul_f32_e32 v123, v123, v124
	v_mul_f32_e32 v114, v114, v123
	v_add_f32_e32 v123, 1.0, v125
	v_mov_b32_dpp v117, v42 row_shr:1 row_mask:0xf bank_mask:0xf bound_ctrl:1
	v_rcp_f32_e32 v123, v123
	v_mov_b32_dpp v55, v32 row_shr:1 row_mask:0xf bank_mask:0xf bound_ctrl:1
	v_fma_f32 v117, v96, v117, v72
	v_fmac_f32_e32 v117, v104, v55
	v_fmac_f32_e32 v117, v100, v62
	v_mul_f32_e32 v115, v115, v123
	v_mul_f32_e32 v123, 0xbfb8aa3b, v117
	v_mov_b32_dpp v116, v53 row_shr:1 row_mask:0xf bank_mask:0xf bound_ctrl:1
	v_exp_f32_e32 v123, v123
	v_mov_b32_dpp v110, v39 row_shr:1 row_mask:0xf bank_mask:0xf bound_ctrl:1
	v_mov_b32_dpp v121, v43 row_shr:1 row_mask:0xf bank_mask:0xf bound_ctrl:1
	v_fma_f32 v116, v79, v116, v91
	v_mov_b32_dpp v47, v33 row_shr:1 row_mask:0xf bank_mask:0xf bound_ctrl:1
	v_fmac_f32_e32 v116, v83, v110
	v_fma_f32 v121, v97, v121, v73
	v_mov_b32_dpp v120, v36 row_shr:1 row_mask:0xf bank_mask:0xf bound_ctrl:1
	v_fmac_f32_e32 v116, v87, v69
	v_fmac_f32_e32 v121, v105, v47
	v_mul_f32_e32 v115, v116, v115
	v_fma_f32 v116, v80, v120, v92
	v_add_f32_e32 v120, 1.0, v123
	v_fmac_f32_e32 v121, v101, v63
	v_rcp_f32_e32 v120, v120
	v_mul_f32_e32 v123, 0xbfb8aa3b, v121
	v_exp_f32_e32 v123, v123
	v_mov_b32_dpp v54, v34 row_shr:1 row_mask:0xf bank_mask:0xf bound_ctrl:1
	v_fmac_f32_e32 v116, v84, v54
	v_fmac_f32_e32 v116, v88, v60
	v_mul_f32_e32 v117, v117, v120
	v_mul_f32_e32 v116, v116, v117
	v_add_f32_e32 v117, 1.0, v123
	v_rcp_f32_e32 v117, v117
	v_mov_b32_dpp v122, v37 row_shr:1 row_mask:0xf bank_mask:0xf bound_ctrl:1
	v_mov_b32_dpp v46, v35 row_shr:1 row_mask:0xf bank_mask:0xf bound_ctrl:1
	v_fma_f32 v120, v81, v122, v93
	v_fmac_f32_e32 v120, v85, v46
	v_cmp_gt_i32_e32 vcc, s64, v218
	v_fmac_f32_e32 v120, v89, v61
	v_mul_f32_e32 v117, v121, v117
	s_and_b64 s[6:7], s[10:11], vcc
	v_mul_f32_e32 v117, v120, v117
	v_cvt_pk_bf16_f32 v144, v114, v115
	v_cvt_pk_bf16_f32 v145, v116, v117
	s_and_saveexec_b64 s[16:17], s[6:7]
	s_cbranch_execz .LBB0_1165
	v_mov_b64_e32 v[114:115], s[4:5]
	v_mad_i64_i32 v[114:115], s[6:7], v218, s80, v[114:115]
	v_lshl_add_u64 v[114:115], v[182:183], 1, v[114:115]
	global_store_dwordx4 v[114:115], v[142:145], off sc1
.LBB0_1165:
	s_or_b64 exec, exec, s[16:17]
	v_fma_f32 v113, v94, v113, v70
	v_fmac_f32_e32 v113, v102, v76
	v_fmac_f32_e32 v113, v98, v56
	v_mul_f32_e32 v114, 0xbfb8aa3b, v113
	v_exp_f32_e32 v114, v114
	v_fma_f32 v111, v95, v111, v71
	v_fmac_f32_e32 v111, v103, v77
	v_fmac_f32_e32 v111, v99, v57
	v_add_f32_e32 v114, 1.0, v114
	v_rcp_f32_e32 v114, v114
	v_mul_f32_e32 v115, 0xbfb8aa3b, v111
	v_exp_f32_e32 v115, v115
	v_fma_f32 v112, v78, v112, v90
	v_fmac_f32_e32 v112, v82, v68
	v_fmac_f32_e32 v112, v86, v50
	v_mul_f32_e32 v113, v113, v114
	v_mul_f32_e32 v112, v112, v113
	v_add_f32_e32 v113, 1.0, v115
	v_rcp_f32_e32 v113, v113
	v_fma_f32 v55, v96, v55, v72
	v_fmac_f32_e32 v55, v104, v62
	v_fmac_f32_e32 v55, v100, v48
	v_mul_f32_e32 v111, v111, v113
	v_mul_f32_e32 v113, 0xbfb8aa3b, v55
	v_exp_f32_e32 v113, v113
	v_fma_f32 v110, v79, v110, v91
	v_fmac_f32_e32 v110, v83, v69
	v_fma_f32 v47, v97, v47, v73
	v_fmac_f32_e32 v110, v87, v51
	v_fmac_f32_e32 v47, v105, v63
	v_mul_f32_e32 v110, v110, v111
	v_add_f32_e32 v111, 1.0, v113
	v_fmac_f32_e32 v47, v101, v49
	v_rcp_f32_e32 v111, v111
	v_mul_f32_e32 v113, 0xbfb8aa3b, v47
	v_exp_f32_e32 v113, v113
	v_fma_f32 v54, v80, v54, v92
	v_fmac_f32_e32 v54, v84, v60
	v_fmac_f32_e32 v54, v88, v40
	v_mul_f32_e32 v55, v55, v111
	v_mul_f32_e32 v54, v54, v55
	v_add_f32_e32 v55, 1.0, v113
	v_rcp_f32_e32 v55, v55
	v_fma_f32 v46, v81, v46, v93
	v_fmac_f32_e32 v46, v85, v61
	v_cmp_gt_i32_e32 vcc, s64, v221
	v_fmac_f32_e32 v46, v89, v41
	v_mul_f32_e32 v47, v47, v55
	s_and_b64 s[6:7], s[10:11], vcc
	v_mul_f32_e32 v46, v46, v47
	v_cvt_pk_bf16_f32 v142, v112, v110
	v_cvt_pk_bf16_f32 v143, v54, v46
	s_and_saveexec_b64 s[16:17], s[6:7]
	s_cbranch_execz .LBB0_1167
	v_mov_b64_e32 v[46:47], s[4:5]
	v_mad_i64_i32 v[46:47], s[6:7], v221, s80, v[46:47]
	v_lshl_add_u64 v[46:47], v[182:183], 1, v[46:47]
	global_store_dwordx4 v[46:47], v[140:143], off sc1
; __device__ __forceinline__ unsigned cvt_pk_bf16(float lo, float hi) { unsigned r; asm volatile("v_cvt_pk_bf16_f32 %0, %1, %2" : "=v"(r) : "v"(lo), "v"(hi)); return r; }
;     __device__ __forceinline__ void operator()(const f32x4 (&acc)[2][2][4][2], const Unit& u, int wr, int wc, int fr, int fq) const {
;     ...
;                 for (int m = 0; m < 4; ++m) {
;                     u32x2_t w; float o[4];
; #pragma unroll
;                     for (int e = 0; e < 4; ++e) {
;                         const float g1 = m >= 1 ? xg[m - (m >= 1 ? 1 : 0)][e] : pg3[e], g2 = m >= 2 ? xg[m - (m >= 2 ? 2 : 0)][e] : (m == 1 ? pg3[e] : pg2[e]);
;                         const float v1 = m >= 1 ? xv[m - (m >= 1 ? 1 : 0)][e] : pv3[e], v2 = m >= 2 ? xv[m - (m >= 2 ? 2 : 0)][e] : (m == 1 ? pv3[e] : pv2[e]);
;                         const float cg_ = bg[e] + w0g[e] * g2 + w1g[e] * g1 + w2g[e] * xg[m][e];
;                         const float cv_ = bv[e] + w0v[e] * v2 + w1v[e] * v1 + w2v[e] * xv[m][e];
;                         o[e] = cg_ * __builtin_amdgcn_rcpf(1.0f + __expf(-cg_)) * cv_;
;                     }
;                     w.x = cvt_pk_bf16(o[0], o[1]); w.y = cvt_pk_bf16(o[2], o[3]);
;                     const int g = g0 + m;
;                     if (n == 0) stash[ai][m] = w;
;                     else if ((fr > 0 || m >= 2) && g < TT) { u32x4 ww; ww.x = stash[ai][m].x; ww.y = stash[ai][m].y; ww.z = w.x; ww.w = w.y; *(u32x4*)(G + (size_t)g * DFF_ + f0 - 4) = ww; }
.LBB0_1167:
	s_or_b64 exec, exec, s[16:17]
	v_fma_f32 v46, v94, v76, v70
	v_fmac_f32_e32 v46, v102, v56
	v_fmac_f32_e32 v46, v98, v58
	v_mul_f32_e32 v47, 0xbfb8aa3b, v46
	v_exp_f32_e32 v47, v47
	v_fma_f32 v55, v95, v77, v71
	v_fmac_f32_e32 v55, v103, v57
	v_fmac_f32_e32 v55, v99, v59
	v_fma_f32 v54, v78, v68, v90
	v_add_f32_e32 v47, 1.0, v47
	v_mul_f32_e32 v68, 0xbfb8aa3b, v55
	v_rcp_f32_e32 v47, v47
	v_exp_f32_e32 v68, v68
	v_fmac_f32_e32 v54, v82, v50
	v_fmac_f32_e32 v54, v86, v52
	v_mul_f32_e32 v46, v46, v47
	v_add_f32_e32 v47, 1.0, v68
	v_rcp_f32_e32 v47, v47
	v_mul_f32_e32 v46, v54, v46
	v_fma_f32 v54, v79, v69, v91
	v_fmac_f32_e32 v54, v83, v51
	v_mul_f32_e32 v47, v55, v47
	v_fma_f32 v55, v96, v62, v72
	v_fmac_f32_e32 v55, v104, v48
	v_fmac_f32_e32 v55, v100, v42
	v_mul_f32_e32 v62, 0xbfb8aa3b, v55
	v_exp_f32_e32 v62, v62
	v_fmac_f32_e32 v54, v87, v53
	v_mul_f32_e32 v47, v54, v47
	v_fma_f32 v54, v80, v60, v92
	v_add_f32_e32 v60, 1.0, v62
	v_fma_f32 v62, v97, v63, v73
	v_fmac_f32_e32 v62, v105, v49
	v_fmac_f32_e32 v62, v101, v43
	v_rcp_f32_e32 v60, v60
	v_mul_f32_e32 v63, 0xbfb8aa3b, v62
	v_exp_f32_e32 v63, v63
	v_fmac_f32_e32 v54, v84, v40
	v_fmac_f32_e32 v54, v88, v36
	v_mul_f32_e32 v55, v55, v60
	v_mul_f32_e32 v54, v54, v55
	v_add_f32_e32 v55, 1.0, v63
	v_rcp_f32_e32 v55, v55
	v_fma_f32 v60, v81, v61, v93
	v_fmac_f32_e32 v60, v85, v41
	v_fmac_f32_e32 v60, v89, v37
	v_mul_f32_e32 v55, v62, v55
	v_cmp_gt_i32_e32 vcc, s81, v218
	v_mul_f32_e32 v55, v60, v55
	v_cvt_pk_bf16_f32 v120, v46, v47
	v_cvt_pk_bf16_f32 v121, v54, v55
	s_and_saveexec_b64 s[16:17], vcc
	s_cbranch_execz .LBB0_1169
	v_mov_b64_e32 v[46:47], s[4:5]
	v_mad_i64_i32 v[46:47], s[6:7], v220, s80, v[46:47]
	v_lshl_add_u64 v[46:47], v[182:183], 1, v[46:47]
	global_store_dwordx4 v[46:47], v[118:121], off sc1
.LBB0_1169:
	s_or_b64 exec, exec, s[16:17]
	v_fma_f32 v46, v94, v56, v70
	v_fmac_f32_e32 v46, v102, v58
	v_fmac_f32_e32 v46, v98, v44
	v_mul_f32_e32 v44, 0xbfb8aa3b, v46
	v_exp_f32_e32 v44, v44
	v_fma_f32 v47, v78, v50, v90
	v_fma_f32 v50, v95, v57, v71
	v_fmac_f32_e32 v50, v103, v59
	v_fmac_f32_e32 v50, v99, v45
	v_add_f32_e32 v44, 1.0, v44
	v_mul_f32_e32 v45, 0xbfb8aa3b, v50
	v_rcp_f32_e32 v44, v44
	v_exp_f32_e32 v45, v45
	v_fmac_f32_e32 v47, v82, v52
	v_fmac_f32_e32 v47, v86, v38
	v_mul_f32_e32 v38, v46, v44
	v_add_f32_e32 v44, 1.0, v45
	v_rcp_f32_e32 v44, v44
	v_fma_f32 v45, v79, v51, v91
	v_fmac_f32_e32 v45, v83, v53
	v_fma_f32 v40, v80, v40, v92
	v_fmac_f32_e32 v45, v87, v39
	v_mul_f32_e32 v39, v50, v44
	v_fma_f32 v44, v96, v48, v72
	v_fmac_f32_e32 v40, v84, v36
	v_fma_f32 v36, v97, v49, v73
	v_fmac_f32_e32 v44, v104, v42
	v_fmac_f32_e32 v36, v105, v43
	v_fmac_f32_e32 v44, v100, v32
	v_fmac_f32_e32 v36, v101, v33
	v_mul_f32_e32 v32, 0xbfb8aa3b, v44
	v_mul_f32_e32 v33, 0xbfb8aa3b, v36
	v_exp_f32_e32 v32, v32
	v_exp_f32_e32 v33, v33
	v_fmac_f32_e32 v40, v88, v34
	v_fma_f32 v34, v81, v41, v93
	v_add_f32_e32 v32, 1.0, v32
	v_add_f32_e32 v33, 1.0, v33
	v_rcp_f32_e32 v32, v32
	v_rcp_f32_e32 v33, v33
	v_fmac_f32_e32 v34, v85, v37
	v_fmac_f32_e32 v34, v89, v35
	v_mul_f32_e32 v32, v44, v32
	v_mul_f32_e32 v33, v36, v33
	v_cmp_gt_i32_e32 vcc, s82, v218
	v_mul_f32_e32 v38, v47, v38
	v_mul_f32_e32 v39, v45, v39
	v_mul_f32_e32 v32, v40, v32
	v_mul_f32_e32 v33, v34, v33
	v_cvt_pk_bf16_f32 v110, v38, v39
	v_cvt_pk_bf16_f32 v111, v32, v33
	s_and_saveexec_b64 s[16:17], vcc
	s_cbranch_execz .LBB0_1171
	v_mov_b64_e32 v[32:33], s[4:5]
	v_mad_i64_i32 v[32:33], s[6:7], v219, s80, v[32:33]
	v_lshl_add_u64 v[32:33], v[182:183], 1, v[32:33]
	global_store_dwordx4 v[32:33], v[108:111], off sc1

; __device__ __forceinline__ unsigned cvt_pk_bf16(float lo, float hi) { unsigned r; asm volatile("v_cvt_pk_bf16_f32 %0, %1, %2" : "=v"(r) : "v"(lo), "v"(hi)); return r; }
; __device__ __forceinline__ float dpp_up1(float x) { return __builtin_bit_cast(float, __builtin_amdgcn_update_dpp(0, __builtin_bit_cast(int, x), 0x111, 0xf, 0xf, true)); }
;     __device__ __forceinline__ void operator()(const f32x4 (&acc)[2][2][4][2], const Unit& u, int wr, int wc, int fr, int fq) const {
;     ...
;                 for (int e = 0; e < 4; ++e) { pg2[e] = dpp_up1(xg[2][e]); pg3[e] = dpp_up1(xg[3][e]); pv2[e] = dpp_up1(xv[2][e]); pv3[e] = dpp_up1(xv[3][e]); }
; #pragma unroll
;                 for (int m = 0; m < 4; ++m) {
;                     u32x2_t w; float o[4];
; #pragma unroll
;                     for (int e = 0; e < 4; ++e) {
;                         const float g1 = m >= 1 ? xg[m - (m >= 1 ? 1 : 0)][e] : pg3[e], g2 = m >= 2 ? xg[m - (m >= 2 ? 2 : 0)][e] : (m == 1 ? pg3[e] : pg2[e]);
;                         const float v1 = m >= 1 ? xv[m - (m >= 1 ? 1 : 0)][e] : pv3[e], v2 = m >= 2 ? xv[m - (m >= 2 ? 2 : 0)][e] : (m == 1 ? pv3[e] : pv2[e]);
;                         const float cg_ = bg[e] + w0g[e] * g2 + w1g[e] * g1 + w2g[e] * xg[m][e];
;                         const float cv_ = bv[e] + w0v[e] * v2 + w1v[e] * v1 + w2v[e] * xv[m][e];
;                         o[e] = cg_ * __builtin_amdgcn_rcpf(1.0f + __expf(-cg_)) * cv_;
;                     }
;                     w.x = cvt_pk_bf16(o[0], o[1]); w.y = cvt_pk_bf16(o[2], o[3]);
;                     const int g = g0 + m;
;                     if (n == 0) stash[ai][m] = w;
;                     else if ((fr > 0 || m >= 2) && g < TT) { u32x4 ww; ww.x = stash[ai][m].x; ww.y = stash[ai][m].y; ww.z = w.x; ww.w = w.y; *(u32x4*)(G + (size_t)g * DFF_ + f0 - 4) = ww; }
.LBB0_1173:
	v_mov_b32_dpp v14, v26 row_shr:1 row_mask:0xf bank_mask:0xf bound_ctrl:1
	v_mov_b32_dpp v39, v12 row_shr:1 row_mask:0xf bank_mask:0xf bound_ctrl:1
	v_fma_f32 v47, v94, v14, v70
	v_fmac_f32_e32 v47, v102, v39
	v_fmac_f32_e32 v47, v98, v34
	v_mul_f32_e32 v14, 0xbfb8aa3b, v47
	v_exp_f32_e32 v48, v14
	v_mov_b32_dpp v41, v27 row_shr:1 row_mask:0xf bank_mask:0xf bound_ctrl:1
	v_mov_b32_dpp v37, v13 row_shr:1 row_mask:0xf bank_mask:0xf bound_ctrl:1
	v_fma_f32 v41, v95, v41, v71
	v_fmac_f32_e32 v41, v103, v37
	v_add_f32_e32 v48, 1.0, v48
	v_fmac_f32_e32 v41, v99, v35
	v_rcp_f32_e32 v48, v48
	v_mul_f32_e32 v49, 0xbfb8aa3b, v41
	v_mov_b32_dpp v40, v20 row_shr:1 row_mask:0xf bank_mask:0xf bound_ctrl:1
	v_exp_f32_e32 v49, v49
	v_mov_b32_dpp v38, v6 row_shr:1 row_mask:0xf bank_mask:0xf bound_ctrl:1
	v_fma_f32 v40, v78, v40, v90
	v_fmac_f32_e32 v40, v82, v38
	v_fmac_f32_e32 v40, v86, v32
	v_mul_f32_e32 v47, v47, v48
	v_mul_f32_e32 v40, v40, v47
	v_add_f32_e32 v47, 1.0, v49
	v_mov_b32_dpp v43, v10 row_shr:1 row_mask:0xf bank_mask:0xf bound_ctrl:1
	v_rcp_f32_e32 v47, v47
	v_mov_b32_dpp v23, v0 row_shr:1 row_mask:0xf bank_mask:0xf bound_ctrl:1
	v_fma_f32 v43, v96, v43, v72
	v_fmac_f32_e32 v43, v104, v23
	v_fmac_f32_e32 v43, v100, v30
	v_mul_f32_e32 v41, v41, v47
	v_mul_f32_e32 v47, 0xbfb8aa3b, v43
	v_mov_b32_dpp v42, v21 row_shr:1 row_mask:0xf bank_mask:0xf bound_ctrl:1
	v_exp_f32_e32 v47, v47
	v_mov_b32_dpp v36, v7 row_shr:1 row_mask:0xf bank_mask:0xf bound_ctrl:1
	v_mov_b32_dpp v45, v11 row_shr:1 row_mask:0xf bank_mask:0xf bound_ctrl:1
	v_fma_f32 v42, v79, v42, v91
	v_mov_b32_dpp v15, v1 row_shr:1 row_mask:0xf bank_mask:0xf bound_ctrl:1
	v_fmac_f32_e32 v42, v83, v36
	v_fma_f32 v45, v97, v45, v73
	v_mov_b32_dpp v44, v4 row_shr:1 row_mask:0xf bank_mask:0xf bound_ctrl:1
	v_fmac_f32_e32 v42, v87, v33
	v_fmac_f32_e32 v45, v105, v15
	v_mul_f32_e32 v41, v42, v41
	v_fma_f32 v42, v80, v44, v92
	v_add_f32_e32 v44, 1.0, v47
	v_fmac_f32_e32 v45, v101, v31
	v_rcp_f32_e32 v44, v44
	v_mul_f32_e32 v47, 0xbfb8aa3b, v45
	v_exp_f32_e32 v47, v47
	v_mov_b32_dpp v22, v2 row_shr:1 row_mask:0xf bank_mask:0xf bound_ctrl:1
	v_fmac_f32_e32 v42, v84, v22
	v_fmac_f32_e32 v42, v88, v28
	v_mul_f32_e32 v43, v43, v44
	v_mul_f32_e32 v42, v42, v43
	v_add_f32_e32 v43, 1.0, v47
	v_rcp_f32_e32 v43, v43
	v_mov_b32_dpp v46, v5 row_shr:1 row_mask:0xf bank_mask:0xf bound_ctrl:1
	v_mov_b32_dpp v14, v3 row_shr:1 row_mask:0xf bank_mask:0xf bound_ctrl:1
	v_fma_f32 v44, v81, v46, v93
	v_fmac_f32_e32 v44, v85, v14
	v_cmp_gt_i32_e32 vcc, s64, v214
	v_fmac_f32_e32 v44, v89, v29
	v_mul_f32_e32 v43, v45, v43
	s_and_b64 s[6:7], s[10:11], vcc
	v_mul_f32_e32 v43, v44, v43
	v_cvt_pk_bf16_f32 v108, v40, v41
	v_cvt_pk_bf16_f32 v109, v42, v43
	s_and_saveexec_b64 s[14:15], s[6:7]
	s_cbranch_execz .LBB0_1175
	v_mov_b64_e32 v[40:41], s[4:5]
	v_mad_i64_i32 v[40:41], s[6:7], v214, s80, v[40:41]
	v_lshl_add_u64 v[40:41], v[182:183], 1, v[40:41]
	global_store_dwordx4 v[40:41], v[106:109], off sc1
.LBB0_1175:
	s_or_b64 exec, exec, s[14:15]
	v_fma_f32 v39, v94, v39, v70
	v_fmac_f32_e32 v39, v102, v34
	v_fmac_f32_e32 v39, v98, v24
	v_mul_f32_e32 v40, 0xbfb8aa3b, v39
	v_exp_f32_e32 v40, v40
	v_fma_f32 v37, v95, v37, v71
	v_fmac_f32_e32 v37, v103, v35
	v_fmac_f32_e32 v37, v99, v25
	v_add_f32_e32 v40, 1.0, v40
	v_rcp_f32_e32 v40, v40
	v_mul_f32_e32 v41, 0xbfb8aa3b, v37
	v_exp_f32_e32 v41, v41
	v_fma_f32 v38, v78, v38, v90
	v_fmac_f32_e32 v38, v82, v32
	v_fmac_f32_e32 v38, v86, v18
	v_mul_f32_e32 v39, v39, v40
	v_mul_f32_e32 v38, v38, v39
	v_add_f32_e32 v39, 1.0, v41
	v_rcp_f32_e32 v39, v39
	v_fma_f32 v23, v96, v23, v72
	v_fmac_f32_e32 v23, v104, v30
	v_fmac_f32_e32 v23, v100, v16
	v_mul_f32_e32 v37, v37, v39
	v_mul_f32_e32 v39, 0xbfb8aa3b, v23
	v_exp_f32_e32 v39, v39
	v_fma_f32 v36, v79, v36, v91
	v_fmac_f32_e32 v36, v83, v33
	v_fma_f32 v15, v97, v15, v73
	v_fmac_f32_e32 v36, v87, v19
	v_fmac_f32_e32 v15, v105, v31
	v_mul_f32_e32 v36, v36, v37
	v_add_f32_e32 v37, 1.0, v39
	v_fmac_f32_e32 v15, v101, v17
	v_rcp_f32_e32 v37, v37
	v_mul_f32_e32 v39, 0xbfb8aa3b, v15
	v_exp_f32_e32 v39, v39
	v_fma_f32 v22, v80, v22, v92
	v_fmac_f32_e32 v22, v84, v28
	v_fmac_f32_e32 v22, v88, v8
	v_mul_f32_e32 v23, v23, v37
	v_mul_f32_e32 v22, v22, v23
	v_add_f32_e32 v23, 1.0, v39
	v_rcp_f32_e32 v23, v23
	v_fma_f32 v14, v81, v14, v93
	v_fmac_f32_e32 v14, v85, v29
	v_cmp_gt_i32_e32 vcc, s64, v217
	v_fmac_f32_e32 v14, v89, v9
	v_mul_f32_e32 v15, v15, v23
	s_and_b64 s[6:7], s[10:11], vcc
	v_mul_f32_e32 v14, v14, v15
	v_cvt_pk_bf16_f32 v76, v38, v36
	v_cvt_pk_bf16_f32 v77, v22, v14
	s_and_saveexec_b64 s[14:15], s[6:7]
	s_cbranch_execz .LBB0_1177
	v_mov_b64_e32 v[14:15], s[4:5]
	v_mad_i64_i32 v[14:15], s[6:7], v217, s80, v[14:15]
	v_lshl_add_u64 v[14:15], v[182:183], 1, v[14:15]
	global_store_dwordx4 v[14:15], v[74:77], off sc1
; __device__ __forceinline__ unsigned cvt_pk_bf16(float lo, float hi) { unsigned r; asm volatile("v_cvt_pk_bf16_f32 %0, %1, %2" : "=v"(r) : "v"(lo), "v"(hi)); return r; }
;     __device__ __forceinline__ void operator()(const f32x4 (&acc)[2][2][4][2], const Unit& u, int wr, int wc, int fr, int fq) const {
;     ...
;                 for (int m = 0; m < 4; ++m) {
;                     u32x2_t w; float o[4];
; #pragma unroll
;                     for (int e = 0; e < 4; ++e) {
;                         const float g1 = m >= 1 ? xg[m - (m >= 1 ? 1 : 0)][e] : pg3[e], g2 = m >= 2 ? xg[m - (m >= 2 ? 2 : 0)][e] : (m == 1 ? pg3[e] : pg2[e]);
;                         const float v1 = m >= 1 ? xv[m - (m >= 1 ? 1 : 0)][e] : pv3[e], v2 = m >= 2 ? xv[m - (m >= 2 ? 2 : 0)][e] : (m == 1 ? pv3[e] : pv2[e]);
;                         const float cg_ = bg[e] + w0g[e] * g2 + w1g[e] * g1 + w2g[e] * xg[m][e];
;                         const float cv_ = bv[e] + w0v[e] * v2 + w1v[e] * v1 + w2v[e] * xv[m][e];
;                         o[e] = cg_ * __builtin_amdgcn_rcpf(1.0f + __expf(-cg_)) * cv_;
;                     }
;                     w.x = cvt_pk_bf16(o[0], o[1]); w.y = cvt_pk_bf16(o[2], o[3]);
;                     const int g = g0 + m;
;                     if (n == 0) stash[ai][m] = w;
;                     else if ((fr > 0 || m >= 2) && g < TT) { u32x4 ww; ww.x = stash[ai][m].x; ww.y = stash[ai][m].y; ww.z = w.x; ww.w = w.y; *(u32x4*)(G + (size_t)g * DFF_ + f0 - 4) = ww; }
.LBB0_1177:
	s_or_b64 exec, exec, s[14:15]
	v_fma_f32 v14, v94, v34, v70
	v_fmac_f32_e32 v14, v102, v24
	v_fmac_f32_e32 v14, v98, v26
	v_mul_f32_e32 v15, 0xbfb8aa3b, v14
	v_exp_f32_e32 v15, v15
	v_fma_f32 v23, v95, v35, v71
	v_fmac_f32_e32 v23, v103, v25
	v_fmac_f32_e32 v23, v99, v27
	v_fma_f32 v22, v78, v32, v90
	v_add_f32_e32 v15, 1.0, v15
	v_mul_f32_e32 v32, 0xbfb8aa3b, v23
	v_rcp_f32_e32 v15, v15
	v_exp_f32_e32 v32, v32
	v_fmac_f32_e32 v22, v82, v18
	v_fmac_f32_e32 v22, v86, v20
	v_mul_f32_e32 v14, v14, v15
	v_add_f32_e32 v15, 1.0, v32
	v_rcp_f32_e32 v15, v15
	v_mul_f32_e32 v14, v22, v14
	v_fma_f32 v22, v79, v33, v91
	v_fmac_f32_e32 v22, v83, v19
	v_mul_f32_e32 v15, v23, v15
	v_fma_f32 v23, v96, v30, v72
	v_fmac_f32_e32 v23, v104, v16
	v_fmac_f32_e32 v23, v100, v10
	v_mul_f32_e32 v30, 0xbfb8aa3b, v23
	v_exp_f32_e32 v30, v30
	v_fmac_f32_e32 v22, v87, v21
	v_mul_f32_e32 v15, v22, v15
	v_fma_f32 v22, v80, v28, v92
	v_add_f32_e32 v28, 1.0, v30
	v_fma_f32 v30, v97, v31, v73
	v_fmac_f32_e32 v30, v105, v17
	v_fmac_f32_e32 v30, v101, v11
	v_rcp_f32_e32 v28, v28
	v_mul_f32_e32 v31, 0xbfb8aa3b, v30
	v_exp_f32_e32 v31, v31
	v_fmac_f32_e32 v22, v84, v8
	v_fmac_f32_e32 v22, v88, v4
	v_mul_f32_e32 v23, v23, v28
	v_mul_f32_e32 v22, v22, v23
	v_add_f32_e32 v23, 1.0, v31
	v_rcp_f32_e32 v23, v23
	v_fma_f32 v28, v81, v29, v93
	v_fmac_f32_e32 v28, v85, v9
	v_fmac_f32_e32 v28, v89, v5
	v_mul_f32_e32 v23, v30, v23
	v_cmp_gt_i32_e32 vcc, s81, v214
	v_mul_f32_e32 v23, v28, v23
	v_cvt_pk_bf16_f32 v68, v14, v15
	v_cvt_pk_bf16_f32 v69, v22, v23
	s_and_saveexec_b64 s[14:15], vcc
	s_cbranch_execz .LBB0_1179
	v_mov_b64_e32 v[14:15], s[4:5]
	v_mad_i64_i32 v[14:15], s[6:7], v216, s80, v[14:15]
	v_lshl_add_u64 v[14:15], v[182:183], 1, v[14:15]
	global_store_dwordx4 v[14:15], v[66:69], off sc1
.LBB0_1179:
	s_or_b64 exec, exec, s[14:15]
	v_fma_f32 v14, v94, v24, v70
	v_fmac_f32_e32 v14, v102, v26
	v_fmac_f32_e32 v14, v98, v12
	v_mul_f32_e32 v12, 0xbfb8aa3b, v14
	v_exp_f32_e32 v12, v12
	v_fma_f32 v15, v78, v18, v90
	v_fma_f32 v18, v95, v25, v71
	v_fmac_f32_e32 v18, v103, v27
	v_fmac_f32_e32 v18, v99, v13
	v_add_f32_e32 v12, 1.0, v12
	v_mul_f32_e32 v13, 0xbfb8aa3b, v18
	v_rcp_f32_e32 v12, v12
	v_exp_f32_e32 v13, v13
	v_fmac_f32_e32 v15, v82, v20
	v_fmac_f32_e32 v15, v86, v6
	v_mul_f32_e32 v6, v14, v12
	v_add_f32_e32 v12, 1.0, v13
	v_rcp_f32_e32 v12, v12
	v_fma_f32 v13, v79, v19, v91
	v_fmac_f32_e32 v13, v83, v21
	v_fmac_f32_e32 v13, v87, v7
	v_mul_f32_e32 v7, v18, v12
	v_fma_f32 v12, v96, v16, v72
	v_fmac_f32_e32 v73, v97, v17
	v_fmac_f32_e32 v12, v104, v10
	v_fmac_f32_e32 v73, v105, v11
	v_fmac_f32_e32 v12, v100, v0
	v_fmac_f32_e32 v73, v101, v1
	v_mul_f32_e32 v0, 0xbfb8aa3b, v12
	v_mul_f32_e32 v1, 0xbfb8aa3b, v73
	v_exp_f32_e32 v0, v0
	v_exp_f32_e32 v1, v1
	v_fma_f32 v8, v80, v8, v92
	v_fmac_f32_e32 v93, v81, v9
	v_add_f32_e32 v0, 1.0, v0
	v_add_f32_e32 v1, 1.0, v1
	v_rcp_f32_e32 v0, v0
	v_rcp_f32_e32 v1, v1
	v_fmac_f32_e32 v8, v84, v4
	v_fmac_f32_e32 v93, v85, v5
	v_fmac_f32_e32 v8, v88, v2
	v_mul_f32_e32 v0, v12, v0
	v_fmac_f32_e32 v93, v89, v3
	v_mul_f32_e32 v1, v73, v1
	v_cmp_gt_i32_e32 vcc, s82, v214
	v_mul_f32_e32 v6, v15, v6
	v_mul_f32_e32 v7, v13, v7
	v_mul_f32_e32 v0, v8, v0
	v_mul_f32_e32 v1, v93, v1
	v_cvt_pk_bf16_f32 v66, v6, v7
	v_cvt_pk_bf16_f32 v67, v0, v1
	s_and_saveexec_b64 s[14:15], vcc
	s_cbranch_execz .LBB0_1181
	v_mov_b64_e32 v[0:1], s[4:5]
	v_mad_i64_i32 v[0:1], s[6:7], v215, s80, v[0:1]
	v_lshl_add_u64 v[0:1], v[182:183], 1, v[0:1]
	global_store_dwordx4 v[0:1], v[64:67], off sc1

; #define LAS __attribute__((address_space(3)))
; __device__ __forceinline__ unsigned cvtpk(float lo, float hi) { f32x2 v = {lo, hi}; bf16x2_t b = __builtin_convertvector(v, bf16x2_t); return __builtin_bit_cast(unsigned, b); }
; __device__ __forceinline__ void witem_store(const WItem& w, int K, bf16_t* WT, int kvperm, LAS float* scr, int item, int nblk, int lane) {
;     ...
;     for (int i = 0; i < 8; ++i) { LAS float* d = scr + (8 * i + rr) * 33 + col; const float g = w.g[i]; d[0] = w.v[i].x * g; d[1] = w.v[i].y * g; d[2] = w.v[i].z * g; d[3] = w.v[i].w * g; }
;     asm volatile("s_waitcnt lgkmcnt(0)" ::: "memory");
;     const int c = lane & 7;
; #pragma unroll
;     for (int j = 0; j < 4; ++j) { const int n = (lane >> 3) + 8 * j; const LAS float* s = scr + (8 * c) * 33 + n;
;         u32x4 o; o.x = cvtpk(s[0 * 33], s[1 * 33]); o.y = cvtpk(s[2 * 33], s[3 * 33]); o.z = cvtpk(s[4 * 33], s[5 * 33]); o.w = cvtpk(s[6 * 33], s[7 * 33]);
;         int nr = n0 + n; if (kvperm == 1) { const int hh = nr >> 8, ww = nr & 255; nr = (ww < 128) ? hh * 128 + ww : 2048 + hh * 128 + (ww - 128); }
;         else if (kvperm == 2) { const int isv = nr >= 5632, f = isv ? nr - 5632 : nr; nr = (f >> 7) * 256 + isv * 128 + (f & 127); }
;         *(u32x4*)(WT + (size_t)nr * K + k0 + 8 * c) = o; }
;     ...
;     while (it < i1) {
;         cur = nxt;
;         const int nit = it + NGW;
;         if (nit < i1) witem_load(nxt, W, N, gk, nit, nblk, lane);
;         witem_store(cur, K, WT, kvperm, scr, it, nblk, lane);
;         it = nit;
.LBB0_1205:
	v_pk_mul_f32 v[2:3], v[12:13], v[72:73] op_sel_hi:[1,0]
	ds_write2_b32 v79, v2, v3 offset1:1
	v_pk_mul_f32 v[2:3], v[14:15], v[72:73] op_sel_hi:[1,0]
	ds_write2_b32 v79, v2, v3 offset0:2 offset1:3
	v_pk_mul_f32 v[2:3], v[4:5], v[74:75] op_sel_hi:[1,0]
	v_add_u32_e32 v4, 0x420, v79
	ds_write2_b32 v4, v2, v3 offset1:1
	v_pk_mul_f32 v[2:3], v[6:7], v[74:75] op_sel_hi:[1,0]
	v_add_u32_e32 v4, 0x428, v79
	ds_write2_b32 v4, v2, v3 offset1:1
	v_pk_mul_f32 v[2:3], v[24:25], v[76:77] op_sel_hi:[1,0]
	v_add_u32_e32 v4, 0x840, v79
	ds_write2_b32 v4, v2, v3 offset1:1
	v_pk_mul_f32 v[2:3], v[26:27], v[76:77] op_sel_hi:[1,0]
	v_add_u32_e32 v4, 0x848, v79
	ds_write2_b32 v4, v2, v3 offset1:1
	v_pk_mul_f32 v[2:3], v[20:21], v[78:79] op_sel_hi:[1,0]
	v_add_u32_e32 v4, 0xc60, v79
	ds_write2_b32 v4, v2, v3 offset1:1
	v_pk_mul_f32 v[2:3], v[22:23], v[78:79] op_sel_hi:[1,0]
	v_add_u32_e32 v4, 0xc68, v79
	ds_write2_b32 v4, v2, v3 offset1:1
	v_pk_mul_f32 v[2:3], v[36:37], v[80:81] op_sel_hi:[1,0]
	v_add_u32_e32 v4, 0x1080, v79
	ds_write2_b32 v4, v2, v3 offset1:1
	v_pk_mul_f32 v[2:3], v[38:39], v[80:81] op_sel_hi:[1,0]
	v_add_u32_e32 v4, 0x1088, v79
	ds_write2_b32 v4, v2, v3 offset1:1
	v_pk_mul_f32 v[2:3], v[28:29], v[82:83] op_sel_hi:[1,0]
	v_add_u32_e32 v4, 0x14a0, v79
	ds_write2_b32 v4, v2, v3 offset1:1
	v_pk_mul_f32 v[2:3], v[30:31], v[82:83] op_sel_hi:[1,0]
	v_add_u32_e32 v4, 0x14a8, v79
	ds_write2_b32 v4, v2, v3 offset1:1
	s_waitcnt vmcnt(7)
	v_pk_mul_f32 v[2:3], v[48:49], v[84:85] op_sel_hi:[1,0]
	v_add_u32_e32 v4, 0x18c0, v79
	s_mul_hi_i32 s6, s6, 0x2e8ba2e9
	ds_write2_b32 v4, v2, v3 offset1:1
	v_pk_mul_f32 v[2:3], v[50:51], v[84:85] op_sel_hi:[1,0]
	v_add_u32_e32 v4, 0x18c8, v79
	s_lshr_b32 s10, s6, 31
	s_ashr_i32 s6, s6, 6
	ds_write2_b32 v4, v2, v3 offset1:1
	s_waitcnt vmcnt(6)
	v_pk_mul_f32 v[2:3], v[44:45], v[86:87] op_sel_hi:[1,0]
	v_add_u32_e32 v4, 0x1ce0, v79
	s_add_i32 s6, s6, s10
	ds_write2_b32 v4, v2, v3 offset1:1
	v_pk_mul_f32 v[2:3], v[46:47], v[86:87] op_sel_hi:[1,0]
	v_add_u32_e32 v4, 0x1ce8, v79
	s_lshl_b32 s10, s6, 6
	ds_write2_b32 v4, v2, v3 offset1:1
	s_mulk_i32 s6, 0xd400
	s_waitcnt lgkmcnt(0)
	s_add_i32 s6, s6, s7
	ds_read2_b32 v[6:7], v77 offset0:33 offset1:41
	ds_read2_b32 v[12:13], v77 offset1:8
	ds_read2_b32 v[14:15], v77 offset0:66 offset1:74
	ds_read2_b32 v[20:21], v77 offset0:99 offset1:107
	ds_read2_b32 v[22:23], v77 offset0:132 offset1:140
	ds_read2_b32 v[24:25], v77 offset0:165 offset1:173
	ds_read2_b32 v[26:27], v77 offset0:198 offset1:206
	ds_read2_b32 v[28:29], v77 offset0:231 offset1:239
	v_add_u32_e32 v38, s6, v83
	s_waitcnt lgkmcnt(6)
	v_cvt_pk_bf16_f32 v2, v12, v6
	v_add_u32_e32 v6, 0xffffea00, v38
	v_cmp_lt_i32_e32 vcc, s16, v38
	s_waitcnt lgkmcnt(4)
	v_cvt_pk_bf16_f32 v3, v14, v20
	s_ashr_i32 s11, s10, 31
	v_cndmask_b32_e32 v6, v38, v6, vcc
	v_lshlrev_b32_e32 v12, 1, v6
	v_and_b32_e32 v12, 0xffffff00, v12
	v_cndmask_b32_e32 v14, 0, v81, vcc
	v_and_b32_e32 v6, 0x67, v6
	v_or3_b32 v36, v6, v14, v12
	v_ashrrev_i32_e32 v37, 31, v36
	v_lshl_add_u64 v[30:31], s[10:11], 1, v[70:71]
	v_lshlrev_b64 v[36:37], 12, v[36:37]
	s_waitcnt lgkmcnt(2)
	v_cvt_pk_bf16_f32 v4, v22, v24
	s_waitcnt lgkmcnt(0)
	v_cvt_pk_bf16_f32 v5, v26, v28
	v_lshl_add_u64 v[36:37], v[30:31], 0, v[36:37]
	v_add_u32_e32 v6, 8, v38
	global_store_dwordx4 v[36:37], v[2:5], off sc1
	v_cmp_lt_i32_e32 vcc, s16, v6
	s_waitcnt vmcnt(3)
	v_mov_b64_e32 v[48:49], v[60:61]
	v_cvt_pk_bf16_f32 v2, v13, v7
	v_add_u32_e32 v7, 0xffffea08, v38
	v_cndmask_b32_e32 v6, v6, v7, vcc
	v_lshlrev_b32_e32 v7, 1, v6
	v_and_b32_e32 v7, 0xffffff00, v7
	v_cndmask_b32_e32 v12, 0, v81, vcc
	v_and_b32_e32 v6, 0x6f, v6
	v_or3_b32 v6, v6, v12, v7
	v_ashrrev_i32_e32 v7, 31, v6
	v_lshlrev_b64 v[6:7], 12, v[6:7]
	v_cvt_pk_bf16_f32 v3, v15, v21
	v_cvt_pk_bf16_f32 v4, v23, v25
	v_cvt_pk_bf16_f32 v5, v27, v29
	v_lshl_add_u64 v[6:7], v[30:31], 0, v[6:7]
	ds_read2_b32 v[12:13], v77 offset0:16 offset1:24
	ds_read2_b32 v[14:15], v77 offset0:49 offset1:57
	ds_read2_b32 v[20:21], v77 offset0:82 offset1:90
	ds_read2_b32 v[22:23], v77 offset0:115 offset1:123
	ds_read2_b32 v[24:25], v77 offset0:148 offset1:156
	ds_read2_b32 v[26:27], v77 offset0:181 offset1:189
	ds_read2_b32 v[28:29], v77 offset0:214 offset1:222
	ds_read2_b32 v[36:37], v77 offset0:247 offset1:255
	global_store_dwordx4 v[6:7], v[2:5], off sc1
	v_add_u32_e32 v6, 16, v38
	v_add_u32_e32 v7, 0xffffea10, v38
	v_cmp_lt_i32_e32 vcc, s16, v6
	s_waitcnt lgkmcnt(6)
	v_cvt_pk_bf16_f32 v2, v12, v14
	s_waitcnt lgkmcnt(4)
	v_cvt_pk_bf16_f32 v3, v20, v22
	v_cndmask_b32_e32 v6, v6, v7, vcc
	v_lshlrev_b32_e32 v7, 1, v6
	v_and_b32_e32 v7, 0xffffff00, v7
	v_cndmask_b32_e32 v12, 0, v81, vcc
	v_and_b32_e32 v6, 0x77, v6
	v_or3_b32 v6, v6, v12, v7
	v_ashrrev_i32_e32 v7, 31, v6
	v_lshlrev_b64 v[6:7], 12, v[6:7]
	s_waitcnt lgkmcnt(2)
	v_cvt_pk_bf16_f32 v4, v24, v26
	s_waitcnt lgkmcnt(0)
	v_cvt_pk_bf16_f32 v5, v28, v36
	v_lshl_add_u64 v[6:7], v[30:31], 0, v[6:7]
	global_store_dwordx4 v[6:7], v[2:5], off sc1
	s_waitcnt vmcnt(4)
	v_mov_b64_e32 v[44:45], v[64:65]
	v_add_u32_e32 v83, s12, v83
	v_add_u32_e32 v2, 24, v38
	v_add_u32_e32 v3, 0xffffea18, v38
	v_cmp_lt_i32_e32 vcc, s16, v2
	v_cvt_pk_bf16_f32 v5, v29, v37
	v_mov_b64_e32 v[36:37], v[52:53]
	v_cndmask_b32_e32 v2, v2, v3, vcc
	v_lshlrev_b32_e32 v3, 1, v2
	v_and_b32_e32 v3, 0xffffff00, v3
	v_cndmask_b32_e32 v4, 0, v81, vcc
	v_and_b32_e32 v2, 0x7f, v2
	v_or3_b32 v6, v2, v4, v3
	v_ashrrev_i32_e32 v7, 31, v6
	v_lshlrev_b64 v[6:7], 12, v[6:7]
	v_cvt_pk_bf16_f32 v2, v13, v15
	v_cvt_pk_bf16_f32 v3, v21, v23
	v_cvt_pk_bf16_f32 v4, v25, v27
	v_lshl_add_u64 v[6:7], v[30:31], 0, v[6:7]
	global_store_dwordx4 v[6:7], v[2:5], off sc1
	s_waitcnt lgkmcnt(0)
	v_mov_b64_e32 v[12:13], v[16:17]
	v_mov_b64_e32 v[24:25], v[32:33]
	v_mov_b64_e32 v[4:5], v[8:9]
	v_mov_b64_e32 v[20:21], v[40:41]
	v_mov_b64_e32 v[28:29], v[56:57]
	s_add_i32 s17, s17, s12
	v_add_u32_e32 v73, s12, v73
	s_andn2_b64 vcc, exec, s[8:9]
	s_mov_b32 s6, s18
	v_mov_b64_e32 v[14:15], v[18:19]
	v_mov_b64_e32 v[6:7], v[10:11]
	v_mov_b64_e32 v[26:27], v[34:35]
	v_mov_b64_e32 v[22:23], v[42:43]
	v_mov_b64_e32 v[38:39], v[54:55]
	v_mov_b64_e32 v[30:31], v[58:59]
	v_mov_b64_e32 v[50:51], v[62:63]
	v_mov_b64_e32 v[46:47], v[66:67]
	v_mov_b32_e32 v72, v85
	v_mov_b32_e32 v74, v87
	v_mov_b32_e32 v76, v89
	v_mov_b32_e32 v78, v94
	v_mov_b32_e32 v80, v95
	v_mov_b32_e32 v82, v96
	v_mov_b32_e32 v84, v97
	s_waitcnt vmcnt(4)
	v_mov_b32_e32 v86, v1
	s_cbranch_vccz .LBB0_1223

; __device__ __forceinline__ unsigned cvt_pk_bf16(float lo, float hi) { unsigned r; asm volatile("v_cvt_pk_bf16_f32 %0, %1, %2" : "=v"(r) : "v"(lo), "v"(hi)); return r; }
;     __device__ __forceinline__ void operator()(const f32x4 (&acc)[2][2][4][2], const Unit& u, int wr, int wc, int fr, int fq) const {
;     ...
;         for (int ai = 0; ai < 2; ++ai) {
;             u32x4 old[4][2];
; #pragma unroll
;             for (int m = 0; m < 4; ++m)
; #pragma unroll
;                 for (int bj = 0; bj < 2; ++bj) old[m][bj] = *(const u32x4*)(HB + (size_t)(row0 + ai * HALF + m * 16) * ldc + col0 + bj * HALF);
; #pragma unroll
;             for (int m = 0; m < 4; ++m) { const int row = row0 + ai * HALF + m * 16; float ss = 0.f;
; #pragma unroll
;                 for (int bj = 0; bj < 2; ++bj) { const u32x4 ow = old[m][bj];
;                     f32x4 v0 = (acc[ai][bj][m][0] + bv[bj][0]) * accs, v1 = (acc[ai][bj][m][1] + bv[bj][1]) * accs;
;                     v0[0] += __uint_as_float(ow.x << 16); v0[1] += __uint_as_float(ow.x & 0xffff0000u); v0[2] += __uint_as_float(ow.y << 16); v0[3] += __uint_as_float(ow.y & 0xffff0000u);
;                     v1[0] += __uint_as_float(ow.z << 16); v1[1] += __uint_as_float(ow.z & 0xffff0000u); v1[2] += __uint_as_float(ow.w << 16); v1[3] += __uint_as_float(ow.w & 0xffff0000u);
;                     ss += (v0[0] * v0[0] + v0[1] * v0[1]) + (v0[2] * v0[2] + v0[3] * v0[3]) + (v1[0] * v1[0] + v1[1] * v1[1]) + (v1[2] * v1[2] + v1[3] * v1[3]);
;                     u32x4 w; w.x = cvt_pk_bf16(v0[0], v0[1]); w.y = cvt_pk_bf16(v0[2], v0[3]); w.z = cvt_pk_bf16(v1[0], v1[1]); w.w = cvt_pk_bf16(v1[2], v1[3]);
;                     *(u32x4*)(HB + (size_t)row * ldc + col0 + bj * HALF) = w; }
;                 ss += __shfl_xor(ss, 16); ss += __shfl_xor(ss, 32);
;                 if (fq == 0) ssp[(size_t)row * 32] = ss; }
.LBB0_1301:
	v_lshl_or_b32 v152, s6, 8, v166
	v_ashrrev_i32_e32 v153, 31, v152
	v_lshl_add_u32 v154, s7, 8, v164
	v_lshlrev_b64 v[180:181], 1, v[152:153]
	v_ashrrev_i32_e32 v155, 31, v154
	v_lshl_add_u64 v[156:157], s[8:9], 0, v[180:181]
	v_lshlrev_b64 v[182:183], 12, v[154:155]
	v_lshl_add_u64 v[128:129], v[156:157], 0, v[182:183]
	global_load_dwordx4 v[172:175], v[128:129], off
	global_load_dwordx4 v[176:179], v[128:129], off offset:256
	v_or_b32_e32 v162, 16, v154
	v_or_b32_e32 v160, 32, v154
	v_or_b32_e32 v158, 48, v154
	v_ashrrev_i32_e32 v163, 31, v162
	v_ashrrev_i32_e32 v161, 31, v160
	v_pk_add_f32 v[196:197], v[114:115], 0 op_sel_hi:[1,0]
	v_pk_add_f32 v[198:199], v[112:113], 0 op_sel_hi:[1,0]
	v_ashrrev_i32_e32 v159, 31, v158
	v_lshlrev_b64 v[112:113], 12, v[162:163]
	v_lshlrev_b64 v[114:115], 12, v[160:161]
	v_pk_add_f32 v[194:195], v[116:117], 0 op_sel_hi:[1,0]
	v_lshlrev_b64 v[116:117], 12, v[158:159]
	v_lshl_add_u64 v[112:113], v[156:157], 0, v[112:113]
	v_lshl_add_u64 v[114:115], v[156:157], 0, v[114:115]
	v_pk_add_f32 v[184:185], v[126:127], 0 op_sel_hi:[1,0]
	v_pk_add_f32 v[186:187], v[124:125], 0 op_sel_hi:[1,0]
	v_pk_add_f32 v[188:189], v[122:123], 0 op_sel_hi:[1,0]
	v_pk_add_f32 v[190:191], v[120:121], 0 op_sel_hi:[1,0]
	v_pk_add_f32 v[192:193], v[118:119], 0 op_sel_hi:[1,0]
	v_lshl_add_u64 v[200:201], v[156:157], 0, v[116:117]
	global_load_dwordx4 v[132:135], v[112:113], off
	global_load_dwordx4 v[128:131], v[112:113], off offset:256
	global_load_dwordx4 v[124:127], v[114:115], off
	global_load_dwordx4 v[120:123], v[114:115], off offset:256
	global_load_dwordx4 v[116:119], v[200:201], off
	s_nop 0
	global_load_dwordx4 v[112:115], v[200:201], off offset:256
	s_lshl_b32 s6, s6, 2
	s_or_b32 s6, s6, s42
	s_ashr_i32 s7, s6, 31
	s_lshl_b64 s[6:7], s[6:7], 2
	s_add_u32 s22, s40, s6
	s_addc_u32 s23, s41, s7
	s_waitcnt vmcnt(0)
	v_lshlrev_b32_e32 v171, 16, v172
	v_and_b32_e32 v172, 0xffff0000, v172
	v_lshlrev_b32_e32 v200, 16, v173
	v_and_b32_e32 v173, 0xffff0000, v173
	v_lshlrev_b32_e32 v201, 16, v174
	v_lshlrev_b32_e32 v202, 16, v175
	v_lshlrev_b32_e32 v203, 16, v176
	v_and_b32_e32 v176, 0xffff0000, v176
	v_lshlrev_b32_e32 v206, 16, v177
	v_and_b32_e32 v177, 0xffff0000, v177
	v_add_f32_e32 v172, v187, v172
	v_add_f32_e32 v173, v185, v173
	v_and_b32_e32 v175, 0xffff0000, v175
	v_lshlrev_b32_e32 v207, 16, v178
	v_and_b32_e32 v178, 0xffff0000, v178
	v_lshlrev_b32_e32 v208, 16, v179
	v_add_f32_e32 v171, v186, v171
	v_add_f32_e32 v184, v184, v200
	v_add_f32_e32 v185, v190, v201
	v_add_f32_e32 v186, v188, v202
	v_add_f32_e32 v188, v195, v176
	v_add_f32_e32 v190, v193, v177
	v_mul_f32_e32 v176, v172, v172
	v_mul_f32_e32 v177, v173, v173
	v_and_b32_e32 v174, 0xffff0000, v174
	v_add_f32_e32 v175, v189, v175
	v_add_f32_e32 v187, v194, v203
	v_add_f32_e32 v189, v192, v206
	v_add_f32_e32 v178, v199, v178
	v_add_f32_e32 v192, v196, v208
	v_mul_f32_e32 v195, v188, v188
	v_mul_f32_e32 v196, v190, v190
	v_fmac_f32_e32 v176, v171, v171
	v_fmac_f32_e32 v177, v184, v184
	v_and_b32_e32 v179, 0xffff0000, v179
	v_add_f32_e32 v174, v191, v174
	v_add_f32_e32 v191, v198, v207
	v_cvt_pk_bf16_f32 v172, v171, v172
	v_fmac_f32_e32 v195, v187, v187
	v_add_f32_e32 v171, v176, v177
	v_fmac_f32_e32 v196, v189, v189
	v_mul_f32_e32 v177, v178, v178
	v_add_f32_e32 v179, v197, v179
	v_mul_f32_e32 v193, v174, v174
	v_add_f32_e32 v176, v195, v196
	v_fmac_f32_e32 v177, v191, v191
	v_mul_f32_e32 v194, v175, v175
	v_fmac_f32_e32 v193, v185, v185
	v_add_f32_e32 v176, v177, v176
	v_mul_f32_e32 v177, v179, v179
	v_fmac_f32_e32 v194, v186, v186
	v_add_f32_e32 v171, v193, v171
	v_fmac_f32_e32 v177, v192, v192
	v_add_f32_e32 v171, v194, v171
	v_add_f32_e32 v176, v177, v176
	v_cvt_pk_bf16_f32 v173, v184, v173
	v_add_f32_e32 v184, v171, v176
	v_and_b32_e32 v176, 64, v170
	v_cvt_pk_bf16_f32 v174, v185, v174
	v_xor_b32_e32 v171, 16, v170
	v_add_u32_e32 v185, 64, v176
	v_cmp_lt_i32_e32 vcc, v171, v185
	v_cvt_pk_bf16_f32 v175, v186, v175
	v_lshl_add_u64 v[176:177], s[8:9], 0, v[182:183]
	v_lshl_add_u64 v[180:181], v[176:177], 0, v[180:181]
	v_cndmask_b32_e32 v171, v170, v171, vcc
	v_lshlrev_b32_e32 v171, 2, v171
	ds_bpermute_b32 v186, v171, v184
	global_store_dwordx4 v[180:181], v[172:175], off sc1
	v_cvt_pk_bf16_f32 v176, v187, v188
	v_cvt_pk_bf16_f32 v177, v189, v190
	v_cvt_pk_bf16_f32 v178, v191, v178
	v_cvt_pk_bf16_f32 v179, v192, v179
	global_store_dwordx4 v[180:181], v[176:179], off offset:256 sc1
	s_nop 0
	v_xor_b32_e32 v172, 32, v170
	v_cmp_lt_i32_e32 vcc, v172, v185
	s_waitcnt lgkmcnt(0)
	v_add_f32_e32 v173, v184, v186
	v_cndmask_b32_e32 v172, v170, v172, vcc
	v_lshlrev_b32_e32 v172, 2, v172
	ds_bpermute_b32 v174, v172, v173
	s_and_saveexec_b64 s[24:25], s[10:11]
	s_cbranch_execz .LBB0_1303
	v_lshlrev_b64 v[176:177], 7, v[154:155]
	v_lshl_add_u64 v[176:177], s[22:23], 0, v[176:177]
	s_waitcnt lgkmcnt(0)
	v_add_f32_e32 v155, v173, v174
	global_store_dword v[176:177], v155, off
; __device__ __forceinline__ unsigned cvt_pk_bf16(float lo, float hi) { unsigned r; asm volatile("v_cvt_pk_bf16_f32 %0, %1, %2" : "=v"(r) : "v"(lo), "v"(hi)); return r; }
;     __device__ __forceinline__ void operator()(const f32x4 (&acc)[2][2][4][2], const Unit& u, int wr, int wc, int fr, int fq) const {
;     ...
;             for (int m = 0; m < 4; ++m) { const int row = row0 + ai * HALF + m * 16; float ss = 0.f;
; #pragma unroll
;                 for (int bj = 0; bj < 2; ++bj) { const u32x4 ow = old[m][bj];
;                     f32x4 v0 = (acc[ai][bj][m][0] + bv[bj][0]) * accs, v1 = (acc[ai][bj][m][1] + bv[bj][1]) * accs;
;                     v0[0] += __uint_as_float(ow.x << 16); v0[1] += __uint_as_float(ow.x & 0xffff0000u); v0[2] += __uint_as_float(ow.y << 16); v0[3] += __uint_as_float(ow.y & 0xffff0000u);
;                     v1[0] += __uint_as_float(ow.z << 16); v1[1] += __uint_as_float(ow.z & 0xffff0000u); v1[2] += __uint_as_float(ow.w << 16); v1[3] += __uint_as_float(ow.w & 0xffff0000u);
;                     ss += (v0[0] * v0[0] + v0[1] * v0[1]) + (v0[2] * v0[2] + v0[3] * v0[3]) + (v1[0] * v1[0] + v1[1] * v1[1]) + (v1[2] * v1[2] + v1[3] * v1[3]);
;                     u32x4 w; w.x = cvt_pk_bf16(v0[0], v0[1]); w.y = cvt_pk_bf16(v0[2], v0[3]); w.z = cvt_pk_bf16(v1[0], v1[1]); w.w = cvt_pk_bf16(v1[2], v1[3]);
;                     *(u32x4*)(HB + (size_t)row * ldc + col0 + bj * HALF) = w; }
;                 ss += __shfl_xor(ss, 16); ss += __shfl_xor(ss, 32);
;                 if (fq == 0) ssp[(size_t)row * 32] = ss; }
.LBB0_1303:
	s_or_b64 exec, exec, s[24:25]
	v_pk_add_f32 v[108:109], v[108:109], 0 op_sel_hi:[1,0]
	v_lshlrev_b32_e32 v155, 16, v132
	v_and_b32_e32 v132, 0xffff0000, v132
	v_pk_add_f32 v[110:111], v[110:111], 0 op_sel_hi:[1,0]
	v_add_f32_e32 v109, v109, v132
	v_lshlrev_b32_e32 v132, 16, v133
	v_add_f32_e32 v110, v110, v132
	v_and_b32_e32 v132, 0xffff0000, v133
	v_pk_add_f32 v[104:105], v[104:105], 0 op_sel_hi:[1,0]
	v_add_f32_e32 v111, v111, v132
	v_lshlrev_b32_e32 v132, 16, v134
	v_add_f32_e32 v132, v104, v132
	v_and_b32_e32 v104, 0xffff0000, v134
	v_pk_add_f32 v[106:107], v[106:107], 0 op_sel_hi:[1,0]
	v_add_f32_e32 v133, v105, v104
	v_lshlrev_b32_e32 v104, 16, v135
	v_add_f32_e32 v134, v106, v104
	v_and_b32_e32 v104, 0xffff0000, v135
	v_add_f32_e32 v108, v108, v155
	v_add_f32_e32 v107, v107, v104
	v_mul_f32_e32 v104, v109, v109
	v_mul_f32_e32 v105, v111, v111
	v_fmac_f32_e32 v104, v108, v108
	v_fmac_f32_e32 v105, v110, v110
	v_add_f32_e32 v104, v104, v105
	v_mul_f32_e32 v105, v133, v133
	v_fmac_f32_e32 v105, v132, v132
	v_add_f32_e32 v104, v105, v104
	v_mul_f32_e32 v105, v107, v107
	v_fmac_f32_e32 v105, v134, v134
	v_add_f32_e32 v135, v105, v104
	v_cvt_pk_bf16_f32 v104, v108, v109
	v_pk_add_f32 v[100:101], v[100:101], 0 op_sel_hi:[1,0]
	v_lshlrev_b32_e32 v108, 16, v128
	v_add_f32_e32 v100, v100, v108
	v_and_b32_e32 v108, 0xffff0000, v128
	v_pk_add_f32 v[102:103], v[102:103], 0 op_sel_hi:[1,0]
	v_add_f32_e32 v101, v101, v108
	v_lshlrev_b32_e32 v108, 16, v129
	v_add_f32_e32 v108, v102, v108
	v_and_b32_e32 v102, 0xffff0000, v129
	v_pk_add_f32 v[96:97], v[96:97], 0 op_sel_hi:[1,0]
	v_add_f32_e32 v109, v103, v102
	v_lshlrev_b32_e32 v102, 16, v130
	v_cvt_pk_bf16_f32 v105, v110, v111
	v_add_f32_e32 v110, v96, v102
	v_and_b32_e32 v96, 0xffff0000, v130
	v_pk_add_f32 v[98:99], v[98:99], 0 op_sel_hi:[1,0]
	v_add_f32_e32 v111, v97, v96
	v_lshlrev_b32_e32 v96, 16, v131
	v_add_f32_e32 v128, v98, v96
	v_and_b32_e32 v96, 0xffff0000, v131
	v_add_f32_e32 v129, v99, v96
	v_mul_f32_e32 v96, v101, v101
	v_mul_f32_e32 v97, v109, v109
	v_fmac_f32_e32 v96, v100, v100
	v_fmac_f32_e32 v97, v108, v108
	v_add_f32_e32 v96, v96, v97
	v_mul_f32_e32 v97, v111, v111
	v_fmac_f32_e32 v97, v110, v110
	v_add_f32_e32 v96, v97, v96
	v_mul_f32_e32 v97, v129, v129
	v_fmac_f32_e32 v97, v128, v128
	v_add_f32_e32 v96, v97, v96
	v_add_f32_e32 v99, v135, v96
	ds_bpermute_b32 v130, v171, v99
	s_waitcnt lgkmcnt(1)
	v_lshlrev_b64 v[174:175], 11, v[162:163]
	v_lshl_add_u64 v[96:97], v[174:175], 1, s[8:9]
	v_lshl_add_u64 v[102:103], v[152:153], 1, v[96:97]
	v_cvt_pk_bf16_f32 v106, v132, v133
	s_waitcnt lgkmcnt(0)
	v_add_f32_e32 v96, v99, v130
	ds_bpermute_b32 v97, v172, v96
	v_cvt_pk_bf16_f32 v107, v134, v107
	global_store_dwordx4 v[102:103], v[104:107], off sc1
	v_cvt_pk_bf16_f32 v98, v100, v101
	v_cvt_pk_bf16_f32 v99, v108, v109
	v_cvt_pk_bf16_f32 v100, v110, v111
	v_cvt_pk_bf16_f32 v101, v128, v129
	global_store_dwordx4 v[102:103], v[98:101], off offset:256 sc1
	s_and_saveexec_b64 s[24:25], s[10:11]
	s_cbranch_execz .LBB0_1305
	v_lshlrev_b64 v[98:99], 7, v[162:163]
	v_lshl_add_u64 v[98:99], s[22:23], 0, v[98:99]
	s_waitcnt lgkmcnt(0)
	v_add_f32_e32 v96, v96, v97
	global_store_dword v[98:99], v96, off
.LBB0_1305:
	s_or_b64 exec, exec, s[24:25]
	v_pk_add_f32 v[92:93], v[92:93], 0 op_sel_hi:[1,0]
	v_lshlrev_b32_e32 v98, 16, v124
	v_add_f32_e32 v92, v92, v98
	v_and_b32_e32 v98, 0xffff0000, v124
	v_pk_add_f32 v[94:95], v[94:95], 0 op_sel_hi:[1,0]
	v_add_f32_e32 v93, v93, v98
	v_lshlrev_b32_e32 v98, 16, v125
	v_add_f32_e32 v94, v94, v98
	v_and_b32_e32 v98, 0xffff0000, v125
	v_pk_add_f32 v[88:89], v[88:89], 0 op_sel_hi:[1,0]
	v_add_f32_e32 v95, v95, v98
	v_lshlrev_b32_e32 v98, 16, v126
	v_add_f32_e32 v98, v88, v98
	v_and_b32_e32 v88, 0xffff0000, v126
	v_pk_add_f32 v[90:91], v[90:91], 0 op_sel_hi:[1,0]
	v_add_f32_e32 v99, v89, v88
	v_lshlrev_b32_e32 v88, 16, v127
	v_add_f32_e32 v100, v90, v88
	v_and_b32_e32 v88, 0xffff0000, v127
	v_add_f32_e32 v91, v91, v88
	v_mul_f32_e32 v88, v93, v93
	v_mul_f32_e32 v89, v95, v95
	v_fmac_f32_e32 v88, v92, v92
	v_fmac_f32_e32 v89, v94, v94
	v_add_f32_e32 v88, v88, v89
	v_mul_f32_e32 v89, v99, v99
	v_fmac_f32_e32 v89, v98, v98
	v_add_f32_e32 v88, v89, v88
	v_mul_f32_e32 v89, v91, v91
	v_fmac_f32_e32 v89, v100, v100
	v_add_f32_e32 v101, v89, v88
	v_cvt_pk_bf16_f32 v88, v92, v93
	v_pk_add_f32 v[84:85], v[84:85], 0 op_sel_hi:[1,0]
	v_lshlrev_b32_e32 v92, 16, v120
	v_add_f32_e32 v84, v84, v92
	v_and_b32_e32 v92, 0xffff0000, v120
	v_pk_add_f32 v[86:87], v[86:87], 0 op_sel_hi:[1,0]
	v_add_f32_e32 v85, v85, v92
	v_lshlrev_b32_e32 v92, 16, v121
	v_add_f32_e32 v92, v86, v92
	v_and_b32_e32 v86, 0xffff0000, v121
	v_pk_add_f32 v[80:81], v[80:81], 0 op_sel_hi:[1,0]
	v_add_f32_e32 v93, v87, v86
	v_lshlrev_b32_e32 v86, 16, v122
	v_cvt_pk_bf16_f32 v89, v94, v95
	v_add_f32_e32 v94, v80, v86
	v_and_b32_e32 v80, 0xffff0000, v122
	v_pk_add_f32 v[82:83], v[82:83], 0 op_sel_hi:[1,0]
	v_add_f32_e32 v95, v81, v80
	v_lshlrev_b32_e32 v80, 16, v123
	v_cvt_pk_bf16_f32 v90, v98, v99
	v_add_f32_e32 v98, v82, v80
	v_and_b32_e32 v80, 0xffff0000, v123
	v_add_f32_e32 v99, v83, v80
	v_mul_f32_e32 v80, v85, v85
	v_mul_f32_e32 v81, v93, v93
	v_fmac_f32_e32 v80, v84, v84
	v_fmac_f32_e32 v81, v92, v92
	v_add_f32_e32 v80, v80, v81
	v_mul_f32_e32 v81, v95, v95
	v_fmac_f32_e32 v81, v94, v94
	v_add_f32_e32 v80, v81, v80
	v_mul_f32_e32 v81, v99, v99
	v_fmac_f32_e32 v81, v98, v98
	v_add_f32_e32 v80, v81, v80
	v_add_f32_e32 v83, v101, v80
	v_cvt_pk_bf16_f32 v91, v100, v91
	ds_bpermute_b32 v100, v171, v83
	s_waitcnt lgkmcnt(1)
	v_lshlrev_b64 v[96:97], 11, v[160:161]
	v_lshl_add_u64 v[80:81], v[96:97], 1, s[8:9]
	v_lshl_add_u64 v[86:87], v[152:153], 1, v[80:81]
	global_store_dwordx4 v[86:87], v[88:91], off sc1
	s_waitcnt lgkmcnt(0)
	v_add_f32_e32 v80, v83, v100
	ds_bpermute_b32 v81, v172, v80
	v_cvt_pk_bf16_f32 v82, v84, v85
	v_cvt_pk_bf16_f32 v83, v92, v93
	v_cvt_pk_bf16_f32 v84, v94, v95
	v_cvt_pk_bf16_f32 v85, v98, v99
	global_store_dwordx4 v[86:87], v[82:85], off offset:256 sc1
	s_and_saveexec_b64 s[24:25], s[10:11]
	s_cbranch_execz .LBB0_1307
	v_lshlrev_b64 v[82:83], 7, v[160:161]
	v_lshl_add_u64 v[82:83], s[22:23], 0, v[82:83]
	s_waitcnt lgkmcnt(0)
	v_add_f32_e32 v80, v80, v81
	global_store_dword v[82:83], v80, off
; __device__ __forceinline__ unsigned cvt_pk_bf16(float lo, float hi) { unsigned r; asm volatile("v_cvt_pk_bf16_f32 %0, %1, %2" : "=v"(r) : "v"(lo), "v"(hi)); return r; }
;     __device__ __forceinline__ void operator()(const f32x4 (&acc)[2][2][4][2], const Unit& u, int wr, int wc, int fr, int fq) const {
;     ...
;         for (int ai = 0; ai < 2; ++ai) {
;             u32x4 old[4][2];
; #pragma unroll
;             for (int m = 0; m < 4; ++m)
; #pragma unroll
;                 for (int bj = 0; bj < 2; ++bj) old[m][bj] = *(const u32x4*)(HB + (size_t)(row0 + ai * HALF + m * 16) * ldc + col0 + bj * HALF);
; #pragma unroll
;             for (int m = 0; m < 4; ++m) { const int row = row0 + ai * HALF + m * 16; float ss = 0.f;
; #pragma unroll
;                 for (int bj = 0; bj < 2; ++bj) { const u32x4 ow = old[m][bj];
;                     f32x4 v0 = (acc[ai][bj][m][0] + bv[bj][0]) * accs, v1 = (acc[ai][bj][m][1] + bv[bj][1]) * accs;
;                     v0[0] += __uint_as_float(ow.x << 16); v0[1] += __uint_as_float(ow.x & 0xffff0000u); v0[2] += __uint_as_float(ow.y << 16); v0[3] += __uint_as_float(ow.y & 0xffff0000u);
;                     v1[0] += __uint_as_float(ow.z << 16); v1[1] += __uint_as_float(ow.z & 0xffff0000u); v1[2] += __uint_as_float(ow.w << 16); v1[3] += __uint_as_float(ow.w & 0xffff0000u);
;                     ss += (v0[0] * v0[0] + v0[1] * v0[1]) + (v0[2] * v0[2] + v0[3] * v0[3]) + (v1[0] * v1[0] + v1[1] * v1[1]) + (v1[2] * v1[2] + v1[3] * v1[3]);
;                     u32x4 w; w.x = cvt_pk_bf16(v0[0], v0[1]); w.y = cvt_pk_bf16(v0[2], v0[3]); w.z = cvt_pk_bf16(v1[0], v1[1]); w.w = cvt_pk_bf16(v1[2], v1[3]);
;                     *(u32x4*)(HB + (size_t)row * ldc + col0 + bj * HALF) = w; }
;                 ss += __shfl_xor(ss, 16); ss += __shfl_xor(ss, 32);
;                 if (fq == 0) ssp[(size_t)row * 32] = ss; }
.LBB0_1307:
	s_or_b64 exec, exec, s[24:25]
	v_pk_add_f32 v[76:77], v[76:77], 0 op_sel_hi:[1,0]
	v_lshlrev_b32_e32 v82, 16, v116
	v_add_f32_e32 v76, v76, v82
	v_and_b32_e32 v82, 0xffff0000, v116
	v_pk_add_f32 v[78:79], v[78:79], 0 op_sel_hi:[1,0]
	v_add_f32_e32 v77, v77, v82
	v_lshlrev_b32_e32 v82, 16, v117
	v_add_f32_e32 v78, v78, v82
	v_and_b32_e32 v82, 0xffff0000, v117
	v_pk_add_f32 v[72:73], v[72:73], 0 op_sel_hi:[1,0]
	v_add_f32_e32 v79, v79, v82
	v_lshlrev_b32_e32 v82, 16, v118
	v_add_f32_e32 v82, v72, v82
	v_and_b32_e32 v72, 0xffff0000, v118
	v_pk_add_f32 v[74:75], v[74:75], 0 op_sel_hi:[1,0]
	v_add_f32_e32 v83, v73, v72
	v_lshlrev_b32_e32 v72, 16, v119
	v_add_f32_e32 v84, v74, v72
	v_and_b32_e32 v72, 0xffff0000, v119
	v_add_f32_e32 v75, v75, v72
	v_mul_f32_e32 v72, v77, v77
	v_mul_f32_e32 v73, v79, v79
	v_fmac_f32_e32 v72, v76, v76
	v_fmac_f32_e32 v73, v78, v78
	v_add_f32_e32 v72, v72, v73
	v_mul_f32_e32 v73, v83, v83
	v_fmac_f32_e32 v73, v82, v82
	v_add_f32_e32 v72, v73, v72
	v_mul_f32_e32 v73, v75, v75
	v_fmac_f32_e32 v73, v84, v84
	v_add_f32_e32 v85, v73, v72
	v_cvt_pk_bf16_f32 v72, v76, v77
	v_pk_add_f32 v[68:69], v[68:69], 0 op_sel_hi:[1,0]
	v_lshlrev_b32_e32 v76, 16, v112
	v_add_f32_e32 v68, v68, v76
	v_and_b32_e32 v76, 0xffff0000, v112
	v_pk_add_f32 v[70:71], v[70:71], 0 op_sel_hi:[1,0]
	v_add_f32_e32 v69, v69, v76
	v_lshlrev_b32_e32 v76, 16, v113
	v_add_f32_e32 v76, v70, v76
	v_and_b32_e32 v70, 0xffff0000, v113
	v_pk_add_f32 v[64:65], v[64:65], 0 op_sel_hi:[1,0]
	v_add_f32_e32 v77, v71, v70
	v_lshlrev_b32_e32 v70, 16, v114
	v_cvt_pk_bf16_f32 v73, v78, v79
	v_add_f32_e32 v78, v64, v70
	v_and_b32_e32 v64, 0xffff0000, v114
	v_pk_add_f32 v[66:67], v[66:67], 0 op_sel_hi:[1,0]
	v_add_f32_e32 v79, v65, v64
	v_lshlrev_b32_e32 v64, 16, v115
	v_cvt_pk_bf16_f32 v74, v82, v83
	v_add_f32_e32 v82, v66, v64
	v_and_b32_e32 v64, 0xffff0000, v115
	v_add_f32_e32 v83, v67, v64
	v_mul_f32_e32 v64, v69, v69
	v_mul_f32_e32 v65, v77, v77
	v_fmac_f32_e32 v64, v68, v68
	v_fmac_f32_e32 v65, v76, v76
	v_add_f32_e32 v64, v64, v65
	v_mul_f32_e32 v65, v79, v79
	v_fmac_f32_e32 v65, v78, v78
	v_add_f32_e32 v64, v65, v64
	v_mul_f32_e32 v65, v83, v83
	v_fmac_f32_e32 v65, v82, v82
	v_add_f32_e32 v64, v65, v64
	v_add_f32_e32 v67, v85, v64
	v_cvt_pk_bf16_f32 v75, v84, v75
	ds_bpermute_b32 v84, v171, v67
	s_waitcnt lgkmcnt(1)
	v_lshlrev_b64 v[80:81], 11, v[158:159]
	v_lshl_add_u64 v[64:65], v[80:81], 1, s[8:9]
	v_lshl_add_u64 v[70:71], v[152:153], 1, v[64:65]
	global_store_dwordx4 v[70:71], v[72:75], off sc1
	s_waitcnt lgkmcnt(0)
	v_add_f32_e32 v64, v67, v84
	ds_bpermute_b32 v65, v172, v64
	v_cvt_pk_bf16_f32 v66, v68, v69
	v_cvt_pk_bf16_f32 v67, v76, v77
	v_cvt_pk_bf16_f32 v68, v78, v79
	v_cvt_pk_bf16_f32 v69, v82, v83
	global_store_dwordx4 v[70:71], v[66:69], off offset:256 sc1
	s_and_saveexec_b64 s[24:25], s[10:11]
	s_cbranch_execz .LBB0_1309
	v_lshlrev_b64 v[66:67], 7, v[158:159]
	v_lshl_add_u64 v[66:67], s[22:23], 0, v[66:67]
	s_waitcnt lgkmcnt(0)
	v_add_f32_e32 v64, v64, v65
	global_store_dword v[66:67], v64, off
.LBB0_1309:
	s_or_b64 exec, exec, s[24:25]
	v_add_u32_e32 v94, 0x80, v154
	v_ashrrev_i32_e32 v95, 31, v94
	v_lshlrev_b64 v[104:105], 12, v[94:95]
	s_waitcnt lgkmcnt(0)
	v_lshl_add_u64 v[64:65], v[156:157], 0, v[104:105]
	global_load_dwordx4 v[96:99], v[64:65], off
	global_load_dwordx4 v[100:103], v[64:65], off offset:256
	v_add_u32_e32 v92, 0x90, v154
	v_add_u32_e32 v90, 0xa0, v154
	v_add_u32_e32 v88, 0xb0, v154
	v_ashrrev_i32_e32 v93, 31, v92
	v_ashrrev_i32_e32 v91, 31, v90
	v_ashrrev_i32_e32 v89, 31, v88
	v_lshlrev_b64 v[64:65], 12, v[92:93]
	v_lshlrev_b64 v[66:67], 12, v[90:91]
	v_lshlrev_b64 v[68:69], 12, v[88:89]
	v_lshl_add_u64 v[64:65], v[156:157], 0, v[64:65]
	v_lshl_add_u64 v[66:67], v[156:157], 0, v[66:67]
	v_lshl_add_u64 v[106:107], v[156:157], 0, v[68:69]
	global_load_dwordx4 v[84:87], v[64:65], off
	global_load_dwordx4 v[80:83], v[64:65], off offset:256
	global_load_dwordx4 v[76:79], v[66:67], off
	global_load_dwordx4 v[72:75], v[66:67], off offset:256
	global_load_dwordx4 v[68:71], v[106:107], off
	s_nop 0
	global_load_dwordx4 v[64:67], v[106:107], off offset:256
	v_pk_add_f32 v[62:63], v[62:63], 0 op_sel_hi:[1,0]
	v_pk_add_f32 v[60:61], v[60:61], 0 op_sel_hi:[1,0]
	v_pk_add_f32 v[58:59], v[58:59], 0 op_sel_hi:[1,0]
	v_pk_add_f32 v[56:57], v[56:57], 0 op_sel_hi:[1,0]
	v_pk_add_f32 v[54:55], v[54:55], 0 op_sel_hi:[1,0]
	v_pk_add_f32 v[52:53], v[52:53], 0 op_sel_hi:[1,0]
	v_pk_add_f32 v[50:51], v[50:51], 0 op_sel_hi:[1,0]
	v_pk_add_f32 v[48:49], v[48:49], 0 op_sel_hi:[1,0]
	s_waitcnt vmcnt(7)
	v_lshlrev_b32_e32 v106, 16, v96
	v_and_b32_e32 v96, 0xffff0000, v96
	v_lshlrev_b32_e32 v107, 16, v97
	v_and_b32_e32 v97, 0xffff0000, v97
	v_lshlrev_b32_e32 v108, 16, v98
	v_and_b32_e32 v98, 0xffff0000, v98
	v_lshlrev_b32_e32 v109, 16, v99
	v_and_b32_e32 v99, 0xffff0000, v99
	s_waitcnt vmcnt(6)
	v_lshlrev_b32_e32 v110, 16, v100
	v_and_b32_e32 v100, 0xffff0000, v100
	v_lshlrev_b32_e32 v111, 16, v101
	v_and_b32_e32 v101, 0xffff0000, v101
	v_lshlrev_b32_e32 v112, 16, v102
	v_and_b32_e32 v102, 0xffff0000, v102
	v_lshlrev_b32_e32 v113, 16, v103
	v_and_b32_e32 v103, 0xffff0000, v103
	v_add_f32_e32 v61, v61, v96
	v_add_f32_e32 v63, v63, v97
	v_add_f32_e32 v57, v57, v98
	v_add_f32_e32 v59, v59, v99
	v_add_f32_e32 v97, v53, v100
	v_add_f32_e32 v99, v55, v101
	v_add_f32_e32 v60, v60, v106
	v_add_f32_e32 v62, v62, v107
	v_add_f32_e32 v56, v56, v108
	v_add_f32_e32 v58, v58, v109
	v_add_f32_e32 v96, v52, v110
	v_add_f32_e32 v98, v54, v111
	v_add_f32_e32 v100, v48, v112
	v_add_f32_e32 v101, v49, v102
	v_add_f32_e32 v102, v50, v113
	v_add_f32_e32 v103, v51, v103
	v_mul_f32_e32 v52, v61, v61
	v_mul_f32_e32 v53, v63, v63
	v_mul_f32_e32 v54, v57, v57
	v_mul_f32_e32 v55, v59, v59
	v_cvt_pk_bf16_f32 v48, v60, v61
	v_cvt_pk_bf16_f32 v49, v62, v63
	v_cvt_pk_bf16_f32 v50, v56, v57
	v_cvt_pk_bf16_f32 v51, v58, v59
	v_mul_f32_e32 v57, v97, v97
	v_mul_f32_e32 v59, v99, v99
	v_mul_f32_e32 v61, v101, v101
	v_fmac_f32_e32 v52, v60, v60
	v_fmac_f32_e32 v53, v62, v62
	v_fmac_f32_e32 v57, v96, v96
	v_fmac_f32_e32 v59, v98, v98
	v_mul_f32_e32 v63, v103, v103
	v_fmac_f32_e32 v54, v56, v56
	v_fmac_f32_e32 v61, v100, v100
	v_add_f32_e32 v52, v52, v53
	v_add_f32_e32 v53, v57, v59
	v_fmac_f32_e32 v55, v58, v58
	v_fmac_f32_e32 v63, v102, v102
	v_add_f32_e32 v52, v54, v52
	v_add_f32_e32 v53, v61, v53
	v_add_f32_e32 v52, v55, v52
	v_add_f32_e32 v53, v63, v53
	v_add_f32_e32 v56, v52, v53
	ds_bpermute_b32 v57, v171, v56
	v_lshl_add_u64 v[52:53], s[8:9], 0, v[104:105]
	v_lshl_add_u64 v[54:55], v[152:153], 1, v[52:53]
	global_store_dwordx4 v[54:55], v[48:51], off sc1
	s_waitcnt lgkmcnt(0)
	s_nop 0
	v_add_f32_e32 v48, v56, v57
	ds_bpermute_b32 v49, v172, v48
	v_cvt_pk_bf16_f32 v50, v96, v97
	v_cvt_pk_bf16_f32 v51, v98, v99
	v_cvt_pk_bf16_f32 v52, v100, v101
	v_cvt_pk_bf16_f32 v53, v102, v103
	global_store_dwordx4 v[54:55], v[50:53], off offset:256 sc1
	s_and_saveexec_b64 s[24:25], s[10:11]
	s_cbranch_execz .LBB0_1311
; __device__ __forceinline__ unsigned cvt_pk_bf16(float lo, float hi) { unsigned r; asm volatile("v_cvt_pk_bf16_f32 %0, %1, %2" : "=v"(r) : "v"(lo), "v"(hi)); return r; }
;     __device__ __forceinline__ void operator()(const f32x4 (&acc)[2][2][4][2], const Unit& u, int wr, int wc, int fr, int fq) const {
;     ...
;             for (int m = 0; m < 4; ++m) { const int row = row0 + ai * HALF + m * 16; float ss = 0.f;
; #pragma unroll
;                 for (int bj = 0; bj < 2; ++bj) { const u32x4 ow = old[m][bj];
;                     f32x4 v0 = (acc[ai][bj][m][0] + bv[bj][0]) * accs, v1 = (acc[ai][bj][m][1] + bv[bj][1]) * accs;
;                     v0[0] += __uint_as_float(ow.x << 16); v0[1] += __uint_as_float(ow.x & 0xffff0000u); v0[2] += __uint_as_float(ow.y << 16); v0[3] += __uint_as_float(ow.y & 0xffff0000u);
;                     v1[0] += __uint_as_float(ow.z << 16); v1[1] += __uint_as_float(ow.z & 0xffff0000u); v1[2] += __uint_as_float(ow.w << 16); v1[3] += __uint_as_float(ow.w & 0xffff0000u);
;                     ss += (v0[0] * v0[0] + v0[1] * v0[1]) + (v0[2] * v0[2] + v0[3] * v0[3]) + (v1[0] * v1[0] + v1[1] * v1[1]) + (v1[2] * v1[2] + v1[3] * v1[3]);
;                     u32x4 w; w.x = cvt_pk_bf16(v0[0], v0[1]); w.y = cvt_pk_bf16(v0[2], v0[3]); w.z = cvt_pk_bf16(v1[0], v1[1]); w.w = cvt_pk_bf16(v1[2], v1[3]);
;                     *(u32x4*)(HB + (size_t)row * ldc + col0 + bj * HALF) = w; }
;                 ss += __shfl_xor(ss, 16); ss += __shfl_xor(ss, 32);
;                 if (fq == 0) ssp[(size_t)row * 32] = ss; }
	v_lshlrev_b64 v[50:51], 7, v[94:95]
	v_lshl_add_u64 v[50:51], s[22:23], 0, v[50:51]
	s_waitcnt lgkmcnt(0)
	v_add_f32_e32 v48, v48, v49
	global_store_dword v[50:51], v48, off
.LBB0_1311:
	s_or_b64 exec, exec, s[24:25]
	v_pk_add_f32 v[44:45], v[44:45], 0 op_sel_hi:[1,0]
	s_waitcnt vmcnt(7)
	v_lshlrev_b32_e32 v50, 16, v84
	v_add_f32_e32 v44, v44, v50
	v_and_b32_e32 v50, 0xffff0000, v84
	v_pk_add_f32 v[46:47], v[46:47], 0 op_sel_hi:[1,0]
	v_add_f32_e32 v45, v45, v50
	v_lshlrev_b32_e32 v50, 16, v85
	v_add_f32_e32 v46, v46, v50
	v_and_b32_e32 v50, 0xffff0000, v85
	v_pk_add_f32 v[40:41], v[40:41], 0 op_sel_hi:[1,0]
	v_add_f32_e32 v47, v47, v50
	v_lshlrev_b32_e32 v50, 16, v86
	v_add_f32_e32 v50, v40, v50
	v_and_b32_e32 v40, 0xffff0000, v86
	v_pk_add_f32 v[42:43], v[42:43], 0 op_sel_hi:[1,0]
	v_add_f32_e32 v51, v41, v40
	v_lshlrev_b32_e32 v40, 16, v87
	v_add_f32_e32 v52, v42, v40
	v_and_b32_e32 v40, 0xffff0000, v87
	v_add_f32_e32 v43, v43, v40
	v_mul_f32_e32 v40, v45, v45
	v_mul_f32_e32 v41, v47, v47
	v_fmac_f32_e32 v40, v44, v44
	v_fmac_f32_e32 v41, v46, v46
	v_add_f32_e32 v40, v40, v41
	v_mul_f32_e32 v41, v51, v51
	v_fmac_f32_e32 v41, v50, v50
	v_add_f32_e32 v40, v41, v40
	v_mul_f32_e32 v41, v43, v43
	v_fmac_f32_e32 v41, v52, v52
	v_add_f32_e32 v53, v41, v40
	v_cvt_pk_bf16_f32 v40, v44, v45
	v_pk_add_f32 v[36:37], v[36:37], 0 op_sel_hi:[1,0]
	s_waitcnt vmcnt(6)
	v_lshlrev_b32_e32 v44, 16, v80
	v_add_f32_e32 v36, v36, v44
	v_and_b32_e32 v44, 0xffff0000, v80
	v_pk_add_f32 v[38:39], v[38:39], 0 op_sel_hi:[1,0]
	v_add_f32_e32 v37, v37, v44
	v_lshlrev_b32_e32 v44, 16, v81
	v_add_f32_e32 v44, v38, v44
	v_and_b32_e32 v38, 0xffff0000, v81
	v_pk_add_f32 v[32:33], v[32:33], 0 op_sel_hi:[1,0]
	v_add_f32_e32 v45, v39, v38
	v_lshlrev_b32_e32 v38, 16, v82
	v_cvt_pk_bf16_f32 v41, v46, v47
	v_add_f32_e32 v46, v32, v38
	v_and_b32_e32 v32, 0xffff0000, v82
	v_pk_add_f32 v[34:35], v[34:35], 0 op_sel_hi:[1,0]
	v_add_f32_e32 v47, v33, v32
	v_lshlrev_b32_e32 v32, 16, v83
	v_cvt_pk_bf16_f32 v42, v50, v51
	v_add_f32_e32 v50, v34, v32
	v_and_b32_e32 v32, 0xffff0000, v83
	v_add_f32_e32 v51, v35, v32
	v_mul_f32_e32 v32, v37, v37
	v_mul_f32_e32 v33, v45, v45
	v_fmac_f32_e32 v32, v36, v36
	v_fmac_f32_e32 v33, v44, v44
	v_add_f32_e32 v32, v32, v33
	v_mul_f32_e32 v33, v47, v47
	v_fmac_f32_e32 v33, v46, v46
	v_add_f32_e32 v32, v33, v32
	v_mul_f32_e32 v33, v51, v51
	v_fmac_f32_e32 v33, v50, v50
	v_add_f32_e32 v32, v33, v32
	v_add_f32_e32 v35, v53, v32
	v_cvt_pk_bf16_f32 v43, v52, v43
	ds_bpermute_b32 v52, v171, v35
	s_waitcnt lgkmcnt(1)
	v_lshlrev_b64 v[48:49], 11, v[92:93]
	v_lshl_add_u64 v[32:33], v[48:49], 1, s[8:9]
	v_lshl_add_u64 v[38:39], v[152:153], 1, v[32:33]
	global_store_dwordx4 v[38:39], v[40:43], off sc1
	s_waitcnt lgkmcnt(0)
	v_add_f32_e32 v32, v35, v52
	ds_bpermute_b32 v33, v172, v32
	v_cvt_pk_bf16_f32 v34, v36, v37
	v_cvt_pk_bf16_f32 v35, v44, v45
	v_cvt_pk_bf16_f32 v36, v46, v47
	v_cvt_pk_bf16_f32 v37, v50, v51
	global_store_dwordx4 v[38:39], v[34:37], off offset:256 sc1
	s_and_saveexec_b64 s[24:25], s[10:11]
	s_cbranch_execz .LBB0_1313
	v_lshlrev_b64 v[34:35], 7, v[92:93]
	v_lshl_add_u64 v[34:35], s[22:23], 0, v[34:35]
	s_waitcnt lgkmcnt(0)
	v_add_f32_e32 v32, v32, v33
	global_store_dword v[34:35], v32, off
; __device__ __forceinline__ unsigned cvt_pk_bf16(float lo, float hi) { unsigned r; asm volatile("v_cvt_pk_bf16_f32 %0, %1, %2" : "=v"(r) : "v"(lo), "v"(hi)); return r; }
;     __device__ __forceinline__ void operator()(const f32x4 (&acc)[2][2][4][2], const Unit& u, int wr, int wc, int fr, int fq) const {
;     ...
;             for (int m = 0; m < 4; ++m) { const int row = row0 + ai * HALF + m * 16; float ss = 0.f;
; #pragma unroll
;                 for (int bj = 0; bj < 2; ++bj) { const u32x4 ow = old[m][bj];
;                     f32x4 v0 = (acc[ai][bj][m][0] + bv[bj][0]) * accs, v1 = (acc[ai][bj][m][1] + bv[bj][1]) * accs;
;                     v0[0] += __uint_as_float(ow.x << 16); v0[1] += __uint_as_float(ow.x & 0xffff0000u); v0[2] += __uint_as_float(ow.y << 16); v0[3] += __uint_as_float(ow.y & 0xffff0000u);
;                     v1[0] += __uint_as_float(ow.z << 16); v1[1] += __uint_as_float(ow.z & 0xffff0000u); v1[2] += __uint_as_float(ow.w << 16); v1[3] += __uint_as_float(ow.w & 0xffff0000u);
;                     ss += (v0[0] * v0[0] + v0[1] * v0[1]) + (v0[2] * v0[2] + v0[3] * v0[3]) + (v1[0] * v1[0] + v1[1] * v1[1]) + (v1[2] * v1[2] + v1[3] * v1[3]);
;                     u32x4 w; w.x = cvt_pk_bf16(v0[0], v0[1]); w.y = cvt_pk_bf16(v0[2], v0[3]); w.z = cvt_pk_bf16(v1[0], v1[1]); w.w = cvt_pk_bf16(v1[2], v1[3]);
;                     *(u32x4*)(HB + (size_t)row * ldc + col0 + bj * HALF) = w; }
;                 ss += __shfl_xor(ss, 16); ss += __shfl_xor(ss, 32);
;                 if (fq == 0) ssp[(size_t)row * 32] = ss; }
.LBB0_1313:
	s_or_b64 exec, exec, s[24:25]
	v_pk_add_f32 v[28:29], v[28:29], 0 op_sel_hi:[1,0]
	s_waitcnt vmcnt(7)
	v_lshlrev_b32_e32 v34, 16, v76
	v_add_f32_e32 v28, v28, v34
	v_and_b32_e32 v34, 0xffff0000, v76
	v_pk_add_f32 v[30:31], v[30:31], 0 op_sel_hi:[1,0]
	v_add_f32_e32 v29, v29, v34
	v_lshlrev_b32_e32 v34, 16, v77
	v_add_f32_e32 v30, v30, v34
	v_and_b32_e32 v34, 0xffff0000, v77
	v_pk_add_f32 v[24:25], v[24:25], 0 op_sel_hi:[1,0]
	v_add_f32_e32 v31, v31, v34
	v_lshlrev_b32_e32 v34, 16, v78
	v_add_f32_e32 v34, v24, v34
	v_and_b32_e32 v24, 0xffff0000, v78
	v_pk_add_f32 v[26:27], v[26:27], 0 op_sel_hi:[1,0]
	v_add_f32_e32 v35, v25, v24
	v_lshlrev_b32_e32 v24, 16, v79
	v_add_f32_e32 v36, v26, v24
	v_and_b32_e32 v24, 0xffff0000, v79
	v_add_f32_e32 v27, v27, v24
	v_mul_f32_e32 v24, v29, v29
	v_mul_f32_e32 v25, v31, v31
	v_fmac_f32_e32 v24, v28, v28
	v_fmac_f32_e32 v25, v30, v30
	v_add_f32_e32 v24, v24, v25
	v_mul_f32_e32 v25, v35, v35
	v_fmac_f32_e32 v25, v34, v34
	v_add_f32_e32 v24, v25, v24
	v_mul_f32_e32 v25, v27, v27
	v_fmac_f32_e32 v25, v36, v36
	v_add_f32_e32 v37, v25, v24
	v_cvt_pk_bf16_f32 v24, v28, v29
	v_pk_add_f32 v[20:21], v[20:21], 0 op_sel_hi:[1,0]
	s_waitcnt vmcnt(6)
	v_lshlrev_b32_e32 v28, 16, v72
	v_add_f32_e32 v20, v20, v28
	v_and_b32_e32 v28, 0xffff0000, v72
	v_pk_add_f32 v[22:23], v[22:23], 0 op_sel_hi:[1,0]
	v_add_f32_e32 v21, v21, v28
	v_lshlrev_b32_e32 v28, 16, v73
	v_add_f32_e32 v28, v22, v28
	v_and_b32_e32 v22, 0xffff0000, v73
	v_pk_add_f32 v[16:17], v[16:17], 0 op_sel_hi:[1,0]
	v_add_f32_e32 v29, v23, v22
	v_lshlrev_b32_e32 v22, 16, v74
	v_cvt_pk_bf16_f32 v25, v30, v31
	v_add_f32_e32 v30, v16, v22
	v_and_b32_e32 v16, 0xffff0000, v74
	v_pk_add_f32 v[18:19], v[18:19], 0 op_sel_hi:[1,0]
	v_add_f32_e32 v31, v17, v16
	v_lshlrev_b32_e32 v16, 16, v75
	v_cvt_pk_bf16_f32 v26, v34, v35
	v_add_f32_e32 v34, v18, v16
	v_and_b32_e32 v16, 0xffff0000, v75
	v_add_f32_e32 v35, v19, v16
	v_mul_f32_e32 v16, v21, v21
	v_mul_f32_e32 v17, v29, v29
	v_fmac_f32_e32 v16, v20, v20
	v_fmac_f32_e32 v17, v28, v28
	v_add_f32_e32 v16, v16, v17
	v_mul_f32_e32 v17, v31, v31
	v_fmac_f32_e32 v17, v30, v30
	v_add_f32_e32 v16, v17, v16
	v_mul_f32_e32 v17, v35, v35
	v_fmac_f32_e32 v17, v34, v34
	v_add_f32_e32 v16, v17, v16
	v_add_f32_e32 v19, v37, v16
	v_cvt_pk_bf16_f32 v27, v36, v27
	ds_bpermute_b32 v36, v171, v19
	s_waitcnt lgkmcnt(1)
	v_lshlrev_b64 v[32:33], 11, v[90:91]
	v_lshl_add_u64 v[16:17], v[32:33], 1, s[8:9]
	v_lshl_add_u64 v[22:23], v[152:153], 1, v[16:17]
	global_store_dwordx4 v[22:23], v[24:27], off sc1
	s_waitcnt lgkmcnt(0)
	v_add_f32_e32 v16, v19, v36
	ds_bpermute_b32 v17, v172, v16
	v_cvt_pk_bf16_f32 v18, v20, v21
	v_cvt_pk_bf16_f32 v19, v28, v29
	v_cvt_pk_bf16_f32 v20, v30, v31
	v_cvt_pk_bf16_f32 v21, v34, v35
	global_store_dwordx4 v[22:23], v[18:21], off offset:256 sc1
	s_and_saveexec_b64 s[24:25], s[10:11]
	s_cbranch_execz .LBB0_1315
	v_lshlrev_b64 v[18:19], 7, v[90:91]
	v_lshl_add_u64 v[18:19], s[22:23], 0, v[18:19]
	s_waitcnt lgkmcnt(0)
	v_add_f32_e32 v16, v16, v17
	global_store_dword v[18:19], v16, off
.LBB0_1315:
	s_or_b64 exec, exec, s[24:25]
	v_pk_add_f32 v[12:13], v[12:13], 0 op_sel_hi:[1,0]
	s_waitcnt vmcnt(7)
	v_lshlrev_b32_e32 v18, 16, v68
	v_add_f32_e32 v12, v12, v18
	v_and_b32_e32 v18, 0xffff0000, v68
	v_pk_add_f32 v[14:15], v[14:15], 0 op_sel_hi:[1,0]
	v_add_f32_e32 v13, v13, v18
	v_lshlrev_b32_e32 v18, 16, v69
	v_add_f32_e32 v14, v14, v18
	v_and_b32_e32 v18, 0xffff0000, v69
	v_pk_add_f32 v[8:9], v[8:9], 0 op_sel_hi:[1,0]
	v_add_f32_e32 v15, v15, v18
	v_lshlrev_b32_e32 v18, 16, v70
	v_add_f32_e32 v18, v8, v18
	v_and_b32_e32 v8, 0xffff0000, v70
	v_pk_add_f32 v[10:11], v[10:11], 0 op_sel_hi:[1,0]
	v_add_f32_e32 v19, v9, v8
	v_lshlrev_b32_e32 v8, 16, v71
	v_add_f32_e32 v20, v10, v8
	v_and_b32_e32 v8, 0xffff0000, v71
	v_add_f32_e32 v11, v11, v8
	v_mul_f32_e32 v8, v13, v13
	v_mul_f32_e32 v9, v15, v15
	v_fmac_f32_e32 v8, v12, v12
	v_fmac_f32_e32 v9, v14, v14
	v_add_f32_e32 v8, v8, v9
	v_mul_f32_e32 v9, v19, v19
	v_fmac_f32_e32 v9, v18, v18
	v_add_f32_e32 v8, v9, v8
	v_mul_f32_e32 v9, v11, v11
	v_fmac_f32_e32 v9, v20, v20
	v_add_f32_e32 v21, v9, v8
	v_cvt_pk_bf16_f32 v8, v12, v13
	v_pk_add_f32 v[4:5], v[4:5], 0 op_sel_hi:[1,0]
	s_waitcnt vmcnt(6)
	v_lshlrev_b32_e32 v12, 16, v64
	v_add_f32_e32 v4, v4, v12
	v_and_b32_e32 v12, 0xffff0000, v64
	v_pk_add_f32 v[6:7], v[6:7], 0 op_sel_hi:[1,0]
	v_add_f32_e32 v5, v5, v12
	v_lshlrev_b32_e32 v12, 16, v65
	v_add_f32_e32 v12, v6, v12
	v_and_b32_e32 v6, 0xffff0000, v65
	v_pk_add_f32 v[0:1], v[0:1], 0 op_sel_hi:[1,0]
	v_add_f32_e32 v13, v7, v6
	v_lshlrev_b32_e32 v6, 16, v66
	v_cvt_pk_bf16_f32 v9, v14, v15
	v_add_f32_e32 v14, v0, v6
	v_and_b32_e32 v0, 0xffff0000, v66
	v_pk_add_f32 v[2:3], v[2:3], 0 op_sel_hi:[1,0]
	v_add_f32_e32 v15, v1, v0
	v_lshlrev_b32_e32 v0, 16, v67
	v_cvt_pk_bf16_f32 v10, v18, v19
	v_add_f32_e32 v18, v2, v0
	v_and_b32_e32 v0, 0xffff0000, v67
	v_add_f32_e32 v19, v3, v0
	v_mul_f32_e32 v0, v5, v5
	v_mul_f32_e32 v1, v13, v13
	v_fmac_f32_e32 v0, v4, v4
	v_fmac_f32_e32 v1, v12, v12
	v_add_f32_e32 v0, v0, v1
	v_mul_f32_e32 v1, v15, v15
	v_fmac_f32_e32 v1, v14, v14
	v_add_f32_e32 v0, v1, v0
	v_mul_f32_e32 v1, v19, v19
	v_fmac_f32_e32 v1, v18, v18
	v_add_f32_e32 v0, v1, v0
	v_add_f32_e32 v3, v21, v0
	v_cvt_pk_bf16_f32 v11, v20, v11
	ds_bpermute_b32 v20, v171, v3
	s_waitcnt lgkmcnt(1)
	v_lshlrev_b64 v[16:17], 11, v[88:89]
	v_lshl_add_u64 v[0:1], v[16:17], 1, s[8:9]
	v_lshl_add_u64 v[6:7], v[152:153], 1, v[0:1]
	global_store_dwordx4 v[6:7], v[8:11], off sc1
	s_waitcnt lgkmcnt(0)
	v_add_f32_e32 v0, v3, v20
	ds_bpermute_b32 v1, v172, v0
	v_cvt_pk_bf16_f32 v2, v4, v5
	v_cvt_pk_bf16_f32 v3, v12, v13
	v_cvt_pk_bf16_f32 v4, v14, v15
	v_cvt_pk_bf16_f32 v5, v18, v19
	global_store_dwordx4 v[6:7], v[2:5], off offset:256 sc1
	s_and_saveexec_b64 s[24:25], s[10:11]
	s_cbranch_execz .LBB0_1317
	v_lshlrev_b64 v[2:3], 7, v[88:89]
	v_lshl_add_u64 v[2:3], s[22:23], 0, v[2:3]
	s_waitcnt lgkmcnt(0)
	v_add_f32_e32 v0, v0, v1
	global_store_dword v[2:3], v0, off

; __device__ __forceinline__ unsigned cvt_pk_bf16(float lo, float hi) { unsigned r; asm volatile("v_cvt_pk_bf16_f32 %0, %1, %2" : "=v"(r) : "v"(lo), "v"(hi)); return r; }
; __device__ __forceinline__ float row_ss(const float* part, int row, int fq, int nf4) {
;     const f32x4* p = (const f32x4*)(part + (size_t)row * 32);
;     float s = 0.f;
; #pragma unroll
;     for (int j = 0; j < 2; ++j) { const int idx = fq + 4 * j; if (idx < nf4) { const f32x4 v = p[idx]; s += (v[0] + v[1]) + (v[2] + v[3]); } }
;     s += __shfl_xor(s, 16); s += __shfl_xor(s, 32);
;     return s;
;     __device__ __forceinline__ void operator()(const f32x4 (&acc)[2][2][4][2], const Unit& u, int wr, int wc, int fr, int fq) const {
;     ...
;             for (int m = 0; m < 4; ++m) { const int row = row0 + ai * HALF + m * 16; bf16_t* rowp = base + (size_t)row * ldc + col0;
;                 const float rs = rss ? __builtin_amdgcn_rsqf(row_ss(rss, row, fq, nf4) * rinv + 1e-6f) : 1.f;
; #pragma unroll
;                 for (int bj = 0; bj < 2; ++bj) { f32x4 v0 = acc[ai][bj][m][0] * rs + bv[bj][0], v1 = acc[ai][bj][m][1] * rs + bv[bj][1];
;                     v0 = v0 * sc; v1 = v1 * sc; u32x4 w; w.x = cvt_pk_bf16(v0[0], v0[1]); w.y = cvt_pk_bf16(v0[2], v0[3]); w.z = cvt_pk_bf16(v1[0], v1[1]); w.w = cvt_pk_bf16(v1[2], v1[3]);
;                     *(u32x4*)(rowp + bj * HALF) = w; } }
.LBB0_1393:
	v_lshl_add_u32 v162, s28, 8, v165
	v_ashrrev_i32_e32 v163, 31, v162
	v_lshlrev_b64 v[166:167], 7, v[162:163]
	v_lshl_add_u64 v[166:167], v[152:153], 0, v[166:167]
	global_load_dwordx4 v[178:181], v[166:167], off
	global_load_dwordx4 v[182:185], v[166:167], off offset:64
	v_and_b32_e32 v166, 64, v173
	v_xor_b32_e32 v164, 16, v173
	v_add_u32_e32 v166, 64, v166
	v_xor_b32_e32 v167, 32, v173
	v_or_b32_e32 v186, 16, v162
	v_cmp_lt_i32_e32 vcc, v164, v166
	v_lshlrev_b64 v[188:189], 12, v[162:163]
	v_ashrrev_i32_e32 v187, 31, v186
	v_cndmask_b32_e32 v163, v173, v164, vcc
	v_cmp_lt_i32_e32 vcc, v167, v166
	v_lshlrev_b32_e32 v176, 2, v163
	s_ashr_i32 s12, s6, 31
	v_cndmask_b32_e32 v164, v173, v167, vcc
	v_lshlrev_b64 v[166:167], 7, v[186:187]
	v_lshl_add_u64 v[190:191], v[152:153], 0, v[166:167]
	v_lshlrev_b32_e32 v163, 2, v164
	s_lshr_b32 s12, s12, 29
	s_add_i32 s12, s6, s12
	s_ashr_i32 s21, s12, 3
	s_mul_i32 s12, s21, 0x3000000
	s_mul_hi_i32 s13, s21, 0x3000000
	s_add_u32 s12, s44, s12
	s_addc_u32 s13, s45, s13
	s_lshl_b32 s21, s21, 11
	s_add_i32 s6, s6, 7
	s_sub_i32 s7, s7, s21
	s_cmp_lt_u32 s6, 15
	s_cselect_b64 vcc, -1, 0
	s_waitcnt vmcnt(0)
	v_mov_b32_e32 v166, v178
	v_mov_b32_e32 v167, v182
	v_mov_b32_e32 v182, v179
	v_mov_b32_e32 v178, v180
	v_mov_b32_e32 v179, v184
	v_mov_b32_e32 v184, v181
	v_pk_add_f32 v[166:167], v[166:167], v[182:183]
	v_pk_add_f32 v[178:179], v[178:179], v[184:185]
	s_nop 0
	v_pk_add_f32 v[166:167], v[166:167], v[178:179]
	s_nop 0
	v_add_f32_e32 v164, 0, v166
	v_add_f32_e32 v164, v164, v167
	ds_bpermute_b32 v166, v176, v164
	s_waitcnt lgkmcnt(0)
	v_add_f32_e32 v167, v164, v166
	ds_bpermute_b32 v177, v163, v167
	v_or_b32_e32 v166, s7, v169
	v_cndmask_b32_e32 v164, 1.0, v175, vcc
	s_andn2_b64 vcc, exec, s[10:11]
	s_mov_b64 s[10:11], -1
	s_waitcnt lgkmcnt(0)
	v_add_f32_e32 v167, v167, v177
	v_fmamk_f32 v167, v167, 0x3a000000, v174
	v_rsq_f32_e32 v178, v167
	v_ashrrev_i32_e32 v167, 31, v166
	v_lshl_add_u64 v[166:167], v[166:167], 1, s[12:13]
	v_lshl_add_u64 v[180:181], v[166:167], 0, v[188:189]
	v_pk_fma_f32 v[140:141], v[140:141], v[178:179], v[108:109] op_sel_hi:[1,0,1]
	v_pk_fma_f32 v[142:143], v[142:143], v[178:179], v[110:111] op_sel_hi:[1,0,1]
	v_pk_fma_f32 v[136:137], v[136:137], v[178:179], v[104:105] op_sel_hi:[1,0,1]
	v_pk_fma_f32 v[138:139], v[138:139], v[178:179], v[106:107] op_sel_hi:[1,0,1]
	v_pk_fma_f32 v[128:129], v[128:129], v[178:179], v[120:121] op_sel_hi:[1,0,1]
	v_pk_fma_f32 v[130:131], v[130:131], v[178:179], v[122:123] op_sel_hi:[1,0,1]
	v_pk_fma_f32 v[132:133], v[132:133], v[178:179], v[124:125] op_sel_hi:[1,0,1]
	v_pk_fma_f32 v[134:135], v[134:135], v[178:179], v[126:127] op_sel_hi:[1,0,1]
	v_pk_mul_f32 v[142:143], v[164:165], v[142:143] op_sel_hi:[0,1]
	v_pk_mul_f32 v[140:141], v[164:165], v[140:141] op_sel_hi:[0,1]
	v_pk_mul_f32 v[138:139], v[164:165], v[138:139] op_sel_hi:[0,1]
	v_pk_mul_f32 v[136:137], v[164:165], v[136:137] op_sel_hi:[0,1]
	v_pk_mul_f32 v[178:179], v[164:165], v[130:131] op_sel_hi:[0,1]
	v_pk_mul_f32 v[182:183], v[164:165], v[128:129] op_sel_hi:[0,1]
	v_cvt_pk_bf16_f32 v128, v140, v141
	v_cvt_pk_bf16_f32 v129, v142, v143
	v_cvt_pk_bf16_f32 v130, v136, v137
	v_cvt_pk_bf16_f32 v131, v138, v139
	v_pk_mul_f32 v[134:135], v[164:165], v[134:135] op_sel_hi:[0,1]
	v_pk_mul_f32 v[132:133], v[164:165], v[132:133] op_sel_hi:[0,1]
	global_store_dwordx4 v[180:181], v[128:131], off sc1
	s_nop 1
	v_cvt_pk_bf16_f32 v128, v132, v133
	v_cvt_pk_bf16_f32 v129, v134, v135
	v_cvt_pk_bf16_f32 v130, v182, v183
	v_cvt_pk_bf16_f32 v131, v178, v179
	global_store_dwordx4 v[180:181], v[128:131], off offset:256 sc1
	global_load_dwordx4 v[128:131], v[190:191], off
	s_nop 0
	global_load_dwordx4 v[132:135], v[190:191], off offset:64
	s_waitcnt vmcnt(1)
	v_mov_b32_e32 v136, v128
	s_waitcnt vmcnt(0)
	v_mov_b32_e32 v137, v132
	v_mov_b32_e32 v132, v129
	v_mov_b32_e32 v128, v130
	v_mov_b32_e32 v129, v134
	v_mov_b32_e32 v134, v131
	v_pk_add_f32 v[130:131], v[136:137], v[132:133]
	v_pk_add_f32 v[128:129], v[128:129], v[134:135]
	s_nop 0
	v_pk_add_f32 v[128:129], v[130:131], v[128:129]
	v_lshlrev_b64 v[130:131], 12, v[186:187]
	v_add_f32_e32 v128, 0, v128
	v_add_f32_e32 v128, v128, v129
	ds_bpermute_b32 v129, v176, v128
	v_lshl_add_u64 v[130:131], v[166:167], 0, v[130:131]
	s_waitcnt lgkmcnt(0)
	v_add_f32_e32 v132, v128, v129
	ds_bpermute_b32 v133, v163, v132
	v_or_b32_e32 v128, 32, v162
	v_ashrrev_i32_e32 v129, 31, v128
	v_lshlrev_b64 v[134:135], 7, v[128:129]
	v_lshl_add_u64 v[134:135], v[152:153], 0, v[134:135]
	s_waitcnt lgkmcnt(0)
	v_add_f32_e32 v132, v132, v133
	v_fmamk_f32 v132, v132, 0x3a000000, v174
	v_rsq_f32_e32 v132, v132
	s_nop 0
	v_pk_fma_f32 v[116:117], v[116:117], v[132:133], v[108:109] op_sel_hi:[1,0,1]
	v_pk_fma_f32 v[118:119], v[118:119], v[132:133], v[110:111] op_sel_hi:[1,0,1]
	v_pk_fma_f32 v[112:113], v[112:113], v[132:133], v[104:105] op_sel_hi:[1,0,1]
	v_pk_fma_f32 v[114:115], v[114:115], v[132:133], v[106:107] op_sel_hi:[1,0,1]
	v_pk_fma_f32 v[96:97], v[96:97], v[132:133], v[120:121] op_sel_hi:[1,0,1]
	v_pk_fma_f32 v[98:99], v[98:99], v[132:133], v[122:123] op_sel_hi:[1,0,1]
	v_pk_fma_f32 v[100:101], v[100:101], v[132:133], v[124:125] op_sel_hi:[1,0,1]
	v_pk_fma_f32 v[102:103], v[102:103], v[132:133], v[126:127] op_sel_hi:[1,0,1]
	v_pk_mul_f32 v[118:119], v[164:165], v[118:119] op_sel_hi:[0,1]
	v_pk_mul_f32 v[116:117], v[164:165], v[116:117] op_sel_hi:[0,1]
	v_pk_mul_f32 v[114:115], v[164:165], v[114:115] op_sel_hi:[0,1]
	v_pk_mul_f32 v[112:113], v[164:165], v[112:113] op_sel_hi:[0,1]
	v_pk_mul_f32 v[132:133], v[164:165], v[98:99] op_sel_hi:[0,1]
	v_pk_mul_f32 v[136:137], v[164:165], v[96:97] op_sel_hi:[0,1]
	v_cvt_pk_bf16_f32 v96, v116, v117
	v_cvt_pk_bf16_f32 v97, v118, v119
	v_cvt_pk_bf16_f32 v98, v112, v113
	v_cvt_pk_bf16_f32 v99, v114, v115
	v_pk_mul_f32 v[102:103], v[164:165], v[102:103] op_sel_hi:[0,1]
	v_pk_mul_f32 v[100:101], v[164:165], v[100:101] op_sel_hi:[0,1]
	global_store_dwordx4 v[130:131], v[96:99], off sc1
	s_nop 1
	v_cvt_pk_bf16_f32 v96, v100, v101
	v_cvt_pk_bf16_f32 v97, v102, v103
	v_cvt_pk_bf16_f32 v98, v136, v137
	v_cvt_pk_bf16_f32 v99, v132, v133
	global_store_dwordx4 v[130:131], v[96:99], off offset:256 sc1
	global_load_dwordx4 v[96:99], v[134:135], off
	s_nop 0
	global_load_dwordx4 v[100:103], v[134:135], off offset:64
	s_waitcnt vmcnt(1)
; __device__ __forceinline__ unsigned cvt_pk_bf16(float lo, float hi) { unsigned r; asm volatile("v_cvt_pk_bf16_f32 %0, %1, %2" : "=v"(r) : "v"(lo), "v"(hi)); return r; }
; __device__ __forceinline__ float row_ss(const float* part, int row, int fq, int nf4) {
;     const f32x4* p = (const f32x4*)(part + (size_t)row * 32);
;     float s = 0.f;
; #pragma unroll
;     for (int j = 0; j < 2; ++j) { const int idx = fq + 4 * j; if (idx < nf4) { const f32x4 v = p[idx]; s += (v[0] + v[1]) + (v[2] + v[3]); } }
;     s += __shfl_xor(s, 16); s += __shfl_xor(s, 32);
;     return s;
;     __device__ __forceinline__ void operator()(const f32x4 (&acc)[2][2][4][2], const Unit& u, int wr, int wc, int fr, int fq) const {
;     ...
;             for (int m = 0; m < 4; ++m) { const int row = row0 + ai * HALF + m * 16; bf16_t* rowp = base + (size_t)row * ldc + col0;
;                 const float rs = rss ? __builtin_amdgcn_rsqf(row_ss(rss, row, fq, nf4) * rinv + 1e-6f) : 1.f;
; #pragma unroll
;                 for (int bj = 0; bj < 2; ++bj) { f32x4 v0 = acc[ai][bj][m][0] * rs + bv[bj][0], v1 = acc[ai][bj][m][1] * rs + bv[bj][1];
;                     v0 = v0 * sc; v1 = v1 * sc; u32x4 w; w.x = cvt_pk_bf16(v0[0], v0[1]); w.y = cvt_pk_bf16(v0[2], v0[3]); w.z = cvt_pk_bf16(v1[0], v1[1]); w.w = cvt_pk_bf16(v1[2], v1[3]);
;                     *(u32x4*)(rowp + bj * HALF) = w; } }
	v_mov_b32_e32 v112, v96
	s_waitcnt vmcnt(0)
	v_mov_b32_e32 v113, v100
	v_mov_b32_e32 v100, v97
	v_mov_b32_e32 v96, v98
	v_mov_b32_e32 v97, v102
	v_mov_b32_e32 v102, v99
	v_pk_add_f32 v[98:99], v[112:113], v[100:101]
	v_pk_add_f32 v[96:97], v[96:97], v[102:103]
	s_nop 0
	v_pk_add_f32 v[96:97], v[98:99], v[96:97]
	v_lshlrev_b64 v[98:99], 12, v[128:129]
	v_add_f32_e32 v96, 0, v96
	v_add_f32_e32 v96, v96, v97
	ds_bpermute_b32 v97, v176, v96
	v_lshl_add_u64 v[98:99], v[166:167], 0, v[98:99]
	s_waitcnt lgkmcnt(0)
	v_add_f32_e32 v100, v96, v97
	ds_bpermute_b32 v101, v163, v100
	v_or_b32_e32 v96, 48, v162
	v_ashrrev_i32_e32 v97, 31, v96
	v_lshlrev_b64 v[102:103], 7, v[96:97]
	v_lshl_add_u64 v[102:103], v[152:153], 0, v[102:103]
	s_waitcnt lgkmcnt(0)
	v_add_f32_e32 v100, v100, v101
	v_fmamk_f32 v100, v100, 0x3a000000, v174
	v_rsq_f32_e32 v100, v100
	s_nop 0
	v_pk_fma_f32 v[92:93], v[92:93], v[100:101], v[108:109] op_sel_hi:[1,0,1]
	v_pk_fma_f32 v[94:95], v[94:95], v[100:101], v[110:111] op_sel_hi:[1,0,1]
	v_pk_fma_f32 v[88:89], v[88:89], v[100:101], v[104:105] op_sel_hi:[1,0,1]
	v_pk_fma_f32 v[90:91], v[90:91], v[100:101], v[106:107] op_sel_hi:[1,0,1]
	v_pk_fma_f32 v[80:81], v[80:81], v[100:101], v[120:121] op_sel_hi:[1,0,1]
	v_pk_fma_f32 v[82:83], v[82:83], v[100:101], v[122:123] op_sel_hi:[1,0,1]
	v_pk_fma_f32 v[84:85], v[84:85], v[100:101], v[124:125] op_sel_hi:[1,0,1]
	v_pk_fma_f32 v[86:87], v[86:87], v[100:101], v[126:127] op_sel_hi:[1,0,1]
	v_pk_mul_f32 v[94:95], v[164:165], v[94:95] op_sel_hi:[0,1]
	v_pk_mul_f32 v[92:93], v[164:165], v[92:93] op_sel_hi:[0,1]
	v_pk_mul_f32 v[90:91], v[164:165], v[90:91] op_sel_hi:[0,1]
	v_pk_mul_f32 v[88:89], v[164:165], v[88:89] op_sel_hi:[0,1]
	v_pk_mul_f32 v[100:101], v[164:165], v[82:83] op_sel_hi:[0,1]
	v_pk_mul_f32 v[112:113], v[164:165], v[80:81] op_sel_hi:[0,1]
	v_cvt_pk_bf16_f32 v80, v92, v93
	v_cvt_pk_bf16_f32 v81, v94, v95
	v_cvt_pk_bf16_f32 v82, v88, v89
	v_cvt_pk_bf16_f32 v83, v90, v91
	v_pk_mul_f32 v[86:87], v[164:165], v[86:87] op_sel_hi:[0,1]
	v_pk_mul_f32 v[84:85], v[164:165], v[84:85] op_sel_hi:[0,1]
	global_store_dwordx4 v[98:99], v[80:83], off sc1
	s_nop 1
	v_cvt_pk_bf16_f32 v80, v84, v85
	v_cvt_pk_bf16_f32 v81, v86, v87
	v_cvt_pk_bf16_f32 v82, v112, v113
	v_cvt_pk_bf16_f32 v83, v100, v101
	global_store_dwordx4 v[98:99], v[80:83], off offset:256 sc1
	global_load_dwordx4 v[80:83], v[102:103], off
	s_nop 0
	global_load_dwordx4 v[84:87], v[102:103], off offset:64
	s_waitcnt vmcnt(1)
	v_mov_b32_e32 v88, v80
	s_waitcnt vmcnt(0)
	v_mov_b32_e32 v89, v84
	v_mov_b32_e32 v84, v81
	v_mov_b32_e32 v80, v82
	v_mov_b32_e32 v81, v86
	v_mov_b32_e32 v86, v83
	v_pk_add_f32 v[82:83], v[88:89], v[84:85]
	v_pk_add_f32 v[80:81], v[80:81], v[86:87]
	s_nop 0
	v_pk_add_f32 v[80:81], v[82:83], v[80:81]
	v_lshlrev_b64 v[82:83], 12, v[96:97]
	v_add_f32_e32 v80, 0, v80
	v_add_f32_e32 v80, v80, v81
	ds_bpermute_b32 v81, v176, v80
	v_lshl_add_u64 v[82:83], v[166:167], 0, v[82:83]
	s_waitcnt lgkmcnt(0)
	v_add_f32_e32 v84, v80, v81
	ds_bpermute_b32 v85, v163, v84
	v_add_u32_e32 v80, 0x80, v162
	v_ashrrev_i32_e32 v81, 31, v80
	v_lshlrev_b64 v[86:87], 7, v[80:81]
	v_lshl_add_u64 v[86:87], v[152:153], 0, v[86:87]
	s_waitcnt lgkmcnt(0)
	v_add_f32_e32 v84, v84, v85
	v_fmamk_f32 v84, v84, 0x3a000000, v174
	v_rsq_f32_e32 v84, v84
	s_nop 0
	v_pk_fma_f32 v[76:77], v[76:77], v[84:85], v[108:109] op_sel_hi:[1,0,1]
	v_pk_fma_f32 v[78:79], v[78:79], v[84:85], v[110:111] op_sel_hi:[1,0,1]
	v_pk_fma_f32 v[72:73], v[72:73], v[84:85], v[104:105] op_sel_hi:[1,0,1]
	v_pk_fma_f32 v[74:75], v[74:75], v[84:85], v[106:107] op_sel_hi:[1,0,1]
	v_pk_fma_f32 v[64:65], v[64:65], v[84:85], v[120:121] op_sel_hi:[1,0,1]
	v_pk_fma_f32 v[66:67], v[66:67], v[84:85], v[122:123] op_sel_hi:[1,0,1]
	v_pk_fma_f32 v[68:69], v[68:69], v[84:85], v[124:125] op_sel_hi:[1,0,1]
	v_pk_fma_f32 v[70:71], v[70:71], v[84:85], v[126:127] op_sel_hi:[1,0,1]
	v_pk_mul_f32 v[78:79], v[164:165], v[78:79] op_sel_hi:[0,1]
	v_pk_mul_f32 v[76:77], v[164:165], v[76:77] op_sel_hi:[0,1]
	v_pk_mul_f32 v[74:75], v[164:165], v[74:75] op_sel_hi:[0,1]
	v_pk_mul_f32 v[72:73], v[164:165], v[72:73] op_sel_hi:[0,1]
	v_pk_mul_f32 v[84:85], v[164:165], v[66:67] op_sel_hi:[0,1]
	v_pk_mul_f32 v[88:89], v[164:165], v[64:65] op_sel_hi:[0,1]
	v_cvt_pk_bf16_f32 v64, v76, v77
	v_cvt_pk_bf16_f32 v65, v78, v79
	v_cvt_pk_bf16_f32 v66, v72, v73
	v_cvt_pk_bf16_f32 v67, v74, v75
	v_pk_mul_f32 v[70:71], v[164:165], v[70:71] op_sel_hi:[0,1]
	v_pk_mul_f32 v[68:69], v[164:165], v[68:69] op_sel_hi:[0,1]
	global_store_dwordx4 v[82:83], v[64:67], off sc1
	s_nop 1
	v_cvt_pk_bf16_f32 v64, v68, v69
	v_cvt_pk_bf16_f32 v65, v70, v71
	v_cvt_pk_bf16_f32 v66, v88, v89
	v_cvt_pk_bf16_f32 v67, v84, v85
	global_store_dwordx4 v[82:83], v[64:67], off offset:256 sc1
	global_load_dwordx4 v[64:67], v[86:87], off
	s_nop 0
	global_load_dwordx4 v[68:71], v[86:87], off offset:64
	s_waitcnt vmcnt(1)
	v_mov_b32_e32 v72, v64
	s_waitcnt vmcnt(0)
	v_mov_b32_e32 v73, v68
	v_mov_b32_e32 v68, v65
	v_mov_b32_e32 v64, v66
	v_mov_b32_e32 v65, v70
	v_mov_b32_e32 v70, v67
	v_pk_add_f32 v[66:67], v[72:73], v[68:69]
	v_pk_add_f32 v[64:65], v[64:65], v[70:71]
	s_nop 0
	v_pk_add_f32 v[64:65], v[66:67], v[64:65]
	v_lshlrev_b64 v[66:67], 12, v[80:81]
	v_add_f32_e32 v64, 0, v64
	v_add_f32_e32 v64, v64, v65
	ds_bpermute_b32 v65, v176, v64
	v_lshl_add_u64 v[66:67], v[166:167], 0, v[66:67]
	s_waitcnt lgkmcnt(0)
	v_add_f32_e32 v68, v64, v65
	ds_bpermute_b32 v69, v163, v68
	v_add_u32_e32 v64, 0x90, v162
	v_ashrrev_i32_e32 v65, 31, v64
	v_lshlrev_b64 v[70:71], 7, v[64:65]
	v_lshl_add_u64 v[70:71], v[152:153], 0, v[70:71]
	s_waitcnt lgkmcnt(0)
; __device__ __forceinline__ unsigned cvt_pk_bf16(float lo, float hi) { unsigned r; asm volatile("v_cvt_pk_bf16_f32 %0, %1, %2" : "=v"(r) : "v"(lo), "v"(hi)); return r; }
; __device__ __forceinline__ float row_ss(const float* part, int row, int fq, int nf4) {
;     const f32x4* p = (const f32x4*)(part + (size_t)row * 32);
;     float s = 0.f;
; #pragma unroll
;     for (int j = 0; j < 2; ++j) { const int idx = fq + 4 * j; if (idx < nf4) { const f32x4 v = p[idx]; s += (v[0] + v[1]) + (v[2] + v[3]); } }
;     s += __shfl_xor(s, 16); s += __shfl_xor(s, 32);
;     return s;
;     __device__ __forceinline__ void operator()(const f32x4 (&acc)[2][2][4][2], const Unit& u, int wr, int wc, int fr, int fq) const {
;     ...
;             for (int m = 0; m < 4; ++m) { const int row = row0 + ai * HALF + m * 16; bf16_t* rowp = base + (size_t)row * ldc + col0;
;                 const float rs = rss ? __builtin_amdgcn_rsqf(row_ss(rss, row, fq, nf4) * rinv + 1e-6f) : 1.f;
; #pragma unroll
;                 for (int bj = 0; bj < 2; ++bj) { f32x4 v0 = acc[ai][bj][m][0] * rs + bv[bj][0], v1 = acc[ai][bj][m][1] * rs + bv[bj][1];
;                     v0 = v0 * sc; v1 = v1 * sc; u32x4 w; w.x = cvt_pk_bf16(v0[0], v0[1]); w.y = cvt_pk_bf16(v0[2], v0[3]); w.z = cvt_pk_bf16(v1[0], v1[1]); w.w = cvt_pk_bf16(v1[2], v1[3]);
;                     *(u32x4*)(rowp + bj * HALF) = w; } }
	v_add_f32_e32 v68, v68, v69
	v_fmamk_f32 v68, v68, 0x3a000000, v174
	v_rsq_f32_e32 v68, v68
	s_nop 0
	v_pk_fma_f32 v[60:61], v[60:61], v[68:69], v[108:109] op_sel_hi:[1,0,1]
	v_pk_fma_f32 v[62:63], v[62:63], v[68:69], v[110:111] op_sel_hi:[1,0,1]
	v_pk_fma_f32 v[56:57], v[56:57], v[68:69], v[104:105] op_sel_hi:[1,0,1]
	v_pk_fma_f32 v[58:59], v[58:59], v[68:69], v[106:107] op_sel_hi:[1,0,1]
	v_pk_fma_f32 v[48:49], v[48:49], v[68:69], v[120:121] op_sel_hi:[1,0,1]
	v_pk_fma_f32 v[50:51], v[50:51], v[68:69], v[122:123] op_sel_hi:[1,0,1]
	v_pk_fma_f32 v[52:53], v[52:53], v[68:69], v[124:125] op_sel_hi:[1,0,1]
	v_pk_fma_f32 v[54:55], v[54:55], v[68:69], v[126:127] op_sel_hi:[1,0,1]
	v_pk_mul_f32 v[62:63], v[164:165], v[62:63] op_sel_hi:[0,1]
	v_pk_mul_f32 v[60:61], v[164:165], v[60:61] op_sel_hi:[0,1]
	v_pk_mul_f32 v[58:59], v[164:165], v[58:59] op_sel_hi:[0,1]
	v_pk_mul_f32 v[56:57], v[164:165], v[56:57] op_sel_hi:[0,1]
	v_pk_mul_f32 v[68:69], v[164:165], v[50:51] op_sel_hi:[0,1]
	v_pk_mul_f32 v[72:73], v[164:165], v[48:49] op_sel_hi:[0,1]
	v_cvt_pk_bf16_f32 v48, v60, v61
	v_cvt_pk_bf16_f32 v49, v62, v63
	v_cvt_pk_bf16_f32 v50, v56, v57
	v_cvt_pk_bf16_f32 v51, v58, v59
	v_pk_mul_f32 v[54:55], v[164:165], v[54:55] op_sel_hi:[0,1]
	v_pk_mul_f32 v[52:53], v[164:165], v[52:53] op_sel_hi:[0,1]
	global_store_dwordx4 v[66:67], v[48:51], off sc1
	s_nop 1
	v_cvt_pk_bf16_f32 v48, v52, v53
	v_cvt_pk_bf16_f32 v49, v54, v55
	v_cvt_pk_bf16_f32 v50, v72, v73
	v_cvt_pk_bf16_f32 v51, v68, v69
	global_store_dwordx4 v[66:67], v[48:51], off offset:256 sc1
	global_load_dwordx4 v[48:51], v[70:71], off
	s_nop 0
	global_load_dwordx4 v[52:55], v[70:71], off offset:64
	s_waitcnt vmcnt(1)
	v_mov_b32_e32 v56, v48
	s_waitcnt vmcnt(0)
	v_mov_b32_e32 v57, v52
	v_mov_b32_e32 v52, v49
	v_mov_b32_e32 v48, v50
	v_mov_b32_e32 v49, v54
	v_mov_b32_e32 v54, v51
	v_pk_add_f32 v[50:51], v[56:57], v[52:53]
	v_pk_add_f32 v[48:49], v[48:49], v[54:55]
	s_nop 0
	v_pk_add_f32 v[48:49], v[50:51], v[48:49]
	v_lshlrev_b64 v[50:51], 12, v[64:65]
	v_add_f32_e32 v48, 0, v48
	v_add_f32_e32 v48, v48, v49
	ds_bpermute_b32 v49, v176, v48
	v_lshl_add_u64 v[50:51], v[166:167], 0, v[50:51]
	s_waitcnt lgkmcnt(0)
	v_add_f32_e32 v52, v48, v49
	ds_bpermute_b32 v53, v163, v52
	v_add_u32_e32 v48, 0xa0, v162
	v_ashrrev_i32_e32 v49, 31, v48
	v_lshlrev_b64 v[54:55], 7, v[48:49]
	v_lshl_add_u64 v[54:55], v[152:153], 0, v[54:55]
	s_waitcnt lgkmcnt(0)
	v_add_f32_e32 v52, v52, v53
	v_fmamk_f32 v52, v52, 0x3a000000, v174
	v_rsq_f32_e32 v52, v52
	s_nop 0
	v_pk_fma_f32 v[44:45], v[44:45], v[52:53], v[108:109] op_sel_hi:[1,0,1]
	v_pk_fma_f32 v[46:47], v[46:47], v[52:53], v[110:111] op_sel_hi:[1,0,1]
	v_pk_fma_f32 v[40:41], v[40:41], v[52:53], v[104:105] op_sel_hi:[1,0,1]
	v_pk_fma_f32 v[42:43], v[42:43], v[52:53], v[106:107] op_sel_hi:[1,0,1]
	v_pk_fma_f32 v[32:33], v[32:33], v[52:53], v[120:121] op_sel_hi:[1,0,1]
	v_pk_fma_f32 v[34:35], v[34:35], v[52:53], v[122:123] op_sel_hi:[1,0,1]
	v_pk_fma_f32 v[36:37], v[36:37], v[52:53], v[124:125] op_sel_hi:[1,0,1]
	v_pk_fma_f32 v[38:39], v[38:39], v[52:53], v[126:127] op_sel_hi:[1,0,1]
	v_pk_mul_f32 v[46:47], v[164:165], v[46:47] op_sel_hi:[0,1]
	v_pk_mul_f32 v[44:45], v[164:165], v[44:45] op_sel_hi:[0,1]
	v_pk_mul_f32 v[42:43], v[164:165], v[42:43] op_sel_hi:[0,1]
	v_pk_mul_f32 v[40:41], v[164:165], v[40:41] op_sel_hi:[0,1]
	v_pk_mul_f32 v[52:53], v[164:165], v[34:35] op_sel_hi:[0,1]
	v_pk_mul_f32 v[56:57], v[164:165], v[32:33] op_sel_hi:[0,1]
	v_cvt_pk_bf16_f32 v32, v44, v45
	v_cvt_pk_bf16_f32 v33, v46, v47
	v_cvt_pk_bf16_f32 v34, v40, v41
	v_cvt_pk_bf16_f32 v35, v42, v43
	v_pk_mul_f32 v[38:39], v[164:165], v[38:39] op_sel_hi:[0,1]
	v_pk_mul_f32 v[36:37], v[164:165], v[36:37] op_sel_hi:[0,1]
	global_store_dwordx4 v[50:51], v[32:35], off sc1
	s_nop 1
	v_cvt_pk_bf16_f32 v32, v36, v37
	v_cvt_pk_bf16_f32 v33, v38, v39
	v_cvt_pk_bf16_f32 v34, v56, v57
	v_cvt_pk_bf16_f32 v35, v52, v53
	global_store_dwordx4 v[50:51], v[32:35], off offset:256 sc1
	global_load_dwordx4 v[32:35], v[54:55], off
	s_nop 0
	global_load_dwordx4 v[36:39], v[54:55], off offset:64
	s_waitcnt vmcnt(1)
	v_mov_b32_e32 v40, v32
	s_waitcnt vmcnt(0)
; __device__ __forceinline__ unsigned cvt_pk_bf16(float lo, float hi) { unsigned r; asm volatile("v_cvt_pk_bf16_f32 %0, %1, %2" : "=v"(r) : "v"(lo), "v"(hi)); return r; }
; #define PG8_BAR __builtin_amdgcn_s_barrier()
;     __device__ __forceinline__ void operator()(const f32x4 (&acc)[2][2][4][2], const Unit& u, int wr, int wc, int fr, int fq) const {
;     ...
;             for (int m = 0; m < 4; ++m) { const int row = row0 + ai * HALF + m * 16; bf16_t* rowp = base + (size_t)row * ldc + col0;
;                 const float rs = rss ? __builtin_amdgcn_rsqf(row_ss(rss, row, fq, nf4) * rinv + 1e-6f) : 1.f;
; #pragma unroll
;                 for (int bj = 0; bj < 2; ++bj) { f32x4 v0 = acc[ai][bj][m][0] * rs + bv[bj][0], v1 = acc[ai][bj][m][1] * rs + bv[bj][1];
;                     v0 = v0 * sc; v1 = v1 * sc; u32x4 w; w.x = cvt_pk_bf16(v0[0], v0[1]); w.y = cvt_pk_bf16(v0[2], v0[3]); w.z = cvt_pk_bf16(v1[0], v1[1]); w.w = cvt_pk_bf16(v1[2], v1[3]);
;                     *(u32x4*)(rowp + bj * HALF) = w; } }
; template <class Epi, class Sched, bool ALIGN_EPI = false, bool SP2 = false>
; __device__ __forceinline__ void gemm_phase(PG8_LAS unsigned char* lds, const Gemm g, const Sched& S, const Epi& E) {
;     ...
;         if constexpr (ALIGN_EPI) { if (wr == 0) PG8_BAR; }
;         if constexpr (!Epi::AFTER_DRAIN) { E(acc, cur, wr, wc, fr, fq); S.done(cur); }
;         if (!has_next) break;
; #pragma unroll
;         for (int a = 0; a < 2; ++a)
; #pragma unroll
;             for (int b = 0; b < 2; ++b)
; #pragma unroll
;                 for (int m = 0; m < 4; ++m)
; #pragma unroll
;                     for (int n = 0; n < 2; ++n) acc[a][b][m][n] = (f32x4){0.f, 0.f, 0.f, 0.f};
;         cur = nxt; cA = nA; cB = nB; ++ui;
;         if constexpr (ALIGN_EPI) { if (wr == 1) PG8_BAR; }
	v_mov_b32_e32 v41, v36
	v_mov_b32_e32 v36, v33
	v_mov_b32_e32 v32, v34
	v_mov_b32_e32 v33, v38
	v_mov_b32_e32 v38, v35
	v_pk_add_f32 v[34:35], v[40:41], v[36:37]
	v_pk_add_f32 v[32:33], v[32:33], v[38:39]
	s_nop 0
	v_pk_add_f32 v[32:33], v[34:35], v[32:33]
	v_lshlrev_b64 v[34:35], 12, v[48:49]
	v_add_f32_e32 v32, 0, v32
	v_add_f32_e32 v32, v32, v33
	ds_bpermute_b32 v33, v176, v32
	v_lshl_add_u64 v[34:35], v[166:167], 0, v[34:35]
	s_waitcnt lgkmcnt(0)
	v_add_f32_e32 v36, v32, v33
	ds_bpermute_b32 v37, v163, v36
	v_add_u32_e32 v32, 0xb0, v162
	v_ashrrev_i32_e32 v33, 31, v32
	v_lshlrev_b64 v[38:39], 7, v[32:33]
	v_lshl_add_u64 v[38:39], v[152:153], 0, v[38:39]
	s_waitcnt lgkmcnt(0)
	v_add_f32_e32 v36, v36, v37
	v_fmamk_f32 v36, v36, 0x3a000000, v174
	v_rsq_f32_e32 v36, v36
	s_nop 0
	v_pk_fma_f32 v[28:29], v[28:29], v[36:37], v[108:109] op_sel_hi:[1,0,1]
	v_pk_fma_f32 v[30:31], v[30:31], v[36:37], v[110:111] op_sel_hi:[1,0,1]
	v_pk_fma_f32 v[24:25], v[24:25], v[36:37], v[104:105] op_sel_hi:[1,0,1]
	v_pk_fma_f32 v[26:27], v[26:27], v[36:37], v[106:107] op_sel_hi:[1,0,1]
	v_pk_fma_f32 v[16:17], v[16:17], v[36:37], v[120:121] op_sel_hi:[1,0,1]
	v_pk_fma_f32 v[18:19], v[18:19], v[36:37], v[122:123] op_sel_hi:[1,0,1]
	v_pk_fma_f32 v[20:21], v[20:21], v[36:37], v[124:125] op_sel_hi:[1,0,1]
	v_pk_fma_f32 v[22:23], v[22:23], v[36:37], v[126:127] op_sel_hi:[1,0,1]
	v_pk_mul_f32 v[30:31], v[164:165], v[30:31] op_sel_hi:[0,1]
	v_pk_mul_f32 v[28:29], v[164:165], v[28:29] op_sel_hi:[0,1]
	v_pk_mul_f32 v[26:27], v[164:165], v[26:27] op_sel_hi:[0,1]
	v_pk_mul_f32 v[24:25], v[164:165], v[24:25] op_sel_hi:[0,1]
	v_pk_mul_f32 v[36:37], v[164:165], v[18:19] op_sel_hi:[0,1]
	v_pk_mul_f32 v[40:41], v[164:165], v[16:17] op_sel_hi:[0,1]
	v_cvt_pk_bf16_f32 v16, v28, v29
	v_cvt_pk_bf16_f32 v17, v30, v31
	v_cvt_pk_bf16_f32 v18, v24, v25
	v_cvt_pk_bf16_f32 v19, v26, v27
	v_pk_mul_f32 v[22:23], v[164:165], v[22:23] op_sel_hi:[0,1]
	v_pk_mul_f32 v[20:21], v[164:165], v[20:21] op_sel_hi:[0,1]
	global_store_dwordx4 v[34:35], v[16:19], off sc1
	s_nop 1
	v_cvt_pk_bf16_f32 v16, v20, v21
	v_cvt_pk_bf16_f32 v17, v22, v23
	v_cvt_pk_bf16_f32 v18, v40, v41
	v_cvt_pk_bf16_f32 v19, v36, v37
	global_store_dwordx4 v[34:35], v[16:19], off offset:256 sc1
	global_load_dwordx4 v[16:19], v[38:39], off
	s_nop 0
	global_load_dwordx4 v[20:23], v[38:39], off offset:64
	s_waitcnt vmcnt(1)
	v_mov_b32_e32 v24, v16
	s_waitcnt vmcnt(0)
	v_mov_b32_e32 v25, v20
	v_mov_b32_e32 v20, v17
	v_mov_b32_e32 v16, v18
	v_mov_b32_e32 v17, v22
	v_mov_b32_e32 v22, v19
	v_pk_add_f32 v[18:19], v[24:25], v[20:21]
	v_pk_add_f32 v[16:17], v[16:17], v[22:23]
	s_nop 0
	v_pk_add_f32 v[16:17], v[18:19], v[16:17]
	v_lshlrev_b64 v[18:19], 12, v[32:33]
	v_add_f32_e32 v16, 0, v16
	v_add_f32_e32 v16, v16, v17
	ds_bpermute_b32 v17, v176, v16
	v_lshl_add_u64 v[18:19], v[166:167], 0, v[18:19]
	s_waitcnt lgkmcnt(0)
	v_add_f32_e32 v16, v16, v17
	ds_bpermute_b32 v17, v163, v16
	s_waitcnt lgkmcnt(0)
	v_add_f32_e32 v16, v16, v17
	v_fmamk_f32 v16, v16, 0x3a000000, v174
	v_rsq_f32_e32 v16, v16
	s_nop 0
	v_pk_fma_f32 v[12:13], v[12:13], v[16:17], v[108:109] op_sel_hi:[1,0,1]
	v_pk_fma_f32 v[14:15], v[14:15], v[16:17], v[110:111] op_sel_hi:[1,0,1]
	v_pk_fma_f32 v[8:9], v[8:9], v[16:17], v[104:105] op_sel_hi:[1,0,1]
	v_pk_fma_f32 v[10:11], v[10:11], v[16:17], v[106:107] op_sel_hi:[1,0,1]
	v_pk_fma_f32 v[0:1], v[0:1], v[16:17], v[120:121] op_sel_hi:[1,0,1]
	v_pk_fma_f32 v[2:3], v[2:3], v[16:17], v[122:123] op_sel_hi:[1,0,1]
	v_pk_fma_f32 v[4:5], v[4:5], v[16:17], v[124:125] op_sel_hi:[1,0,1]
	v_pk_fma_f32 v[6:7], v[6:7], v[16:17], v[126:127] op_sel_hi:[1,0,1]
	v_pk_mul_f32 v[14:15], v[164:165], v[14:15] op_sel_hi:[0,1]
	v_pk_mul_f32 v[12:13], v[164:165], v[12:13] op_sel_hi:[0,1]
	v_pk_mul_f32 v[10:11], v[164:165], v[10:11] op_sel_hi:[0,1]
	v_pk_mul_f32 v[8:9], v[164:165], v[8:9] op_sel_hi:[0,1]
	v_pk_mul_f32 v[16:17], v[164:165], v[2:3] op_sel_hi:[0,1]
	v_pk_mul_f32 v[20:21], v[164:165], v[0:1] op_sel_hi:[0,1]
	v_cvt_pk_bf16_f32 v0, v12, v13
	v_cvt_pk_bf16_f32 v1, v14, v15
	v_cvt_pk_bf16_f32 v2, v8, v9
	v_cvt_pk_bf16_f32 v3, v10, v11
	v_pk_mul_f32 v[6:7], v[164:165], v[6:7] op_sel_hi:[0,1]
	v_pk_mul_f32 v[4:5], v[164:165], v[4:5] op_sel_hi:[0,1]
	global_store_dwordx4 v[18:19], v[0:3], off sc1
	s_nop 1
	v_cvt_pk_bf16_f32 v0, v4, v5
	v_cvt_pk_bf16_f32 v1, v6, v7
	v_cvt_pk_bf16_f32 v2, v20, v21
	v_cvt_pk_bf16_f32 v3, v16, v17
	global_store_dwordx4 v[18:19], v[0:3], off offset:256 sc1
	s_cbranch_vccnz .LBB0_1378
	s_andn2_b64 vcc, exec, s[8:9]
	s_cbranch_vccnz .LBB0_1377
	s_barrier
	s_branch .LBB0_1377

; #define LAS __attribute__((address_space(3)))
; __device__ __forceinline__ unsigned cvtpk(float lo, float hi) { f32x2 v = {lo, hi}; bf16x2_t b = __builtin_convertvector(v, bf16x2_t); return __builtin_bit_cast(unsigned, b); }
; __device__ __forceinline__ void witem_store(const WItem& w, int K, bf16_t* WT, int kvperm, LAS float* scr, int item, int nblk, int lane) {
;     ...
;     for (int i = 0; i < 8; ++i) { LAS float* d = scr + (8 * i + rr) * 33 + col; const float g = w.g[i]; d[0] = w.v[i].x * g; d[1] = w.v[i].y * g; d[2] = w.v[i].z * g; d[3] = w.v[i].w * g; }
;     asm volatile("s_waitcnt lgkmcnt(0)" ::: "memory");
;     const int c = lane & 7;
; #pragma unroll
;     for (int j = 0; j < 4; ++j) { const int n = (lane >> 3) + 8 * j; const LAS float* s = scr + (8 * c) * 33 + n;
;         u32x4 o; o.x = cvtpk(s[0 * 33], s[1 * 33]); o.y = cvtpk(s[2 * 33], s[3 * 33]); o.z = cvtpk(s[4 * 33], s[5 * 33]); o.w = cvtpk(s[6 * 33], s[7 * 33]);
;         int nr = n0 + n; if (kvperm == 1) { const int hh = nr >> 8, ww = nr & 255; nr = (ww < 128) ? hh * 128 + ww : 2048 + hh * 128 + (ww - 128); }
;         else if (kvperm == 2) { const int isv = nr >= 5632, f = isv ? nr - 5632 : nr; nr = (f >> 7) * 256 + isv * 128 + (f & 127); }
;         *(u32x4*)(WT + (size_t)nr * K + k0 + 8 * c) = o; }
.LBB0_1417:
	ds_write2_b32 v84, v4, v5 offset1:1
	ds_write2_b32 v84, v6, v7 offset0:2 offset1:3
	v_add_u32_e32 v4, 0x420, v84
	ds_write2_b32 v4, v0, v1 offset1:1
	v_add_u32_e32 v0, 0x428, v84
	ds_write2_b32 v0, v2, v3 offset1:1
	v_add_u32_e32 v0, 0x840, v84
	ds_write2_b32 v0, v12, v13 offset1:1
	v_add_u32_e32 v0, 0x848, v84
	ds_write2_b32 v0, v14, v15 offset1:1
	v_add_u32_e32 v0, 0xc60, v84
	ds_write2_b32 v0, v8, v9 offset1:1
	v_add_u32_e32 v0, 0xc68, v84
	ds_write2_b32 v0, v10, v11 offset1:1
	v_add_u32_e32 v0, 0x1080, v84
	ds_write2_b32 v0, v24, v25 offset1:1
	v_add_u32_e32 v0, 0x1088, v84
	ds_write2_b32 v0, v26, v27 offset1:1
	v_add_u32_e32 v0, 0x14a0, v84
	ds_write2_b32 v0, v16, v17 offset1:1
	v_add_u32_e32 v0, 0x14a8, v84
	ds_write2_b32 v0, v18, v19 offset1:1
	v_add_u32_e32 v0, 0x18c0, v84
	ds_write2_b32 v0, v36, v37 offset1:1
	v_add_u32_e32 v0, 0x18c8, v84
	ds_write2_b32 v0, v38, v39 offset1:1
	v_add_u32_e32 v0, 0x1ce0, v84
	ds_write2_b32 v0, v40, v41 offset1:1
	v_add_u32_e32 v0, 0x1ce8, v84
	s_ashr_i32 s12, s14, 31
	ds_write2_b32 v0, v42, v43 offset1:1
	s_lshr_b32 s12, s12, 26
	s_waitcnt lgkmcnt(0)
	s_add_i32 s12, s14, s12
	ds_read2_b32 v[4:5], v80 offset0:33 offset1:41
	ds_read2_b32 v[6:7], v80 offset1:8
	ds_read2_b32 v[8:9], v80 offset0:66 offset1:74
	ds_read2_b32 v[10:11], v80 offset0:99 offset1:107
	ds_read2_b32 v[12:13], v80 offset0:132 offset1:140
	ds_read2_b32 v[14:15], v80 offset0:165 offset1:173
	ds_read2_b32 v[16:17], v80 offset0:198 offset1:206
	ds_read2_b32 v[18:19], v80 offset0:231 offset1:239
	s_lshr_b32 s14, s12, 6
	s_andn2_b32 s12, s12, 63
	s_mul_i32 s14, s14, 0xff500000
	s_ashr_i32 s13, s12, 31
	v_add_u32_e32 v24, s14, v82
	v_lshl_add_u64 v[22:23], s[12:13], 1, v[70:71]
	v_ashrrev_i32_e32 v25, 31, v24
	s_waitcnt lgkmcnt(6)
	v_cvt_pk_bf16_f32 v0, v6, v4
	s_waitcnt lgkmcnt(4)
	v_cvt_pk_bf16_f32 v1, v8, v10
	s_waitcnt lgkmcnt(2)
	v_cvt_pk_bf16_f32 v2, v12, v14
	s_waitcnt lgkmcnt(0)
	v_cvt_pk_bf16_f32 v3, v16, v18
	v_lshl_add_u64 v[26:27], v[24:25], 1, v[22:23]
	global_store_dwordx4 v[26:27], v[0:3], off sc1
	v_add_u32_e32 v4, 0xb000, v24
	s_waitcnt vmcnt(1)
	v_mov_b64_e32 v[36:37], v[60:61]
	v_cvt_pk_bf16_f32 v0, v7, v5
	v_cvt_pk_bf16_f32 v1, v9, v11
	v_cvt_pk_bf16_f32 v2, v13, v15
	v_cvt_pk_bf16_f32 v3, v17, v19
	ds_read2_b32 v[6:7], v80 offset0:49 offset1:57
	ds_read2_b32 v[8:9], v80 offset0:16 offset1:24
	ds_read2_b32 v[10:11], v80 offset0:82 offset1:90
	ds_read2_b32 v[12:13], v80 offset0:115 offset1:123
	ds_read2_b32 v[14:15], v80 offset0:148 offset1:156
	ds_read2_b32 v[16:17], v80 offset0:181 offset1:189
	ds_read2_b32 v[18:19], v80 offset0:214 offset1:222
	ds_read2_b32 v[26:27], v80 offset0:247 offset1:255
	v_ashrrev_i32_e32 v5, 31, v4
	v_lshl_add_u64 v[4:5], v[4:5], 1, v[22:23]
	global_store_dwordx4 v[4:5], v[0:3], off sc1
	v_add_u32_e32 v4, 0x16000, v24
	v_ashrrev_i32_e32 v5, 31, v4
	s_waitcnt lgkmcnt(6)
	v_cvt_pk_bf16_f32 v0, v8, v6
	s_waitcnt lgkmcnt(4)
	v_cvt_pk_bf16_f32 v1, v10, v12
	s_waitcnt lgkmcnt(2)
	v_cvt_pk_bf16_f32 v2, v14, v16
	s_waitcnt lgkmcnt(0)
	v_cvt_pk_bf16_f32 v3, v18, v26
	v_lshl_add_u64 v[4:5], v[4:5], 1, v[22:23]
	global_store_dwordx4 v[4:5], v[0:3], off sc1
	v_add_u32_e32 v4, 0x21000, v24
	v_ashrrev_i32_e32 v5, 31, v4
	v_cvt_pk_bf16_f32 v0, v9, v7
	v_cvt_pk_bf16_f32 v1, v11, v13
	v_cvt_pk_bf16_f32 v2, v15, v17
	v_cvt_pk_bf16_f32 v3, v19, v27
	v_lshl_add_u64 v[4:5], v[4:5], 1, v[22:23]
	global_store_dwordx4 v[4:5], v[0:3], off sc1
	s_waitcnt lgkmcnt(0)
	v_mov_b64_e32 v[4:5], v[32:33]
	v_mov_b64_e32 v[12:13], v[44:45]
	v_mov_b64_e32 v[0:1], v[28:29]
	v_mov_b64_e32 v[8:9], v[48:49]
	v_mov_b64_e32 v[24:25], v[52:53]
	v_mov_b64_e32 v[16:17], v[56:57]
	v_add_u32_e32 v82, s15, v82
	s_add_i32 s16, s16, s17
	s_andn2_b64 vcc, exec, s[10:11]
	s_mov_b32 s14, s22
	v_mov_b64_e32 v[6:7], v[34:35]
	v_mov_b64_e32 v[2:3], v[30:31]
	v_mov_b64_e32 v[14:15], v[46:47]
	v_mov_b64_e32 v[10:11], v[50:51]
	v_mov_b64_e32 v[26:27], v[54:55]
	v_mov_b64_e32 v[18:19], v[58:59]
	v_mov_b64_e32 v[38:39], v[62:63]
	v_mov_b32_e32 v40, v64
	v_mov_b32_e32 v41, v65
	v_mov_b32_e32 v42, v66
	v_mov_b32_e32 v43, v67
	s_cbranch_vccz .LBB0_1435

; #define LAS __attribute__((address_space(3)))
; __device__ __forceinline__ unsigned cvtpk(float lo, float hi) { f32x2 v = {lo, hi}; bf16x2_t b = __builtin_convertvector(v, bf16x2_t); return __builtin_bit_cast(unsigned, b); }
; __device__ __forceinline__ void witem_store(const WItem& w, int K, bf16_t* WT, int kvperm, LAS float* scr, int item, int nblk, int lane) {
;     ...
;     for (int i = 0; i < 8; ++i) { LAS float* d = scr + (8 * i + rr) * 33 + col; const float g = w.g[i]; d[0] = w.v[i].x * g; d[1] = w.v[i].y * g; d[2] = w.v[i].z * g; d[3] = w.v[i].w * g; }
;     asm volatile("s_waitcnt lgkmcnt(0)" ::: "memory");
;     const int c = lane & 7;
; #pragma unroll
;     for (int j = 0; j < 4; ++j) { const int n = (lane >> 3) + 8 * j; const LAS float* s = scr + (8 * c) * 33 + n;
;         u32x4 o; o.x = cvtpk(s[0 * 33], s[1 * 33]); o.y = cvtpk(s[2 * 33], s[3 * 33]); o.z = cvtpk(s[4 * 33], s[5 * 33]); o.w = cvtpk(s[6 * 33], s[7 * 33]);
;         int nr = n0 + n; if (kvperm == 1) { const int hh = nr >> 8, ww = nr & 255; nr = (ww < 128) ? hh * 128 + ww : 2048 + hh * 128 + (ww - 128); }
;         else if (kvperm == 2) { const int isv = nr >= 5632, f = isv ? nr - 5632 : nr; nr = (f >> 7) * 256 + isv * 128 + (f & 127); }
;         *(u32x4*)(WT + (size_t)nr * K + k0 + 8 * c) = o; }
.LBB0_1454:
	v_pk_mul_f32 v[2:3], v[8:9], v[72:73] op_sel_hi:[1,0]
	ds_write2_b32 v87, v2, v3 offset1:1
	v_pk_mul_f32 v[2:3], v[10:11], v[72:73] op_sel_hi:[1,0]
	ds_write2_b32 v87, v2, v3 offset0:2 offset1:3
	v_pk_mul_f32 v[2:3], v[4:5], v[74:75] op_sel_hi:[1,0]
	v_add_u32_e32 v4, 0x420, v87
	ds_write2_b32 v4, v2, v3 offset1:1
	v_pk_mul_f32 v[2:3], v[6:7], v[74:75] op_sel_hi:[1,0]
	v_add_u32_e32 v4, 0x428, v87
	ds_write2_b32 v4, v2, v3 offset1:1
	v_pk_mul_f32 v[2:3], v[20:21], v[76:77] op_sel_hi:[1,0]
	v_add_u32_e32 v4, 0x840, v87
	ds_write2_b32 v4, v2, v3 offset1:1
	v_pk_mul_f32 v[2:3], v[22:23], v[76:77] op_sel_hi:[1,0]
	v_add_u32_e32 v4, 0x848, v87
	ds_write2_b32 v4, v2, v3 offset1:1
	v_pk_mul_f32 v[2:3], v[12:13], v[78:79] op_sel_hi:[1,0]
	v_add_u32_e32 v4, 0xc60, v87
	ds_write2_b32 v4, v2, v3 offset1:1
	v_pk_mul_f32 v[2:3], v[14:15], v[78:79] op_sel_hi:[1,0]
	v_add_u32_e32 v4, 0xc68, v87
	ds_write2_b32 v4, v2, v3 offset1:1
	v_pk_mul_f32 v[2:3], v[32:33], v[80:81] op_sel_hi:[1,0]
	v_add_u32_e32 v4, 0x1080, v87
	ds_write2_b32 v4, v2, v3 offset1:1
	v_pk_mul_f32 v[2:3], v[34:35], v[80:81] op_sel_hi:[1,0]
	v_add_u32_e32 v4, 0x1088, v87
	ds_write2_b32 v4, v2, v3 offset1:1
	v_pk_mul_f32 v[2:3], v[28:29], v[82:83] op_sel_hi:[1,0]
	v_add_u32_e32 v4, 0x14a0, v87
	ds_write2_b32 v4, v2, v3 offset1:1
	v_pk_mul_f32 v[2:3], v[30:31], v[82:83] op_sel_hi:[1,0]
	v_add_u32_e32 v4, 0x14a8, v87
	ds_write2_b32 v4, v2, v3 offset1:1
	v_pk_mul_f32 v[2:3], v[44:45], v[84:85] op_sel_hi:[1,0]
	v_add_u32_e32 v4, 0x18c0, v87
	s_mul_hi_i32 s14, s21, 0x2aaaaaab
	ds_write2_b32 v4, v2, v3 offset1:1
	v_pk_mul_f32 v[2:3], v[46:47], v[84:85] op_sel_hi:[1,0]
	v_add_u32_e32 v4, 0x18c8, v87
	s_lshr_b32 s15, s14, 31
	s_ashr_i32 s14, s14, 5
	ds_write2_b32 v4, v2, v3 offset1:1
	v_pk_mul_f32 v[2:3], v[36:37], v[86:87] op_sel_hi:[1,0]
	v_add_u32_e32 v4, 0x1ce0, v87
	s_add_i32 s21, s14, s15
	ds_write2_b32 v4, v2, v3 offset1:1
	v_pk_mul_f32 v[2:3], v[38:39], v[86:87] op_sel_hi:[1,0]
	v_add_u32_e32 v4, 0x1ce8, v87
	s_lshl_b32 s14, s21, 6
	ds_write2_b32 v4, v2, v3 offset1:1
	s_waitcnt lgkmcnt(0)
	s_ashr_i32 s15, s14, 31
	ds_read2_b32 v[6:7], v85 offset0:33 offset1:41
	ds_read2_b32 v[8:9], v85 offset1:8
	ds_read2_b32 v[10:11], v85 offset0:66 offset1:74
	ds_read2_b32 v[12:13], v85 offset0:99 offset1:107
	ds_read2_b32 v[14:15], v85 offset0:132 offset1:140
	ds_read2_b32 v[20:21], v85 offset0:165 offset1:173
	ds_read2_b32 v[22:23], v85 offset0:198 offset1:206
	ds_read2_b32 v[28:29], v85 offset0:231 offset1:239
	v_lshl_add_u64 v[30:31], s[14:15], 1, v[70:71]
	s_mul_i32 s14, s21, 0xffffe800
	s_add_i32 s14, s14, s22
	v_add_u32_e32 v32, s14, v94
	v_ashrrev_i32_e32 v33, 31, v32
	v_lshlrev_b64 v[34:35], 12, v[32:33]
	s_waitcnt lgkmcnt(6)
	v_cvt_pk_bf16_f32 v2, v8, v6
	s_waitcnt lgkmcnt(4)
	v_cvt_pk_bf16_f32 v3, v10, v12
	s_waitcnt lgkmcnt(2)
	v_cvt_pk_bf16_f32 v4, v14, v20
	s_waitcnt lgkmcnt(0)
	v_cvt_pk_bf16_f32 v5, v22, v28
	v_lshl_add_u64 v[34:35], v[30:31], 0, v[34:35]
	v_add_u32_e32 v6, 8, v32
	global_store_dwordx4 v[34:35], v[2:5], off sc1
	s_waitcnt vmcnt(3)
	v_mov_b64_e32 v[44:45], v[60:61]
	s_waitcnt vmcnt(2)
	v_mov_b64_e32 v[36:37], v[64:65]
	v_cvt_pk_bf16_f32 v2, v9, v7
	v_ashrrev_i32_e32 v7, 31, v6
	v_cvt_pk_bf16_f32 v3, v11, v13
	v_cvt_pk_bf16_f32 v4, v15, v21
	v_cvt_pk_bf16_f32 v5, v23, v29
	v_lshlrev_b64 v[6:7], 12, v[6:7]
	ds_read2_b32 v[8:9], v85 offset0:49 offset1:57
	ds_read2_b32 v[10:11], v85 offset0:16 offset1:24
	ds_read2_b32 v[12:13], v85 offset0:82 offset1:90
	ds_read2_b32 v[14:15], v85 offset0:115 offset1:123
	ds_read2_b32 v[20:21], v85 offset0:148 offset1:156
	ds_read2_b32 v[22:23], v85 offset0:181 offset1:189
	ds_read2_b32 v[28:29], v85 offset0:214 offset1:222
	ds_read2_b32 v[34:35], v85 offset0:247 offset1:255
	v_lshl_add_u64 v[6:7], v[30:31], 0, v[6:7]
	global_store_dwordx4 v[6:7], v[2:5], off sc1
	v_add_u32_e32 v6, 16, v32
	v_ashrrev_i32_e32 v7, 31, v6
	v_lshlrev_b64 v[6:7], 12, v[6:7]
	s_waitcnt lgkmcnt(6)
	v_cvt_pk_bf16_f32 v2, v10, v8
	s_waitcnt lgkmcnt(4)
	v_cvt_pk_bf16_f32 v3, v12, v14
	s_waitcnt lgkmcnt(2)
	v_cvt_pk_bf16_f32 v4, v20, v22
	s_waitcnt lgkmcnt(0)
	v_cvt_pk_bf16_f32 v5, v28, v34
	v_lshl_add_u64 v[6:7], v[30:31], 0, v[6:7]
	global_store_dwordx4 v[6:7], v[2:5], off sc1
	v_add_u32_e32 v6, 24, v32
	v_ashrrev_i32_e32 v7, 31, v6
	v_lshlrev_b64 v[6:7], 12, v[6:7]
	v_cvt_pk_bf16_f32 v2, v11, v9
	v_cvt_pk_bf16_f32 v3, v13, v15
	v_cvt_pk_bf16_f32 v4, v21, v23
	v_cvt_pk_bf16_f32 v5, v29, v35
	v_lshl_add_u64 v[6:7], v[30:31], 0, v[6:7]
	global_store_dwordx4 v[6:7], v[2:5], off sc1
	s_waitcnt lgkmcnt(0)
	v_mov_b64_e32 v[8:9], v[24:25]
	v_mov_b64_e32 v[20:21], v[40:41]
	v_mov_b64_e32 v[4:5], v[16:17]
	v_mov_b64_e32 v[12:13], v[48:49]
	v_mov_b64_e32 v[32:33], v[52:53]
	v_mov_b64_e32 v[28:29], v[56:57]
	v_add_u32_e32 v94, s23, v94
	s_add_i32 s27, s27, s23
	v_add_u32_e32 v73, s23, v73
	s_andn2_b64 vcc, exec, s[12:13]
	s_mov_b32 s21, s28
	v_mov_b64_e32 v[10:11], v[26:27]
	v_mov_b64_e32 v[6:7], v[18:19]
	v_mov_b64_e32 v[22:23], v[42:43]
	v_mov_b64_e32 v[14:15], v[50:51]
	v_mov_b64_e32 v[34:35], v[54:55]
	v_mov_b64_e32 v[30:31], v[58:59]
	v_mov_b64_e32 v[46:47], v[62:63]
	v_mov_b64_e32 v[38:39], v[66:67]
	v_mov_b32_e32 v72, v89
	v_mov_b32_e32 v74, v95
	v_mov_b32_e32 v76, v96
	v_mov_b32_e32 v78, v97
	v_mov_b32_e32 v80, v98
	v_mov_b32_e32 v82, v99
	v_mov_b32_e32 v84, v100
	s_waitcnt vmcnt(4)
	v_mov_b32_e32 v86, v1
	s_cbranch_vccz .LBB0_1472

; #define LAS __attribute__((address_space(3)))
; __device__ __forceinline__ unsigned cvtpk(float lo, float hi) { f32x2 v = {lo, hi}; bf16x2_t b = __builtin_convertvector(v, bf16x2_t); return __builtin_bit_cast(unsigned, b); }
; __device__ __forceinline__ void witem_store(const WItem& w, int K, bf16_t* WT, int kvperm, LAS float* scr, int item, int nblk, int lane) {
;     ...
;     for (int i = 0; i < 8; ++i) { LAS float* d = scr + (8 * i + rr) * 33 + col; const float g = w.g[i]; d[0] = w.v[i].x * g; d[1] = w.v[i].y * g; d[2] = w.v[i].z * g; d[3] = w.v[i].w * g; }
;     asm volatile("s_waitcnt lgkmcnt(0)" ::: "memory");
;     const int c = lane & 7;
; #pragma unroll
;     for (int j = 0; j < 4; ++j) { const int n = (lane >> 3) + 8 * j; const LAS float* s = scr + (8 * c) * 33 + n;
;         u32x4 o; o.x = cvtpk(s[0 * 33], s[1 * 33]); o.y = cvtpk(s[2 * 33], s[3 * 33]); o.z = cvtpk(s[4 * 33], s[5 * 33]); o.w = cvtpk(s[6 * 33], s[7 * 33]);
;         int nr = n0 + n; if (kvperm == 1) { const int hh = nr >> 8, ww = nr & 255; nr = (ww < 128) ? hh * 128 + ww : 2048 + hh * 128 + (ww - 128); }
;         else if (kvperm == 2) { const int isv = nr >= 5632, f = isv ? nr - 5632 : nr; nr = (f >> 7) * 256 + isv * 128 + (f & 127); }
;         *(u32x4*)(WT + (size_t)nr * K + k0 + 8 * c) = o; }
.LBB0_1491:
	v_pk_mul_f32 v[2:3], v[16:17], v[72:73] op_sel_hi:[1,0]
	ds_write2_b32 v85, v2, v3 offset1:1
	v_pk_mul_f32 v[2:3], v[18:19], v[72:73] op_sel_hi:[1,0]
	ds_write2_b32 v85, v2, v3 offset0:2 offset1:3
	v_pk_mul_f32 v[2:3], v[4:5], v[74:75] op_sel_hi:[1,0]
	v_add_u32_e32 v4, 0x420, v85
	ds_write2_b32 v4, v2, v3 offset1:1
	v_pk_mul_f32 v[2:3], v[6:7], v[74:75] op_sel_hi:[1,0]
	v_add_u32_e32 v4, 0x428, v85
	ds_write2_b32 v4, v2, v3 offset1:1
	v_pk_mul_f32 v[2:3], v[24:25], v[76:77] op_sel_hi:[1,0]
	v_add_u32_e32 v4, 0x840, v85
	ds_write2_b32 v4, v2, v3 offset1:1
	v_pk_mul_f32 v[2:3], v[26:27], v[76:77] op_sel_hi:[1,0]
	v_add_u32_e32 v4, 0x848, v85
	ds_write2_b32 v4, v2, v3 offset1:1
	v_pk_mul_f32 v[2:3], v[20:21], v[78:79] op_sel_hi:[1,0]
	v_add_u32_e32 v4, 0xc60, v85
	ds_write2_b32 v4, v2, v3 offset1:1
	v_pk_mul_f32 v[2:3], v[22:23], v[78:79] op_sel_hi:[1,0]
	v_add_u32_e32 v4, 0xc68, v85
	ds_write2_b32 v4, v2, v3 offset1:1
	v_pk_mul_f32 v[2:3], v[36:37], v[80:81] op_sel_hi:[1,0]
	v_add_u32_e32 v4, 0x1080, v85
	ds_write2_b32 v4, v2, v3 offset1:1
	v_pk_mul_f32 v[2:3], v[38:39], v[80:81] op_sel_hi:[1,0]
	v_add_u32_e32 v4, 0x1088, v85
	ds_write2_b32 v4, v2, v3 offset1:1
	v_pk_mul_f32 v[2:3], v[32:33], v[82:83] op_sel_hi:[1,0]
	v_add_u32_e32 v4, 0x14a0, v85
	s_mul_hi_i32 s16, s27, 0x2e8ba2e9
	ds_write2_b32 v4, v2, v3 offset1:1
	v_pk_mul_f32 v[2:3], v[34:35], v[82:83] op_sel_hi:[1,0]
	v_add_u32_e32 v4, 0x14a8, v85
	s_lshr_b32 s17, s16, 31
	s_ashr_i32 s16, s16, 6
	ds_write2_b32 v4, v2, v3 offset1:1
	v_pk_mul_f32 v[2:3], v[52:53], v[84:85] op_sel_hi:[1,0]
	v_add_u32_e32 v4, 0x18c0, v85
	s_add_i32 s27, s16, s17
	ds_write2_b32 v4, v2, v3 offset1:1
	v_pk_mul_f32 v[2:3], v[54:55], v[84:85] op_sel_hi:[1,0]
	v_add_u32_e32 v4, 0x18c8, v85
	s_lshl_b32 s16, s27, 6
	ds_write2_b32 v4, v2, v3 offset1:1
	v_pk_mul_f32 v[2:3], v[44:45], v[86:87] op_sel_hi:[1,0]
	v_add_u32_e32 v4, 0x1ce0, v85
	ds_write2_b32 v4, v2, v3 offset1:1
	v_pk_mul_f32 v[2:3], v[46:47], v[86:87] op_sel_hi:[1,0]
	v_add_u32_e32 v4, 0x1ce8, v85
	s_ashr_i32 s17, s16, 31
	ds_write2_b32 v4, v2, v3 offset1:1
	v_lshl_add_u64 v[34:35], s[16:17], 1, v[70:71]
	s_mul_i32 s16, s27, 0xffffd400
	s_waitcnt lgkmcnt(0)
	s_add_i32 s16, s16, s22
	ds_read2_b32 v[6:7], v83 offset0:33 offset1:41
	ds_read2_b32 v[16:17], v83 offset1:8
	ds_read2_b32 v[18:19], v83 offset0:66 offset1:74
	ds_read2_b32 v[20:21], v83 offset0:99 offset1:107
	ds_read2_b32 v[22:23], v83 offset0:132 offset1:140
	ds_read2_b32 v[24:25], v83 offset0:165 offset1:173
	ds_read2_b32 v[26:27], v83 offset0:198 offset1:206
	ds_read2_b32 v[32:33], v83 offset0:231 offset1:239
	v_add_u32_e32 v38, s16, v94
	s_waitcnt lgkmcnt(6)
	v_cvt_pk_bf16_f32 v2, v16, v6
	v_add_u32_e32 v6, 0xffffea00, v38
	v_cmp_lt_i32_e32 vcc, s28, v38
	s_waitcnt lgkmcnt(4)
	v_cvt_pk_bf16_f32 v3, v18, v20
	s_waitcnt lgkmcnt(2)
	v_cvt_pk_bf16_f32 v4, v22, v24
	v_cndmask_b32_e32 v6, v38, v6, vcc
	v_lshlrev_b32_e32 v16, 1, v6
	v_and_b32_e32 v16, 0xffffff00, v16
	v_cndmask_b32_e32 v18, 0, v87, vcc
	v_and_b32_e32 v6, 0x67, v6
	v_or3_b32 v36, v6, v18, v16
	v_ashrrev_i32_e32 v37, 31, v36
	v_lshlrev_b64 v[36:37], 12, v[36:37]
	s_waitcnt lgkmcnt(0)
	v_cvt_pk_bf16_f32 v5, v26, v32
	v_lshl_add_u64 v[36:37], v[34:35], 0, v[36:37]
	v_add_u32_e32 v6, 8, v38
	global_store_dwordx4 v[36:37], v[2:5], off sc1
	v_cmp_lt_i32_e32 vcc, s28, v6
	s_waitcnt vmcnt(3)
	v_mov_b64_e32 v[52:53], v[60:61]
	v_cvt_pk_bf16_f32 v2, v17, v7
	v_add_u32_e32 v7, 0xffffea08, v38
	v_cndmask_b32_e32 v6, v6, v7, vcc
	v_lshlrev_b32_e32 v7, 1, v6
	v_and_b32_e32 v7, 0xffffff00, v7
	v_cndmask_b32_e32 v16, 0, v87, vcc
	v_and_b32_e32 v6, 0x6f, v6
	v_or3_b32 v6, v6, v16, v7
	v_ashrrev_i32_e32 v7, 31, v6
	v_lshlrev_b64 v[6:7], 12, v[6:7]
	v_cvt_pk_bf16_f32 v3, v19, v21
	v_cvt_pk_bf16_f32 v4, v23, v25
	v_cvt_pk_bf16_f32 v5, v27, v33
	v_lshl_add_u64 v[6:7], v[34:35], 0, v[6:7]
	ds_read2_b32 v[16:17], v83 offset0:16 offset1:24
	ds_read2_b32 v[18:19], v83 offset0:49 offset1:57
	ds_read2_b32 v[20:21], v83 offset0:82 offset1:90
	ds_read2_b32 v[22:23], v83 offset0:115 offset1:123
	ds_read2_b32 v[24:25], v83 offset0:148 offset1:156
	ds_read2_b32 v[26:27], v83 offset0:181 offset1:189
	ds_read2_b32 v[32:33], v83 offset0:214 offset1:222
	ds_read2_b32 v[36:37], v83 offset0:247 offset1:255
	global_store_dwordx4 v[6:7], v[2:5], off sc1
	v_add_u32_e32 v6, 16, v38
	v_add_u32_e32 v7, 0xffffea10, v38
	v_cmp_lt_i32_e32 vcc, s28, v6
	s_waitcnt lgkmcnt(6)
	v_cvt_pk_bf16_f32 v2, v16, v18
	s_waitcnt lgkmcnt(4)
	v_cvt_pk_bf16_f32 v3, v20, v22
	v_cndmask_b32_e32 v6, v6, v7, vcc
	v_lshlrev_b32_e32 v7, 1, v6
	v_and_b32_e32 v7, 0xffffff00, v7
	v_cndmask_b32_e32 v16, 0, v87, vcc
	v_and_b32_e32 v6, 0x77, v6
	v_or3_b32 v6, v6, v16, v7
	v_ashrrev_i32_e32 v7, 31, v6
	v_lshlrev_b64 v[6:7], 12, v[6:7]
	s_waitcnt lgkmcnt(2)
	v_cvt_pk_bf16_f32 v4, v24, v26
	s_waitcnt lgkmcnt(0)
	v_cvt_pk_bf16_f32 v5, v32, v36
	v_lshl_add_u64 v[6:7], v[34:35], 0, v[6:7]
	global_store_dwordx4 v[6:7], v[2:5], off sc1
	s_waitcnt vmcnt(4)
	v_mov_b64_e32 v[44:45], v[64:65]
	v_add_u32_e32 v94, s23, v94
	v_add_u32_e32 v2, 24, v38
	v_add_u32_e32 v3, 0xffffea18, v38
	v_cmp_lt_i32_e32 vcc, s28, v2
	v_cvt_pk_bf16_f32 v5, v33, v37
	v_mov_b64_e32 v[36:37], v[48:49]
	v_cndmask_b32_e32 v2, v2, v3, vcc
	v_lshlrev_b32_e32 v3, 1, v2
	v_and_b32_e32 v3, 0xffffff00, v3
	v_cndmask_b32_e32 v4, 0, v87, vcc
	v_and_b32_e32 v2, 0x7f, v2
	v_or3_b32 v6, v2, v4, v3
	v_ashrrev_i32_e32 v7, 31, v6
	v_lshlrev_b64 v[6:7], 12, v[6:7]
	v_cvt_pk_bf16_f32 v2, v17, v19
	v_cvt_pk_bf16_f32 v3, v21, v23
	v_cvt_pk_bf16_f32 v4, v25, v27
	v_lshl_add_u64 v[6:7], v[34:35], 0, v[6:7]
	global_store_dwordx4 v[6:7], v[2:5], off sc1
	s_waitcnt lgkmcnt(0)
	v_mov_b64_e32 v[18:19], v[14:15]
	v_mov_b64_e32 v[24:25], v[28:29]
	v_mov_b64_e32 v[4:5], v[8:9]
	v_mov_b64_e32 v[20:21], v[40:41]
	v_mov_b64_e32 v[32:33], v[56:57]
	s_add_i32 s29, s29, s23
	v_add_u32_e32 v73, s23, v73
	s_andn2_b64 vcc, exec, s[14:15]
	s_mov_b32 s27, s30
	v_mov_b64_e32 v[16:17], v[12:13]
	v_mov_b64_e32 v[6:7], v[10:11]
	v_mov_b64_e32 v[26:27], v[30:31]
	v_mov_b64_e32 v[22:23], v[42:43]
	v_mov_b64_e32 v[38:39], v[50:51]
	v_mov_b64_e32 v[34:35], v[58:59]
	v_mov_b64_e32 v[54:55], v[62:63]
	v_mov_b64_e32 v[46:47], v[66:67]
	v_mov_b32_e32 v72, v89
	v_mov_b32_e32 v74, v95
	v_mov_b32_e32 v76, v96
	v_mov_b32_e32 v78, v97
	v_mov_b32_e32 v80, v98
	v_mov_b32_e32 v82, v99
	v_mov_b32_e32 v84, v100
	s_waitcnt vmcnt(4)
	v_mov_b32_e32 v86, v1
	s_cbranch_vccz .LBB0_1509

; #define LAS __attribute__((address_space(3)))
; __device__ __forceinline__ unsigned cvtpk(float lo, float hi) { f32x2 v = {lo, hi}; bf16x2_t b = __builtin_convertvector(v, bf16x2_t); return __builtin_bit_cast(unsigned, b); }
; __device__ __forceinline__ void witem_store(const WItem& w, int K, bf16_t* WT, int kvperm, LAS float* scr, int item, int nblk, int lane) {
;     ...
;     for (int i = 0; i < 8; ++i) { LAS float* d = scr + (8 * i + rr) * 33 + col; const float g = w.g[i]; d[0] = w.v[i].x * g; d[1] = w.v[i].y * g; d[2] = w.v[i].z * g; d[3] = w.v[i].w * g; }
;     asm volatile("s_waitcnt lgkmcnt(0)" ::: "memory");
;     const int c = lane & 7;
; #pragma unroll
;     for (int j = 0; j < 4; ++j) { const int n = (lane >> 3) + 8 * j; const LAS float* s = scr + (8 * c) * 33 + n;
;         u32x4 o; o.x = cvtpk(s[0 * 33], s[1 * 33]); o.y = cvtpk(s[2 * 33], s[3 * 33]); o.z = cvtpk(s[4 * 33], s[5 * 33]); o.w = cvtpk(s[6 * 33], s[7 * 33]);
;         int nr = n0 + n; if (kvperm == 1) { const int hh = nr >> 8, ww = nr & 255; nr = (ww < 128) ? hh * 128 + ww : 2048 + hh * 128 + (ww - 128); }
;         else if (kvperm == 2) { const int isv = nr >= 5632, f = isv ? nr - 5632 : nr; nr = (f >> 7) * 256 + isv * 128 + (f & 127); }
;         *(u32x4*)(WT + (size_t)nr * K + k0 + 8 * c) = o; }
.LBB0_1528:
	v_pk_mul_f32 v[2:3], v[16:17], v[72:73] op_sel_hi:[1,0]
	ds_write2_b32 v79, v2, v3 offset1:1
	v_pk_mul_f32 v[2:3], v[18:19], v[72:73] op_sel_hi:[1,0]
	ds_write2_b32 v79, v2, v3 offset0:2 offset1:3
	v_pk_mul_f32 v[2:3], v[4:5], v[74:75] op_sel_hi:[1,0]
	v_add_u32_e32 v4, 0x420, v79
	ds_write2_b32 v4, v2, v3 offset1:1
	v_pk_mul_f32 v[2:3], v[6:7], v[74:75] op_sel_hi:[1,0]
	v_add_u32_e32 v4, 0x428, v79
	ds_write2_b32 v4, v2, v3 offset1:1
	v_pk_mul_f32 v[2:3], v[24:25], v[76:77] op_sel_hi:[1,0]
	v_add_u32_e32 v4, 0x840, v79
	ds_write2_b32 v4, v2, v3 offset1:1
	v_pk_mul_f32 v[2:3], v[26:27], v[76:77] op_sel_hi:[1,0]
	v_add_u32_e32 v4, 0x848, v79
	ds_write2_b32 v4, v2, v3 offset1:1
	v_pk_mul_f32 v[2:3], v[20:21], v[78:79] op_sel_hi:[1,0]
	v_add_u32_e32 v4, 0xc60, v79
	ds_write2_b32 v4, v2, v3 offset1:1
	v_pk_mul_f32 v[2:3], v[22:23], v[78:79] op_sel_hi:[1,0]
	v_add_u32_e32 v4, 0xc68, v79
	ds_write2_b32 v4, v2, v3 offset1:1
	v_pk_mul_f32 v[2:3], v[36:37], v[80:81] op_sel_hi:[1,0]
	v_add_u32_e32 v4, 0x1080, v79
	ds_write2_b32 v4, v2, v3 offset1:1
	v_pk_mul_f32 v[2:3], v[38:39], v[80:81] op_sel_hi:[1,0]
	v_add_u32_e32 v4, 0x1088, v79
	ds_write2_b32 v4, v2, v3 offset1:1
	v_pk_mul_f32 v[2:3], v[32:33], v[82:83] op_sel_hi:[1,0]
	v_add_u32_e32 v4, 0x14a0, v79
	s_mul_hi_i32 s10, s15, 0x2e8ba2e9
	ds_write2_b32 v4, v2, v3 offset1:1
	v_pk_mul_f32 v[2:3], v[34:35], v[82:83] op_sel_hi:[1,0]
	v_add_u32_e32 v4, 0x14a8, v79
	s_lshr_b32 s11, s10, 31
	s_ashr_i32 s10, s10, 6
	ds_write2_b32 v4, v2, v3 offset1:1
	s_waitcnt vmcnt(7)
	v_pk_mul_f32 v[2:3], v[52:53], v[84:85] op_sel_hi:[1,0]
	v_add_u32_e32 v4, 0x18c0, v79
	s_add_i32 s15, s10, s11
	ds_write2_b32 v4, v2, v3 offset1:1
	v_pk_mul_f32 v[2:3], v[54:55], v[84:85] op_sel_hi:[1,0]
	v_add_u32_e32 v4, 0x18c8, v79
	s_lshl_b32 s10, s15, 6
	ds_write2_b32 v4, v2, v3 offset1:1
	s_waitcnt vmcnt(6)
	v_pk_mul_f32 v[2:3], v[44:45], v[86:87] op_sel_hi:[1,0]
	v_add_u32_e32 v4, 0x1ce0, v79
	ds_write2_b32 v4, v2, v3 offset1:1
	v_pk_mul_f32 v[2:3], v[46:47], v[86:87] op_sel_hi:[1,0]
	v_add_u32_e32 v4, 0x1ce8, v79
	s_ashr_i32 s11, s10, 31
	ds_write2_b32 v4, v2, v3 offset1:1
	v_lshl_add_u64 v[34:35], s[10:11], 1, v[70:71]
	s_mul_i32 s10, s15, 0xffffd400
	s_waitcnt lgkmcnt(0)
	s_add_i32 s10, s10, s2
	ds_read2_b32 v[6:7], v75 offset0:33 offset1:41
	ds_read2_b32 v[16:17], v75 offset1:8
	ds_read2_b32 v[18:19], v75 offset0:66 offset1:74
	ds_read2_b32 v[20:21], v75 offset0:99 offset1:107
	ds_read2_b32 v[22:23], v75 offset0:132 offset1:140
	ds_read2_b32 v[24:25], v75 offset0:165 offset1:173
	ds_read2_b32 v[26:27], v75 offset0:198 offset1:206
	ds_read2_b32 v[32:33], v75 offset0:231 offset1:239
	v_add_u32_e32 v38, s10, v83
	s_waitcnt lgkmcnt(6)
	v_cvt_pk_bf16_f32 v2, v16, v6
	v_add_u32_e32 v6, 0xffffea00, v38
	v_cmp_lt_i32_e32 vcc, s14, v38
	s_waitcnt lgkmcnt(4)
	v_cvt_pk_bf16_f32 v3, v18, v20
	s_waitcnt lgkmcnt(2)
	v_cvt_pk_bf16_f32 v4, v22, v24
	v_cndmask_b32_e32 v6, v38, v6, vcc
	v_lshlrev_b32_e32 v16, 1, v6
	v_and_b32_e32 v16, 0xffffff00, v16
	v_cndmask_b32_e32 v18, 0, v81, vcc
	v_and_b32_e32 v6, 0x67, v6
	v_or3_b32 v36, v6, v18, v16
	v_ashrrev_i32_e32 v37, 31, v36
	v_lshlrev_b64 v[36:37], 12, v[36:37]
	s_waitcnt lgkmcnt(0)
	v_cvt_pk_bf16_f32 v5, v26, v32
	v_lshl_add_u64 v[36:37], v[34:35], 0, v[36:37]
	v_add_u32_e32 v6, 8, v38
	global_store_dwordx4 v[36:37], v[2:5], off sc1
	v_cmp_lt_i32_e32 vcc, s14, v6
	s_waitcnt vmcnt(3)
	v_mov_b64_e32 v[52:53], v[60:61]
	v_cvt_pk_bf16_f32 v2, v17, v7
	v_add_u32_e32 v7, 0xffffea08, v38
	v_cndmask_b32_e32 v6, v6, v7, vcc
	v_lshlrev_b32_e32 v7, 1, v6
	v_and_b32_e32 v7, 0xffffff00, v7
	v_cndmask_b32_e32 v16, 0, v81, vcc
	v_and_b32_e32 v6, 0x6f, v6
	v_or3_b32 v6, v6, v16, v7
	v_ashrrev_i32_e32 v7, 31, v6
	v_lshlrev_b64 v[6:7], 12, v[6:7]
	v_cvt_pk_bf16_f32 v3, v19, v21
	v_cvt_pk_bf16_f32 v4, v23, v25
	v_cvt_pk_bf16_f32 v5, v27, v33
	v_lshl_add_u64 v[6:7], v[34:35], 0, v[6:7]
	ds_read2_b32 v[16:17], v75 offset0:16 offset1:24
	ds_read2_b32 v[18:19], v75 offset0:49 offset1:57
	ds_read2_b32 v[20:21], v75 offset0:82 offset1:90
	ds_read2_b32 v[22:23], v75 offset0:115 offset1:123
	ds_read2_b32 v[24:25], v75 offset0:148 offset1:156
	ds_read2_b32 v[26:27], v75 offset0:181 offset1:189
	ds_read2_b32 v[32:33], v75 offset0:214 offset1:222
	ds_read2_b32 v[36:37], v75 offset0:247 offset1:255
	global_store_dwordx4 v[6:7], v[2:5], off sc1
	v_add_u32_e32 v6, 16, v38
	v_add_u32_e32 v7, 0xffffea10, v38
	v_cmp_lt_i32_e32 vcc, s14, v6
	s_waitcnt lgkmcnt(6)
	v_cvt_pk_bf16_f32 v2, v16, v18
	s_waitcnt lgkmcnt(4)
	v_cvt_pk_bf16_f32 v3, v20, v22
	v_cndmask_b32_e32 v6, v6, v7, vcc
	v_lshlrev_b32_e32 v7, 1, v6
	v_and_b32_e32 v7, 0xffffff00, v7
	v_cndmask_b32_e32 v16, 0, v81, vcc
	v_and_b32_e32 v6, 0x77, v6
	v_or3_b32 v6, v6, v16, v7
	v_ashrrev_i32_e32 v7, 31, v6
	v_lshlrev_b64 v[6:7], 12, v[6:7]
	s_waitcnt lgkmcnt(2)
	v_cvt_pk_bf16_f32 v4, v24, v26
	s_waitcnt lgkmcnt(0)
	v_cvt_pk_bf16_f32 v5, v32, v36
	v_lshl_add_u64 v[6:7], v[34:35], 0, v[6:7]
	global_store_dwordx4 v[6:7], v[2:5], off sc1
	s_waitcnt vmcnt(4)
	v_mov_b64_e32 v[44:45], v[64:65]
	v_add_u32_e32 v83, s6, v83
	v_add_u32_e32 v2, 24, v38
	v_add_u32_e32 v3, 0xffffea18, v38
	v_cmp_lt_i32_e32 vcc, s14, v2
	v_cvt_pk_bf16_f32 v5, v33, v37
	v_mov_b64_e32 v[36:37], v[48:49]
	v_cndmask_b32_e32 v2, v2, v3, vcc
	v_lshlrev_b32_e32 v3, 1, v2
	v_and_b32_e32 v3, 0xffffff00, v3
	v_cndmask_b32_e32 v4, 0, v81, vcc
	v_and_b32_e32 v2, 0x7f, v2
	v_or3_b32 v6, v2, v4, v3
	v_ashrrev_i32_e32 v7, 31, v6
	v_lshlrev_b64 v[6:7], 12, v[6:7]
	v_cvt_pk_bf16_f32 v2, v17, v19
	v_cvt_pk_bf16_f32 v3, v21, v23
	v_cvt_pk_bf16_f32 v4, v25, v27
	v_lshl_add_u64 v[6:7], v[34:35], 0, v[6:7]
	global_store_dwordx4 v[6:7], v[2:5], off sc1
	s_waitcnt lgkmcnt(0)
	v_mov_b64_e32 v[18:19], v[14:15]
	v_mov_b64_e32 v[24:25], v[28:29]
	v_mov_b64_e32 v[4:5], v[8:9]
	v_mov_b64_e32 v[20:21], v[40:41]
	v_mov_b64_e32 v[32:33], v[56:57]
	s_add_i32 s16, s16, s6
	v_add_u32_e32 v73, s6, v73
	s_andn2_b64 vcc, exec, s[0:1]
	s_mov_b32 s15, s17
	v_mov_b64_e32 v[16:17], v[12:13]
	v_mov_b64_e32 v[6:7], v[10:11]
	v_mov_b64_e32 v[26:27], v[30:31]
	v_mov_b64_e32 v[22:23], v[42:43]
	v_mov_b64_e32 v[38:39], v[50:51]
	v_mov_b64_e32 v[34:35], v[58:59]
	v_mov_b64_e32 v[54:55], v[62:63]
	v_mov_b64_e32 v[46:47], v[66:67]
	v_mov_b32_e32 v72, v85
	v_mov_b32_e32 v74, v87
	v_mov_b32_e32 v76, v89
	v_mov_b32_e32 v78, v94
	v_mov_b32_e32 v80, v95
	v_mov_b32_e32 v82, v96
	v_mov_b32_e32 v84, v97
	s_waitcnt vmcnt(4)
	v_mov_b32_e32 v86, v1
	s_cbranch_vccz .LBB0_1546

; __device__ __forceinline__ unsigned cvt_pk_bf16(float lo, float hi) { unsigned r; asm volatile("v_cvt_pk_bf16_f32 %0, %1, %2" : "=v"(r) : "v"(lo), "v"(hi)); return r; }
;     __device__ __forceinline__ void operator()(const f32x4 (&acc)[2][2][4][2], const Unit& u, int wr, int wc, int fr, int fq) const {
;         const int row0 = u.pm * BM + wr * 64 + fr, col0 = u.pn * BM + wc * 32 + 8 * fq;
;         f32x4 bv[2][2];
; #pragma unroll
;         for (int bj = 0; bj < 2; ++bj)
; #pragma unroll
;             for (int n = 0; n < 2; ++n) bv[bj][n] = bias ? *(const f32x4*)(bias + col0 + bj * HALF + 4 * n) : (f32x4){0.f, 0.f, 0.f, 0.f};
;         float* ssp = ssout + (size_t)(u.pn * 4 + wc);
; #pragma unroll
;         for (int ai = 0; ai < 2; ++ai) {
;             u32x4 old[4][2];
; #pragma unroll
;             for (int m = 0; m < 4; ++m)
; #pragma unroll
;                 for (int bj = 0; bj < 2; ++bj) old[m][bj] = *(const u32x4*)(HB + (size_t)(row0 + ai * HALF + m * 16) * ldc + col0 + bj * HALF);
; #pragma unroll
;             for (int m = 0; m < 4; ++m) { const int row = row0 + ai * HALF + m * 16; float ss = 0.f;
; #pragma unroll
;                 for (int bj = 0; bj < 2; ++bj) { const u32x4 ow = old[m][bj];
;                     f32x4 v0 = (acc[ai][bj][m][0] + bv[bj][0]) * accs, v1 = (acc[ai][bj][m][1] + bv[bj][1]) * accs;
;                     v0[0] += __uint_as_float(ow.x << 16); v0[1] += __uint_as_float(ow.x & 0xffff0000u); v0[2] += __uint_as_float(ow.y << 16); v0[3] += __uint_as_float(ow.y & 0xffff0000u);
;                     v1[0] += __uint_as_float(ow.z << 16); v1[1] += __uint_as_float(ow.z & 0xffff0000u); v1[2] += __uint_as_float(ow.w << 16); v1[3] += __uint_as_float(ow.w & 0xffff0000u);
;                     ss += (v0[0] * v0[0] + v0[1] * v0[1]) + (v0[2] * v0[2] + v0[3] * v0[3]) + (v1[0] * v1[0] + v1[1] * v1[1]) + (v1[2] * v1[2] + v1[3] * v1[3]);
;                     u32x4 w; w.x = cvt_pk_bf16(v0[0], v0[1]); w.y = cvt_pk_bf16(v0[2], v0[3]); w.z = cvt_pk_bf16(v1[0], v1[1]); w.w = cvt_pk_bf16(v1[2], v1[3]);
;                     *(u32x4*)(HB + (size_t)row * ldc + col0 + bj * HALF) = w; }
;                 ss += __shfl_xor(ss, 16); ss += __shfl_xor(ss, 32);
;                 if (fq == 0) ssp[(size_t)row * 32] = ss; }
.LBB0_1708:
	v_lshl_add_u32 v170, s38, 8, v180
	v_lshlrev_b64 v[196:197], 1, v[168:169]
	v_ashrrev_i32_e32 v171, 31, v170
	v_lshl_add_u64 v[172:173], s[18:19], 0, v[196:197]
	v_lshlrev_b64 v[198:199], 12, v[170:171]
	v_lshl_add_u64 v[144:145], v[172:173], 0, v[198:199]
	global_load_dwordx4 v[188:191], v[144:145], off
	global_load_dwordx4 v[192:195], v[144:145], off offset:256
	v_or_b32_e32 v178, 16, v170
	v_or_b32_e32 v176, 32, v170
	v_or_b32_e32 v174, 48, v170
	v_ashrrev_i32_e32 v179, 31, v178
	v_ashrrev_i32_e32 v177, 31, v176
	s_waitcnt vmcnt(0)
	v_pk_add_f32 v[214:215], v[130:131], v[94:95]
	v_pk_add_f32 v[216:217], v[128:129], v[92:93]
	v_ashrrev_i32_e32 v175, 31, v174
	v_lshlrev_b64 v[128:129], 12, v[178:179]
	v_lshlrev_b64 v[130:131], 12, v[176:177]
	v_pk_add_f32 v[212:213], v[132:133], v[100:101]
	v_lshlrev_b64 v[132:133], 12, v[174:175]
	v_lshl_add_u64 v[128:129], v[172:173], 0, v[128:129]
	v_lshl_add_u64 v[130:131], v[172:173], 0, v[130:131]
	v_pk_add_f32 v[200:201], v[142:143], v[110:111]
	v_pk_add_f32 v[202:203], v[140:141], v[108:109]
	v_pk_add_f32 v[206:207], v[138:139], v[98:99]
	v_pk_add_f32 v[208:209], v[136:137], v[96:97]
	v_pk_add_f32 v[210:211], v[134:135], v[102:103]
	v_lshl_add_u64 v[218:219], v[172:173], 0, v[132:133]
	global_load_dwordx4 v[148:151], v[128:129], off
	global_load_dwordx4 v[144:147], v[128:129], off offset:256
	global_load_dwordx4 v[140:143], v[130:131], off
	global_load_dwordx4 v[136:139], v[130:131], off offset:256
	global_load_dwordx4 v[132:135], v[218:219], off
	s_nop 0
	global_load_dwordx4 v[128:131], v[218:219], off offset:256
	s_lshl_b32 s6, s36, 2
	s_or_b32 s6, s6, s53
	s_ashr_i32 s7, s6, 31
	s_lshl_b64 s[6:7], s[6:7], 2
	s_add_u32 s14, s51, s6
	s_addc_u32 s15, s52, s7
	v_lshlrev_b32_e32 v187, 16, v188
	v_and_b32_e32 v188, 0xffff0000, v188
	v_lshlrev_b32_e32 v218, 16, v189
	v_and_b32_e32 v189, 0xffff0000, v189
	v_lshlrev_b32_e32 v219, 16, v190
	v_lshlrev_b32_e32 v220, 16, v191
	v_lshlrev_b32_e32 v221, 16, v192
	v_and_b32_e32 v192, 0xffff0000, v192
	v_lshlrev_b32_e32 v222, 16, v193
	v_and_b32_e32 v193, 0xffff0000, v193
	v_add_f32_e32 v188, v203, v188
	v_add_f32_e32 v189, v201, v189
	v_and_b32_e32 v191, 0xffff0000, v191
	v_lshlrev_b32_e32 v223, 16, v194
	v_and_b32_e32 v194, 0xffff0000, v194
	v_lshlrev_b32_e32 v224, 16, v195
	v_add_f32_e32 v187, v202, v187
	v_add_f32_e32 v200, v200, v218
	v_add_f32_e32 v201, v208, v219
	v_add_f32_e32 v202, v206, v220
	v_add_f32_e32 v206, v213, v192
	v_add_f32_e32 v208, v211, v193
	v_mul_f32_e32 v192, v188, v188
	v_mul_f32_e32 v193, v189, v189
	v_and_b32_e32 v190, 0xffff0000, v190
	v_add_f32_e32 v191, v207, v191
	v_add_f32_e32 v203, v212, v221
	v_add_f32_e32 v207, v210, v222
	v_add_f32_e32 v194, v217, v194
	v_add_f32_e32 v210, v214, v224
	v_mul_f32_e32 v213, v206, v206
	v_mul_f32_e32 v214, v208, v208
	v_fmac_f32_e32 v192, v187, v187
	v_fmac_f32_e32 v193, v200, v200
	v_and_b32_e32 v195, 0xffff0000, v195
	v_add_f32_e32 v190, v209, v190
	v_add_f32_e32 v209, v216, v223
	v_cvt_pk_bf16_f32 v188, v187, v188
	v_fmac_f32_e32 v213, v203, v203
	v_fmac_f32_e32 v214, v207, v207
	v_add_f32_e32 v187, v192, v193
	v_mul_f32_e32 v193, v194, v194
	v_add_f32_e32 v195, v215, v195
	v_mul_f32_e32 v211, v190, v190
	v_add_f32_e32 v192, v213, v214
	v_fmac_f32_e32 v193, v209, v209
	v_mul_f32_e32 v212, v191, v191
	v_fmac_f32_e32 v211, v201, v201
	v_add_f32_e32 v192, v193, v192
	v_mul_f32_e32 v193, v195, v195
	v_fmac_f32_e32 v212, v202, v202
	v_add_f32_e32 v187, v211, v187
	v_fmac_f32_e32 v193, v210, v210
	v_add_f32_e32 v187, v212, v187
	v_add_f32_e32 v192, v193, v192
	v_cvt_pk_bf16_f32 v189, v200, v189
	v_add_f32_e32 v200, v187, v192
	v_and_b32_e32 v192, 64, v186
	v_cvt_pk_bf16_f32 v190, v201, v190
	v_xor_b32_e32 v187, 16, v186
	v_add_u32_e32 v201, 64, v192
	v_cmp_lt_i32_e32 vcc, v187, v201
	v_cvt_pk_bf16_f32 v191, v202, v191
	v_lshl_add_u64 v[192:193], s[18:19], 0, v[198:199]
	v_lshl_add_u64 v[196:197], v[192:193], 0, v[196:197]
	v_cndmask_b32_e32 v187, v186, v187, vcc
	v_lshlrev_b32_e32 v187, 2, v187
	ds_bpermute_b32 v202, v187, v200
	global_store_dwordx4 v[196:197], v[188:191], off sc1
	v_cvt_pk_bf16_f32 v192, v203, v206
	v_cvt_pk_bf16_f32 v193, v207, v208
	v_cvt_pk_bf16_f32 v194, v209, v194
	v_cvt_pk_bf16_f32 v195, v210, v195
	global_store_dwordx4 v[196:197], v[192:195], off offset:256 sc1
	s_nop 0
	v_xor_b32_e32 v188, 32, v186
	v_cmp_lt_i32_e32 vcc, v188, v201
	s_waitcnt lgkmcnt(0)
	v_add_f32_e32 v189, v200, v202
	v_cndmask_b32_e32 v188, v186, v188, vcc
	v_lshlrev_b32_e32 v188, 2, v188
	ds_bpermute_b32 v190, v188, v189
	s_and_saveexec_b64 s[36:37], s[10:11]
	s_cbranch_execz .LBB0_1710
	v_lshlrev_b64 v[192:193], 7, v[170:171]
	v_lshl_add_u64 v[192:193], s[14:15], 0, v[192:193]
	s_waitcnt lgkmcnt(0)
	v_add_f32_e32 v171, v189, v190
	global_store_dword v[192:193], v171, off
; __device__ __forceinline__ unsigned cvt_pk_bf16(float lo, float hi) { unsigned r; asm volatile("v_cvt_pk_bf16_f32 %0, %1, %2" : "=v"(r) : "v"(lo), "v"(hi)); return r; }
;     __device__ __forceinline__ void operator()(const f32x4 (&acc)[2][2][4][2], const Unit& u, int wr, int wc, int fr, int fq) const {
;     ...
;             for (int m = 0; m < 4; ++m) { const int row = row0 + ai * HALF + m * 16; float ss = 0.f;
; #pragma unroll
;                 for (int bj = 0; bj < 2; ++bj) { const u32x4 ow = old[m][bj];
;                     f32x4 v0 = (acc[ai][bj][m][0] + bv[bj][0]) * accs, v1 = (acc[ai][bj][m][1] + bv[bj][1]) * accs;
;                     v0[0] += __uint_as_float(ow.x << 16); v0[1] += __uint_as_float(ow.x & 0xffff0000u); v0[2] += __uint_as_float(ow.y << 16); v0[3] += __uint_as_float(ow.y & 0xffff0000u);
;                     v1[0] += __uint_as_float(ow.z << 16); v1[1] += __uint_as_float(ow.z & 0xffff0000u); v1[2] += __uint_as_float(ow.w << 16); v1[3] += __uint_as_float(ow.w & 0xffff0000u);
;                     ss += (v0[0] * v0[0] + v0[1] * v0[1]) + (v0[2] * v0[2] + v0[3] * v0[3]) + (v1[0] * v1[0] + v1[1] * v1[1]) + (v1[2] * v1[2] + v1[3] * v1[3]);
;                     u32x4 w; w.x = cvt_pk_bf16(v0[0], v0[1]); w.y = cvt_pk_bf16(v0[2], v0[3]); w.z = cvt_pk_bf16(v1[0], v1[1]); w.w = cvt_pk_bf16(v1[2], v1[3]);
;                     *(u32x4*)(HB + (size_t)row * ldc + col0 + bj * HALF) = w; }
;                 ss += __shfl_xor(ss, 16); ss += __shfl_xor(ss, 32);
;                 if (fq == 0) ssp[(size_t)row * 32] = ss; }
.LBB0_1710:
	s_or_b64 exec, exec, s[36:37]
	v_pk_add_f32 v[124:125], v[124:125], v[108:109]
	s_waitcnt vmcnt(7)
	v_lshlrev_b32_e32 v171, 16, v148
	v_and_b32_e32 v148, 0xffff0000, v148
	v_pk_add_f32 v[126:127], v[126:127], v[110:111]
	v_add_f32_e32 v125, v125, v148
	v_lshlrev_b32_e32 v148, 16, v149
	v_add_f32_e32 v126, v126, v148
	v_and_b32_e32 v148, 0xffff0000, v149
	v_pk_add_f32 v[120:121], v[120:121], v[96:97]
	v_add_f32_e32 v127, v127, v148
	v_lshlrev_b32_e32 v148, 16, v150
	v_add_f32_e32 v148, v120, v148
	v_and_b32_e32 v120, 0xffff0000, v150
	v_pk_add_f32 v[122:123], v[122:123], v[98:99]
	v_add_f32_e32 v149, v121, v120
	v_lshlrev_b32_e32 v120, 16, v151
	v_add_f32_e32 v150, v122, v120
	v_and_b32_e32 v120, 0xffff0000, v151
	v_add_f32_e32 v124, v124, v171
	v_add_f32_e32 v123, v123, v120
	v_mul_f32_e32 v120, v125, v125
	v_mul_f32_e32 v121, v127, v127
	v_fmac_f32_e32 v120, v124, v124
	v_fmac_f32_e32 v121, v126, v126
	v_add_f32_e32 v120, v120, v121
	v_mul_f32_e32 v121, v149, v149
	v_fmac_f32_e32 v121, v148, v148
	v_add_f32_e32 v120, v121, v120
	v_mul_f32_e32 v121, v123, v123
	v_fmac_f32_e32 v121, v150, v150
	v_add_f32_e32 v151, v121, v120
	v_cvt_pk_bf16_f32 v120, v124, v125
	v_pk_add_f32 v[116:117], v[116:117], v[100:101]
	s_waitcnt vmcnt(6)
	v_lshlrev_b32_e32 v124, 16, v144
	v_add_f32_e32 v116, v116, v124
	v_and_b32_e32 v124, 0xffff0000, v144
	v_pk_add_f32 v[118:119], v[118:119], v[102:103]
	v_add_f32_e32 v117, v117, v124
	v_lshlrev_b32_e32 v124, 16, v145
	v_add_f32_e32 v124, v118, v124
	v_and_b32_e32 v118, 0xffff0000, v145
	v_pk_add_f32 v[112:113], v[112:113], v[92:93]
	v_add_f32_e32 v125, v119, v118
	v_lshlrev_b32_e32 v118, 16, v146
	v_cvt_pk_bf16_f32 v121, v126, v127
	v_add_f32_e32 v126, v112, v118
	v_and_b32_e32 v112, 0xffff0000, v146
	v_pk_add_f32 v[114:115], v[114:115], v[94:95]
	v_add_f32_e32 v127, v113, v112
	v_lshlrev_b32_e32 v112, 16, v147
	v_add_f32_e32 v144, v114, v112
	v_and_b32_e32 v112, 0xffff0000, v147
	v_add_f32_e32 v145, v115, v112
	v_mul_f32_e32 v112, v117, v117
	v_mul_f32_e32 v113, v125, v125
	v_fmac_f32_e32 v112, v116, v116
	v_fmac_f32_e32 v113, v124, v124
	v_add_f32_e32 v112, v112, v113
	v_mul_f32_e32 v113, v127, v127
	v_fmac_f32_e32 v113, v126, v126
	v_add_f32_e32 v112, v113, v112
	v_mul_f32_e32 v113, v145, v145
	v_fmac_f32_e32 v113, v144, v144
	v_add_f32_e32 v112, v113, v112
	v_add_f32_e32 v115, v151, v112
	ds_bpermute_b32 v146, v187, v115
	s_waitcnt lgkmcnt(1)
	v_lshlrev_b64 v[190:191], 11, v[178:179]
	v_lshl_add_u64 v[112:113], v[190:191], 1, s[18:19]
	v_lshl_add_u64 v[118:119], v[168:169], 1, v[112:113]
	v_cvt_pk_bf16_f32 v122, v148, v149
	s_waitcnt lgkmcnt(0)
	v_add_f32_e32 v112, v115, v146
	ds_bpermute_b32 v113, v188, v112
	v_cvt_pk_bf16_f32 v123, v150, v123
	global_store_dwordx4 v[118:119], v[120:123], off sc1
	v_cvt_pk_bf16_f32 v114, v116, v117
	v_cvt_pk_bf16_f32 v115, v124, v125
	v_cvt_pk_bf16_f32 v116, v126, v127
	v_cvt_pk_bf16_f32 v117, v144, v145
	global_store_dwordx4 v[118:119], v[114:117], off offset:256 sc1
	s_and_saveexec_b64 s[36:37], s[10:11]
	s_cbranch_execz .LBB0_1712
	v_lshlrev_b64 v[114:115], 7, v[178:179]
	v_lshl_add_u64 v[114:115], s[14:15], 0, v[114:115]
	s_waitcnt lgkmcnt(0)
	v_add_f32_e32 v112, v112, v113
	global_store_dword v[114:115], v112, off
.LBB0_1712:
	s_or_b64 exec, exec, s[36:37]
	v_pk_add_f32 v[104:105], v[104:105], v[108:109]
	s_waitcnt vmcnt(7)
	v_lshlrev_b32_e32 v114, 16, v140
	v_add_f32_e32 v104, v104, v114
	v_and_b32_e32 v114, 0xffff0000, v140
	v_pk_add_f32 v[106:107], v[106:107], v[110:111]
	v_add_f32_e32 v105, v105, v114
	v_lshlrev_b32_e32 v114, 16, v141
	v_add_f32_e32 v106, v106, v114
	v_and_b32_e32 v114, 0xffff0000, v141
	v_pk_add_f32 v[88:89], v[88:89], v[96:97]
	v_add_f32_e32 v107, v107, v114
	v_lshlrev_b32_e32 v114, 16, v142
	v_add_f32_e32 v114, v88, v114
	v_and_b32_e32 v88, 0xffff0000, v142
	v_pk_add_f32 v[90:91], v[90:91], v[98:99]
	v_add_f32_e32 v115, v89, v88
	v_lshlrev_b32_e32 v88, 16, v143
	v_add_f32_e32 v116, v90, v88
	v_and_b32_e32 v88, 0xffff0000, v143
	v_add_f32_e32 v91, v91, v88
	v_mul_f32_e32 v88, v105, v105
	v_mul_f32_e32 v89, v107, v107
	v_fmac_f32_e32 v88, v104, v104
	v_fmac_f32_e32 v89, v106, v106
	v_add_f32_e32 v88, v88, v89
	v_mul_f32_e32 v89, v115, v115
	v_fmac_f32_e32 v89, v114, v114
	v_add_f32_e32 v88, v89, v88
	v_mul_f32_e32 v89, v91, v91
	v_fmac_f32_e32 v89, v116, v116
	v_add_f32_e32 v117, v89, v88
	v_cvt_pk_bf16_f32 v88, v104, v105
	v_pk_add_f32 v[84:85], v[84:85], v[100:101]
	s_waitcnt vmcnt(6)
	v_lshlrev_b32_e32 v104, 16, v136
	v_add_f32_e32 v84, v84, v104
	v_and_b32_e32 v104, 0xffff0000, v136
	v_pk_add_f32 v[86:87], v[86:87], v[102:103]
	v_add_f32_e32 v85, v85, v104
	v_lshlrev_b32_e32 v104, 16, v137
	v_add_f32_e32 v104, v86, v104
	v_and_b32_e32 v86, 0xffff0000, v137
	v_pk_add_f32 v[80:81], v[80:81], v[92:93]
	v_add_f32_e32 v105, v87, v86
	v_lshlrev_b32_e32 v86, 16, v138
	v_cvt_pk_bf16_f32 v89, v106, v107
	v_add_f32_e32 v106, v80, v86
	v_and_b32_e32 v80, 0xffff0000, v138
	v_pk_add_f32 v[82:83], v[82:83], v[94:95]
	v_add_f32_e32 v107, v81, v80
	v_lshlrev_b32_e32 v80, 16, v139
	v_cvt_pk_bf16_f32 v90, v114, v115
	v_add_f32_e32 v114, v82, v80
	v_and_b32_e32 v80, 0xffff0000, v139
	v_add_f32_e32 v115, v83, v80
	v_mul_f32_e32 v80, v85, v85
	v_mul_f32_e32 v81, v105, v105
	v_fmac_f32_e32 v80, v84, v84
	v_fmac_f32_e32 v81, v104, v104
	v_add_f32_e32 v80, v80, v81
	v_mul_f32_e32 v81, v107, v107
	v_fmac_f32_e32 v81, v106, v106
	v_add_f32_e32 v80, v81, v80
	v_mul_f32_e32 v81, v115, v115
	v_fmac_f32_e32 v81, v114, v114
	v_add_f32_e32 v80, v81, v80
	v_add_f32_e32 v83, v117, v80
	v_cvt_pk_bf16_f32 v91, v116, v91
	ds_bpermute_b32 v116, v187, v83
	s_waitcnt lgkmcnt(1)
	v_lshlrev_b64 v[112:113], 11, v[176:177]
	v_lshl_add_u64 v[80:81], v[112:113], 1, s[18:19]
	v_lshl_add_u64 v[86:87], v[168:169], 1, v[80:81]
	global_store_dwordx4 v[86:87], v[88:91], off sc1
	s_waitcnt lgkmcnt(0)
	v_add_f32_e32 v80, v83, v116
	ds_bpermute_b32 v81, v188, v80
	v_cvt_pk_bf16_f32 v82, v84, v85
	v_cvt_pk_bf16_f32 v83, v104, v105
	v_cvt_pk_bf16_f32 v84, v106, v107
	v_cvt_pk_bf16_f32 v85, v114, v115
	global_store_dwordx4 v[86:87], v[82:85], off offset:256 sc1
	s_and_saveexec_b64 s[36:37], s[10:11]
	s_cbranch_execz .LBB0_1714
	v_lshlrev_b64 v[82:83], 7, v[176:177]
	v_lshl_add_u64 v[82:83], s[14:15], 0, v[82:83]
	s_waitcnt lgkmcnt(0)
	v_add_f32_e32 v80, v80, v81
	global_store_dword v[82:83], v80, off
; __device__ __forceinline__ unsigned cvt_pk_bf16(float lo, float hi) { unsigned r; asm volatile("v_cvt_pk_bf16_f32 %0, %1, %2" : "=v"(r) : "v"(lo), "v"(hi)); return r; }
;     __device__ __forceinline__ void operator()(const f32x4 (&acc)[2][2][4][2], const Unit& u, int wr, int wc, int fr, int fq) const {
;     ...
;         for (int ai = 0; ai < 2; ++ai) {
;             u32x4 old[4][2];
; #pragma unroll
;             for (int m = 0; m < 4; ++m)
; #pragma unroll
;                 for (int bj = 0; bj < 2; ++bj) old[m][bj] = *(const u32x4*)(HB + (size_t)(row0 + ai * HALF + m * 16) * ldc + col0 + bj * HALF);
; #pragma unroll
;             for (int m = 0; m < 4; ++m) { const int row = row0 + ai * HALF + m * 16; float ss = 0.f;
; #pragma unroll
;                 for (int bj = 0; bj < 2; ++bj) { const u32x4 ow = old[m][bj];
;                     f32x4 v0 = (acc[ai][bj][m][0] + bv[bj][0]) * accs, v1 = (acc[ai][bj][m][1] + bv[bj][1]) * accs;
;                     v0[0] += __uint_as_float(ow.x << 16); v0[1] += __uint_as_float(ow.x & 0xffff0000u); v0[2] += __uint_as_float(ow.y << 16); v0[3] += __uint_as_float(ow.y & 0xffff0000u);
;                     v1[0] += __uint_as_float(ow.z << 16); v1[1] += __uint_as_float(ow.z & 0xffff0000u); v1[2] += __uint_as_float(ow.w << 16); v1[3] += __uint_as_float(ow.w & 0xffff0000u);
;                     ss += (v0[0] * v0[0] + v0[1] * v0[1]) + (v0[2] * v0[2] + v0[3] * v0[3]) + (v1[0] * v1[0] + v1[1] * v1[1]) + (v1[2] * v1[2] + v1[3] * v1[3]);
;                     u32x4 w; w.x = cvt_pk_bf16(v0[0], v0[1]); w.y = cvt_pk_bf16(v0[2], v0[3]); w.z = cvt_pk_bf16(v1[0], v1[1]); w.w = cvt_pk_bf16(v1[2], v1[3]);
;                     *(u32x4*)(HB + (size_t)row * ldc + col0 + bj * HALF) = w; }
;                 ss += __shfl_xor(ss, 16); ss += __shfl_xor(ss, 32);
;                 if (fq == 0) ssp[(size_t)row * 32] = ss; }
.LBB0_1714:
	s_or_b64 exec, exec, s[36:37]
	v_pk_add_f32 v[76:77], v[76:77], v[108:109]
	s_waitcnt vmcnt(7)
	v_lshlrev_b32_e32 v82, 16, v132
	v_add_f32_e32 v76, v76, v82
	v_and_b32_e32 v82, 0xffff0000, v132
	v_pk_add_f32 v[78:79], v[78:79], v[110:111]
	v_add_f32_e32 v77, v77, v82
	v_lshlrev_b32_e32 v82, 16, v133
	v_add_f32_e32 v78, v78, v82
	v_and_b32_e32 v82, 0xffff0000, v133
	v_pk_add_f32 v[72:73], v[72:73], v[96:97]
	v_add_f32_e32 v79, v79, v82
	v_lshlrev_b32_e32 v82, 16, v134
	v_add_f32_e32 v82, v72, v82
	v_and_b32_e32 v72, 0xffff0000, v134
	v_pk_add_f32 v[74:75], v[74:75], v[98:99]
	v_add_f32_e32 v83, v73, v72
	v_lshlrev_b32_e32 v72, 16, v135
	v_add_f32_e32 v84, v74, v72
	v_and_b32_e32 v72, 0xffff0000, v135
	v_add_f32_e32 v75, v75, v72
	v_mul_f32_e32 v72, v77, v77
	v_mul_f32_e32 v73, v79, v79
	v_fmac_f32_e32 v72, v76, v76
	v_fmac_f32_e32 v73, v78, v78
	v_add_f32_e32 v72, v72, v73
	v_mul_f32_e32 v73, v83, v83
	v_fmac_f32_e32 v73, v82, v82
	v_add_f32_e32 v72, v73, v72
	v_mul_f32_e32 v73, v75, v75
	v_fmac_f32_e32 v73, v84, v84
	v_add_f32_e32 v85, v73, v72
	v_cvt_pk_bf16_f32 v72, v76, v77
	v_pk_add_f32 v[68:69], v[68:69], v[100:101]
	s_waitcnt vmcnt(6)
	v_lshlrev_b32_e32 v76, 16, v128
	v_add_f32_e32 v68, v68, v76
	v_and_b32_e32 v76, 0xffff0000, v128
	v_pk_add_f32 v[70:71], v[70:71], v[102:103]
	v_add_f32_e32 v69, v69, v76
	v_lshlrev_b32_e32 v76, 16, v129
	v_add_f32_e32 v76, v70, v76
	v_and_b32_e32 v70, 0xffff0000, v129
	v_pk_add_f32 v[64:65], v[64:65], v[92:93]
	v_add_f32_e32 v77, v71, v70
	v_lshlrev_b32_e32 v70, 16, v130
	v_cvt_pk_bf16_f32 v73, v78, v79
	v_add_f32_e32 v78, v64, v70
	v_and_b32_e32 v64, 0xffff0000, v130
	v_pk_add_f32 v[66:67], v[66:67], v[94:95]
	v_add_f32_e32 v79, v65, v64
	v_lshlrev_b32_e32 v64, 16, v131
	v_cvt_pk_bf16_f32 v74, v82, v83
	v_add_f32_e32 v82, v66, v64
	v_and_b32_e32 v64, 0xffff0000, v131
	v_add_f32_e32 v83, v67, v64
	v_mul_f32_e32 v64, v69, v69
	v_mul_f32_e32 v65, v77, v77
	v_fmac_f32_e32 v64, v68, v68
	v_fmac_f32_e32 v65, v76, v76
	v_add_f32_e32 v64, v64, v65
	v_mul_f32_e32 v65, v79, v79
	v_fmac_f32_e32 v65, v78, v78
	v_add_f32_e32 v64, v65, v64
	v_mul_f32_e32 v65, v83, v83
	v_fmac_f32_e32 v65, v82, v82
	v_add_f32_e32 v64, v65, v64
	v_add_f32_e32 v67, v85, v64
	v_cvt_pk_bf16_f32 v75, v84, v75
	ds_bpermute_b32 v84, v187, v67
	s_waitcnt lgkmcnt(1)
	v_lshlrev_b64 v[80:81], 11, v[174:175]
	v_lshl_add_u64 v[64:65], v[80:81], 1, s[18:19]
	v_lshl_add_u64 v[70:71], v[168:169], 1, v[64:65]
	global_store_dwordx4 v[70:71], v[72:75], off sc1
	s_waitcnt lgkmcnt(0)
	v_add_f32_e32 v64, v67, v84
	ds_bpermute_b32 v65, v188, v64
	v_cvt_pk_bf16_f32 v66, v68, v69
	v_cvt_pk_bf16_f32 v67, v76, v77
	v_cvt_pk_bf16_f32 v68, v78, v79
	v_cvt_pk_bf16_f32 v69, v82, v83
	global_store_dwordx4 v[70:71], v[66:69], off offset:256 sc1
	s_and_saveexec_b64 s[36:37], s[10:11]
	s_cbranch_execz .LBB0_1716
	v_lshlrev_b64 v[66:67], 7, v[174:175]
	v_lshl_add_u64 v[66:67], s[14:15], 0, v[66:67]
	s_waitcnt lgkmcnt(0)
	v_add_f32_e32 v64, v64, v65
	global_store_dword v[66:67], v64, off
.LBB0_1716:
	s_or_b64 exec, exec, s[36:37]
	v_add_u32_e32 v106, 0x80, v170
	v_ashrrev_i32_e32 v107, 31, v106
	v_lshlrev_b64 v[120:121], 12, v[106:107]
	s_waitcnt lgkmcnt(0)
	v_lshl_add_u64 v[64:65], v[172:173], 0, v[120:121]
	global_load_dwordx4 v[112:115], v[64:65], off
	global_load_dwordx4 v[116:119], v[64:65], off offset:256
	v_add_u32_e32 v104, 0x90, v170
	v_add_u32_e32 v90, 0xa0, v170
	v_add_u32_e32 v88, 0xb0, v170
	v_ashrrev_i32_e32 v105, 31, v104
	v_ashrrev_i32_e32 v91, 31, v90
	v_ashrrev_i32_e32 v89, 31, v88
	v_lshlrev_b64 v[64:65], 12, v[104:105]
	v_lshlrev_b64 v[66:67], 12, v[90:91]
	v_lshlrev_b64 v[68:69], 12, v[88:89]
	v_lshl_add_u64 v[64:65], v[172:173], 0, v[64:65]
	v_lshl_add_u64 v[66:67], v[172:173], 0, v[66:67]
	v_lshl_add_u64 v[122:123], v[172:173], 0, v[68:69]
	global_load_dwordx4 v[84:87], v[64:65], off
	global_load_dwordx4 v[80:83], v[64:65], off offset:256
	global_load_dwordx4 v[76:79], v[66:67], off
	global_load_dwordx4 v[72:75], v[66:67], off offset:256
	global_load_dwordx4 v[68:71], v[122:123], off
	s_nop 0
	global_load_dwordx4 v[64:67], v[122:123], off offset:256
	v_pk_add_f32 v[62:63], v[62:63], v[110:111]
	v_pk_add_f32 v[60:61], v[60:61], v[108:109]
	v_pk_add_f32 v[58:59], v[58:59], v[98:99]
	v_pk_add_f32 v[56:57], v[56:57], v[96:97]
	v_pk_add_f32 v[54:55], v[54:55], v[102:103]
	v_pk_add_f32 v[52:53], v[52:53], v[100:101]
	v_pk_add_f32 v[50:51], v[50:51], v[94:95]
	v_pk_add_f32 v[48:49], v[48:49], v[92:93]
	s_waitcnt vmcnt(7)
	v_lshlrev_b32_e32 v122, 16, v112
	v_and_b32_e32 v112, 0xffff0000, v112
	v_lshlrev_b32_e32 v123, 16, v113
	v_and_b32_e32 v113, 0xffff0000, v113
	v_lshlrev_b32_e32 v124, 16, v114
	v_and_b32_e32 v114, 0xffff0000, v114
	v_lshlrev_b32_e32 v125, 16, v115
	v_and_b32_e32 v115, 0xffff0000, v115
	s_waitcnt vmcnt(6)
	v_lshlrev_b32_e32 v126, 16, v116
	v_and_b32_e32 v116, 0xffff0000, v116
	v_lshlrev_b32_e32 v127, 16, v117
	v_and_b32_e32 v117, 0xffff0000, v117
	v_lshlrev_b32_e32 v128, 16, v118
	v_and_b32_e32 v118, 0xffff0000, v118
	v_lshlrev_b32_e32 v129, 16, v119
	v_and_b32_e32 v119, 0xffff0000, v119
	v_add_f32_e32 v61, v61, v112
	v_add_f32_e32 v63, v63, v113
	v_add_f32_e32 v57, v57, v114
	v_add_f32_e32 v59, v59, v115
	v_add_f32_e32 v113, v53, v116
	v_add_f32_e32 v115, v55, v117
	v_add_f32_e32 v60, v60, v122
	v_add_f32_e32 v62, v62, v123
	v_add_f32_e32 v56, v56, v124
	v_add_f32_e32 v58, v58, v125
	v_add_f32_e32 v112, v52, v126
	v_add_f32_e32 v114, v54, v127
	v_add_f32_e32 v116, v48, v128
	v_add_f32_e32 v117, v49, v118
	v_add_f32_e32 v118, v50, v129
	v_add_f32_e32 v119, v51, v119
	v_mul_f32_e32 v52, v61, v61
	v_mul_f32_e32 v53, v63, v63
	v_mul_f32_e32 v54, v57, v57
	v_mul_f32_e32 v55, v59, v59
	v_cvt_pk_bf16_f32 v48, v60, v61
	v_cvt_pk_bf16_f32 v49, v62, v63
	v_cvt_pk_bf16_f32 v50, v56, v57
	v_cvt_pk_bf16_f32 v51, v58, v59
	v_mul_f32_e32 v57, v113, v113
	v_mul_f32_e32 v59, v115, v115
	v_mul_f32_e32 v61, v117, v117
	v_fmac_f32_e32 v52, v60, v60
	v_fmac_f32_e32 v53, v62, v62
	v_fmac_f32_e32 v57, v112, v112
	v_fmac_f32_e32 v59, v114, v114
	v_mul_f32_e32 v63, v119, v119
	v_fmac_f32_e32 v54, v56, v56
	v_fmac_f32_e32 v61, v116, v116
	v_add_f32_e32 v52, v52, v53
	v_add_f32_e32 v53, v57, v59
	v_fmac_f32_e32 v55, v58, v58
	v_fmac_f32_e32 v63, v118, v118
	v_add_f32_e32 v52, v54, v52
	v_add_f32_e32 v53, v61, v53
	v_add_f32_e32 v52, v55, v52
	v_add_f32_e32 v53, v63, v53
	v_add_f32_e32 v56, v52, v53
	ds_bpermute_b32 v57, v187, v56
	v_lshl_add_u64 v[52:53], s[18:19], 0, v[120:121]
	v_lshl_add_u64 v[54:55], v[168:169], 1, v[52:53]
	global_store_dwordx4 v[54:55], v[48:51], off sc1
	s_waitcnt lgkmcnt(0)
	s_nop 0
	v_add_f32_e32 v48, v56, v57
	ds_bpermute_b32 v49, v188, v48
	v_cvt_pk_bf16_f32 v50, v112, v113
	v_cvt_pk_bf16_f32 v51, v114, v115
	v_cvt_pk_bf16_f32 v52, v116, v117
	v_cvt_pk_bf16_f32 v53, v118, v119
	global_store_dwordx4 v[54:55], v[50:53], off offset:256 sc1
	s_and_saveexec_b64 s[36:37], s[10:11]
	s_cbranch_execz .LBB0_1718
; __device__ __forceinline__ unsigned cvt_pk_bf16(float lo, float hi) { unsigned r; asm volatile("v_cvt_pk_bf16_f32 %0, %1, %2" : "=v"(r) : "v"(lo), "v"(hi)); return r; }
;     __device__ __forceinline__ void operator()(const f32x4 (&acc)[2][2][4][2], const Unit& u, int wr, int wc, int fr, int fq) const {
;     ...
;             for (int m = 0; m < 4; ++m) { const int row = row0 + ai * HALF + m * 16; float ss = 0.f;
; #pragma unroll
;                 for (int bj = 0; bj < 2; ++bj) { const u32x4 ow = old[m][bj];
;                     f32x4 v0 = (acc[ai][bj][m][0] + bv[bj][0]) * accs, v1 = (acc[ai][bj][m][1] + bv[bj][1]) * accs;
;                     v0[0] += __uint_as_float(ow.x << 16); v0[1] += __uint_as_float(ow.x & 0xffff0000u); v0[2] += __uint_as_float(ow.y << 16); v0[3] += __uint_as_float(ow.y & 0xffff0000u);
;                     v1[0] += __uint_as_float(ow.z << 16); v1[1] += __uint_as_float(ow.z & 0xffff0000u); v1[2] += __uint_as_float(ow.w << 16); v1[3] += __uint_as_float(ow.w & 0xffff0000u);
;                     ss += (v0[0] * v0[0] + v0[1] * v0[1]) + (v0[2] * v0[2] + v0[3] * v0[3]) + (v1[0] * v1[0] + v1[1] * v1[1]) + (v1[2] * v1[2] + v1[3] * v1[3]);
;                     u32x4 w; w.x = cvt_pk_bf16(v0[0], v0[1]); w.y = cvt_pk_bf16(v0[2], v0[3]); w.z = cvt_pk_bf16(v1[0], v1[1]); w.w = cvt_pk_bf16(v1[2], v1[3]);
;                     *(u32x4*)(HB + (size_t)row * ldc + col0 + bj * HALF) = w; }
;                 ss += __shfl_xor(ss, 16); ss += __shfl_xor(ss, 32);
;                 if (fq == 0) ssp[(size_t)row * 32] = ss; }
	v_lshlrev_b64 v[50:51], 7, v[106:107]
	v_lshl_add_u64 v[50:51], s[14:15], 0, v[50:51]
	s_waitcnt lgkmcnt(0)
	v_add_f32_e32 v48, v48, v49
	global_store_dword v[50:51], v48, off
.LBB0_1718:
	s_or_b64 exec, exec, s[36:37]
	v_pk_add_f32 v[44:45], v[44:45], v[108:109]
	s_waitcnt vmcnt(7)
	v_lshlrev_b32_e32 v50, 16, v84
	v_add_f32_e32 v44, v44, v50
	v_and_b32_e32 v50, 0xffff0000, v84
	v_pk_add_f32 v[46:47], v[46:47], v[110:111]
	v_add_f32_e32 v45, v45, v50
	v_lshlrev_b32_e32 v50, 16, v85
	v_add_f32_e32 v46, v46, v50
	v_and_b32_e32 v50, 0xffff0000, v85
	v_pk_add_f32 v[40:41], v[40:41], v[96:97]
	v_add_f32_e32 v47, v47, v50
	v_lshlrev_b32_e32 v50, 16, v86
	v_add_f32_e32 v50, v40, v50
	v_and_b32_e32 v40, 0xffff0000, v86
	v_pk_add_f32 v[42:43], v[42:43], v[98:99]
	v_add_f32_e32 v51, v41, v40
	v_lshlrev_b32_e32 v40, 16, v87
	v_add_f32_e32 v52, v42, v40
	v_and_b32_e32 v40, 0xffff0000, v87
	v_add_f32_e32 v43, v43, v40
	v_mul_f32_e32 v40, v45, v45
	v_mul_f32_e32 v41, v47, v47
	v_fmac_f32_e32 v40, v44, v44
	v_fmac_f32_e32 v41, v46, v46
	v_add_f32_e32 v40, v40, v41
	v_mul_f32_e32 v41, v51, v51
	v_fmac_f32_e32 v41, v50, v50
	v_add_f32_e32 v40, v41, v40
	v_mul_f32_e32 v41, v43, v43
	v_fmac_f32_e32 v41, v52, v52
	v_add_f32_e32 v53, v41, v40
	v_cvt_pk_bf16_f32 v40, v44, v45
	v_pk_add_f32 v[36:37], v[36:37], v[100:101]
	s_waitcnt vmcnt(6)
	v_lshlrev_b32_e32 v44, 16, v80
	v_add_f32_e32 v36, v36, v44
	v_and_b32_e32 v44, 0xffff0000, v80
	v_pk_add_f32 v[38:39], v[38:39], v[102:103]
	v_add_f32_e32 v37, v37, v44
	v_lshlrev_b32_e32 v44, 16, v81
	v_add_f32_e32 v44, v38, v44
	v_and_b32_e32 v38, 0xffff0000, v81
	v_pk_add_f32 v[32:33], v[32:33], v[92:93]
	v_add_f32_e32 v45, v39, v38
	v_lshlrev_b32_e32 v38, 16, v82
	v_cvt_pk_bf16_f32 v41, v46, v47
	v_add_f32_e32 v46, v32, v38
	v_and_b32_e32 v32, 0xffff0000, v82
	v_pk_add_f32 v[34:35], v[34:35], v[94:95]
	v_add_f32_e32 v47, v33, v32
	v_lshlrev_b32_e32 v32, 16, v83
	v_cvt_pk_bf16_f32 v42, v50, v51
	v_add_f32_e32 v50, v34, v32
	v_and_b32_e32 v32, 0xffff0000, v83
	v_add_f32_e32 v51, v35, v32
	v_mul_f32_e32 v32, v37, v37
	v_mul_f32_e32 v33, v45, v45
	v_fmac_f32_e32 v32, v36, v36
	v_fmac_f32_e32 v33, v44, v44
	v_add_f32_e32 v32, v32, v33
	v_mul_f32_e32 v33, v47, v47
	v_fmac_f32_e32 v33, v46, v46
	v_add_f32_e32 v32, v33, v32
	v_mul_f32_e32 v33, v51, v51
	v_fmac_f32_e32 v33, v50, v50
	v_add_f32_e32 v32, v33, v32
	v_add_f32_e32 v35, v53, v32
	v_cvt_pk_bf16_f32 v43, v52, v43
	ds_bpermute_b32 v52, v187, v35
	s_waitcnt lgkmcnt(1)
	v_lshlrev_b64 v[48:49], 11, v[104:105]
	v_lshl_add_u64 v[32:33], v[48:49], 1, s[18:19]
	v_lshl_add_u64 v[38:39], v[168:169], 1, v[32:33]
	global_store_dwordx4 v[38:39], v[40:43], off sc1
	s_waitcnt lgkmcnt(0)
	v_add_f32_e32 v32, v35, v52
	ds_bpermute_b32 v33, v188, v32
	v_cvt_pk_bf16_f32 v34, v36, v37
	v_cvt_pk_bf16_f32 v35, v44, v45
	v_cvt_pk_bf16_f32 v36, v46, v47
	v_cvt_pk_bf16_f32 v37, v50, v51
	global_store_dwordx4 v[38:39], v[34:37], off offset:256 sc1
	s_and_saveexec_b64 s[36:37], s[10:11]
	s_cbranch_execz .LBB0_1720
	v_lshlrev_b64 v[34:35], 7, v[104:105]
	v_lshl_add_u64 v[34:35], s[14:15], 0, v[34:35]
	s_waitcnt lgkmcnt(0)
	v_add_f32_e32 v32, v32, v33
	global_store_dword v[34:35], v32, off
; __device__ __forceinline__ unsigned cvt_pk_bf16(float lo, float hi) { unsigned r; asm volatile("v_cvt_pk_bf16_f32 %0, %1, %2" : "=v"(r) : "v"(lo), "v"(hi)); return r; }
;     __device__ __forceinline__ void operator()(const f32x4 (&acc)[2][2][4][2], const Unit& u, int wr, int wc, int fr, int fq) const {
;     ...
;             for (int m = 0; m < 4; ++m) { const int row = row0 + ai * HALF + m * 16; float ss = 0.f;
; #pragma unroll
;                 for (int bj = 0; bj < 2; ++bj) { const u32x4 ow = old[m][bj];
;                     f32x4 v0 = (acc[ai][bj][m][0] + bv[bj][0]) * accs, v1 = (acc[ai][bj][m][1] + bv[bj][1]) * accs;
;                     v0[0] += __uint_as_float(ow.x << 16); v0[1] += __uint_as_float(ow.x & 0xffff0000u); v0[2] += __uint_as_float(ow.y << 16); v0[3] += __uint_as_float(ow.y & 0xffff0000u);
;                     v1[0] += __uint_as_float(ow.z << 16); v1[1] += __uint_as_float(ow.z & 0xffff0000u); v1[2] += __uint_as_float(ow.w << 16); v1[3] += __uint_as_float(ow.w & 0xffff0000u);
;                     ss += (v0[0] * v0[0] + v0[1] * v0[1]) + (v0[2] * v0[2] + v0[3] * v0[3]) + (v1[0] * v1[0] + v1[1] * v1[1]) + (v1[2] * v1[2] + v1[3] * v1[3]);
;                     u32x4 w; w.x = cvt_pk_bf16(v0[0], v0[1]); w.y = cvt_pk_bf16(v0[2], v0[3]); w.z = cvt_pk_bf16(v1[0], v1[1]); w.w = cvt_pk_bf16(v1[2], v1[3]);
;                     *(u32x4*)(HB + (size_t)row * ldc + col0 + bj * HALF) = w; }
;                 ss += __shfl_xor(ss, 16); ss += __shfl_xor(ss, 32);
;                 if (fq == 0) ssp[(size_t)row * 32] = ss; }
.LBB0_1720:
	s_or_b64 exec, exec, s[36:37]
	v_pk_add_f32 v[28:29], v[28:29], v[108:109]
	s_waitcnt vmcnt(7)
	v_lshlrev_b32_e32 v34, 16, v76
	v_add_f32_e32 v28, v28, v34
	v_and_b32_e32 v34, 0xffff0000, v76
	v_pk_add_f32 v[30:31], v[30:31], v[110:111]
	v_add_f32_e32 v29, v29, v34
	v_lshlrev_b32_e32 v34, 16, v77
	v_add_f32_e32 v30, v30, v34
	v_and_b32_e32 v34, 0xffff0000, v77
	v_pk_add_f32 v[24:25], v[24:25], v[96:97]
	v_add_f32_e32 v31, v31, v34
	v_lshlrev_b32_e32 v34, 16, v78
	v_add_f32_e32 v34, v24, v34
	v_and_b32_e32 v24, 0xffff0000, v78
	v_pk_add_f32 v[26:27], v[26:27], v[98:99]
	v_add_f32_e32 v35, v25, v24
	v_lshlrev_b32_e32 v24, 16, v79
	v_add_f32_e32 v36, v26, v24
	v_and_b32_e32 v24, 0xffff0000, v79
	v_add_f32_e32 v27, v27, v24
	v_mul_f32_e32 v24, v29, v29
	v_mul_f32_e32 v25, v31, v31
	v_fmac_f32_e32 v24, v28, v28
	v_fmac_f32_e32 v25, v30, v30
	v_add_f32_e32 v24, v24, v25
	v_mul_f32_e32 v25, v35, v35
	v_fmac_f32_e32 v25, v34, v34
	v_add_f32_e32 v24, v25, v24
	v_mul_f32_e32 v25, v27, v27
	v_fmac_f32_e32 v25, v36, v36
	v_add_f32_e32 v37, v25, v24
	v_cvt_pk_bf16_f32 v24, v28, v29
	v_pk_add_f32 v[20:21], v[20:21], v[100:101]
	s_waitcnt vmcnt(6)
	v_lshlrev_b32_e32 v28, 16, v72
	v_add_f32_e32 v20, v20, v28
	v_and_b32_e32 v28, 0xffff0000, v72
	v_pk_add_f32 v[22:23], v[22:23], v[102:103]
	v_add_f32_e32 v21, v21, v28
	v_lshlrev_b32_e32 v28, 16, v73
	v_add_f32_e32 v28, v22, v28
	v_and_b32_e32 v22, 0xffff0000, v73
	v_pk_add_f32 v[16:17], v[16:17], v[92:93]
	v_add_f32_e32 v29, v23, v22
	v_lshlrev_b32_e32 v22, 16, v74
	v_cvt_pk_bf16_f32 v25, v30, v31
	v_add_f32_e32 v30, v16, v22
	v_and_b32_e32 v16, 0xffff0000, v74
	v_pk_add_f32 v[18:19], v[18:19], v[94:95]
	v_add_f32_e32 v31, v17, v16
	v_lshlrev_b32_e32 v16, 16, v75
	v_cvt_pk_bf16_f32 v26, v34, v35
	v_add_f32_e32 v34, v18, v16
	v_and_b32_e32 v16, 0xffff0000, v75
	v_add_f32_e32 v35, v19, v16
	v_mul_f32_e32 v16, v21, v21
	v_mul_f32_e32 v17, v29, v29
	v_fmac_f32_e32 v16, v20, v20
	v_fmac_f32_e32 v17, v28, v28
	v_add_f32_e32 v16, v16, v17
	v_mul_f32_e32 v17, v31, v31
	v_fmac_f32_e32 v17, v30, v30
	v_add_f32_e32 v16, v17, v16
	v_mul_f32_e32 v17, v35, v35
	v_fmac_f32_e32 v17, v34, v34
	v_add_f32_e32 v16, v17, v16
	v_add_f32_e32 v19, v37, v16
	v_cvt_pk_bf16_f32 v27, v36, v27
	ds_bpermute_b32 v36, v187, v19
	s_waitcnt lgkmcnt(1)
	v_lshlrev_b64 v[32:33], 11, v[90:91]
	v_lshl_add_u64 v[16:17], v[32:33], 1, s[18:19]
	v_lshl_add_u64 v[22:23], v[168:169], 1, v[16:17]
	global_store_dwordx4 v[22:23], v[24:27], off sc1
	s_waitcnt lgkmcnt(0)
	v_add_f32_e32 v16, v19, v36
	ds_bpermute_b32 v17, v188, v16
	v_cvt_pk_bf16_f32 v18, v20, v21
	v_cvt_pk_bf16_f32 v19, v28, v29
	v_cvt_pk_bf16_f32 v20, v30, v31
	v_cvt_pk_bf16_f32 v21, v34, v35
	global_store_dwordx4 v[22:23], v[18:21], off offset:256 sc1
	s_and_saveexec_b64 s[36:37], s[10:11]
	s_cbranch_execz .LBB0_1722
	v_lshlrev_b64 v[18:19], 7, v[90:91]
	v_lshl_add_u64 v[18:19], s[14:15], 0, v[18:19]
	s_waitcnt lgkmcnt(0)
	v_add_f32_e32 v16, v16, v17
	global_store_dword v[18:19], v16, off
.LBB0_1722:
	s_or_b64 exec, exec, s[36:37]
	v_pk_add_f32 v[12:13], v[12:13], v[108:109]
	s_waitcnt vmcnt(7)
	v_lshlrev_b32_e32 v18, 16, v68
	v_add_f32_e32 v12, v12, v18
	v_and_b32_e32 v18, 0xffff0000, v68
	v_pk_add_f32 v[14:15], v[14:15], v[110:111]
	v_add_f32_e32 v13, v13, v18
	v_lshlrev_b32_e32 v18, 16, v69
	v_add_f32_e32 v14, v14, v18
	v_and_b32_e32 v18, 0xffff0000, v69
	v_pk_add_f32 v[8:9], v[8:9], v[96:97]
	v_add_f32_e32 v15, v15, v18
	v_lshlrev_b32_e32 v18, 16, v70
	v_add_f32_e32 v18, v8, v18
	v_and_b32_e32 v8, 0xffff0000, v70
	v_pk_add_f32 v[10:11], v[10:11], v[98:99]
	v_add_f32_e32 v19, v9, v8
	v_lshlrev_b32_e32 v8, 16, v71
	v_add_f32_e32 v20, v10, v8
	v_and_b32_e32 v8, 0xffff0000, v71
	v_add_f32_e32 v11, v11, v8
	v_mul_f32_e32 v8, v13, v13
	v_mul_f32_e32 v9, v15, v15
	v_fmac_f32_e32 v8, v12, v12
	v_fmac_f32_e32 v9, v14, v14
	v_add_f32_e32 v8, v8, v9
	v_mul_f32_e32 v9, v19, v19
	v_fmac_f32_e32 v9, v18, v18
	v_add_f32_e32 v8, v9, v8
	v_mul_f32_e32 v9, v11, v11
	v_fmac_f32_e32 v9, v20, v20
	v_add_f32_e32 v21, v9, v8
	v_cvt_pk_bf16_f32 v8, v12, v13
	v_pk_add_f32 v[4:5], v[4:5], v[100:101]
	s_waitcnt vmcnt(6)
	v_lshlrev_b32_e32 v12, 16, v64
	v_add_f32_e32 v4, v4, v12
	v_and_b32_e32 v12, 0xffff0000, v64
	v_pk_add_f32 v[6:7], v[6:7], v[102:103]
	v_add_f32_e32 v5, v5, v12
	v_lshlrev_b32_e32 v12, 16, v65
	v_add_f32_e32 v12, v6, v12
	v_and_b32_e32 v6, 0xffff0000, v65
	v_pk_add_f32 v[0:1], v[0:1], v[92:93]
	v_add_f32_e32 v13, v7, v6
	v_lshlrev_b32_e32 v6, 16, v66
	v_cvt_pk_bf16_f32 v9, v14, v15
	v_add_f32_e32 v14, v0, v6
	v_and_b32_e32 v0, 0xffff0000, v66
	v_pk_add_f32 v[2:3], v[2:3], v[94:95]
	v_add_f32_e32 v15, v1, v0
	v_lshlrev_b32_e32 v0, 16, v67
	v_cvt_pk_bf16_f32 v10, v18, v19
	v_add_f32_e32 v18, v2, v0
	v_and_b32_e32 v0, 0xffff0000, v67
	v_add_f32_e32 v19, v3, v0
	v_mul_f32_e32 v0, v5, v5
	v_mul_f32_e32 v1, v13, v13
	v_fmac_f32_e32 v0, v4, v4
	v_fmac_f32_e32 v1, v12, v12
	v_add_f32_e32 v0, v0, v1
	v_mul_f32_e32 v1, v15, v15
	v_fmac_f32_e32 v1, v14, v14
	v_add_f32_e32 v0, v1, v0
	v_mul_f32_e32 v1, v19, v19
	v_fmac_f32_e32 v1, v18, v18
	v_add_f32_e32 v0, v1, v0
	v_add_f32_e32 v3, v21, v0
	v_cvt_pk_bf16_f32 v11, v20, v11
	ds_bpermute_b32 v20, v187, v3
	s_waitcnt lgkmcnt(1)
	v_lshlrev_b64 v[16:17], 11, v[88:89]
	v_lshl_add_u64 v[0:1], v[16:17], 1, s[18:19]
	v_lshl_add_u64 v[6:7], v[168:169], 1, v[0:1]
	global_store_dwordx4 v[6:7], v[8:11], off sc1
	s_waitcnt lgkmcnt(0)
	v_add_f32_e32 v0, v3, v20
	ds_bpermute_b32 v1, v188, v0
	v_cvt_pk_bf16_f32 v2, v4, v5
	v_cvt_pk_bf16_f32 v3, v12, v13
	v_cvt_pk_bf16_f32 v4, v14, v15
	v_cvt_pk_bf16_f32 v5, v18, v19
	global_store_dwordx4 v[6:7], v[2:5], off offset:256 sc1
	s_and_saveexec_b64 s[36:37], s[10:11]
	s_cbranch_execz .LBB0_1724
	v_lshlrev_b64 v[2:3], 7, v[88:89]
	v_lshl_add_u64 v[2:3], s[14:15], 0, v[2:3]
	s_waitcnt lgkmcnt(0)
	v_add_f32_e32 v0, v0, v1
	global_store_dword v[2:3], v0, off

; __device__ __forceinline__ unsigned cvt_pk_bf16(float lo, float hi) { unsigned r; asm volatile("v_cvt_pk_bf16_f32 %0, %1, %2" : "=v"(r) : "v"(lo), "v"(hi)); return r; }
; __device__ __forceinline__ float dpp_up1(float x) { return __builtin_bit_cast(float, __builtin_amdgcn_update_dpp(0, __builtin_bit_cast(int, x), 0x111, 0xf, 0xf, true)); }
;     __device__ __forceinline__ void operator()(const f32x4 (&acc)[2][2][4][2], const Unit& u, int wr, int wc, int fr, int fq) const {
;     ...
;                 f32x4 pg2, pg3, pv2, pv3;
; #pragma unroll
;                 for (int e = 0; e < 4; ++e) { pg2[e] = dpp_up1(xg[2][e]); pg3[e] = dpp_up1(xg[3][e]); pv2[e] = dpp_up1(xv[2][e]); pv3[e] = dpp_up1(xv[3][e]); }
; #pragma unroll
;                 for (int m = 0; m < 4; ++m) {
;                     u32x2_t w; float o[4];
; #pragma unroll
;                     for (int e = 0; e < 4; ++e) {
;                         const float g1 = m >= 1 ? xg[m - (m >= 1 ? 1 : 0)][e] : pg3[e], g2 = m >= 2 ? xg[m - (m >= 2 ? 2 : 0)][e] : (m == 1 ? pg3[e] : pg2[e]);
;                         const float v1 = m >= 1 ? xv[m - (m >= 1 ? 1 : 0)][e] : pv3[e], v2 = m >= 2 ? xv[m - (m >= 2 ? 2 : 0)][e] : (m == 1 ? pv3[e] : pv2[e]);
;                         const float cg_ = bg[e] + w0g[e] * g2 + w1g[e] * g1 + w2g[e] * xg[m][e];
;                         const float cv_ = bv[e] + w0v[e] * v2 + w1v[e] * v1 + w2v[e] * xv[m][e];
;                         o[e] = cg_ * __builtin_amdgcn_rcpf(1.0f + __expf(-cg_)) * cv_;
;                     }
;                     w.x = cvt_pk_bf16(o[0], o[1]); w.y = cvt_pk_bf16(o[2], o[3]);
;                     const int g = g0 + m;
;                     if (n == 0) stash[ai][m] = w;
;                     else if ((fr > 0 || m >= 2) && g < TT) { u32x4 ww; ww.x = stash[ai][m].x; ww.y = stash[ai][m].y; ww.z = w.x; ww.w = w.y; *(u32x4*)(G + (size_t)g * DFF_ + f0 - 4) = ww; }
.LBB0_1802:
	v_mov_b32_dpp v46, v58 row_shr:1 row_mask:0xf bank_mask:0xf bound_ctrl:1
	v_mov_b32_dpp v115, v44 row_shr:1 row_mask:0xf bank_mask:0xf bound_ctrl:1
	s_waitcnt vmcnt(4)
	v_fma_f32 v123, v102, v46, v70
	v_fmac_f32_e32 v123, v94, v115
	v_fmac_f32_e32 v123, v98, v76
	v_mul_f32_e32 v46, 0xbfb8aa3b, v123
	v_exp_f32_e32 v124, v46
	v_mov_b32_dpp v117, v59 row_shr:1 row_mask:0xf bank_mask:0xf bound_ctrl:1
	v_mov_b32_dpp v113, v45 row_shr:1 row_mask:0xf bank_mask:0xf bound_ctrl:1
	v_fma_f32 v117, v103, v117, v71
	v_fmac_f32_e32 v117, v95, v113
	v_add_f32_e32 v124, 1.0, v124
	v_fmac_f32_e32 v117, v99, v77
	v_rcp_f32_e32 v124, v124
	v_mul_f32_e32 v125, 0xbfb8aa3b, v117
	v_mov_b32_dpp v116, v52 row_shr:1 row_mask:0xf bank_mask:0xf bound_ctrl:1
	v_exp_f32_e32 v125, v125
	v_mov_b32_dpp v114, v38 row_shr:1 row_mask:0xf bank_mask:0xf bound_ctrl:1
	s_waitcnt vmcnt(0)
	v_fma_f32 v116, v78, v116, v90
	v_fmac_f32_e32 v116, v82, v114
	v_fmac_f32_e32 v116, v86, v68
	v_mul_f32_e32 v123, v123, v124
	v_mul_f32_e32 v116, v116, v123
	v_add_f32_e32 v123, 1.0, v125
	v_mov_b32_dpp v119, v42 row_shr:1 row_mask:0xf bank_mask:0xf bound_ctrl:1
	v_rcp_f32_e32 v123, v123
	v_mov_b32_dpp v55, v32 row_shr:1 row_mask:0xf bank_mask:0xf bound_ctrl:1
	v_fma_f32 v119, v104, v119, v72
	v_fmac_f32_e32 v119, v96, v55
	v_fmac_f32_e32 v119, v100, v62
	v_mul_f32_e32 v117, v117, v123
	v_mul_f32_e32 v123, 0xbfb8aa3b, v119
	v_mov_b32_dpp v118, v53 row_shr:1 row_mask:0xf bank_mask:0xf bound_ctrl:1
	v_exp_f32_e32 v123, v123
	v_mov_b32_dpp v112, v39 row_shr:1 row_mask:0xf bank_mask:0xf bound_ctrl:1
	v_mov_b32_dpp v121, v43 row_shr:1 row_mask:0xf bank_mask:0xf bound_ctrl:1
	v_fma_f32 v118, v79, v118, v91
	v_mov_b32_dpp v47, v33 row_shr:1 row_mask:0xf bank_mask:0xf bound_ctrl:1
	v_fmac_f32_e32 v118, v83, v112
	v_fma_f32 v121, v105, v121, v73
	v_mov_b32_dpp v120, v36 row_shr:1 row_mask:0xf bank_mask:0xf bound_ctrl:1
	v_fmac_f32_e32 v118, v87, v69
	v_fmac_f32_e32 v121, v97, v47
	v_mul_f32_e32 v117, v118, v117
	v_fma_f32 v118, v80, v120, v92
	v_add_f32_e32 v120, 1.0, v123
	v_fmac_f32_e32 v121, v101, v63
	v_rcp_f32_e32 v120, v120
	v_mul_f32_e32 v123, 0xbfb8aa3b, v121
	v_exp_f32_e32 v123, v123
	v_mov_b32_dpp v54, v34 row_shr:1 row_mask:0xf bank_mask:0xf bound_ctrl:1
	v_fmac_f32_e32 v118, v84, v54
	v_fmac_f32_e32 v118, v88, v60
	v_mul_f32_e32 v119, v119, v120
	v_mul_f32_e32 v118, v118, v119
	v_add_f32_e32 v119, 1.0, v123
	v_rcp_f32_e32 v119, v119
	v_mov_b32_dpp v122, v37 row_shr:1 row_mask:0xf bank_mask:0xf bound_ctrl:1
	v_mov_b32_dpp v46, v35 row_shr:1 row_mask:0xf bank_mask:0xf bound_ctrl:1
	v_fma_f32 v120, v81, v122, v93
	v_fmac_f32_e32 v120, v85, v46
	v_cmp_gt_i32_e32 vcc, s70, v216
	v_fmac_f32_e32 v120, v89, v61
	v_mul_f32_e32 v119, v121, v119
	s_and_b64 s[6:7], s[10:11], vcc
	v_mul_f32_e32 v119, v120, v119
	v_cvt_pk_bf16_f32 v144, v116, v117
	v_cvt_pk_bf16_f32 v145, v118, v119
	s_and_saveexec_b64 s[16:17], s[6:7]
	s_cbranch_execz .LBB0_1804
	v_mov_b64_e32 v[116:117], s[30:31]
	v_mad_i64_i32 v[116:117], s[6:7], v216, s86, v[116:117]
	v_lshl_add_u64 v[116:117], v[178:179], 1, v[116:117]
	global_store_dwordx4 v[116:117], v[142:145], off sc1
.LBB0_1804:
	s_or_b64 exec, exec, s[16:17]
	v_fma_f32 v115, v102, v115, v70
	v_fmac_f32_e32 v115, v94, v76
	v_fmac_f32_e32 v115, v98, v56
	v_mul_f32_e32 v116, 0xbfb8aa3b, v115
	v_exp_f32_e32 v116, v116
	v_fma_f32 v113, v103, v113, v71
	v_fmac_f32_e32 v113, v95, v77
	v_fmac_f32_e32 v113, v99, v57
	v_add_f32_e32 v116, 1.0, v116
	v_rcp_f32_e32 v116, v116
	v_mul_f32_e32 v117, 0xbfb8aa3b, v113
	v_exp_f32_e32 v117, v117
	v_fma_f32 v114, v78, v114, v90
	v_fmac_f32_e32 v114, v82, v68
	v_fmac_f32_e32 v114, v86, v50
	v_mul_f32_e32 v115, v115, v116
	v_mul_f32_e32 v114, v114, v115
	v_add_f32_e32 v115, 1.0, v117
	v_rcp_f32_e32 v115, v115
	v_fma_f32 v55, v104, v55, v72
	v_fmac_f32_e32 v55, v96, v62
	v_fmac_f32_e32 v55, v100, v48
	v_mul_f32_e32 v113, v113, v115
	v_mul_f32_e32 v115, 0xbfb8aa3b, v55
	v_exp_f32_e32 v115, v115
	v_fma_f32 v112, v79, v112, v91
	v_fmac_f32_e32 v112, v83, v69
	v_fma_f32 v47, v105, v47, v73
	v_fmac_f32_e32 v112, v87, v51
	v_fmac_f32_e32 v47, v97, v63
	v_mul_f32_e32 v112, v112, v113
	v_add_f32_e32 v113, 1.0, v115
	v_fmac_f32_e32 v47, v101, v49
	v_rcp_f32_e32 v113, v113
	v_mul_f32_e32 v115, 0xbfb8aa3b, v47
	v_exp_f32_e32 v115, v115
	v_fma_f32 v54, v80, v54, v92
	v_fmac_f32_e32 v54, v84, v60
	v_fmac_f32_e32 v54, v88, v40
	v_mul_f32_e32 v55, v55, v113
	v_mul_f32_e32 v54, v54, v55
	v_add_f32_e32 v55, 1.0, v115
	v_rcp_f32_e32 v55, v55
	v_fma_f32 v46, v81, v46, v93
	v_fmac_f32_e32 v46, v85, v61
	v_cmp_gt_i32_e32 vcc, s70, v219
	v_fmac_f32_e32 v46, v89, v41
	v_mul_f32_e32 v47, v47, v55
	s_and_b64 s[6:7], s[10:11], vcc
	v_mul_f32_e32 v46, v46, v47
	v_cvt_pk_bf16_f32 v142, v114, v112
	v_cvt_pk_bf16_f32 v143, v54, v46
	s_and_saveexec_b64 s[16:17], s[6:7]
	s_cbranch_execz .LBB0_1806
	v_mov_b64_e32 v[46:47], s[30:31]
	v_mad_i64_i32 v[46:47], s[6:7], v219, s86, v[46:47]
	v_lshl_add_u64 v[46:47], v[178:179], 1, v[46:47]
	global_store_dwordx4 v[46:47], v[140:143], off sc1
; __device__ __forceinline__ unsigned cvt_pk_bf16(float lo, float hi) { unsigned r; asm volatile("v_cvt_pk_bf16_f32 %0, %1, %2" : "=v"(r) : "v"(lo), "v"(hi)); return r; }
;     __device__ __forceinline__ void operator()(const f32x4 (&acc)[2][2][4][2], const Unit& u, int wr, int wc, int fr, int fq) const {
;     ...
;                 for (int m = 0; m < 4; ++m) {
;                     u32x2_t w; float o[4];
; #pragma unroll
;                     for (int e = 0; e < 4; ++e) {
;                         const float g1 = m >= 1 ? xg[m - (m >= 1 ? 1 : 0)][e] : pg3[e], g2 = m >= 2 ? xg[m - (m >= 2 ? 2 : 0)][e] : (m == 1 ? pg3[e] : pg2[e]);
;                         const float v1 = m >= 1 ? xv[m - (m >= 1 ? 1 : 0)][e] : pv3[e], v2 = m >= 2 ? xv[m - (m >= 2 ? 2 : 0)][e] : (m == 1 ? pv3[e] : pv2[e]);
;                         const float cg_ = bg[e] + w0g[e] * g2 + w1g[e] * g1 + w2g[e] * xg[m][e];
;                         const float cv_ = bv[e] + w0v[e] * v2 + w1v[e] * v1 + w2v[e] * xv[m][e];
;                         o[e] = cg_ * __builtin_amdgcn_rcpf(1.0f + __expf(-cg_)) * cv_;
;                     }
;                     w.x = cvt_pk_bf16(o[0], o[1]); w.y = cvt_pk_bf16(o[2], o[3]);
;                     const int g = g0 + m;
;                     if (n == 0) stash[ai][m] = w;
;                     else if ((fr > 0 || m >= 2) && g < TT) { u32x4 ww; ww.x = stash[ai][m].x; ww.y = stash[ai][m].y; ww.z = w.x; ww.w = w.y; *(u32x4*)(G + (size_t)g * DFF_ + f0 - 4) = ww; }
.LBB0_1806:
	s_or_b64 exec, exec, s[16:17]
	v_fma_f32 v46, v102, v76, v70
	v_fmac_f32_e32 v46, v94, v56
	v_fmac_f32_e32 v46, v98, v58
	v_mul_f32_e32 v47, 0xbfb8aa3b, v46
	v_exp_f32_e32 v47, v47
	v_fma_f32 v55, v103, v77, v71
	v_fmac_f32_e32 v55, v95, v57
	v_fmac_f32_e32 v55, v99, v59
	v_fma_f32 v54, v78, v68, v90
	v_add_f32_e32 v47, 1.0, v47
	v_mul_f32_e32 v68, 0xbfb8aa3b, v55
	v_rcp_f32_e32 v47, v47
	v_exp_f32_e32 v68, v68
	v_fmac_f32_e32 v54, v82, v50
	v_fmac_f32_e32 v54, v86, v52
	v_mul_f32_e32 v46, v46, v47
	v_add_f32_e32 v47, 1.0, v68
	v_rcp_f32_e32 v47, v47
	v_mul_f32_e32 v46, v54, v46
	v_fma_f32 v54, v79, v69, v91
	v_fmac_f32_e32 v54, v83, v51
	v_mul_f32_e32 v47, v55, v47
	v_fma_f32 v55, v104, v62, v72
	v_fmac_f32_e32 v55, v96, v48
	v_fmac_f32_e32 v55, v100, v42
	v_mul_f32_e32 v62, 0xbfb8aa3b, v55
	v_exp_f32_e32 v62, v62
	v_fmac_f32_e32 v54, v87, v53
	v_mul_f32_e32 v47, v54, v47
	v_fma_f32 v54, v80, v60, v92
	v_add_f32_e32 v60, 1.0, v62
	v_fma_f32 v62, v105, v63, v73
	v_fmac_f32_e32 v62, v97, v49
	v_fmac_f32_e32 v62, v101, v43
	v_rcp_f32_e32 v60, v60
	v_mul_f32_e32 v63, 0xbfb8aa3b, v62
	v_exp_f32_e32 v63, v63
	v_fmac_f32_e32 v54, v84, v40
	v_fmac_f32_e32 v54, v88, v36
	v_mul_f32_e32 v55, v55, v60
	v_mul_f32_e32 v54, v54, v55
	v_add_f32_e32 v55, 1.0, v63
	v_rcp_f32_e32 v55, v55
	v_fma_f32 v60, v81, v61, v93
	v_fmac_f32_e32 v60, v85, v41
	v_fmac_f32_e32 v60, v89, v37
	v_mul_f32_e32 v55, v62, v55
	v_cmp_gt_i32_e32 vcc, s87, v216
	v_mul_f32_e32 v55, v60, v55
	v_cvt_pk_bf16_f32 v112, v46, v47
	v_cvt_pk_bf16_f32 v113, v54, v55
	s_and_saveexec_b64 s[16:17], vcc
	s_cbranch_execz .LBB0_1808
	v_mov_b64_e32 v[46:47], s[30:31]
	v_mad_i64_i32 v[46:47], s[6:7], v218, s86, v[46:47]
	v_lshl_add_u64 v[46:47], v[178:179], 1, v[46:47]
	global_store_dwordx4 v[46:47], v[110:113], off sc1
.LBB0_1808:
	s_or_b64 exec, exec, s[16:17]
	v_fma_f32 v46, v102, v56, v70
	v_fmac_f32_e32 v46, v94, v58
	v_fmac_f32_e32 v46, v98, v44
	v_mul_f32_e32 v44, 0xbfb8aa3b, v46
	v_exp_f32_e32 v44, v44
	v_fma_f32 v47, v78, v50, v90
	v_fma_f32 v50, v103, v57, v71
	v_fmac_f32_e32 v50, v95, v59
	v_fmac_f32_e32 v50, v99, v45
	v_add_f32_e32 v44, 1.0, v44
	v_mul_f32_e32 v45, 0xbfb8aa3b, v50
	v_rcp_f32_e32 v44, v44
	v_exp_f32_e32 v45, v45
	v_fmac_f32_e32 v47, v82, v52
	v_fmac_f32_e32 v47, v86, v38
	v_mul_f32_e32 v38, v46, v44
	v_add_f32_e32 v44, 1.0, v45
	v_rcp_f32_e32 v44, v44
	v_fma_f32 v45, v79, v51, v91
	v_fmac_f32_e32 v45, v83, v53
	v_fma_f32 v40, v80, v40, v92
	v_fmac_f32_e32 v45, v87, v39
	v_mul_f32_e32 v39, v50, v44
	v_fma_f32 v44, v104, v48, v72
	v_fmac_f32_e32 v40, v84, v36
	v_fma_f32 v36, v105, v49, v73
	v_fmac_f32_e32 v44, v96, v42
	v_fmac_f32_e32 v36, v97, v43
	v_fmac_f32_e32 v44, v100, v32
	v_fmac_f32_e32 v36, v101, v33
	v_mul_f32_e32 v32, 0xbfb8aa3b, v44
	v_mul_f32_e32 v33, 0xbfb8aa3b, v36
	v_exp_f32_e32 v32, v32
	v_exp_f32_e32 v33, v33
	v_fmac_f32_e32 v40, v88, v34
	v_fma_f32 v34, v81, v41, v93
	v_add_f32_e32 v32, 1.0, v32
	v_add_f32_e32 v33, 1.0, v33
	v_rcp_f32_e32 v32, v32
	v_rcp_f32_e32 v33, v33
	v_fmac_f32_e32 v34, v85, v37
	v_fmac_f32_e32 v34, v89, v35
	v_mul_f32_e32 v32, v44, v32
	v_mul_f32_e32 v33, v36, v33
	v_cmp_gt_i32_e32 vcc, s88, v216
	v_mul_f32_e32 v38, v47, v38
	v_mul_f32_e32 v39, v45, v39
	v_mul_f32_e32 v32, v40, v32
	v_mul_f32_e32 v33, v34, v33
	v_cvt_pk_bf16_f32 v110, v38, v39
	v_cvt_pk_bf16_f32 v111, v32, v33
	s_and_saveexec_b64 s[16:17], vcc
	s_cbranch_execz .LBB0_1810
	v_mov_b64_e32 v[32:33], s[30:31]
	v_mad_i64_i32 v[32:33], s[6:7], v217, s86, v[32:33]
	v_lshl_add_u64 v[32:33], v[178:179], 1, v[32:33]
	global_store_dwordx4 v[32:33], v[108:111], off sc1

; __device__ __forceinline__ unsigned cvt_pk_bf16(float lo, float hi) { unsigned r; asm volatile("v_cvt_pk_bf16_f32 %0, %1, %2" : "=v"(r) : "v"(lo), "v"(hi)); return r; }
; __device__ __forceinline__ float dpp_up1(float x) { return __builtin_bit_cast(float, __builtin_amdgcn_update_dpp(0, __builtin_bit_cast(int, x), 0x111, 0xf, 0xf, true)); }
;     __device__ __forceinline__ void operator()(const f32x4 (&acc)[2][2][4][2], const Unit& u, int wr, int wc, int fr, int fq) const {
;     ...
;                 f32x4 pg2, pg3, pv2, pv3;
; #pragma unroll
;                 for (int e = 0; e < 4; ++e) { pg2[e] = dpp_up1(xg[2][e]); pg3[e] = dpp_up1(xg[3][e]); pv2[e] = dpp_up1(xv[2][e]); pv3[e] = dpp_up1(xv[3][e]); }
; #pragma unroll
;                 for (int m = 0; m < 4; ++m) {
;                     u32x2_t w; float o[4];
; #pragma unroll
;                     for (int e = 0; e < 4; ++e) {
;                         const float g1 = m >= 1 ? xg[m - (m >= 1 ? 1 : 0)][e] : pg3[e], g2 = m >= 2 ? xg[m - (m >= 2 ? 2 : 0)][e] : (m == 1 ? pg3[e] : pg2[e]);
;                         const float v1 = m >= 1 ? xv[m - (m >= 1 ? 1 : 0)][e] : pv3[e], v2 = m >= 2 ? xv[m - (m >= 2 ? 2 : 0)][e] : (m == 1 ? pv3[e] : pv2[e]);
;                         const float cg_ = bg[e] + w0g[e] * g2 + w1g[e] * g1 + w2g[e] * xg[m][e];
;                         const float cv_ = bv[e] + w0v[e] * v2 + w1v[e] * v1 + w2v[e] * xv[m][e];
;                         o[e] = cg_ * __builtin_amdgcn_rcpf(1.0f + __expf(-cg_)) * cv_;
;                     }
;                     w.x = cvt_pk_bf16(o[0], o[1]); w.y = cvt_pk_bf16(o[2], o[3]);
;                     const int g = g0 + m;
;                     if (n == 0) stash[ai][m] = w;
;                     else if ((fr > 0 || m >= 2) && g < TT) { u32x4 ww; ww.x = stash[ai][m].x; ww.y = stash[ai][m].y; ww.z = w.x; ww.w = w.y; *(u32x4*)(G + (size_t)g * DFF_ + f0 - 4) = ww; }
.LBB0_1812:
	v_mov_b32_dpp v14, v26 row_shr:1 row_mask:0xf bank_mask:0xf bound_ctrl:1
	v_mov_b32_dpp v39, v12 row_shr:1 row_mask:0xf bank_mask:0xf bound_ctrl:1
	v_fma_f32 v47, v102, v14, v70
	v_fmac_f32_e32 v47, v94, v39
	v_fmac_f32_e32 v47, v98, v34
	v_mul_f32_e32 v14, 0xbfb8aa3b, v47
	v_exp_f32_e32 v48, v14
	v_mov_b32_dpp v41, v27 row_shr:1 row_mask:0xf bank_mask:0xf bound_ctrl:1
	v_mov_b32_dpp v37, v13 row_shr:1 row_mask:0xf bank_mask:0xf bound_ctrl:1
	v_fma_f32 v41, v103, v41, v71
	v_fmac_f32_e32 v41, v95, v37
	v_add_f32_e32 v48, 1.0, v48
	v_fmac_f32_e32 v41, v99, v35
	v_rcp_f32_e32 v48, v48
	v_mul_f32_e32 v49, 0xbfb8aa3b, v41
	v_mov_b32_dpp v40, v20 row_shr:1 row_mask:0xf bank_mask:0xf bound_ctrl:1
	v_exp_f32_e32 v49, v49
	v_mov_b32_dpp v38, v6 row_shr:1 row_mask:0xf bank_mask:0xf bound_ctrl:1
	v_fma_f32 v40, v78, v40, v90
	v_fmac_f32_e32 v40, v82, v38
	v_fmac_f32_e32 v40, v86, v32
	v_mul_f32_e32 v47, v47, v48
	v_mul_f32_e32 v40, v40, v47
	v_add_f32_e32 v47, 1.0, v49
	v_mov_b32_dpp v43, v10 row_shr:1 row_mask:0xf bank_mask:0xf bound_ctrl:1
	v_rcp_f32_e32 v47, v47
	v_mov_b32_dpp v23, v0 row_shr:1 row_mask:0xf bank_mask:0xf bound_ctrl:1
	v_fma_f32 v43, v104, v43, v72
	v_fmac_f32_e32 v43, v96, v23
	v_fmac_f32_e32 v43, v100, v30
	v_mul_f32_e32 v41, v41, v47
	v_mul_f32_e32 v47, 0xbfb8aa3b, v43
	v_mov_b32_dpp v42, v21 row_shr:1 row_mask:0xf bank_mask:0xf bound_ctrl:1
	v_exp_f32_e32 v47, v47
	v_mov_b32_dpp v36, v7 row_shr:1 row_mask:0xf bank_mask:0xf bound_ctrl:1
	v_mov_b32_dpp v45, v11 row_shr:1 row_mask:0xf bank_mask:0xf bound_ctrl:1
	v_fma_f32 v42, v79, v42, v91
	v_mov_b32_dpp v15, v1 row_shr:1 row_mask:0xf bank_mask:0xf bound_ctrl:1
	v_fmac_f32_e32 v42, v83, v36
	v_fma_f32 v45, v105, v45, v73
	v_mov_b32_dpp v44, v4 row_shr:1 row_mask:0xf bank_mask:0xf bound_ctrl:1
	v_fmac_f32_e32 v42, v87, v33
	v_fmac_f32_e32 v45, v97, v15
	v_mul_f32_e32 v41, v42, v41
	v_fma_f32 v42, v80, v44, v92
	v_add_f32_e32 v44, 1.0, v47
	v_fmac_f32_e32 v45, v101, v31
	v_rcp_f32_e32 v44, v44
	v_mul_f32_e32 v47, 0xbfb8aa3b, v45
	v_exp_f32_e32 v47, v47
	v_mov_b32_dpp v22, v2 row_shr:1 row_mask:0xf bank_mask:0xf bound_ctrl:1
	v_fmac_f32_e32 v42, v84, v22
	v_fmac_f32_e32 v42, v88, v28
	v_mul_f32_e32 v43, v43, v44
	v_mul_f32_e32 v42, v42, v43
	v_add_f32_e32 v43, 1.0, v47
	v_rcp_f32_e32 v43, v43
	v_mov_b32_dpp v46, v5 row_shr:1 row_mask:0xf bank_mask:0xf bound_ctrl:1
	v_mov_b32_dpp v14, v3 row_shr:1 row_mask:0xf bank_mask:0xf bound_ctrl:1
	v_fma_f32 v44, v81, v46, v93
	v_fmac_f32_e32 v44, v85, v14
	v_cmp_gt_i32_e32 vcc, s70, v212
	v_fmac_f32_e32 v44, v89, v29
	v_mul_f32_e32 v43, v45, v43
	s_and_b64 s[6:7], s[10:11], vcc
	v_mul_f32_e32 v43, v44, v43
	v_cvt_pk_bf16_f32 v108, v40, v41
	v_cvt_pk_bf16_f32 v109, v42, v43
	s_and_saveexec_b64 s[14:15], s[6:7]
	s_cbranch_execz .LBB0_1814
	v_mov_b64_e32 v[40:41], s[30:31]
	v_mad_i64_i32 v[40:41], s[6:7], v212, s86, v[40:41]
	v_lshl_add_u64 v[40:41], v[178:179], 1, v[40:41]
	global_store_dwordx4 v[40:41], v[106:109], off sc1
.LBB0_1814:
	s_or_b64 exec, exec, s[14:15]
	v_fma_f32 v39, v102, v39, v70
	v_fmac_f32_e32 v39, v94, v34
	v_fmac_f32_e32 v39, v98, v24
	v_mul_f32_e32 v40, 0xbfb8aa3b, v39
	v_exp_f32_e32 v40, v40
	v_fma_f32 v37, v103, v37, v71
	v_fmac_f32_e32 v37, v95, v35
	v_fmac_f32_e32 v37, v99, v25
	v_add_f32_e32 v40, 1.0, v40
	v_rcp_f32_e32 v40, v40
	v_mul_f32_e32 v41, 0xbfb8aa3b, v37
	v_exp_f32_e32 v41, v41
	v_fma_f32 v38, v78, v38, v90
	v_fmac_f32_e32 v38, v82, v32
	v_fmac_f32_e32 v38, v86, v18
	v_mul_f32_e32 v39, v39, v40
	v_mul_f32_e32 v38, v38, v39
	v_add_f32_e32 v39, 1.0, v41
	v_rcp_f32_e32 v39, v39
	v_fma_f32 v23, v104, v23, v72
	v_fmac_f32_e32 v23, v96, v30
	v_fmac_f32_e32 v23, v100, v16
	v_mul_f32_e32 v37, v37, v39
	v_mul_f32_e32 v39, 0xbfb8aa3b, v23
	v_exp_f32_e32 v39, v39
	v_fma_f32 v36, v79, v36, v91
	v_fmac_f32_e32 v36, v83, v33
	v_fma_f32 v15, v105, v15, v73
	v_fmac_f32_e32 v36, v87, v19
	v_fmac_f32_e32 v15, v97, v31
	v_mul_f32_e32 v36, v36, v37
	v_add_f32_e32 v37, 1.0, v39
	v_fmac_f32_e32 v15, v101, v17
	v_rcp_f32_e32 v37, v37
	v_mul_f32_e32 v39, 0xbfb8aa3b, v15
	v_exp_f32_e32 v39, v39
	v_fma_f32 v22, v80, v22, v92
	v_fmac_f32_e32 v22, v84, v28
	v_fmac_f32_e32 v22, v88, v8
	v_mul_f32_e32 v23, v23, v37
	v_mul_f32_e32 v22, v22, v23
	v_add_f32_e32 v23, 1.0, v39
	v_rcp_f32_e32 v23, v23
	v_fma_f32 v14, v81, v14, v93
	v_fmac_f32_e32 v14, v85, v29
	v_cmp_gt_i32_e32 vcc, s70, v215
	v_fmac_f32_e32 v14, v89, v9
	v_mul_f32_e32 v15, v15, v23
	s_and_b64 s[6:7], s[10:11], vcc
	v_mul_f32_e32 v14, v14, v15
	v_cvt_pk_bf16_f32 v76, v38, v36
	v_cvt_pk_bf16_f32 v77, v22, v14
	s_and_saveexec_b64 s[14:15], s[6:7]
	s_cbranch_execz .LBB0_1816
	v_mov_b64_e32 v[14:15], s[30:31]
	v_mad_i64_i32 v[14:15], s[6:7], v215, s86, v[14:15]
	v_lshl_add_u64 v[14:15], v[178:179], 1, v[14:15]
	global_store_dwordx4 v[14:15], v[74:77], off sc1
; __device__ __forceinline__ unsigned cvt_pk_bf16(float lo, float hi) { unsigned r; asm volatile("v_cvt_pk_bf16_f32 %0, %1, %2" : "=v"(r) : "v"(lo), "v"(hi)); return r; }
;     __device__ __forceinline__ void operator()(const f32x4 (&acc)[2][2][4][2], const Unit& u, int wr, int wc, int fr, int fq) const {
;     ...
;                 for (int m = 0; m < 4; ++m) {
;                     u32x2_t w; float o[4];
; #pragma unroll
;                     for (int e = 0; e < 4; ++e) {
;                         const float g1 = m >= 1 ? xg[m - (m >= 1 ? 1 : 0)][e] : pg3[e], g2 = m >= 2 ? xg[m - (m >= 2 ? 2 : 0)][e] : (m == 1 ? pg3[e] : pg2[e]);
;                         const float v1 = m >= 1 ? xv[m - (m >= 1 ? 1 : 0)][e] : pv3[e], v2 = m >= 2 ? xv[m - (m >= 2 ? 2 : 0)][e] : (m == 1 ? pv3[e] : pv2[e]);
;                         const float cg_ = bg[e] + w0g[e] * g2 + w1g[e] * g1 + w2g[e] * xg[m][e];
;                         const float cv_ = bv[e] + w0v[e] * v2 + w1v[e] * v1 + w2v[e] * xv[m][e];
;                         o[e] = cg_ * __builtin_amdgcn_rcpf(1.0f + __expf(-cg_)) * cv_;
;                     }
;                     w.x = cvt_pk_bf16(o[0], o[1]); w.y = cvt_pk_bf16(o[2], o[3]);
;                     const int g = g0 + m;
;                     if (n == 0) stash[ai][m] = w;
;                     else if ((fr > 0 || m >= 2) && g < TT) { u32x4 ww; ww.x = stash[ai][m].x; ww.y = stash[ai][m].y; ww.z = w.x; ww.w = w.y; *(u32x4*)(G + (size_t)g * DFF_ + f0 - 4) = ww; }
.LBB0_1816:
	s_or_b64 exec, exec, s[14:15]
	v_fma_f32 v14, v102, v34, v70
	v_fmac_f32_e32 v14, v94, v24
	v_fmac_f32_e32 v14, v98, v26
	v_mul_f32_e32 v15, 0xbfb8aa3b, v14
	v_exp_f32_e32 v15, v15
	v_fma_f32 v23, v103, v35, v71
	v_fmac_f32_e32 v23, v95, v25
	v_fmac_f32_e32 v23, v99, v27
	v_fma_f32 v22, v78, v32, v90
	v_add_f32_e32 v15, 1.0, v15
	v_mul_f32_e32 v32, 0xbfb8aa3b, v23
	v_rcp_f32_e32 v15, v15
	v_exp_f32_e32 v32, v32
	v_fmac_f32_e32 v22, v82, v18
	v_fmac_f32_e32 v22, v86, v20
	v_mul_f32_e32 v14, v14, v15
	v_add_f32_e32 v15, 1.0, v32
	v_rcp_f32_e32 v15, v15
	v_mul_f32_e32 v14, v22, v14
	v_fma_f32 v22, v79, v33, v91
	v_fmac_f32_e32 v22, v83, v19
	v_mul_f32_e32 v15, v23, v15
	v_fma_f32 v23, v104, v30, v72
	v_fmac_f32_e32 v23, v96, v16
	v_fmac_f32_e32 v23, v100, v10
	v_mul_f32_e32 v30, 0xbfb8aa3b, v23
	v_exp_f32_e32 v30, v30
	v_fmac_f32_e32 v22, v87, v21
	v_mul_f32_e32 v15, v22, v15
	v_fma_f32 v22, v80, v28, v92
	v_add_f32_e32 v28, 1.0, v30
	v_fma_f32 v30, v105, v31, v73
	v_fmac_f32_e32 v30, v97, v17
	v_fmac_f32_e32 v30, v101, v11
	v_rcp_f32_e32 v28, v28
	v_mul_f32_e32 v31, 0xbfb8aa3b, v30
	v_exp_f32_e32 v31, v31
	v_fmac_f32_e32 v22, v84, v8
	v_fmac_f32_e32 v22, v88, v4
	v_mul_f32_e32 v23, v23, v28
	v_mul_f32_e32 v22, v22, v23
	v_add_f32_e32 v23, 1.0, v31
	v_rcp_f32_e32 v23, v23
	v_fma_f32 v28, v81, v29, v93
	v_fmac_f32_e32 v28, v85, v9
	v_fmac_f32_e32 v28, v89, v5
	v_mul_f32_e32 v23, v30, v23
	v_cmp_gt_i32_e32 vcc, s87, v212
	v_mul_f32_e32 v23, v28, v23
	v_cvt_pk_bf16_f32 v68, v14, v15
	v_cvt_pk_bf16_f32 v69, v22, v23
	s_and_saveexec_b64 s[14:15], vcc
	s_cbranch_execz .LBB0_1818
	v_mov_b64_e32 v[14:15], s[30:31]
	v_mad_i64_i32 v[14:15], s[6:7], v214, s86, v[14:15]
	v_lshl_add_u64 v[14:15], v[178:179], 1, v[14:15]
	global_store_dwordx4 v[14:15], v[66:69], off sc1
.LBB0_1818:
	s_or_b64 exec, exec, s[14:15]
	v_fma_f32 v14, v102, v24, v70
	v_fmac_f32_e32 v14, v94, v26
	v_fmac_f32_e32 v14, v98, v12
	v_mul_f32_e32 v12, 0xbfb8aa3b, v14
	v_exp_f32_e32 v12, v12
	v_fma_f32 v15, v78, v18, v90
	v_fma_f32 v18, v103, v25, v71
	v_fmac_f32_e32 v18, v95, v27
	v_fmac_f32_e32 v18, v99, v13
	v_add_f32_e32 v12, 1.0, v12
	v_mul_f32_e32 v13, 0xbfb8aa3b, v18
	v_rcp_f32_e32 v12, v12
	v_exp_f32_e32 v13, v13
	v_fmac_f32_e32 v15, v82, v20
	v_fmac_f32_e32 v15, v86, v6
	v_mul_f32_e32 v6, v14, v12
	v_add_f32_e32 v12, 1.0, v13
	v_rcp_f32_e32 v12, v12
	v_fma_f32 v13, v79, v19, v91
	v_fmac_f32_e32 v13, v83, v21
	v_fmac_f32_e32 v13, v87, v7
	v_mul_f32_e32 v7, v18, v12
	v_fma_f32 v12, v104, v16, v72
	v_fmac_f32_e32 v73, v105, v17
	v_fmac_f32_e32 v12, v96, v10
	v_fmac_f32_e32 v73, v97, v11
	v_fmac_f32_e32 v12, v100, v0
	v_fmac_f32_e32 v73, v101, v1
	v_mul_f32_e32 v0, 0xbfb8aa3b, v12
	v_mul_f32_e32 v1, 0xbfb8aa3b, v73
	v_exp_f32_e32 v0, v0
	v_exp_f32_e32 v1, v1
	v_fma_f32 v8, v80, v8, v92
	v_fmac_f32_e32 v93, v81, v9
	v_add_f32_e32 v0, 1.0, v0
	v_add_f32_e32 v1, 1.0, v1
	v_rcp_f32_e32 v0, v0
	v_rcp_f32_e32 v1, v1
	v_fmac_f32_e32 v8, v84, v4
	v_fmac_f32_e32 v93, v85, v5
	v_fmac_f32_e32 v8, v88, v2
	v_mul_f32_e32 v0, v12, v0
	v_fmac_f32_e32 v93, v89, v3
	v_mul_f32_e32 v1, v73, v1
	v_cmp_gt_i32_e32 vcc, s88, v212
	v_mul_f32_e32 v6, v15, v6
	v_mul_f32_e32 v7, v13, v7
	v_mul_f32_e32 v0, v8, v0
	v_mul_f32_e32 v1, v93, v1
	v_cvt_pk_bf16_f32 v66, v6, v7
	v_cvt_pk_bf16_f32 v67, v0, v1
	s_and_saveexec_b64 s[14:15], vcc
	s_cbranch_execz .LBB0_1820
	v_mov_b64_e32 v[0:1], s[30:31]
	v_mad_i64_i32 v[0:1], s[6:7], v213, s86, v[0:1]
	v_lshl_add_u64 v[0:1], v[178:179], 1, v[0:1]
	global_store_dwordx4 v[0:1], v[64:67], off sc1

; #define LAS __attribute__((address_space(3)))
; __device__ __forceinline__ unsigned cvtpk(float lo, float hi) { f32x2 v = {lo, hi}; bf16x2_t b = __builtin_convertvector(v, bf16x2_t); return __builtin_bit_cast(unsigned, b); }
; __device__ __forceinline__ void witem_store(const WItem& w, int K, bf16_t* WT, int kvperm, LAS float* scr, int item, int nblk, int lane) {
;     ...
;     for (int i = 0; i < 8; ++i) { LAS float* d = scr + (8 * i + rr) * 33 + col; const float g = w.g[i]; d[0] = w.v[i].x * g; d[1] = w.v[i].y * g; d[2] = w.v[i].z * g; d[3] = w.v[i].w * g; }
;     asm volatile("s_waitcnt lgkmcnt(0)" ::: "memory");
;     const int c = lane & 7;
; #pragma unroll
;     for (int j = 0; j < 4; ++j) { const int n = (lane >> 3) + 8 * j; const LAS float* s = scr + (8 * c) * 33 + n;
;         u32x4 o; o.x = cvtpk(s[0 * 33], s[1 * 33]); o.y = cvtpk(s[2 * 33], s[3 * 33]); o.z = cvtpk(s[4 * 33], s[5 * 33]); o.w = cvtpk(s[6 * 33], s[7 * 33]);
;         int nr = n0 + n; if (kvperm == 1) { const int hh = nr >> 8, ww = nr & 255; nr = (ww < 128) ? hh * 128 + ww : 2048 + hh * 128 + (ww - 128); }
;         else if (kvperm == 2) { const int isv = nr >= 5632, f = isv ? nr - 5632 : nr; nr = (f >> 7) * 256 + isv * 128 + (f & 127); }
;         *(u32x4*)(WT + (size_t)nr * K + k0 + 8 * c) = o; }
;     ...
;     while (it < i1) {
;         cur = nxt;
;         const int nit = it + NGW;
;         if (nit < i1) witem_load(nxt, W, N, gk, nit, nblk, lane);
;         witem_store(cur, K, WT, kvperm, scr, it, nblk, lane);
;         it = nit;
.LBB0_1844:
	v_pk_mul_f32 v[2:3], v[12:13], v[72:73] op_sel_hi:[1,0]
	ds_write2_b32 v79, v2, v3 offset1:1
	v_pk_mul_f32 v[2:3], v[14:15], v[72:73] op_sel_hi:[1,0]
	ds_write2_b32 v79, v2, v3 offset0:2 offset1:3
	v_pk_mul_f32 v[2:3], v[4:5], v[74:75] op_sel_hi:[1,0]
	v_add_u32_e32 v4, 0x420, v79
	ds_write2_b32 v4, v2, v3 offset1:1
	v_pk_mul_f32 v[2:3], v[6:7], v[74:75] op_sel_hi:[1,0]
	v_add_u32_e32 v4, 0x428, v79
	ds_write2_b32 v4, v2, v3 offset1:1
	v_pk_mul_f32 v[2:3], v[24:25], v[76:77] op_sel_hi:[1,0]
	v_add_u32_e32 v4, 0x840, v79
	ds_write2_b32 v4, v2, v3 offset1:1
	v_pk_mul_f32 v[2:3], v[26:27], v[76:77] op_sel_hi:[1,0]
	v_add_u32_e32 v4, 0x848, v79
	ds_write2_b32 v4, v2, v3 offset1:1
	v_pk_mul_f32 v[2:3], v[20:21], v[78:79] op_sel_hi:[1,0]
	v_add_u32_e32 v4, 0xc60, v79
	ds_write2_b32 v4, v2, v3 offset1:1
	v_pk_mul_f32 v[2:3], v[22:23], v[78:79] op_sel_hi:[1,0]
	v_add_u32_e32 v4, 0xc68, v79
	ds_write2_b32 v4, v2, v3 offset1:1
	v_pk_mul_f32 v[2:3], v[36:37], v[80:81] op_sel_hi:[1,0]
	v_add_u32_e32 v4, 0x1080, v79
	ds_write2_b32 v4, v2, v3 offset1:1
	v_pk_mul_f32 v[2:3], v[38:39], v[80:81] op_sel_hi:[1,0]
	v_add_u32_e32 v4, 0x1088, v79
	ds_write2_b32 v4, v2, v3 offset1:1
	v_pk_mul_f32 v[2:3], v[28:29], v[82:83] op_sel_hi:[1,0]
	v_add_u32_e32 v4, 0x14a0, v79
	ds_write2_b32 v4, v2, v3 offset1:1
	v_pk_mul_f32 v[2:3], v[30:31], v[82:83] op_sel_hi:[1,0]
	v_add_u32_e32 v4, 0x14a8, v79
	ds_write2_b32 v4, v2, v3 offset1:1
	s_waitcnt vmcnt(7)
	v_pk_mul_f32 v[2:3], v[48:49], v[84:85] op_sel_hi:[1,0]
	v_add_u32_e32 v4, 0x18c0, v79
	s_mul_hi_i32 s6, s6, 0x2e8ba2e9
	ds_write2_b32 v4, v2, v3 offset1:1
	v_pk_mul_f32 v[2:3], v[50:51], v[84:85] op_sel_hi:[1,0]
	v_add_u32_e32 v4, 0x18c8, v79
	s_lshr_b32 s12, s6, 31
	s_ashr_i32 s6, s6, 6
	ds_write2_b32 v4, v2, v3 offset1:1
	s_waitcnt vmcnt(6)
	v_pk_mul_f32 v[2:3], v[44:45], v[86:87] op_sel_hi:[1,0]
	v_add_u32_e32 v4, 0x1ce0, v79
	s_add_i32 s6, s6, s12
	ds_write2_b32 v4, v2, v3 offset1:1
	v_pk_mul_f32 v[2:3], v[46:47], v[86:87] op_sel_hi:[1,0]
	v_add_u32_e32 v4, 0x1ce8, v79
	s_lshl_b32 s12, s6, 6
	ds_write2_b32 v4, v2, v3 offset1:1
	s_mulk_i32 s6, 0xd400
	s_waitcnt lgkmcnt(0)
	s_add_i32 s6, s6, s7
	ds_read2_b32 v[6:7], v77 offset0:33 offset1:41
	ds_read2_b32 v[12:13], v77 offset1:8
	ds_read2_b32 v[14:15], v77 offset0:66 offset1:74
	ds_read2_b32 v[20:21], v77 offset0:99 offset1:107
	ds_read2_b32 v[22:23], v77 offset0:132 offset1:140
	ds_read2_b32 v[24:25], v77 offset0:165 offset1:173
	ds_read2_b32 v[26:27], v77 offset0:198 offset1:206
	ds_read2_b32 v[28:29], v77 offset0:231 offset1:239
	v_add_u32_e32 v38, s6, v83
	s_waitcnt lgkmcnt(6)
	v_cvt_pk_bf16_f32 v2, v12, v6
	v_add_u32_e32 v6, 0xffffea00, v38
	v_cmp_lt_i32_e32 vcc, s18, v38
	s_waitcnt lgkmcnt(4)
	v_cvt_pk_bf16_f32 v3, v14, v20
	s_ashr_i32 s13, s12, 31
	v_cndmask_b32_e32 v6, v38, v6, vcc
	v_lshlrev_b32_e32 v12, 1, v6
	v_and_b32_e32 v12, 0xffffff00, v12
	v_cndmask_b32_e32 v14, 0, v81, vcc
	v_and_b32_e32 v6, 0x67, v6
	v_or3_b32 v36, v6, v14, v12
	v_ashrrev_i32_e32 v37, 31, v36
	v_lshl_add_u64 v[30:31], s[12:13], 1, v[70:71]
	v_lshlrev_b64 v[36:37], 12, v[36:37]
	s_waitcnt lgkmcnt(2)
	v_cvt_pk_bf16_f32 v4, v22, v24
	s_waitcnt lgkmcnt(0)
	v_cvt_pk_bf16_f32 v5, v26, v28
	v_lshl_add_u64 v[36:37], v[30:31], 0, v[36:37]
	v_add_u32_e32 v6, 8, v38
	global_store_dwordx4 v[36:37], v[2:5], off sc1
	v_cmp_lt_i32_e32 vcc, s18, v6
	s_waitcnt vmcnt(3)
	v_mov_b64_e32 v[48:49], v[60:61]
	v_cvt_pk_bf16_f32 v2, v13, v7
	v_add_u32_e32 v7, 0xffffea08, v38
	v_cndmask_b32_e32 v6, v6, v7, vcc
	v_lshlrev_b32_e32 v7, 1, v6
	v_and_b32_e32 v7, 0xffffff00, v7
	v_cndmask_b32_e32 v12, 0, v81, vcc
	v_and_b32_e32 v6, 0x6f, v6
	v_or3_b32 v6, v6, v12, v7
	v_ashrrev_i32_e32 v7, 31, v6
	v_lshlrev_b64 v[6:7], 12, v[6:7]
	v_cvt_pk_bf16_f32 v3, v15, v21
	v_cvt_pk_bf16_f32 v4, v23, v25
	v_cvt_pk_bf16_f32 v5, v27, v29
	v_lshl_add_u64 v[6:7], v[30:31], 0, v[6:7]
	ds_read2_b32 v[12:13], v77 offset0:16 offset1:24
	ds_read2_b32 v[14:15], v77 offset0:49 offset1:57
	ds_read2_b32 v[20:21], v77 offset0:82 offset1:90
	ds_read2_b32 v[22:23], v77 offset0:115 offset1:123
	ds_read2_b32 v[24:25], v77 offset0:148 offset1:156
	ds_read2_b32 v[26:27], v77 offset0:181 offset1:189
	ds_read2_b32 v[28:29], v77 offset0:214 offset1:222
	ds_read2_b32 v[36:37], v77 offset0:247 offset1:255
	global_store_dwordx4 v[6:7], v[2:5], off sc1
	v_add_u32_e32 v6, 16, v38
	v_add_u32_e32 v7, 0xffffea10, v38
	v_cmp_lt_i32_e32 vcc, s18, v6
	s_waitcnt lgkmcnt(6)
	v_cvt_pk_bf16_f32 v2, v12, v14
	s_waitcnt lgkmcnt(4)
	v_cvt_pk_bf16_f32 v3, v20, v22
	v_cndmask_b32_e32 v6, v6, v7, vcc
	v_lshlrev_b32_e32 v7, 1, v6
	v_and_b32_e32 v7, 0xffffff00, v7
	v_cndmask_b32_e32 v12, 0, v81, vcc
	v_and_b32_e32 v6, 0x77, v6
	v_or3_b32 v6, v6, v12, v7
	v_ashrrev_i32_e32 v7, 31, v6
	v_lshlrev_b64 v[6:7], 12, v[6:7]
	s_waitcnt lgkmcnt(2)
	v_cvt_pk_bf16_f32 v4, v24, v26
	s_waitcnt lgkmcnt(0)
	v_cvt_pk_bf16_f32 v5, v28, v36
	v_lshl_add_u64 v[6:7], v[30:31], 0, v[6:7]
	global_store_dwordx4 v[6:7], v[2:5], off sc1
	s_waitcnt vmcnt(4)
	v_mov_b64_e32 v[44:45], v[64:65]
	v_add_u32_e32 v83, s14, v83
	v_add_u32_e32 v2, 24, v38
	v_add_u32_e32 v3, 0xffffea18, v38
	v_cmp_lt_i32_e32 vcc, s18, v2
	v_cvt_pk_bf16_f32 v5, v29, v37
	v_mov_b64_e32 v[36:37], v[52:53]
	v_cndmask_b32_e32 v2, v2, v3, vcc
	v_lshlrev_b32_e32 v3, 1, v2
	v_and_b32_e32 v3, 0xffffff00, v3
	v_cndmask_b32_e32 v4, 0, v81, vcc
	v_and_b32_e32 v2, 0x7f, v2
	v_or3_b32 v6, v2, v4, v3
	v_ashrrev_i32_e32 v7, 31, v6
	v_lshlrev_b64 v[6:7], 12, v[6:7]
	v_cvt_pk_bf16_f32 v2, v13, v15
	v_cvt_pk_bf16_f32 v3, v21, v23
	v_cvt_pk_bf16_f32 v4, v25, v27
	v_lshl_add_u64 v[6:7], v[30:31], 0, v[6:7]
	global_store_dwordx4 v[6:7], v[2:5], off sc1
	s_waitcnt lgkmcnt(0)
	v_mov_b64_e32 v[12:13], v[16:17]
	v_mov_b64_e32 v[24:25], v[32:33]
	v_mov_b64_e32 v[4:5], v[8:9]
	v_mov_b64_e32 v[20:21], v[40:41]
	v_mov_b64_e32 v[28:29], v[56:57]
	s_add_i32 s19, s19, s14
	v_add_u32_e32 v73, s14, v73
	s_andn2_b64 vcc, exec, s[10:11]
	s_mov_b32 s6, s20
	v_mov_b64_e32 v[14:15], v[18:19]
	v_mov_b64_e32 v[6:7], v[10:11]
	v_mov_b64_e32 v[26:27], v[34:35]
	v_mov_b64_e32 v[22:23], v[42:43]
	v_mov_b64_e32 v[38:39], v[54:55]
	v_mov_b64_e32 v[30:31], v[58:59]
	v_mov_b64_e32 v[50:51], v[62:63]
	v_mov_b64_e32 v[46:47], v[66:67]
	v_mov_b32_e32 v72, v85
	v_mov_b32_e32 v74, v87
	v_mov_b32_e32 v76, v89
	v_mov_b32_e32 v78, v94
	v_mov_b32_e32 v80, v95
	v_mov_b32_e32 v82, v96
	v_mov_b32_e32 v84, v97
	s_waitcnt vmcnt(4)
	v_mov_b32_e32 v86, v1
	s_cbranch_vccz .LBB0_1862

; __device__ __forceinline__ unsigned cvt_pk_bf16(float lo, float hi) { unsigned r; asm volatile("v_cvt_pk_bf16_f32 %0, %1, %2" : "=v"(r) : "v"(lo), "v"(hi)); return r; }
;     __device__ __forceinline__ void operator()(const f32x4 (&acc)[2][2][4][2], const Unit& u, int wr, int wc, int fr, int fq) const {
;     ...
;             for (int n = 0; n < 2; ++n) bv[bj][n] = bias ? *(const f32x4*)(bias + col0 + bj * HALF + 4 * n) : (f32x4){0.f, 0.f, 0.f, 0.f};
;         float* ssp = ssout + (size_t)(u.pn * 4 + wc);
; #pragma unroll
;         for (int ai = 0; ai < 2; ++ai) {
;             u32x4 old[4][2];
; #pragma unroll
;             for (int m = 0; m < 4; ++m)
; #pragma unroll
;                 for (int bj = 0; bj < 2; ++bj) old[m][bj] = *(const u32x4*)(HB + (size_t)(row0 + ai * HALF + m * 16) * ldc + col0 + bj * HALF);
; #pragma unroll
;             for (int m = 0; m < 4; ++m) { const int row = row0 + ai * HALF + m * 16; float ss = 0.f;
; #pragma unroll
;                 for (int bj = 0; bj < 2; ++bj) { const u32x4 ow = old[m][bj];
;                     f32x4 v0 = (acc[ai][bj][m][0] + bv[bj][0]) * accs, v1 = (acc[ai][bj][m][1] + bv[bj][1]) * accs;
;                     v0[0] += __uint_as_float(ow.x << 16); v0[1] += __uint_as_float(ow.x & 0xffff0000u); v0[2] += __uint_as_float(ow.y << 16); v0[3] += __uint_as_float(ow.y & 0xffff0000u);
;                     v1[0] += __uint_as_float(ow.z << 16); v1[1] += __uint_as_float(ow.z & 0xffff0000u); v1[2] += __uint_as_float(ow.w << 16); v1[3] += __uint_as_float(ow.w & 0xffff0000u);
;                     ss += (v0[0] * v0[0] + v0[1] * v0[1]) + (v0[2] * v0[2] + v0[3] * v0[3]) + (v1[0] * v1[0] + v1[1] * v1[1]) + (v1[2] * v1[2] + v1[3] * v1[3]);
;                     u32x4 w; w.x = cvt_pk_bf16(v0[0], v0[1]); w.y = cvt_pk_bf16(v0[2], v0[3]); w.z = cvt_pk_bf16(v1[0], v1[1]); w.w = cvt_pk_bf16(v1[2], v1[3]);
;                     *(u32x4*)(HB + (size_t)row * ldc + col0 + bj * HALF) = w; }
;                 ss += __shfl_xor(ss, 16); ss += __shfl_xor(ss, 32);
;                 if (fq == 0) ssp[(size_t)row * 32] = ss; }
.LBB0_1940:
	v_lshl_or_b32 v152, s6, 8, v166
	v_ashrrev_i32_e32 v153, 31, v152
	v_lshl_add_u32 v154, s7, 8, v164
	v_lshlrev_b64 v[180:181], 1, v[152:153]
	v_ashrrev_i32_e32 v155, 31, v154
	v_lshl_add_u64 v[156:157], s[16:17], 0, v[180:181]
	v_lshlrev_b64 v[182:183], 12, v[154:155]
	v_lshl_add_u64 v[128:129], v[156:157], 0, v[182:183]
	global_load_dwordx4 v[172:175], v[128:129], off
	global_load_dwordx4 v[176:179], v[128:129], off offset:256
	v_or_b32_e32 v162, 16, v154
	v_or_b32_e32 v160, 32, v154
	v_or_b32_e32 v158, 48, v154
	v_ashrrev_i32_e32 v163, 31, v162
	v_ashrrev_i32_e32 v161, 31, v160
	v_pk_add_f32 v[196:197], v[114:115], 0 op_sel_hi:[1,0]
	v_pk_add_f32 v[198:199], v[112:113], 0 op_sel_hi:[1,0]
	v_ashrrev_i32_e32 v159, 31, v158
	v_lshlrev_b64 v[112:113], 12, v[162:163]
	v_lshlrev_b64 v[114:115], 12, v[160:161]
	v_pk_add_f32 v[194:195], v[116:117], 0 op_sel_hi:[1,0]
	v_lshlrev_b64 v[116:117], 12, v[158:159]
	v_lshl_add_u64 v[112:113], v[156:157], 0, v[112:113]
	v_lshl_add_u64 v[114:115], v[156:157], 0, v[114:115]
	v_pk_add_f32 v[184:185], v[126:127], 0 op_sel_hi:[1,0]
	v_pk_add_f32 v[186:187], v[124:125], 0 op_sel_hi:[1,0]
	v_pk_add_f32 v[188:189], v[122:123], 0 op_sel_hi:[1,0]
	v_pk_add_f32 v[190:191], v[120:121], 0 op_sel_hi:[1,0]
	v_pk_add_f32 v[192:193], v[118:119], 0 op_sel_hi:[1,0]
	v_lshl_add_u64 v[200:201], v[156:157], 0, v[116:117]
	global_load_dwordx4 v[132:135], v[112:113], off
	global_load_dwordx4 v[128:131], v[112:113], off offset:256
	global_load_dwordx4 v[124:127], v[114:115], off
	global_load_dwordx4 v[120:123], v[114:115], off offset:256
	global_load_dwordx4 v[116:119], v[200:201], off
	s_nop 0
	global_load_dwordx4 v[112:115], v[200:201], off offset:256
	s_lshl_b32 s6, s6, 2
	s_or_b32 s6, s6, s44
	s_ashr_i32 s7, s6, 31
	s_lshl_b64 s[6:7], s[6:7], 2
	s_add_u32 s24, s42, s6
	s_addc_u32 s25, s43, s7
	s_waitcnt vmcnt(0)
	v_lshlrev_b32_e32 v171, 16, v172
	v_and_b32_e32 v172, 0xffff0000, v172
	v_lshlrev_b32_e32 v200, 16, v173
	v_and_b32_e32 v173, 0xffff0000, v173
	v_lshlrev_b32_e32 v201, 16, v174
	v_lshlrev_b32_e32 v202, 16, v175
	v_lshlrev_b32_e32 v203, 16, v176
	v_and_b32_e32 v176, 0xffff0000, v176
	v_lshlrev_b32_e32 v206, 16, v177
	v_and_b32_e32 v177, 0xffff0000, v177
	v_add_f32_e32 v172, v187, v172
	v_add_f32_e32 v173, v185, v173
	v_and_b32_e32 v175, 0xffff0000, v175
	v_lshlrev_b32_e32 v207, 16, v178
	v_and_b32_e32 v178, 0xffff0000, v178
	v_lshlrev_b32_e32 v208, 16, v179
	v_add_f32_e32 v171, v186, v171
	v_add_f32_e32 v184, v184, v200
	v_add_f32_e32 v185, v190, v201
	v_add_f32_e32 v186, v188, v202
	v_add_f32_e32 v188, v195, v176
	v_add_f32_e32 v190, v193, v177
	v_mul_f32_e32 v176, v172, v172
	v_mul_f32_e32 v177, v173, v173
	v_and_b32_e32 v174, 0xffff0000, v174
	v_add_f32_e32 v175, v189, v175
	v_add_f32_e32 v187, v194, v203
	v_add_f32_e32 v189, v192, v206
	v_add_f32_e32 v178, v199, v178
	v_add_f32_e32 v192, v196, v208
	v_mul_f32_e32 v195, v188, v188
	v_mul_f32_e32 v196, v190, v190
	v_fmac_f32_e32 v176, v171, v171
	v_fmac_f32_e32 v177, v184, v184
	v_and_b32_e32 v179, 0xffff0000, v179
	v_add_f32_e32 v174, v191, v174
	v_add_f32_e32 v191, v198, v207
	v_cvt_pk_bf16_f32 v172, v171, v172
	v_fmac_f32_e32 v195, v187, v187
	v_add_f32_e32 v171, v176, v177
	v_fmac_f32_e32 v196, v189, v189
	v_mul_f32_e32 v177, v178, v178
	v_add_f32_e32 v179, v197, v179
	v_mul_f32_e32 v193, v174, v174
	v_add_f32_e32 v176, v195, v196
	v_fmac_f32_e32 v177, v191, v191
	v_mul_f32_e32 v194, v175, v175
	v_fmac_f32_e32 v193, v185, v185
	v_add_f32_e32 v176, v177, v176
	v_mul_f32_e32 v177, v179, v179
	v_fmac_f32_e32 v194, v186, v186
	v_add_f32_e32 v171, v193, v171
	v_fmac_f32_e32 v177, v192, v192
	v_add_f32_e32 v171, v194, v171
	v_add_f32_e32 v176, v177, v176
	v_cvt_pk_bf16_f32 v173, v184, v173
	v_add_f32_e32 v184, v171, v176
	v_and_b32_e32 v176, 64, v170
	v_cvt_pk_bf16_f32 v174, v185, v174
	v_xor_b32_e32 v171, 16, v170
	v_add_u32_e32 v185, 64, v176
	v_cmp_lt_i32_e32 vcc, v171, v185
	v_cvt_pk_bf16_f32 v175, v186, v175
	v_lshl_add_u64 v[176:177], s[16:17], 0, v[182:183]
	v_lshl_add_u64 v[180:181], v[176:177], 0, v[180:181]
	v_cndmask_b32_e32 v171, v170, v171, vcc
	v_lshlrev_b32_e32 v171, 2, v171
	ds_bpermute_b32 v186, v171, v184
	global_store_dwordx4 v[180:181], v[172:175], off sc1
	v_cvt_pk_bf16_f32 v176, v187, v188
	v_cvt_pk_bf16_f32 v177, v189, v190
	v_cvt_pk_bf16_f32 v178, v191, v178
	v_cvt_pk_bf16_f32 v179, v192, v179
	global_store_dwordx4 v[180:181], v[176:179], off offset:256 sc1
	s_nop 0
	v_xor_b32_e32 v172, 32, v170
	v_cmp_lt_i32_e32 vcc, v172, v185
	s_waitcnt lgkmcnt(0)
	v_add_f32_e32 v173, v184, v186
	v_cndmask_b32_e32 v172, v170, v172, vcc
	v_lshlrev_b32_e32 v172, 2, v172
	ds_bpermute_b32 v174, v172, v173
	s_and_saveexec_b64 s[26:27], s[10:11]
	s_cbranch_execz .LBB0_1942
	v_lshlrev_b64 v[176:177], 7, v[154:155]
	v_lshl_add_u64 v[176:177], s[24:25], 0, v[176:177]
	s_waitcnt lgkmcnt(0)
	v_add_f32_e32 v155, v173, v174
	global_store_dword v[176:177], v155, off
; __device__ __forceinline__ unsigned cvt_pk_bf16(float lo, float hi) { unsigned r; asm volatile("v_cvt_pk_bf16_f32 %0, %1, %2" : "=v"(r) : "v"(lo), "v"(hi)); return r; }
;     __device__ __forceinline__ void operator()(const f32x4 (&acc)[2][2][4][2], const Unit& u, int wr, int wc, int fr, int fq) const {
;     ...
;             for (int m = 0; m < 4; ++m) { const int row = row0 + ai * HALF + m * 16; float ss = 0.f;
; #pragma unroll
;                 for (int bj = 0; bj < 2; ++bj) { const u32x4 ow = old[m][bj];
;                     f32x4 v0 = (acc[ai][bj][m][0] + bv[bj][0]) * accs, v1 = (acc[ai][bj][m][1] + bv[bj][1]) * accs;
;                     v0[0] += __uint_as_float(ow.x << 16); v0[1] += __uint_as_float(ow.x & 0xffff0000u); v0[2] += __uint_as_float(ow.y << 16); v0[3] += __uint_as_float(ow.y & 0xffff0000u);
;                     v1[0] += __uint_as_float(ow.z << 16); v1[1] += __uint_as_float(ow.z & 0xffff0000u); v1[2] += __uint_as_float(ow.w << 16); v1[3] += __uint_as_float(ow.w & 0xffff0000u);
;                     ss += (v0[0] * v0[0] + v0[1] * v0[1]) + (v0[2] * v0[2] + v0[3] * v0[3]) + (v1[0] * v1[0] + v1[1] * v1[1]) + (v1[2] * v1[2] + v1[3] * v1[3]);
;                     u32x4 w; w.x = cvt_pk_bf16(v0[0], v0[1]); w.y = cvt_pk_bf16(v0[2], v0[3]); w.z = cvt_pk_bf16(v1[0], v1[1]); w.w = cvt_pk_bf16(v1[2], v1[3]);
;                     *(u32x4*)(HB + (size_t)row * ldc + col0 + bj * HALF) = w; }
;                 ss += __shfl_xor(ss, 16); ss += __shfl_xor(ss, 32);
;                 if (fq == 0) ssp[(size_t)row * 32] = ss; }
.LBB0_1942:
	s_or_b64 exec, exec, s[26:27]
	v_pk_add_f32 v[108:109], v[108:109], 0 op_sel_hi:[1,0]
	v_lshlrev_b32_e32 v155, 16, v132
	v_and_b32_e32 v132, 0xffff0000, v132
	v_pk_add_f32 v[110:111], v[110:111], 0 op_sel_hi:[1,0]
	v_add_f32_e32 v109, v109, v132
	v_lshlrev_b32_e32 v132, 16, v133
	v_add_f32_e32 v110, v110, v132
	v_and_b32_e32 v132, 0xffff0000, v133
	v_pk_add_f32 v[104:105], v[104:105], 0 op_sel_hi:[1,0]
	v_add_f32_e32 v111, v111, v132
	v_lshlrev_b32_e32 v132, 16, v134
	v_add_f32_e32 v132, v104, v132
	v_and_b32_e32 v104, 0xffff0000, v134
	v_pk_add_f32 v[106:107], v[106:107], 0 op_sel_hi:[1,0]
	v_add_f32_e32 v133, v105, v104
	v_lshlrev_b32_e32 v104, 16, v135
	v_add_f32_e32 v134, v106, v104
	v_and_b32_e32 v104, 0xffff0000, v135
	v_add_f32_e32 v108, v108, v155
	v_add_f32_e32 v107, v107, v104
	v_mul_f32_e32 v104, v109, v109
	v_mul_f32_e32 v105, v111, v111
	v_fmac_f32_e32 v104, v108, v108
	v_fmac_f32_e32 v105, v110, v110
	v_add_f32_e32 v104, v104, v105
	v_mul_f32_e32 v105, v133, v133
	v_fmac_f32_e32 v105, v132, v132
	v_add_f32_e32 v104, v105, v104
	v_mul_f32_e32 v105, v107, v107
	v_fmac_f32_e32 v105, v134, v134
	v_add_f32_e32 v135, v105, v104
	v_cvt_pk_bf16_f32 v104, v108, v109
	v_pk_add_f32 v[100:101], v[100:101], 0 op_sel_hi:[1,0]
	v_lshlrev_b32_e32 v108, 16, v128
	v_add_f32_e32 v100, v100, v108
	v_and_b32_e32 v108, 0xffff0000, v128
	v_pk_add_f32 v[102:103], v[102:103], 0 op_sel_hi:[1,0]
	v_add_f32_e32 v101, v101, v108
	v_lshlrev_b32_e32 v108, 16, v129
	v_add_f32_e32 v108, v102, v108
	v_and_b32_e32 v102, 0xffff0000, v129
	v_pk_add_f32 v[96:97], v[96:97], 0 op_sel_hi:[1,0]
	v_add_f32_e32 v109, v103, v102
	v_lshlrev_b32_e32 v102, 16, v130
	v_cvt_pk_bf16_f32 v105, v110, v111
	v_add_f32_e32 v110, v96, v102
	v_and_b32_e32 v96, 0xffff0000, v130
	v_pk_add_f32 v[98:99], v[98:99], 0 op_sel_hi:[1,0]
	v_add_f32_e32 v111, v97, v96
	v_lshlrev_b32_e32 v96, 16, v131
	v_add_f32_e32 v128, v98, v96
	v_and_b32_e32 v96, 0xffff0000, v131
	v_add_f32_e32 v129, v99, v96
	v_mul_f32_e32 v96, v101, v101
	v_mul_f32_e32 v97, v109, v109
	v_fmac_f32_e32 v96, v100, v100
	v_fmac_f32_e32 v97, v108, v108
	v_add_f32_e32 v96, v96, v97
	v_mul_f32_e32 v97, v111, v111
	v_fmac_f32_e32 v97, v110, v110
	v_add_f32_e32 v96, v97, v96
	v_mul_f32_e32 v97, v129, v129
	v_fmac_f32_e32 v97, v128, v128
	v_add_f32_e32 v96, v97, v96
	v_add_f32_e32 v99, v135, v96
	ds_bpermute_b32 v130, v171, v99
	s_waitcnt lgkmcnt(1)
	v_lshlrev_b64 v[174:175], 11, v[162:163]
	v_lshl_add_u64 v[96:97], v[174:175], 1, s[16:17]
	v_lshl_add_u64 v[102:103], v[152:153], 1, v[96:97]
	v_cvt_pk_bf16_f32 v106, v132, v133
	s_waitcnt lgkmcnt(0)
	v_add_f32_e32 v96, v99, v130
	ds_bpermute_b32 v97, v172, v96
	v_cvt_pk_bf16_f32 v107, v134, v107
	global_store_dwordx4 v[102:103], v[104:107], off sc1
	v_cvt_pk_bf16_f32 v98, v100, v101
	v_cvt_pk_bf16_f32 v99, v108, v109
	v_cvt_pk_bf16_f32 v100, v110, v111
	v_cvt_pk_bf16_f32 v101, v128, v129
	global_store_dwordx4 v[102:103], v[98:101], off offset:256 sc1
	s_and_saveexec_b64 s[26:27], s[10:11]
	s_cbranch_execz .LBB0_1944
	v_lshlrev_b64 v[98:99], 7, v[162:163]
	v_lshl_add_u64 v[98:99], s[24:25], 0, v[98:99]
	s_waitcnt lgkmcnt(0)
	v_add_f32_e32 v96, v96, v97
	global_store_dword v[98:99], v96, off
.LBB0_1944:
	s_or_b64 exec, exec, s[26:27]
	v_pk_add_f32 v[92:93], v[92:93], 0 op_sel_hi:[1,0]
	v_lshlrev_b32_e32 v98, 16, v124
	v_add_f32_e32 v92, v92, v98
	v_and_b32_e32 v98, 0xffff0000, v124
	v_pk_add_f32 v[94:95], v[94:95], 0 op_sel_hi:[1,0]
	v_add_f32_e32 v93, v93, v98
	v_lshlrev_b32_e32 v98, 16, v125
	v_add_f32_e32 v94, v94, v98
	v_and_b32_e32 v98, 0xffff0000, v125
	v_pk_add_f32 v[88:89], v[88:89], 0 op_sel_hi:[1,0]
	v_add_f32_e32 v95, v95, v98
	v_lshlrev_b32_e32 v98, 16, v126
	v_add_f32_e32 v98, v88, v98
	v_and_b32_e32 v88, 0xffff0000, v126
	v_pk_add_f32 v[90:91], v[90:91], 0 op_sel_hi:[1,0]
	v_add_f32_e32 v99, v89, v88
	v_lshlrev_b32_e32 v88, 16, v127
	v_add_f32_e32 v100, v90, v88
	v_and_b32_e32 v88, 0xffff0000, v127
	v_add_f32_e32 v91, v91, v88
	v_mul_f32_e32 v88, v93, v93
	v_mul_f32_e32 v89, v95, v95
	v_fmac_f32_e32 v88, v92, v92
	v_fmac_f32_e32 v89, v94, v94
	v_add_f32_e32 v88, v88, v89
	v_mul_f32_e32 v89, v99, v99
	v_fmac_f32_e32 v89, v98, v98
	v_add_f32_e32 v88, v89, v88
	v_mul_f32_e32 v89, v91, v91
	v_fmac_f32_e32 v89, v100, v100
	v_add_f32_e32 v101, v89, v88
	v_cvt_pk_bf16_f32 v88, v92, v93
	v_pk_add_f32 v[84:85], v[84:85], 0 op_sel_hi:[1,0]
	v_lshlrev_b32_e32 v92, 16, v120
	v_add_f32_e32 v84, v84, v92
	v_and_b32_e32 v92, 0xffff0000, v120
	v_pk_add_f32 v[86:87], v[86:87], 0 op_sel_hi:[1,0]
	v_add_f32_e32 v85, v85, v92
	v_lshlrev_b32_e32 v92, 16, v121
	v_add_f32_e32 v92, v86, v92
	v_and_b32_e32 v86, 0xffff0000, v121
	v_pk_add_f32 v[80:81], v[80:81], 0 op_sel_hi:[1,0]
	v_add_f32_e32 v93, v87, v86
	v_lshlrev_b32_e32 v86, 16, v122
	v_cvt_pk_bf16_f32 v89, v94, v95
	v_add_f32_e32 v94, v80, v86
	v_and_b32_e32 v80, 0xffff0000, v122
	v_pk_add_f32 v[82:83], v[82:83], 0 op_sel_hi:[1,0]
	v_add_f32_e32 v95, v81, v80
	v_lshlrev_b32_e32 v80, 16, v123
	v_cvt_pk_bf16_f32 v90, v98, v99
	v_add_f32_e32 v98, v82, v80
	v_and_b32_e32 v80, 0xffff0000, v123
	v_add_f32_e32 v99, v83, v80
	v_mul_f32_e32 v80, v85, v85
	v_mul_f32_e32 v81, v93, v93
	v_fmac_f32_e32 v80, v84, v84
	v_fmac_f32_e32 v81, v92, v92
	v_add_f32_e32 v80, v80, v81
	v_mul_f32_e32 v81, v95, v95
	v_fmac_f32_e32 v81, v94, v94
	v_add_f32_e32 v80, v81, v80
	v_mul_f32_e32 v81, v99, v99
	v_fmac_f32_e32 v81, v98, v98
	v_add_f32_e32 v80, v81, v80
	v_add_f32_e32 v83, v101, v80
	v_cvt_pk_bf16_f32 v91, v100, v91
	ds_bpermute_b32 v100, v171, v83
	s_waitcnt lgkmcnt(1)
	v_lshlrev_b64 v[96:97], 11, v[160:161]
	v_lshl_add_u64 v[80:81], v[96:97], 1, s[16:17]
	v_lshl_add_u64 v[86:87], v[152:153], 1, v[80:81]
	global_store_dwordx4 v[86:87], v[88:91], off sc1
	s_waitcnt lgkmcnt(0)
	v_add_f32_e32 v80, v83, v100
	ds_bpermute_b32 v81, v172, v80
	v_cvt_pk_bf16_f32 v82, v84, v85
	v_cvt_pk_bf16_f32 v83, v92, v93
	v_cvt_pk_bf16_f32 v84, v94, v95
	v_cvt_pk_bf16_f32 v85, v98, v99
	global_store_dwordx4 v[86:87], v[82:85], off offset:256 sc1
	s_and_saveexec_b64 s[26:27], s[10:11]
	s_cbranch_execz .LBB0_1946
	v_lshlrev_b64 v[82:83], 7, v[160:161]
	v_lshl_add_u64 v[82:83], s[24:25], 0, v[82:83]
	s_waitcnt lgkmcnt(0)
	v_add_f32_e32 v80, v80, v81
	global_store_dword v[82:83], v80, off
; __device__ __forceinline__ unsigned cvt_pk_bf16(float lo, float hi) { unsigned r; asm volatile("v_cvt_pk_bf16_f32 %0, %1, %2" : "=v"(r) : "v"(lo), "v"(hi)); return r; }
;     __device__ __forceinline__ void operator()(const f32x4 (&acc)[2][2][4][2], const Unit& u, int wr, int wc, int fr, int fq) const {
;     ...
;             u32x4 old[4][2];
; #pragma unroll
;             for (int m = 0; m < 4; ++m)
; #pragma unroll
;                 for (int bj = 0; bj < 2; ++bj) old[m][bj] = *(const u32x4*)(HB + (size_t)(row0 + ai * HALF + m * 16) * ldc + col0 + bj * HALF);
; #pragma unroll
;             for (int m = 0; m < 4; ++m) { const int row = row0 + ai * HALF + m * 16; float ss = 0.f;
; #pragma unroll
;                 for (int bj = 0; bj < 2; ++bj) { const u32x4 ow = old[m][bj];
;                     f32x4 v0 = (acc[ai][bj][m][0] + bv[bj][0]) * accs, v1 = (acc[ai][bj][m][1] + bv[bj][1]) * accs;
;                     v0[0] += __uint_as_float(ow.x << 16); v0[1] += __uint_as_float(ow.x & 0xffff0000u); v0[2] += __uint_as_float(ow.y << 16); v0[3] += __uint_as_float(ow.y & 0xffff0000u);
;                     v1[0] += __uint_as_float(ow.z << 16); v1[1] += __uint_as_float(ow.z & 0xffff0000u); v1[2] += __uint_as_float(ow.w << 16); v1[3] += __uint_as_float(ow.w & 0xffff0000u);
;                     ss += (v0[0] * v0[0] + v0[1] * v0[1]) + (v0[2] * v0[2] + v0[3] * v0[3]) + (v1[0] * v1[0] + v1[1] * v1[1]) + (v1[2] * v1[2] + v1[3] * v1[3]);
;                     u32x4 w; w.x = cvt_pk_bf16(v0[0], v0[1]); w.y = cvt_pk_bf16(v0[2], v0[3]); w.z = cvt_pk_bf16(v1[0], v1[1]); w.w = cvt_pk_bf16(v1[2], v1[3]);
;                     *(u32x4*)(HB + (size_t)row * ldc + col0 + bj * HALF) = w; }
;                 ss += __shfl_xor(ss, 16); ss += __shfl_xor(ss, 32);
;                 if (fq == 0) ssp[(size_t)row * 32] = ss; }
.LBB0_1946:
	s_or_b64 exec, exec, s[26:27]
	v_pk_add_f32 v[76:77], v[76:77], 0 op_sel_hi:[1,0]
	v_lshlrev_b32_e32 v82, 16, v116
	v_add_f32_e32 v76, v76, v82
	v_and_b32_e32 v82, 0xffff0000, v116
	v_pk_add_f32 v[78:79], v[78:79], 0 op_sel_hi:[1,0]
	v_add_f32_e32 v77, v77, v82
	v_lshlrev_b32_e32 v82, 16, v117
	v_add_f32_e32 v78, v78, v82
	v_and_b32_e32 v82, 0xffff0000, v117
	v_pk_add_f32 v[72:73], v[72:73], 0 op_sel_hi:[1,0]
	v_add_f32_e32 v79, v79, v82
	v_lshlrev_b32_e32 v82, 16, v118
	v_add_f32_e32 v82, v72, v82
	v_and_b32_e32 v72, 0xffff0000, v118
	v_pk_add_f32 v[74:75], v[74:75], 0 op_sel_hi:[1,0]
	v_add_f32_e32 v83, v73, v72
	v_lshlrev_b32_e32 v72, 16, v119
	v_add_f32_e32 v84, v74, v72
	v_and_b32_e32 v72, 0xffff0000, v119
	v_add_f32_e32 v75, v75, v72
	v_mul_f32_e32 v72, v77, v77
	v_mul_f32_e32 v73, v79, v79
	v_fmac_f32_e32 v72, v76, v76
	v_fmac_f32_e32 v73, v78, v78
	v_add_f32_e32 v72, v72, v73
	v_mul_f32_e32 v73, v83, v83
	v_fmac_f32_e32 v73, v82, v82
	v_add_f32_e32 v72, v73, v72
	v_mul_f32_e32 v73, v75, v75
	v_fmac_f32_e32 v73, v84, v84
	v_add_f32_e32 v85, v73, v72
	v_cvt_pk_bf16_f32 v72, v76, v77
	v_pk_add_f32 v[68:69], v[68:69], 0 op_sel_hi:[1,0]
	v_lshlrev_b32_e32 v76, 16, v112
	v_add_f32_e32 v68, v68, v76
	v_and_b32_e32 v76, 0xffff0000, v112
	v_pk_add_f32 v[70:71], v[70:71], 0 op_sel_hi:[1,0]
	v_add_f32_e32 v69, v69, v76
	v_lshlrev_b32_e32 v76, 16, v113
	v_add_f32_e32 v76, v70, v76
	v_and_b32_e32 v70, 0xffff0000, v113
	v_pk_add_f32 v[64:65], v[64:65], 0 op_sel_hi:[1,0]
	v_add_f32_e32 v77, v71, v70
	v_lshlrev_b32_e32 v70, 16, v114
	v_cvt_pk_bf16_f32 v73, v78, v79
	v_add_f32_e32 v78, v64, v70
	v_and_b32_e32 v64, 0xffff0000, v114
	v_pk_add_f32 v[66:67], v[66:67], 0 op_sel_hi:[1,0]
	v_add_f32_e32 v79, v65, v64
	v_lshlrev_b32_e32 v64, 16, v115
	v_cvt_pk_bf16_f32 v74, v82, v83
	v_add_f32_e32 v82, v66, v64
	v_and_b32_e32 v64, 0xffff0000, v115
	v_add_f32_e32 v83, v67, v64
	v_mul_f32_e32 v64, v69, v69
	v_mul_f32_e32 v65, v77, v77
	v_fmac_f32_e32 v64, v68, v68
	v_fmac_f32_e32 v65, v76, v76
	v_add_f32_e32 v64, v64, v65
	v_mul_f32_e32 v65, v79, v79
	v_fmac_f32_e32 v65, v78, v78
	v_add_f32_e32 v64, v65, v64
	v_mul_f32_e32 v65, v83, v83
	v_fmac_f32_e32 v65, v82, v82
	v_add_f32_e32 v64, v65, v64
	v_add_f32_e32 v67, v85, v64
	v_cvt_pk_bf16_f32 v75, v84, v75
	ds_bpermute_b32 v84, v171, v67
	s_waitcnt lgkmcnt(1)
	v_lshlrev_b64 v[80:81], 11, v[158:159]
	v_lshl_add_u64 v[64:65], v[80:81], 1, s[16:17]
	v_lshl_add_u64 v[70:71], v[152:153], 1, v[64:65]
	global_store_dwordx4 v[70:71], v[72:75], off sc1
	s_waitcnt lgkmcnt(0)
	v_add_f32_e32 v64, v67, v84
	ds_bpermute_b32 v65, v172, v64
	v_cvt_pk_bf16_f32 v66, v68, v69
	v_cvt_pk_bf16_f32 v67, v76, v77
	v_cvt_pk_bf16_f32 v68, v78, v79
	v_cvt_pk_bf16_f32 v69, v82, v83
	global_store_dwordx4 v[70:71], v[66:69], off offset:256 sc1
	s_and_saveexec_b64 s[26:27], s[10:11]
	s_cbranch_execz .LBB0_1948
	v_lshlrev_b64 v[66:67], 7, v[158:159]
	v_lshl_add_u64 v[66:67], s[24:25], 0, v[66:67]
	s_waitcnt lgkmcnt(0)
	v_add_f32_e32 v64, v64, v65
	global_store_dword v[66:67], v64, off
.LBB0_1948:
	s_or_b64 exec, exec, s[26:27]
	v_add_u32_e32 v94, 0x80, v154
	v_ashrrev_i32_e32 v95, 31, v94
	v_lshlrev_b64 v[104:105], 12, v[94:95]
	s_waitcnt lgkmcnt(0)
	v_lshl_add_u64 v[64:65], v[156:157], 0, v[104:105]
	global_load_dwordx4 v[96:99], v[64:65], off
	global_load_dwordx4 v[100:103], v[64:65], off offset:256
	v_add_u32_e32 v92, 0x90, v154
	v_add_u32_e32 v90, 0xa0, v154
	v_add_u32_e32 v88, 0xb0, v154
	v_ashrrev_i32_e32 v93, 31, v92
	v_ashrrev_i32_e32 v91, 31, v90
	v_ashrrev_i32_e32 v89, 31, v88
	v_lshlrev_b64 v[64:65], 12, v[92:93]
	v_lshlrev_b64 v[66:67], 12, v[90:91]
	v_lshlrev_b64 v[68:69], 12, v[88:89]
	v_lshl_add_u64 v[64:65], v[156:157], 0, v[64:65]
	v_lshl_add_u64 v[66:67], v[156:157], 0, v[66:67]
	v_lshl_add_u64 v[106:107], v[156:157], 0, v[68:69]
	global_load_dwordx4 v[84:87], v[64:65], off
	global_load_dwordx4 v[80:83], v[64:65], off offset:256
	global_load_dwordx4 v[76:79], v[66:67], off
	global_load_dwordx4 v[72:75], v[66:67], off offset:256
	global_load_dwordx4 v[68:71], v[106:107], off
	s_nop 0
	global_load_dwordx4 v[64:67], v[106:107], off offset:256
	v_pk_add_f32 v[62:63], v[62:63], 0 op_sel_hi:[1,0]
	v_pk_add_f32 v[60:61], v[60:61], 0 op_sel_hi:[1,0]
	v_pk_add_f32 v[58:59], v[58:59], 0 op_sel_hi:[1,0]
	v_pk_add_f32 v[56:57], v[56:57], 0 op_sel_hi:[1,0]
	v_pk_add_f32 v[54:55], v[54:55], 0 op_sel_hi:[1,0]
	v_pk_add_f32 v[52:53], v[52:53], 0 op_sel_hi:[1,0]
	v_pk_add_f32 v[50:51], v[50:51], 0 op_sel_hi:[1,0]
	v_pk_add_f32 v[48:49], v[48:49], 0 op_sel_hi:[1,0]
	s_waitcnt vmcnt(7)
	v_lshlrev_b32_e32 v106, 16, v96
	v_and_b32_e32 v96, 0xffff0000, v96
	v_lshlrev_b32_e32 v107, 16, v97
	v_and_b32_e32 v97, 0xffff0000, v97
	v_lshlrev_b32_e32 v108, 16, v98
	v_and_b32_e32 v98, 0xffff0000, v98
	v_lshlrev_b32_e32 v109, 16, v99
	v_and_b32_e32 v99, 0xffff0000, v99
	s_waitcnt vmcnt(6)
	v_lshlrev_b32_e32 v110, 16, v100
	v_and_b32_e32 v100, 0xffff0000, v100
	v_lshlrev_b32_e32 v111, 16, v101
	v_and_b32_e32 v101, 0xffff0000, v101
	v_lshlrev_b32_e32 v112, 16, v102
	v_and_b32_e32 v102, 0xffff0000, v102
	v_lshlrev_b32_e32 v113, 16, v103
	v_and_b32_e32 v103, 0xffff0000, v103
	v_add_f32_e32 v61, v61, v96
	v_add_f32_e32 v63, v63, v97
	v_add_f32_e32 v57, v57, v98
	v_add_f32_e32 v59, v59, v99
	v_add_f32_e32 v97, v53, v100
	v_add_f32_e32 v99, v55, v101
	v_add_f32_e32 v60, v60, v106
	v_add_f32_e32 v62, v62, v107
	v_add_f32_e32 v56, v56, v108
	v_add_f32_e32 v58, v58, v109
	v_add_f32_e32 v96, v52, v110
	v_add_f32_e32 v98, v54, v111
	v_add_f32_e32 v100, v48, v112
	v_add_f32_e32 v101, v49, v102
	v_add_f32_e32 v102, v50, v113
	v_add_f32_e32 v103, v51, v103
	v_mul_f32_e32 v52, v61, v61
	v_mul_f32_e32 v53, v63, v63
	v_mul_f32_e32 v54, v57, v57
	v_mul_f32_e32 v55, v59, v59
	v_cvt_pk_bf16_f32 v48, v60, v61
	v_cvt_pk_bf16_f32 v49, v62, v63
	v_cvt_pk_bf16_f32 v50, v56, v57
	v_cvt_pk_bf16_f32 v51, v58, v59
	v_mul_f32_e32 v57, v97, v97
	v_mul_f32_e32 v59, v99, v99
	v_mul_f32_e32 v61, v101, v101
	v_fmac_f32_e32 v52, v60, v60
	v_fmac_f32_e32 v53, v62, v62
	v_fmac_f32_e32 v57, v96, v96
	v_fmac_f32_e32 v59, v98, v98
	v_mul_f32_e32 v63, v103, v103
	v_fmac_f32_e32 v54, v56, v56
	v_fmac_f32_e32 v61, v100, v100
	v_add_f32_e32 v52, v52, v53
	v_add_f32_e32 v53, v57, v59
	v_fmac_f32_e32 v55, v58, v58
	v_fmac_f32_e32 v63, v102, v102
	v_add_f32_e32 v52, v54, v52
	v_add_f32_e32 v53, v61, v53
	v_add_f32_e32 v52, v55, v52
	v_add_f32_e32 v53, v63, v53
	v_add_f32_e32 v56, v52, v53
	ds_bpermute_b32 v57, v171, v56
	v_lshl_add_u64 v[52:53], s[16:17], 0, v[104:105]
	v_lshl_add_u64 v[54:55], v[152:153], 1, v[52:53]
	global_store_dwordx4 v[54:55], v[48:51], off sc1
	s_waitcnt lgkmcnt(0)
	s_nop 0
	v_add_f32_e32 v48, v56, v57
	ds_bpermute_b32 v49, v172, v48
	v_cvt_pk_bf16_f32 v50, v96, v97
	v_cvt_pk_bf16_f32 v51, v98, v99
	v_cvt_pk_bf16_f32 v52, v100, v101
	v_cvt_pk_bf16_f32 v53, v102, v103
	global_store_dwordx4 v[54:55], v[50:53], off offset:256 sc1
	s_and_saveexec_b64 s[26:27], s[10:11]
	s_cbranch_execz .LBB0_1950
; __device__ __forceinline__ unsigned cvt_pk_bf16(float lo, float hi) { unsigned r; asm volatile("v_cvt_pk_bf16_f32 %0, %1, %2" : "=v"(r) : "v"(lo), "v"(hi)); return r; }
;     __device__ __forceinline__ void operator()(const f32x4 (&acc)[2][2][4][2], const Unit& u, int wr, int wc, int fr, int fq) const {
;     ...
;             for (int m = 0; m < 4; ++m) { const int row = row0 + ai * HALF + m * 16; float ss = 0.f;
; #pragma unroll
;                 for (int bj = 0; bj < 2; ++bj) { const u32x4 ow = old[m][bj];
;                     f32x4 v0 = (acc[ai][bj][m][0] + bv[bj][0]) * accs, v1 = (acc[ai][bj][m][1] + bv[bj][1]) * accs;
;                     v0[0] += __uint_as_float(ow.x << 16); v0[1] += __uint_as_float(ow.x & 0xffff0000u); v0[2] += __uint_as_float(ow.y << 16); v0[3] += __uint_as_float(ow.y & 0xffff0000u);
;                     v1[0] += __uint_as_float(ow.z << 16); v1[1] += __uint_as_float(ow.z & 0xffff0000u); v1[2] += __uint_as_float(ow.w << 16); v1[3] += __uint_as_float(ow.w & 0xffff0000u);
;                     ss += (v0[0] * v0[0] + v0[1] * v0[1]) + (v0[2] * v0[2] + v0[3] * v0[3]) + (v1[0] * v1[0] + v1[1] * v1[1]) + (v1[2] * v1[2] + v1[3] * v1[3]);
;                     u32x4 w; w.x = cvt_pk_bf16(v0[0], v0[1]); w.y = cvt_pk_bf16(v0[2], v0[3]); w.z = cvt_pk_bf16(v1[0], v1[1]); w.w = cvt_pk_bf16(v1[2], v1[3]);
;                     *(u32x4*)(HB + (size_t)row * ldc + col0 + bj * HALF) = w; }
;                 ss += __shfl_xor(ss, 16); ss += __shfl_xor(ss, 32);
;                 if (fq == 0) ssp[(size_t)row * 32] = ss; }
	v_lshlrev_b64 v[50:51], 7, v[94:95]
	v_lshl_add_u64 v[50:51], s[24:25], 0, v[50:51]
	s_waitcnt lgkmcnt(0)
	v_add_f32_e32 v48, v48, v49
	global_store_dword v[50:51], v48, off
.LBB0_1950:
	s_or_b64 exec, exec, s[26:27]
	v_pk_add_f32 v[44:45], v[44:45], 0 op_sel_hi:[1,0]
	s_waitcnt vmcnt(7)
	v_lshlrev_b32_e32 v50, 16, v84
	v_add_f32_e32 v44, v44, v50
	v_and_b32_e32 v50, 0xffff0000, v84
	v_pk_add_f32 v[46:47], v[46:47], 0 op_sel_hi:[1,0]
	v_add_f32_e32 v45, v45, v50
	v_lshlrev_b32_e32 v50, 16, v85
	v_add_f32_e32 v46, v46, v50
	v_and_b32_e32 v50, 0xffff0000, v85
	v_pk_add_f32 v[40:41], v[40:41], 0 op_sel_hi:[1,0]
	v_add_f32_e32 v47, v47, v50
	v_lshlrev_b32_e32 v50, 16, v86
	v_add_f32_e32 v50, v40, v50
	v_and_b32_e32 v40, 0xffff0000, v86
	v_pk_add_f32 v[42:43], v[42:43], 0 op_sel_hi:[1,0]
	v_add_f32_e32 v51, v41, v40
	v_lshlrev_b32_e32 v40, 16, v87
	v_add_f32_e32 v52, v42, v40
	v_and_b32_e32 v40, 0xffff0000, v87
	v_add_f32_e32 v43, v43, v40
	v_mul_f32_e32 v40, v45, v45
	v_mul_f32_e32 v41, v47, v47
	v_fmac_f32_e32 v40, v44, v44
	v_fmac_f32_e32 v41, v46, v46
	v_add_f32_e32 v40, v40, v41
	v_mul_f32_e32 v41, v51, v51
	v_fmac_f32_e32 v41, v50, v50
	v_add_f32_e32 v40, v41, v40
	v_mul_f32_e32 v41, v43, v43
	v_fmac_f32_e32 v41, v52, v52
	v_add_f32_e32 v53, v41, v40
	v_cvt_pk_bf16_f32 v40, v44, v45
	v_pk_add_f32 v[36:37], v[36:37], 0 op_sel_hi:[1,0]
	s_waitcnt vmcnt(6)
	v_lshlrev_b32_e32 v44, 16, v80
	v_add_f32_e32 v36, v36, v44
	v_and_b32_e32 v44, 0xffff0000, v80
	v_pk_add_f32 v[38:39], v[38:39], 0 op_sel_hi:[1,0]
	v_add_f32_e32 v37, v37, v44
	v_lshlrev_b32_e32 v44, 16, v81
	v_add_f32_e32 v44, v38, v44
	v_and_b32_e32 v38, 0xffff0000, v81
	v_pk_add_f32 v[32:33], v[32:33], 0 op_sel_hi:[1,0]
	v_add_f32_e32 v45, v39, v38
	v_lshlrev_b32_e32 v38, 16, v82
	v_cvt_pk_bf16_f32 v41, v46, v47
	v_add_f32_e32 v46, v32, v38
	v_and_b32_e32 v32, 0xffff0000, v82
	v_pk_add_f32 v[34:35], v[34:35], 0 op_sel_hi:[1,0]
	v_add_f32_e32 v47, v33, v32
	v_lshlrev_b32_e32 v32, 16, v83
	v_cvt_pk_bf16_f32 v42, v50, v51
	v_add_f32_e32 v50, v34, v32
	v_and_b32_e32 v32, 0xffff0000, v83
	v_add_f32_e32 v51, v35, v32
	v_mul_f32_e32 v32, v37, v37
	v_mul_f32_e32 v33, v45, v45
	v_fmac_f32_e32 v32, v36, v36
	v_fmac_f32_e32 v33, v44, v44
	v_add_f32_e32 v32, v32, v33
	v_mul_f32_e32 v33, v47, v47
	v_fmac_f32_e32 v33, v46, v46
	v_add_f32_e32 v32, v33, v32
	v_mul_f32_e32 v33, v51, v51
	v_fmac_f32_e32 v33, v50, v50
	v_add_f32_e32 v32, v33, v32
	v_add_f32_e32 v35, v53, v32
	v_cvt_pk_bf16_f32 v43, v52, v43
	ds_bpermute_b32 v52, v171, v35
	s_waitcnt lgkmcnt(1)
	v_lshlrev_b64 v[48:49], 11, v[92:93]
	v_lshl_add_u64 v[32:33], v[48:49], 1, s[16:17]
	v_lshl_add_u64 v[38:39], v[152:153], 1, v[32:33]
	global_store_dwordx4 v[38:39], v[40:43], off sc1
	s_waitcnt lgkmcnt(0)
	v_add_f32_e32 v32, v35, v52
	ds_bpermute_b32 v33, v172, v32
	v_cvt_pk_bf16_f32 v34, v36, v37
	v_cvt_pk_bf16_f32 v35, v44, v45
	v_cvt_pk_bf16_f32 v36, v46, v47
	v_cvt_pk_bf16_f32 v37, v50, v51
	global_store_dwordx4 v[38:39], v[34:37], off offset:256 sc1
	s_and_saveexec_b64 s[26:27], s[10:11]
	s_cbranch_execz .LBB0_1952
	v_lshlrev_b64 v[34:35], 7, v[92:93]
	v_lshl_add_u64 v[34:35], s[24:25], 0, v[34:35]
	s_waitcnt lgkmcnt(0)
	v_add_f32_e32 v32, v32, v33
	global_store_dword v[34:35], v32, off
; __device__ __forceinline__ unsigned cvt_pk_bf16(float lo, float hi) { unsigned r; asm volatile("v_cvt_pk_bf16_f32 %0, %1, %2" : "=v"(r) : "v"(lo), "v"(hi)); return r; }
;     __device__ __forceinline__ void operator()(const f32x4 (&acc)[2][2][4][2], const Unit& u, int wr, int wc, int fr, int fq) const {
;     ...
;             for (int m = 0; m < 4; ++m) { const int row = row0 + ai * HALF + m * 16; float ss = 0.f;
; #pragma unroll
;                 for (int bj = 0; bj < 2; ++bj) { const u32x4 ow = old[m][bj];
;                     f32x4 v0 = (acc[ai][bj][m][0] + bv[bj][0]) * accs, v1 = (acc[ai][bj][m][1] + bv[bj][1]) * accs;
;                     v0[0] += __uint_as_float(ow.x << 16); v0[1] += __uint_as_float(ow.x & 0xffff0000u); v0[2] += __uint_as_float(ow.y << 16); v0[3] += __uint_as_float(ow.y & 0xffff0000u);
;                     v1[0] += __uint_as_float(ow.z << 16); v1[1] += __uint_as_float(ow.z & 0xffff0000u); v1[2] += __uint_as_float(ow.w << 16); v1[3] += __uint_as_float(ow.w & 0xffff0000u);
;                     ss += (v0[0] * v0[0] + v0[1] * v0[1]) + (v0[2] * v0[2] + v0[3] * v0[3]) + (v1[0] * v1[0] + v1[1] * v1[1]) + (v1[2] * v1[2] + v1[3] * v1[3]);
;                     u32x4 w; w.x = cvt_pk_bf16(v0[0], v0[1]); w.y = cvt_pk_bf16(v0[2], v0[3]); w.z = cvt_pk_bf16(v1[0], v1[1]); w.w = cvt_pk_bf16(v1[2], v1[3]);
;                     *(u32x4*)(HB + (size_t)row * ldc + col0 + bj * HALF) = w; }
;                 ss += __shfl_xor(ss, 16); ss += __shfl_xor(ss, 32);
;                 if (fq == 0) ssp[(size_t)row * 32] = ss; }
.LBB0_1952:
	s_or_b64 exec, exec, s[26:27]
	v_pk_add_f32 v[28:29], v[28:29], 0 op_sel_hi:[1,0]
	s_waitcnt vmcnt(7)
	v_lshlrev_b32_e32 v34, 16, v76
	v_add_f32_e32 v28, v28, v34
	v_and_b32_e32 v34, 0xffff0000, v76
	v_pk_add_f32 v[30:31], v[30:31], 0 op_sel_hi:[1,0]
	v_add_f32_e32 v29, v29, v34
	v_lshlrev_b32_e32 v34, 16, v77
	v_add_f32_e32 v30, v30, v34
	v_and_b32_e32 v34, 0xffff0000, v77
	v_pk_add_f32 v[24:25], v[24:25], 0 op_sel_hi:[1,0]
	v_add_f32_e32 v31, v31, v34
	v_lshlrev_b32_e32 v34, 16, v78
	v_add_f32_e32 v34, v24, v34
	v_and_b32_e32 v24, 0xffff0000, v78
	v_pk_add_f32 v[26:27], v[26:27], 0 op_sel_hi:[1,0]
	v_add_f32_e32 v35, v25, v24
	v_lshlrev_b32_e32 v24, 16, v79
	v_add_f32_e32 v36, v26, v24
	v_and_b32_e32 v24, 0xffff0000, v79
	v_add_f32_e32 v27, v27, v24
	v_mul_f32_e32 v24, v29, v29
	v_mul_f32_e32 v25, v31, v31
	v_fmac_f32_e32 v24, v28, v28
	v_fmac_f32_e32 v25, v30, v30
	v_add_f32_e32 v24, v24, v25
	v_mul_f32_e32 v25, v35, v35
	v_fmac_f32_e32 v25, v34, v34
	v_add_f32_e32 v24, v25, v24
	v_mul_f32_e32 v25, v27, v27
	v_fmac_f32_e32 v25, v36, v36
	v_add_f32_e32 v37, v25, v24
	v_cvt_pk_bf16_f32 v24, v28, v29
	v_pk_add_f32 v[20:21], v[20:21], 0 op_sel_hi:[1,0]
	s_waitcnt vmcnt(6)
	v_lshlrev_b32_e32 v28, 16, v72
	v_add_f32_e32 v20, v20, v28
	v_and_b32_e32 v28, 0xffff0000, v72
	v_pk_add_f32 v[22:23], v[22:23], 0 op_sel_hi:[1,0]
	v_add_f32_e32 v21, v21, v28
	v_lshlrev_b32_e32 v28, 16, v73
	v_add_f32_e32 v28, v22, v28
	v_and_b32_e32 v22, 0xffff0000, v73
	v_pk_add_f32 v[16:17], v[16:17], 0 op_sel_hi:[1,0]
	v_add_f32_e32 v29, v23, v22
	v_lshlrev_b32_e32 v22, 16, v74
	v_cvt_pk_bf16_f32 v25, v30, v31
	v_add_f32_e32 v30, v16, v22
	v_and_b32_e32 v16, 0xffff0000, v74
	v_pk_add_f32 v[18:19], v[18:19], 0 op_sel_hi:[1,0]
	v_add_f32_e32 v31, v17, v16
	v_lshlrev_b32_e32 v16, 16, v75
	v_cvt_pk_bf16_f32 v26, v34, v35
	v_add_f32_e32 v34, v18, v16
	v_and_b32_e32 v16, 0xffff0000, v75
	v_add_f32_e32 v35, v19, v16
	v_mul_f32_e32 v16, v21, v21
	v_mul_f32_e32 v17, v29, v29
	v_fmac_f32_e32 v16, v20, v20
	v_fmac_f32_e32 v17, v28, v28
	v_add_f32_e32 v16, v16, v17
	v_mul_f32_e32 v17, v31, v31
	v_fmac_f32_e32 v17, v30, v30
	v_add_f32_e32 v16, v17, v16
	v_mul_f32_e32 v17, v35, v35
	v_fmac_f32_e32 v17, v34, v34
	v_add_f32_e32 v16, v17, v16
	v_add_f32_e32 v19, v37, v16
	v_cvt_pk_bf16_f32 v27, v36, v27
	ds_bpermute_b32 v36, v171, v19
	s_waitcnt lgkmcnt(1)
	v_lshlrev_b64 v[32:33], 11, v[90:91]
	v_lshl_add_u64 v[16:17], v[32:33], 1, s[16:17]
	v_lshl_add_u64 v[22:23], v[152:153], 1, v[16:17]
	global_store_dwordx4 v[22:23], v[24:27], off sc1
	s_waitcnt lgkmcnt(0)
	v_add_f32_e32 v16, v19, v36
	ds_bpermute_b32 v17, v172, v16
	v_cvt_pk_bf16_f32 v18, v20, v21
	v_cvt_pk_bf16_f32 v19, v28, v29
	v_cvt_pk_bf16_f32 v20, v30, v31
	v_cvt_pk_bf16_f32 v21, v34, v35
	global_store_dwordx4 v[22:23], v[18:21], off offset:256 sc1
	s_and_saveexec_b64 s[26:27], s[10:11]
	s_cbranch_execz .LBB0_1954
	v_lshlrev_b64 v[18:19], 7, v[90:91]
	v_lshl_add_u64 v[18:19], s[24:25], 0, v[18:19]
	s_waitcnt lgkmcnt(0)
	v_add_f32_e32 v16, v16, v17
	global_store_dword v[18:19], v16, off
.LBB0_1954:
	s_or_b64 exec, exec, s[26:27]
	v_pk_add_f32 v[12:13], v[12:13], 0 op_sel_hi:[1,0]
	s_waitcnt vmcnt(7)
	v_lshlrev_b32_e32 v18, 16, v68
	v_add_f32_e32 v12, v12, v18
	v_and_b32_e32 v18, 0xffff0000, v68
	v_pk_add_f32 v[14:15], v[14:15], 0 op_sel_hi:[1,0]
	v_add_f32_e32 v13, v13, v18
	v_lshlrev_b32_e32 v18, 16, v69
	v_add_f32_e32 v14, v14, v18
	v_and_b32_e32 v18, 0xffff0000, v69
	v_pk_add_f32 v[8:9], v[8:9], 0 op_sel_hi:[1,0]
	v_add_f32_e32 v15, v15, v18
	v_lshlrev_b32_e32 v18, 16, v70
	v_add_f32_e32 v18, v8, v18
	v_and_b32_e32 v8, 0xffff0000, v70
	v_pk_add_f32 v[10:11], v[10:11], 0 op_sel_hi:[1,0]
	v_add_f32_e32 v19, v9, v8
	v_lshlrev_b32_e32 v8, 16, v71
	v_add_f32_e32 v20, v10, v8
	v_and_b32_e32 v8, 0xffff0000, v71
	v_add_f32_e32 v11, v11, v8
	v_mul_f32_e32 v8, v13, v13
	v_mul_f32_e32 v9, v15, v15
	v_fmac_f32_e32 v8, v12, v12
	v_fmac_f32_e32 v9, v14, v14
	v_add_f32_e32 v8, v8, v9
	v_mul_f32_e32 v9, v19, v19
	v_fmac_f32_e32 v9, v18, v18
	v_add_f32_e32 v8, v9, v8
	v_mul_f32_e32 v9, v11, v11
	v_fmac_f32_e32 v9, v20, v20
	v_add_f32_e32 v21, v9, v8
	v_cvt_pk_bf16_f32 v8, v12, v13
	v_pk_add_f32 v[4:5], v[4:5], 0 op_sel_hi:[1,0]
	s_waitcnt vmcnt(6)
	v_lshlrev_b32_e32 v12, 16, v64
	v_add_f32_e32 v4, v4, v12
	v_and_b32_e32 v12, 0xffff0000, v64
	v_pk_add_f32 v[6:7], v[6:7], 0 op_sel_hi:[1,0]
	v_add_f32_e32 v5, v5, v12
	v_lshlrev_b32_e32 v12, 16, v65
	v_add_f32_e32 v12, v6, v12
	v_and_b32_e32 v6, 0xffff0000, v65
	v_pk_add_f32 v[0:1], v[0:1], 0 op_sel_hi:[1,0]
	v_add_f32_e32 v13, v7, v6
	v_lshlrev_b32_e32 v6, 16, v66
	v_cvt_pk_bf16_f32 v9, v14, v15
	v_add_f32_e32 v14, v0, v6
	v_and_b32_e32 v0, 0xffff0000, v66
	v_pk_add_f32 v[2:3], v[2:3], 0 op_sel_hi:[1,0]
	v_add_f32_e32 v15, v1, v0
	v_lshlrev_b32_e32 v0, 16, v67
	v_cvt_pk_bf16_f32 v10, v18, v19
	v_add_f32_e32 v18, v2, v0
	v_and_b32_e32 v0, 0xffff0000, v67
	v_add_f32_e32 v19, v3, v0
	v_mul_f32_e32 v0, v5, v5
	v_mul_f32_e32 v1, v13, v13
	v_fmac_f32_e32 v0, v4, v4
	v_fmac_f32_e32 v1, v12, v12
	v_add_f32_e32 v0, v0, v1
	v_mul_f32_e32 v1, v15, v15
	v_fmac_f32_e32 v1, v14, v14
	v_add_f32_e32 v0, v1, v0
	v_mul_f32_e32 v1, v19, v19
	v_fmac_f32_e32 v1, v18, v18
	v_add_f32_e32 v0, v1, v0
	v_add_f32_e32 v3, v21, v0
	v_cvt_pk_bf16_f32 v11, v20, v11
	ds_bpermute_b32 v20, v171, v3
	s_waitcnt lgkmcnt(1)
	v_lshlrev_b64 v[16:17], 11, v[88:89]
	v_lshl_add_u64 v[0:1], v[16:17], 1, s[16:17]
	v_lshl_add_u64 v[6:7], v[152:153], 1, v[0:1]
	global_store_dwordx4 v[6:7], v[8:11], off sc1
	s_waitcnt lgkmcnt(0)
	v_add_f32_e32 v0, v3, v20
	ds_bpermute_b32 v1, v172, v0
	v_cvt_pk_bf16_f32 v2, v4, v5
	v_cvt_pk_bf16_f32 v3, v12, v13
	v_cvt_pk_bf16_f32 v4, v14, v15
	v_cvt_pk_bf16_f32 v5, v18, v19
	global_store_dwordx4 v[6:7], v[2:5], off offset:256 sc1
	s_and_saveexec_b64 s[26:27], s[10:11]
	s_cbranch_execz .LBB0_1956
	v_lshlrev_b64 v[2:3], 7, v[88:89]
	v_lshl_add_u64 v[2:3], s[24:25], 0, v[2:3]
	s_waitcnt lgkmcnt(0)
	v_add_f32_e32 v0, v0, v1
	global_store_dword v[2:3], v0, off

; __device__ __forceinline__ unsigned cvt_pk_bf16(float lo, float hi) { unsigned r; asm volatile("v_cvt_pk_bf16_f32 %0, %1, %2" : "=v"(r) : "v"(lo), "v"(hi)); return r; }
; __device__ __forceinline__ float row_ss(const float* part, int row, int fq, int nf4) {
;     const f32x4* p = (const f32x4*)(part + (size_t)row * 32);
;     float s = 0.f;
; #pragma unroll
;     for (int j = 0; j < 2; ++j) { const int idx = fq + 4 * j; if (idx < nf4) { const f32x4 v = p[idx]; s += (v[0] + v[1]) + (v[2] + v[3]); } }
;     s += __shfl_xor(s, 16); s += __shfl_xor(s, 32);
;     return s;
;     __device__ __forceinline__ void operator()(const f32x4 (&acc)[2][2][4][2], const Unit& u, int wr, int wc, int fr, int fq) const {
;         const int row0 = u.pm * BM + wr * 64 + fr; int colt = u.pn * BM; bf16_t* base = O;
;         float sc = 1.f; if (split_cols) { const int t = colt / split_cols; base += (size_t)t * split_stride; colt -= t * split_cols; if (t == 0) sc = scale0; } else sc = scale0;
;         const int col0 = colt + wc * 32 + 8 * fq, bcol0 = u.pn * BM + wc * 32 + 8 * fq;
;         f32x4 bv[2][2];
; #pragma unroll
;         for (int bj = 0; bj < 2; ++bj)
; #pragma unroll
;             for (int n = 0; n < 2; ++n) bv[bj][n] = bias ? *(const f32x4*)(bias + bcol0 + bj * HALF + 4 * n) : (f32x4){0.f, 0.f, 0.f, 0.f};
; #pragma unroll
;         for (int ai = 0; ai < 2; ++ai)
; #pragma unroll
;             for (int m = 0; m < 4; ++m) { const int row = row0 + ai * HALF + m * 16; bf16_t* rowp = base + (size_t)row * ldc + col0;
;                 const float rs = rss ? __builtin_amdgcn_rsqf(row_ss(rss, row, fq, nf4) * rinv + 1e-6f) : 1.f;
; #pragma unroll
;                 for (int bj = 0; bj < 2; ++bj) { f32x4 v0 = acc[ai][bj][m][0] * rs + bv[bj][0], v1 = acc[ai][bj][m][1] * rs + bv[bj][1];
;                     v0 = v0 * sc; v1 = v1 * sc; u32x4 w; w.x = cvt_pk_bf16(v0[0], v0[1]); w.y = cvt_pk_bf16(v0[2], v0[3]); w.z = cvt_pk_bf16(v1[0], v1[1]); w.w = cvt_pk_bf16(v1[2], v1[3]);
;                     *(u32x4*)(rowp + bj * HALF) = w; } }
.LBB0_2024:
	v_lshl_add_u32 v146, s24, 8, v149
	v_ashrrev_i32_e32 v147, 31, v146
	v_lshlrev_b64 v[150:151], 7, v[146:147]
	v_lshl_add_u64 v[150:151], v[136:137], 0, v[150:151]
	global_load_dwordx4 v[162:165], v[150:151], off
	global_load_dwordx4 v[166:169], v[150:151], off offset:64
	v_and_b32_e32 v150, 64, v157
	v_xor_b32_e32 v148, 16, v157
	v_add_u32_e32 v150, 64, v150
	v_xor_b32_e32 v151, 32, v157
	v_or_b32_e32 v170, 16, v146
	v_cmp_lt_i32_e32 vcc, v148, v150
	v_lshlrev_b64 v[172:173], 12, v[146:147]
	v_ashrrev_i32_e32 v171, 31, v170
	v_cndmask_b32_e32 v147, v157, v148, vcc
	v_cmp_lt_i32_e32 vcc, v151, v150
	v_lshlrev_b32_e32 v160, 2, v147
	s_ashr_i32 s17, s6, 31
	v_cndmask_b32_e32 v148, v157, v151, vcc
	v_lshlrev_b64 v[150:151], 7, v[170:171]
	v_lshl_add_u64 v[174:175], v[136:137], 0, v[150:151]
	v_lshlrev_b32_e32 v147, 2, v148
	s_lshr_b32 s17, s17, 29
	s_add_i32 s17, s6, s17
	s_ashr_i32 s17, s17, 3
	s_lshl_b32 s7, s6, 8
	s_mul_i32 s24, s17, 0x3000000
	s_mul_hi_i32 s19, s17, 0x3000000
	s_add_u32 s26, s43, s24
	s_addc_u32 s27, s44, s19
	s_lshl_b32 s17, s17, 11
	s_add_i32 s6, s6, 7
	s_sub_i32 s7, s7, s17
	s_cmp_lt_u32 s6, 15
	s_cselect_b64 vcc, -1, 0
	s_waitcnt vmcnt(0)
	v_mov_b32_e32 v150, v162
	v_mov_b32_e32 v151, v166
	v_mov_b32_e32 v166, v163
	v_mov_b32_e32 v162, v164
	v_mov_b32_e32 v163, v168
	v_mov_b32_e32 v168, v165
	v_pk_add_f32 v[150:151], v[150:151], v[166:167]
	v_pk_add_f32 v[162:163], v[162:163], v[168:169]
	s_nop 0
	v_pk_add_f32 v[150:151], v[150:151], v[162:163]
	s_nop 0
	v_add_f32_e32 v148, 0, v150
	v_add_f32_e32 v148, v148, v151
	ds_bpermute_b32 v150, v160, v148
	s_waitcnt lgkmcnt(0)
	v_add_f32_e32 v151, v148, v150
	ds_bpermute_b32 v161, v147, v151
	v_or_b32_e32 v150, s7, v153
	v_cndmask_b32_e32 v148, 1.0, v159, vcc
	s_andn2_b64 vcc, exec, s[10:11]
	s_mov_b64 s[10:11], -1
	s_waitcnt lgkmcnt(0)
	v_add_f32_e32 v151, v151, v161
	v_fmamk_f32 v151, v151, 0x3a000000, v158
	v_rsq_f32_e32 v162, v151
	v_ashrrev_i32_e32 v151, 31, v150
	v_lshl_add_u64 v[150:151], v[150:151], 1, s[26:27]
	v_lshl_add_u64 v[164:165], v[150:151], 0, v[172:173]
	v_pk_fma_f32 v[124:125], v[124:125], v[162:163], 0 op_sel_hi:[1,0,0]
	v_pk_fma_f32 v[126:127], v[126:127], v[162:163], 0 op_sel_hi:[1,0,0]
	v_pk_fma_f32 v[120:121], v[120:121], v[162:163], 0 op_sel_hi:[1,0,0]
	v_pk_fma_f32 v[122:123], v[122:123], v[162:163], 0 op_sel_hi:[1,0,0]
	v_pk_fma_f32 v[112:113], v[112:113], v[162:163], 0 op_sel_hi:[1,0,0]
	v_pk_fma_f32 v[114:115], v[114:115], v[162:163], 0 op_sel_hi:[1,0,0]
	v_pk_fma_f32 v[116:117], v[116:117], v[162:163], 0 op_sel_hi:[1,0,0]
	v_pk_fma_f32 v[118:119], v[118:119], v[162:163], 0 op_sel_hi:[1,0,0]
	v_pk_mul_f32 v[126:127], v[148:149], v[126:127] op_sel_hi:[0,1]
	v_pk_mul_f32 v[124:125], v[148:149], v[124:125] op_sel_hi:[0,1]
	v_pk_mul_f32 v[122:123], v[148:149], v[122:123] op_sel_hi:[0,1]
	v_pk_mul_f32 v[120:121], v[148:149], v[120:121] op_sel_hi:[0,1]
	v_pk_mul_f32 v[162:163], v[148:149], v[114:115] op_sel_hi:[0,1]
	v_pk_mul_f32 v[166:167], v[148:149], v[112:113] op_sel_hi:[0,1]
	v_cvt_pk_bf16_f32 v112, v124, v125
	v_cvt_pk_bf16_f32 v113, v126, v127
	v_cvt_pk_bf16_f32 v114, v120, v121
	v_cvt_pk_bf16_f32 v115, v122, v123
	v_pk_mul_f32 v[118:119], v[148:149], v[118:119] op_sel_hi:[0,1]
	v_pk_mul_f32 v[116:117], v[148:149], v[116:117] op_sel_hi:[0,1]
	global_store_dwordx4 v[164:165], v[112:115], off sc1
	s_nop 1
	v_cvt_pk_bf16_f32 v112, v116, v117
	v_cvt_pk_bf16_f32 v113, v118, v119
	v_cvt_pk_bf16_f32 v114, v166, v167
	v_cvt_pk_bf16_f32 v115, v162, v163
	global_store_dwordx4 v[164:165], v[112:115], off offset:256 sc1
	global_load_dwordx4 v[112:115], v[174:175], off
	s_nop 0
	global_load_dwordx4 v[116:119], v[174:175], off offset:64
	s_waitcnt vmcnt(1)
	v_mov_b32_e32 v120, v112
	s_waitcnt vmcnt(0)
	v_mov_b32_e32 v121, v116
	v_mov_b32_e32 v116, v113
	v_mov_b32_e32 v112, v114
	v_mov_b32_e32 v113, v118
	v_mov_b32_e32 v118, v115
	v_pk_add_f32 v[114:115], v[120:121], v[116:117]
	v_pk_add_f32 v[112:113], v[112:113], v[118:119]
	s_nop 0
	v_pk_add_f32 v[112:113], v[114:115], v[112:113]
	v_lshlrev_b64 v[114:115], 12, v[170:171]
	v_add_f32_e32 v112, 0, v112
	v_add_f32_e32 v112, v112, v113
	ds_bpermute_b32 v113, v160, v112
	v_lshl_add_u64 v[114:115], v[150:151], 0, v[114:115]
	s_waitcnt lgkmcnt(0)
	v_add_f32_e32 v116, v112, v113
	ds_bpermute_b32 v117, v147, v116
	v_or_b32_e32 v112, 32, v146
	v_ashrrev_i32_e32 v113, 31, v112
	v_lshlrev_b64 v[118:119], 7, v[112:113]
	v_lshl_add_u64 v[118:119], v[136:137], 0, v[118:119]
	s_waitcnt lgkmcnt(0)
	v_add_f32_e32 v116, v116, v117
	v_fmamk_f32 v116, v116, 0x3a000000, v158
	v_rsq_f32_e32 v116, v116
	s_nop 0
	v_pk_fma_f32 v[108:109], v[108:109], v[116:117], 0 op_sel_hi:[1,0,0]
	v_pk_fma_f32 v[110:111], v[110:111], v[116:117], 0 op_sel_hi:[1,0,0]
	v_pk_fma_f32 v[104:105], v[104:105], v[116:117], 0 op_sel_hi:[1,0,0]
	v_pk_fma_f32 v[106:107], v[106:107], v[116:117], 0 op_sel_hi:[1,0,0]
	v_pk_fma_f32 v[96:97], v[96:97], v[116:117], 0 op_sel_hi:[1,0,0]
	v_pk_fma_f32 v[98:99], v[98:99], v[116:117], 0 op_sel_hi:[1,0,0]
	v_pk_fma_f32 v[100:101], v[100:101], v[116:117], 0 op_sel_hi:[1,0,0]
	v_pk_fma_f32 v[102:103], v[102:103], v[116:117], 0 op_sel_hi:[1,0,0]
	v_pk_mul_f32 v[110:111], v[148:149], v[110:111] op_sel_hi:[0,1]
	v_pk_mul_f32 v[108:109], v[148:149], v[108:109] op_sel_hi:[0,1]
	v_pk_mul_f32 v[106:107], v[148:149], v[106:107] op_sel_hi:[0,1]
	v_pk_mul_f32 v[104:105], v[148:149], v[104:105] op_sel_hi:[0,1]
	v_pk_mul_f32 v[116:117], v[148:149], v[98:99] op_sel_hi:[0,1]
	v_pk_mul_f32 v[120:121], v[148:149], v[96:97] op_sel_hi:[0,1]
	v_cvt_pk_bf16_f32 v96, v108, v109
	v_cvt_pk_bf16_f32 v97, v110, v111
	v_cvt_pk_bf16_f32 v98, v104, v105
	v_cvt_pk_bf16_f32 v99, v106, v107
	v_pk_mul_f32 v[102:103], v[148:149], v[102:103] op_sel_hi:[0,1]
	v_pk_mul_f32 v[100:101], v[148:149], v[100:101] op_sel_hi:[0,1]
	global_store_dwordx4 v[114:115], v[96:99], off sc1
	s_nop 1
	v_cvt_pk_bf16_f32 v96, v100, v101
	v_cvt_pk_bf16_f32 v97, v102, v103
	v_cvt_pk_bf16_f32 v98, v120, v121
	v_cvt_pk_bf16_f32 v99, v116, v117
	global_store_dwordx4 v[114:115], v[96:99], off offset:256 sc1
	global_load_dwordx4 v[96:99], v[118:119], off
	s_nop 0
	global_load_dwordx4 v[100:103], v[118:119], off offset:64
	s_waitcnt vmcnt(1)
; __device__ __forceinline__ unsigned cvt_pk_bf16(float lo, float hi) { unsigned r; asm volatile("v_cvt_pk_bf16_f32 %0, %1, %2" : "=v"(r) : "v"(lo), "v"(hi)); return r; }
; __device__ __forceinline__ float row_ss(const float* part, int row, int fq, int nf4) {
;     const f32x4* p = (const f32x4*)(part + (size_t)row * 32);
;     float s = 0.f;
; #pragma unroll
;     for (int j = 0; j < 2; ++j) { const int idx = fq + 4 * j; if (idx < nf4) { const f32x4 v = p[idx]; s += (v[0] + v[1]) + (v[2] + v[3]); } }
;     s += __shfl_xor(s, 16); s += __shfl_xor(s, 32);
;     return s;
;     __device__ __forceinline__ void operator()(const f32x4 (&acc)[2][2][4][2], const Unit& u, int wr, int wc, int fr, int fq) const {
;     ...
;             for (int m = 0; m < 4; ++m) { const int row = row0 + ai * HALF + m * 16; bf16_t* rowp = base + (size_t)row * ldc + col0;
;                 const float rs = rss ? __builtin_amdgcn_rsqf(row_ss(rss, row, fq, nf4) * rinv + 1e-6f) : 1.f;
; #pragma unroll
;                 for (int bj = 0; bj < 2; ++bj) { f32x4 v0 = acc[ai][bj][m][0] * rs + bv[bj][0], v1 = acc[ai][bj][m][1] * rs + bv[bj][1];
;                     v0 = v0 * sc; v1 = v1 * sc; u32x4 w; w.x = cvt_pk_bf16(v0[0], v0[1]); w.y = cvt_pk_bf16(v0[2], v0[3]); w.z = cvt_pk_bf16(v1[0], v1[1]); w.w = cvt_pk_bf16(v1[2], v1[3]);
;                     *(u32x4*)(rowp + bj * HALF) = w; } }
	v_mov_b32_e32 v104, v96
	s_waitcnt vmcnt(0)
	v_mov_b32_e32 v105, v100
	v_mov_b32_e32 v100, v97
	v_mov_b32_e32 v96, v98
	v_mov_b32_e32 v97, v102
	v_mov_b32_e32 v102, v99
	v_pk_add_f32 v[98:99], v[104:105], v[100:101]
	v_pk_add_f32 v[96:97], v[96:97], v[102:103]
	s_nop 0
	v_pk_add_f32 v[96:97], v[98:99], v[96:97]
	v_lshlrev_b64 v[98:99], 12, v[112:113]
	v_add_f32_e32 v96, 0, v96
	v_add_f32_e32 v96, v96, v97
	ds_bpermute_b32 v97, v160, v96
	v_lshl_add_u64 v[98:99], v[150:151], 0, v[98:99]
	s_waitcnt lgkmcnt(0)
	v_add_f32_e32 v100, v96, v97
	ds_bpermute_b32 v101, v147, v100
	v_or_b32_e32 v96, 48, v146
	v_ashrrev_i32_e32 v97, 31, v96
	v_lshlrev_b64 v[102:103], 7, v[96:97]
	v_lshl_add_u64 v[102:103], v[136:137], 0, v[102:103]
	s_waitcnt lgkmcnt(0)
	v_add_f32_e32 v100, v100, v101
	v_fmamk_f32 v100, v100, 0x3a000000, v158
	v_rsq_f32_e32 v100, v100
	s_nop 0
	v_pk_fma_f32 v[92:93], v[92:93], v[100:101], 0 op_sel_hi:[1,0,0]
	v_pk_fma_f32 v[94:95], v[94:95], v[100:101], 0 op_sel_hi:[1,0,0]
	v_pk_fma_f32 v[88:89], v[88:89], v[100:101], 0 op_sel_hi:[1,0,0]
	v_pk_fma_f32 v[90:91], v[90:91], v[100:101], 0 op_sel_hi:[1,0,0]
	v_pk_fma_f32 v[80:81], v[80:81], v[100:101], 0 op_sel_hi:[1,0,0]
	v_pk_fma_f32 v[82:83], v[82:83], v[100:101], 0 op_sel_hi:[1,0,0]
	v_pk_fma_f32 v[84:85], v[84:85], v[100:101], 0 op_sel_hi:[1,0,0]
	v_pk_fma_f32 v[86:87], v[86:87], v[100:101], 0 op_sel_hi:[1,0,0]
	v_pk_mul_f32 v[94:95], v[148:149], v[94:95] op_sel_hi:[0,1]
	v_pk_mul_f32 v[92:93], v[148:149], v[92:93] op_sel_hi:[0,1]
	v_pk_mul_f32 v[90:91], v[148:149], v[90:91] op_sel_hi:[0,1]
	v_pk_mul_f32 v[88:89], v[148:149], v[88:89] op_sel_hi:[0,1]
	v_pk_mul_f32 v[100:101], v[148:149], v[82:83] op_sel_hi:[0,1]
	v_pk_mul_f32 v[104:105], v[148:149], v[80:81] op_sel_hi:[0,1]
	v_cvt_pk_bf16_f32 v80, v92, v93
	v_cvt_pk_bf16_f32 v81, v94, v95
	v_cvt_pk_bf16_f32 v82, v88, v89
	v_cvt_pk_bf16_f32 v83, v90, v91
	v_pk_mul_f32 v[86:87], v[148:149], v[86:87] op_sel_hi:[0,1]
	v_pk_mul_f32 v[84:85], v[148:149], v[84:85] op_sel_hi:[0,1]
	global_store_dwordx4 v[98:99], v[80:83], off sc1
	s_nop 1
	v_cvt_pk_bf16_f32 v80, v84, v85
	v_cvt_pk_bf16_f32 v81, v86, v87
	v_cvt_pk_bf16_f32 v82, v104, v105
	v_cvt_pk_bf16_f32 v83, v100, v101
	global_store_dwordx4 v[98:99], v[80:83], off offset:256 sc1
	global_load_dwordx4 v[80:83], v[102:103], off
	s_nop 0
	global_load_dwordx4 v[84:87], v[102:103], off offset:64
	s_waitcnt vmcnt(1)
	v_mov_b32_e32 v88, v80
	s_waitcnt vmcnt(0)
	v_mov_b32_e32 v89, v84
	v_mov_b32_e32 v84, v81
	v_mov_b32_e32 v80, v82
	v_mov_b32_e32 v81, v86
	v_mov_b32_e32 v86, v83
	v_pk_add_f32 v[82:83], v[88:89], v[84:85]
	v_pk_add_f32 v[80:81], v[80:81], v[86:87]
	s_nop 0
	v_pk_add_f32 v[80:81], v[82:83], v[80:81]
	v_lshlrev_b64 v[82:83], 12, v[96:97]
	v_add_f32_e32 v80, 0, v80
	v_add_f32_e32 v80, v80, v81
	ds_bpermute_b32 v81, v160, v80
	v_lshl_add_u64 v[82:83], v[150:151], 0, v[82:83]
	s_waitcnt lgkmcnt(0)
	v_add_f32_e32 v84, v80, v81
	ds_bpermute_b32 v85, v147, v84
	v_add_u32_e32 v80, 0x80, v146
	v_ashrrev_i32_e32 v81, 31, v80
	v_lshlrev_b64 v[86:87], 7, v[80:81]
	v_lshl_add_u64 v[86:87], v[136:137], 0, v[86:87]
	s_waitcnt lgkmcnt(0)
	v_add_f32_e32 v84, v84, v85
	v_fmamk_f32 v84, v84, 0x3a000000, v158
	v_rsq_f32_e32 v84, v84
	s_nop 0
	v_pk_fma_f32 v[76:77], v[76:77], v[84:85], 0 op_sel_hi:[1,0,0]
	v_pk_fma_f32 v[78:79], v[78:79], v[84:85], 0 op_sel_hi:[1,0,0]
	v_pk_fma_f32 v[72:73], v[72:73], v[84:85], 0 op_sel_hi:[1,0,0]
	v_pk_fma_f32 v[74:75], v[74:75], v[84:85], 0 op_sel_hi:[1,0,0]
	v_pk_fma_f32 v[64:65], v[64:65], v[84:85], 0 op_sel_hi:[1,0,0]
	v_pk_fma_f32 v[66:67], v[66:67], v[84:85], 0 op_sel_hi:[1,0,0]
	v_pk_fma_f32 v[68:69], v[68:69], v[84:85], 0 op_sel_hi:[1,0,0]
	v_pk_fma_f32 v[70:71], v[70:71], v[84:85], 0 op_sel_hi:[1,0,0]
	v_pk_mul_f32 v[78:79], v[148:149], v[78:79] op_sel_hi:[0,1]
	v_pk_mul_f32 v[76:77], v[148:149], v[76:77] op_sel_hi:[0,1]
	v_pk_mul_f32 v[74:75], v[148:149], v[74:75] op_sel_hi:[0,1]
	v_pk_mul_f32 v[72:73], v[148:149], v[72:73] op_sel_hi:[0,1]
	v_pk_mul_f32 v[84:85], v[148:149], v[66:67] op_sel_hi:[0,1]
	v_pk_mul_f32 v[88:89], v[148:149], v[64:65] op_sel_hi:[0,1]
	v_cvt_pk_bf16_f32 v64, v76, v77
	v_cvt_pk_bf16_f32 v65, v78, v79
	v_cvt_pk_bf16_f32 v66, v72, v73
	v_cvt_pk_bf16_f32 v67, v74, v75
	v_pk_mul_f32 v[70:71], v[148:149], v[70:71] op_sel_hi:[0,1]
	v_pk_mul_f32 v[68:69], v[148:149], v[68:69] op_sel_hi:[0,1]
	global_store_dwordx4 v[82:83], v[64:67], off sc1
	s_nop 1
	v_cvt_pk_bf16_f32 v64, v68, v69
	v_cvt_pk_bf16_f32 v65, v70, v71
	v_cvt_pk_bf16_f32 v66, v88, v89
	v_cvt_pk_bf16_f32 v67, v84, v85
	global_store_dwordx4 v[82:83], v[64:67], off offset:256 sc1
	global_load_dwordx4 v[64:67], v[86:87], off
	s_nop 0
	global_load_dwordx4 v[68:71], v[86:87], off offset:64
	s_waitcnt vmcnt(1)
	v_mov_b32_e32 v72, v64
	s_waitcnt vmcnt(0)
	v_mov_b32_e32 v73, v68
	v_mov_b32_e32 v68, v65
	v_mov_b32_e32 v64, v66
	v_mov_b32_e32 v65, v70
	v_mov_b32_e32 v70, v67
	v_pk_add_f32 v[66:67], v[72:73], v[68:69]
	v_pk_add_f32 v[64:65], v[64:65], v[70:71]
	s_nop 0
	v_pk_add_f32 v[64:65], v[66:67], v[64:65]
	v_lshlrev_b64 v[66:67], 12, v[80:81]
	v_add_f32_e32 v64, 0, v64
	v_add_f32_e32 v64, v64, v65
	ds_bpermute_b32 v65, v160, v64
	v_lshl_add_u64 v[66:67], v[150:151], 0, v[66:67]
	s_waitcnt lgkmcnt(0)
	v_add_f32_e32 v68, v64, v65
	ds_bpermute_b32 v69, v147, v68
	v_add_u32_e32 v64, 0x90, v146
	v_ashrrev_i32_e32 v65, 31, v64
	v_lshlrev_b64 v[70:71], 7, v[64:65]
	v_lshl_add_u64 v[70:71], v[136:137], 0, v[70:71]
	s_waitcnt lgkmcnt(0)
; __device__ __forceinline__ unsigned cvt_pk_bf16(float lo, float hi) { unsigned r; asm volatile("v_cvt_pk_bf16_f32 %0, %1, %2" : "=v"(r) : "v"(lo), "v"(hi)); return r; }
; __device__ __forceinline__ float row_ss(const float* part, int row, int fq, int nf4) {
;     const f32x4* p = (const f32x4*)(part + (size_t)row * 32);
;     float s = 0.f;
; #pragma unroll
;     for (int j = 0; j < 2; ++j) { const int idx = fq + 4 * j; if (idx < nf4) { const f32x4 v = p[idx]; s += (v[0] + v[1]) + (v[2] + v[3]); } }
;     s += __shfl_xor(s, 16); s += __shfl_xor(s, 32);
;     return s;
;     __device__ __forceinline__ void operator()(const f32x4 (&acc)[2][2][4][2], const Unit& u, int wr, int wc, int fr, int fq) const {
;     ...
;             for (int m = 0; m < 4; ++m) { const int row = row0 + ai * HALF + m * 16; bf16_t* rowp = base + (size_t)row * ldc + col0;
;                 const float rs = rss ? __builtin_amdgcn_rsqf(row_ss(rss, row, fq, nf4) * rinv + 1e-6f) : 1.f;
; #pragma unroll
;                 for (int bj = 0; bj < 2; ++bj) { f32x4 v0 = acc[ai][bj][m][0] * rs + bv[bj][0], v1 = acc[ai][bj][m][1] * rs + bv[bj][1];
;                     v0 = v0 * sc; v1 = v1 * sc; u32x4 w; w.x = cvt_pk_bf16(v0[0], v0[1]); w.y = cvt_pk_bf16(v0[2], v0[3]); w.z = cvt_pk_bf16(v1[0], v1[1]); w.w = cvt_pk_bf16(v1[2], v1[3]);
;                     *(u32x4*)(rowp + bj * HALF) = w; } }
	v_add_f32_e32 v68, v68, v69
	v_fmamk_f32 v68, v68, 0x3a000000, v158
	v_rsq_f32_e32 v68, v68
	s_nop 0
	v_pk_fma_f32 v[60:61], v[60:61], v[68:69], 0 op_sel_hi:[1,0,0]
	v_pk_fma_f32 v[62:63], v[62:63], v[68:69], 0 op_sel_hi:[1,0,0]
	v_pk_fma_f32 v[56:57], v[56:57], v[68:69], 0 op_sel_hi:[1,0,0]
	v_pk_fma_f32 v[58:59], v[58:59], v[68:69], 0 op_sel_hi:[1,0,0]
	v_pk_fma_f32 v[48:49], v[48:49], v[68:69], 0 op_sel_hi:[1,0,0]
	v_pk_fma_f32 v[50:51], v[50:51], v[68:69], 0 op_sel_hi:[1,0,0]
	v_pk_fma_f32 v[52:53], v[52:53], v[68:69], 0 op_sel_hi:[1,0,0]
	v_pk_fma_f32 v[54:55], v[54:55], v[68:69], 0 op_sel_hi:[1,0,0]
	v_pk_mul_f32 v[62:63], v[148:149], v[62:63] op_sel_hi:[0,1]
	v_pk_mul_f32 v[60:61], v[148:149], v[60:61] op_sel_hi:[0,1]
	v_pk_mul_f32 v[58:59], v[148:149], v[58:59] op_sel_hi:[0,1]
	v_pk_mul_f32 v[56:57], v[148:149], v[56:57] op_sel_hi:[0,1]
	v_pk_mul_f32 v[68:69], v[148:149], v[50:51] op_sel_hi:[0,1]
	v_pk_mul_f32 v[72:73], v[148:149], v[48:49] op_sel_hi:[0,1]
	v_cvt_pk_bf16_f32 v48, v60, v61
	v_cvt_pk_bf16_f32 v49, v62, v63
	v_cvt_pk_bf16_f32 v50, v56, v57
	v_cvt_pk_bf16_f32 v51, v58, v59
	v_pk_mul_f32 v[54:55], v[148:149], v[54:55] op_sel_hi:[0,1]
	v_pk_mul_f32 v[52:53], v[148:149], v[52:53] op_sel_hi:[0,1]
	global_store_dwordx4 v[66:67], v[48:51], off sc1
	s_nop 1
	v_cvt_pk_bf16_f32 v48, v52, v53
	v_cvt_pk_bf16_f32 v49, v54, v55
	v_cvt_pk_bf16_f32 v50, v72, v73
	v_cvt_pk_bf16_f32 v51, v68, v69
	global_store_dwordx4 v[66:67], v[48:51], off offset:256 sc1
	global_load_dwordx4 v[48:51], v[70:71], off
	s_nop 0
	global_load_dwordx4 v[52:55], v[70:71], off offset:64
	s_waitcnt vmcnt(1)
	v_mov_b32_e32 v56, v48
	s_waitcnt vmcnt(0)
	v_mov_b32_e32 v57, v52
	v_mov_b32_e32 v52, v49
	v_mov_b32_e32 v48, v50
	v_mov_b32_e32 v49, v54
	v_mov_b32_e32 v54, v51
	v_pk_add_f32 v[50:51], v[56:57], v[52:53]
	v_pk_add_f32 v[48:49], v[48:49], v[54:55]
	s_nop 0
	v_pk_add_f32 v[48:49], v[50:51], v[48:49]
	v_lshlrev_b64 v[50:51], 12, v[64:65]
	v_add_f32_e32 v48, 0, v48
	v_add_f32_e32 v48, v48, v49
	ds_bpermute_b32 v49, v160, v48
	v_lshl_add_u64 v[50:51], v[150:151], 0, v[50:51]
	s_waitcnt lgkmcnt(0)
	v_add_f32_e32 v52, v48, v49
	ds_bpermute_b32 v53, v147, v52
	v_add_u32_e32 v48, 0xa0, v146
	v_ashrrev_i32_e32 v49, 31, v48
	v_lshlrev_b64 v[54:55], 7, v[48:49]
	v_lshl_add_u64 v[54:55], v[136:137], 0, v[54:55]
	s_waitcnt lgkmcnt(0)
	v_add_f32_e32 v52, v52, v53
	v_fmamk_f32 v52, v52, 0x3a000000, v158
	v_rsq_f32_e32 v52, v52
	s_nop 0
	v_pk_fma_f32 v[44:45], v[44:45], v[52:53], 0 op_sel_hi:[1,0,0]
	v_pk_fma_f32 v[46:47], v[46:47], v[52:53], 0 op_sel_hi:[1,0,0]
	v_pk_fma_f32 v[40:41], v[40:41], v[52:53], 0 op_sel_hi:[1,0,0]
	v_pk_fma_f32 v[42:43], v[42:43], v[52:53], 0 op_sel_hi:[1,0,0]
	v_pk_fma_f32 v[32:33], v[32:33], v[52:53], 0 op_sel_hi:[1,0,0]
	v_pk_fma_f32 v[34:35], v[34:35], v[52:53], 0 op_sel_hi:[1,0,0]
	v_pk_fma_f32 v[36:37], v[36:37], v[52:53], 0 op_sel_hi:[1,0,0]
	v_pk_fma_f32 v[38:39], v[38:39], v[52:53], 0 op_sel_hi:[1,0,0]
	v_pk_mul_f32 v[46:47], v[148:149], v[46:47] op_sel_hi:[0,1]
	v_pk_mul_f32 v[44:45], v[148:149], v[44:45] op_sel_hi:[0,1]
	v_pk_mul_f32 v[42:43], v[148:149], v[42:43] op_sel_hi:[0,1]
	v_pk_mul_f32 v[40:41], v[148:149], v[40:41] op_sel_hi:[0,1]
	v_pk_mul_f32 v[52:53], v[148:149], v[34:35] op_sel_hi:[0,1]
	v_pk_mul_f32 v[56:57], v[148:149], v[32:33] op_sel_hi:[0,1]
	v_cvt_pk_bf16_f32 v32, v44, v45
	v_cvt_pk_bf16_f32 v33, v46, v47
	v_cvt_pk_bf16_f32 v34, v40, v41
	v_cvt_pk_bf16_f32 v35, v42, v43
	v_pk_mul_f32 v[38:39], v[148:149], v[38:39] op_sel_hi:[0,1]
	v_pk_mul_f32 v[36:37], v[148:149], v[36:37] op_sel_hi:[0,1]
	global_store_dwordx4 v[50:51], v[32:35], off sc1
	s_nop 1
	v_cvt_pk_bf16_f32 v32, v36, v37
	v_cvt_pk_bf16_f32 v33, v38, v39
	v_cvt_pk_bf16_f32 v34, v56, v57
	v_cvt_pk_bf16_f32 v35, v52, v53
	global_store_dwordx4 v[50:51], v[32:35], off offset:256 sc1
	global_load_dwordx4 v[32:35], v[54:55], off
	s_nop 0
	global_load_dwordx4 v[36:39], v[54:55], off offset:64
	s_waitcnt vmcnt(1)
	v_mov_b32_e32 v40, v32
	s_waitcnt vmcnt(0)
; __device__ __forceinline__ unsigned cvt_pk_bf16(float lo, float hi) { unsigned r; asm volatile("v_cvt_pk_bf16_f32 %0, %1, %2" : "=v"(r) : "v"(lo), "v"(hi)); return r; }
; #define PG8_BAR __builtin_amdgcn_s_barrier()
; __device__ __forceinline__ float row_ss(const float* part, int row, int fq, int nf4) {
;     const f32x4* p = (const f32x4*)(part + (size_t)row * 32);
;     float s = 0.f;
; #pragma unroll
;     for (int j = 0; j < 2; ++j) { const int idx = fq + 4 * j; if (idx < nf4) { const f32x4 v = p[idx]; s += (v[0] + v[1]) + (v[2] + v[3]); } }
;     s += __shfl_xor(s, 16); s += __shfl_xor(s, 32);
;     return s;
;     __device__ __forceinline__ void operator()(const f32x4 (&acc)[2][2][4][2], const Unit& u, int wr, int wc, int fr, int fq) const {
;     ...
;             for (int m = 0; m < 4; ++m) { const int row = row0 + ai * HALF + m * 16; bf16_t* rowp = base + (size_t)row * ldc + col0;
;                 const float rs = rss ? __builtin_amdgcn_rsqf(row_ss(rss, row, fq, nf4) * rinv + 1e-6f) : 1.f;
; #pragma unroll
;                 for (int bj = 0; bj < 2; ++bj) { f32x4 v0 = acc[ai][bj][m][0] * rs + bv[bj][0], v1 = acc[ai][bj][m][1] * rs + bv[bj][1];
;                     v0 = v0 * sc; v1 = v1 * sc; u32x4 w; w.x = cvt_pk_bf16(v0[0], v0[1]); w.y = cvt_pk_bf16(v0[2], v0[3]); w.z = cvt_pk_bf16(v1[0], v1[1]); w.w = cvt_pk_bf16(v1[2], v1[3]);
;                     *(u32x4*)(rowp + bj * HALF) = w; } }
; template <class Epi, class Sched, bool ALIGN_EPI = false, bool SP2 = false>
; __device__ __forceinline__ void gemm_phase(PG8_LAS unsigned char* lds, const Gemm g, const Sched& S, const Epi& E) {
;     ...
;         if constexpr (ALIGN_EPI) { if (wr == 0) PG8_BAR; }
;         if constexpr (!Epi::AFTER_DRAIN) { E(acc, cur, wr, wc, fr, fq); S.done(cur); }
;         if (!has_next) break;
; #pragma unroll
;         for (int a = 0; a < 2; ++a)
; #pragma unroll
;             for (int b = 0; b < 2; ++b)
; #pragma unroll
;                 for (int m = 0; m < 4; ++m)
; #pragma unroll
;                     for (int n = 0; n < 2; ++n) acc[a][b][m][n] = (f32x4){0.f, 0.f, 0.f, 0.f};
;         cur = nxt; cA = nA; cB = nB; ++ui;
;         if constexpr (ALIGN_EPI) { if (wr == 1) PG8_BAR; }
	v_mov_b32_e32 v41, v36
	v_mov_b32_e32 v36, v33
	v_mov_b32_e32 v32, v34
	v_mov_b32_e32 v33, v38
	v_mov_b32_e32 v38, v35
	v_pk_add_f32 v[34:35], v[40:41], v[36:37]
	v_pk_add_f32 v[32:33], v[32:33], v[38:39]
	s_nop 0
	v_pk_add_f32 v[32:33], v[34:35], v[32:33]
	v_lshlrev_b64 v[34:35], 12, v[48:49]
	v_add_f32_e32 v32, 0, v32
	v_add_f32_e32 v32, v32, v33
	ds_bpermute_b32 v33, v160, v32
	v_lshl_add_u64 v[34:35], v[150:151], 0, v[34:35]
	s_waitcnt lgkmcnt(0)
	v_add_f32_e32 v36, v32, v33
	ds_bpermute_b32 v37, v147, v36
	v_add_u32_e32 v32, 0xb0, v146
	v_ashrrev_i32_e32 v33, 31, v32
	v_lshlrev_b64 v[38:39], 7, v[32:33]
	v_lshl_add_u64 v[38:39], v[136:137], 0, v[38:39]
	s_waitcnt lgkmcnt(0)
	v_add_f32_e32 v36, v36, v37
	v_fmamk_f32 v36, v36, 0x3a000000, v158
	v_rsq_f32_e32 v36, v36
	s_nop 0
	v_pk_fma_f32 v[28:29], v[28:29], v[36:37], 0 op_sel_hi:[1,0,0]
	v_pk_fma_f32 v[30:31], v[30:31], v[36:37], 0 op_sel_hi:[1,0,0]
	v_pk_fma_f32 v[24:25], v[24:25], v[36:37], 0 op_sel_hi:[1,0,0]
	v_pk_fma_f32 v[26:27], v[26:27], v[36:37], 0 op_sel_hi:[1,0,0]
	v_pk_fma_f32 v[16:17], v[16:17], v[36:37], 0 op_sel_hi:[1,0,0]
	v_pk_fma_f32 v[18:19], v[18:19], v[36:37], 0 op_sel_hi:[1,0,0]
	v_pk_fma_f32 v[20:21], v[20:21], v[36:37], 0 op_sel_hi:[1,0,0]
	v_pk_fma_f32 v[22:23], v[22:23], v[36:37], 0 op_sel_hi:[1,0,0]
	v_pk_mul_f32 v[30:31], v[148:149], v[30:31] op_sel_hi:[0,1]
	v_pk_mul_f32 v[28:29], v[148:149], v[28:29] op_sel_hi:[0,1]
	v_pk_mul_f32 v[26:27], v[148:149], v[26:27] op_sel_hi:[0,1]
	v_pk_mul_f32 v[24:25], v[148:149], v[24:25] op_sel_hi:[0,1]
	v_pk_mul_f32 v[36:37], v[148:149], v[18:19] op_sel_hi:[0,1]
	v_pk_mul_f32 v[40:41], v[148:149], v[16:17] op_sel_hi:[0,1]
	v_cvt_pk_bf16_f32 v16, v28, v29
	v_cvt_pk_bf16_f32 v17, v30, v31
	v_cvt_pk_bf16_f32 v18, v24, v25
	v_cvt_pk_bf16_f32 v19, v26, v27
	v_pk_mul_f32 v[22:23], v[148:149], v[22:23] op_sel_hi:[0,1]
	v_pk_mul_f32 v[20:21], v[148:149], v[20:21] op_sel_hi:[0,1]
	global_store_dwordx4 v[34:35], v[16:19], off sc1
	s_nop 1
	v_cvt_pk_bf16_f32 v16, v20, v21
	v_cvt_pk_bf16_f32 v17, v22, v23
	v_cvt_pk_bf16_f32 v18, v40, v41
	v_cvt_pk_bf16_f32 v19, v36, v37
	global_store_dwordx4 v[34:35], v[16:19], off offset:256 sc1
	global_load_dwordx4 v[16:19], v[38:39], off
	s_nop 0
	global_load_dwordx4 v[20:23], v[38:39], off offset:64
	s_waitcnt vmcnt(1)
	v_mov_b32_e32 v24, v16
	s_waitcnt vmcnt(0)
	v_mov_b32_e32 v25, v20
	v_mov_b32_e32 v20, v17
	v_mov_b32_e32 v16, v18
	v_mov_b32_e32 v17, v22
	v_mov_b32_e32 v22, v19
	v_pk_add_f32 v[18:19], v[24:25], v[20:21]
	v_pk_add_f32 v[16:17], v[16:17], v[22:23]
	s_nop 0
	v_pk_add_f32 v[16:17], v[18:19], v[16:17]
	v_lshlrev_b64 v[18:19], 12, v[32:33]
	v_add_f32_e32 v16, 0, v16
	v_add_f32_e32 v16, v16, v17
	ds_bpermute_b32 v17, v160, v16
	v_lshl_add_u64 v[18:19], v[150:151], 0, v[18:19]
	s_waitcnt lgkmcnt(0)
	v_add_f32_e32 v16, v16, v17
	ds_bpermute_b32 v17, v147, v16
	s_waitcnt lgkmcnt(0)
	v_add_f32_e32 v16, v16, v17
	v_fmamk_f32 v16, v16, 0x3a000000, v158
	v_rsq_f32_e32 v16, v16
	s_nop 0
	v_pk_fma_f32 v[12:13], v[12:13], v[16:17], 0 op_sel_hi:[1,0,0]
	v_pk_fma_f32 v[14:15], v[14:15], v[16:17], 0 op_sel_hi:[1,0,0]
	v_pk_fma_f32 v[8:9], v[8:9], v[16:17], 0 op_sel_hi:[1,0,0]
	v_pk_fma_f32 v[10:11], v[10:11], v[16:17], 0 op_sel_hi:[1,0,0]
	v_pk_fma_f32 v[0:1], v[0:1], v[16:17], 0 op_sel_hi:[1,0,0]
	v_pk_fma_f32 v[2:3], v[2:3], v[16:17], 0 op_sel_hi:[1,0,0]
	v_pk_fma_f32 v[4:5], v[4:5], v[16:17], 0 op_sel_hi:[1,0,0]
	v_pk_fma_f32 v[6:7], v[6:7], v[16:17], 0 op_sel_hi:[1,0,0]
	v_pk_mul_f32 v[14:15], v[148:149], v[14:15] op_sel_hi:[0,1]
	v_pk_mul_f32 v[12:13], v[148:149], v[12:13] op_sel_hi:[0,1]
	v_pk_mul_f32 v[10:11], v[148:149], v[10:11] op_sel_hi:[0,1]
	v_pk_mul_f32 v[8:9], v[148:149], v[8:9] op_sel_hi:[0,1]
	v_pk_mul_f32 v[16:17], v[148:149], v[2:3] op_sel_hi:[0,1]
	v_pk_mul_f32 v[20:21], v[148:149], v[0:1] op_sel_hi:[0,1]
	v_cvt_pk_bf16_f32 v0, v12, v13
	v_cvt_pk_bf16_f32 v1, v14, v15
	v_cvt_pk_bf16_f32 v2, v8, v9
	v_cvt_pk_bf16_f32 v3, v10, v11
	v_pk_mul_f32 v[6:7], v[148:149], v[6:7] op_sel_hi:[0,1]
	v_pk_mul_f32 v[4:5], v[148:149], v[4:5] op_sel_hi:[0,1]
	global_store_dwordx4 v[18:19], v[0:3], off sc1
	s_nop 1
	v_cvt_pk_bf16_f32 v0, v4, v5
	v_cvt_pk_bf16_f32 v1, v6, v7
	v_cvt_pk_bf16_f32 v2, v20, v21
	v_cvt_pk_bf16_f32 v3, v16, v17
	global_store_dwordx4 v[18:19], v[0:3], off offset:256 sc1
	s_cbranch_vccnz .LBB0_2017
	s_andn2_b64 vcc, exec, s[0:1]
	s_cbranch_vccnz .LBB0_2016
	s_barrier
	s_branch .LBB0_2016

; __device__ __forceinline__ unsigned cvt_pk_bf16(float lo, float hi) { unsigned r; asm volatile("v_cvt_pk_bf16_f32 %0, %1, %2" : "=v"(r) : "v"(lo), "v"(hi)); return r; }
;     __device__ __forceinline__ void operator()(const f32x4 (&acc)[2][2][4][2], const Unit& u, int wr, int wc, int fr, int fq) const {
;     ...
;             for (int n = 0; n < 2; ++n) bv[bj][n] = bias ? *(const f32x4*)(bias + col0 + bj * HALF + 4 * n) : (f32x4){0.f, 0.f, 0.f, 0.f};
;         float* ssp = ssout + (size_t)(u.pn * 4 + wc);
; #pragma unroll
;         for (int ai = 0; ai < 2; ++ai) {
;             u32x4 old[4][2];
; #pragma unroll
;             for (int m = 0; m < 4; ++m)
; #pragma unroll
;                 for (int bj = 0; bj < 2; ++bj) old[m][bj] = *(const u32x4*)(HB + (size_t)(row0 + ai * HALF + m * 16) * ldc + col0 + bj * HALF);
; #pragma unroll
;             for (int m = 0; m < 4; ++m) { const int row = row0 + ai * HALF + m * 16; float ss = 0.f;
; #pragma unroll
;                 for (int bj = 0; bj < 2; ++bj) { const u32x4 ow = old[m][bj];
;                     f32x4 v0 = (acc[ai][bj][m][0] + bv[bj][0]) * accs, v1 = (acc[ai][bj][m][1] + bv[bj][1]) * accs;
;                     v0[0] += __uint_as_float(ow.x << 16); v0[1] += __uint_as_float(ow.x & 0xffff0000u); v0[2] += __uint_as_float(ow.y << 16); v0[3] += __uint_as_float(ow.y & 0xffff0000u);
;                     v1[0] += __uint_as_float(ow.z << 16); v1[1] += __uint_as_float(ow.z & 0xffff0000u); v1[2] += __uint_as_float(ow.w << 16); v1[3] += __uint_as_float(ow.w & 0xffff0000u);
;                     ss += (v0[0] * v0[0] + v0[1] * v0[1]) + (v0[2] * v0[2] + v0[3] * v0[3]) + (v1[0] * v1[0] + v1[1] * v1[1]) + (v1[2] * v1[2] + v1[3] * v1[3]);
;                     u32x4 w; w.x = cvt_pk_bf16(v0[0], v0[1]); w.y = cvt_pk_bf16(v0[2], v0[3]); w.z = cvt_pk_bf16(v1[0], v1[1]); w.w = cvt_pk_bf16(v1[2], v1[3]);
;                     *(u32x4*)(HB + (size_t)row * ldc + col0 + bj * HALF) = w; }
;                 ss += __shfl_xor(ss, 16); ss += __shfl_xor(ss, 32);
;                 if (fq == 0) ssp[(size_t)row * 32] = ss; }
.LBB0_2198:
	v_lshl_or_b32 v152, s22, 8, v166
	v_ashrrev_i32_e32 v153, 31, v152
	v_lshl_add_u32 v156, s24, 8, v164
	v_lshlrev_b64 v[178:179], 1, v[152:153]
	v_ashrrev_i32_e32 v157, 31, v156
	v_lshl_add_u64 v[154:155], s[10:11], 0, v[178:179]
	v_lshlrev_b64 v[180:181], 12, v[156:157]
	v_lshl_add_u64 v[128:129], v[154:155], 0, v[180:181]
	global_load_dwordx4 v[170:173], v[128:129], off
	global_load_dwordx4 v[174:177], v[128:129], off offset:256
	v_or_b32_e32 v162, 16, v156
	v_or_b32_e32 v160, 32, v156
	v_or_b32_e32 v158, 48, v156
	v_ashrrev_i32_e32 v163, 31, v162
	v_ashrrev_i32_e32 v161, 31, v160
	v_pk_add_f32 v[194:195], v[114:115], 0 op_sel_hi:[1,0]
	v_pk_add_f32 v[196:197], v[112:113], 0 op_sel_hi:[1,0]
	v_ashrrev_i32_e32 v159, 31, v158
	v_lshlrev_b64 v[112:113], 12, v[162:163]
	v_lshlrev_b64 v[114:115], 12, v[160:161]
	v_pk_add_f32 v[192:193], v[116:117], 0 op_sel_hi:[1,0]
	v_lshlrev_b64 v[116:117], 12, v[158:159]
	v_lshl_add_u64 v[112:113], v[154:155], 0, v[112:113]
	v_lshl_add_u64 v[114:115], v[154:155], 0, v[114:115]
	v_pk_add_f32 v[182:183], v[126:127], 0 op_sel_hi:[1,0]
	v_pk_add_f32 v[184:185], v[124:125], 0 op_sel_hi:[1,0]
	v_pk_add_f32 v[186:187], v[122:123], 0 op_sel_hi:[1,0]
	v_pk_add_f32 v[188:189], v[120:121], 0 op_sel_hi:[1,0]
	v_pk_add_f32 v[190:191], v[118:119], 0 op_sel_hi:[1,0]
	v_lshl_add_u64 v[198:199], v[154:155], 0, v[116:117]
	global_load_dwordx4 v[132:135], v[112:113], off
	global_load_dwordx4 v[128:131], v[112:113], off offset:256
	global_load_dwordx4 v[124:127], v[114:115], off
	global_load_dwordx4 v[120:123], v[114:115], off offset:256
	global_load_dwordx4 v[116:119], v[198:199], off
	s_nop 0
	global_load_dwordx4 v[112:115], v[198:199], off offset:256
	s_lshl_b32 s2, s22, 2
	s_or_b32 s6, s2, s38
	s_ashr_i32 s7, s6, 31
	s_lshl_b64 s[6:7], s[6:7], 2
	s_add_u32 s22, s3, s6
	s_addc_u32 s23, s33, s7
	s_waitcnt vmcnt(0)
	v_lshlrev_b32_e32 v198, 16, v170
	v_and_b32_e32 v170, 0xffff0000, v170
	v_lshlrev_b32_e32 v199, 16, v171
	v_and_b32_e32 v171, 0xffff0000, v171
	v_lshlrev_b32_e32 v200, 16, v172
	v_and_b32_e32 v172, 0xffff0000, v172
	v_lshlrev_b32_e32 v203, 16, v174
	v_and_b32_e32 v174, 0xffff0000, v174
	v_lshlrev_b32_e32 v205, 16, v175
	v_and_b32_e32 v175, 0xffff0000, v175
	v_lshlrev_b32_e32 v201, 16, v173
	v_and_b32_e32 v173, 0xffff0000, v173
	v_lshlrev_b32_e32 v206, 16, v176
	v_and_b32_e32 v176, 0xffff0000, v176
	v_lshlrev_b32_e32 v207, 16, v177
	v_and_b32_e32 v177, 0xffff0000, v177
	v_add_f32_e32 v170, v185, v170
	v_add_f32_e32 v171, v183, v171
	v_add_f32_e32 v185, v189, v172
	v_add_f32_e32 v189, v193, v174
	v_add_f32_e32 v191, v191, v175
	v_add_f32_e32 v184, v184, v198
	v_add_f32_e32 v182, v182, v199
	v_add_f32_e32 v183, v188, v200
	v_add_f32_e32 v187, v187, v173
	v_add_f32_e32 v188, v192, v203
	v_add_f32_e32 v190, v190, v205
	v_add_f32_e32 v193, v197, v176
	v_add_f32_e32 v195, v195, v177
	v_mul_f32_e32 v176, v170, v170
	v_mul_f32_e32 v177, v171, v171
	v_cvt_pk_bf16_f32 v172, v184, v170
	v_cvt_pk_bf16_f32 v173, v182, v171
	v_mul_f32_e32 v170, v189, v189
	v_mul_f32_e32 v171, v191, v191
	v_fmac_f32_e32 v170, v188, v188
	v_fmac_f32_e32 v171, v190, v190
	v_add_f32_e32 v192, v196, v206
	v_add_f32_e32 v170, v170, v171
	v_mul_f32_e32 v171, v193, v193
	v_mul_f32_e32 v196, v185, v185
	v_fmac_f32_e32 v176, v184, v184
	v_fmac_f32_e32 v177, v182, v182
	v_fmac_f32_e32 v171, v192, v192
	v_add_f32_e32 v186, v186, v201
	v_add_f32_e32 v194, v194, v207
	v_mul_f32_e32 v197, v187, v187
	v_fmac_f32_e32 v196, v183, v183
	v_add_f32_e32 v176, v176, v177
	v_add_f32_e32 v170, v171, v170
	v_mul_f32_e32 v171, v195, v195
	v_fmac_f32_e32 v197, v186, v186
	v_add_f32_e32 v176, v196, v176
	v_fmac_f32_e32 v171, v194, v194
	v_add_f32_e32 v176, v197, v176
	v_add_f32_e32 v170, v171, v170
	v_add_f32_e32 v171, v176, v170
	v_and_b32_e32 v176, 64, v202
	v_xor_b32_e32 v170, 16, v202
	v_add_u32_e32 v182, 64, v176
	v_cmp_lt_i32_e32 vcc, v170, v182
	v_cvt_pk_bf16_f32 v174, v183, v185
	v_lshl_add_u64 v[176:177], s[10:11], 0, v[180:181]
	v_lshl_add_u64 v[178:179], v[176:177], 0, v[178:179]
	v_cndmask_b32_e32 v170, v202, v170, vcc
	v_lshlrev_b32_e32 v170, 2, v170
	ds_bpermute_b32 v183, v170, v171
	v_cvt_pk_bf16_f32 v175, v186, v187
	global_store_dwordx4 v[178:179], v[172:175], off sc1
	s_waitcnt lgkmcnt(0)
	s_nop 0
	v_add_f32_e32 v172, v171, v183
	v_xor_b32_e32 v171, 32, v202
	v_cmp_lt_i32_e32 vcc, v171, v182
	v_cvt_pk_bf16_f32 v174, v188, v189
	v_cvt_pk_bf16_f32 v175, v190, v191
	v_cvt_pk_bf16_f32 v176, v192, v193
	v_cvt_pk_bf16_f32 v177, v194, v195
	global_store_dwordx4 v[178:179], v[174:177], off offset:256 sc1
	s_nop 0
	v_cndmask_b32_e32 v171, v202, v171, vcc
	v_lshlrev_b32_e32 v171, 2, v171
	ds_bpermute_b32 v173, v171, v172
	s_and_saveexec_b64 s[24:25], s[44:45]
	s_cbranch_execz .LBB0_2200
	v_lshlrev_b64 v[174:175], 7, v[156:157]
	v_lshl_add_u64 v[174:175], s[22:23], 0, v[174:175]
	s_waitcnt lgkmcnt(0)
	v_add_f32_e32 v157, v172, v173
	global_store_dword v[174:175], v157, off
; __device__ __forceinline__ unsigned cvt_pk_bf16(float lo, float hi) { unsigned r; asm volatile("v_cvt_pk_bf16_f32 %0, %1, %2" : "=v"(r) : "v"(lo), "v"(hi)); return r; }
;     __device__ __forceinline__ void operator()(const f32x4 (&acc)[2][2][4][2], const Unit& u, int wr, int wc, int fr, int fq) const {
;     ...
;             for (int m = 0; m < 4; ++m) { const int row = row0 + ai * HALF + m * 16; float ss = 0.f;
; #pragma unroll
;                 for (int bj = 0; bj < 2; ++bj) { const u32x4 ow = old[m][bj];
;                     f32x4 v0 = (acc[ai][bj][m][0] + bv[bj][0]) * accs, v1 = (acc[ai][bj][m][1] + bv[bj][1]) * accs;
;                     v0[0] += __uint_as_float(ow.x << 16); v0[1] += __uint_as_float(ow.x & 0xffff0000u); v0[2] += __uint_as_float(ow.y << 16); v0[3] += __uint_as_float(ow.y & 0xffff0000u);
;                     v1[0] += __uint_as_float(ow.z << 16); v1[1] += __uint_as_float(ow.z & 0xffff0000u); v1[2] += __uint_as_float(ow.w << 16); v1[3] += __uint_as_float(ow.w & 0xffff0000u);
;                     ss += (v0[0] * v0[0] + v0[1] * v0[1]) + (v0[2] * v0[2] + v0[3] * v0[3]) + (v1[0] * v1[0] + v1[1] * v1[1]) + (v1[2] * v1[2] + v1[3] * v1[3]);
;                     u32x4 w; w.x = cvt_pk_bf16(v0[0], v0[1]); w.y = cvt_pk_bf16(v0[2], v0[3]); w.z = cvt_pk_bf16(v1[0], v1[1]); w.w = cvt_pk_bf16(v1[2], v1[3]);
;                     *(u32x4*)(HB + (size_t)row * ldc + col0 + bj * HALF) = w; }
;                 ss += __shfl_xor(ss, 16); ss += __shfl_xor(ss, 32);
;                 if (fq == 0) ssp[(size_t)row * 32] = ss; }
.LBB0_2200:
	s_or_b64 exec, exec, s[24:25]
	v_pk_add_f32 v[108:109], v[108:109], 0 op_sel_hi:[1,0]
	v_lshlrev_b32_e32 v157, 16, v132
	v_and_b32_e32 v132, 0xffff0000, v132
	v_pk_add_f32 v[110:111], v[110:111], 0 op_sel_hi:[1,0]
	v_add_f32_e32 v109, v109, v132
	v_lshlrev_b32_e32 v132, 16, v133
	v_add_f32_e32 v110, v110, v132
	v_and_b32_e32 v132, 0xffff0000, v133
	v_pk_add_f32 v[104:105], v[104:105], 0 op_sel_hi:[1,0]
	v_add_f32_e32 v111, v111, v132
	v_lshlrev_b32_e32 v132, 16, v134
	v_add_f32_e32 v132, v104, v132
	v_and_b32_e32 v104, 0xffff0000, v134
	v_pk_add_f32 v[106:107], v[106:107], 0 op_sel_hi:[1,0]
	v_add_f32_e32 v133, v105, v104
	v_lshlrev_b32_e32 v104, 16, v135
	v_add_f32_e32 v134, v106, v104
	v_and_b32_e32 v104, 0xffff0000, v135
	v_add_f32_e32 v108, v108, v157
	v_add_f32_e32 v107, v107, v104
	v_mul_f32_e32 v104, v109, v109
	v_mul_f32_e32 v105, v111, v111
	v_fmac_f32_e32 v104, v108, v108
	v_fmac_f32_e32 v105, v110, v110
	v_add_f32_e32 v104, v104, v105
	v_mul_f32_e32 v105, v133, v133
	v_fmac_f32_e32 v105, v132, v132
	v_add_f32_e32 v104, v105, v104
	v_mul_f32_e32 v105, v107, v107
	v_fmac_f32_e32 v105, v134, v134
	v_add_f32_e32 v135, v105, v104
	v_cvt_pk_bf16_f32 v104, v108, v109
	v_pk_add_f32 v[100:101], v[100:101], 0 op_sel_hi:[1,0]
	v_lshlrev_b32_e32 v108, 16, v128
	v_add_f32_e32 v100, v100, v108
	v_and_b32_e32 v108, 0xffff0000, v128
	v_pk_add_f32 v[102:103], v[102:103], 0 op_sel_hi:[1,0]
	v_add_f32_e32 v101, v101, v108
	v_lshlrev_b32_e32 v108, 16, v129
	v_add_f32_e32 v108, v102, v108
	v_and_b32_e32 v102, 0xffff0000, v129
	v_pk_add_f32 v[96:97], v[96:97], 0 op_sel_hi:[1,0]
	v_add_f32_e32 v109, v103, v102
	v_lshlrev_b32_e32 v102, 16, v130
	v_cvt_pk_bf16_f32 v105, v110, v111
	v_add_f32_e32 v110, v96, v102
	v_and_b32_e32 v96, 0xffff0000, v130
	v_pk_add_f32 v[98:99], v[98:99], 0 op_sel_hi:[1,0]
	v_add_f32_e32 v111, v97, v96
	v_lshlrev_b32_e32 v96, 16, v131
	v_add_f32_e32 v128, v98, v96
	v_and_b32_e32 v96, 0xffff0000, v131
	v_add_f32_e32 v129, v99, v96
	v_mul_f32_e32 v96, v101, v101
	v_mul_f32_e32 v97, v109, v109
	v_fmac_f32_e32 v96, v100, v100
	v_fmac_f32_e32 v97, v108, v108
	v_add_f32_e32 v96, v96, v97
	v_mul_f32_e32 v97, v111, v111
	v_fmac_f32_e32 v97, v110, v110
	v_add_f32_e32 v96, v97, v96
	v_mul_f32_e32 v97, v129, v129
	v_fmac_f32_e32 v97, v128, v128
	v_add_f32_e32 v96, v97, v96
	v_add_f32_e32 v99, v135, v96
	ds_bpermute_b32 v130, v170, v99
	s_waitcnt lgkmcnt(1)
	v_lshlrev_b64 v[172:173], 11, v[162:163]
	v_lshl_add_u64 v[96:97], v[172:173], 1, s[10:11]
	v_lshl_add_u64 v[102:103], v[152:153], 1, v[96:97]
	v_cvt_pk_bf16_f32 v106, v132, v133
	s_waitcnt lgkmcnt(0)
	v_add_f32_e32 v96, v99, v130
	ds_bpermute_b32 v97, v171, v96
	v_cvt_pk_bf16_f32 v107, v134, v107
	global_store_dwordx4 v[102:103], v[104:107], off sc1
	v_cvt_pk_bf16_f32 v98, v100, v101
	v_cvt_pk_bf16_f32 v99, v108, v109
	v_cvt_pk_bf16_f32 v100, v110, v111
	v_cvt_pk_bf16_f32 v101, v128, v129
	global_store_dwordx4 v[102:103], v[98:101], off offset:256 sc1
	s_and_saveexec_b64 s[24:25], s[44:45]
	s_cbranch_execz .LBB0_2202
	v_lshlrev_b64 v[98:99], 7, v[162:163]
	v_lshl_add_u64 v[98:99], s[22:23], 0, v[98:99]
	s_waitcnt lgkmcnt(0)
	v_add_f32_e32 v96, v96, v97
	global_store_dword v[98:99], v96, off
.LBB0_2202:
	s_or_b64 exec, exec, s[24:25]
	v_pk_add_f32 v[92:93], v[92:93], 0 op_sel_hi:[1,0]
	v_lshlrev_b32_e32 v98, 16, v124
	v_add_f32_e32 v92, v92, v98
	v_and_b32_e32 v98, 0xffff0000, v124
	v_pk_add_f32 v[94:95], v[94:95], 0 op_sel_hi:[1,0]
	v_add_f32_e32 v93, v93, v98
	v_lshlrev_b32_e32 v98, 16, v125
	v_add_f32_e32 v94, v94, v98
	v_and_b32_e32 v98, 0xffff0000, v125
	v_pk_add_f32 v[88:89], v[88:89], 0 op_sel_hi:[1,0]
	v_add_f32_e32 v95, v95, v98
	v_lshlrev_b32_e32 v98, 16, v126
	v_add_f32_e32 v98, v88, v98
	v_and_b32_e32 v88, 0xffff0000, v126
	v_pk_add_f32 v[90:91], v[90:91], 0 op_sel_hi:[1,0]
	v_add_f32_e32 v99, v89, v88
	v_lshlrev_b32_e32 v88, 16, v127
	v_add_f32_e32 v100, v90, v88
	v_and_b32_e32 v88, 0xffff0000, v127
	v_add_f32_e32 v91, v91, v88
	v_mul_f32_e32 v88, v93, v93
	v_mul_f32_e32 v89, v95, v95
	v_fmac_f32_e32 v88, v92, v92
	v_fmac_f32_e32 v89, v94, v94
	v_add_f32_e32 v88, v88, v89
	v_mul_f32_e32 v89, v99, v99
	v_fmac_f32_e32 v89, v98, v98
	v_add_f32_e32 v88, v89, v88
	v_mul_f32_e32 v89, v91, v91
	v_fmac_f32_e32 v89, v100, v100
	v_add_f32_e32 v101, v89, v88
	v_cvt_pk_bf16_f32 v88, v92, v93
	v_pk_add_f32 v[84:85], v[84:85], 0 op_sel_hi:[1,0]
	v_lshlrev_b32_e32 v92, 16, v120
	v_add_f32_e32 v84, v84, v92
	v_and_b32_e32 v92, 0xffff0000, v120
	v_pk_add_f32 v[86:87], v[86:87], 0 op_sel_hi:[1,0]
	v_add_f32_e32 v85, v85, v92
	v_lshlrev_b32_e32 v92, 16, v121
	v_add_f32_e32 v92, v86, v92
	v_and_b32_e32 v86, 0xffff0000, v121
	v_pk_add_f32 v[80:81], v[80:81], 0 op_sel_hi:[1,0]
	v_add_f32_e32 v93, v87, v86
	v_lshlrev_b32_e32 v86, 16, v122
	v_cvt_pk_bf16_f32 v89, v94, v95
	v_add_f32_e32 v94, v80, v86
	v_and_b32_e32 v80, 0xffff0000, v122
	v_pk_add_f32 v[82:83], v[82:83], 0 op_sel_hi:[1,0]
	v_add_f32_e32 v95, v81, v80
	v_lshlrev_b32_e32 v80, 16, v123
	v_cvt_pk_bf16_f32 v90, v98, v99
	v_add_f32_e32 v98, v82, v80
	v_and_b32_e32 v80, 0xffff0000, v123
	v_add_f32_e32 v99, v83, v80
	v_mul_f32_e32 v80, v85, v85
	v_mul_f32_e32 v81, v93, v93
	v_fmac_f32_e32 v80, v84, v84
	v_fmac_f32_e32 v81, v92, v92
	v_add_f32_e32 v80, v80, v81
	v_mul_f32_e32 v81, v95, v95
	v_fmac_f32_e32 v81, v94, v94
	v_add_f32_e32 v80, v81, v80
	v_mul_f32_e32 v81, v99, v99
	v_fmac_f32_e32 v81, v98, v98
	v_add_f32_e32 v80, v81, v80
	v_add_f32_e32 v83, v101, v80
	v_cvt_pk_bf16_f32 v91, v100, v91
	ds_bpermute_b32 v100, v170, v83
	s_waitcnt lgkmcnt(1)
	v_lshlrev_b64 v[96:97], 11, v[160:161]
	v_lshl_add_u64 v[80:81], v[96:97], 1, s[10:11]
	v_lshl_add_u64 v[86:87], v[152:153], 1, v[80:81]
	global_store_dwordx4 v[86:87], v[88:91], off sc1
	s_waitcnt lgkmcnt(0)
	v_add_f32_e32 v80, v83, v100
	ds_bpermute_b32 v81, v171, v80
	v_cvt_pk_bf16_f32 v82, v84, v85
	v_cvt_pk_bf16_f32 v83, v92, v93
	v_cvt_pk_bf16_f32 v84, v94, v95
	v_cvt_pk_bf16_f32 v85, v98, v99
	global_store_dwordx4 v[86:87], v[82:85], off offset:256 sc1
	s_and_saveexec_b64 s[24:25], s[44:45]
	s_cbranch_execz .LBB0_2204
	v_lshlrev_b64 v[82:83], 7, v[160:161]
	v_lshl_add_u64 v[82:83], s[22:23], 0, v[82:83]
	s_waitcnt lgkmcnt(0)
	v_add_f32_e32 v80, v80, v81
	global_store_dword v[82:83], v80, off
; __device__ __forceinline__ unsigned cvt_pk_bf16(float lo, float hi) { unsigned r; asm volatile("v_cvt_pk_bf16_f32 %0, %1, %2" : "=v"(r) : "v"(lo), "v"(hi)); return r; }
;     __device__ __forceinline__ void operator()(const f32x4 (&acc)[2][2][4][2], const Unit& u, int wr, int wc, int fr, int fq) const {
;     ...
;             u32x4 old[4][2];
; #pragma unroll
;             for (int m = 0; m < 4; ++m)
; #pragma unroll
;                 for (int bj = 0; bj < 2; ++bj) old[m][bj] = *(const u32x4*)(HB + (size_t)(row0 + ai * HALF + m * 16) * ldc + col0 + bj * HALF);
; #pragma unroll
;             for (int m = 0; m < 4; ++m) { const int row = row0 + ai * HALF + m * 16; float ss = 0.f;
; #pragma unroll
;                 for (int bj = 0; bj < 2; ++bj) { const u32x4 ow = old[m][bj];
;                     f32x4 v0 = (acc[ai][bj][m][0] + bv[bj][0]) * accs, v1 = (acc[ai][bj][m][1] + bv[bj][1]) * accs;
;                     v0[0] += __uint_as_float(ow.x << 16); v0[1] += __uint_as_float(ow.x & 0xffff0000u); v0[2] += __uint_as_float(ow.y << 16); v0[3] += __uint_as_float(ow.y & 0xffff0000u);
;                     v1[0] += __uint_as_float(ow.z << 16); v1[1] += __uint_as_float(ow.z & 0xffff0000u); v1[2] += __uint_as_float(ow.w << 16); v1[3] += __uint_as_float(ow.w & 0xffff0000u);
;                     ss += (v0[0] * v0[0] + v0[1] * v0[1]) + (v0[2] * v0[2] + v0[3] * v0[3]) + (v1[0] * v1[0] + v1[1] * v1[1]) + (v1[2] * v1[2] + v1[3] * v1[3]);
;                     u32x4 w; w.x = cvt_pk_bf16(v0[0], v0[1]); w.y = cvt_pk_bf16(v0[2], v0[3]); w.z = cvt_pk_bf16(v1[0], v1[1]); w.w = cvt_pk_bf16(v1[2], v1[3]);
;                     *(u32x4*)(HB + (size_t)row * ldc + col0 + bj * HALF) = w; }
;                 ss += __shfl_xor(ss, 16); ss += __shfl_xor(ss, 32);
;                 if (fq == 0) ssp[(size_t)row * 32] = ss; }
.LBB0_2204:
	s_or_b64 exec, exec, s[24:25]
	v_pk_add_f32 v[76:77], v[76:77], 0 op_sel_hi:[1,0]
	v_lshlrev_b32_e32 v82, 16, v116
	v_add_f32_e32 v76, v76, v82
	v_and_b32_e32 v82, 0xffff0000, v116
	v_pk_add_f32 v[78:79], v[78:79], 0 op_sel_hi:[1,0]
	v_add_f32_e32 v77, v77, v82
	v_lshlrev_b32_e32 v82, 16, v117
	v_add_f32_e32 v78, v78, v82
	v_and_b32_e32 v82, 0xffff0000, v117
	v_pk_add_f32 v[72:73], v[72:73], 0 op_sel_hi:[1,0]
	v_add_f32_e32 v79, v79, v82
	v_lshlrev_b32_e32 v82, 16, v118
	v_add_f32_e32 v82, v72, v82
	v_and_b32_e32 v72, 0xffff0000, v118
	v_pk_add_f32 v[74:75], v[74:75], 0 op_sel_hi:[1,0]
	v_add_f32_e32 v83, v73, v72
	v_lshlrev_b32_e32 v72, 16, v119
	v_add_f32_e32 v84, v74, v72
	v_and_b32_e32 v72, 0xffff0000, v119
	v_add_f32_e32 v75, v75, v72
	v_mul_f32_e32 v72, v77, v77
	v_mul_f32_e32 v73, v79, v79
	v_fmac_f32_e32 v72, v76, v76
	v_fmac_f32_e32 v73, v78, v78
	v_add_f32_e32 v72, v72, v73
	v_mul_f32_e32 v73, v83, v83
	v_fmac_f32_e32 v73, v82, v82
	v_add_f32_e32 v72, v73, v72
	v_mul_f32_e32 v73, v75, v75
	v_fmac_f32_e32 v73, v84, v84
	v_add_f32_e32 v85, v73, v72
	v_cvt_pk_bf16_f32 v72, v76, v77
	v_pk_add_f32 v[68:69], v[68:69], 0 op_sel_hi:[1,0]
	v_lshlrev_b32_e32 v76, 16, v112
	v_add_f32_e32 v68, v68, v76
	v_and_b32_e32 v76, 0xffff0000, v112
	v_pk_add_f32 v[70:71], v[70:71], 0 op_sel_hi:[1,0]
	v_add_f32_e32 v69, v69, v76
	v_lshlrev_b32_e32 v76, 16, v113
	v_add_f32_e32 v76, v70, v76
	v_and_b32_e32 v70, 0xffff0000, v113
	v_pk_add_f32 v[64:65], v[64:65], 0 op_sel_hi:[1,0]
	v_add_f32_e32 v77, v71, v70
	v_lshlrev_b32_e32 v70, 16, v114
	v_cvt_pk_bf16_f32 v73, v78, v79
	v_add_f32_e32 v78, v64, v70
	v_and_b32_e32 v64, 0xffff0000, v114
	v_pk_add_f32 v[66:67], v[66:67], 0 op_sel_hi:[1,0]
	v_add_f32_e32 v79, v65, v64
	v_lshlrev_b32_e32 v64, 16, v115
	v_cvt_pk_bf16_f32 v74, v82, v83
	v_add_f32_e32 v82, v66, v64
	v_and_b32_e32 v64, 0xffff0000, v115
	v_add_f32_e32 v83, v67, v64
	v_mul_f32_e32 v64, v69, v69
	v_mul_f32_e32 v65, v77, v77
	v_fmac_f32_e32 v64, v68, v68
	v_fmac_f32_e32 v65, v76, v76
	v_add_f32_e32 v64, v64, v65
	v_mul_f32_e32 v65, v79, v79
	v_fmac_f32_e32 v65, v78, v78
	v_add_f32_e32 v64, v65, v64
	v_mul_f32_e32 v65, v83, v83
	v_fmac_f32_e32 v65, v82, v82
	v_add_f32_e32 v64, v65, v64
	v_add_f32_e32 v67, v85, v64
	v_cvt_pk_bf16_f32 v75, v84, v75
	ds_bpermute_b32 v84, v170, v67
	s_waitcnt lgkmcnt(1)
	v_lshlrev_b64 v[80:81], 11, v[158:159]
	v_lshl_add_u64 v[64:65], v[80:81], 1, s[10:11]
	v_lshl_add_u64 v[70:71], v[152:153], 1, v[64:65]
	global_store_dwordx4 v[70:71], v[72:75], off sc1
	s_waitcnt lgkmcnt(0)
	v_add_f32_e32 v64, v67, v84
	ds_bpermute_b32 v65, v171, v64
	v_cvt_pk_bf16_f32 v66, v68, v69
	v_cvt_pk_bf16_f32 v67, v76, v77
	v_cvt_pk_bf16_f32 v68, v78, v79
	v_cvt_pk_bf16_f32 v69, v82, v83
	global_store_dwordx4 v[70:71], v[66:69], off offset:256 sc1
	s_and_saveexec_b64 s[24:25], s[44:45]
	s_cbranch_execz .LBB0_2206
	v_lshlrev_b64 v[66:67], 7, v[158:159]
	v_lshl_add_u64 v[66:67], s[22:23], 0, v[66:67]
	s_waitcnt lgkmcnt(0)
	v_add_f32_e32 v64, v64, v65
	global_store_dword v[66:67], v64, off
.LBB0_2206:
	s_or_b64 exec, exec, s[24:25]
	v_add_u32_e32 v98, 0x80, v156
	v_ashrrev_i32_e32 v99, 31, v98
	v_lshlrev_b64 v[104:105], 12, v[98:99]
	s_waitcnt lgkmcnt(0)
	v_lshl_add_u64 v[64:65], v[154:155], 0, v[104:105]
	global_load_dwordx4 v[100:103], v[64:65], off
	global_load_dwordx4 v[88:91], v[64:65], off offset:256
	v_add_u32_e32 v96, 0x90, v156
	v_ashrrev_i32_e32 v97, 31, v96
	v_lshlrev_b64 v[64:65], 12, v[96:97]
	v_add_u32_e32 v94, 0xa0, v156
	v_lshl_add_u64 v[64:65], v[154:155], 0, v[64:65]
	v_ashrrev_i32_e32 v95, 31, v94
	global_load_dwordx4 v[84:87], v[64:65], off
	global_load_dwordx4 v[80:83], v[64:65], off offset:256
	v_lshlrev_b64 v[64:65], 12, v[94:95]
	v_add_u32_e32 v92, 0xb0, v156
	v_lshl_add_u64 v[64:65], v[154:155], 0, v[64:65]
	v_ashrrev_i32_e32 v93, 31, v92
	global_load_dwordx4 v[76:79], v[64:65], off
	global_load_dwordx4 v[72:75], v[64:65], off offset:256
	v_lshlrev_b64 v[64:65], 12, v[92:93]
	v_lshl_add_u64 v[64:65], v[154:155], 0, v[64:65]
	global_load_dwordx4 v[68:71], v[64:65], off
	s_nop 0
	global_load_dwordx4 v[64:67], v[64:65], off offset:256
	v_pk_add_f32 v[60:61], v[60:61], 0 op_sel_hi:[1,0]
	v_pk_add_f32 v[62:63], v[62:63], 0 op_sel_hi:[1,0]
	v_pk_add_f32 v[56:57], v[56:57], 0 op_sel_hi:[1,0]
	v_pk_add_f32 v[58:59], v[58:59], 0 op_sel_hi:[1,0]
	v_pk_add_f32 v[52:53], v[52:53], 0 op_sel_hi:[1,0]
	v_pk_add_f32 v[54:55], v[54:55], 0 op_sel_hi:[1,0]
	v_pk_add_f32 v[48:49], v[48:49], 0 op_sel_hi:[1,0]
	v_pk_add_f32 v[50:51], v[50:51], 0 op_sel_hi:[1,0]
	s_waitcnt vmcnt(7)
	v_lshlrev_b32_e32 v106, 16, v100
	v_and_b32_e32 v100, 0xffff0000, v100
	v_add_f32_e32 v61, v61, v100
	v_lshlrev_b32_e32 v100, 16, v101
	v_add_f32_e32 v62, v62, v100
	v_and_b32_e32 v100, 0xffff0000, v101
	v_add_f32_e32 v63, v63, v100
	v_lshlrev_b32_e32 v100, 16, v102
	v_add_f32_e32 v56, v56, v100
	v_and_b32_e32 v100, 0xffff0000, v102
	v_add_f32_e32 v57, v57, v100
	v_lshlrev_b32_e32 v100, 16, v103
	v_add_f32_e32 v100, v58, v100
	v_and_b32_e32 v58, 0xffff0000, v103
	v_add_f32_e32 v60, v60, v106
	v_add_f32_e32 v101, v59, v58
	v_mul_f32_e32 v58, v61, v61
	v_mul_f32_e32 v59, v63, v63
	v_fmac_f32_e32 v58, v60, v60
	v_fmac_f32_e32 v59, v62, v62
	v_add_f32_e32 v58, v58, v59
	v_mul_f32_e32 v59, v57, v57
	v_fmac_f32_e32 v59, v56, v56
	v_add_f32_e32 v58, v59, v58
	v_mul_f32_e32 v59, v101, v101
	v_fmac_f32_e32 v59, v100, v100
	v_add_f32_e32 v102, v59, v58
	v_cvt_pk_bf16_f32 v58, v60, v61
	v_cvt_pk_bf16_f32 v59, v62, v63
	v_cvt_pk_bf16_f32 v60, v56, v57
	v_lshl_add_u64 v[56:57], s[10:11], 0, v[104:105]
	v_lshl_add_u64 v[56:57], v[152:153], 1, v[56:57]
	v_cvt_pk_bf16_f32 v61, v100, v101
	global_store_dwordx4 v[56:57], v[58:61], off sc1
	s_waitcnt vmcnt(7)
	s_nop 0
	v_lshlrev_b32_e32 v58, 16, v88
	v_add_f32_e32 v52, v52, v58
	v_and_b32_e32 v58, 0xffff0000, v88
	v_add_f32_e32 v53, v53, v58
	v_lshlrev_b32_e32 v58, 16, v89
	v_add_f32_e32 v54, v54, v58
	v_and_b32_e32 v58, 0xffff0000, v89
	v_add_f32_e32 v55, v55, v58
	v_lshlrev_b32_e32 v58, 16, v90
	v_add_f32_e32 v58, v48, v58
	v_and_b32_e32 v48, 0xffff0000, v90
	v_add_f32_e32 v59, v49, v48
	v_lshlrev_b32_e32 v48, 16, v91
	v_add_f32_e32 v60, v50, v48
	v_and_b32_e32 v48, 0xffff0000, v91
	v_add_f32_e32 v51, v51, v48
	v_mul_f32_e32 v48, v53, v53
	v_mul_f32_e32 v49, v55, v55
	v_fmac_f32_e32 v48, v52, v52
	v_fmac_f32_e32 v49, v54, v54
	v_add_f32_e32 v48, v48, v49
	v_mul_f32_e32 v49, v59, v59
	v_fmac_f32_e32 v49, v58, v58
	v_add_f32_e32 v48, v49, v48
	v_mul_f32_e32 v49, v51, v51
	v_fmac_f32_e32 v49, v60, v60
	v_add_f32_e32 v48, v49, v48
	v_add_f32_e32 v61, v102, v48
	v_cvt_pk_bf16_f32 v48, v52, v53
	v_cvt_pk_bf16_f32 v49, v54, v55
	v_cvt_pk_bf16_f32 v50, v58, v59
	v_cvt_pk_bf16_f32 v51, v60, v51
	global_store_dwordx4 v[56:57], v[48:51], off offset:256 sc1
	ds_bpermute_b32 v48, v170, v61
	s_waitcnt lgkmcnt(0)
	v_add_f32_e32 v48, v61, v48
	ds_bpermute_b32 v49, v171, v48
	s_and_saveexec_b64 s[24:25], s[44:45]
	s_cbranch_execz .LBB0_2208
; __device__ __forceinline__ unsigned cvt_pk_bf16(float lo, float hi) { unsigned r; asm volatile("v_cvt_pk_bf16_f32 %0, %1, %2" : "=v"(r) : "v"(lo), "v"(hi)); return r; }
;     __device__ __forceinline__ void operator()(const f32x4 (&acc)[2][2][4][2], const Unit& u, int wr, int wc, int fr, int fq) const {
;     ...
;             for (int m = 0; m < 4; ++m) { const int row = row0 + ai * HALF + m * 16; float ss = 0.f;
; #pragma unroll
;                 for (int bj = 0; bj < 2; ++bj) { const u32x4 ow = old[m][bj];
;                     f32x4 v0 = (acc[ai][bj][m][0] + bv[bj][0]) * accs, v1 = (acc[ai][bj][m][1] + bv[bj][1]) * accs;
;                     v0[0] += __uint_as_float(ow.x << 16); v0[1] += __uint_as_float(ow.x & 0xffff0000u); v0[2] += __uint_as_float(ow.y << 16); v0[3] += __uint_as_float(ow.y & 0xffff0000u);
;                     v1[0] += __uint_as_float(ow.z << 16); v1[1] += __uint_as_float(ow.z & 0xffff0000u); v1[2] += __uint_as_float(ow.w << 16); v1[3] += __uint_as_float(ow.w & 0xffff0000u);
;                     ss += (v0[0] * v0[0] + v0[1] * v0[1]) + (v0[2] * v0[2] + v0[3] * v0[3]) + (v1[0] * v1[0] + v1[1] * v1[1]) + (v1[2] * v1[2] + v1[3] * v1[3]);
;                     u32x4 w; w.x = cvt_pk_bf16(v0[0], v0[1]); w.y = cvt_pk_bf16(v0[2], v0[3]); w.z = cvt_pk_bf16(v1[0], v1[1]); w.w = cvt_pk_bf16(v1[2], v1[3]);
;                     *(u32x4*)(HB + (size_t)row * ldc + col0 + bj * HALF) = w; }
;                 ss += __shfl_xor(ss, 16); ss += __shfl_xor(ss, 32);
;                 if (fq == 0) ssp[(size_t)row * 32] = ss; }
	v_lshlrev_b64 v[50:51], 7, v[98:99]
	v_lshl_add_u64 v[50:51], s[22:23], 0, v[50:51]
	s_waitcnt lgkmcnt(0)
	v_add_f32_e32 v48, v48, v49
	global_store_dword v[50:51], v48, off
.LBB0_2208:
	s_or_b64 exec, exec, s[24:25]
	v_pk_add_f32 v[44:45], v[44:45], 0 op_sel_hi:[1,0]
	s_waitcnt vmcnt(7)
	v_lshlrev_b32_e32 v50, 16, v84
	v_add_f32_e32 v44, v44, v50
	v_and_b32_e32 v50, 0xffff0000, v84
	v_pk_add_f32 v[46:47], v[46:47], 0 op_sel_hi:[1,0]
	v_add_f32_e32 v45, v45, v50
	v_lshlrev_b32_e32 v50, 16, v85
	v_add_f32_e32 v46, v46, v50
	v_and_b32_e32 v50, 0xffff0000, v85
	v_pk_add_f32 v[40:41], v[40:41], 0 op_sel_hi:[1,0]
	v_add_f32_e32 v47, v47, v50
	v_lshlrev_b32_e32 v50, 16, v86
	v_add_f32_e32 v50, v40, v50
	v_and_b32_e32 v40, 0xffff0000, v86
	v_pk_add_f32 v[42:43], v[42:43], 0 op_sel_hi:[1,0]
	v_add_f32_e32 v51, v41, v40
	v_lshlrev_b32_e32 v40, 16, v87
	v_add_f32_e32 v52, v42, v40
	v_and_b32_e32 v40, 0xffff0000, v87
	v_add_f32_e32 v43, v43, v40
	v_mul_f32_e32 v40, v45, v45
	v_mul_f32_e32 v41, v47, v47
	v_fmac_f32_e32 v40, v44, v44
	v_fmac_f32_e32 v41, v46, v46
	v_add_f32_e32 v40, v40, v41
	v_mul_f32_e32 v41, v51, v51
	v_fmac_f32_e32 v41, v50, v50
	v_add_f32_e32 v40, v41, v40
	v_mul_f32_e32 v41, v43, v43
	v_fmac_f32_e32 v41, v52, v52
	v_add_f32_e32 v53, v41, v40
	v_cvt_pk_bf16_f32 v40, v44, v45
	v_pk_add_f32 v[36:37], v[36:37], 0 op_sel_hi:[1,0]
	s_waitcnt vmcnt(6)
	v_lshlrev_b32_e32 v44, 16, v80
	v_add_f32_e32 v36, v36, v44
	v_and_b32_e32 v44, 0xffff0000, v80
	v_pk_add_f32 v[38:39], v[38:39], 0 op_sel_hi:[1,0]
	v_add_f32_e32 v37, v37, v44
	v_lshlrev_b32_e32 v44, 16, v81
	v_add_f32_e32 v44, v38, v44
	v_and_b32_e32 v38, 0xffff0000, v81
	v_pk_add_f32 v[32:33], v[32:33], 0 op_sel_hi:[1,0]
	v_add_f32_e32 v45, v39, v38
	v_lshlrev_b32_e32 v38, 16, v82
	v_cvt_pk_bf16_f32 v41, v46, v47
	v_add_f32_e32 v46, v32, v38
	v_and_b32_e32 v32, 0xffff0000, v82
	v_pk_add_f32 v[34:35], v[34:35], 0 op_sel_hi:[1,0]
	v_add_f32_e32 v47, v33, v32
	v_lshlrev_b32_e32 v32, 16, v83
	v_cvt_pk_bf16_f32 v42, v50, v51
	v_add_f32_e32 v50, v34, v32
	v_and_b32_e32 v32, 0xffff0000, v83
	v_add_f32_e32 v51, v35, v32
	v_mul_f32_e32 v32, v37, v37
	v_mul_f32_e32 v33, v45, v45
	v_fmac_f32_e32 v32, v36, v36
	v_fmac_f32_e32 v33, v44, v44
	v_add_f32_e32 v32, v32, v33
	v_mul_f32_e32 v33, v47, v47
	v_fmac_f32_e32 v33, v46, v46
	v_add_f32_e32 v32, v33, v32
	v_mul_f32_e32 v33, v51, v51
	v_fmac_f32_e32 v33, v50, v50
	v_add_f32_e32 v32, v33, v32
	v_add_f32_e32 v35, v53, v32
	v_cvt_pk_bf16_f32 v43, v52, v43
	ds_bpermute_b32 v52, v170, v35
	s_waitcnt lgkmcnt(1)
	v_lshlrev_b64 v[48:49], 11, v[96:97]
	v_lshl_add_u64 v[32:33], v[48:49], 1, s[10:11]
	v_lshl_add_u64 v[38:39], v[152:153], 1, v[32:33]
	global_store_dwordx4 v[38:39], v[40:43], off sc1
	s_waitcnt lgkmcnt(0)
	v_add_f32_e32 v32, v35, v52
	ds_bpermute_b32 v33, v171, v32
	v_cvt_pk_bf16_f32 v34, v36, v37
	v_cvt_pk_bf16_f32 v35, v44, v45
	v_cvt_pk_bf16_f32 v36, v46, v47
	v_cvt_pk_bf16_f32 v37, v50, v51
	global_store_dwordx4 v[38:39], v[34:37], off offset:256 sc1
	s_and_saveexec_b64 s[24:25], s[44:45]
	s_cbranch_execz .LBB0_2210
	v_lshlrev_b64 v[34:35], 7, v[96:97]
	v_lshl_add_u64 v[34:35], s[22:23], 0, v[34:35]
	s_waitcnt lgkmcnt(0)
	v_add_f32_e32 v32, v32, v33
	global_store_dword v[34:35], v32, off
; __device__ __forceinline__ unsigned cvt_pk_bf16(float lo, float hi) { unsigned r; asm volatile("v_cvt_pk_bf16_f32 %0, %1, %2" : "=v"(r) : "v"(lo), "v"(hi)); return r; }
;     __device__ __forceinline__ void operator()(const f32x4 (&acc)[2][2][4][2], const Unit& u, int wr, int wc, int fr, int fq) const {
;     ...
;             for (int m = 0; m < 4; ++m) { const int row = row0 + ai * HALF + m * 16; float ss = 0.f;
; #pragma unroll
;                 for (int bj = 0; bj < 2; ++bj) { const u32x4 ow = old[m][bj];
;                     f32x4 v0 = (acc[ai][bj][m][0] + bv[bj][0]) * accs, v1 = (acc[ai][bj][m][1] + bv[bj][1]) * accs;
;                     v0[0] += __uint_as_float(ow.x << 16); v0[1] += __uint_as_float(ow.x & 0xffff0000u); v0[2] += __uint_as_float(ow.y << 16); v0[3] += __uint_as_float(ow.y & 0xffff0000u);
;                     v1[0] += __uint_as_float(ow.z << 16); v1[1] += __uint_as_float(ow.z & 0xffff0000u); v1[2] += __uint_as_float(ow.w << 16); v1[3] += __uint_as_float(ow.w & 0xffff0000u);
;                     ss += (v0[0] * v0[0] + v0[1] * v0[1]) + (v0[2] * v0[2] + v0[3] * v0[3]) + (v1[0] * v1[0] + v1[1] * v1[1]) + (v1[2] * v1[2] + v1[3] * v1[3]);
;                     u32x4 w; w.x = cvt_pk_bf16(v0[0], v0[1]); w.y = cvt_pk_bf16(v0[2], v0[3]); w.z = cvt_pk_bf16(v1[0], v1[1]); w.w = cvt_pk_bf16(v1[2], v1[3]);
;                     *(u32x4*)(HB + (size_t)row * ldc + col0 + bj * HALF) = w; }
;                 ss += __shfl_xor(ss, 16); ss += __shfl_xor(ss, 32);
;                 if (fq == 0) ssp[(size_t)row * 32] = ss; }
.LBB0_2210:
	s_or_b64 exec, exec, s[24:25]
	v_pk_add_f32 v[28:29], v[28:29], 0 op_sel_hi:[1,0]
	s_waitcnt vmcnt(7)
	v_lshlrev_b32_e32 v34, 16, v76
	v_add_f32_e32 v28, v28, v34
	v_and_b32_e32 v34, 0xffff0000, v76
	v_pk_add_f32 v[30:31], v[30:31], 0 op_sel_hi:[1,0]
	v_add_f32_e32 v29, v29, v34
	v_lshlrev_b32_e32 v34, 16, v77
	v_add_f32_e32 v30, v30, v34
	v_and_b32_e32 v34, 0xffff0000, v77
	v_pk_add_f32 v[24:25], v[24:25], 0 op_sel_hi:[1,0]
	v_add_f32_e32 v31, v31, v34
	v_lshlrev_b32_e32 v34, 16, v78
	v_add_f32_e32 v34, v24, v34
	v_and_b32_e32 v24, 0xffff0000, v78
	v_pk_add_f32 v[26:27], v[26:27], 0 op_sel_hi:[1,0]
	v_add_f32_e32 v35, v25, v24
	v_lshlrev_b32_e32 v24, 16, v79
	v_add_f32_e32 v36, v26, v24
	v_and_b32_e32 v24, 0xffff0000, v79
	v_add_f32_e32 v27, v27, v24
	v_mul_f32_e32 v24, v29, v29
	v_mul_f32_e32 v25, v31, v31
	v_fmac_f32_e32 v24, v28, v28
	v_fmac_f32_e32 v25, v30, v30
	v_add_f32_e32 v24, v24, v25
	v_mul_f32_e32 v25, v35, v35
	v_fmac_f32_e32 v25, v34, v34
	v_add_f32_e32 v24, v25, v24
	v_mul_f32_e32 v25, v27, v27
	v_fmac_f32_e32 v25, v36, v36
	v_add_f32_e32 v37, v25, v24
	v_cvt_pk_bf16_f32 v24, v28, v29
	v_pk_add_f32 v[20:21], v[20:21], 0 op_sel_hi:[1,0]
	s_waitcnt vmcnt(6)
	v_lshlrev_b32_e32 v28, 16, v72
	v_add_f32_e32 v20, v20, v28
	v_and_b32_e32 v28, 0xffff0000, v72
	v_pk_add_f32 v[22:23], v[22:23], 0 op_sel_hi:[1,0]
	v_add_f32_e32 v21, v21, v28
	v_lshlrev_b32_e32 v28, 16, v73
	v_add_f32_e32 v28, v22, v28
	v_and_b32_e32 v22, 0xffff0000, v73
	v_pk_add_f32 v[16:17], v[16:17], 0 op_sel_hi:[1,0]
	v_add_f32_e32 v29, v23, v22
	v_lshlrev_b32_e32 v22, 16, v74
	v_cvt_pk_bf16_f32 v25, v30, v31
	v_add_f32_e32 v30, v16, v22
	v_and_b32_e32 v16, 0xffff0000, v74
	v_pk_add_f32 v[18:19], v[18:19], 0 op_sel_hi:[1,0]
	v_add_f32_e32 v31, v17, v16
	v_lshlrev_b32_e32 v16, 16, v75
	v_cvt_pk_bf16_f32 v26, v34, v35
	v_add_f32_e32 v34, v18, v16
	v_and_b32_e32 v16, 0xffff0000, v75
	v_add_f32_e32 v35, v19, v16
	v_mul_f32_e32 v16, v21, v21
	v_mul_f32_e32 v17, v29, v29
	v_fmac_f32_e32 v16, v20, v20
	v_fmac_f32_e32 v17, v28, v28
	v_add_f32_e32 v16, v16, v17
	v_mul_f32_e32 v17, v31, v31
	v_fmac_f32_e32 v17, v30, v30
	v_add_f32_e32 v16, v17, v16
	v_mul_f32_e32 v17, v35, v35
	v_fmac_f32_e32 v17, v34, v34
	v_add_f32_e32 v16, v17, v16
	v_add_f32_e32 v19, v37, v16
	v_cvt_pk_bf16_f32 v27, v36, v27
	ds_bpermute_b32 v36, v170, v19
	s_waitcnt lgkmcnt(1)
	v_lshlrev_b64 v[32:33], 11, v[94:95]
	v_lshl_add_u64 v[16:17], v[32:33], 1, s[10:11]
	v_lshl_add_u64 v[22:23], v[152:153], 1, v[16:17]
	global_store_dwordx4 v[22:23], v[24:27], off sc1
	s_waitcnt lgkmcnt(0)
	v_add_f32_e32 v16, v19, v36
	ds_bpermute_b32 v17, v171, v16
	v_cvt_pk_bf16_f32 v18, v20, v21
	v_cvt_pk_bf16_f32 v19, v28, v29
	v_cvt_pk_bf16_f32 v20, v30, v31
	v_cvt_pk_bf16_f32 v21, v34, v35
	global_store_dwordx4 v[22:23], v[18:21], off offset:256 sc1
	s_and_saveexec_b64 s[24:25], s[44:45]
	s_cbranch_execz .LBB0_2212
	v_lshlrev_b64 v[18:19], 7, v[94:95]
	v_lshl_add_u64 v[18:19], s[22:23], 0, v[18:19]
	s_waitcnt lgkmcnt(0)
	v_add_f32_e32 v16, v16, v17
	global_store_dword v[18:19], v16, off
.LBB0_2212:
	s_or_b64 exec, exec, s[24:25]
	v_pk_add_f32 v[12:13], v[12:13], 0 op_sel_hi:[1,0]
	s_waitcnt vmcnt(7)
	v_lshlrev_b32_e32 v18, 16, v68
	v_add_f32_e32 v12, v12, v18
	v_and_b32_e32 v18, 0xffff0000, v68
	v_pk_add_f32 v[14:15], v[14:15], 0 op_sel_hi:[1,0]
	v_add_f32_e32 v13, v13, v18
	v_lshlrev_b32_e32 v18, 16, v69
	v_add_f32_e32 v14, v14, v18
	v_and_b32_e32 v18, 0xffff0000, v69
	v_pk_add_f32 v[8:9], v[8:9], 0 op_sel_hi:[1,0]
	v_add_f32_e32 v15, v15, v18
	v_lshlrev_b32_e32 v18, 16, v70
	v_add_f32_e32 v18, v8, v18
	v_and_b32_e32 v8, 0xffff0000, v70
	v_pk_add_f32 v[10:11], v[10:11], 0 op_sel_hi:[1,0]
	v_add_f32_e32 v19, v9, v8
	v_lshlrev_b32_e32 v8, 16, v71
	v_add_f32_e32 v20, v10, v8
	v_and_b32_e32 v8, 0xffff0000, v71
	v_add_f32_e32 v11, v11, v8
	v_mul_f32_e32 v8, v13, v13
	v_mul_f32_e32 v9, v15, v15
	v_fmac_f32_e32 v8, v12, v12
	v_fmac_f32_e32 v9, v14, v14
	v_add_f32_e32 v8, v8, v9
	v_mul_f32_e32 v9, v19, v19
	v_fmac_f32_e32 v9, v18, v18
	v_add_f32_e32 v8, v9, v8
	v_mul_f32_e32 v9, v11, v11
	v_fmac_f32_e32 v9, v20, v20
	v_add_f32_e32 v21, v9, v8
	v_cvt_pk_bf16_f32 v8, v12, v13
	v_pk_add_f32 v[4:5], v[4:5], 0 op_sel_hi:[1,0]
	s_waitcnt vmcnt(6)
	v_lshlrev_b32_e32 v12, 16, v64
	v_add_f32_e32 v4, v4, v12
	v_and_b32_e32 v12, 0xffff0000, v64
	v_pk_add_f32 v[6:7], v[6:7], 0 op_sel_hi:[1,0]
	v_add_f32_e32 v5, v5, v12
	v_lshlrev_b32_e32 v12, 16, v65
	v_add_f32_e32 v12, v6, v12
	v_and_b32_e32 v6, 0xffff0000, v65
	v_pk_add_f32 v[0:1], v[0:1], 0 op_sel_hi:[1,0]
	v_add_f32_e32 v13, v7, v6
	v_lshlrev_b32_e32 v6, 16, v66
	v_cvt_pk_bf16_f32 v9, v14, v15
	v_add_f32_e32 v14, v0, v6
	v_and_b32_e32 v0, 0xffff0000, v66
	v_pk_add_f32 v[2:3], v[2:3], 0 op_sel_hi:[1,0]
	v_add_f32_e32 v15, v1, v0
	v_lshlrev_b32_e32 v0, 16, v67
	v_cvt_pk_bf16_f32 v10, v18, v19
	v_add_f32_e32 v18, v2, v0
	v_and_b32_e32 v0, 0xffff0000, v67
	v_add_f32_e32 v19, v3, v0
	v_mul_f32_e32 v0, v5, v5
	v_mul_f32_e32 v1, v13, v13
	v_fmac_f32_e32 v0, v4, v4
	v_fmac_f32_e32 v1, v12, v12
	v_add_f32_e32 v0, v0, v1
	v_mul_f32_e32 v1, v15, v15
	v_fmac_f32_e32 v1, v14, v14
	v_add_f32_e32 v0, v1, v0
	v_mul_f32_e32 v1, v19, v19
	v_fmac_f32_e32 v1, v18, v18
	v_add_f32_e32 v0, v1, v0
	v_add_f32_e32 v3, v21, v0
	v_cvt_pk_bf16_f32 v11, v20, v11
	ds_bpermute_b32 v20, v170, v3
	s_waitcnt lgkmcnt(1)
	v_lshlrev_b64 v[16:17], 11, v[92:93]
	v_lshl_add_u64 v[0:1], v[16:17], 1, s[10:11]
	v_lshl_add_u64 v[6:7], v[152:153], 1, v[0:1]
	global_store_dwordx4 v[6:7], v[8:11], off sc1
	s_waitcnt lgkmcnt(0)
	v_add_f32_e32 v0, v3, v20
	ds_bpermute_b32 v1, v171, v0
	v_cvt_pk_bf16_f32 v2, v4, v5
	v_cvt_pk_bf16_f32 v3, v12, v13
	v_cvt_pk_bf16_f32 v4, v14, v15
	v_cvt_pk_bf16_f32 v5, v18, v19
	global_store_dwordx4 v[6:7], v[2:5], off offset:256 sc1
	s_and_saveexec_b64 s[24:25], s[44:45]
	s_cbranch_execz .LBB0_2214
	v_lshlrev_b64 v[2:3], 7, v[92:93]
	v_lshl_add_u64 v[2:3], s[22:23], 0, v[2:3]
	s_waitcnt lgkmcnt(0)
	v_add_f32_e32 v0, v0, v1
	global_store_dword v[2:3], v0, off

; __device__ __forceinline__ unsigned cvt_pk_bf16(float lo, float hi) { unsigned r; asm volatile("v_cvt_pk_bf16_f32 %0, %1, %2" : "=v"(r) : "v"(lo), "v"(hi)); return r; }
; __device__ __forceinline__ float dpp_up1(float x) { return __builtin_bit_cast(float, __builtin_amdgcn_update_dpp(0, __builtin_bit_cast(int, x), 0x111, 0xf, 0xf, true)); }
;     __device__ __forceinline__ void operator()(const f32x4 (&acc)[2][2][4][2], const Unit& u, int wr, int wc, int fr, int fq) const {
;     ...
;                 f32x4 pg2, pg3, pv2, pv3;
; #pragma unroll
;                 for (int e = 0; e < 4; ++e) { pg2[e] = dpp_up1(xg[2][e]); pg3[e] = dpp_up1(xg[3][e]); pv2[e] = dpp_up1(xv[2][e]); pv3[e] = dpp_up1(xv[3][e]); }
; #pragma unroll
;                 for (int m = 0; m < 4; ++m) {
;                     u32x2_t w; float o[4];
; #pragma unroll
;                     for (int e = 0; e < 4; ++e) {
;                         const float g1 = m >= 1 ? xg[m - (m >= 1 ? 1 : 0)][e] : pg3[e], g2 = m >= 2 ? xg[m - (m >= 2 ? 2 : 0)][e] : (m == 1 ? pg3[e] : pg2[e]);
;                         const float v1 = m >= 1 ? xv[m - (m >= 1 ? 1 : 0)][e] : pv3[e], v2 = m >= 2 ? xv[m - (m >= 2 ? 2 : 0)][e] : (m == 1 ? pv3[e] : pv2[e]);
;                         const float cg_ = bg[e] + w0g[e] * g2 + w1g[e] * g1 + w2g[e] * xg[m][e];
;                         const float cv_ = bv[e] + w0v[e] * v2 + w1v[e] * v1 + w2v[e] * xv[m][e];
;                         o[e] = cg_ * __builtin_amdgcn_rcpf(1.0f + __expf(-cg_)) * cv_;
;                     }
;                     w.x = cvt_pk_bf16(o[0], o[1]); w.y = cvt_pk_bf16(o[2], o[3]);
;                     const int g = g0 + m;
;                     if (n == 0) stash[ai][m] = w;
;                     else if ((fr > 0 || m >= 2) && g < TT) { u32x4 ww; ww.x = stash[ai][m].x; ww.y = stash[ai][m].y; ww.z = w.x; ww.w = w.y; *(u32x4*)(G + (size_t)g * DFF_ + f0 - 4) = ww; }
.LBB0_2292:
	v_mov_b32_dpp v112, v58 row_shr:1 row_mask:0xf bank_mask:0xf bound_ctrl:1
	v_mov_b32_dpp v125, v44 row_shr:1 row_mask:0xf bank_mask:0xf bound_ctrl:1
	s_waitcnt vmcnt(4)
	v_fma_f32 v112, v98, v112, v70
	v_fmac_f32_e32 v112, v90, v125
	v_fmac_f32_e32 v112, v94, v116
	v_mul_f32_e32 v132, 0xbfb8aa3b, v112
	v_exp_f32_e32 v132, v132
	v_mov_b32_dpp v113, v52 row_shr:1 row_mask:0xf bank_mask:0xf bound_ctrl:1
	v_mov_b32_dpp v123, v38 row_shr:1 row_mask:0xf bank_mask:0xf bound_ctrl:1
	s_waitcnt vmcnt(0)
	v_fma_f32 v113, v74, v113, v86
	v_add_f32_e32 v132, 1.0, v132
	v_rcp_f32_e32 v132, v132
	v_fmac_f32_e32 v113, v78, v123
	v_mov_b32_dpp v126, v59 row_shr:1 row_mask:0xf bank_mask:0xf bound_ctrl:1
	v_fmac_f32_e32 v113, v82, v68
	v_mul_f32_e32 v112, v112, v132
	v_mov_b32_dpp v121, v45 row_shr:1 row_mask:0xf bank_mask:0xf bound_ctrl:1
	v_mul_f32_e32 v112, v113, v112
	v_fma_f32 v113, v99, v126, v71
	v_fmac_f32_e32 v113, v91, v121
	v_mov_b32_dpp v127, v53 row_shr:1 row_mask:0xf bank_mask:0xf bound_ctrl:1
	v_fmac_f32_e32 v113, v95, v117
	v_fma_f32 v126, v75, v127, v87
	v_mul_f32_e32 v127, 0xbfb8aa3b, v113
	v_exp_f32_e32 v127, v127
	v_mov_b32_dpp v119, v39 row_shr:1 row_mask:0xf bank_mask:0xf bound_ctrl:1
	v_fmac_f32_e32 v126, v79, v119
	v_mov_b32_dpp v128, v42 row_shr:1 row_mask:0xf bank_mask:0xf bound_ctrl:1
	v_add_f32_e32 v127, 1.0, v127
	v_rcp_f32_e32 v127, v127
	v_fmac_f32_e32 v126, v83, v69
	v_mov_b32_dpp v55, v32 row_shr:1 row_mask:0xf bank_mask:0xf bound_ctrl:1
	v_mov_b32_dpp v129, v36 row_shr:1 row_mask:0xf bank_mask:0xf bound_ctrl:1
	v_mul_f32_e32 v113, v113, v127
	v_mul_f32_e32 v113, v126, v113
	v_fma_f32 v126, v100, v128, v72
	v_fmac_f32_e32 v126, v92, v55
	v_fmac_f32_e32 v126, v96, v62
	v_mul_f32_e32 v128, 0xbfb8aa3b, v126
	v_exp_f32_e32 v128, v128
	v_mov_b32_dpp v54, v34 row_shr:1 row_mask:0xf bank_mask:0xf bound_ctrl:1
	v_fma_f32 v127, v76, v129, v88
	v_fmac_f32_e32 v127, v80, v54
	v_add_f32_e32 v128, 1.0, v128
	v_rcp_f32_e32 v128, v128
	v_mov_b32_dpp v130, v43 row_shr:1 row_mask:0xf bank_mask:0xf bound_ctrl:1
	v_fmac_f32_e32 v127, v84, v60
	v_mov_b32_dpp v47, v33 row_shr:1 row_mask:0xf bank_mask:0xf bound_ctrl:1
	v_mul_f32_e32 v126, v126, v128
	v_mul_f32_e32 v126, v127, v126
	v_fma_f32 v127, v101, v130, v73
	v_fmac_f32_e32 v127, v93, v47
	v_fmac_f32_e32 v127, v97, v63
	v_mul_f32_e32 v129, 0xbfb8aa3b, v127
	v_exp_f32_e32 v129, v129
	v_mov_b32_dpp v131, v37 row_shr:1 row_mask:0xf bank_mask:0xf bound_ctrl:1
	v_mov_b32_dpp v46, v35 row_shr:1 row_mask:0xf bank_mask:0xf bound_ctrl:1
	v_fma_f32 v128, v77, v131, v89
	v_add_f32_e32 v129, 1.0, v129
	v_rcp_f32_e32 v129, v129
	v_fmac_f32_e32 v128, v81, v46
	v_cmp_gt_i32_e32 vcc, s85, v215
	v_fmac_f32_e32 v128, v85, v61
	v_mul_f32_e32 v127, v127, v129
	s_and_b64 s[2:3], s[44:45], vcc
	v_mul_f32_e32 v127, v128, v127
	v_cvt_pk_bf16_f32 v112, v112, v113
	v_cvt_pk_bf16_f32 v113, v126, v127
	s_and_saveexec_b64 s[0:1], s[2:3]
	s_cbranch_execz .LBB0_2294
	v_mov_b64_e32 v[126:127], s[14:15]
	v_mad_i64_i32 v[126:127], s[2:3], v215, s92, v[126:127]
	v_lshl_add_u64 v[126:127], v[178:179], 1, v[126:127]
	global_store_dwordx4 v[126:127], v[110:113], off sc1
.LBB0_2294:
	s_or_b64 exec, exec, s[0:1]
	s_nop 0
	v_fma_f32 v110, v98, v125, v70
	v_fmac_f32_e32 v110, v90, v116
	v_fmac_f32_e32 v110, v94, v56
	v_mul_f32_e32 v112, 0xbfb8aa3b, v110
	v_exp_f32_e32 v112, v112
	v_fma_f32 v111, v74, v123, v86
	v_fmac_f32_e32 v111, v78, v68
	v_fmac_f32_e32 v111, v82, v50
	v_add_f32_e32 v112, 1.0, v112
	v_rcp_f32_e32 v112, v112
	v_fma_f32 v55, v100, v55, v72
	v_fmac_f32_e32 v55, v92, v62
	v_fmac_f32_e32 v55, v96, v48
	v_mul_f32_e32 v110, v110, v112
	v_mul_f32_e32 v110, v111, v110
	v_fma_f32 v111, v99, v121, v71
	v_fmac_f32_e32 v111, v91, v117
	v_fmac_f32_e32 v111, v95, v57
	v_mul_f32_e32 v113, 0xbfb8aa3b, v111
	v_exp_f32_e32 v113, v113
	v_fma_f32 v112, v75, v119, v87
	v_fmac_f32_e32 v112, v79, v69
	v_fmac_f32_e32 v112, v83, v51
	v_add_f32_e32 v113, 1.0, v113
	v_rcp_f32_e32 v113, v113
	v_fma_f32 v54, v76, v54, v88
	v_fma_f32 v47, v101, v47, v73
	v_fmac_f32_e32 v54, v80, v60
	v_mul_f32_e32 v111, v111, v113
	v_mul_f32_e32 v111, v112, v111
	v_mul_f32_e32 v112, 0xbfb8aa3b, v55
	v_exp_f32_e32 v112, v112
	v_fmac_f32_e32 v47, v93, v63
	v_fmac_f32_e32 v54, v84, v40
	v_fmac_f32_e32 v47, v97, v49
	v_add_f32_e32 v112, 1.0, v112
	v_rcp_f32_e32 v112, v112
	v_fma_f32 v46, v77, v46, v89
	v_fmac_f32_e32 v46, v81, v61
	v_cmp_gt_i32_e32 vcc, s85, v218
	v_mul_f32_e32 v55, v55, v112
	v_mul_f32_e32 v54, v54, v55
	v_mul_f32_e32 v55, 0xbfb8aa3b, v47
	v_exp_f32_e32 v55, v55
	v_fmac_f32_e32 v46, v85, v41
	s_and_b64 s[2:3], s[44:45], vcc
	v_cvt_pk_bf16_f32 v110, v110, v111
	v_add_f32_e32 v55, 1.0, v55
	v_rcp_f32_e32 v55, v55
	s_nop 0
	v_mul_f32_e32 v47, v47, v55
	v_mul_f32_e32 v46, v46, v47
	v_cvt_pk_bf16_f32 v111, v54, v46
	s_and_saveexec_b64 s[0:1], s[2:3]
	s_cbranch_execz .LBB0_2296
	v_mov_b64_e32 v[46:47], s[14:15]
	v_mad_i64_i32 v[46:47], s[2:3], v218, s92, v[46:47]
	v_lshl_add_u64 v[46:47], v[178:179], 1, v[46:47]
	global_store_dwordx4 v[46:47], v[108:111], off sc1
; __device__ __forceinline__ unsigned cvt_pk_bf16(float lo, float hi) { unsigned r; asm volatile("v_cvt_pk_bf16_f32 %0, %1, %2" : "=v"(r) : "v"(lo), "v"(hi)); return r; }
;     __device__ __forceinline__ void operator()(const f32x4 (&acc)[2][2][4][2], const Unit& u, int wr, int wc, int fr, int fq) const {
;     ...
;                 for (int m = 0; m < 4; ++m) {
;                     u32x2_t w; float o[4];
; #pragma unroll
;                     for (int e = 0; e < 4; ++e) {
;                         const float g1 = m >= 1 ? xg[m - (m >= 1 ? 1 : 0)][e] : pg3[e], g2 = m >= 2 ? xg[m - (m >= 2 ? 2 : 0)][e] : (m == 1 ? pg3[e] : pg2[e]);
;                         const float v1 = m >= 1 ? xv[m - (m >= 1 ? 1 : 0)][e] : pv3[e], v2 = m >= 2 ? xv[m - (m >= 2 ? 2 : 0)][e] : (m == 1 ? pv3[e] : pv2[e]);
;                         const float cg_ = bg[e] + w0g[e] * g2 + w1g[e] * g1 + w2g[e] * xg[m][e];
;                         const float cv_ = bv[e] + w0v[e] * v2 + w1v[e] * v1 + w2v[e] * xv[m][e];
;                         o[e] = cg_ * __builtin_amdgcn_rcpf(1.0f + __expf(-cg_)) * cv_;
;                     }
;                     w.x = cvt_pk_bf16(o[0], o[1]); w.y = cvt_pk_bf16(o[2], o[3]);
;                     const int g = g0 + m;
;                     if (n == 0) stash[ai][m] = w;
;                     else if ((fr > 0 || m >= 2) && g < TT) { u32x4 ww; ww.x = stash[ai][m].x; ww.y = stash[ai][m].y; ww.z = w.x; ww.w = w.y; *(u32x4*)(G + (size_t)g * DFF_ + f0 - 4) = ww; }
.LBB0_2296:
	s_or_b64 exec, exec, s[0:1]
	v_fma_f32 v46, v98, v116, v70
	v_fmac_f32_e32 v46, v90, v56
	v_fmac_f32_e32 v46, v94, v58
	v_mul_f32_e32 v54, 0xbfb8aa3b, v46
	v_exp_f32_e32 v54, v54
	v_fma_f32 v47, v74, v68, v86
	v_fmac_f32_e32 v47, v78, v50
	v_fmac_f32_e32 v47, v82, v52
	v_add_f32_e32 v54, 1.0, v54
	v_rcp_f32_e32 v54, v54
	v_cmp_gt_i32_e32 vcc, s93, v215
	v_mul_f32_e32 v46, v46, v54
	v_mul_f32_e32 v46, v47, v46
	v_fma_f32 v47, v99, v117, v71
	v_fmac_f32_e32 v47, v91, v57
	v_fmac_f32_e32 v47, v95, v59
	v_mul_f32_e32 v55, 0xbfb8aa3b, v47
	v_exp_f32_e32 v55, v55
	v_fma_f32 v54, v75, v69, v87
	v_fmac_f32_e32 v54, v79, v51
	v_fmac_f32_e32 v54, v83, v53
	v_add_f32_e32 v55, 1.0, v55
	v_rcp_f32_e32 v55, v55
	s_nop 0
	v_mul_f32_e32 v47, v47, v55
	v_mul_f32_e32 v47, v54, v47
	v_fma_f32 v54, v100, v62, v72
	v_fmac_f32_e32 v54, v92, v48
	v_fmac_f32_e32 v54, v96, v42
	v_fma_f32 v55, v76, v60, v88
	v_mul_f32_e32 v60, 0xbfb8aa3b, v54
	v_exp_f32_e32 v60, v60
	v_fmac_f32_e32 v55, v80, v40
	v_fmac_f32_e32 v55, v84, v36
	v_cvt_pk_bf16_f32 v108, v46, v47
	v_add_f32_e32 v60, 1.0, v60
	v_rcp_f32_e32 v60, v60
	s_nop 0
	v_mul_f32_e32 v54, v54, v60
	v_mul_f32_e32 v54, v55, v54
	v_fma_f32 v55, v101, v63, v73
	v_fmac_f32_e32 v55, v93, v49
	v_fmac_f32_e32 v55, v97, v43
	v_fma_f32 v60, v77, v61, v89
	v_mul_f32_e32 v61, 0xbfb8aa3b, v55
	v_exp_f32_e32 v61, v61
	v_fmac_f32_e32 v60, v81, v41
	v_fmac_f32_e32 v60, v85, v37
	v_add_f32_e32 v61, 1.0, v61
	v_rcp_f32_e32 v61, v61
	s_nop 0
	v_mul_f32_e32 v55, v55, v61
	v_mul_f32_e32 v55, v60, v55
	v_cvt_pk_bf16_f32 v109, v54, v55
	s_and_saveexec_b64 s[0:1], vcc
	s_cbranch_execz .LBB0_2298
	v_mov_b64_e32 v[46:47], s[14:15]
	v_mad_i64_i32 v[46:47], s[2:3], v216, s92, v[46:47]
	v_lshl_add_u64 v[46:47], v[178:179], 1, v[46:47]
	global_store_dwordx4 v[46:47], v[106:109], off sc1
.LBB0_2298:
	s_or_b64 exec, exec, s[0:1]
	v_fma_f32 v46, v98, v56, v70
	v_fmac_f32_e32 v46, v90, v58
	v_fmac_f32_e32 v46, v94, v44
	v_mul_f32_e32 v44, 0xbfb8aa3b, v46
	v_exp_f32_e32 v44, v44
	v_fma_f32 v47, v74, v50, v86
	v_fma_f32 v50, v99, v57, v71
	v_fmac_f32_e32 v50, v91, v59
	v_fmac_f32_e32 v50, v95, v45
	v_add_f32_e32 v44, 1.0, v44
	v_mul_f32_e32 v45, 0xbfb8aa3b, v50
	v_rcp_f32_e32 v44, v44
	v_exp_f32_e32 v45, v45
	v_fmac_f32_e32 v47, v78, v52
	v_fmac_f32_e32 v47, v82, v38
	v_mul_f32_e32 v38, v46, v44
	v_add_f32_e32 v44, 1.0, v45
	v_rcp_f32_e32 v44, v44
	v_fma_f32 v45, v75, v51, v87
	v_fmac_f32_e32 v45, v79, v53
	v_fma_f32 v40, v76, v40, v88
	v_fmac_f32_e32 v45, v83, v39
	v_mul_f32_e32 v39, v50, v44
	v_fma_f32 v44, v100, v48, v72
	v_fmac_f32_e32 v40, v80, v36
	v_fma_f32 v36, v101, v49, v73
	v_fmac_f32_e32 v44, v92, v42
	v_fmac_f32_e32 v36, v93, v43
	v_fmac_f32_e32 v44, v96, v32
	v_fmac_f32_e32 v36, v97, v33
	v_mul_f32_e32 v32, 0xbfb8aa3b, v44
	v_mul_f32_e32 v33, 0xbfb8aa3b, v36
	v_exp_f32_e32 v32, v32
	v_exp_f32_e32 v33, v33
	v_fmac_f32_e32 v40, v84, v34
	v_fma_f32 v34, v77, v41, v89
	v_add_f32_e32 v32, 1.0, v32
	v_add_f32_e32 v33, 1.0, v33
	v_rcp_f32_e32 v32, v32
	v_rcp_f32_e32 v33, v33
	v_fmac_f32_e32 v34, v81, v37
	v_fmac_f32_e32 v34, v85, v35
	v_mul_f32_e32 v32, v44, v32
	v_mul_f32_e32 v33, v36, v33
	v_cmp_gt_i32_e32 vcc, s94, v215
	v_mul_f32_e32 v38, v47, v38
	v_mul_f32_e32 v39, v45, v39
	v_mul_f32_e32 v32, v40, v32
	v_mul_f32_e32 v33, v34, v33
	v_cvt_pk_bf16_f32 v116, v38, v39
	v_cvt_pk_bf16_f32 v117, v32, v33
	s_and_saveexec_b64 s[0:1], vcc
	s_cbranch_execz .LBB0_2300
	v_mov_b64_e32 v[32:33], s[14:15]
	v_mad_i64_i32 v[32:33], s[2:3], v217, s92, v[32:33]
	v_lshl_add_u64 v[32:33], v[178:179], 1, v[32:33]
	global_store_dwordx4 v[32:33], v[114:117], off sc1

; __device__ __forceinline__ unsigned cvt_pk_bf16(float lo, float hi) { unsigned r; asm volatile("v_cvt_pk_bf16_f32 %0, %1, %2" : "=v"(r) : "v"(lo), "v"(hi)); return r; }
; __device__ __forceinline__ float dpp_up1(float x) { return __builtin_bit_cast(float, __builtin_amdgcn_update_dpp(0, __builtin_bit_cast(int, x), 0x111, 0xf, 0xf, true)); }
;     __device__ __forceinline__ void operator()(const f32x4 (&acc)[2][2][4][2], const Unit& u, int wr, int wc, int fr, int fq) const {
;     ...
;                 f32x4 pg2, pg3, pv2, pv3;
; #pragma unroll
;                 for (int e = 0; e < 4; ++e) { pg2[e] = dpp_up1(xg[2][e]); pg3[e] = dpp_up1(xg[3][e]); pv2[e] = dpp_up1(xv[2][e]); pv3[e] = dpp_up1(xv[3][e]); }
; #pragma unroll
;                 for (int m = 0; m < 4; ++m) {
;                     u32x2_t w; float o[4];
; #pragma unroll
;                     for (int e = 0; e < 4; ++e) {
;                         const float g1 = m >= 1 ? xg[m - (m >= 1 ? 1 : 0)][e] : pg3[e], g2 = m >= 2 ? xg[m - (m >= 2 ? 2 : 0)][e] : (m == 1 ? pg3[e] : pg2[e]);
;                         const float v1 = m >= 1 ? xv[m - (m >= 1 ? 1 : 0)][e] : pv3[e], v2 = m >= 2 ? xv[m - (m >= 2 ? 2 : 0)][e] : (m == 1 ? pv3[e] : pv2[e]);
;                         const float cg_ = bg[e] + w0g[e] * g2 + w1g[e] * g1 + w2g[e] * xg[m][e];
;                         const float cv_ = bv[e] + w0v[e] * v2 + w1v[e] * v1 + w2v[e] * xv[m][e];
;                         o[e] = cg_ * __builtin_amdgcn_rcpf(1.0f + __expf(-cg_)) * cv_;
;                     }
;                     w.x = cvt_pk_bf16(o[0], o[1]); w.y = cvt_pk_bf16(o[2], o[3]);
;                     const int g = g0 + m;
;                     if (n == 0) stash[ai][m] = w;
;                     else if ((fr > 0 || m >= 2) && g < TT) { u32x4 ww; ww.x = stash[ai][m].x; ww.y = stash[ai][m].y; ww.z = w.x; ww.w = w.y; *(u32x4*)(G + (size_t)g * DFF_ + f0 - 4) = ww; }
.LBB0_2302:
	v_mov_b32_dpp v40, v26 row_shr:1 row_mask:0xf bank_mask:0xf bound_ctrl:1
	v_mov_b32_dpp v39, v12 row_shr:1 row_mask:0xf bank_mask:0xf bound_ctrl:1
	v_fma_f32 v40, v98, v40, v70
	v_fmac_f32_e32 v40, v90, v39
	v_fmac_f32_e32 v40, v94, v34
	v_mul_f32_e32 v48, 0xbfb8aa3b, v40
	v_exp_f32_e32 v48, v48
	v_mov_b32_dpp v41, v20 row_shr:1 row_mask:0xf bank_mask:0xf bound_ctrl:1
	v_mov_b32_dpp v38, v6 row_shr:1 row_mask:0xf bank_mask:0xf bound_ctrl:1
	v_fma_f32 v41, v74, v41, v86
	v_add_f32_e32 v48, 1.0, v48
	v_rcp_f32_e32 v48, v48
	v_fmac_f32_e32 v41, v78, v38
	v_mov_b32_dpp v42, v27 row_shr:1 row_mask:0xf bank_mask:0xf bound_ctrl:1
	v_fmac_f32_e32 v41, v82, v32
	v_mul_f32_e32 v40, v40, v48
	v_mov_b32_dpp v37, v13 row_shr:1 row_mask:0xf bank_mask:0xf bound_ctrl:1
	v_mul_f32_e32 v40, v41, v40
	v_fma_f32 v41, v99, v42, v71
	v_fmac_f32_e32 v41, v91, v37
	v_mov_b32_dpp v43, v21 row_shr:1 row_mask:0xf bank_mask:0xf bound_ctrl:1
	v_fmac_f32_e32 v41, v95, v35
	v_fma_f32 v42, v75, v43, v87
	v_mul_f32_e32 v43, 0xbfb8aa3b, v41
	v_exp_f32_e32 v43, v43
	v_mov_b32_dpp v36, v7 row_shr:1 row_mask:0xf bank_mask:0xf bound_ctrl:1
	v_fmac_f32_e32 v42, v79, v36
	v_mov_b32_dpp v44, v10 row_shr:1 row_mask:0xf bank_mask:0xf bound_ctrl:1
	v_add_f32_e32 v43, 1.0, v43
	v_rcp_f32_e32 v43, v43
	v_fmac_f32_e32 v42, v83, v33
	v_mov_b32_dpp v23, v0 row_shr:1 row_mask:0xf bank_mask:0xf bound_ctrl:1
	v_mov_b32_dpp v45, v4 row_shr:1 row_mask:0xf bank_mask:0xf bound_ctrl:1
	v_mul_f32_e32 v41, v41, v43
	v_mul_f32_e32 v41, v42, v41
	v_fma_f32 v42, v100, v44, v72
	v_fmac_f32_e32 v42, v92, v23
	v_fmac_f32_e32 v42, v96, v30
	v_mul_f32_e32 v44, 0xbfb8aa3b, v42
	v_exp_f32_e32 v44, v44
	v_mov_b32_dpp v22, v2 row_shr:1 row_mask:0xf bank_mask:0xf bound_ctrl:1
	v_fma_f32 v43, v76, v45, v88
	v_fmac_f32_e32 v43, v80, v22
	v_add_f32_e32 v44, 1.0, v44
	v_rcp_f32_e32 v44, v44
	v_mov_b32_dpp v46, v11 row_shr:1 row_mask:0xf bank_mask:0xf bound_ctrl:1
	v_fmac_f32_e32 v43, v84, v28
	v_mov_b32_dpp v15, v1 row_shr:1 row_mask:0xf bank_mask:0xf bound_ctrl:1
	v_mul_f32_e32 v42, v42, v44
	v_mul_f32_e32 v42, v43, v42
	v_fma_f32 v43, v101, v46, v73
	v_fmac_f32_e32 v43, v93, v15
	v_fmac_f32_e32 v43, v97, v31
	v_mul_f32_e32 v45, 0xbfb8aa3b, v43
	v_exp_f32_e32 v45, v45
	v_mov_b32_dpp v47, v5 row_shr:1 row_mask:0xf bank_mask:0xf bound_ctrl:1
	v_mov_b32_dpp v14, v3 row_shr:1 row_mask:0xf bank_mask:0xf bound_ctrl:1
	v_fma_f32 v44, v77, v47, v89
	v_add_f32_e32 v45, 1.0, v45
	v_rcp_f32_e32 v45, v45
	v_fmac_f32_e32 v44, v81, v14
	v_cmp_gt_i32_e32 vcc, s85, v211
	v_fmac_f32_e32 v44, v85, v29
	v_mul_f32_e32 v43, v43, v45
	s_and_b64 s[2:3], s[44:45], vcc
	v_mul_f32_e32 v43, v44, v43
	v_cvt_pk_bf16_f32 v106, v40, v41
	v_cvt_pk_bf16_f32 v107, v42, v43
	s_and_saveexec_b64 s[0:1], s[2:3]
	s_cbranch_execz .LBB0_2304
	v_mov_b64_e32 v[40:41], s[14:15]
	v_mad_i64_i32 v[40:41], s[2:3], v211, s92, v[40:41]
	v_lshl_add_u64 v[40:41], v[178:179], 1, v[40:41]
	global_store_dwordx4 v[40:41], v[104:107], off sc1
.LBB0_2304:
	s_or_b64 exec, exec, s[0:1]
	v_fma_f32 v39, v98, v39, v70
	v_fmac_f32_e32 v39, v90, v34
	v_fmac_f32_e32 v39, v94, v24
	v_mul_f32_e32 v40, 0xbfb8aa3b, v39
	v_exp_f32_e32 v40, v40
	v_fma_f32 v38, v74, v38, v86
	v_fma_f32 v37, v99, v37, v71
	v_fmac_f32_e32 v38, v78, v32
	v_add_f32_e32 v40, 1.0, v40
	v_rcp_f32_e32 v40, v40
	v_fmac_f32_e32 v37, v91, v35
	v_fmac_f32_e32 v38, v82, v18
	v_fmac_f32_e32 v37, v95, v25
	v_mul_f32_e32 v39, v39, v40
	v_mul_f32_e32 v38, v38, v39
	v_mul_f32_e32 v39, 0xbfb8aa3b, v37
	v_exp_f32_e32 v39, v39
	v_fma_f32 v36, v75, v36, v87
	v_fma_f32 v23, v100, v23, v72
	v_fmac_f32_e32 v36, v79, v33
	v_add_f32_e32 v39, 1.0, v39
	v_rcp_f32_e32 v39, v39
	v_fmac_f32_e32 v23, v92, v30
	v_fmac_f32_e32 v36, v83, v19
	v_fmac_f32_e32 v23, v96, v16
	v_mul_f32_e32 v37, v37, v39
	v_mul_f32_e32 v36, v36, v37
	v_mul_f32_e32 v37, 0xbfb8aa3b, v23
	v_exp_f32_e32 v37, v37
	v_fma_f32 v22, v76, v22, v88
	v_fma_f32 v15, v101, v15, v73
	v_fmac_f32_e32 v22, v80, v28
	v_add_f32_e32 v37, 1.0, v37
	v_rcp_f32_e32 v37, v37
	v_fmac_f32_e32 v15, v93, v31
	v_fmac_f32_e32 v22, v84, v8
	v_fmac_f32_e32 v15, v97, v17
	v_mul_f32_e32 v23, v23, v37
	v_mul_f32_e32 v22, v22, v23
	v_mul_f32_e32 v23, 0xbfb8aa3b, v15
	v_exp_f32_e32 v23, v23
	v_fma_f32 v14, v77, v14, v89
	v_fmac_f32_e32 v14, v81, v29
	v_cmp_gt_i32_e32 vcc, s85, v213
	v_add_f32_e32 v23, 1.0, v23
	v_rcp_f32_e32 v23, v23
	v_fmac_f32_e32 v14, v85, v9
	s_and_b64 s[2:3], s[44:45], vcc
	v_cvt_pk_bf16_f32 v104, v38, v36
	v_mul_f32_e32 v15, v15, v23
	v_mul_f32_e32 v14, v14, v15
	v_cvt_pk_bf16_f32 v105, v22, v14
	s_and_saveexec_b64 s[0:1], s[2:3]
	s_cbranch_execz .LBB0_2306
	v_mov_b64_e32 v[14:15], s[14:15]
	v_mad_i64_i32 v[14:15], s[2:3], v213, s92, v[14:15]
	v_lshl_add_u64 v[14:15], v[178:179], 1, v[14:15]
	global_store_dwordx4 v[14:15], v[102:105], off sc1
; __device__ __forceinline__ unsigned cvt_pk_bf16(float lo, float hi) { unsigned r; asm volatile("v_cvt_pk_bf16_f32 %0, %1, %2" : "=v"(r) : "v"(lo), "v"(hi)); return r; }
;     __device__ __forceinline__ void operator()(const f32x4 (&acc)[2][2][4][2], const Unit& u, int wr, int wc, int fr, int fq) const {
;     ...
;                 for (int m = 0; m < 4; ++m) {
;                     u32x2_t w; float o[4];
; #pragma unroll
;                     for (int e = 0; e < 4; ++e) {
;                         const float g1 = m >= 1 ? xg[m - (m >= 1 ? 1 : 0)][e] : pg3[e], g2 = m >= 2 ? xg[m - (m >= 2 ? 2 : 0)][e] : (m == 1 ? pg3[e] : pg2[e]);
;                         const float v1 = m >= 1 ? xv[m - (m >= 1 ? 1 : 0)][e] : pv3[e], v2 = m >= 2 ? xv[m - (m >= 2 ? 2 : 0)][e] : (m == 1 ? pv3[e] : pv2[e]);
;                         const float cg_ = bg[e] + w0g[e] * g2 + w1g[e] * g1 + w2g[e] * xg[m][e];
;                         const float cv_ = bv[e] + w0v[e] * v2 + w1v[e] * v1 + w2v[e] * xv[m][e];
;                         o[e] = cg_ * __builtin_amdgcn_rcpf(1.0f + __expf(-cg_)) * cv_;
;                     }
;                     w.x = cvt_pk_bf16(o[0], o[1]); w.y = cvt_pk_bf16(o[2], o[3]);
;                     const int g = g0 + m;
;                     if (n == 0) stash[ai][m] = w;
;                     else if ((fr > 0 || m >= 2) && g < TT) { u32x4 ww; ww.x = stash[ai][m].x; ww.y = stash[ai][m].y; ww.z = w.x; ww.w = w.y; *(u32x4*)(G + (size_t)g * DFF_ + f0 - 4) = ww; }
.LBB0_2306:
	s_or_b64 exec, exec, s[0:1]
	v_fma_f32 v14, v98, v34, v70
	v_fmac_f32_e32 v14, v90, v24
	v_fmac_f32_e32 v14, v94, v26
	v_mul_f32_e32 v22, 0xbfb8aa3b, v14
	v_exp_f32_e32 v22, v22
	v_fma_f32 v15, v74, v32, v86
	v_fmac_f32_e32 v15, v78, v18
	v_fmac_f32_e32 v15, v82, v20
	v_add_f32_e32 v22, 1.0, v22
	v_rcp_f32_e32 v22, v22
	v_cmp_gt_i32_e32 vcc, s93, v211
	v_mul_f32_e32 v14, v14, v22
	v_mul_f32_e32 v14, v15, v14
	v_fma_f32 v15, v99, v35, v71
	v_fmac_f32_e32 v15, v91, v25
	v_fmac_f32_e32 v15, v95, v27
	v_mul_f32_e32 v23, 0xbfb8aa3b, v15
	v_exp_f32_e32 v23, v23
	v_fma_f32 v22, v75, v33, v87
	v_fmac_f32_e32 v22, v79, v19
	v_fmac_f32_e32 v22, v83, v21
	v_add_f32_e32 v23, 1.0, v23
	v_rcp_f32_e32 v23, v23
	s_nop 0
	v_mul_f32_e32 v15, v15, v23
	v_mul_f32_e32 v15, v22, v15
	v_fma_f32 v22, v100, v30, v72
	v_fmac_f32_e32 v22, v92, v16
	v_fmac_f32_e32 v22, v96, v10
	v_fma_f32 v23, v76, v28, v88
	v_mul_f32_e32 v28, 0xbfb8aa3b, v22
	v_exp_f32_e32 v28, v28
	v_fmac_f32_e32 v23, v80, v8
	v_fmac_f32_e32 v23, v84, v4
	v_cvt_pk_bf16_f32 v68, v14, v15
	v_add_f32_e32 v28, 1.0, v28
	v_rcp_f32_e32 v28, v28
	s_nop 0
	v_mul_f32_e32 v22, v22, v28
	v_mul_f32_e32 v22, v23, v22
	v_fma_f32 v23, v101, v31, v73
	v_fmac_f32_e32 v23, v93, v17
	v_fmac_f32_e32 v23, v97, v11
	v_fma_f32 v28, v77, v29, v89
	v_mul_f32_e32 v29, 0xbfb8aa3b, v23
	v_exp_f32_e32 v29, v29
	v_fmac_f32_e32 v28, v81, v9
	v_fmac_f32_e32 v28, v85, v5
	v_add_f32_e32 v29, 1.0, v29
	v_rcp_f32_e32 v29, v29
	s_nop 0
	v_mul_f32_e32 v23, v23, v29
	v_mul_f32_e32 v23, v28, v23
	v_cvt_pk_bf16_f32 v69, v22, v23
	s_and_saveexec_b64 s[0:1], vcc
	s_cbranch_execz .LBB0_2308
	v_mov_b64_e32 v[14:15], s[14:15]
	v_mad_i64_i32 v[14:15], s[2:3], v212, s92, v[14:15]
	v_lshl_add_u64 v[14:15], v[178:179], 1, v[14:15]
	global_store_dwordx4 v[14:15], v[66:69], off sc1
.LBB0_2308:
	s_or_b64 exec, exec, s[0:1]
	v_fma_f32 v14, v98, v24, v70
	v_fmac_f32_e32 v14, v90, v26
	v_fmac_f32_e32 v14, v94, v12
	v_mul_f32_e32 v12, 0xbfb8aa3b, v14
	v_exp_f32_e32 v12, v12
	v_fma_f32 v15, v74, v18, v86
	v_fma_f32 v18, v99, v25, v71
	v_fmac_f32_e32 v18, v91, v27
	v_fmac_f32_e32 v18, v95, v13
	v_add_f32_e32 v12, 1.0, v12
	v_mul_f32_e32 v13, 0xbfb8aa3b, v18
	v_rcp_f32_e32 v12, v12
	v_exp_f32_e32 v13, v13
	v_fmac_f32_e32 v15, v78, v20
	v_fmac_f32_e32 v15, v82, v6
	v_mul_f32_e32 v6, v14, v12
	v_add_f32_e32 v12, 1.0, v13
	v_rcp_f32_e32 v12, v12
	v_fma_f32 v13, v75, v19, v87
	v_fmac_f32_e32 v13, v79, v21
	v_fmac_f32_e32 v13, v83, v7
	v_mul_f32_e32 v7, v18, v12
	v_fma_f32 v12, v100, v16, v72
	v_fmac_f32_e32 v73, v101, v17
	v_fmac_f32_e32 v12, v92, v10
	v_fmac_f32_e32 v73, v93, v11
	v_fmac_f32_e32 v12, v96, v0
	v_fmac_f32_e32 v73, v97, v1
	v_mul_f32_e32 v0, 0xbfb8aa3b, v12
	v_mul_f32_e32 v1, 0xbfb8aa3b, v73
	v_exp_f32_e32 v0, v0
	v_exp_f32_e32 v1, v1
	v_fma_f32 v8, v76, v8, v88
	v_fmac_f32_e32 v89, v77, v9
	v_add_f32_e32 v0, 1.0, v0
	v_add_f32_e32 v1, 1.0, v1
	v_rcp_f32_e32 v0, v0
	v_rcp_f32_e32 v1, v1
	v_fmac_f32_e32 v8, v80, v4
	v_fmac_f32_e32 v89, v81, v5
	v_fmac_f32_e32 v8, v84, v2
	v_mul_f32_e32 v0, v12, v0
	v_fmac_f32_e32 v89, v85, v3
	v_mul_f32_e32 v1, v73, v1
	v_cmp_gt_i32_e32 vcc, s94, v211
	v_mul_f32_e32 v6, v15, v6
	v_mul_f32_e32 v7, v13, v7
	v_mul_f32_e32 v0, v8, v0
	v_mul_f32_e32 v1, v89, v1
	v_cvt_pk_bf16_f32 v66, v6, v7
	v_cvt_pk_bf16_f32 v67, v0, v1
	s_and_saveexec_b64 s[0:1], vcc
	s_cbranch_execz .LBB0_2310
	v_mov_b64_e32 v[0:1], s[14:15]
	v_mad_i64_i32 v[0:1], s[2:3], v214, s92, v[0:1]
	v_lshl_add_u64 v[0:1], v[178:179], 1, v[0:1]
	global_store_dwordx4 v[0:1], v[64:67], off sc1

; #define LAS __attribute__((address_space(3)))
; __device__ __forceinline__ unsigned cvtpk(float lo, float hi) { f32x2 v = {lo, hi}; bf16x2_t b = __builtin_convertvector(v, bf16x2_t); return __builtin_bit_cast(unsigned, b); }
; __device__ __forceinline__ void witem_store(const WItem& w, int K, bf16_t* WT, int kvperm, LAS float* scr, int item, int nblk, int lane) {
;     ...
; #pragma unroll
;     for (int i = 0; i < 8; ++i) { LAS float* d = scr + (8 * i + rr) * 33 + col; const float g = w.g[i]; d[0] = w.v[i].x * g; d[1] = w.v[i].y * g; d[2] = w.v[i].z * g; d[3] = w.v[i].w * g; }
;     asm volatile("s_waitcnt lgkmcnt(0)" ::: "memory");
;     const int c = lane & 7;
; #pragma unroll
;     for (int j = 0; j < 4; ++j) { const int n = (lane >> 3) + 8 * j; const LAS float* s = scr + (8 * c) * 33 + n;
;         u32x4 o; o.x = cvtpk(s[0 * 33], s[1 * 33]); o.y = cvtpk(s[2 * 33], s[3 * 33]); o.z = cvtpk(s[4 * 33], s[5 * 33]); o.w = cvtpk(s[6 * 33], s[7 * 33]);
;         int nr = n0 + n; if (kvperm == 1) { const int hh = nr >> 8, ww = nr & 255; nr = (ww < 128) ? hh * 128 + ww : 2048 + hh * 128 + (ww - 128); }
;         else if (kvperm == 2) { const int isv = nr >= 5632, f = isv ? nr - 5632 : nr; nr = (f >> 7) * 256 + isv * 128 + (f & 127); }
;         *(u32x4*)(WT + (size_t)nr * K + k0 + 8 * c) = o; }
;     asm volatile("s_waitcnt lgkmcnt(0)" ::: "memory");
;     ...
;     while (it < i1) {
;         cur = nxt;
;         const int nit = it + NGW;
;         if (nit < i1) witem_load(nxt, W, N, gk, nit, nblk, lane);
;         witem_store(cur, K, WT, kvperm, scr, it, nblk, lane);
;         it = nit;
;     }
.LBB0_2334:
	v_pk_mul_f32 v[2:3], v[8:9], v[72:73] op_sel_hi:[1,0]
	ds_write2_b32 v79, v2, v3 offset1:1
	v_pk_mul_f32 v[2:3], v[10:11], v[72:73] op_sel_hi:[1,0]
	ds_write2_b32 v79, v2, v3 offset0:2 offset1:3
	v_pk_mul_f32 v[2:3], v[4:5], v[74:75] op_sel_hi:[1,0]
	v_add_u32_e32 v4, 0x420, v79
	ds_write2_b32 v4, v2, v3 offset1:1
	v_pk_mul_f32 v[2:3], v[6:7], v[74:75] op_sel_hi:[1,0]
	v_add_u32_e32 v4, 0x428, v79
	ds_write2_b32 v4, v2, v3 offset1:1
	v_pk_mul_f32 v[2:3], v[24:25], v[76:77] op_sel_hi:[1,0]
	v_add_u32_e32 v4, 0x840, v79
	ds_write2_b32 v4, v2, v3 offset1:1
	v_pk_mul_f32 v[2:3], v[26:27], v[76:77] op_sel_hi:[1,0]
	v_add_u32_e32 v4, 0x848, v79
	ds_write2_b32 v4, v2, v3 offset1:1
	v_pk_mul_f32 v[2:3], v[20:21], v[78:79] op_sel_hi:[1,0]
	v_add_u32_e32 v4, 0xc60, v79
	ds_write2_b32 v4, v2, v3 offset1:1
	v_pk_mul_f32 v[2:3], v[22:23], v[78:79] op_sel_hi:[1,0]
	v_add_u32_e32 v4, 0xc68, v79
	ds_write2_b32 v4, v2, v3 offset1:1
	v_pk_mul_f32 v[2:3], v[36:37], v[80:81] op_sel_hi:[1,0]
	v_add_u32_e32 v4, 0x1080, v79
	ds_write2_b32 v4, v2, v3 offset1:1
	v_pk_mul_f32 v[2:3], v[38:39], v[80:81] op_sel_hi:[1,0]
	v_add_u32_e32 v4, 0x1088, v79
	ds_write2_b32 v4, v2, v3 offset1:1
	v_pk_mul_f32 v[2:3], v[28:29], v[82:83] op_sel_hi:[1,0]
	v_add_u32_e32 v4, 0x14a0, v79
	ds_write2_b32 v4, v2, v3 offset1:1
	v_pk_mul_f32 v[2:3], v[30:31], v[82:83] op_sel_hi:[1,0]
	v_add_u32_e32 v4, 0x14a8, v79
	ds_write2_b32 v4, v2, v3 offset1:1
	s_waitcnt vmcnt(7)
	v_pk_mul_f32 v[2:3], v[48:49], v[84:85] op_sel_hi:[1,0]
	v_add_u32_e32 v4, 0x18c0, v79
	s_mul_hi_i32 s3, s3, 0x2e8ba2e9
	ds_write2_b32 v4, v2, v3 offset1:1
	v_pk_mul_f32 v[2:3], v[50:51], v[84:85] op_sel_hi:[1,0]
	v_add_u32_e32 v4, 0x18c8, v79
	s_lshr_b32 s8, s3, 31
	s_ashr_i32 s3, s3, 6
	ds_write2_b32 v4, v2, v3 offset1:1
	s_waitcnt vmcnt(6)
	v_pk_mul_f32 v[2:3], v[44:45], v[86:87] op_sel_hi:[1,0]
	v_add_u32_e32 v4, 0x1ce0, v79
	s_add_i32 s3, s3, s8
	ds_write2_b32 v4, v2, v3 offset1:1
	v_pk_mul_f32 v[2:3], v[46:47], v[86:87] op_sel_hi:[1,0]
	v_add_u32_e32 v4, 0x1ce8, v79
	s_lshl_b32 s8, s3, 6
	ds_write2_b32 v4, v2, v3 offset1:1
	s_mulk_i32 s3, 0xd400
	s_waitcnt lgkmcnt(0)
	s_add_i32 s3, s3, s6
	ds_read2_b32 v[6:7], v77 offset0:33 offset1:41
	ds_read2_b32 v[8:9], v77 offset1:8
	ds_read2_b32 v[10:11], v77 offset0:66 offset1:74
	ds_read2_b32 v[20:21], v77 offset0:99 offset1:107
	ds_read2_b32 v[22:23], v77 offset0:132 offset1:140
	ds_read2_b32 v[24:25], v77 offset0:165 offset1:173
	ds_read2_b32 v[26:27], v77 offset0:198 offset1:206
	ds_read2_b32 v[28:29], v77 offset0:231 offset1:239
	v_add_u32_e32 v38, s3, v83
	s_waitcnt lgkmcnt(6)
	v_cvt_pk_bf16_f32 v2, v8, v6
	v_add_u32_e32 v6, 0xffffea00, v38
	v_cmp_lt_i32_e32 vcc, s12, v38
	s_waitcnt lgkmcnt(4)
	v_cvt_pk_bf16_f32 v3, v10, v20
	s_ashr_i32 s9, s8, 31
	v_cndmask_b32_e32 v6, v38, v6, vcc
	v_lshlrev_b32_e32 v8, 1, v6
	v_and_b32_e32 v8, 0xffffff00, v8
	v_cndmask_b32_e32 v10, 0, v81, vcc
	v_and_b32_e32 v6, 0x67, v6
	v_or3_b32 v36, v6, v10, v8
	v_ashrrev_i32_e32 v37, 31, v36
	v_lshl_add_u64 v[30:31], s[8:9], 1, v[70:71]
	v_lshlrev_b64 v[36:37], 12, v[36:37]
	s_waitcnt lgkmcnt(2)
	v_cvt_pk_bf16_f32 v4, v22, v24
	s_waitcnt lgkmcnt(0)
	v_cvt_pk_bf16_f32 v5, v26, v28
	v_lshl_add_u64 v[36:37], v[30:31], 0, v[36:37]
	v_add_u32_e32 v6, 8, v38
	global_store_dwordx4 v[36:37], v[2:5], off sc1
	v_cmp_lt_i32_e32 vcc, s12, v6
	s_waitcnt vmcnt(3)
	v_mov_b64_e32 v[48:49], v[60:61]
	v_cvt_pk_bf16_f32 v2, v9, v7
	v_add_u32_e32 v7, 0xffffea08, v38
	v_cndmask_b32_e32 v6, v6, v7, vcc
	v_lshlrev_b32_e32 v7, 1, v6
	v_and_b32_e32 v7, 0xffffff00, v7
	v_cndmask_b32_e32 v8, 0, v81, vcc
	v_and_b32_e32 v6, 0x6f, v6
	v_or3_b32 v6, v6, v8, v7
	v_ashrrev_i32_e32 v7, 31, v6
	v_lshlrev_b64 v[6:7], 12, v[6:7]
	v_cvt_pk_bf16_f32 v3, v11, v21
	v_cvt_pk_bf16_f32 v4, v23, v25
	v_cvt_pk_bf16_f32 v5, v27, v29
	v_lshl_add_u64 v[6:7], v[30:31], 0, v[6:7]
	ds_read2_b32 v[8:9], v77 offset0:16 offset1:24
	ds_read2_b32 v[10:11], v77 offset0:49 offset1:57
	ds_read2_b32 v[20:21], v77 offset0:82 offset1:90
	ds_read2_b32 v[22:23], v77 offset0:115 offset1:123
	ds_read2_b32 v[24:25], v77 offset0:148 offset1:156
	ds_read2_b32 v[26:27], v77 offset0:181 offset1:189
	ds_read2_b32 v[28:29], v77 offset0:214 offset1:222
	ds_read2_b32 v[36:37], v77 offset0:247 offset1:255
	global_store_dwordx4 v[6:7], v[2:5], off sc1
	v_add_u32_e32 v6, 16, v38
	v_add_u32_e32 v7, 0xffffea10, v38
	v_cmp_lt_i32_e32 vcc, s12, v6
	s_waitcnt lgkmcnt(6)
	v_cvt_pk_bf16_f32 v2, v8, v10
	s_waitcnt lgkmcnt(4)
	v_cvt_pk_bf16_f32 v3, v20, v22
	v_cndmask_b32_e32 v6, v6, v7, vcc
	v_lshlrev_b32_e32 v7, 1, v6
	v_and_b32_e32 v7, 0xffffff00, v7
	v_cndmask_b32_e32 v8, 0, v81, vcc
	v_and_b32_e32 v6, 0x77, v6
	v_or3_b32 v6, v6, v8, v7
	v_ashrrev_i32_e32 v7, 31, v6
	v_lshlrev_b64 v[6:7], 12, v[6:7]
	s_waitcnt lgkmcnt(2)
	v_cvt_pk_bf16_f32 v4, v24, v26
	s_waitcnt lgkmcnt(0)
	v_cvt_pk_bf16_f32 v5, v28, v36
	v_lshl_add_u64 v[6:7], v[30:31], 0, v[6:7]
	global_store_dwordx4 v[6:7], v[2:5], off sc1
	s_waitcnt vmcnt(4)
	v_mov_b64_e32 v[44:45], v[64:65]
	v_add_u32_e32 v83, s7, v83
	v_add_u32_e32 v2, 24, v38
	v_add_u32_e32 v3, 0xffffea18, v38
	v_cmp_lt_i32_e32 vcc, s12, v2
	v_cvt_pk_bf16_f32 v5, v29, v37
	v_mov_b64_e32 v[36:37], v[52:53]
	v_cndmask_b32_e32 v2, v2, v3, vcc
	v_lshlrev_b32_e32 v3, 1, v2
	v_and_b32_e32 v3, 0xffffff00, v3
	v_cndmask_b32_e32 v4, 0, v81, vcc
	v_and_b32_e32 v2, 0x7f, v2
	v_or3_b32 v6, v2, v4, v3
	v_ashrrev_i32_e32 v7, 31, v6
	v_lshlrev_b64 v[6:7], 12, v[6:7]
	v_cvt_pk_bf16_f32 v2, v9, v11
	v_cvt_pk_bf16_f32 v3, v21, v23
	v_cvt_pk_bf16_f32 v4, v25, v27
	v_lshl_add_u64 v[6:7], v[30:31], 0, v[6:7]
	global_store_dwordx4 v[6:7], v[2:5], off sc1
	s_waitcnt lgkmcnt(0)
	v_mov_b64_e32 v[8:9], v[16:17]
	v_mov_b64_e32 v[24:25], v[32:33]
	v_mov_b64_e32 v[4:5], v[12:13]
	v_mov_b64_e32 v[20:21], v[40:41]
	v_mov_b64_e32 v[28:29], v[56:57]
	s_add_i32 s13, s13, s7
	v_add_u32_e32 v73, s7, v73
	s_andn2_b64 vcc, exec, s[4:5]
	s_mov_b32 s3, s14
	v_mov_b64_e32 v[10:11], v[18:19]
	v_mov_b64_e32 v[6:7], v[14:15]
	v_mov_b64_e32 v[26:27], v[34:35]
	v_mov_b64_e32 v[22:23], v[42:43]
	v_mov_b64_e32 v[38:39], v[54:55]
	v_mov_b64_e32 v[30:31], v[58:59]
	v_mov_b64_e32 v[50:51], v[62:63]
	v_mov_b64_e32 v[46:47], v[66:67]
	v_mov_b32_e32 v72, v85
	v_mov_b32_e32 v74, v87
	v_mov_b32_e32 v76, v89
	v_mov_b32_e32 v78, v94
	v_mov_b32_e32 v80, v95
	v_mov_b32_e32 v82, v96
	v_mov_b32_e32 v84, v97
	s_waitcnt vmcnt(4)
	v_mov_b32_e32 v86, v1
	s_cbranch_vccz .LBB0_2352

; __device__ __forceinline__ unsigned cvt_pk_bf16(float lo, float hi) { unsigned r; asm volatile("v_cvt_pk_bf16_f32 %0, %1, %2" : "=v"(r) : "v"(lo), "v"(hi)); return r; }
;     __device__ __forceinline__ void operator()(const f32x4 (&acc)[2][2][4][2], const Unit& u, int wr, int wc, int fr, int fq) const {
;     ...
;         float* ssp = ssout + (size_t)(u.pn * 4 + wc);
; #pragma unroll
;         for (int ai = 0; ai < 2; ++ai) {
;             u32x4 old[4][2];
; #pragma unroll
;             for (int m = 0; m < 4; ++m)
; #pragma unroll
;                 for (int bj = 0; bj < 2; ++bj) old[m][bj] = *(const u32x4*)(HB + (size_t)(row0 + ai * HALF + m * 16) * ldc + col0 + bj * HALF);
; #pragma unroll
;             for (int m = 0; m < 4; ++m) { const int row = row0 + ai * HALF + m * 16; float ss = 0.f;
; #pragma unroll
;                 for (int bj = 0; bj < 2; ++bj) { const u32x4 ow = old[m][bj];
;                     f32x4 v0 = (acc[ai][bj][m][0] + bv[bj][0]) * accs, v1 = (acc[ai][bj][m][1] + bv[bj][1]) * accs;
;                     v0[0] += __uint_as_float(ow.x << 16); v0[1] += __uint_as_float(ow.x & 0xffff0000u); v0[2] += __uint_as_float(ow.y << 16); v0[3] += __uint_as_float(ow.y & 0xffff0000u);
;                     v1[0] += __uint_as_float(ow.z << 16); v1[1] += __uint_as_float(ow.z & 0xffff0000u); v1[2] += __uint_as_float(ow.w << 16); v1[3] += __uint_as_float(ow.w & 0xffff0000u);
;                     ss += (v0[0] * v0[0] + v0[1] * v0[1]) + (v0[2] * v0[2] + v0[3] * v0[3]) + (v1[0] * v1[0] + v1[1] * v1[1]) + (v1[2] * v1[2] + v1[3] * v1[3]);
;                     u32x4 w; w.x = cvt_pk_bf16(v0[0], v0[1]); w.y = cvt_pk_bf16(v0[2], v0[3]); w.z = cvt_pk_bf16(v1[0], v1[1]); w.w = cvt_pk_bf16(v1[2], v1[3]);
;                     *(u32x4*)(HB + (size_t)row * ldc + col0 + bj * HALF) = w; }
;                 ss += __shfl_xor(ss, 16); ss += __shfl_xor(ss, 32);
;                 if (fq == 0) ssp[(size_t)row * 32] = ss; }
.LBB0_2430:
	v_lshl_or_b32 v152, s6, 8, v166
	v_ashrrev_i32_e32 v153, 31, v152
	v_lshl_add_u32 v156, s7, 8, v164
	v_lshlrev_b64 v[178:179], 1, v[152:153]
	v_ashrrev_i32_e32 v157, 31, v156
	v_lshl_add_u64 v[154:155], s[8:9], 0, v[178:179]
	v_lshlrev_b64 v[180:181], 12, v[156:157]
	v_lshl_add_u64 v[128:129], v[154:155], 0, v[180:181]
	global_load_dwordx4 v[170:173], v[128:129], off
	global_load_dwordx4 v[174:177], v[128:129], off offset:256
	v_or_b32_e32 v162, 16, v156
	v_or_b32_e32 v160, 32, v156
	v_or_b32_e32 v158, 48, v156
	v_ashrrev_i32_e32 v163, 31, v162
	v_ashrrev_i32_e32 v161, 31, v160
	v_pk_add_f32 v[194:195], v[114:115], 0 op_sel_hi:[1,0]
	v_pk_add_f32 v[196:197], v[112:113], 0 op_sel_hi:[1,0]
	v_ashrrev_i32_e32 v159, 31, v158
	v_lshlrev_b64 v[112:113], 12, v[162:163]
	v_lshlrev_b64 v[114:115], 12, v[160:161]
	v_pk_add_f32 v[192:193], v[116:117], 0 op_sel_hi:[1,0]
	v_lshlrev_b64 v[116:117], 12, v[158:159]
	v_lshl_add_u64 v[112:113], v[154:155], 0, v[112:113]
	v_lshl_add_u64 v[114:115], v[154:155], 0, v[114:115]
	v_pk_add_f32 v[182:183], v[126:127], 0 op_sel_hi:[1,0]
	v_pk_add_f32 v[184:185], v[124:125], 0 op_sel_hi:[1,0]
	v_pk_add_f32 v[186:187], v[122:123], 0 op_sel_hi:[1,0]
	v_pk_add_f32 v[188:189], v[120:121], 0 op_sel_hi:[1,0]
	v_pk_add_f32 v[190:191], v[118:119], 0 op_sel_hi:[1,0]
	v_lshl_add_u64 v[198:199], v[154:155], 0, v[116:117]
	global_load_dwordx4 v[132:135], v[112:113], off
	global_load_dwordx4 v[128:131], v[112:113], off offset:256
	global_load_dwordx4 v[124:127], v[114:115], off
	global_load_dwordx4 v[120:123], v[114:115], off offset:256
	global_load_dwordx4 v[116:119], v[198:199], off
	s_nop 0
	global_load_dwordx4 v[112:115], v[198:199], off offset:256
	s_lshl_b32 s6, s6, 2
	s_or_b32 s6, s6, s50
	s_ashr_i32 s7, s6, 31
	s_lshl_b64 s[6:7], s[6:7], 2
	s_add_u32 s16, s36, s6
	s_addc_u32 s17, s37, s7
	s_waitcnt vmcnt(0)
	v_lshlrev_b32_e32 v198, 16, v170
	v_and_b32_e32 v170, 0xffff0000, v170
	v_lshlrev_b32_e32 v199, 16, v171
	v_and_b32_e32 v171, 0xffff0000, v171
	v_lshlrev_b32_e32 v200, 16, v172
	v_and_b32_e32 v172, 0xffff0000, v172
	v_lshlrev_b32_e32 v203, 16, v174
	v_and_b32_e32 v174, 0xffff0000, v174
	v_lshlrev_b32_e32 v205, 16, v175
	v_and_b32_e32 v175, 0xffff0000, v175
	v_lshlrev_b32_e32 v201, 16, v173
	v_and_b32_e32 v173, 0xffff0000, v173
	v_lshlrev_b32_e32 v206, 16, v176
	v_and_b32_e32 v176, 0xffff0000, v176
	v_lshlrev_b32_e32 v207, 16, v177
	v_and_b32_e32 v177, 0xffff0000, v177
	v_add_f32_e32 v170, v185, v170
	v_add_f32_e32 v171, v183, v171
	v_add_f32_e32 v185, v189, v172
	v_add_f32_e32 v189, v193, v174
	v_add_f32_e32 v191, v191, v175
	v_add_f32_e32 v184, v184, v198
	v_add_f32_e32 v182, v182, v199
	v_add_f32_e32 v183, v188, v200
	v_add_f32_e32 v187, v187, v173
	v_add_f32_e32 v188, v192, v203
	v_add_f32_e32 v190, v190, v205
	v_add_f32_e32 v193, v197, v176
	v_add_f32_e32 v195, v195, v177
	v_mul_f32_e32 v176, v170, v170
	v_mul_f32_e32 v177, v171, v171
	v_cvt_pk_bf16_f32 v172, v184, v170
	v_cvt_pk_bf16_f32 v173, v182, v171
	v_mul_f32_e32 v170, v189, v189
	v_mul_f32_e32 v171, v191, v191
	v_fmac_f32_e32 v170, v188, v188
	v_fmac_f32_e32 v171, v190, v190
	v_add_f32_e32 v192, v196, v206
	v_add_f32_e32 v170, v170, v171
	v_mul_f32_e32 v171, v193, v193
	v_mul_f32_e32 v196, v185, v185
	v_fmac_f32_e32 v176, v184, v184
	v_fmac_f32_e32 v177, v182, v182
	v_fmac_f32_e32 v171, v192, v192
	v_add_f32_e32 v186, v186, v201
	v_add_f32_e32 v194, v194, v207
	v_mul_f32_e32 v197, v187, v187
	v_fmac_f32_e32 v196, v183, v183
	v_add_f32_e32 v176, v176, v177
	v_add_f32_e32 v170, v171, v170
	v_mul_f32_e32 v171, v195, v195
	v_fmac_f32_e32 v197, v186, v186
	v_add_f32_e32 v176, v196, v176
	v_fmac_f32_e32 v171, v194, v194
	v_add_f32_e32 v176, v197, v176
	v_add_f32_e32 v170, v171, v170
	v_add_f32_e32 v171, v176, v170
	v_and_b32_e32 v176, 64, v202
	v_xor_b32_e32 v170, 16, v202
	v_add_u32_e32 v182, 64, v176
	v_cmp_lt_i32_e32 vcc, v170, v182
	v_cvt_pk_bf16_f32 v174, v183, v185
	v_lshl_add_u64 v[176:177], s[8:9], 0, v[180:181]
	v_lshl_add_u64 v[178:179], v[176:177], 0, v[178:179]
	v_cndmask_b32_e32 v170, v202, v170, vcc
	v_lshlrev_b32_e32 v170, 2, v170
	ds_bpermute_b32 v183, v170, v171
	v_cvt_pk_bf16_f32 v175, v186, v187
	global_store_dwordx4 v[178:179], v[172:175], off sc1
	s_waitcnt lgkmcnt(0)
	s_nop 0
	v_add_f32_e32 v172, v171, v183
	v_xor_b32_e32 v171, 32, v202
	v_cmp_lt_i32_e32 vcc, v171, v182
	v_cvt_pk_bf16_f32 v174, v188, v189
	v_cvt_pk_bf16_f32 v175, v190, v191
	v_cvt_pk_bf16_f32 v176, v192, v193
	v_cvt_pk_bf16_f32 v177, v194, v195
	global_store_dwordx4 v[178:179], v[174:177], off offset:256 sc1
	s_nop 0
	v_cndmask_b32_e32 v171, v202, v171, vcc
	v_lshlrev_b32_e32 v171, 2, v171
	ds_bpermute_b32 v173, v171, v172
	s_and_saveexec_b64 s[18:19], s[44:45]
	s_cbranch_execz .LBB0_2432
	v_lshlrev_b64 v[174:175], 7, v[156:157]
	v_lshl_add_u64 v[174:175], s[16:17], 0, v[174:175]
	s_waitcnt lgkmcnt(0)
	v_add_f32_e32 v157, v172, v173
	global_store_dword v[174:175], v157, off
; __device__ __forceinline__ unsigned cvt_pk_bf16(float lo, float hi) { unsigned r; asm volatile("v_cvt_pk_bf16_f32 %0, %1, %2" : "=v"(r) : "v"(lo), "v"(hi)); return r; }
;     __device__ __forceinline__ void operator()(const f32x4 (&acc)[2][2][4][2], const Unit& u, int wr, int wc, int fr, int fq) const {
;     ...
;             for (int m = 0; m < 4; ++m) { const int row = row0 + ai * HALF + m * 16; float ss = 0.f;
; #pragma unroll
;                 for (int bj = 0; bj < 2; ++bj) { const u32x4 ow = old[m][bj];
;                     f32x4 v0 = (acc[ai][bj][m][0] + bv[bj][0]) * accs, v1 = (acc[ai][bj][m][1] + bv[bj][1]) * accs;
;                     v0[0] += __uint_as_float(ow.x << 16); v0[1] += __uint_as_float(ow.x & 0xffff0000u); v0[2] += __uint_as_float(ow.y << 16); v0[3] += __uint_as_float(ow.y & 0xffff0000u);
;                     v1[0] += __uint_as_float(ow.z << 16); v1[1] += __uint_as_float(ow.z & 0xffff0000u); v1[2] += __uint_as_float(ow.w << 16); v1[3] += __uint_as_float(ow.w & 0xffff0000u);
;                     ss += (v0[0] * v0[0] + v0[1] * v0[1]) + (v0[2] * v0[2] + v0[3] * v0[3]) + (v1[0] * v1[0] + v1[1] * v1[1]) + (v1[2] * v1[2] + v1[3] * v1[3]);
;                     u32x4 w; w.x = cvt_pk_bf16(v0[0], v0[1]); w.y = cvt_pk_bf16(v0[2], v0[3]); w.z = cvt_pk_bf16(v1[0], v1[1]); w.w = cvt_pk_bf16(v1[2], v1[3]);
;                     *(u32x4*)(HB + (size_t)row * ldc + col0 + bj * HALF) = w; }
;                 ss += __shfl_xor(ss, 16); ss += __shfl_xor(ss, 32);
;                 if (fq == 0) ssp[(size_t)row * 32] = ss; }
.LBB0_2432:
	s_or_b64 exec, exec, s[18:19]
	v_pk_add_f32 v[108:109], v[108:109], 0 op_sel_hi:[1,0]
	v_lshlrev_b32_e32 v157, 16, v132
	v_and_b32_e32 v132, 0xffff0000, v132
	v_pk_add_f32 v[110:111], v[110:111], 0 op_sel_hi:[1,0]
	v_add_f32_e32 v109, v109, v132
	v_lshlrev_b32_e32 v132, 16, v133
	v_add_f32_e32 v110, v110, v132
	v_and_b32_e32 v132, 0xffff0000, v133
	v_pk_add_f32 v[104:105], v[104:105], 0 op_sel_hi:[1,0]
	v_add_f32_e32 v111, v111, v132
	v_lshlrev_b32_e32 v132, 16, v134
	v_add_f32_e32 v132, v104, v132
	v_and_b32_e32 v104, 0xffff0000, v134
	v_pk_add_f32 v[106:107], v[106:107], 0 op_sel_hi:[1,0]
	v_add_f32_e32 v133, v105, v104
	v_lshlrev_b32_e32 v104, 16, v135
	v_add_f32_e32 v134, v106, v104
	v_and_b32_e32 v104, 0xffff0000, v135
	v_add_f32_e32 v108, v108, v157
	v_add_f32_e32 v107, v107, v104
	v_mul_f32_e32 v104, v109, v109
	v_mul_f32_e32 v105, v111, v111
	v_fmac_f32_e32 v104, v108, v108
	v_fmac_f32_e32 v105, v110, v110
	v_add_f32_e32 v104, v104, v105
	v_mul_f32_e32 v105, v133, v133
	v_fmac_f32_e32 v105, v132, v132
	v_add_f32_e32 v104, v105, v104
	v_mul_f32_e32 v105, v107, v107
	v_fmac_f32_e32 v105, v134, v134
	v_add_f32_e32 v135, v105, v104
	v_cvt_pk_bf16_f32 v104, v108, v109
	v_pk_add_f32 v[100:101], v[100:101], 0 op_sel_hi:[1,0]
	v_lshlrev_b32_e32 v108, 16, v128
	v_add_f32_e32 v100, v100, v108
	v_and_b32_e32 v108, 0xffff0000, v128
	v_pk_add_f32 v[102:103], v[102:103], 0 op_sel_hi:[1,0]
	v_add_f32_e32 v101, v101, v108
	v_lshlrev_b32_e32 v108, 16, v129
	v_add_f32_e32 v108, v102, v108
	v_and_b32_e32 v102, 0xffff0000, v129
	v_pk_add_f32 v[96:97], v[96:97], 0 op_sel_hi:[1,0]
	v_add_f32_e32 v109, v103, v102
	v_lshlrev_b32_e32 v102, 16, v130
	v_cvt_pk_bf16_f32 v105, v110, v111
	v_add_f32_e32 v110, v96, v102
	v_and_b32_e32 v96, 0xffff0000, v130
	v_pk_add_f32 v[98:99], v[98:99], 0 op_sel_hi:[1,0]
	v_add_f32_e32 v111, v97, v96
	v_lshlrev_b32_e32 v96, 16, v131
	v_add_f32_e32 v128, v98, v96
	v_and_b32_e32 v96, 0xffff0000, v131
	v_add_f32_e32 v129, v99, v96
	v_mul_f32_e32 v96, v101, v101
	v_mul_f32_e32 v97, v109, v109
	v_fmac_f32_e32 v96, v100, v100
	v_fmac_f32_e32 v97, v108, v108
	v_add_f32_e32 v96, v96, v97
	v_mul_f32_e32 v97, v111, v111
	v_fmac_f32_e32 v97, v110, v110
	v_add_f32_e32 v96, v97, v96
	v_mul_f32_e32 v97, v129, v129
	v_fmac_f32_e32 v97, v128, v128
	v_add_f32_e32 v96, v97, v96
	v_add_f32_e32 v99, v135, v96
	ds_bpermute_b32 v130, v170, v99
	s_waitcnt lgkmcnt(1)
	v_lshlrev_b64 v[172:173], 11, v[162:163]
	v_lshl_add_u64 v[96:97], v[172:173], 1, s[8:9]
	v_lshl_add_u64 v[102:103], v[152:153], 1, v[96:97]
	v_cvt_pk_bf16_f32 v106, v132, v133
	s_waitcnt lgkmcnt(0)
	v_add_f32_e32 v96, v99, v130
	ds_bpermute_b32 v97, v171, v96
	v_cvt_pk_bf16_f32 v107, v134, v107
	global_store_dwordx4 v[102:103], v[104:107], off sc1
	v_cvt_pk_bf16_f32 v98, v100, v101
	v_cvt_pk_bf16_f32 v99, v108, v109
	v_cvt_pk_bf16_f32 v100, v110, v111
	v_cvt_pk_bf16_f32 v101, v128, v129
	global_store_dwordx4 v[102:103], v[98:101], off offset:256 sc1
	s_and_saveexec_b64 s[18:19], s[44:45]
	s_cbranch_execz .LBB0_2434
	v_lshlrev_b64 v[98:99], 7, v[162:163]
	v_lshl_add_u64 v[98:99], s[16:17], 0, v[98:99]
	s_waitcnt lgkmcnt(0)
	v_add_f32_e32 v96, v96, v97
	global_store_dword v[98:99], v96, off
.LBB0_2434:
	s_or_b64 exec, exec, s[18:19]
	v_pk_add_f32 v[92:93], v[92:93], 0 op_sel_hi:[1,0]
	v_lshlrev_b32_e32 v98, 16, v124
	v_add_f32_e32 v92, v92, v98
	v_and_b32_e32 v98, 0xffff0000, v124
	v_pk_add_f32 v[94:95], v[94:95], 0 op_sel_hi:[1,0]
	v_add_f32_e32 v93, v93, v98
	v_lshlrev_b32_e32 v98, 16, v125
	v_add_f32_e32 v94, v94, v98
	v_and_b32_e32 v98, 0xffff0000, v125
	v_pk_add_f32 v[88:89], v[88:89], 0 op_sel_hi:[1,0]
	v_add_f32_e32 v95, v95, v98
	v_lshlrev_b32_e32 v98, 16, v126
	v_add_f32_e32 v98, v88, v98
	v_and_b32_e32 v88, 0xffff0000, v126
	v_pk_add_f32 v[90:91], v[90:91], 0 op_sel_hi:[1,0]
	v_add_f32_e32 v99, v89, v88
	v_lshlrev_b32_e32 v88, 16, v127
	v_add_f32_e32 v100, v90, v88
	v_and_b32_e32 v88, 0xffff0000, v127
	v_add_f32_e32 v91, v91, v88
	v_mul_f32_e32 v88, v93, v93
	v_mul_f32_e32 v89, v95, v95
	v_fmac_f32_e32 v88, v92, v92
	v_fmac_f32_e32 v89, v94, v94
	v_add_f32_e32 v88, v88, v89
	v_mul_f32_e32 v89, v99, v99
	v_fmac_f32_e32 v89, v98, v98
	v_add_f32_e32 v88, v89, v88
	v_mul_f32_e32 v89, v91, v91
	v_fmac_f32_e32 v89, v100, v100
	v_add_f32_e32 v101, v89, v88
	v_cvt_pk_bf16_f32 v88, v92, v93
	v_pk_add_f32 v[84:85], v[84:85], 0 op_sel_hi:[1,0]
	v_lshlrev_b32_e32 v92, 16, v120
	v_add_f32_e32 v84, v84, v92
	v_and_b32_e32 v92, 0xffff0000, v120
	v_pk_add_f32 v[86:87], v[86:87], 0 op_sel_hi:[1,0]
	v_add_f32_e32 v85, v85, v92
	v_lshlrev_b32_e32 v92, 16, v121
	v_add_f32_e32 v92, v86, v92
	v_and_b32_e32 v86, 0xffff0000, v121
	v_pk_add_f32 v[80:81], v[80:81], 0 op_sel_hi:[1,0]
	v_add_f32_e32 v93, v87, v86
	v_lshlrev_b32_e32 v86, 16, v122
	v_cvt_pk_bf16_f32 v89, v94, v95
	v_add_f32_e32 v94, v80, v86
	v_and_b32_e32 v80, 0xffff0000, v122
	v_pk_add_f32 v[82:83], v[82:83], 0 op_sel_hi:[1,0]
	v_add_f32_e32 v95, v81, v80
	v_lshlrev_b32_e32 v80, 16, v123
	v_cvt_pk_bf16_f32 v90, v98, v99
	v_add_f32_e32 v98, v82, v80
	v_and_b32_e32 v80, 0xffff0000, v123
	v_add_f32_e32 v99, v83, v80
	v_mul_f32_e32 v80, v85, v85
	v_mul_f32_e32 v81, v93, v93
	v_fmac_f32_e32 v80, v84, v84
	v_fmac_f32_e32 v81, v92, v92
	v_add_f32_e32 v80, v80, v81
	v_mul_f32_e32 v81, v95, v95
	v_fmac_f32_e32 v81, v94, v94
	v_add_f32_e32 v80, v81, v80
	v_mul_f32_e32 v81, v99, v99
	v_fmac_f32_e32 v81, v98, v98
	v_add_f32_e32 v80, v81, v80
	v_add_f32_e32 v83, v101, v80
	v_cvt_pk_bf16_f32 v91, v100, v91
	ds_bpermute_b32 v100, v170, v83
	s_waitcnt lgkmcnt(1)
	v_lshlrev_b64 v[96:97], 11, v[160:161]
	v_lshl_add_u64 v[80:81], v[96:97], 1, s[8:9]
	v_lshl_add_u64 v[86:87], v[152:153], 1, v[80:81]
	global_store_dwordx4 v[86:87], v[88:91], off sc1
	s_waitcnt lgkmcnt(0)
	v_add_f32_e32 v80, v83, v100
	ds_bpermute_b32 v81, v171, v80
	v_cvt_pk_bf16_f32 v82, v84, v85
	v_cvt_pk_bf16_f32 v83, v92, v93
	v_cvt_pk_bf16_f32 v84, v94, v95
	v_cvt_pk_bf16_f32 v85, v98, v99
	global_store_dwordx4 v[86:87], v[82:85], off offset:256 sc1
	s_and_saveexec_b64 s[18:19], s[44:45]
	s_cbranch_execz .LBB0_2436
	v_lshlrev_b64 v[82:83], 7, v[160:161]
	v_lshl_add_u64 v[82:83], s[16:17], 0, v[82:83]
	s_waitcnt lgkmcnt(0)
	v_add_f32_e32 v80, v80, v81
	global_store_dword v[82:83], v80, off
; __device__ __forceinline__ unsigned cvt_pk_bf16(float lo, float hi) { unsigned r; asm volatile("v_cvt_pk_bf16_f32 %0, %1, %2" : "=v"(r) : "v"(lo), "v"(hi)); return r; }
;     __device__ __forceinline__ void operator()(const f32x4 (&acc)[2][2][4][2], const Unit& u, int wr, int wc, int fr, int fq) const {
;     ...
;         for (int ai = 0; ai < 2; ++ai) {
;             u32x4 old[4][2];
; #pragma unroll
;             for (int m = 0; m < 4; ++m)
; #pragma unroll
;                 for (int bj = 0; bj < 2; ++bj) old[m][bj] = *(const u32x4*)(HB + (size_t)(row0 + ai * HALF + m * 16) * ldc + col0 + bj * HALF);
; #pragma unroll
;             for (int m = 0; m < 4; ++m) { const int row = row0 + ai * HALF + m * 16; float ss = 0.f;
; #pragma unroll
;                 for (int bj = 0; bj < 2; ++bj) { const u32x4 ow = old[m][bj];
;                     f32x4 v0 = (acc[ai][bj][m][0] + bv[bj][0]) * accs, v1 = (acc[ai][bj][m][1] + bv[bj][1]) * accs;
;                     v0[0] += __uint_as_float(ow.x << 16); v0[1] += __uint_as_float(ow.x & 0xffff0000u); v0[2] += __uint_as_float(ow.y << 16); v0[3] += __uint_as_float(ow.y & 0xffff0000u);
;                     v1[0] += __uint_as_float(ow.z << 16); v1[1] += __uint_as_float(ow.z & 0xffff0000u); v1[2] += __uint_as_float(ow.w << 16); v1[3] += __uint_as_float(ow.w & 0xffff0000u);
;                     ss += (v0[0] * v0[0] + v0[1] * v0[1]) + (v0[2] * v0[2] + v0[3] * v0[3]) + (v1[0] * v1[0] + v1[1] * v1[1]) + (v1[2] * v1[2] + v1[3] * v1[3]);
;                     u32x4 w; w.x = cvt_pk_bf16(v0[0], v0[1]); w.y = cvt_pk_bf16(v0[2], v0[3]); w.z = cvt_pk_bf16(v1[0], v1[1]); w.w = cvt_pk_bf16(v1[2], v1[3]);
;                     *(u32x4*)(HB + (size_t)row * ldc + col0 + bj * HALF) = w; }
;                 ss += __shfl_xor(ss, 16); ss += __shfl_xor(ss, 32);
;                 if (fq == 0) ssp[(size_t)row * 32] = ss; }
.LBB0_2436:
	s_or_b64 exec, exec, s[18:19]
	v_pk_add_f32 v[76:77], v[76:77], 0 op_sel_hi:[1,0]
	v_lshlrev_b32_e32 v82, 16, v116
	v_add_f32_e32 v76, v76, v82
	v_and_b32_e32 v82, 0xffff0000, v116
	v_pk_add_f32 v[78:79], v[78:79], 0 op_sel_hi:[1,0]
	v_add_f32_e32 v77, v77, v82
	v_lshlrev_b32_e32 v82, 16, v117
	v_add_f32_e32 v78, v78, v82
	v_and_b32_e32 v82, 0xffff0000, v117
	v_pk_add_f32 v[72:73], v[72:73], 0 op_sel_hi:[1,0]
	v_add_f32_e32 v79, v79, v82
	v_lshlrev_b32_e32 v82, 16, v118
	v_add_f32_e32 v82, v72, v82
	v_and_b32_e32 v72, 0xffff0000, v118
	v_pk_add_f32 v[74:75], v[74:75], 0 op_sel_hi:[1,0]
	v_add_f32_e32 v83, v73, v72
	v_lshlrev_b32_e32 v72, 16, v119
	v_add_f32_e32 v84, v74, v72
	v_and_b32_e32 v72, 0xffff0000, v119
	v_add_f32_e32 v75, v75, v72
	v_mul_f32_e32 v72, v77, v77
	v_mul_f32_e32 v73, v79, v79
	v_fmac_f32_e32 v72, v76, v76
	v_fmac_f32_e32 v73, v78, v78
	v_add_f32_e32 v72, v72, v73
	v_mul_f32_e32 v73, v83, v83
	v_fmac_f32_e32 v73, v82, v82
	v_add_f32_e32 v72, v73, v72
	v_mul_f32_e32 v73, v75, v75
	v_fmac_f32_e32 v73, v84, v84
	v_add_f32_e32 v85, v73, v72
	v_cvt_pk_bf16_f32 v72, v76, v77
	v_pk_add_f32 v[68:69], v[68:69], 0 op_sel_hi:[1,0]
	v_lshlrev_b32_e32 v76, 16, v112
	v_add_f32_e32 v68, v68, v76
	v_and_b32_e32 v76, 0xffff0000, v112
	v_pk_add_f32 v[70:71], v[70:71], 0 op_sel_hi:[1,0]
	v_add_f32_e32 v69, v69, v76
	v_lshlrev_b32_e32 v76, 16, v113
	v_add_f32_e32 v76, v70, v76
	v_and_b32_e32 v70, 0xffff0000, v113
	v_pk_add_f32 v[64:65], v[64:65], 0 op_sel_hi:[1,0]
	v_add_f32_e32 v77, v71, v70
	v_lshlrev_b32_e32 v70, 16, v114
	v_cvt_pk_bf16_f32 v73, v78, v79
	v_add_f32_e32 v78, v64, v70
	v_and_b32_e32 v64, 0xffff0000, v114
	v_pk_add_f32 v[66:67], v[66:67], 0 op_sel_hi:[1,0]
	v_add_f32_e32 v79, v65, v64
	v_lshlrev_b32_e32 v64, 16, v115
	v_cvt_pk_bf16_f32 v74, v82, v83
	v_add_f32_e32 v82, v66, v64
	v_and_b32_e32 v64, 0xffff0000, v115
	v_add_f32_e32 v83, v67, v64
	v_mul_f32_e32 v64, v69, v69
	v_mul_f32_e32 v65, v77, v77
	v_fmac_f32_e32 v64, v68, v68
	v_fmac_f32_e32 v65, v76, v76
	v_add_f32_e32 v64, v64, v65
	v_mul_f32_e32 v65, v79, v79
	v_fmac_f32_e32 v65, v78, v78
	v_add_f32_e32 v64, v65, v64
	v_mul_f32_e32 v65, v83, v83
	v_fmac_f32_e32 v65, v82, v82
	v_add_f32_e32 v64, v65, v64
	v_add_f32_e32 v67, v85, v64
	v_cvt_pk_bf16_f32 v75, v84, v75
	ds_bpermute_b32 v84, v170, v67
	s_waitcnt lgkmcnt(1)
	v_lshlrev_b64 v[80:81], 11, v[158:159]
	v_lshl_add_u64 v[64:65], v[80:81], 1, s[8:9]
	v_lshl_add_u64 v[70:71], v[152:153], 1, v[64:65]
	global_store_dwordx4 v[70:71], v[72:75], off sc1
	s_waitcnt lgkmcnt(0)
	v_add_f32_e32 v64, v67, v84
	ds_bpermute_b32 v65, v171, v64
	v_cvt_pk_bf16_f32 v66, v68, v69
	v_cvt_pk_bf16_f32 v67, v76, v77
	v_cvt_pk_bf16_f32 v68, v78, v79
	v_cvt_pk_bf16_f32 v69, v82, v83
	global_store_dwordx4 v[70:71], v[66:69], off offset:256 sc1
	s_and_saveexec_b64 s[18:19], s[44:45]
	s_cbranch_execz .LBB0_2438
	v_lshlrev_b64 v[66:67], 7, v[158:159]
	v_lshl_add_u64 v[66:67], s[16:17], 0, v[66:67]
	s_waitcnt lgkmcnt(0)
	v_add_f32_e32 v64, v64, v65
	global_store_dword v[66:67], v64, off
.LBB0_2438:
	s_or_b64 exec, exec, s[18:19]
	v_add_u32_e32 v98, 0x80, v156
	v_ashrrev_i32_e32 v99, 31, v98
	v_lshlrev_b64 v[104:105], 12, v[98:99]
	s_waitcnt lgkmcnt(0)
	v_lshl_add_u64 v[64:65], v[154:155], 0, v[104:105]
	global_load_dwordx4 v[100:103], v[64:65], off
	global_load_dwordx4 v[88:91], v[64:65], off offset:256
	v_add_u32_e32 v96, 0x90, v156
	v_ashrrev_i32_e32 v97, 31, v96
	v_lshlrev_b64 v[64:65], 12, v[96:97]
	v_add_u32_e32 v94, 0xa0, v156
	v_lshl_add_u64 v[64:65], v[154:155], 0, v[64:65]
	v_ashrrev_i32_e32 v95, 31, v94
	global_load_dwordx4 v[84:87], v[64:65], off
	global_load_dwordx4 v[80:83], v[64:65], off offset:256
	v_lshlrev_b64 v[64:65], 12, v[94:95]
	v_add_u32_e32 v92, 0xb0, v156
	v_lshl_add_u64 v[64:65], v[154:155], 0, v[64:65]
	v_ashrrev_i32_e32 v93, 31, v92
	global_load_dwordx4 v[76:79], v[64:65], off
	global_load_dwordx4 v[72:75], v[64:65], off offset:256
	v_lshlrev_b64 v[64:65], 12, v[92:93]
	v_lshl_add_u64 v[64:65], v[154:155], 0, v[64:65]
	global_load_dwordx4 v[68:71], v[64:65], off
	s_nop 0
	global_load_dwordx4 v[64:67], v[64:65], off offset:256
	v_pk_add_f32 v[60:61], v[60:61], 0 op_sel_hi:[1,0]
	v_pk_add_f32 v[62:63], v[62:63], 0 op_sel_hi:[1,0]
	v_pk_add_f32 v[56:57], v[56:57], 0 op_sel_hi:[1,0]
	v_pk_add_f32 v[58:59], v[58:59], 0 op_sel_hi:[1,0]
	v_pk_add_f32 v[52:53], v[52:53], 0 op_sel_hi:[1,0]
	v_pk_add_f32 v[54:55], v[54:55], 0 op_sel_hi:[1,0]
	v_pk_add_f32 v[48:49], v[48:49], 0 op_sel_hi:[1,0]
	v_pk_add_f32 v[50:51], v[50:51], 0 op_sel_hi:[1,0]
	s_waitcnt vmcnt(7)
	v_lshlrev_b32_e32 v106, 16, v100
	v_and_b32_e32 v100, 0xffff0000, v100
	v_add_f32_e32 v61, v61, v100
	v_lshlrev_b32_e32 v100, 16, v101
	v_add_f32_e32 v62, v62, v100
	v_and_b32_e32 v100, 0xffff0000, v101
	v_add_f32_e32 v63, v63, v100
	v_lshlrev_b32_e32 v100, 16, v102
	v_add_f32_e32 v56, v56, v100
	v_and_b32_e32 v100, 0xffff0000, v102
	v_add_f32_e32 v57, v57, v100
	v_lshlrev_b32_e32 v100, 16, v103
	v_add_f32_e32 v100, v58, v100
	v_and_b32_e32 v58, 0xffff0000, v103
	v_add_f32_e32 v60, v60, v106
	v_add_f32_e32 v101, v59, v58
	v_mul_f32_e32 v58, v61, v61
	v_mul_f32_e32 v59, v63, v63
	v_fmac_f32_e32 v58, v60, v60
	v_fmac_f32_e32 v59, v62, v62
	v_add_f32_e32 v58, v58, v59
	v_mul_f32_e32 v59, v57, v57
	v_fmac_f32_e32 v59, v56, v56
	v_add_f32_e32 v58, v59, v58
	v_mul_f32_e32 v59, v101, v101
	v_fmac_f32_e32 v59, v100, v100
	v_add_f32_e32 v102, v59, v58
	v_cvt_pk_bf16_f32 v58, v60, v61
	v_cvt_pk_bf16_f32 v59, v62, v63
	v_cvt_pk_bf16_f32 v60, v56, v57
	v_lshl_add_u64 v[56:57], s[8:9], 0, v[104:105]
	v_lshl_add_u64 v[56:57], v[152:153], 1, v[56:57]
	v_cvt_pk_bf16_f32 v61, v100, v101
	global_store_dwordx4 v[56:57], v[58:61], off sc1
	s_waitcnt vmcnt(7)
	s_nop 0
	v_lshlrev_b32_e32 v58, 16, v88
	v_add_f32_e32 v52, v52, v58
	v_and_b32_e32 v58, 0xffff0000, v88
	v_add_f32_e32 v53, v53, v58
	v_lshlrev_b32_e32 v58, 16, v89
	v_add_f32_e32 v54, v54, v58
	v_and_b32_e32 v58, 0xffff0000, v89
	v_add_f32_e32 v55, v55, v58
	v_lshlrev_b32_e32 v58, 16, v90
	v_add_f32_e32 v58, v48, v58
	v_and_b32_e32 v48, 0xffff0000, v90
	v_add_f32_e32 v59, v49, v48
	v_lshlrev_b32_e32 v48, 16, v91
	v_add_f32_e32 v60, v50, v48
	v_and_b32_e32 v48, 0xffff0000, v91
	v_add_f32_e32 v51, v51, v48
	v_mul_f32_e32 v48, v53, v53
	v_mul_f32_e32 v49, v55, v55
	v_fmac_f32_e32 v48, v52, v52
	v_fmac_f32_e32 v49, v54, v54
	v_add_f32_e32 v48, v48, v49
	v_mul_f32_e32 v49, v59, v59
	v_fmac_f32_e32 v49, v58, v58
	v_add_f32_e32 v48, v49, v48
	v_mul_f32_e32 v49, v51, v51
	v_fmac_f32_e32 v49, v60, v60
	v_add_f32_e32 v48, v49, v48
	v_add_f32_e32 v61, v102, v48
	v_cvt_pk_bf16_f32 v48, v52, v53
	v_cvt_pk_bf16_f32 v49, v54, v55
	v_cvt_pk_bf16_f32 v50, v58, v59
	v_cvt_pk_bf16_f32 v51, v60, v51
	global_store_dwordx4 v[56:57], v[48:51], off offset:256 sc1
	ds_bpermute_b32 v48, v170, v61
	s_waitcnt lgkmcnt(0)
	v_add_f32_e32 v48, v61, v48
	ds_bpermute_b32 v49, v171, v48
	s_and_saveexec_b64 s[18:19], s[44:45]
	s_cbranch_execz .LBB0_2440
; __device__ __forceinline__ unsigned cvt_pk_bf16(float lo, float hi) { unsigned r; asm volatile("v_cvt_pk_bf16_f32 %0, %1, %2" : "=v"(r) : "v"(lo), "v"(hi)); return r; }
;     __device__ __forceinline__ void operator()(const f32x4 (&acc)[2][2][4][2], const Unit& u, int wr, int wc, int fr, int fq) const {
;     ...
;             for (int m = 0; m < 4; ++m) { const int row = row0 + ai * HALF + m * 16; float ss = 0.f;
; #pragma unroll
;                 for (int bj = 0; bj < 2; ++bj) { const u32x4 ow = old[m][bj];
;                     f32x4 v0 = (acc[ai][bj][m][0] + bv[bj][0]) * accs, v1 = (acc[ai][bj][m][1] + bv[bj][1]) * accs;
;                     v0[0] += __uint_as_float(ow.x << 16); v0[1] += __uint_as_float(ow.x & 0xffff0000u); v0[2] += __uint_as_float(ow.y << 16); v0[3] += __uint_as_float(ow.y & 0xffff0000u);
;                     v1[0] += __uint_as_float(ow.z << 16); v1[1] += __uint_as_float(ow.z & 0xffff0000u); v1[2] += __uint_as_float(ow.w << 16); v1[3] += __uint_as_float(ow.w & 0xffff0000u);
;                     ss += (v0[0] * v0[0] + v0[1] * v0[1]) + (v0[2] * v0[2] + v0[3] * v0[3]) + (v1[0] * v1[0] + v1[1] * v1[1]) + (v1[2] * v1[2] + v1[3] * v1[3]);
;                     u32x4 w; w.x = cvt_pk_bf16(v0[0], v0[1]); w.y = cvt_pk_bf16(v0[2], v0[3]); w.z = cvt_pk_bf16(v1[0], v1[1]); w.w = cvt_pk_bf16(v1[2], v1[3]);
;                     *(u32x4*)(HB + (size_t)row * ldc + col0 + bj * HALF) = w; }
;                 ss += __shfl_xor(ss, 16); ss += __shfl_xor(ss, 32);
;                 if (fq == 0) ssp[(size_t)row * 32] = ss; }
	v_lshlrev_b64 v[50:51], 7, v[98:99]
	v_lshl_add_u64 v[50:51], s[16:17], 0, v[50:51]
	s_waitcnt lgkmcnt(0)
	v_add_f32_e32 v48, v48, v49
	global_store_dword v[50:51], v48, off
.LBB0_2440:
	s_or_b64 exec, exec, s[18:19]
	v_pk_add_f32 v[44:45], v[44:45], 0 op_sel_hi:[1,0]
	s_waitcnt vmcnt(7)
	v_lshlrev_b32_e32 v50, 16, v84
	v_add_f32_e32 v44, v44, v50
	v_and_b32_e32 v50, 0xffff0000, v84
	v_pk_add_f32 v[46:47], v[46:47], 0 op_sel_hi:[1,0]
	v_add_f32_e32 v45, v45, v50
	v_lshlrev_b32_e32 v50, 16, v85
	v_add_f32_e32 v46, v46, v50
	v_and_b32_e32 v50, 0xffff0000, v85
	v_pk_add_f32 v[40:41], v[40:41], 0 op_sel_hi:[1,0]
	v_add_f32_e32 v47, v47, v50
	v_lshlrev_b32_e32 v50, 16, v86
	v_add_f32_e32 v50, v40, v50
	v_and_b32_e32 v40, 0xffff0000, v86
	v_pk_add_f32 v[42:43], v[42:43], 0 op_sel_hi:[1,0]
	v_add_f32_e32 v51, v41, v40
	v_lshlrev_b32_e32 v40, 16, v87
	v_add_f32_e32 v52, v42, v40
	v_and_b32_e32 v40, 0xffff0000, v87
	v_add_f32_e32 v43, v43, v40
	v_mul_f32_e32 v40, v45, v45
	v_mul_f32_e32 v41, v47, v47
	v_fmac_f32_e32 v40, v44, v44
	v_fmac_f32_e32 v41, v46, v46
	v_add_f32_e32 v40, v40, v41
	v_mul_f32_e32 v41, v51, v51
	v_fmac_f32_e32 v41, v50, v50
	v_add_f32_e32 v40, v41, v40
	v_mul_f32_e32 v41, v43, v43
	v_fmac_f32_e32 v41, v52, v52
	v_add_f32_e32 v53, v41, v40
	v_cvt_pk_bf16_f32 v40, v44, v45
	v_pk_add_f32 v[36:37], v[36:37], 0 op_sel_hi:[1,0]
	s_waitcnt vmcnt(6)
	v_lshlrev_b32_e32 v44, 16, v80
	v_add_f32_e32 v36, v36, v44
	v_and_b32_e32 v44, 0xffff0000, v80
	v_pk_add_f32 v[38:39], v[38:39], 0 op_sel_hi:[1,0]
	v_add_f32_e32 v37, v37, v44
	v_lshlrev_b32_e32 v44, 16, v81
	v_add_f32_e32 v44, v38, v44
	v_and_b32_e32 v38, 0xffff0000, v81
	v_pk_add_f32 v[32:33], v[32:33], 0 op_sel_hi:[1,0]
	v_add_f32_e32 v45, v39, v38
	v_lshlrev_b32_e32 v38, 16, v82
	v_cvt_pk_bf16_f32 v41, v46, v47
	v_add_f32_e32 v46, v32, v38
	v_and_b32_e32 v32, 0xffff0000, v82
	v_pk_add_f32 v[34:35], v[34:35], 0 op_sel_hi:[1,0]
	v_add_f32_e32 v47, v33, v32
	v_lshlrev_b32_e32 v32, 16, v83
	v_cvt_pk_bf16_f32 v42, v50, v51
	v_add_f32_e32 v50, v34, v32
	v_and_b32_e32 v32, 0xffff0000, v83
	v_add_f32_e32 v51, v35, v32
	v_mul_f32_e32 v32, v37, v37
	v_mul_f32_e32 v33, v45, v45
	v_fmac_f32_e32 v32, v36, v36
	v_fmac_f32_e32 v33, v44, v44
	v_add_f32_e32 v32, v32, v33
	v_mul_f32_e32 v33, v47, v47
	v_fmac_f32_e32 v33, v46, v46
	v_add_f32_e32 v32, v33, v32
	v_mul_f32_e32 v33, v51, v51
	v_fmac_f32_e32 v33, v50, v50
	v_add_f32_e32 v32, v33, v32
	v_add_f32_e32 v35, v53, v32
	v_cvt_pk_bf16_f32 v43, v52, v43
	ds_bpermute_b32 v52, v170, v35
	s_waitcnt lgkmcnt(1)
	v_lshlrev_b64 v[48:49], 11, v[96:97]
	v_lshl_add_u64 v[32:33], v[48:49], 1, s[8:9]
	v_lshl_add_u64 v[38:39], v[152:153], 1, v[32:33]
	global_store_dwordx4 v[38:39], v[40:43], off sc1
	s_waitcnt lgkmcnt(0)
	v_add_f32_e32 v32, v35, v52
	ds_bpermute_b32 v33, v171, v32
	v_cvt_pk_bf16_f32 v34, v36, v37
	v_cvt_pk_bf16_f32 v35, v44, v45
	v_cvt_pk_bf16_f32 v36, v46, v47
	v_cvt_pk_bf16_f32 v37, v50, v51
	global_store_dwordx4 v[38:39], v[34:37], off offset:256 sc1
	s_and_saveexec_b64 s[18:19], s[44:45]
	s_cbranch_execz .LBB0_2442
	v_lshlrev_b64 v[34:35], 7, v[96:97]
	v_lshl_add_u64 v[34:35], s[16:17], 0, v[34:35]
	s_waitcnt lgkmcnt(0)
	v_add_f32_e32 v32, v32, v33
	global_store_dword v[34:35], v32, off
; __device__ __forceinline__ unsigned cvt_pk_bf16(float lo, float hi) { unsigned r; asm volatile("v_cvt_pk_bf16_f32 %0, %1, %2" : "=v"(r) : "v"(lo), "v"(hi)); return r; }
;     __device__ __forceinline__ void operator()(const f32x4 (&acc)[2][2][4][2], const Unit& u, int wr, int wc, int fr, int fq) const {
;     ...
;             for (int m = 0; m < 4; ++m) { const int row = row0 + ai * HALF + m * 16; float ss = 0.f;
; #pragma unroll
;                 for (int bj = 0; bj < 2; ++bj) { const u32x4 ow = old[m][bj];
;                     f32x4 v0 = (acc[ai][bj][m][0] + bv[bj][0]) * accs, v1 = (acc[ai][bj][m][1] + bv[bj][1]) * accs;
;                     v0[0] += __uint_as_float(ow.x << 16); v0[1] += __uint_as_float(ow.x & 0xffff0000u); v0[2] += __uint_as_float(ow.y << 16); v0[3] += __uint_as_float(ow.y & 0xffff0000u);
;                     v1[0] += __uint_as_float(ow.z << 16); v1[1] += __uint_as_float(ow.z & 0xffff0000u); v1[2] += __uint_as_float(ow.w << 16); v1[3] += __uint_as_float(ow.w & 0xffff0000u);
;                     ss += (v0[0] * v0[0] + v0[1] * v0[1]) + (v0[2] * v0[2] + v0[3] * v0[3]) + (v1[0] * v1[0] + v1[1] * v1[1]) + (v1[2] * v1[2] + v1[3] * v1[3]);
;                     u32x4 w; w.x = cvt_pk_bf16(v0[0], v0[1]); w.y = cvt_pk_bf16(v0[2], v0[3]); w.z = cvt_pk_bf16(v1[0], v1[1]); w.w = cvt_pk_bf16(v1[2], v1[3]);
;                     *(u32x4*)(HB + (size_t)row * ldc + col0 + bj * HALF) = w; }
;                 ss += __shfl_xor(ss, 16); ss += __shfl_xor(ss, 32);
;                 if (fq == 0) ssp[(size_t)row * 32] = ss; }
.LBB0_2442:
	s_or_b64 exec, exec, s[18:19]
	v_pk_add_f32 v[28:29], v[28:29], 0 op_sel_hi:[1,0]
	s_waitcnt vmcnt(7)
	v_lshlrev_b32_e32 v34, 16, v76
	v_add_f32_e32 v28, v28, v34
	v_and_b32_e32 v34, 0xffff0000, v76
	v_pk_add_f32 v[30:31], v[30:31], 0 op_sel_hi:[1,0]
	v_add_f32_e32 v29, v29, v34
	v_lshlrev_b32_e32 v34, 16, v77
	v_add_f32_e32 v30, v30, v34
	v_and_b32_e32 v34, 0xffff0000, v77
	v_pk_add_f32 v[24:25], v[24:25], 0 op_sel_hi:[1,0]
	v_add_f32_e32 v31, v31, v34
	v_lshlrev_b32_e32 v34, 16, v78
	v_add_f32_e32 v34, v24, v34
	v_and_b32_e32 v24, 0xffff0000, v78
	v_pk_add_f32 v[26:27], v[26:27], 0 op_sel_hi:[1,0]
	v_add_f32_e32 v35, v25, v24
	v_lshlrev_b32_e32 v24, 16, v79
	v_add_f32_e32 v36, v26, v24
	v_and_b32_e32 v24, 0xffff0000, v79
	v_add_f32_e32 v27, v27, v24
	v_mul_f32_e32 v24, v29, v29
	v_mul_f32_e32 v25, v31, v31
	v_fmac_f32_e32 v24, v28, v28
	v_fmac_f32_e32 v25, v30, v30
	v_add_f32_e32 v24, v24, v25
	v_mul_f32_e32 v25, v35, v35
	v_fmac_f32_e32 v25, v34, v34
	v_add_f32_e32 v24, v25, v24
	v_mul_f32_e32 v25, v27, v27
	v_fmac_f32_e32 v25, v36, v36
	v_add_f32_e32 v37, v25, v24
	v_cvt_pk_bf16_f32 v24, v28, v29
	v_pk_add_f32 v[20:21], v[20:21], 0 op_sel_hi:[1,0]
	s_waitcnt vmcnt(6)
	v_lshlrev_b32_e32 v28, 16, v72
	v_add_f32_e32 v20, v20, v28
	v_and_b32_e32 v28, 0xffff0000, v72
	v_pk_add_f32 v[22:23], v[22:23], 0 op_sel_hi:[1,0]
	v_add_f32_e32 v21, v21, v28
	v_lshlrev_b32_e32 v28, 16, v73
	v_add_f32_e32 v28, v22, v28
	v_and_b32_e32 v22, 0xffff0000, v73
	v_pk_add_f32 v[16:17], v[16:17], 0 op_sel_hi:[1,0]
	v_add_f32_e32 v29, v23, v22
	v_lshlrev_b32_e32 v22, 16, v74
	v_cvt_pk_bf16_f32 v25, v30, v31
	v_add_f32_e32 v30, v16, v22
	v_and_b32_e32 v16, 0xffff0000, v74
	v_pk_add_f32 v[18:19], v[18:19], 0 op_sel_hi:[1,0]
	v_add_f32_e32 v31, v17, v16
	v_lshlrev_b32_e32 v16, 16, v75
	v_cvt_pk_bf16_f32 v26, v34, v35
	v_add_f32_e32 v34, v18, v16
	v_and_b32_e32 v16, 0xffff0000, v75
	v_add_f32_e32 v35, v19, v16
	v_mul_f32_e32 v16, v21, v21
	v_mul_f32_e32 v17, v29, v29
	v_fmac_f32_e32 v16, v20, v20
	v_fmac_f32_e32 v17, v28, v28
	v_add_f32_e32 v16, v16, v17
	v_mul_f32_e32 v17, v31, v31
	v_fmac_f32_e32 v17, v30, v30
	v_add_f32_e32 v16, v17, v16
	v_mul_f32_e32 v17, v35, v35
	v_fmac_f32_e32 v17, v34, v34
	v_add_f32_e32 v16, v17, v16
	v_add_f32_e32 v19, v37, v16
	v_cvt_pk_bf16_f32 v27, v36, v27
	ds_bpermute_b32 v36, v170, v19
	s_waitcnt lgkmcnt(1)
	v_lshlrev_b64 v[32:33], 11, v[94:95]
	v_lshl_add_u64 v[16:17], v[32:33], 1, s[8:9]
	v_lshl_add_u64 v[22:23], v[152:153], 1, v[16:17]
	global_store_dwordx4 v[22:23], v[24:27], off sc1
	s_waitcnt lgkmcnt(0)
	v_add_f32_e32 v16, v19, v36
	ds_bpermute_b32 v17, v171, v16
	v_cvt_pk_bf16_f32 v18, v20, v21
	v_cvt_pk_bf16_f32 v19, v28, v29
	v_cvt_pk_bf16_f32 v20, v30, v31
	v_cvt_pk_bf16_f32 v21, v34, v35
	global_store_dwordx4 v[22:23], v[18:21], off offset:256 sc1
	s_and_saveexec_b64 s[18:19], s[44:45]
	s_cbranch_execz .LBB0_2444
	v_lshlrev_b64 v[18:19], 7, v[94:95]
	v_lshl_add_u64 v[18:19], s[16:17], 0, v[18:19]
	s_waitcnt lgkmcnt(0)
	v_add_f32_e32 v16, v16, v17
	global_store_dword v[18:19], v16, off
.LBB0_2444:
	s_or_b64 exec, exec, s[18:19]
	v_pk_add_f32 v[12:13], v[12:13], 0 op_sel_hi:[1,0]
	s_waitcnt vmcnt(7)
	v_lshlrev_b32_e32 v18, 16, v68
	v_add_f32_e32 v12, v12, v18
	v_and_b32_e32 v18, 0xffff0000, v68
	v_pk_add_f32 v[14:15], v[14:15], 0 op_sel_hi:[1,0]
	v_add_f32_e32 v13, v13, v18
	v_lshlrev_b32_e32 v18, 16, v69
	v_add_f32_e32 v14, v14, v18
	v_and_b32_e32 v18, 0xffff0000, v69
	v_pk_add_f32 v[8:9], v[8:9], 0 op_sel_hi:[1,0]
	v_add_f32_e32 v15, v15, v18
	v_lshlrev_b32_e32 v18, 16, v70
	v_add_f32_e32 v18, v8, v18
	v_and_b32_e32 v8, 0xffff0000, v70
	v_pk_add_f32 v[10:11], v[10:11], 0 op_sel_hi:[1,0]
	v_add_f32_e32 v19, v9, v8
	v_lshlrev_b32_e32 v8, 16, v71
	v_add_f32_e32 v20, v10, v8
	v_and_b32_e32 v8, 0xffff0000, v71
	v_add_f32_e32 v11, v11, v8
	v_mul_f32_e32 v8, v13, v13
	v_mul_f32_e32 v9, v15, v15
	v_fmac_f32_e32 v8, v12, v12
	v_fmac_f32_e32 v9, v14, v14
	v_add_f32_e32 v8, v8, v9
	v_mul_f32_e32 v9, v19, v19
	v_fmac_f32_e32 v9, v18, v18
	v_add_f32_e32 v8, v9, v8
	v_mul_f32_e32 v9, v11, v11
	v_fmac_f32_e32 v9, v20, v20
	v_add_f32_e32 v21, v9, v8
	v_cvt_pk_bf16_f32 v8, v12, v13
	v_pk_add_f32 v[4:5], v[4:5], 0 op_sel_hi:[1,0]
	s_waitcnt vmcnt(6)
	v_lshlrev_b32_e32 v12, 16, v64
	v_add_f32_e32 v4, v4, v12
	v_and_b32_e32 v12, 0xffff0000, v64
	v_pk_add_f32 v[6:7], v[6:7], 0 op_sel_hi:[1,0]
	v_add_f32_e32 v5, v5, v12
	v_lshlrev_b32_e32 v12, 16, v65
	v_add_f32_e32 v12, v6, v12
	v_and_b32_e32 v6, 0xffff0000, v65
	v_pk_add_f32 v[0:1], v[0:1], 0 op_sel_hi:[1,0]
	v_add_f32_e32 v13, v7, v6
	v_lshlrev_b32_e32 v6, 16, v66
	v_cvt_pk_bf16_f32 v9, v14, v15
	v_add_f32_e32 v14, v0, v6
	v_and_b32_e32 v0, 0xffff0000, v66
	v_pk_add_f32 v[2:3], v[2:3], 0 op_sel_hi:[1,0]
	v_add_f32_e32 v15, v1, v0
	v_lshlrev_b32_e32 v0, 16, v67
	v_cvt_pk_bf16_f32 v10, v18, v19
	v_add_f32_e32 v18, v2, v0
	v_and_b32_e32 v0, 0xffff0000, v67
	v_add_f32_e32 v19, v3, v0
	v_mul_f32_e32 v0, v5, v5
	v_mul_f32_e32 v1, v13, v13
	v_fmac_f32_e32 v0, v4, v4
	v_fmac_f32_e32 v1, v12, v12
	v_add_f32_e32 v0, v0, v1
	v_mul_f32_e32 v1, v15, v15
	v_fmac_f32_e32 v1, v14, v14
	v_add_f32_e32 v0, v1, v0
	v_mul_f32_e32 v1, v19, v19
	v_fmac_f32_e32 v1, v18, v18
	v_add_f32_e32 v0, v1, v0
	v_add_f32_e32 v3, v21, v0
	v_cvt_pk_bf16_f32 v11, v20, v11
	ds_bpermute_b32 v20, v170, v3
	s_waitcnt lgkmcnt(1)
	v_lshlrev_b64 v[16:17], 11, v[92:93]
	v_lshl_add_u64 v[0:1], v[16:17], 1, s[8:9]
	v_lshl_add_u64 v[6:7], v[152:153], 1, v[0:1]
	global_store_dwordx4 v[6:7], v[8:11], off sc1
	s_waitcnt lgkmcnt(0)
	v_add_f32_e32 v0, v3, v20
	ds_bpermute_b32 v1, v171, v0
	v_cvt_pk_bf16_f32 v2, v4, v5
	v_cvt_pk_bf16_f32 v3, v12, v13
	v_cvt_pk_bf16_f32 v4, v14, v15
	v_cvt_pk_bf16_f32 v5, v18, v19
	global_store_dwordx4 v[6:7], v[2:5], off offset:256 sc1
	s_and_saveexec_b64 s[18:19], s[44:45]
	s_cbranch_execz .LBB0_2446
	v_lshlrev_b64 v[2:3], 7, v[92:93]
	v_lshl_add_u64 v[2:3], s[16:17], 0, v[2:3]
	s_waitcnt lgkmcnt(0)
	v_add_f32_e32 v0, v0, v1
	global_store_dword v[2:3], v0, off

; __device__ __forceinline__ unsigned cvt_pk_bf16(float lo, float hi) { unsigned r; asm volatile("v_cvt_pk_bf16_f32 %0, %1, %2" : "=v"(r) : "v"(lo), "v"(hi)); return r; }
; __device__ __forceinline__ float row_ss(const float* part, int row, int fq, int nf4) {
;     const f32x4* p = (const f32x4*)(part + (size_t)row * 32);
;     float s = 0.f;
; #pragma unroll
;     for (int j = 0; j < 2; ++j) { const int idx = fq + 4 * j; if (idx < nf4) { const f32x4 v = p[idx]; s += (v[0] + v[1]) + (v[2] + v[3]); } }
;     s += __shfl_xor(s, 16); s += __shfl_xor(s, 32);
;     return s;
;     __device__ __forceinline__ void operator()(const f32x4 (&acc)[2][2][4][2], const Unit& u, int wr, int wc, int fr, int fq) const {
;         const int row0 = u.pm * BM + wr * 64 + fr; int colt = u.pn * BM; bf16_t* base = O;
;         float sc = 1.f; if (split_cols) { const int t = colt / split_cols; base += (size_t)t * split_stride; colt -= t * split_cols; if (t == 0) sc = scale0; } else sc = scale0;
;         const int col0 = colt + wc * 32 + 8 * fq, bcol0 = u.pn * BM + wc * 32 + 8 * fq;
;         f32x4 bv[2][2];
; #pragma unroll
;         for (int bj = 0; bj < 2; ++bj)
; #pragma unroll
;             for (int n = 0; n < 2; ++n) bv[bj][n] = bias ? *(const f32x4*)(bias + bcol0 + bj * HALF + 4 * n) : (f32x4){0.f, 0.f, 0.f, 0.f};
; #pragma unroll
;         for (int ai = 0; ai < 2; ++ai)
; #pragma unroll
;             for (int m = 0; m < 4; ++m) { const int row = row0 + ai * HALF + m * 16; bf16_t* rowp = base + (size_t)row * ldc + col0;
;                 const float rs = rss ? __builtin_amdgcn_rsqf(row_ss(rss, row, fq, nf4) * rinv + 1e-6f) : 1.f;
; #pragma unroll
;                 for (int bj = 0; bj < 2; ++bj) { f32x4 v0 = acc[ai][bj][m][0] * rs + bv[bj][0], v1 = acc[ai][bj][m][1] * rs + bv[bj][1];
;                     v0 = v0 * sc; v1 = v1 * sc; u32x4 w; w.x = cvt_pk_bf16(v0[0], v0[1]); w.y = cvt_pk_bf16(v0[2], v0[3]); w.z = cvt_pk_bf16(v1[0], v1[1]); w.w = cvt_pk_bf16(v1[2], v1[3]);
;                     *(u32x4*)(rowp + bj * HALF) = w; } }
.LBB0_2514:
	s_ashr_i32 s2, s1, 31
	s_lshr_b32 s2, s2, 29
	s_add_i32 s2, s1, s2
	s_ashr_i32 s6, s2, 3
	v_lshl_add_u32 v150, s0, 8, v147
	s_lshl_b32 s0, s1, 8
	s_mul_i32 s2, s6, 0x3000000
	s_mul_hi_i32 s3, s6, 0x3000000
	s_add_u32 s2, s47, s2
	s_addc_u32 s3, s48, s3
	s_lshl_b32 s6, s6, 11
	s_sub_i32 s0, s0, s6
	v_or_b32_e32 v148, s0, v153
	v_ashrrev_i32_e32 v149, 31, v148
	v_ashrrev_i32_e32 v151, 31, v150
	v_lshl_add_u64 v[148:149], v[148:149], 1, s[2:3]
	v_lshlrev_b64 v[160:161], 12, v[150:151]
	v_lshl_add_u64 v[168:169], v[148:149], 0, v[160:161]
	v_lshlrev_b64 v[160:161], 7, v[150:151]
	v_lshl_add_u64 v[164:165], v[136:137], 0, v[160:161]
	global_load_dwordx4 v[160:163], v[164:165], off
	s_nop 0
	global_load_dwordx4 v[164:167], v[164:165], off offset:64
	s_add_i32 s1, s1, 7
	s_cmp_lt_u32 s1, 15
	s_cselect_b64 vcc, -1, 0
	v_cndmask_b32_e32 v146, 1.0, v158, vcc
	v_readlane_b32 s38, v245, 6
	v_readlane_b32 s40, v245, 8
	s_mov_b64 s[0:1], -1
	v_readlane_b32 s39, v245, 7
	v_readlane_b32 s41, v245, 9
	s_waitcnt vmcnt(0)
	v_mov_b32_e32 v170, v160
	v_mov_b32_e32 v171, v164
	v_mov_b32_e32 v164, v161
	v_pk_add_f32 v[160:161], v[170:171], v[164:165]
	v_mov_b32_e32 v164, v162
	v_mov_b32_e32 v165, v166
	v_mov_b32_e32 v166, v163
	v_pk_add_f32 v[162:163], v[164:165], v[166:167]
	s_nop 0
	v_pk_add_f32 v[160:161], v[160:161], v[162:163]
	s_nop 0
	v_add_f32_e32 v151, 0, v160
	v_and_b32_e32 v160, 64, v202
	v_add_f32_e32 v159, v151, v161
	v_xor_b32_e32 v151, 16, v202
	v_add_u32_e32 v160, 64, v160
	v_cmp_lt_i32_e32 vcc, v151, v160
	s_nop 1
	v_cndmask_b32_e32 v151, v202, v151, vcc
	v_lshlrev_b32_e32 v151, 2, v151
	ds_bpermute_b32 v161, v151, v159
	s_waitcnt lgkmcnt(0)
	v_add_f32_e32 v161, v159, v161
	v_xor_b32_e32 v159, 32, v202
	v_cmp_lt_i32_e32 vcc, v159, v160
	s_nop 1
	v_cndmask_b32_e32 v159, v202, v159, vcc
	v_lshlrev_b32_e32 v159, 2, v159
	ds_bpermute_b32 v160, v159, v161
	s_andn2_b64 vcc, exec, s[44:45]
	s_waitcnt lgkmcnt(0)
	v_add_f32_e32 v160, v161, v160
	v_fmamk_f32 v160, v160, 0x3a000000, v157
	v_rsq_f32_e32 v160, v160
	s_nop 0
	v_pk_fma_f32 v[124:125], v[124:125], v[160:161], 0 op_sel_hi:[1,0,0]
	v_pk_fma_f32 v[126:127], v[126:127], v[160:161], 0 op_sel_hi:[1,0,0]
	v_pk_fma_f32 v[120:121], v[120:121], v[160:161], 0 op_sel_hi:[1,0,0]
	v_pk_fma_f32 v[122:123], v[122:123], v[160:161], 0 op_sel_hi:[1,0,0]
	v_pk_mul_f32 v[126:127], v[146:147], v[126:127] op_sel_hi:[0,1]
	v_pk_mul_f32 v[124:125], v[146:147], v[124:125] op_sel_hi:[0,1]
	v_pk_mul_f32 v[162:163], v[146:147], v[122:123] op_sel_hi:[0,1]
	v_pk_mul_f32 v[122:123], v[146:147], v[120:121] op_sel_hi:[0,1]
	v_cvt_pk_bf16_f32 v120, v124, v125
	v_cvt_pk_bf16_f32 v121, v126, v127
	v_pk_fma_f32 v[116:117], v[116:117], v[160:161], 0 op_sel_hi:[1,0,0]
	v_pk_fma_f32 v[112:113], v[112:113], v[160:161], 0 op_sel_hi:[1,0,0]
	v_pk_fma_f32 v[114:115], v[114:115], v[160:161], 0 op_sel_hi:[1,0,0]
	v_cvt_pk_bf16_f32 v122, v122, v123
	v_cvt_pk_bf16_f32 v123, v162, v163
	global_store_dwordx4 v[168:169], v[120:123], off sc1
	v_pk_fma_f32 v[118:119], v[118:119], v[160:161], 0 op_sel_hi:[1,0,0]
	v_pk_mul_f32 v[116:117], v[146:147], v[116:117] op_sel_hi:[0,1]
	v_pk_mul_f32 v[120:121], v[146:147], v[114:115] op_sel_hi:[0,1]
	v_pk_mul_f32 v[114:115], v[146:147], v[112:113] op_sel_hi:[0,1]
	v_cvt_pk_bf16_f32 v112, v116, v117
	v_pk_mul_f32 v[118:119], v[146:147], v[118:119] op_sel_hi:[0,1]
	v_cvt_pk_bf16_f32 v113, v118, v119
	v_cvt_pk_bf16_f32 v114, v114, v115
	v_cvt_pk_bf16_f32 v115, v120, v121
	global_store_dwordx4 v[168:169], v[112:115], off offset:256 sc1
	s_nop 1
	v_or_b32_e32 v112, 16, v150
	v_ashrrev_i32_e32 v113, 31, v112
	v_lshlrev_b64 v[114:115], 12, v[112:113]
	v_lshlrev_b64 v[112:113], 7, v[112:113]
	v_lshl_add_u64 v[116:117], v[136:137], 0, v[112:113]
	v_lshl_add_u64 v[120:121], v[148:149], 0, v[114:115]
	global_load_dwordx4 v[112:115], v[116:117], off
	s_nop 0
	global_load_dwordx4 v[116:119], v[116:117], off offset:64
	s_waitcnt vmcnt(1)
	v_mov_b32_e32 v122, v112
	s_waitcnt vmcnt(0)
	v_mov_b32_e32 v123, v116
	v_mov_b32_e32 v116, v113
	v_pk_add_f32 v[112:113], v[122:123], v[116:117]
	v_mov_b32_e32 v116, v114
	v_mov_b32_e32 v117, v118
	v_mov_b32_e32 v118, v115
	v_pk_add_f32 v[114:115], v[116:117], v[118:119]
	s_nop 0
	v_pk_add_f32 v[112:113], v[112:113], v[114:115]
	s_nop 0
	v_add_f32_e32 v112, 0, v112
	v_add_f32_e32 v112, v112, v113
	ds_bpermute_b32 v113, v151, v112
	s_waitcnt lgkmcnt(0)
	v_add_f32_e32 v112, v112, v113
	ds_bpermute_b32 v113, v159, v112
	s_waitcnt lgkmcnt(0)
	v_add_f32_e32 v112, v112, v113
	v_fmamk_f32 v112, v112, 0x3a000000, v157
	v_rsq_f32_e32 v112, v112
	s_nop 0
	v_pk_fma_f32 v[108:109], v[108:109], v[112:113], 0 op_sel_hi:[1,0,0]
	v_pk_fma_f32 v[110:111], v[110:111], v[112:113], 0 op_sel_hi:[1,0,0]
	v_pk_fma_f32 v[104:105], v[104:105], v[112:113], 0 op_sel_hi:[1,0,0]
	v_pk_fma_f32 v[106:107], v[106:107], v[112:113], 0 op_sel_hi:[1,0,0]
	v_pk_mul_f32 v[110:111], v[146:147], v[110:111] op_sel_hi:[0,1]
	v_pk_mul_f32 v[108:109], v[146:147], v[108:109] op_sel_hi:[0,1]
	v_pk_mul_f32 v[114:115], v[146:147], v[106:107] op_sel_hi:[0,1]
	v_pk_mul_f32 v[106:107], v[146:147], v[104:105] op_sel_hi:[0,1]
	v_cvt_pk_bf16_f32 v104, v108, v109
	v_cvt_pk_bf16_f32 v105, v110, v111
	v_pk_fma_f32 v[100:101], v[100:101], v[112:113], 0 op_sel_hi:[1,0,0]
	v_pk_fma_f32 v[96:97], v[96:97], v[112:113], 0 op_sel_hi:[1,0,0]
	v_pk_fma_f32 v[98:99], v[98:99], v[112:113], 0 op_sel_hi:[1,0,0]
	v_cvt_pk_bf16_f32 v106, v106, v107
	v_cvt_pk_bf16_f32 v107, v114, v115
	global_store_dwordx4 v[120:121], v[104:107], off sc1
	v_pk_fma_f32 v[102:103], v[102:103], v[112:113], 0 op_sel_hi:[1,0,0]
	v_pk_mul_f32 v[100:101], v[146:147], v[100:101] op_sel_hi:[0,1]
	v_pk_mul_f32 v[104:105], v[146:147], v[98:99] op_sel_hi:[0,1]
	v_pk_mul_f32 v[98:99], v[146:147], v[96:97] op_sel_hi:[0,1]
	v_cvt_pk_bf16_f32 v96, v100, v101
	v_pk_mul_f32 v[102:103], v[146:147], v[102:103] op_sel_hi:[0,1]
	v_cvt_pk_bf16_f32 v97, v102, v103
	v_cvt_pk_bf16_f32 v98, v98, v99
	v_cvt_pk_bf16_f32 v99, v104, v105
	global_store_dwordx4 v[120:121], v[96:99], off offset:256 sc1
	s_nop 1
	v_or_b32_e32 v96, 32, v150
	v_ashrrev_i32_e32 v97, 31, v96
	v_lshlrev_b64 v[98:99], 12, v[96:97]
	v_lshlrev_b64 v[96:97], 7, v[96:97]
	v_lshl_add_u64 v[100:101], v[136:137], 0, v[96:97]
	v_lshl_add_u64 v[104:105], v[148:149], 0, v[98:99]
	global_load_dwordx4 v[96:99], v[100:101], off
	s_nop 0
	global_load_dwordx4 v[100:103], v[100:101], off offset:64
	s_waitcnt vmcnt(1)
; __device__ __forceinline__ unsigned cvt_pk_bf16(float lo, float hi) { unsigned r; asm volatile("v_cvt_pk_bf16_f32 %0, %1, %2" : "=v"(r) : "v"(lo), "v"(hi)); return r; }
; __device__ __forceinline__ float row_ss(const float* part, int row, int fq, int nf4) {
;     const f32x4* p = (const f32x4*)(part + (size_t)row * 32);
;     float s = 0.f;
; #pragma unroll
;     for (int j = 0; j < 2; ++j) { const int idx = fq + 4 * j; if (idx < nf4) { const f32x4 v = p[idx]; s += (v[0] + v[1]) + (v[2] + v[3]); } }
;     s += __shfl_xor(s, 16); s += __shfl_xor(s, 32);
;     return s;
;     __device__ __forceinline__ void operator()(const f32x4 (&acc)[2][2][4][2], const Unit& u, int wr, int wc, int fr, int fq) const {
;     ...
;             for (int m = 0; m < 4; ++m) { const int row = row0 + ai * HALF + m * 16; bf16_t* rowp = base + (size_t)row * ldc + col0;
;                 const float rs = rss ? __builtin_amdgcn_rsqf(row_ss(rss, row, fq, nf4) * rinv + 1e-6f) : 1.f;
; #pragma unroll
;                 for (int bj = 0; bj < 2; ++bj) { f32x4 v0 = acc[ai][bj][m][0] * rs + bv[bj][0], v1 = acc[ai][bj][m][1] * rs + bv[bj][1];
;                     v0 = v0 * sc; v1 = v1 * sc; u32x4 w; w.x = cvt_pk_bf16(v0[0], v0[1]); w.y = cvt_pk_bf16(v0[2], v0[3]); w.z = cvt_pk_bf16(v1[0], v1[1]); w.w = cvt_pk_bf16(v1[2], v1[3]);
;                     *(u32x4*)(rowp + bj * HALF) = w; } }
	v_mov_b32_e32 v106, v96
	s_waitcnt vmcnt(0)
	v_mov_b32_e32 v107, v100
	v_mov_b32_e32 v100, v97
	v_pk_add_f32 v[96:97], v[106:107], v[100:101]
	v_mov_b32_e32 v100, v98
	v_mov_b32_e32 v101, v102
	v_mov_b32_e32 v102, v99
	v_pk_add_f32 v[98:99], v[100:101], v[102:103]
	s_nop 0
	v_pk_add_f32 v[96:97], v[96:97], v[98:99]
	s_nop 0
	v_add_f32_e32 v96, 0, v96
	v_add_f32_e32 v96, v96, v97
	ds_bpermute_b32 v97, v151, v96
	s_waitcnt lgkmcnt(0)
	v_add_f32_e32 v96, v96, v97
	ds_bpermute_b32 v97, v159, v96
	s_waitcnt lgkmcnt(0)
	v_add_f32_e32 v96, v96, v97
	v_fmamk_f32 v96, v96, 0x3a000000, v157
	v_rsq_f32_e32 v96, v96
	s_nop 0
	v_pk_fma_f32 v[92:93], v[92:93], v[96:97], 0 op_sel_hi:[1,0,0]
	v_pk_fma_f32 v[94:95], v[94:95], v[96:97], 0 op_sel_hi:[1,0,0]
	v_pk_fma_f32 v[88:89], v[88:89], v[96:97], 0 op_sel_hi:[1,0,0]
	v_pk_fma_f32 v[90:91], v[90:91], v[96:97], 0 op_sel_hi:[1,0,0]
	v_pk_mul_f32 v[94:95], v[146:147], v[94:95] op_sel_hi:[0,1]
	v_pk_mul_f32 v[92:93], v[146:147], v[92:93] op_sel_hi:[0,1]
	v_pk_mul_f32 v[98:99], v[146:147], v[90:91] op_sel_hi:[0,1]
	v_pk_mul_f32 v[90:91], v[146:147], v[88:89] op_sel_hi:[0,1]
	v_cvt_pk_bf16_f32 v88, v92, v93
	v_cvt_pk_bf16_f32 v89, v94, v95
	v_pk_fma_f32 v[84:85], v[84:85], v[96:97], 0 op_sel_hi:[1,0,0]
	v_pk_fma_f32 v[80:81], v[80:81], v[96:97], 0 op_sel_hi:[1,0,0]
	v_pk_fma_f32 v[82:83], v[82:83], v[96:97], 0 op_sel_hi:[1,0,0]
	v_cvt_pk_bf16_f32 v90, v90, v91
	v_cvt_pk_bf16_f32 v91, v98, v99
	global_store_dwordx4 v[104:105], v[88:91], off sc1
	v_pk_fma_f32 v[86:87], v[86:87], v[96:97], 0 op_sel_hi:[1,0,0]
	v_pk_mul_f32 v[84:85], v[146:147], v[84:85] op_sel_hi:[0,1]
	v_pk_mul_f32 v[88:89], v[146:147], v[82:83] op_sel_hi:[0,1]
	v_pk_mul_f32 v[82:83], v[146:147], v[80:81] op_sel_hi:[0,1]
	v_cvt_pk_bf16_f32 v80, v84, v85
	v_pk_mul_f32 v[86:87], v[146:147], v[86:87] op_sel_hi:[0,1]
	v_cvt_pk_bf16_f32 v81, v86, v87
	v_cvt_pk_bf16_f32 v82, v82, v83
	v_cvt_pk_bf16_f32 v83, v88, v89
	global_store_dwordx4 v[104:105], v[80:83], off offset:256 sc1
	s_nop 1
	v_or_b32_e32 v80, 48, v150
	v_ashrrev_i32_e32 v81, 31, v80
	v_lshlrev_b64 v[82:83], 12, v[80:81]
	v_lshlrev_b64 v[80:81], 7, v[80:81]
	v_lshl_add_u64 v[84:85], v[136:137], 0, v[80:81]
	v_lshl_add_u64 v[88:89], v[148:149], 0, v[82:83]
	global_load_dwordx4 v[80:83], v[84:85], off
	s_nop 0
	global_load_dwordx4 v[84:87], v[84:85], off offset:64
	s_waitcnt vmcnt(1)
	v_mov_b32_e32 v90, v80
	s_waitcnt vmcnt(0)
	v_mov_b32_e32 v91, v84
	v_mov_b32_e32 v84, v81
	v_pk_add_f32 v[80:81], v[90:91], v[84:85]
	v_mov_b32_e32 v84, v82
	v_mov_b32_e32 v85, v86
	v_mov_b32_e32 v86, v83
	v_pk_add_f32 v[82:83], v[84:85], v[86:87]
	s_nop 0
	v_pk_add_f32 v[80:81], v[80:81], v[82:83]
	s_nop 0
	v_add_f32_e32 v80, 0, v80
	v_add_f32_e32 v80, v80, v81
	ds_bpermute_b32 v81, v151, v80
	s_waitcnt lgkmcnt(0)
	v_add_f32_e32 v80, v80, v81
	ds_bpermute_b32 v81, v159, v80
	s_waitcnt lgkmcnt(0)
	v_add_f32_e32 v80, v80, v81
	v_fmamk_f32 v80, v80, 0x3a000000, v157
	v_rsq_f32_e32 v80, v80
	s_nop 0
	v_pk_fma_f32 v[76:77], v[76:77], v[80:81], 0 op_sel_hi:[1,0,0]
	v_pk_fma_f32 v[78:79], v[78:79], v[80:81], 0 op_sel_hi:[1,0,0]
	v_pk_fma_f32 v[72:73], v[72:73], v[80:81], 0 op_sel_hi:[1,0,0]
	v_pk_fma_f32 v[74:75], v[74:75], v[80:81], 0 op_sel_hi:[1,0,0]
	v_pk_mul_f32 v[78:79], v[146:147], v[78:79] op_sel_hi:[0,1]
	v_pk_mul_f32 v[76:77], v[146:147], v[76:77] op_sel_hi:[0,1]
	v_pk_mul_f32 v[82:83], v[146:147], v[74:75] op_sel_hi:[0,1]
	v_pk_mul_f32 v[74:75], v[146:147], v[72:73] op_sel_hi:[0,1]
	v_cvt_pk_bf16_f32 v72, v76, v77
	v_cvt_pk_bf16_f32 v73, v78, v79
	v_pk_fma_f32 v[68:69], v[68:69], v[80:81], 0 op_sel_hi:[1,0,0]
	v_pk_fma_f32 v[64:65], v[64:65], v[80:81], 0 op_sel_hi:[1,0,0]
	v_pk_fma_f32 v[66:67], v[66:67], v[80:81], 0 op_sel_hi:[1,0,0]
	v_cvt_pk_bf16_f32 v74, v74, v75
	v_cvt_pk_bf16_f32 v75, v82, v83
	global_store_dwordx4 v[88:89], v[72:75], off sc1
	v_pk_fma_f32 v[70:71], v[70:71], v[80:81], 0 op_sel_hi:[1,0,0]
	v_pk_mul_f32 v[68:69], v[146:147], v[68:69] op_sel_hi:[0,1]
	v_pk_mul_f32 v[72:73], v[146:147], v[66:67] op_sel_hi:[0,1]
	v_pk_mul_f32 v[66:67], v[146:147], v[64:65] op_sel_hi:[0,1]
	v_cvt_pk_bf16_f32 v64, v68, v69
	v_pk_mul_f32 v[70:71], v[146:147], v[70:71] op_sel_hi:[0,1]
	v_cvt_pk_bf16_f32 v65, v70, v71
	v_cvt_pk_bf16_f32 v66, v66, v67
	v_cvt_pk_bf16_f32 v67, v72, v73
	global_store_dwordx4 v[88:89], v[64:67], off offset:256 sc1
	s_nop 1
	v_add_u32_e32 v64, 0x80, v150
	v_ashrrev_i32_e32 v65, 31, v64
	v_lshlrev_b64 v[66:67], 12, v[64:65]
	v_lshlrev_b64 v[64:65], 7, v[64:65]
	v_lshl_add_u64 v[68:69], v[136:137], 0, v[64:65]
	v_lshl_add_u64 v[72:73], v[148:149], 0, v[66:67]
	global_load_dwordx4 v[64:67], v[68:69], off
	s_nop 0
	global_load_dwordx4 v[68:71], v[68:69], off offset:64
	s_waitcnt vmcnt(1)
	v_mov_b32_e32 v74, v64
	s_waitcnt vmcnt(0)
	v_mov_b32_e32 v75, v68
	v_mov_b32_e32 v68, v65
	v_pk_add_f32 v[64:65], v[74:75], v[68:69]
	v_mov_b32_e32 v68, v66
	v_mov_b32_e32 v69, v70
	v_mov_b32_e32 v70, v67
	v_pk_add_f32 v[66:67], v[68:69], v[70:71]
	s_nop 0
	v_pk_add_f32 v[64:65], v[64:65], v[66:67]
	s_nop 0
	v_add_f32_e32 v64, 0, v64
	v_add_f32_e32 v64, v64, v65
	ds_bpermute_b32 v65, v151, v64
	s_waitcnt lgkmcnt(0)
	v_add_f32_e32 v64, v64, v65
	ds_bpermute_b32 v65, v159, v64
	s_waitcnt lgkmcnt(0)
; __device__ __forceinline__ unsigned cvt_pk_bf16(float lo, float hi) { unsigned r; asm volatile("v_cvt_pk_bf16_f32 %0, %1, %2" : "=v"(r) : "v"(lo), "v"(hi)); return r; }
; __device__ __forceinline__ float row_ss(const float* part, int row, int fq, int nf4) {
;     const f32x4* p = (const f32x4*)(part + (size_t)row * 32);
;     float s = 0.f;
; #pragma unroll
;     for (int j = 0; j < 2; ++j) { const int idx = fq + 4 * j; if (idx < nf4) { const f32x4 v = p[idx]; s += (v[0] + v[1]) + (v[2] + v[3]); } }
;     s += __shfl_xor(s, 16); s += __shfl_xor(s, 32);
;     return s;
;     __device__ __forceinline__ void operator()(const f32x4 (&acc)[2][2][4][2], const Unit& u, int wr, int wc, int fr, int fq) const {
;     ...
;             for (int m = 0; m < 4; ++m) { const int row = row0 + ai * HALF + m * 16; bf16_t* rowp = base + (size_t)row * ldc + col0;
;                 const float rs = rss ? __builtin_amdgcn_rsqf(row_ss(rss, row, fq, nf4) * rinv + 1e-6f) : 1.f;
; #pragma unroll
;                 for (int bj = 0; bj < 2; ++bj) { f32x4 v0 = acc[ai][bj][m][0] * rs + bv[bj][0], v1 = acc[ai][bj][m][1] * rs + bv[bj][1];
;                     v0 = v0 * sc; v1 = v1 * sc; u32x4 w; w.x = cvt_pk_bf16(v0[0], v0[1]); w.y = cvt_pk_bf16(v0[2], v0[3]); w.z = cvt_pk_bf16(v1[0], v1[1]); w.w = cvt_pk_bf16(v1[2], v1[3]);
;                     *(u32x4*)(rowp + bj * HALF) = w; } }
	v_add_f32_e32 v64, v64, v65
	v_fmamk_f32 v64, v64, 0x3a000000, v157
	v_rsq_f32_e32 v64, v64
	s_nop 0
	v_pk_fma_f32 v[60:61], v[60:61], v[64:65], 0 op_sel_hi:[1,0,0]
	v_pk_fma_f32 v[62:63], v[62:63], v[64:65], 0 op_sel_hi:[1,0,0]
	v_pk_fma_f32 v[56:57], v[56:57], v[64:65], 0 op_sel_hi:[1,0,0]
	v_pk_fma_f32 v[58:59], v[58:59], v[64:65], 0 op_sel_hi:[1,0,0]
	v_pk_mul_f32 v[62:63], v[146:147], v[62:63] op_sel_hi:[0,1]
	v_pk_mul_f32 v[60:61], v[146:147], v[60:61] op_sel_hi:[0,1]
	v_pk_mul_f32 v[66:67], v[146:147], v[58:59] op_sel_hi:[0,1]
	v_pk_mul_f32 v[58:59], v[146:147], v[56:57] op_sel_hi:[0,1]
	v_cvt_pk_bf16_f32 v56, v60, v61
	v_cvt_pk_bf16_f32 v57, v62, v63
	v_pk_fma_f32 v[52:53], v[52:53], v[64:65], 0 op_sel_hi:[1,0,0]
	v_pk_fma_f32 v[48:49], v[48:49], v[64:65], 0 op_sel_hi:[1,0,0]
	v_pk_fma_f32 v[50:51], v[50:51], v[64:65], 0 op_sel_hi:[1,0,0]
	v_cvt_pk_bf16_f32 v58, v58, v59
	v_cvt_pk_bf16_f32 v59, v66, v67
	global_store_dwordx4 v[72:73], v[56:59], off sc1
	v_pk_fma_f32 v[54:55], v[54:55], v[64:65], 0 op_sel_hi:[1,0,0]
	v_pk_mul_f32 v[52:53], v[146:147], v[52:53] op_sel_hi:[0,1]
	v_pk_mul_f32 v[56:57], v[146:147], v[50:51] op_sel_hi:[0,1]
	v_pk_mul_f32 v[50:51], v[146:147], v[48:49] op_sel_hi:[0,1]
	v_cvt_pk_bf16_f32 v48, v52, v53
	v_pk_mul_f32 v[54:55], v[146:147], v[54:55] op_sel_hi:[0,1]
	v_cvt_pk_bf16_f32 v49, v54, v55
	v_cvt_pk_bf16_f32 v50, v50, v51
	v_cvt_pk_bf16_f32 v51, v56, v57
	global_store_dwordx4 v[72:73], v[48:51], off offset:256 sc1
	s_nop 1
	v_add_u32_e32 v48, 0x90, v150
	v_ashrrev_i32_e32 v49, 31, v48
	v_lshlrev_b64 v[50:51], 12, v[48:49]
	v_lshlrev_b64 v[48:49], 7, v[48:49]
	v_lshl_add_u64 v[52:53], v[136:137], 0, v[48:49]
	v_lshl_add_u64 v[56:57], v[148:149], 0, v[50:51]
	global_load_dwordx4 v[48:51], v[52:53], off
	s_nop 0
	global_load_dwordx4 v[52:55], v[52:53], off offset:64
	s_waitcnt vmcnt(1)
	v_mov_b32_e32 v58, v48
	s_waitcnt vmcnt(0)
	v_mov_b32_e32 v59, v52
	v_mov_b32_e32 v52, v49
	v_pk_add_f32 v[48:49], v[58:59], v[52:53]
	v_mov_b32_e32 v52, v50
	v_mov_b32_e32 v53, v54
	v_mov_b32_e32 v54, v51
	v_pk_add_f32 v[50:51], v[52:53], v[54:55]
	s_nop 0
	v_pk_add_f32 v[48:49], v[48:49], v[50:51]
	s_nop 0
	v_add_f32_e32 v48, 0, v48
	v_add_f32_e32 v48, v48, v49
	ds_bpermute_b32 v49, v151, v48
	s_waitcnt lgkmcnt(0)
	v_add_f32_e32 v48, v48, v49
	ds_bpermute_b32 v49, v159, v48
	s_waitcnt lgkmcnt(0)
	v_add_f32_e32 v48, v48, v49
	v_fmamk_f32 v48, v48, 0x3a000000, v157
	v_rsq_f32_e32 v48, v48
	s_nop 0
	v_pk_fma_f32 v[44:45], v[44:45], v[48:49], 0 op_sel_hi:[1,0,0]
	v_pk_fma_f32 v[46:47], v[46:47], v[48:49], 0 op_sel_hi:[1,0,0]
	v_pk_fma_f32 v[40:41], v[40:41], v[48:49], 0 op_sel_hi:[1,0,0]
	v_pk_fma_f32 v[42:43], v[42:43], v[48:49], 0 op_sel_hi:[1,0,0]
	v_pk_mul_f32 v[46:47], v[146:147], v[46:47] op_sel_hi:[0,1]
	v_pk_mul_f32 v[44:45], v[146:147], v[44:45] op_sel_hi:[0,1]
	v_pk_mul_f32 v[50:51], v[146:147], v[42:43] op_sel_hi:[0,1]
	v_pk_mul_f32 v[42:43], v[146:147], v[40:41] op_sel_hi:[0,1]
	v_cvt_pk_bf16_f32 v40, v44, v45
	v_cvt_pk_bf16_f32 v41, v46, v47
	v_pk_fma_f32 v[36:37], v[36:37], v[48:49], 0 op_sel_hi:[1,0,0]
	v_pk_fma_f32 v[32:33], v[32:33], v[48:49], 0 op_sel_hi:[1,0,0]
	v_pk_fma_f32 v[34:35], v[34:35], v[48:49], 0 op_sel_hi:[1,0,0]
	v_cvt_pk_bf16_f32 v42, v42, v43
	v_cvt_pk_bf16_f32 v43, v50, v51
	global_store_dwordx4 v[56:57], v[40:43], off sc1
	v_pk_fma_f32 v[38:39], v[38:39], v[48:49], 0 op_sel_hi:[1,0,0]
	v_pk_mul_f32 v[36:37], v[146:147], v[36:37] op_sel_hi:[0,1]
	v_pk_mul_f32 v[40:41], v[146:147], v[34:35] op_sel_hi:[0,1]
	v_pk_mul_f32 v[34:35], v[146:147], v[32:33] op_sel_hi:[0,1]
	v_cvt_pk_bf16_f32 v32, v36, v37
	v_pk_mul_f32 v[38:39], v[146:147], v[38:39] op_sel_hi:[0,1]
	v_cvt_pk_bf16_f32 v33, v38, v39
	v_cvt_pk_bf16_f32 v34, v34, v35
	v_cvt_pk_bf16_f32 v35, v40, v41
	global_store_dwordx4 v[56:57], v[32:35], off offset:256 sc1
	s_nop 1
	v_add_u32_e32 v32, 0xa0, v150
	v_ashrrev_i32_e32 v33, 31, v32
	v_lshlrev_b64 v[34:35], 12, v[32:33]
	v_lshlrev_b64 v[32:33], 7, v[32:33]
	v_lshl_add_u64 v[36:37], v[136:137], 0, v[32:33]
	v_lshl_add_u64 v[40:41], v[148:149], 0, v[34:35]
	global_load_dwordx4 v[32:35], v[36:37], off
	s_nop 0
	global_load_dwordx4 v[36:39], v[36:37], off offset:64
	s_waitcnt vmcnt(1)
	v_mov_b32_e32 v42, v32
	s_waitcnt vmcnt(0)
; __device__ __forceinline__ unsigned cvt_pk_bf16(float lo, float hi) { unsigned r; asm volatile("v_cvt_pk_bf16_f32 %0, %1, %2" : "=v"(r) : "v"(lo), "v"(hi)); return r; }
; __device__ __forceinline__ float row_ss(const float* part, int row, int fq, int nf4) {
;     const f32x4* p = (const f32x4*)(part + (size_t)row * 32);
;     float s = 0.f;
; #pragma unroll
;     for (int j = 0; j < 2; ++j) { const int idx = fq + 4 * j; if (idx < nf4) { const f32x4 v = p[idx]; s += (v[0] + v[1]) + (v[2] + v[3]); } }
;     s += __shfl_xor(s, 16); s += __shfl_xor(s, 32);
;     return s;
;     __device__ __forceinline__ void operator()(const f32x4 (&acc)[2][2][4][2], const Unit& u, int wr, int wc, int fr, int fq) const {
;     ...
;             for (int m = 0; m < 4; ++m) { const int row = row0 + ai * HALF + m * 16; bf16_t* rowp = base + (size_t)row * ldc + col0;
;                 const float rs = rss ? __builtin_amdgcn_rsqf(row_ss(rss, row, fq, nf4) * rinv + 1e-6f) : 1.f;
; #pragma unroll
;                 for (int bj = 0; bj < 2; ++bj) { f32x4 v0 = acc[ai][bj][m][0] * rs + bv[bj][0], v1 = acc[ai][bj][m][1] * rs + bv[bj][1];
;                     v0 = v0 * sc; v1 = v1 * sc; u32x4 w; w.x = cvt_pk_bf16(v0[0], v0[1]); w.y = cvt_pk_bf16(v0[2], v0[3]); w.z = cvt_pk_bf16(v1[0], v1[1]); w.w = cvt_pk_bf16(v1[2], v1[3]);
;                     *(u32x4*)(rowp + bj * HALF) = w; } }
	v_mov_b32_e32 v43, v36
	v_mov_b32_e32 v36, v33
	v_pk_add_f32 v[32:33], v[42:43], v[36:37]
	v_mov_b32_e32 v36, v34
	v_mov_b32_e32 v37, v38
	v_mov_b32_e32 v38, v35
	v_pk_add_f32 v[34:35], v[36:37], v[38:39]
	s_nop 0
	v_pk_add_f32 v[32:33], v[32:33], v[34:35]
	s_nop 0
	v_add_f32_e32 v32, 0, v32
	v_add_f32_e32 v32, v32, v33
	ds_bpermute_b32 v33, v151, v32
	s_waitcnt lgkmcnt(0)
	v_add_f32_e32 v32, v32, v33
	ds_bpermute_b32 v33, v159, v32
	s_waitcnt lgkmcnt(0)
	v_add_f32_e32 v32, v32, v33
	v_fmamk_f32 v32, v32, 0x3a000000, v157
	v_rsq_f32_e32 v32, v32
	s_nop 0
	v_pk_fma_f32 v[28:29], v[28:29], v[32:33], 0 op_sel_hi:[1,0,0]
	v_pk_fma_f32 v[30:31], v[30:31], v[32:33], 0 op_sel_hi:[1,0,0]
	v_pk_fma_f32 v[24:25], v[24:25], v[32:33], 0 op_sel_hi:[1,0,0]
	v_pk_fma_f32 v[26:27], v[26:27], v[32:33], 0 op_sel_hi:[1,0,0]
	v_pk_mul_f32 v[30:31], v[146:147], v[30:31] op_sel_hi:[0,1]
	v_pk_mul_f32 v[28:29], v[146:147], v[28:29] op_sel_hi:[0,1]
	v_pk_mul_f32 v[34:35], v[146:147], v[26:27] op_sel_hi:[0,1]
	v_pk_mul_f32 v[26:27], v[146:147], v[24:25] op_sel_hi:[0,1]
	v_cvt_pk_bf16_f32 v24, v28, v29
	v_cvt_pk_bf16_f32 v25, v30, v31
	v_pk_fma_f32 v[16:17], v[16:17], v[32:33], 0 op_sel_hi:[1,0,0]
	v_pk_fma_f32 v[18:19], v[18:19], v[32:33], 0 op_sel_hi:[1,0,0]
	v_cvt_pk_bf16_f32 v26, v26, v27
	v_cvt_pk_bf16_f32 v27, v34, v35
	global_store_dwordx4 v[40:41], v[24:27], off sc1
	v_pk_fma_f32 v[20:21], v[20:21], v[32:33], 0 op_sel_hi:[1,0,0]
	v_pk_fma_f32 v[22:23], v[22:23], v[32:33], 0 op_sel_hi:[1,0,0]
	v_pk_mul_f32 v[24:25], v[146:147], v[18:19] op_sel_hi:[0,1]
	v_pk_mul_f32 v[18:19], v[146:147], v[16:17] op_sel_hi:[0,1]
	v_pk_mul_f32 v[22:23], v[146:147], v[22:23] op_sel_hi:[0,1]
	v_pk_mul_f32 v[20:21], v[146:147], v[20:21] op_sel_hi:[0,1]
	v_cvt_pk_bf16_f32 v16, v20, v21
	v_cvt_pk_bf16_f32 v17, v22, v23
	v_cvt_pk_bf16_f32 v18, v18, v19
	v_cvt_pk_bf16_f32 v19, v24, v25
	v_add_u32_e32 v24, 0xb0, v150
	v_ashrrev_i32_e32 v25, 31, v24
	global_store_dwordx4 v[40:41], v[16:19], off offset:256 sc1
	s_nop 1
	v_lshlrev_b64 v[16:17], 7, v[24:25]
	v_lshl_add_u64 v[20:21], v[136:137], 0, v[16:17]
	global_load_dwordx4 v[16:19], v[20:21], off
	s_nop 0
	global_load_dwordx4 v[20:23], v[20:21], off offset:64
	s_waitcnt vmcnt(1)
	v_mov_b32_e32 v26, v16
	s_waitcnt vmcnt(0)
	v_mov_b32_e32 v27, v20
	v_mov_b32_e32 v20, v17
	v_pk_add_f32 v[16:17], v[26:27], v[20:21]
	v_mov_b32_e32 v20, v18
	v_mov_b32_e32 v21, v22
	v_mov_b32_e32 v22, v19
	v_pk_add_f32 v[18:19], v[20:21], v[22:23]
	s_nop 0
	v_pk_add_f32 v[16:17], v[16:17], v[18:19]
	v_lshlrev_b64 v[18:19], 12, v[24:25]
	v_add_f32_e32 v16, 0, v16
	v_add_f32_e32 v16, v16, v17
	ds_bpermute_b32 v17, v151, v16
	v_lshl_add_u64 v[18:19], v[148:149], 0, v[18:19]
	s_waitcnt lgkmcnt(0)
	v_add_f32_e32 v16, v16, v17
	ds_bpermute_b32 v17, v159, v16
	s_waitcnt lgkmcnt(0)
	v_add_f32_e32 v16, v16, v17
	v_fmamk_f32 v16, v16, 0x3a000000, v157
	v_rsq_f32_e32 v16, v16
	s_nop 0
	v_pk_fma_f32 v[12:13], v[12:13], v[16:17], 0 op_sel_hi:[1,0,0]
	v_pk_fma_f32 v[14:15], v[14:15], v[16:17], 0 op_sel_hi:[1,0,0]
	v_pk_fma_f32 v[8:9], v[8:9], v[16:17], 0 op_sel_hi:[1,0,0]
	v_pk_fma_f32 v[10:11], v[10:11], v[16:17], 0 op_sel_hi:[1,0,0]
	v_pk_mul_f32 v[14:15], v[146:147], v[14:15] op_sel_hi:[0,1]
	v_pk_mul_f32 v[12:13], v[146:147], v[12:13] op_sel_hi:[0,1]
	v_pk_mul_f32 v[20:21], v[146:147], v[10:11] op_sel_hi:[0,1]
	v_pk_mul_f32 v[10:11], v[146:147], v[8:9] op_sel_hi:[0,1]
	v_cvt_pk_bf16_f32 v8, v12, v13
	v_cvt_pk_bf16_f32 v9, v14, v15
	v_pk_fma_f32 v[0:1], v[0:1], v[16:17], 0 op_sel_hi:[1,0,0]
	v_pk_fma_f32 v[2:3], v[2:3], v[16:17], 0 op_sel_hi:[1,0,0]
	v_cvt_pk_bf16_f32 v10, v10, v11
	v_cvt_pk_bf16_f32 v11, v20, v21
	global_store_dwordx4 v[18:19], v[8:11], off sc1
	v_pk_fma_f32 v[4:5], v[4:5], v[16:17], 0 op_sel_hi:[1,0,0]
	v_pk_fma_f32 v[6:7], v[6:7], v[16:17], 0 op_sel_hi:[1,0,0]
	v_pk_mul_f32 v[8:9], v[146:147], v[2:3] op_sel_hi:[0,1]
	v_pk_mul_f32 v[2:3], v[146:147], v[0:1] op_sel_hi:[0,1]
	v_pk_mul_f32 v[6:7], v[146:147], v[6:7] op_sel_hi:[0,1]
	v_pk_mul_f32 v[4:5], v[146:147], v[4:5] op_sel_hi:[0,1]
	v_cvt_pk_bf16_f32 v0, v4, v5
	v_cvt_pk_bf16_f32 v1, v6, v7
	v_cvt_pk_bf16_f32 v2, v2, v3
	v_cvt_pk_bf16_f32 v3, v8, v9
	global_store_dwordx4 v[18:19], v[0:3], off offset:256 sc1
	s_cbranch_vccnz .LBB0_2507
	s_andn2_b64 vcc, exec, s[4:5]
	s_cbranch_vccnz .LBB0_2506
	s_barrier
	s_branch .LBB0_2506

; #define LAS __attribute__((address_space(3)))
; __device__ __forceinline__ unsigned cvtpk(float lo, float hi) { f32x2 v = {lo, hi}; bf16x2_t b = __builtin_convertvector(v, bf16x2_t); return __builtin_bit_cast(unsigned, b); }
; __device__ __forceinline__ void witem_store(const WItem& w, int K, bf16_t* WT, int kvperm, LAS float* scr, int item, int nblk, int lane) {
;     ...
; #pragma unroll
;     for (int i = 0; i < 8; ++i) { LAS float* d = scr + (8 * i + rr) * 33 + col; const float g = w.g[i]; d[0] = w.v[i].x * g; d[1] = w.v[i].y * g; d[2] = w.v[i].z * g; d[3] = w.v[i].w * g; }
;     asm volatile("s_waitcnt lgkmcnt(0)" ::: "memory");
;     const int c = lane & 7;
; #pragma unroll
;     for (int j = 0; j < 4; ++j) { const int n = (lane >> 3) + 8 * j; const LAS float* s = scr + (8 * c) * 33 + n;
;         u32x4 o; o.x = cvtpk(s[0 * 33], s[1 * 33]); o.y = cvtpk(s[2 * 33], s[3 * 33]); o.z = cvtpk(s[4 * 33], s[5 * 33]); o.w = cvtpk(s[6 * 33], s[7 * 33]);
;         int nr = n0 + n; if (kvperm == 1) { const int hh = nr >> 8, ww = nr & 255; nr = (ww < 128) ? hh * 128 + ww : 2048 + hh * 128 + (ww - 128); }
;         else if (kvperm == 2) { const int isv = nr >= 5632, f = isv ? nr - 5632 : nr; nr = (f >> 7) * 256 + isv * 128 + (f & 127); }
;         *(u32x4*)(WT + (size_t)nr * K + k0 + 8 * c) = o; }
;     asm volatile("s_waitcnt lgkmcnt(0)" ::: "memory");
;     ...
;     while (it < i1) {
;         cur = nxt;
;         const int nit = it + NGW;
;         if (nit < i1) witem_load(nxt, W, N, gk, nit, nblk, lane);
;         witem_store(cur, K, WT, kvperm, scr, it, nblk, lane);
;         it = nit;
;     }
.LBB0_2538:
	ds_write2_b32 v84, v4, v5 offset1:1
	ds_write2_b32 v84, v6, v7 offset0:2 offset1:3
	v_add_u32_e32 v4, 0x420, v84
	ds_write2_b32 v4, v0, v1 offset1:1
	v_add_u32_e32 v0, 0x428, v84
	ds_write2_b32 v0, v2, v3 offset1:1
	v_add_u32_e32 v0, 0x840, v84
	ds_write2_b32 v0, v12, v13 offset1:1
	v_add_u32_e32 v0, 0x848, v84
	ds_write2_b32 v0, v14, v15 offset1:1
	v_add_u32_e32 v0, 0xc60, v84
	ds_write2_b32 v0, v8, v9 offset1:1
	v_add_u32_e32 v0, 0xc68, v84
	ds_write2_b32 v0, v10, v11 offset1:1
	v_add_u32_e32 v0, 0x1080, v84
	ds_write2_b32 v0, v24, v25 offset1:1
	v_add_u32_e32 v0, 0x1088, v84
	ds_write2_b32 v0, v26, v27 offset1:1
	v_add_u32_e32 v0, 0x14a0, v84
	ds_write2_b32 v0, v16, v17 offset1:1
	v_add_u32_e32 v0, 0x14a8, v84
	ds_write2_b32 v0, v18, v19 offset1:1
	v_add_u32_e32 v0, 0x18c0, v84
	ds_write2_b32 v0, v36, v37 offset1:1
	v_add_u32_e32 v0, 0x18c8, v84
	ds_write2_b32 v0, v38, v39 offset1:1
	v_add_u32_e32 v0, 0x1ce0, v84
	ds_write2_b32 v0, v40, v41 offset1:1
	v_add_u32_e32 v0, 0x1ce8, v84
	s_ashr_i32 s10, s13, 31
	ds_write2_b32 v0, v42, v43 offset1:1
	s_lshr_b32 s10, s10, 26
	s_waitcnt lgkmcnt(0)
	s_add_i32 s10, s13, s10
	ds_read2_b32 v[4:5], v82 offset0:33 offset1:41
	ds_read2_b32 v[6:7], v82 offset1:8
	ds_read2_b32 v[8:9], v82 offset0:66 offset1:74
	ds_read2_b32 v[10:11], v82 offset0:99 offset1:107
	ds_read2_b32 v[12:13], v82 offset0:132 offset1:140
	ds_read2_b32 v[14:15], v82 offset0:165 offset1:173
	ds_read2_b32 v[16:17], v82 offset0:198 offset1:206
	ds_read2_b32 v[18:19], v82 offset0:231 offset1:239
	s_lshr_b32 s13, s10, 6
	s_andn2_b32 s10, s10, 63
	s_mul_i32 s13, s13, 0xff500000
	s_ashr_i32 s11, s10, 31
	v_add_u32_e32 v24, s13, v83
	v_lshl_add_u64 v[22:23], s[10:11], 1, v[70:71]
	v_ashrrev_i32_e32 v25, 31, v24
	s_waitcnt lgkmcnt(6)
	v_cvt_pk_bf16_f32 v0, v6, v4
	s_waitcnt lgkmcnt(4)
	v_cvt_pk_bf16_f32 v1, v8, v10
	s_waitcnt lgkmcnt(2)
	v_cvt_pk_bf16_f32 v2, v12, v14
	s_waitcnt lgkmcnt(0)
	v_cvt_pk_bf16_f32 v3, v16, v18
	v_lshl_add_u64 v[26:27], v[24:25], 1, v[22:23]
	global_store_dwordx4 v[26:27], v[0:3], off sc1
	v_add_u32_e32 v4, 0xb000, v24
	s_mul_i32 s10, s2, 0x2c000
	v_cvt_pk_bf16_f32 v0, v7, v5
	v_cvt_pk_bf16_f32 v1, v9, v11
	v_cvt_pk_bf16_f32 v2, v13, v15
	v_cvt_pk_bf16_f32 v3, v17, v19
	ds_read2_b32 v[6:7], v82 offset0:49 offset1:57
	ds_read2_b32 v[8:9], v82 offset0:16 offset1:24
	ds_read2_b32 v[10:11], v82 offset0:82 offset1:90
	ds_read2_b32 v[12:13], v82 offset0:115 offset1:123
	ds_read2_b32 v[14:15], v82 offset0:148 offset1:156
	ds_read2_b32 v[16:17], v82 offset0:181 offset1:189
	ds_read2_b32 v[18:19], v82 offset0:214 offset1:222
	ds_read2_b32 v[26:27], v82 offset0:247 offset1:255
	v_ashrrev_i32_e32 v5, 31, v4
	v_lshl_add_u64 v[4:5], v[4:5], 1, v[22:23]
	global_store_dwordx4 v[4:5], v[0:3], off sc1
	v_add_u32_e32 v4, 0x16000, v24
	v_ashrrev_i32_e32 v5, 31, v4
	s_waitcnt lgkmcnt(6)
	v_cvt_pk_bf16_f32 v0, v8, v6
	s_waitcnt lgkmcnt(4)
	v_cvt_pk_bf16_f32 v1, v10, v12
	s_waitcnt lgkmcnt(2)
	v_cvt_pk_bf16_f32 v2, v14, v16
	s_waitcnt lgkmcnt(0)
	v_cvt_pk_bf16_f32 v3, v18, v26
	v_lshl_add_u64 v[4:5], v[4:5], 1, v[22:23]
	global_store_dwordx4 v[4:5], v[0:3], off sc1
	v_add_u32_e32 v4, 0x21000, v24
	v_ashrrev_i32_e32 v5, 31, v4
	v_cvt_pk_bf16_f32 v0, v9, v7
	v_cvt_pk_bf16_f32 v1, v11, v13
	v_cvt_pk_bf16_f32 v2, v15, v17
	v_cvt_pk_bf16_f32 v3, v19, v27
	v_lshl_add_u64 v[4:5], v[4:5], 1, v[22:23]
	global_store_dwordx4 v[4:5], v[0:3], off sc1
	s_waitcnt lgkmcnt(0)
	s_waitcnt vmcnt(4)
	v_mov_b64_e32 v[4:5], v[32:33]
	v_mov_b64_e32 v[12:13], v[44:45]
	v_mov_b64_e32 v[0:1], v[28:29]
	v_mov_b64_e32 v[8:9], v[48:49]
	v_mov_b64_e32 v[24:25], v[52:53]
	v_mov_b64_e32 v[16:17], v[56:57]
	v_mov_b64_e32 v[36:37], v[60:61]
	v_add_u32_e32 v83, s10, v83
	s_add_i32 s14, s14, s15
	s_andn2_b64 vcc, exec, s[8:9]
	s_mov_b32 s13, s16
	v_mov_b64_e32 v[6:7], v[34:35]
	v_mov_b64_e32 v[2:3], v[30:31]
	v_mov_b64_e32 v[14:15], v[46:47]
	v_mov_b64_e32 v[10:11], v[50:51]
	v_mov_b64_e32 v[26:27], v[54:55]
	v_mov_b64_e32 v[18:19], v[58:59]
	v_mov_b64_e32 v[38:39], v[62:63]
	v_mov_b32_e32 v40, v64
	v_mov_b32_e32 v41, v65
	v_mov_b32_e32 v42, v66
	v_mov_b32_e32 v43, v67
	s_cbranch_vccz .LBB0_2556

; #define LAS __attribute__((address_space(3)))
; __device__ __forceinline__ unsigned cvtpk(float lo, float hi) { f32x2 v = {lo, hi}; bf16x2_t b = __builtin_convertvector(v, bf16x2_t); return __builtin_bit_cast(unsigned, b); }
; __device__ __forceinline__ void witem_store(const WItem& w, int K, bf16_t* WT, int kvperm, LAS float* scr, int item, int nblk, int lane) {
;     ...
; #pragma unroll
;     for (int i = 0; i < 8; ++i) { LAS float* d = scr + (8 * i + rr) * 33 + col; const float g = w.g[i]; d[0] = w.v[i].x * g; d[1] = w.v[i].y * g; d[2] = w.v[i].z * g; d[3] = w.v[i].w * g; }
;     asm volatile("s_waitcnt lgkmcnt(0)" ::: "memory");
;     const int c = lane & 7;
; #pragma unroll
;     for (int j = 0; j < 4; ++j) { const int n = (lane >> 3) + 8 * j; const LAS float* s = scr + (8 * c) * 33 + n;
;         u32x4 o; o.x = cvtpk(s[0 * 33], s[1 * 33]); o.y = cvtpk(s[2 * 33], s[3 * 33]); o.z = cvtpk(s[4 * 33], s[5 * 33]); o.w = cvtpk(s[6 * 33], s[7 * 33]);
;         int nr = n0 + n; if (kvperm == 1) { const int hh = nr >> 8, ww = nr & 255; nr = (ww < 128) ? hh * 128 + ww : 2048 + hh * 128 + (ww - 128); }
;         else if (kvperm == 2) { const int isv = nr >= 5632, f = isv ? nr - 5632 : nr; nr = (f >> 7) * 256 + isv * 128 + (f & 127); }
;         *(u32x4*)(WT + (size_t)nr * K + k0 + 8 * c) = o; }
;     asm volatile("s_waitcnt lgkmcnt(0)" ::: "memory");
;     ...
;     while (it < i1) {
;         cur = nxt;
;         const int nit = it + NGW;
;         if (nit < i1) witem_load(nxt, W, N, gk, nit, nblk, lane);
;         witem_store(cur, K, WT, kvperm, scr, it, nblk, lane);
;         it = nit;
;     }
.LBB0_2575:
	ds_write2_b32 v82, v4, v5 offset1:1
	ds_write2_b32 v82, v6, v7 offset0:2 offset1:3
	v_add_u32_e32 v4, 0x420, v82
	ds_write2_b32 v4, v0, v1 offset1:1
	v_add_u32_e32 v0, 0x428, v82
	ds_write2_b32 v0, v2, v3 offset1:1
	v_add_u32_e32 v0, 0x840, v82
	ds_write2_b32 v0, v12, v13 offset1:1
	v_add_u32_e32 v0, 0x848, v82
	ds_write2_b32 v0, v14, v15 offset1:1
	v_add_u32_e32 v0, 0xc60, v82
	ds_write2_b32 v0, v8, v9 offset1:1
	v_add_u32_e32 v0, 0xc68, v82
	ds_write2_b32 v0, v10, v11 offset1:1
	v_add_u32_e32 v0, 0x1080, v82
	ds_write2_b32 v0, v24, v25 offset1:1
	v_add_u32_e32 v0, 0x1088, v82
	ds_write2_b32 v0, v26, v27 offset1:1
	v_add_u32_e32 v0, 0x14a0, v82
	ds_write2_b32 v0, v20, v21 offset1:1
	v_add_u32_e32 v0, 0x14a8, v82
	ds_write2_b32 v0, v22, v23 offset1:1
	v_add_u32_e32 v0, 0x18c0, v82
	s_ashr_i32 s10, s15, 31
	ds_write2_b32 v0, v36, v37 offset1:1
	v_add_u32_e32 v0, 0x18c8, v82
	s_lshr_b32 s10, s10, 26
	ds_write2_b32 v0, v38, v39 offset1:1
	v_add_u32_e32 v0, 0x1ce0, v82
	s_add_i32 s15, s15, s10
	ds_write2_b32 v0, v40, v41 offset1:1
	v_add_u32_e32 v0, 0x1ce8, v82
	s_and_b32 s10, s15, 0xffffffc0
	ds_write2_b32 v0, v42, v43 offset1:1
	s_waitcnt lgkmcnt(0)
	s_ashr_i32 s11, s10, 31
	ds_read2_b32 v[4:5], v81 offset0:33 offset1:41
	ds_read2_b32 v[6:7], v81 offset1:8
	ds_read2_b32 v[8:9], v81 offset0:66 offset1:74
	ds_read2_b32 v[10:11], v81 offset0:99 offset1:107
	ds_read2_b32 v[12:13], v81 offset0:132 offset1:140
	ds_read2_b32 v[14:15], v81 offset0:165 offset1:173
	ds_read2_b32 v[18:19], v81 offset0:198 offset1:206
	ds_read2_b32 v[20:21], v81 offset0:231 offset1:239
	v_lshl_add_u64 v[22:23], s[10:11], 1, v[70:71]
	s_lshl_b32 s10, s15, 5
	s_waitcnt lgkmcnt(6)
	v_cvt_pk_bf16_f32 v0, v6, v4
	v_add_u32_e32 v4, s16, v83
	s_and_b32 s10, s10, 0xfffff800
	v_subrev_u32_e32 v24, s10, v4
	v_ashrrev_i32_e32 v25, 31, v24
	v_lshlrev_b64 v[26:27], 12, v[24:25]
	s_waitcnt lgkmcnt(4)
	v_cvt_pk_bf16_f32 v1, v8, v10
	s_waitcnt lgkmcnt(2)
	v_cvt_pk_bf16_f32 v2, v12, v14
	s_waitcnt lgkmcnt(0)
	v_cvt_pk_bf16_f32 v3, v18, v20
	v_lshl_add_u64 v[26:27], v[22:23], 0, v[26:27]
	v_add_u32_e32 v4, 8, v24
	global_store_dwordx4 v[26:27], v[0:3], off sc1
	s_waitcnt vmcnt(1)
	v_mov_b64_e32 v[36:37], v[60:61]
	v_add_u32_e32 v83, s17, v83
	v_cvt_pk_bf16_f32 v0, v7, v5
	v_ashrrev_i32_e32 v5, 31, v4
	v_cvt_pk_bf16_f32 v1, v9, v11
	v_cvt_pk_bf16_f32 v2, v13, v15
	v_cvt_pk_bf16_f32 v3, v19, v21
	v_lshlrev_b64 v[4:5], 12, v[4:5]
	ds_read2_b32 v[6:7], v81 offset0:49 offset1:57
	ds_read2_b32 v[8:9], v81 offset0:16 offset1:24
	ds_read2_b32 v[10:11], v81 offset0:82 offset1:90
	ds_read2_b32 v[12:13], v81 offset0:115 offset1:123
	ds_read2_b32 v[14:15], v81 offset0:148 offset1:156
	ds_read2_b32 v[18:19], v81 offset0:181 offset1:189
	ds_read2_b32 v[20:21], v81 offset0:214 offset1:222
	ds_read2_b32 v[26:27], v81 offset0:247 offset1:255
	v_lshl_add_u64 v[4:5], v[22:23], 0, v[4:5]
	global_store_dwordx4 v[4:5], v[0:3], off sc1
	v_add_u32_e32 v4, 16, v24
	v_ashrrev_i32_e32 v5, 31, v4
	v_lshlrev_b64 v[4:5], 12, v[4:5]
	s_waitcnt lgkmcnt(6)
	v_cvt_pk_bf16_f32 v0, v8, v6
	s_waitcnt lgkmcnt(4)
	v_cvt_pk_bf16_f32 v1, v10, v12
	s_waitcnt lgkmcnt(2)
	v_cvt_pk_bf16_f32 v2, v14, v18
	s_waitcnt lgkmcnt(0)
	v_cvt_pk_bf16_f32 v3, v20, v26
	v_lshl_add_u64 v[4:5], v[22:23], 0, v[4:5]
	global_store_dwordx4 v[4:5], v[0:3], off sc1
	v_add_u32_e32 v4, 24, v24
	v_ashrrev_i32_e32 v5, 31, v4
	v_lshlrev_b64 v[4:5], 12, v[4:5]
	v_cvt_pk_bf16_f32 v0, v9, v7
	v_cvt_pk_bf16_f32 v1, v11, v13
	v_cvt_pk_bf16_f32 v2, v15, v19
	v_cvt_pk_bf16_f32 v3, v21, v27
	v_lshl_add_u64 v[4:5], v[22:23], 0, v[4:5]
	global_store_dwordx4 v[4:5], v[0:3], off sc1
	s_waitcnt lgkmcnt(0)
	v_mov_b64_e32 v[4:5], v[32:33]
	v_mov_b64_e32 v[12:13], v[44:45]
	v_mov_b64_e32 v[0:1], v[28:29]
	v_mov_b64_e32 v[8:9], v[48:49]
	v_mov_b64_e32 v[24:25], v[52:53]
	v_mov_b64_e32 v[20:21], v[56:57]
	s_add_i32 s19, s19, s17
	v_add_u32_e32 v80, s17, v80
	s_andn2_b64 vcc, exec, s[8:9]
	s_mov_b32 s15, s20
	v_mov_b64_e32 v[6:7], v[34:35]
	v_mov_b64_e32 v[2:3], v[30:31]
	v_mov_b64_e32 v[14:15], v[46:47]
	v_mov_b64_e32 v[10:11], v[50:51]
	v_mov_b64_e32 v[26:27], v[54:55]
	v_mov_b64_e32 v[22:23], v[58:59]
	v_mov_b64_e32 v[38:39], v[62:63]
	v_mov_b32_e32 v40, v64
	v_mov_b32_e32 v41, v65
	v_mov_b32_e32 v42, v66
	v_mov_b32_e32 v43, v67
	s_cbranch_vccz .LBB0_2593

; #define LAS __attribute__((address_space(3)))
; __device__ __forceinline__ unsigned cvtpk(float lo, float hi) { f32x2 v = {lo, hi}; bf16x2_t b = __builtin_convertvector(v, bf16x2_t); return __builtin_bit_cast(unsigned, b); }
; __device__ __forceinline__ void witem_store(const WItem& w, int K, bf16_t* WT, int kvperm, LAS float* scr, int item, int nblk, int lane) {
;     ...
; #pragma unroll
;     for (int i = 0; i < 8; ++i) { LAS float* d = scr + (8 * i + rr) * 33 + col; const float g = w.g[i]; d[0] = w.v[i].x * g; d[1] = w.v[i].y * g; d[2] = w.v[i].z * g; d[3] = w.v[i].w * g; }
;     asm volatile("s_waitcnt lgkmcnt(0)" ::: "memory");
;     const int c = lane & 7;
; #pragma unroll
;     for (int j = 0; j < 4; ++j) { const int n = (lane >> 3) + 8 * j; const LAS float* s = scr + (8 * c) * 33 + n;
;         u32x4 o; o.x = cvtpk(s[0 * 33], s[1 * 33]); o.y = cvtpk(s[2 * 33], s[3 * 33]); o.z = cvtpk(s[4 * 33], s[5 * 33]); o.w = cvtpk(s[6 * 33], s[7 * 33]);
;         int nr = n0 + n; if (kvperm == 1) { const int hh = nr >> 8, ww = nr & 255; nr = (ww < 128) ? hh * 128 + ww : 2048 + hh * 128 + (ww - 128); }
;         else if (kvperm == 2) { const int isv = nr >= 5632, f = isv ? nr - 5632 : nr; nr = (f >> 7) * 256 + isv * 128 + (f & 127); }
;         *(u32x4*)(WT + (size_t)nr * K + k0 + 8 * c) = o; }
;     asm volatile("s_waitcnt lgkmcnt(0)" ::: "memory");
;     ...
;     while (it < i1) {
;         cur = nxt;
;         const int nit = it + NGW;
;         if (nit < i1) witem_load(nxt, W, N, gk, nit, nblk, lane);
;         witem_store(cur, K, WT, kvperm, scr, it, nblk, lane);
;         it = nit;
;     }
.LBB0_2612:
	v_pk_mul_f32 v[2:3], v[16:17], v[72:73] op_sel_hi:[1,0]
	ds_write2_b32 v79, v2, v3 offset1:1
	v_pk_mul_f32 v[2:3], v[18:19], v[72:73] op_sel_hi:[1,0]
	ds_write2_b32 v79, v2, v3 offset0:2 offset1:3
	v_pk_mul_f32 v[2:3], v[4:5], v[74:75] op_sel_hi:[1,0]
	v_add_u32_e32 v4, 0x420, v79
	ds_write2_b32 v4, v2, v3 offset1:1
	v_pk_mul_f32 v[2:3], v[6:7], v[74:75] op_sel_hi:[1,0]
	v_add_u32_e32 v4, 0x428, v79
	ds_write2_b32 v4, v2, v3 offset1:1
	v_pk_mul_f32 v[2:3], v[24:25], v[76:77] op_sel_hi:[1,0]
	v_add_u32_e32 v4, 0x840, v79
	ds_write2_b32 v4, v2, v3 offset1:1
	v_pk_mul_f32 v[2:3], v[26:27], v[76:77] op_sel_hi:[1,0]
	v_add_u32_e32 v4, 0x848, v79
	ds_write2_b32 v4, v2, v3 offset1:1
	v_pk_mul_f32 v[2:3], v[20:21], v[78:79] op_sel_hi:[1,0]
	v_add_u32_e32 v4, 0xc60, v79
	ds_write2_b32 v4, v2, v3 offset1:1
	v_pk_mul_f32 v[2:3], v[22:23], v[78:79] op_sel_hi:[1,0]
	v_add_u32_e32 v4, 0xc68, v79
	ds_write2_b32 v4, v2, v3 offset1:1
	v_pk_mul_f32 v[2:3], v[36:37], v[80:81] op_sel_hi:[1,0]
	v_add_u32_e32 v4, 0x1080, v79
	ds_write2_b32 v4, v2, v3 offset1:1
	v_pk_mul_f32 v[2:3], v[38:39], v[80:81] op_sel_hi:[1,0]
	v_add_u32_e32 v4, 0x1088, v79
	ds_write2_b32 v4, v2, v3 offset1:1
	v_pk_mul_f32 v[2:3], v[32:33], v[82:83] op_sel_hi:[1,0]
	v_add_u32_e32 v4, 0x14a0, v79
	s_mul_hi_i32 s8, s12, 0x2e8ba2e9
	ds_write2_b32 v4, v2, v3 offset1:1
	v_pk_mul_f32 v[2:3], v[34:35], v[82:83] op_sel_hi:[1,0]
	v_add_u32_e32 v4, 0x14a8, v79
	s_lshr_b32 s9, s8, 31
	s_ashr_i32 s8, s8, 6
	ds_write2_b32 v4, v2, v3 offset1:1
	s_waitcnt vmcnt(7)
	v_pk_mul_f32 v[2:3], v[48:49], v[84:85] op_sel_hi:[1,0]
	v_add_u32_e32 v4, 0x18c0, v79
	s_add_i32 s12, s8, s9
	ds_write2_b32 v4, v2, v3 offset1:1
	v_pk_mul_f32 v[2:3], v[50:51], v[84:85] op_sel_hi:[1,0]
	v_add_u32_e32 v4, 0x18c8, v79
	s_lshl_b32 s8, s12, 6
	ds_write2_b32 v4, v2, v3 offset1:1
	s_waitcnt vmcnt(6)
	v_pk_mul_f32 v[2:3], v[44:45], v[86:87] op_sel_hi:[1,0]
	v_add_u32_e32 v4, 0x1ce0, v79
	ds_write2_b32 v4, v2, v3 offset1:1
	v_pk_mul_f32 v[2:3], v[46:47], v[86:87] op_sel_hi:[1,0]
	v_add_u32_e32 v4, 0x1ce8, v79
	s_ashr_i32 s9, s8, 31
	ds_write2_b32 v4, v2, v3 offset1:1
	v_lshl_add_u64 v[34:35], s[8:9], 1, v[70:71]
	s_mul_i32 s8, s12, 0xffffd400
	s_waitcnt lgkmcnt(0)
	s_add_i32 s8, s8, s3
	ds_read2_b32 v[6:7], v75 offset0:33 offset1:41
	ds_read2_b32 v[16:17], v75 offset1:8
	ds_read2_b32 v[18:19], v75 offset0:66 offset1:74
	ds_read2_b32 v[20:21], v75 offset0:99 offset1:107
	ds_read2_b32 v[22:23], v75 offset0:132 offset1:140
	ds_read2_b32 v[24:25], v75 offset0:165 offset1:173
	ds_read2_b32 v[26:27], v75 offset0:198 offset1:206
	ds_read2_b32 v[32:33], v75 offset0:231 offset1:239
	v_add_u32_e32 v38, s8, v83
	s_waitcnt lgkmcnt(6)
	v_cvt_pk_bf16_f32 v2, v16, v6
	v_add_u32_e32 v6, 0xffffea00, v38
	v_cmp_lt_i32_e32 vcc, s11, v38
	s_waitcnt lgkmcnt(4)
	v_cvt_pk_bf16_f32 v3, v18, v20
	s_waitcnt lgkmcnt(2)
	v_cvt_pk_bf16_f32 v4, v22, v24
	v_cndmask_b32_e32 v6, v38, v6, vcc
	v_lshlrev_b32_e32 v16, 1, v6
	v_and_b32_e32 v16, 0xffffff00, v16
	v_cndmask_b32_e32 v18, 0, v81, vcc
	v_and_b32_e32 v6, 0x67, v6
	v_or3_b32 v36, v6, v18, v16
	v_ashrrev_i32_e32 v37, 31, v36
	v_lshlrev_b64 v[36:37], 12, v[36:37]
	s_waitcnt lgkmcnt(0)
	v_cvt_pk_bf16_f32 v5, v26, v32
	v_lshl_add_u64 v[36:37], v[34:35], 0, v[36:37]
	v_add_u32_e32 v6, 8, v38
	global_store_dwordx4 v[36:37], v[2:5], off sc1
	v_cmp_lt_i32_e32 vcc, s11, v6
	s_waitcnt vmcnt(3)
	v_mov_b64_e32 v[48:49], v[60:61]
	v_cvt_pk_bf16_f32 v2, v17, v7
	v_add_u32_e32 v7, 0xffffea08, v38
	v_cndmask_b32_e32 v6, v6, v7, vcc
	v_lshlrev_b32_e32 v7, 1, v6
	v_and_b32_e32 v7, 0xffffff00, v7
	v_cndmask_b32_e32 v16, 0, v81, vcc
	v_and_b32_e32 v6, 0x6f, v6
	v_or3_b32 v6, v6, v16, v7
	v_ashrrev_i32_e32 v7, 31, v6
	v_lshlrev_b64 v[6:7], 12, v[6:7]
	v_cvt_pk_bf16_f32 v3, v19, v21
	v_cvt_pk_bf16_f32 v4, v23, v25
	v_cvt_pk_bf16_f32 v5, v27, v33
	v_lshl_add_u64 v[6:7], v[34:35], 0, v[6:7]
	ds_read2_b32 v[16:17], v75 offset0:16 offset1:24
	ds_read2_b32 v[18:19], v75 offset0:49 offset1:57
	ds_read2_b32 v[20:21], v75 offset0:82 offset1:90
	ds_read2_b32 v[22:23], v75 offset0:115 offset1:123
	ds_read2_b32 v[24:25], v75 offset0:148 offset1:156
	ds_read2_b32 v[26:27], v75 offset0:181 offset1:189
	ds_read2_b32 v[32:33], v75 offset0:214 offset1:222
	ds_read2_b32 v[36:37], v75 offset0:247 offset1:255
	global_store_dwordx4 v[6:7], v[2:5], off sc1
	v_add_u32_e32 v6, 16, v38
	v_add_u32_e32 v7, 0xffffea10, v38
	v_cmp_lt_i32_e32 vcc, s11, v6
	s_waitcnt lgkmcnt(6)
	v_cvt_pk_bf16_f32 v2, v16, v18
	s_waitcnt lgkmcnt(4)
	v_cvt_pk_bf16_f32 v3, v20, v22
	v_cndmask_b32_e32 v6, v6, v7, vcc
	v_lshlrev_b32_e32 v7, 1, v6
	v_and_b32_e32 v7, 0xffffff00, v7
	v_cndmask_b32_e32 v16, 0, v81, vcc
	v_and_b32_e32 v6, 0x77, v6
	v_or3_b32 v6, v6, v16, v7
	v_ashrrev_i32_e32 v7, 31, v6
	v_lshlrev_b64 v[6:7], 12, v[6:7]
	s_waitcnt lgkmcnt(2)
	v_cvt_pk_bf16_f32 v4, v24, v26
	s_waitcnt lgkmcnt(0)
	v_cvt_pk_bf16_f32 v5, v32, v36
	v_lshl_add_u64 v[6:7], v[34:35], 0, v[6:7]
	global_store_dwordx4 v[6:7], v[2:5], off sc1
	s_waitcnt vmcnt(4)
	v_mov_b64_e32 v[44:45], v[64:65]
	v_add_u32_e32 v83, s6, v83
	v_add_u32_e32 v2, 24, v38
	v_add_u32_e32 v3, 0xffffea18, v38
	v_cmp_lt_i32_e32 vcc, s11, v2
	v_cvt_pk_bf16_f32 v5, v33, v37
	v_mov_b64_e32 v[36:37], v[52:53]
	v_cndmask_b32_e32 v2, v2, v3, vcc
	v_lshlrev_b32_e32 v3, 1, v2
	v_and_b32_e32 v3, 0xffffff00, v3
	v_cndmask_b32_e32 v4, 0, v81, vcc
	v_and_b32_e32 v2, 0x7f, v2
	v_or3_b32 v6, v2, v4, v3
	v_ashrrev_i32_e32 v7, 31, v6
	v_lshlrev_b64 v[6:7], 12, v[6:7]
	v_cvt_pk_bf16_f32 v2, v17, v19
	v_cvt_pk_bf16_f32 v3, v21, v23
	v_cvt_pk_bf16_f32 v4, v25, v27
	v_lshl_add_u64 v[6:7], v[34:35], 0, v[6:7]
	global_store_dwordx4 v[6:7], v[2:5], off sc1
	s_waitcnt lgkmcnt(0)
	v_mov_b64_e32 v[18:19], v[14:15]
	v_mov_b64_e32 v[24:25], v[28:29]
	v_mov_b64_e32 v[4:5], v[8:9]
	v_mov_b64_e32 v[20:21], v[40:41]
	v_mov_b64_e32 v[32:33], v[56:57]
	s_add_i32 s13, s13, s6
	v_add_u32_e32 v73, s6, v73
	s_andn2_b64 vcc, exec, s[0:1]
	s_mov_b32 s12, s14
	v_mov_b64_e32 v[16:17], v[12:13]
	v_mov_b64_e32 v[6:7], v[10:11]
	v_mov_b64_e32 v[26:27], v[30:31]
	v_mov_b64_e32 v[22:23], v[42:43]
	v_mov_b64_e32 v[38:39], v[54:55]
	v_mov_b64_e32 v[34:35], v[58:59]
	v_mov_b64_e32 v[50:51], v[62:63]
	v_mov_b64_e32 v[46:47], v[66:67]
	v_mov_b32_e32 v72, v85
	v_mov_b32_e32 v74, v87
	v_mov_b32_e32 v76, v89
	v_mov_b32_e32 v78, v94
	v_mov_b32_e32 v80, v95
	v_mov_b32_e32 v82, v96
	v_mov_b32_e32 v84, v97
	s_waitcnt vmcnt(4)
	v_mov_b32_e32 v86, v1
	s_cbranch_vccz .LBB0_2630

; __device__ __forceinline__ unsigned cvt_pk_bf16(float lo, float hi) { unsigned r; asm volatile("v_cvt_pk_bf16_f32 %0, %1, %2" : "=v"(r) : "v"(lo), "v"(hi)); return r; }
;     __device__ __forceinline__ void operator()(const f32x4 (&acc)[2][2][4][2], const Unit& u, int wr, int wc, int fr, int fq) const {
;     ...
;         float* ssp = ssout + (size_t)(u.pn * 4 + wc);
; #pragma unroll
;         for (int ai = 0; ai < 2; ++ai) {
;             u32x4 old[4][2];
; #pragma unroll
;             for (int m = 0; m < 4; ++m)
; #pragma unroll
;                 for (int bj = 0; bj < 2; ++bj) old[m][bj] = *(const u32x4*)(HB + (size_t)(row0 + ai * HALF + m * 16) * ldc + col0 + bj * HALF);
; #pragma unroll
;             for (int m = 0; m < 4; ++m) { const int row = row0 + ai * HALF + m * 16; float ss = 0.f;
; #pragma unroll
;                 for (int bj = 0; bj < 2; ++bj) { const u32x4 ow = old[m][bj];
;                     f32x4 v0 = (acc[ai][bj][m][0] + bv[bj][0]) * accs, v1 = (acc[ai][bj][m][1] + bv[bj][1]) * accs;
;                     v0[0] += __uint_as_float(ow.x << 16); v0[1] += __uint_as_float(ow.x & 0xffff0000u); v0[2] += __uint_as_float(ow.y << 16); v0[3] += __uint_as_float(ow.y & 0xffff0000u);
;                     v1[0] += __uint_as_float(ow.z << 16); v1[1] += __uint_as_float(ow.z & 0xffff0000u); v1[2] += __uint_as_float(ow.w << 16); v1[3] += __uint_as_float(ow.w & 0xffff0000u);
;                     ss += (v0[0] * v0[0] + v0[1] * v0[1]) + (v0[2] * v0[2] + v0[3] * v0[3]) + (v1[0] * v1[0] + v1[1] * v1[1]) + (v1[2] * v1[2] + v1[3] * v1[3]);
;                     u32x4 w; w.x = cvt_pk_bf16(v0[0], v0[1]); w.y = cvt_pk_bf16(v0[2], v0[3]); w.z = cvt_pk_bf16(v1[0], v1[1]); w.w = cvt_pk_bf16(v1[2], v1[3]);
;                     *(u32x4*)(HB + (size_t)row * ldc + col0 + bj * HALF) = w; }
;                 ss += __shfl_xor(ss, 16); ss += __shfl_xor(ss, 32);
;                 if (fq == 0) ssp[(size_t)row * 32] = ss; }
.LBB0_2849:
	v_lshl_or_b32 v152, s20, 8, v166
	v_ashrrev_i32_e32 v153, 31, v152
	v_lshl_add_u32 v156, s22, 8, v164
	v_lshlrev_b64 v[178:179], 1, v[152:153]
	v_ashrrev_i32_e32 v157, 31, v156
	v_lshl_add_u64 v[154:155], s[8:9], 0, v[178:179]
	v_lshlrev_b64 v[180:181], 12, v[156:157]
	v_lshl_add_u64 v[128:129], v[154:155], 0, v[180:181]
	global_load_dwordx4 v[170:173], v[128:129], off
	global_load_dwordx4 v[174:177], v[128:129], off offset:256
	v_or_b32_e32 v162, 16, v156
	v_or_b32_e32 v160, 32, v156
	v_or_b32_e32 v158, 48, v156
	v_ashrrev_i32_e32 v163, 31, v162
	v_ashrrev_i32_e32 v161, 31, v160
	v_pk_add_f32 v[194:195], v[114:115], 0 op_sel_hi:[1,0]
	v_pk_add_f32 v[196:197], v[112:113], 0 op_sel_hi:[1,0]
	v_ashrrev_i32_e32 v159, 31, v158
	v_lshlrev_b64 v[112:113], 12, v[162:163]
	v_lshlrev_b64 v[114:115], 12, v[160:161]
	v_pk_add_f32 v[192:193], v[116:117], 0 op_sel_hi:[1,0]
	v_lshlrev_b64 v[116:117], 12, v[158:159]
	v_lshl_add_u64 v[112:113], v[154:155], 0, v[112:113]
	v_lshl_add_u64 v[114:115], v[154:155], 0, v[114:115]
	v_pk_add_f32 v[182:183], v[126:127], 0 op_sel_hi:[1,0]
	v_pk_add_f32 v[184:185], v[124:125], 0 op_sel_hi:[1,0]
	v_pk_add_f32 v[186:187], v[122:123], 0 op_sel_hi:[1,0]
	v_pk_add_f32 v[188:189], v[120:121], 0 op_sel_hi:[1,0]
	v_pk_add_f32 v[190:191], v[118:119], 0 op_sel_hi:[1,0]
	v_lshl_add_u64 v[198:199], v[154:155], 0, v[116:117]
	global_load_dwordx4 v[132:135], v[112:113], off
	global_load_dwordx4 v[128:131], v[112:113], off offset:256
	global_load_dwordx4 v[124:127], v[114:115], off
	global_load_dwordx4 v[120:123], v[114:115], off offset:256
	global_load_dwordx4 v[116:119], v[198:199], off
	s_nop 0
	global_load_dwordx4 v[112:115], v[198:199], off offset:256
	s_lshl_b32 s2, s20, 2
	s_or_b32 s20, s2, s38
	s_ashr_i32 s21, s20, 31
	s_lshl_b64 s[20:21], s[20:21], 2
	s_add_u32 s20, s3, s20
	s_addc_u32 s21, s33, s21
	s_waitcnt vmcnt(0)
	v_lshlrev_b32_e32 v198, 16, v170
	v_and_b32_e32 v170, 0xffff0000, v170
	v_lshlrev_b32_e32 v199, 16, v171
	v_and_b32_e32 v171, 0xffff0000, v171
	v_lshlrev_b32_e32 v200, 16, v172
	v_and_b32_e32 v172, 0xffff0000, v172
	v_lshlrev_b32_e32 v203, 16, v174
	v_and_b32_e32 v174, 0xffff0000, v174
	v_lshlrev_b32_e32 v205, 16, v175
	v_and_b32_e32 v175, 0xffff0000, v175
	v_lshlrev_b32_e32 v201, 16, v173
	v_and_b32_e32 v173, 0xffff0000, v173
	v_lshlrev_b32_e32 v206, 16, v176
	v_and_b32_e32 v176, 0xffff0000, v176
	v_lshlrev_b32_e32 v207, 16, v177
	v_and_b32_e32 v177, 0xffff0000, v177
	v_add_f32_e32 v170, v185, v170
	v_add_f32_e32 v171, v183, v171
	v_add_f32_e32 v185, v189, v172
	v_add_f32_e32 v189, v193, v174
	v_add_f32_e32 v191, v191, v175
	v_add_f32_e32 v184, v184, v198
	v_add_f32_e32 v182, v182, v199
	v_add_f32_e32 v183, v188, v200
	v_add_f32_e32 v187, v187, v173
	v_add_f32_e32 v188, v192, v203
	v_add_f32_e32 v190, v190, v205
	v_add_f32_e32 v193, v197, v176
	v_add_f32_e32 v195, v195, v177
	v_mul_f32_e32 v176, v170, v170
	v_mul_f32_e32 v177, v171, v171
	v_cvt_pk_bf16_f32 v172, v184, v170
	v_cvt_pk_bf16_f32 v173, v182, v171
	v_mul_f32_e32 v170, v189, v189
	v_mul_f32_e32 v171, v191, v191
	v_fmac_f32_e32 v170, v188, v188
	v_fmac_f32_e32 v171, v190, v190
	v_add_f32_e32 v192, v196, v206
	v_add_f32_e32 v170, v170, v171
	v_mul_f32_e32 v171, v193, v193
	v_mul_f32_e32 v196, v185, v185
	v_fmac_f32_e32 v176, v184, v184
	v_fmac_f32_e32 v177, v182, v182
	v_fmac_f32_e32 v171, v192, v192
	v_add_f32_e32 v186, v186, v201
	v_add_f32_e32 v194, v194, v207
	v_mul_f32_e32 v197, v187, v187
	v_fmac_f32_e32 v196, v183, v183
	v_add_f32_e32 v176, v176, v177
	v_add_f32_e32 v170, v171, v170
	v_mul_f32_e32 v171, v195, v195
	v_fmac_f32_e32 v197, v186, v186
	v_add_f32_e32 v176, v196, v176
	v_fmac_f32_e32 v171, v194, v194
	v_add_f32_e32 v176, v197, v176
	v_add_f32_e32 v170, v171, v170
	v_add_f32_e32 v171, v176, v170
	v_and_b32_e32 v176, 64, v202
	v_xor_b32_e32 v170, 16, v202
	v_add_u32_e32 v182, 64, v176
	v_cmp_lt_i32_e32 vcc, v170, v182
	v_cvt_pk_bf16_f32 v174, v183, v185
	v_lshl_add_u64 v[176:177], s[8:9], 0, v[180:181]
	v_lshl_add_u64 v[178:179], v[176:177], 0, v[178:179]
	v_cndmask_b32_e32 v170, v202, v170, vcc
	v_lshlrev_b32_e32 v170, 2, v170
	ds_bpermute_b32 v183, v170, v171
	v_cvt_pk_bf16_f32 v175, v186, v187
	global_store_dwordx4 v[178:179], v[172:175], off sc1
	s_waitcnt lgkmcnt(0)
	s_nop 0
	v_add_f32_e32 v172, v171, v183
	v_xor_b32_e32 v171, 32, v202
	v_cmp_lt_i32_e32 vcc, v171, v182
	v_cvt_pk_bf16_f32 v174, v188, v189
	v_cvt_pk_bf16_f32 v175, v190, v191
	v_cvt_pk_bf16_f32 v176, v192, v193
	v_cvt_pk_bf16_f32 v177, v194, v195
	global_store_dwordx4 v[178:179], v[174:177], off offset:256 sc1
	s_nop 0
	v_cndmask_b32_e32 v171, v202, v171, vcc
	v_lshlrev_b32_e32 v171, 2, v171
	ds_bpermute_b32 v173, v171, v172
	s_and_saveexec_b64 s[22:23], s[6:7]
	s_cbranch_execz .LBB0_2851
	v_lshlrev_b64 v[174:175], 7, v[156:157]
	v_lshl_add_u64 v[174:175], s[20:21], 0, v[174:175]
	s_waitcnt lgkmcnt(0)
	v_add_f32_e32 v157, v172, v173
	global_store_dword v[174:175], v157, off
; __device__ __forceinline__ unsigned cvt_pk_bf16(float lo, float hi) { unsigned r; asm volatile("v_cvt_pk_bf16_f32 %0, %1, %2" : "=v"(r) : "v"(lo), "v"(hi)); return r; }
;     __device__ __forceinline__ void operator()(const f32x4 (&acc)[2][2][4][2], const Unit& u, int wr, int wc, int fr, int fq) const {
;     ...
;             for (int m = 0; m < 4; ++m) { const int row = row0 + ai * HALF + m * 16; float ss = 0.f;
; #pragma unroll
;                 for (int bj = 0; bj < 2; ++bj) { const u32x4 ow = old[m][bj];
;                     f32x4 v0 = (acc[ai][bj][m][0] + bv[bj][0]) * accs, v1 = (acc[ai][bj][m][1] + bv[bj][1]) * accs;
;                     v0[0] += __uint_as_float(ow.x << 16); v0[1] += __uint_as_float(ow.x & 0xffff0000u); v0[2] += __uint_as_float(ow.y << 16); v0[3] += __uint_as_float(ow.y & 0xffff0000u);
;                     v1[0] += __uint_as_float(ow.z << 16); v1[1] += __uint_as_float(ow.z & 0xffff0000u); v1[2] += __uint_as_float(ow.w << 16); v1[3] += __uint_as_float(ow.w & 0xffff0000u);
;                     ss += (v0[0] * v0[0] + v0[1] * v0[1]) + (v0[2] * v0[2] + v0[3] * v0[3]) + (v1[0] * v1[0] + v1[1] * v1[1]) + (v1[2] * v1[2] + v1[3] * v1[3]);
;                     u32x4 w; w.x = cvt_pk_bf16(v0[0], v0[1]); w.y = cvt_pk_bf16(v0[2], v0[3]); w.z = cvt_pk_bf16(v1[0], v1[1]); w.w = cvt_pk_bf16(v1[2], v1[3]);
;                     *(u32x4*)(HB + (size_t)row * ldc + col0 + bj * HALF) = w; }
;                 ss += __shfl_xor(ss, 16); ss += __shfl_xor(ss, 32);
;                 if (fq == 0) ssp[(size_t)row * 32] = ss; }
.LBB0_2851:
	s_or_b64 exec, exec, s[22:23]
	v_pk_add_f32 v[108:109], v[108:109], 0 op_sel_hi:[1,0]
	v_lshlrev_b32_e32 v157, 16, v132
	v_and_b32_e32 v132, 0xffff0000, v132
	v_pk_add_f32 v[110:111], v[110:111], 0 op_sel_hi:[1,0]
	v_add_f32_e32 v109, v109, v132
	v_lshlrev_b32_e32 v132, 16, v133
	v_add_f32_e32 v110, v110, v132
	v_and_b32_e32 v132, 0xffff0000, v133
	v_pk_add_f32 v[104:105], v[104:105], 0 op_sel_hi:[1,0]
	v_add_f32_e32 v111, v111, v132
	v_lshlrev_b32_e32 v132, 16, v134
	v_add_f32_e32 v132, v104, v132
	v_and_b32_e32 v104, 0xffff0000, v134
	v_pk_add_f32 v[106:107], v[106:107], 0 op_sel_hi:[1,0]
	v_add_f32_e32 v133, v105, v104
	v_lshlrev_b32_e32 v104, 16, v135
	v_add_f32_e32 v134, v106, v104
	v_and_b32_e32 v104, 0xffff0000, v135
	v_add_f32_e32 v108, v108, v157
	v_add_f32_e32 v107, v107, v104
	v_mul_f32_e32 v104, v109, v109
	v_mul_f32_e32 v105, v111, v111
	v_fmac_f32_e32 v104, v108, v108
	v_fmac_f32_e32 v105, v110, v110
	v_add_f32_e32 v104, v104, v105
	v_mul_f32_e32 v105, v133, v133
	v_fmac_f32_e32 v105, v132, v132
	v_add_f32_e32 v104, v105, v104
	v_mul_f32_e32 v105, v107, v107
	v_fmac_f32_e32 v105, v134, v134
	v_add_f32_e32 v135, v105, v104
	v_cvt_pk_bf16_f32 v104, v108, v109
	v_pk_add_f32 v[100:101], v[100:101], 0 op_sel_hi:[1,0]
	v_lshlrev_b32_e32 v108, 16, v128
	v_add_f32_e32 v100, v100, v108
	v_and_b32_e32 v108, 0xffff0000, v128
	v_pk_add_f32 v[102:103], v[102:103], 0 op_sel_hi:[1,0]
	v_add_f32_e32 v101, v101, v108
	v_lshlrev_b32_e32 v108, 16, v129
	v_add_f32_e32 v108, v102, v108
	v_and_b32_e32 v102, 0xffff0000, v129
	v_pk_add_f32 v[96:97], v[96:97], 0 op_sel_hi:[1,0]
	v_add_f32_e32 v109, v103, v102
	v_lshlrev_b32_e32 v102, 16, v130
	v_cvt_pk_bf16_f32 v105, v110, v111
	v_add_f32_e32 v110, v96, v102
	v_and_b32_e32 v96, 0xffff0000, v130
	v_pk_add_f32 v[98:99], v[98:99], 0 op_sel_hi:[1,0]
	v_add_f32_e32 v111, v97, v96
	v_lshlrev_b32_e32 v96, 16, v131
	v_add_f32_e32 v128, v98, v96
	v_and_b32_e32 v96, 0xffff0000, v131
	v_add_f32_e32 v129, v99, v96
	v_mul_f32_e32 v96, v101, v101
	v_mul_f32_e32 v97, v109, v109
	v_fmac_f32_e32 v96, v100, v100
	v_fmac_f32_e32 v97, v108, v108
	v_add_f32_e32 v96, v96, v97
	v_mul_f32_e32 v97, v111, v111
	v_fmac_f32_e32 v97, v110, v110
	v_add_f32_e32 v96, v97, v96
	v_mul_f32_e32 v97, v129, v129
	v_fmac_f32_e32 v97, v128, v128
	v_add_f32_e32 v96, v97, v96
	v_add_f32_e32 v99, v135, v96
	ds_bpermute_b32 v130, v170, v99
	s_waitcnt lgkmcnt(1)
	v_lshlrev_b64 v[172:173], 11, v[162:163]
	v_lshl_add_u64 v[96:97], v[172:173], 1, s[8:9]
	v_lshl_add_u64 v[102:103], v[152:153], 1, v[96:97]
	v_cvt_pk_bf16_f32 v106, v132, v133
	s_waitcnt lgkmcnt(0)
	v_add_f32_e32 v96, v99, v130
	ds_bpermute_b32 v97, v171, v96
	v_cvt_pk_bf16_f32 v107, v134, v107
	global_store_dwordx4 v[102:103], v[104:107], off sc1
	v_cvt_pk_bf16_f32 v98, v100, v101
	v_cvt_pk_bf16_f32 v99, v108, v109
	v_cvt_pk_bf16_f32 v100, v110, v111
	v_cvt_pk_bf16_f32 v101, v128, v129
	global_store_dwordx4 v[102:103], v[98:101], off offset:256 sc1
	s_and_saveexec_b64 s[22:23], s[6:7]
	s_cbranch_execz .LBB0_2853
	v_lshlrev_b64 v[98:99], 7, v[162:163]
	v_lshl_add_u64 v[98:99], s[20:21], 0, v[98:99]
	s_waitcnt lgkmcnt(0)
	v_add_f32_e32 v96, v96, v97
	global_store_dword v[98:99], v96, off
.LBB0_2853:
	s_or_b64 exec, exec, s[22:23]
	v_pk_add_f32 v[92:93], v[92:93], 0 op_sel_hi:[1,0]
	v_lshlrev_b32_e32 v98, 16, v124
	v_add_f32_e32 v92, v92, v98
	v_and_b32_e32 v98, 0xffff0000, v124
	v_pk_add_f32 v[94:95], v[94:95], 0 op_sel_hi:[1,0]
	v_add_f32_e32 v93, v93, v98
	v_lshlrev_b32_e32 v98, 16, v125
	v_add_f32_e32 v94, v94, v98
	v_and_b32_e32 v98, 0xffff0000, v125
	v_pk_add_f32 v[88:89], v[88:89], 0 op_sel_hi:[1,0]
	v_add_f32_e32 v95, v95, v98
	v_lshlrev_b32_e32 v98, 16, v126
	v_add_f32_e32 v98, v88, v98
	v_and_b32_e32 v88, 0xffff0000, v126
	v_pk_add_f32 v[90:91], v[90:91], 0 op_sel_hi:[1,0]
	v_add_f32_e32 v99, v89, v88
	v_lshlrev_b32_e32 v88, 16, v127
	v_add_f32_e32 v100, v90, v88
	v_and_b32_e32 v88, 0xffff0000, v127
	v_add_f32_e32 v91, v91, v88
	v_mul_f32_e32 v88, v93, v93
	v_mul_f32_e32 v89, v95, v95
	v_fmac_f32_e32 v88, v92, v92
	v_fmac_f32_e32 v89, v94, v94
	v_add_f32_e32 v88, v88, v89
	v_mul_f32_e32 v89, v99, v99
	v_fmac_f32_e32 v89, v98, v98
	v_add_f32_e32 v88, v89, v88
	v_mul_f32_e32 v89, v91, v91
	v_fmac_f32_e32 v89, v100, v100
	v_add_f32_e32 v101, v89, v88
	v_cvt_pk_bf16_f32 v88, v92, v93
	v_pk_add_f32 v[84:85], v[84:85], 0 op_sel_hi:[1,0]
	v_lshlrev_b32_e32 v92, 16, v120
	v_add_f32_e32 v84, v84, v92
	v_and_b32_e32 v92, 0xffff0000, v120
	v_pk_add_f32 v[86:87], v[86:87], 0 op_sel_hi:[1,0]
	v_add_f32_e32 v85, v85, v92
	v_lshlrev_b32_e32 v92, 16, v121
	v_add_f32_e32 v92, v86, v92
	v_and_b32_e32 v86, 0xffff0000, v121
	v_pk_add_f32 v[80:81], v[80:81], 0 op_sel_hi:[1,0]
	v_add_f32_e32 v93, v87, v86
	v_lshlrev_b32_e32 v86, 16, v122
	v_cvt_pk_bf16_f32 v89, v94, v95
	v_add_f32_e32 v94, v80, v86
	v_and_b32_e32 v80, 0xffff0000, v122
	v_pk_add_f32 v[82:83], v[82:83], 0 op_sel_hi:[1,0]
	v_add_f32_e32 v95, v81, v80
	v_lshlrev_b32_e32 v80, 16, v123
	v_cvt_pk_bf16_f32 v90, v98, v99
	v_add_f32_e32 v98, v82, v80
	v_and_b32_e32 v80, 0xffff0000, v123
	v_add_f32_e32 v99, v83, v80
	v_mul_f32_e32 v80, v85, v85
	v_mul_f32_e32 v81, v93, v93
	v_fmac_f32_e32 v80, v84, v84
	v_fmac_f32_e32 v81, v92, v92
	v_add_f32_e32 v80, v80, v81
	v_mul_f32_e32 v81, v95, v95
	v_fmac_f32_e32 v81, v94, v94
	v_add_f32_e32 v80, v81, v80
	v_mul_f32_e32 v81, v99, v99
	v_fmac_f32_e32 v81, v98, v98
	v_add_f32_e32 v80, v81, v80
	v_add_f32_e32 v83, v101, v80
	v_cvt_pk_bf16_f32 v91, v100, v91
	ds_bpermute_b32 v100, v170, v83
	s_waitcnt lgkmcnt(1)
	v_lshlrev_b64 v[96:97], 11, v[160:161]
	v_lshl_add_u64 v[80:81], v[96:97], 1, s[8:9]
	v_lshl_add_u64 v[86:87], v[152:153], 1, v[80:81]
	global_store_dwordx4 v[86:87], v[88:91], off sc1
	s_waitcnt lgkmcnt(0)
	v_add_f32_e32 v80, v83, v100
	ds_bpermute_b32 v81, v171, v80
	v_cvt_pk_bf16_f32 v82, v84, v85
	v_cvt_pk_bf16_f32 v83, v92, v93
	v_cvt_pk_bf16_f32 v84, v94, v95
	v_cvt_pk_bf16_f32 v85, v98, v99
	global_store_dwordx4 v[86:87], v[82:85], off offset:256 sc1
	s_and_saveexec_b64 s[22:23], s[6:7]
	s_cbranch_execz .LBB0_2855
	v_lshlrev_b64 v[82:83], 7, v[160:161]
	v_lshl_add_u64 v[82:83], s[20:21], 0, v[82:83]
	s_waitcnt lgkmcnt(0)
	v_add_f32_e32 v80, v80, v81
	global_store_dword v[82:83], v80, off
; __device__ __forceinline__ unsigned cvt_pk_bf16(float lo, float hi) { unsigned r; asm volatile("v_cvt_pk_bf16_f32 %0, %1, %2" : "=v"(r) : "v"(lo), "v"(hi)); return r; }
;     __device__ __forceinline__ void operator()(const f32x4 (&acc)[2][2][4][2], const Unit& u, int wr, int wc, int fr, int fq) const {
;     ...
;         for (int ai = 0; ai < 2; ++ai) {
;             u32x4 old[4][2];
; #pragma unroll
;             for (int m = 0; m < 4; ++m)
; #pragma unroll
;                 for (int bj = 0; bj < 2; ++bj) old[m][bj] = *(const u32x4*)(HB + (size_t)(row0 + ai * HALF + m * 16) * ldc + col0 + bj * HALF);
; #pragma unroll
;             for (int m = 0; m < 4; ++m) { const int row = row0 + ai * HALF + m * 16; float ss = 0.f;
; #pragma unroll
;                 for (int bj = 0; bj < 2; ++bj) { const u32x4 ow = old[m][bj];
;                     f32x4 v0 = (acc[ai][bj][m][0] + bv[bj][0]) * accs, v1 = (acc[ai][bj][m][1] + bv[bj][1]) * accs;
;                     v0[0] += __uint_as_float(ow.x << 16); v0[1] += __uint_as_float(ow.x & 0xffff0000u); v0[2] += __uint_as_float(ow.y << 16); v0[3] += __uint_as_float(ow.y & 0xffff0000u);
;                     v1[0] += __uint_as_float(ow.z << 16); v1[1] += __uint_as_float(ow.z & 0xffff0000u); v1[2] += __uint_as_float(ow.w << 16); v1[3] += __uint_as_float(ow.w & 0xffff0000u);
;                     ss += (v0[0] * v0[0] + v0[1] * v0[1]) + (v0[2] * v0[2] + v0[3] * v0[3]) + (v1[0] * v1[0] + v1[1] * v1[1]) + (v1[2] * v1[2] + v1[3] * v1[3]);
;                     u32x4 w; w.x = cvt_pk_bf16(v0[0], v0[1]); w.y = cvt_pk_bf16(v0[2], v0[3]); w.z = cvt_pk_bf16(v1[0], v1[1]); w.w = cvt_pk_bf16(v1[2], v1[3]);
;                     *(u32x4*)(HB + (size_t)row * ldc + col0 + bj * HALF) = w; }
;                 ss += __shfl_xor(ss, 16); ss += __shfl_xor(ss, 32);
;                 if (fq == 0) ssp[(size_t)row * 32] = ss; }
.LBB0_2855:
	s_or_b64 exec, exec, s[22:23]
	v_pk_add_f32 v[76:77], v[76:77], 0 op_sel_hi:[1,0]
	v_lshlrev_b32_e32 v82, 16, v116
	v_add_f32_e32 v76, v76, v82
	v_and_b32_e32 v82, 0xffff0000, v116
	v_pk_add_f32 v[78:79], v[78:79], 0 op_sel_hi:[1,0]
	v_add_f32_e32 v77, v77, v82
	v_lshlrev_b32_e32 v82, 16, v117
	v_add_f32_e32 v78, v78, v82
	v_and_b32_e32 v82, 0xffff0000, v117
	v_pk_add_f32 v[72:73], v[72:73], 0 op_sel_hi:[1,0]
	v_add_f32_e32 v79, v79, v82
	v_lshlrev_b32_e32 v82, 16, v118
	v_add_f32_e32 v82, v72, v82
	v_and_b32_e32 v72, 0xffff0000, v118
	v_pk_add_f32 v[74:75], v[74:75], 0 op_sel_hi:[1,0]
	v_add_f32_e32 v83, v73, v72
	v_lshlrev_b32_e32 v72, 16, v119
	v_add_f32_e32 v84, v74, v72
	v_and_b32_e32 v72, 0xffff0000, v119
	v_add_f32_e32 v75, v75, v72
	v_mul_f32_e32 v72, v77, v77
	v_mul_f32_e32 v73, v79, v79
	v_fmac_f32_e32 v72, v76, v76
	v_fmac_f32_e32 v73, v78, v78
	v_add_f32_e32 v72, v72, v73
	v_mul_f32_e32 v73, v83, v83
	v_fmac_f32_e32 v73, v82, v82
	v_add_f32_e32 v72, v73, v72
	v_mul_f32_e32 v73, v75, v75
	v_fmac_f32_e32 v73, v84, v84
	v_add_f32_e32 v85, v73, v72
	v_cvt_pk_bf16_f32 v72, v76, v77
	v_pk_add_f32 v[68:69], v[68:69], 0 op_sel_hi:[1,0]
	v_lshlrev_b32_e32 v76, 16, v112
	v_add_f32_e32 v68, v68, v76
	v_and_b32_e32 v76, 0xffff0000, v112
	v_pk_add_f32 v[70:71], v[70:71], 0 op_sel_hi:[1,0]
	v_add_f32_e32 v69, v69, v76
	v_lshlrev_b32_e32 v76, 16, v113
	v_add_f32_e32 v76, v70, v76
	v_and_b32_e32 v70, 0xffff0000, v113
	v_pk_add_f32 v[64:65], v[64:65], 0 op_sel_hi:[1,0]
	v_add_f32_e32 v77, v71, v70
	v_lshlrev_b32_e32 v70, 16, v114
	v_cvt_pk_bf16_f32 v73, v78, v79
	v_add_f32_e32 v78, v64, v70
	v_and_b32_e32 v64, 0xffff0000, v114
	v_pk_add_f32 v[66:67], v[66:67], 0 op_sel_hi:[1,0]
	v_add_f32_e32 v79, v65, v64
	v_lshlrev_b32_e32 v64, 16, v115
	v_cvt_pk_bf16_f32 v74, v82, v83
	v_add_f32_e32 v82, v66, v64
	v_and_b32_e32 v64, 0xffff0000, v115
	v_add_f32_e32 v83, v67, v64
	v_mul_f32_e32 v64, v69, v69
	v_mul_f32_e32 v65, v77, v77
	v_fmac_f32_e32 v64, v68, v68
	v_fmac_f32_e32 v65, v76, v76
	v_add_f32_e32 v64, v64, v65
	v_mul_f32_e32 v65, v79, v79
	v_fmac_f32_e32 v65, v78, v78
	v_add_f32_e32 v64, v65, v64
	v_mul_f32_e32 v65, v83, v83
	v_fmac_f32_e32 v65, v82, v82
	v_add_f32_e32 v64, v65, v64
	v_add_f32_e32 v67, v85, v64
	v_cvt_pk_bf16_f32 v75, v84, v75
	ds_bpermute_b32 v84, v170, v67
	s_waitcnt lgkmcnt(1)
	v_lshlrev_b64 v[80:81], 11, v[158:159]
	v_lshl_add_u64 v[64:65], v[80:81], 1, s[8:9]
	v_lshl_add_u64 v[70:71], v[152:153], 1, v[64:65]
	global_store_dwordx4 v[70:71], v[72:75], off sc1
	s_waitcnt lgkmcnt(0)
	v_add_f32_e32 v64, v67, v84
	ds_bpermute_b32 v65, v171, v64
	v_cvt_pk_bf16_f32 v66, v68, v69
	v_cvt_pk_bf16_f32 v67, v76, v77
	v_cvt_pk_bf16_f32 v68, v78, v79
	v_cvt_pk_bf16_f32 v69, v82, v83
	global_store_dwordx4 v[70:71], v[66:69], off offset:256 sc1
	s_and_saveexec_b64 s[22:23], s[6:7]
	s_cbranch_execz .LBB0_2857
	v_lshlrev_b64 v[66:67], 7, v[158:159]
	v_lshl_add_u64 v[66:67], s[20:21], 0, v[66:67]
	s_waitcnt lgkmcnt(0)
	v_add_f32_e32 v64, v64, v65
	global_store_dword v[66:67], v64, off
.LBB0_2857:
	s_or_b64 exec, exec, s[22:23]
	v_add_u32_e32 v98, 0x80, v156
	v_ashrrev_i32_e32 v99, 31, v98
	v_lshlrev_b64 v[104:105], 12, v[98:99]
	s_waitcnt lgkmcnt(0)
	v_lshl_add_u64 v[64:65], v[154:155], 0, v[104:105]
	global_load_dwordx4 v[100:103], v[64:65], off
	global_load_dwordx4 v[88:91], v[64:65], off offset:256
	v_add_u32_e32 v96, 0x90, v156
	v_ashrrev_i32_e32 v97, 31, v96
	v_lshlrev_b64 v[64:65], 12, v[96:97]
	v_add_u32_e32 v94, 0xa0, v156
	v_lshl_add_u64 v[64:65], v[154:155], 0, v[64:65]
	v_ashrrev_i32_e32 v95, 31, v94
	global_load_dwordx4 v[84:87], v[64:65], off
	global_load_dwordx4 v[80:83], v[64:65], off offset:256
	v_lshlrev_b64 v[64:65], 12, v[94:95]
	v_add_u32_e32 v92, 0xb0, v156
	v_lshl_add_u64 v[64:65], v[154:155], 0, v[64:65]
	v_ashrrev_i32_e32 v93, 31, v92
	global_load_dwordx4 v[76:79], v[64:65], off
	global_load_dwordx4 v[72:75], v[64:65], off offset:256
	v_lshlrev_b64 v[64:65], 12, v[92:93]
	v_lshl_add_u64 v[64:65], v[154:155], 0, v[64:65]
	global_load_dwordx4 v[68:71], v[64:65], off
	s_nop 0
	global_load_dwordx4 v[64:67], v[64:65], off offset:256
	v_pk_add_f32 v[60:61], v[60:61], 0 op_sel_hi:[1,0]
	v_pk_add_f32 v[62:63], v[62:63], 0 op_sel_hi:[1,0]
	v_pk_add_f32 v[56:57], v[56:57], 0 op_sel_hi:[1,0]
	v_pk_add_f32 v[58:59], v[58:59], 0 op_sel_hi:[1,0]
	v_pk_add_f32 v[52:53], v[52:53], 0 op_sel_hi:[1,0]
	v_pk_add_f32 v[54:55], v[54:55], 0 op_sel_hi:[1,0]
	v_pk_add_f32 v[48:49], v[48:49], 0 op_sel_hi:[1,0]
	v_pk_add_f32 v[50:51], v[50:51], 0 op_sel_hi:[1,0]
	s_waitcnt vmcnt(7)
	v_lshlrev_b32_e32 v106, 16, v100
	v_and_b32_e32 v100, 0xffff0000, v100
	v_add_f32_e32 v61, v61, v100
	v_lshlrev_b32_e32 v100, 16, v101
	v_add_f32_e32 v62, v62, v100
	v_and_b32_e32 v100, 0xffff0000, v101
	v_add_f32_e32 v63, v63, v100
	v_lshlrev_b32_e32 v100, 16, v102
	v_add_f32_e32 v56, v56, v100
	v_and_b32_e32 v100, 0xffff0000, v102
	v_add_f32_e32 v57, v57, v100
	v_lshlrev_b32_e32 v100, 16, v103
	v_add_f32_e32 v100, v58, v100
	v_and_b32_e32 v58, 0xffff0000, v103
	v_add_f32_e32 v60, v60, v106
	v_add_f32_e32 v101, v59, v58
	v_mul_f32_e32 v58, v61, v61
	v_mul_f32_e32 v59, v63, v63
	v_fmac_f32_e32 v58, v60, v60
	v_fmac_f32_e32 v59, v62, v62
	v_add_f32_e32 v58, v58, v59
	v_mul_f32_e32 v59, v57, v57
	v_fmac_f32_e32 v59, v56, v56
	v_add_f32_e32 v58, v59, v58
	v_mul_f32_e32 v59, v101, v101
	v_fmac_f32_e32 v59, v100, v100
	v_add_f32_e32 v102, v59, v58
	v_cvt_pk_bf16_f32 v58, v60, v61
	v_cvt_pk_bf16_f32 v59, v62, v63
	v_cvt_pk_bf16_f32 v60, v56, v57
	v_lshl_add_u64 v[56:57], s[8:9], 0, v[104:105]
	v_lshl_add_u64 v[56:57], v[152:153], 1, v[56:57]
	v_cvt_pk_bf16_f32 v61, v100, v101
	global_store_dwordx4 v[56:57], v[58:61], off sc1
	s_waitcnt vmcnt(7)
	s_nop 0
	v_lshlrev_b32_e32 v58, 16, v88
	v_add_f32_e32 v52, v52, v58
	v_and_b32_e32 v58, 0xffff0000, v88
	v_add_f32_e32 v53, v53, v58
	v_lshlrev_b32_e32 v58, 16, v89
	v_add_f32_e32 v54, v54, v58
	v_and_b32_e32 v58, 0xffff0000, v89
	v_add_f32_e32 v55, v55, v58
	v_lshlrev_b32_e32 v58, 16, v90
	v_add_f32_e32 v58, v48, v58
	v_and_b32_e32 v48, 0xffff0000, v90
	v_add_f32_e32 v59, v49, v48
	v_lshlrev_b32_e32 v48, 16, v91
	v_add_f32_e32 v60, v50, v48
	v_and_b32_e32 v48, 0xffff0000, v91
	v_add_f32_e32 v51, v51, v48
	v_mul_f32_e32 v48, v53, v53
	v_mul_f32_e32 v49, v55, v55
	v_fmac_f32_e32 v48, v52, v52
	v_fmac_f32_e32 v49, v54, v54
	v_add_f32_e32 v48, v48, v49
	v_mul_f32_e32 v49, v59, v59
	v_fmac_f32_e32 v49, v58, v58
	v_add_f32_e32 v48, v49, v48
	v_mul_f32_e32 v49, v51, v51
	v_fmac_f32_e32 v49, v60, v60
	v_add_f32_e32 v48, v49, v48
	v_add_f32_e32 v61, v102, v48
	v_cvt_pk_bf16_f32 v48, v52, v53
	v_cvt_pk_bf16_f32 v49, v54, v55
	v_cvt_pk_bf16_f32 v50, v58, v59
	v_cvt_pk_bf16_f32 v51, v60, v51
	global_store_dwordx4 v[56:57], v[48:51], off offset:256 sc1
	ds_bpermute_b32 v48, v170, v61
	s_waitcnt lgkmcnt(0)
	v_add_f32_e32 v48, v61, v48
	ds_bpermute_b32 v49, v171, v48
	s_and_saveexec_b64 s[22:23], s[6:7]
	s_cbranch_execz .LBB0_2859
; __device__ __forceinline__ unsigned cvt_pk_bf16(float lo, float hi) { unsigned r; asm volatile("v_cvt_pk_bf16_f32 %0, %1, %2" : "=v"(r) : "v"(lo), "v"(hi)); return r; }
;     __device__ __forceinline__ void operator()(const f32x4 (&acc)[2][2][4][2], const Unit& u, int wr, int wc, int fr, int fq) const {
;     ...
;             for (int m = 0; m < 4; ++m) { const int row = row0 + ai * HALF + m * 16; float ss = 0.f;
; #pragma unroll
;                 for (int bj = 0; bj < 2; ++bj) { const u32x4 ow = old[m][bj];
;                     f32x4 v0 = (acc[ai][bj][m][0] + bv[bj][0]) * accs, v1 = (acc[ai][bj][m][1] + bv[bj][1]) * accs;
;                     v0[0] += __uint_as_float(ow.x << 16); v0[1] += __uint_as_float(ow.x & 0xffff0000u); v0[2] += __uint_as_float(ow.y << 16); v0[3] += __uint_as_float(ow.y & 0xffff0000u);
;                     v1[0] += __uint_as_float(ow.z << 16); v1[1] += __uint_as_float(ow.z & 0xffff0000u); v1[2] += __uint_as_float(ow.w << 16); v1[3] += __uint_as_float(ow.w & 0xffff0000u);
;                     ss += (v0[0] * v0[0] + v0[1] * v0[1]) + (v0[2] * v0[2] + v0[3] * v0[3]) + (v1[0] * v1[0] + v1[1] * v1[1]) + (v1[2] * v1[2] + v1[3] * v1[3]);
;                     u32x4 w; w.x = cvt_pk_bf16(v0[0], v0[1]); w.y = cvt_pk_bf16(v0[2], v0[3]); w.z = cvt_pk_bf16(v1[0], v1[1]); w.w = cvt_pk_bf16(v1[2], v1[3]);
;                     *(u32x4*)(HB + (size_t)row * ldc + col0 + bj * HALF) = w; }
;                 ss += __shfl_xor(ss, 16); ss += __shfl_xor(ss, 32);
;                 if (fq == 0) ssp[(size_t)row * 32] = ss; }
	v_lshlrev_b64 v[50:51], 7, v[98:99]
	v_lshl_add_u64 v[50:51], s[20:21], 0, v[50:51]
	s_waitcnt lgkmcnt(0)
	v_add_f32_e32 v48, v48, v49
	global_store_dword v[50:51], v48, off
.LBB0_2859:
	s_or_b64 exec, exec, s[22:23]
	v_pk_add_f32 v[44:45], v[44:45], 0 op_sel_hi:[1,0]
	s_waitcnt vmcnt(7)
	v_lshlrev_b32_e32 v50, 16, v84
	v_add_f32_e32 v44, v44, v50
	v_and_b32_e32 v50, 0xffff0000, v84
	v_pk_add_f32 v[46:47], v[46:47], 0 op_sel_hi:[1,0]
	v_add_f32_e32 v45, v45, v50
	v_lshlrev_b32_e32 v50, 16, v85
	v_add_f32_e32 v46, v46, v50
	v_and_b32_e32 v50, 0xffff0000, v85
	v_pk_add_f32 v[40:41], v[40:41], 0 op_sel_hi:[1,0]
	v_add_f32_e32 v47, v47, v50
	v_lshlrev_b32_e32 v50, 16, v86
	v_add_f32_e32 v50, v40, v50
	v_and_b32_e32 v40, 0xffff0000, v86
	v_pk_add_f32 v[42:43], v[42:43], 0 op_sel_hi:[1,0]
	v_add_f32_e32 v51, v41, v40
	v_lshlrev_b32_e32 v40, 16, v87
	v_add_f32_e32 v52, v42, v40
	v_and_b32_e32 v40, 0xffff0000, v87
	v_add_f32_e32 v43, v43, v40
	v_mul_f32_e32 v40, v45, v45
	v_mul_f32_e32 v41, v47, v47
	v_fmac_f32_e32 v40, v44, v44
	v_fmac_f32_e32 v41, v46, v46
	v_add_f32_e32 v40, v40, v41
	v_mul_f32_e32 v41, v51, v51
	v_fmac_f32_e32 v41, v50, v50
	v_add_f32_e32 v40, v41, v40
	v_mul_f32_e32 v41, v43, v43
	v_fmac_f32_e32 v41, v52, v52
	v_add_f32_e32 v53, v41, v40
	v_cvt_pk_bf16_f32 v40, v44, v45
	v_pk_add_f32 v[36:37], v[36:37], 0 op_sel_hi:[1,0]
	s_waitcnt vmcnt(6)
	v_lshlrev_b32_e32 v44, 16, v80
	v_add_f32_e32 v36, v36, v44
	v_and_b32_e32 v44, 0xffff0000, v80
	v_pk_add_f32 v[38:39], v[38:39], 0 op_sel_hi:[1,0]
	v_add_f32_e32 v37, v37, v44
	v_lshlrev_b32_e32 v44, 16, v81
	v_add_f32_e32 v44, v38, v44
	v_and_b32_e32 v38, 0xffff0000, v81
	v_pk_add_f32 v[32:33], v[32:33], 0 op_sel_hi:[1,0]
	v_add_f32_e32 v45, v39, v38
	v_lshlrev_b32_e32 v38, 16, v82
	v_cvt_pk_bf16_f32 v41, v46, v47
	v_add_f32_e32 v46, v32, v38
	v_and_b32_e32 v32, 0xffff0000, v82
	v_pk_add_f32 v[34:35], v[34:35], 0 op_sel_hi:[1,0]
	v_add_f32_e32 v47, v33, v32
	v_lshlrev_b32_e32 v32, 16, v83
	v_cvt_pk_bf16_f32 v42, v50, v51
	v_add_f32_e32 v50, v34, v32
	v_and_b32_e32 v32, 0xffff0000, v83
	v_add_f32_e32 v51, v35, v32
	v_mul_f32_e32 v32, v37, v37
	v_mul_f32_e32 v33, v45, v45
	v_fmac_f32_e32 v32, v36, v36
	v_fmac_f32_e32 v33, v44, v44
	v_add_f32_e32 v32, v32, v33
	v_mul_f32_e32 v33, v47, v47
	v_fmac_f32_e32 v33, v46, v46
	v_add_f32_e32 v32, v33, v32
	v_mul_f32_e32 v33, v51, v51
	v_fmac_f32_e32 v33, v50, v50
	v_add_f32_e32 v32, v33, v32
	v_add_f32_e32 v35, v53, v32
	v_cvt_pk_bf16_f32 v43, v52, v43
	ds_bpermute_b32 v52, v170, v35
	s_waitcnt lgkmcnt(1)
	v_lshlrev_b64 v[48:49], 11, v[96:97]
	v_lshl_add_u64 v[32:33], v[48:49], 1, s[8:9]
	v_lshl_add_u64 v[38:39], v[152:153], 1, v[32:33]
	global_store_dwordx4 v[38:39], v[40:43], off sc1
	s_waitcnt lgkmcnt(0)
	v_add_f32_e32 v32, v35, v52
	ds_bpermute_b32 v33, v171, v32
	v_cvt_pk_bf16_f32 v34, v36, v37
	v_cvt_pk_bf16_f32 v35, v44, v45
	v_cvt_pk_bf16_f32 v36, v46, v47
	v_cvt_pk_bf16_f32 v37, v50, v51
	global_store_dwordx4 v[38:39], v[34:37], off offset:256 sc1
	s_and_saveexec_b64 s[22:23], s[6:7]
	s_cbranch_execz .LBB0_2861
	v_lshlrev_b64 v[34:35], 7, v[96:97]
	v_lshl_add_u64 v[34:35], s[20:21], 0, v[34:35]
	s_waitcnt lgkmcnt(0)
	v_add_f32_e32 v32, v32, v33
	global_store_dword v[34:35], v32, off
; __device__ __forceinline__ unsigned cvt_pk_bf16(float lo, float hi) { unsigned r; asm volatile("v_cvt_pk_bf16_f32 %0, %1, %2" : "=v"(r) : "v"(lo), "v"(hi)); return r; }
;     __device__ __forceinline__ void operator()(const f32x4 (&acc)[2][2][4][2], const Unit& u, int wr, int wc, int fr, int fq) const {
;     ...
;             for (int m = 0; m < 4; ++m) { const int row = row0 + ai * HALF + m * 16; float ss = 0.f;
; #pragma unroll
;                 for (int bj = 0; bj < 2; ++bj) { const u32x4 ow = old[m][bj];
;                     f32x4 v0 = (acc[ai][bj][m][0] + bv[bj][0]) * accs, v1 = (acc[ai][bj][m][1] + bv[bj][1]) * accs;
;                     v0[0] += __uint_as_float(ow.x << 16); v0[1] += __uint_as_float(ow.x & 0xffff0000u); v0[2] += __uint_as_float(ow.y << 16); v0[3] += __uint_as_float(ow.y & 0xffff0000u);
;                     v1[0] += __uint_as_float(ow.z << 16); v1[1] += __uint_as_float(ow.z & 0xffff0000u); v1[2] += __uint_as_float(ow.w << 16); v1[3] += __uint_as_float(ow.w & 0xffff0000u);
;                     ss += (v0[0] * v0[0] + v0[1] * v0[1]) + (v0[2] * v0[2] + v0[3] * v0[3]) + (v1[0] * v1[0] + v1[1] * v1[1]) + (v1[2] * v1[2] + v1[3] * v1[3]);
;                     u32x4 w; w.x = cvt_pk_bf16(v0[0], v0[1]); w.y = cvt_pk_bf16(v0[2], v0[3]); w.z = cvt_pk_bf16(v1[0], v1[1]); w.w = cvt_pk_bf16(v1[2], v1[3]);
;                     *(u32x4*)(HB + (size_t)row * ldc + col0 + bj * HALF) = w; }
;                 ss += __shfl_xor(ss, 16); ss += __shfl_xor(ss, 32);
;                 if (fq == 0) ssp[(size_t)row * 32] = ss; }
.LBB0_2861:
	s_or_b64 exec, exec, s[22:23]
	v_pk_add_f32 v[28:29], v[28:29], 0 op_sel_hi:[1,0]
	s_waitcnt vmcnt(7)
	v_lshlrev_b32_e32 v34, 16, v76
	v_add_f32_e32 v28, v28, v34
	v_and_b32_e32 v34, 0xffff0000, v76
	v_pk_add_f32 v[30:31], v[30:31], 0 op_sel_hi:[1,0]
	v_add_f32_e32 v29, v29, v34
	v_lshlrev_b32_e32 v34, 16, v77
	v_add_f32_e32 v30, v30, v34
	v_and_b32_e32 v34, 0xffff0000, v77
	v_pk_add_f32 v[24:25], v[24:25], 0 op_sel_hi:[1,0]
	v_add_f32_e32 v31, v31, v34
	v_lshlrev_b32_e32 v34, 16, v78
	v_add_f32_e32 v34, v24, v34
	v_and_b32_e32 v24, 0xffff0000, v78
	v_pk_add_f32 v[26:27], v[26:27], 0 op_sel_hi:[1,0]
	v_add_f32_e32 v35, v25, v24
	v_lshlrev_b32_e32 v24, 16, v79
	v_add_f32_e32 v36, v26, v24
	v_and_b32_e32 v24, 0xffff0000, v79
	v_add_f32_e32 v27, v27, v24
	v_mul_f32_e32 v24, v29, v29
	v_mul_f32_e32 v25, v31, v31
	v_fmac_f32_e32 v24, v28, v28
	v_fmac_f32_e32 v25, v30, v30
	v_add_f32_e32 v24, v24, v25
	v_mul_f32_e32 v25, v35, v35
	v_fmac_f32_e32 v25, v34, v34
	v_add_f32_e32 v24, v25, v24
	v_mul_f32_e32 v25, v27, v27
	v_fmac_f32_e32 v25, v36, v36
	v_add_f32_e32 v37, v25, v24
	v_cvt_pk_bf16_f32 v24, v28, v29
	v_pk_add_f32 v[20:21], v[20:21], 0 op_sel_hi:[1,0]
	s_waitcnt vmcnt(6)
	v_lshlrev_b32_e32 v28, 16, v72
	v_add_f32_e32 v20, v20, v28
	v_and_b32_e32 v28, 0xffff0000, v72
	v_pk_add_f32 v[22:23], v[22:23], 0 op_sel_hi:[1,0]
	v_add_f32_e32 v21, v21, v28
	v_lshlrev_b32_e32 v28, 16, v73
	v_add_f32_e32 v28, v22, v28
	v_and_b32_e32 v22, 0xffff0000, v73
	v_pk_add_f32 v[16:17], v[16:17], 0 op_sel_hi:[1,0]
	v_add_f32_e32 v29, v23, v22
	v_lshlrev_b32_e32 v22, 16, v74
	v_cvt_pk_bf16_f32 v25, v30, v31
	v_add_f32_e32 v30, v16, v22
	v_and_b32_e32 v16, 0xffff0000, v74
	v_pk_add_f32 v[18:19], v[18:19], 0 op_sel_hi:[1,0]
	v_add_f32_e32 v31, v17, v16
	v_lshlrev_b32_e32 v16, 16, v75
	v_cvt_pk_bf16_f32 v26, v34, v35
	v_add_f32_e32 v34, v18, v16
	v_and_b32_e32 v16, 0xffff0000, v75
	v_add_f32_e32 v35, v19, v16
	v_mul_f32_e32 v16, v21, v21
	v_mul_f32_e32 v17, v29, v29
	v_fmac_f32_e32 v16, v20, v20
	v_fmac_f32_e32 v17, v28, v28
	v_add_f32_e32 v16, v16, v17
	v_mul_f32_e32 v17, v31, v31
	v_fmac_f32_e32 v17, v30, v30
	v_add_f32_e32 v16, v17, v16
	v_mul_f32_e32 v17, v35, v35
	v_fmac_f32_e32 v17, v34, v34
	v_add_f32_e32 v16, v17, v16
	v_add_f32_e32 v19, v37, v16
	v_cvt_pk_bf16_f32 v27, v36, v27
	ds_bpermute_b32 v36, v170, v19
	s_waitcnt lgkmcnt(1)
	v_lshlrev_b64 v[32:33], 11, v[94:95]
	v_lshl_add_u64 v[16:17], v[32:33], 1, s[8:9]
	v_lshl_add_u64 v[22:23], v[152:153], 1, v[16:17]
	global_store_dwordx4 v[22:23], v[24:27], off sc1
	s_waitcnt lgkmcnt(0)
	v_add_f32_e32 v16, v19, v36
	ds_bpermute_b32 v17, v171, v16
	v_cvt_pk_bf16_f32 v18, v20, v21
	v_cvt_pk_bf16_f32 v19, v28, v29
	v_cvt_pk_bf16_f32 v20, v30, v31
	v_cvt_pk_bf16_f32 v21, v34, v35
	global_store_dwordx4 v[22:23], v[18:21], off offset:256 sc1
	s_and_saveexec_b64 s[22:23], s[6:7]
	s_cbranch_execz .LBB0_2863
	v_lshlrev_b64 v[18:19], 7, v[94:95]
	v_lshl_add_u64 v[18:19], s[20:21], 0, v[18:19]
	s_waitcnt lgkmcnt(0)
	v_add_f32_e32 v16, v16, v17
	global_store_dword v[18:19], v16, off
.LBB0_2863:
	s_or_b64 exec, exec, s[22:23]
	v_pk_add_f32 v[12:13], v[12:13], 0 op_sel_hi:[1,0]
	s_waitcnt vmcnt(7)
	v_lshlrev_b32_e32 v18, 16, v68
	v_add_f32_e32 v12, v12, v18
	v_and_b32_e32 v18, 0xffff0000, v68
	v_pk_add_f32 v[14:15], v[14:15], 0 op_sel_hi:[1,0]
	v_add_f32_e32 v13, v13, v18
	v_lshlrev_b32_e32 v18, 16, v69
	v_add_f32_e32 v14, v14, v18
	v_and_b32_e32 v18, 0xffff0000, v69
	v_pk_add_f32 v[8:9], v[8:9], 0 op_sel_hi:[1,0]
	v_add_f32_e32 v15, v15, v18
	v_lshlrev_b32_e32 v18, 16, v70
	v_add_f32_e32 v18, v8, v18
	v_and_b32_e32 v8, 0xffff0000, v70
	v_pk_add_f32 v[10:11], v[10:11], 0 op_sel_hi:[1,0]
	v_add_f32_e32 v19, v9, v8
	v_lshlrev_b32_e32 v8, 16, v71
	v_add_f32_e32 v20, v10, v8
	v_and_b32_e32 v8, 0xffff0000, v71
	v_add_f32_e32 v11, v11, v8
	v_mul_f32_e32 v8, v13, v13
	v_mul_f32_e32 v9, v15, v15
	v_fmac_f32_e32 v8, v12, v12
	v_fmac_f32_e32 v9, v14, v14
	v_add_f32_e32 v8, v8, v9
	v_mul_f32_e32 v9, v19, v19
	v_fmac_f32_e32 v9, v18, v18
	v_add_f32_e32 v8, v9, v8
	v_mul_f32_e32 v9, v11, v11
	v_fmac_f32_e32 v9, v20, v20
	v_add_f32_e32 v21, v9, v8
	v_cvt_pk_bf16_f32 v8, v12, v13
	v_pk_add_f32 v[4:5], v[4:5], 0 op_sel_hi:[1,0]
	s_waitcnt vmcnt(6)
	v_lshlrev_b32_e32 v12, 16, v64
	v_add_f32_e32 v4, v4, v12
	v_and_b32_e32 v12, 0xffff0000, v64
	v_pk_add_f32 v[6:7], v[6:7], 0 op_sel_hi:[1,0]
	v_add_f32_e32 v5, v5, v12
	v_lshlrev_b32_e32 v12, 16, v65
	v_add_f32_e32 v12, v6, v12
	v_and_b32_e32 v6, 0xffff0000, v65
	v_pk_add_f32 v[0:1], v[0:1], 0 op_sel_hi:[1,0]
	v_add_f32_e32 v13, v7, v6
	v_lshlrev_b32_e32 v6, 16, v66
	v_cvt_pk_bf16_f32 v9, v14, v15
	v_add_f32_e32 v14, v0, v6
	v_and_b32_e32 v0, 0xffff0000, v66
	v_pk_add_f32 v[2:3], v[2:3], 0 op_sel_hi:[1,0]
	v_add_f32_e32 v15, v1, v0
	v_lshlrev_b32_e32 v0, 16, v67
	v_cvt_pk_bf16_f32 v10, v18, v19
	v_add_f32_e32 v18, v2, v0
	v_and_b32_e32 v0, 0xffff0000, v67
	v_add_f32_e32 v19, v3, v0
	v_mul_f32_e32 v0, v5, v5
	v_mul_f32_e32 v1, v13, v13
	v_fmac_f32_e32 v0, v4, v4
	v_fmac_f32_e32 v1, v12, v12
	v_add_f32_e32 v0, v0, v1
	v_mul_f32_e32 v1, v15, v15
	v_fmac_f32_e32 v1, v14, v14
	v_add_f32_e32 v0, v1, v0
	v_mul_f32_e32 v1, v19, v19
	v_fmac_f32_e32 v1, v18, v18
	v_add_f32_e32 v0, v1, v0
	v_add_f32_e32 v3, v21, v0
	v_cvt_pk_bf16_f32 v11, v20, v11
	ds_bpermute_b32 v20, v170, v3
	s_waitcnt lgkmcnt(1)
	v_lshlrev_b64 v[16:17], 11, v[92:93]
	v_lshl_add_u64 v[0:1], v[16:17], 1, s[8:9]
	v_lshl_add_u64 v[6:7], v[152:153], 1, v[0:1]
	global_store_dwordx4 v[6:7], v[8:11], off sc1
	s_waitcnt lgkmcnt(0)
	v_add_f32_e32 v0, v3, v20
	ds_bpermute_b32 v1, v171, v0
	v_cvt_pk_bf16_f32 v2, v4, v5
	v_cvt_pk_bf16_f32 v3, v12, v13
	v_cvt_pk_bf16_f32 v4, v14, v15
	v_cvt_pk_bf16_f32 v5, v18, v19
	global_store_dwordx4 v[6:7], v[2:5], off offset:256 sc1
	s_and_saveexec_b64 s[22:23], s[6:7]
	s_cbranch_execz .LBB0_2865
	v_lshlrev_b64 v[2:3], 7, v[92:93]
	v_lshl_add_u64 v[2:3], s[20:21], 0, v[2:3]
	s_waitcnt lgkmcnt(0)
	v_add_f32_e32 v0, v0, v1
	global_store_dword v[2:3], v0, off

; __device__ __forceinline__ unsigned cvt_pk_bf16(float lo, float hi) { unsigned r; asm volatile("v_cvt_pk_bf16_f32 %0, %1, %2" : "=v"(r) : "v"(lo), "v"(hi)); return r; }
; __device__ __forceinline__ float dpp_up1(float x) { return __builtin_bit_cast(float, __builtin_amdgcn_update_dpp(0, __builtin_bit_cast(int, x), 0x111, 0xf, 0xf, true)); }
;     __device__ __forceinline__ void operator()(const f32x4 (&acc)[2][2][4][2], const Unit& u, int wr, int wc, int fr, int fq) const {
;     ...
;                 f32x4 pg2, pg3, pv2, pv3;
; #pragma unroll
;                 for (int e = 0; e < 4; ++e) { pg2[e] = dpp_up1(xg[2][e]); pg3[e] = dpp_up1(xg[3][e]); pv2[e] = dpp_up1(xv[2][e]); pv3[e] = dpp_up1(xv[3][e]); }
; #pragma unroll
;                 for (int m = 0; m < 4; ++m) {
;                     u32x2_t w; float o[4];
; #pragma unroll
;                     for (int e = 0; e < 4; ++e) {
;                         const float g1 = m >= 1 ? xg[m - (m >= 1 ? 1 : 0)][e] : pg3[e], g2 = m >= 2 ? xg[m - (m >= 2 ? 2 : 0)][e] : (m == 1 ? pg3[e] : pg2[e]);
;                         const float v1 = m >= 1 ? xv[m - (m >= 1 ? 1 : 0)][e] : pv3[e], v2 = m >= 2 ? xv[m - (m >= 2 ? 2 : 0)][e] : (m == 1 ? pv3[e] : pv2[e]);
;                         const float cg_ = bg[e] + w0g[e] * g2 + w1g[e] * g1 + w2g[e] * xg[m][e];
;                         const float cv_ = bv[e] + w0v[e] * v2 + w1v[e] * v1 + w2v[e] * xv[m][e];
;                         o[e] = cg_ * __builtin_amdgcn_rcpf(1.0f + __expf(-cg_)) * cv_;
;                     }
;                     w.x = cvt_pk_bf16(o[0], o[1]); w.y = cvt_pk_bf16(o[2], o[3]);
;                     const int g = g0 + m;
;                     if (n == 0) stash[ai][m] = w;
;                     else if ((fr > 0 || m >= 2) && g < TT) { u32x4 ww; ww.x = stash[ai][m].x; ww.y = stash[ai][m].y; ww.z = w.x; ww.w = w.y; *(u32x4*)(G + (size_t)g * DFF_ + f0 - 4) = ww; }
.LBB0_2943:
	v_mov_b32_dpp v112, v58 row_shr:1 row_mask:0xf bank_mask:0xf bound_ctrl:1
	v_mov_b32_dpp v125, v44 row_shr:1 row_mask:0xf bank_mask:0xf bound_ctrl:1
	s_waitcnt vmcnt(4)
	v_fma_f32 v112, v98, v112, v70
	v_fmac_f32_e32 v112, v90, v125
	v_fmac_f32_e32 v112, v94, v116
	v_mul_f32_e32 v132, 0xbfb8aa3b, v112
	v_exp_f32_e32 v132, v132
	v_mov_b32_dpp v113, v52 row_shr:1 row_mask:0xf bank_mask:0xf bound_ctrl:1
	v_mov_b32_dpp v123, v38 row_shr:1 row_mask:0xf bank_mask:0xf bound_ctrl:1
	s_waitcnt vmcnt(0)
	v_fma_f32 v113, v74, v113, v86
	v_add_f32_e32 v132, 1.0, v132
	v_rcp_f32_e32 v132, v132
	v_fmac_f32_e32 v113, v78, v123
	v_mov_b32_dpp v126, v59 row_shr:1 row_mask:0xf bank_mask:0xf bound_ctrl:1
	v_fmac_f32_e32 v113, v82, v68
	v_mul_f32_e32 v112, v112, v132
	v_mov_b32_dpp v121, v45 row_shr:1 row_mask:0xf bank_mask:0xf bound_ctrl:1
	v_mul_f32_e32 v112, v113, v112
	v_fma_f32 v113, v99, v126, v71
	v_fmac_f32_e32 v113, v91, v121
	v_mov_b32_dpp v127, v53 row_shr:1 row_mask:0xf bank_mask:0xf bound_ctrl:1
	v_fmac_f32_e32 v113, v95, v117
	v_fma_f32 v126, v75, v127, v87
	v_mul_f32_e32 v127, 0xbfb8aa3b, v113
	v_exp_f32_e32 v127, v127
	v_mov_b32_dpp v119, v39 row_shr:1 row_mask:0xf bank_mask:0xf bound_ctrl:1
	v_fmac_f32_e32 v126, v79, v119
	v_mov_b32_dpp v128, v42 row_shr:1 row_mask:0xf bank_mask:0xf bound_ctrl:1
	v_add_f32_e32 v127, 1.0, v127
	v_rcp_f32_e32 v127, v127
	v_fmac_f32_e32 v126, v83, v69
	v_mov_b32_dpp v55, v32 row_shr:1 row_mask:0xf bank_mask:0xf bound_ctrl:1
	v_mov_b32_dpp v129, v36 row_shr:1 row_mask:0xf bank_mask:0xf bound_ctrl:1
	v_mul_f32_e32 v113, v113, v127
	v_mul_f32_e32 v113, v126, v113
	v_fma_f32 v126, v100, v128, v72
	v_fmac_f32_e32 v126, v92, v55
	v_fmac_f32_e32 v126, v96, v62
	v_mul_f32_e32 v128, 0xbfb8aa3b, v126
	v_exp_f32_e32 v128, v128
	v_mov_b32_dpp v54, v34 row_shr:1 row_mask:0xf bank_mask:0xf bound_ctrl:1
	v_fma_f32 v127, v76, v129, v88
	v_fmac_f32_e32 v127, v80, v54
	v_add_f32_e32 v128, 1.0, v128
	v_rcp_f32_e32 v128, v128
	v_mov_b32_dpp v130, v43 row_shr:1 row_mask:0xf bank_mask:0xf bound_ctrl:1
	v_fmac_f32_e32 v127, v84, v60
	v_mov_b32_dpp v47, v33 row_shr:1 row_mask:0xf bank_mask:0xf bound_ctrl:1
	v_mul_f32_e32 v126, v126, v128
	v_mul_f32_e32 v126, v127, v126
	v_fma_f32 v127, v101, v130, v73
	v_fmac_f32_e32 v127, v93, v47
	v_fmac_f32_e32 v127, v97, v63
	v_mul_f32_e32 v129, 0xbfb8aa3b, v127
	v_exp_f32_e32 v129, v129
	v_mov_b32_dpp v131, v37 row_shr:1 row_mask:0xf bank_mask:0xf bound_ctrl:1
	v_mov_b32_dpp v46, v35 row_shr:1 row_mask:0xf bank_mask:0xf bound_ctrl:1
	v_fma_f32 v128, v77, v131, v89
	v_add_f32_e32 v129, 1.0, v129
	v_rcp_f32_e32 v129, v129
	v_fmac_f32_e32 v128, v81, v46
	v_cmp_gt_i32_e32 vcc, s79, v215
	v_fmac_f32_e32 v128, v85, v61
	v_mul_f32_e32 v127, v127, v129
	s_and_b64 s[2:3], s[6:7], vcc
	v_mul_f32_e32 v127, v128, v127
	v_cvt_pk_bf16_f32 v112, v112, v113
	v_cvt_pk_bf16_f32 v113, v126, v127
	s_and_saveexec_b64 s[0:1], s[2:3]
	s_cbranch_execz .LBB0_2945
	v_mov_b64_e32 v[126:127], s[12:13]
	v_mad_i64_i32 v[126:127], s[2:3], v215, s86, v[126:127]
	v_lshl_add_u64 v[126:127], v[178:179], 1, v[126:127]
	global_store_dwordx4 v[126:127], v[110:113], off sc1
.LBB0_2945:
	s_or_b64 exec, exec, s[0:1]
	s_nop 0
	v_fma_f32 v110, v98, v125, v70
	v_fmac_f32_e32 v110, v90, v116
	v_fmac_f32_e32 v110, v94, v56
	v_mul_f32_e32 v112, 0xbfb8aa3b, v110
	v_exp_f32_e32 v112, v112
	v_fma_f32 v111, v74, v123, v86
	v_fmac_f32_e32 v111, v78, v68
	v_fmac_f32_e32 v111, v82, v50
	v_add_f32_e32 v112, 1.0, v112
	v_rcp_f32_e32 v112, v112
	v_fma_f32 v55, v100, v55, v72
	v_fmac_f32_e32 v55, v92, v62
	v_fmac_f32_e32 v55, v96, v48
	v_mul_f32_e32 v110, v110, v112
	v_mul_f32_e32 v110, v111, v110
	v_fma_f32 v111, v99, v121, v71
	v_fmac_f32_e32 v111, v91, v117
	v_fmac_f32_e32 v111, v95, v57
	v_mul_f32_e32 v113, 0xbfb8aa3b, v111
	v_exp_f32_e32 v113, v113
	v_fma_f32 v112, v75, v119, v87
	v_fmac_f32_e32 v112, v79, v69
	v_fmac_f32_e32 v112, v83, v51
	v_add_f32_e32 v113, 1.0, v113
	v_rcp_f32_e32 v113, v113
	v_fma_f32 v54, v76, v54, v88
	v_fma_f32 v47, v101, v47, v73
	v_fmac_f32_e32 v54, v80, v60
	v_mul_f32_e32 v111, v111, v113
	v_mul_f32_e32 v111, v112, v111
	v_mul_f32_e32 v112, 0xbfb8aa3b, v55
	v_exp_f32_e32 v112, v112
	v_fmac_f32_e32 v47, v93, v63
	v_fmac_f32_e32 v54, v84, v40
	v_fmac_f32_e32 v47, v97, v49
	v_add_f32_e32 v112, 1.0, v112
	v_rcp_f32_e32 v112, v112
	v_fma_f32 v46, v77, v46, v89
	v_fmac_f32_e32 v46, v81, v61
	v_cmp_gt_i32_e32 vcc, s79, v218
	v_mul_f32_e32 v55, v55, v112
	v_mul_f32_e32 v54, v54, v55
	v_mul_f32_e32 v55, 0xbfb8aa3b, v47
	v_exp_f32_e32 v55, v55
	v_fmac_f32_e32 v46, v85, v41
	s_and_b64 s[2:3], s[6:7], vcc
	v_cvt_pk_bf16_f32 v110, v110, v111
	v_add_f32_e32 v55, 1.0, v55
	v_rcp_f32_e32 v55, v55
	s_nop 0
	v_mul_f32_e32 v47, v47, v55
	v_mul_f32_e32 v46, v46, v47
	v_cvt_pk_bf16_f32 v111, v54, v46
	s_and_saveexec_b64 s[0:1], s[2:3]
	s_cbranch_execz .LBB0_2947
	v_mov_b64_e32 v[46:47], s[12:13]
	v_mad_i64_i32 v[46:47], s[2:3], v218, s86, v[46:47]
	v_lshl_add_u64 v[46:47], v[178:179], 1, v[46:47]
	global_store_dwordx4 v[46:47], v[108:111], off sc1
; __device__ __forceinline__ unsigned cvt_pk_bf16(float lo, float hi) { unsigned r; asm volatile("v_cvt_pk_bf16_f32 %0, %1, %2" : "=v"(r) : "v"(lo), "v"(hi)); return r; }
;     __device__ __forceinline__ void operator()(const f32x4 (&acc)[2][2][4][2], const Unit& u, int wr, int wc, int fr, int fq) const {
;     ...
;                 for (int m = 0; m < 4; ++m) {
;                     u32x2_t w; float o[4];
; #pragma unroll
;                     for (int e = 0; e < 4; ++e) {
;                         const float g1 = m >= 1 ? xg[m - (m >= 1 ? 1 : 0)][e] : pg3[e], g2 = m >= 2 ? xg[m - (m >= 2 ? 2 : 0)][e] : (m == 1 ? pg3[e] : pg2[e]);
;                         const float v1 = m >= 1 ? xv[m - (m >= 1 ? 1 : 0)][e] : pv3[e], v2 = m >= 2 ? xv[m - (m >= 2 ? 2 : 0)][e] : (m == 1 ? pv3[e] : pv2[e]);
;                         const float cg_ = bg[e] + w0g[e] * g2 + w1g[e] * g1 + w2g[e] * xg[m][e];
;                         const float cv_ = bv[e] + w0v[e] * v2 + w1v[e] * v1 + w2v[e] * xv[m][e];
;                         o[e] = cg_ * __builtin_amdgcn_rcpf(1.0f + __expf(-cg_)) * cv_;
;                     }
;                     w.x = cvt_pk_bf16(o[0], o[1]); w.y = cvt_pk_bf16(o[2], o[3]);
;                     const int g = g0 + m;
;                     if (n == 0) stash[ai][m] = w;
;                     else if ((fr > 0 || m >= 2) && g < TT) { u32x4 ww; ww.x = stash[ai][m].x; ww.y = stash[ai][m].y; ww.z = w.x; ww.w = w.y; *(u32x4*)(G + (size_t)g * DFF_ + f0 - 4) = ww; }
.LBB0_2947:
	s_or_b64 exec, exec, s[0:1]
	v_fma_f32 v46, v98, v116, v70
	v_fmac_f32_e32 v46, v90, v56
	v_fmac_f32_e32 v46, v94, v58
	v_mul_f32_e32 v54, 0xbfb8aa3b, v46
	v_exp_f32_e32 v54, v54
	v_fma_f32 v47, v74, v68, v86
	v_fmac_f32_e32 v47, v78, v50
	v_fmac_f32_e32 v47, v82, v52
	v_add_f32_e32 v54, 1.0, v54
	v_rcp_f32_e32 v54, v54
	v_cmp_gt_i32_e32 vcc, s87, v215
	v_mul_f32_e32 v46, v46, v54
	v_mul_f32_e32 v46, v47, v46
	v_fma_f32 v47, v99, v117, v71
	v_fmac_f32_e32 v47, v91, v57
	v_fmac_f32_e32 v47, v95, v59
	v_mul_f32_e32 v55, 0xbfb8aa3b, v47
	v_exp_f32_e32 v55, v55
	v_fma_f32 v54, v75, v69, v87
	v_fmac_f32_e32 v54, v79, v51
	v_fmac_f32_e32 v54, v83, v53
	v_add_f32_e32 v55, 1.0, v55
	v_rcp_f32_e32 v55, v55
	s_nop 0
	v_mul_f32_e32 v47, v47, v55
	v_mul_f32_e32 v47, v54, v47
	v_fma_f32 v54, v100, v62, v72
	v_fmac_f32_e32 v54, v92, v48
	v_fmac_f32_e32 v54, v96, v42
	v_fma_f32 v55, v76, v60, v88
	v_mul_f32_e32 v60, 0xbfb8aa3b, v54
	v_exp_f32_e32 v60, v60
	v_fmac_f32_e32 v55, v80, v40
	v_fmac_f32_e32 v55, v84, v36
	v_cvt_pk_bf16_f32 v108, v46, v47
	v_add_f32_e32 v60, 1.0, v60
	v_rcp_f32_e32 v60, v60
	s_nop 0
	v_mul_f32_e32 v54, v54, v60
	v_mul_f32_e32 v54, v55, v54
	v_fma_f32 v55, v101, v63, v73
	v_fmac_f32_e32 v55, v93, v49
	v_fmac_f32_e32 v55, v97, v43
	v_fma_f32 v60, v77, v61, v89
	v_mul_f32_e32 v61, 0xbfb8aa3b, v55
	v_exp_f32_e32 v61, v61
	v_fmac_f32_e32 v60, v81, v41
	v_fmac_f32_e32 v60, v85, v37
	v_add_f32_e32 v61, 1.0, v61
	v_rcp_f32_e32 v61, v61
	s_nop 0
	v_mul_f32_e32 v55, v55, v61
	v_mul_f32_e32 v55, v60, v55
	v_cvt_pk_bf16_f32 v109, v54, v55
	s_and_saveexec_b64 s[0:1], vcc
	s_cbranch_execz .LBB0_2949
	v_mov_b64_e32 v[46:47], s[12:13]
	v_mad_i64_i32 v[46:47], s[2:3], v216, s86, v[46:47]
	v_lshl_add_u64 v[46:47], v[178:179], 1, v[46:47]
	global_store_dwordx4 v[46:47], v[106:109], off sc1
.LBB0_2949:
	s_or_b64 exec, exec, s[0:1]
	v_fma_f32 v46, v98, v56, v70
	v_fmac_f32_e32 v46, v90, v58
	v_fmac_f32_e32 v46, v94, v44
	v_mul_f32_e32 v44, 0xbfb8aa3b, v46
	v_exp_f32_e32 v44, v44
	v_fma_f32 v47, v74, v50, v86
	v_fma_f32 v50, v99, v57, v71
	v_fmac_f32_e32 v50, v91, v59
	v_fmac_f32_e32 v50, v95, v45
	v_add_f32_e32 v44, 1.0, v44
	v_mul_f32_e32 v45, 0xbfb8aa3b, v50
	v_rcp_f32_e32 v44, v44
	v_exp_f32_e32 v45, v45
	v_fmac_f32_e32 v47, v78, v52
	v_fmac_f32_e32 v47, v82, v38
	v_mul_f32_e32 v38, v46, v44
	v_add_f32_e32 v44, 1.0, v45
	v_rcp_f32_e32 v44, v44
	v_fma_f32 v45, v75, v51, v87
	v_fmac_f32_e32 v45, v79, v53
	v_fma_f32 v40, v76, v40, v88
	v_fmac_f32_e32 v45, v83, v39
	v_mul_f32_e32 v39, v50, v44
	v_fma_f32 v44, v100, v48, v72
	v_fmac_f32_e32 v40, v80, v36
	v_fma_f32 v36, v101, v49, v73
	v_fmac_f32_e32 v44, v92, v42
	v_fmac_f32_e32 v36, v93, v43
	v_fmac_f32_e32 v44, v96, v32
	v_fmac_f32_e32 v36, v97, v33
	v_mul_f32_e32 v32, 0xbfb8aa3b, v44
	v_mul_f32_e32 v33, 0xbfb8aa3b, v36
	v_exp_f32_e32 v32, v32
	v_exp_f32_e32 v33, v33
	v_fmac_f32_e32 v40, v84, v34
	v_fma_f32 v34, v77, v41, v89
	v_add_f32_e32 v32, 1.0, v32
	v_add_f32_e32 v33, 1.0, v33
	v_rcp_f32_e32 v32, v32
	v_rcp_f32_e32 v33, v33
	v_fmac_f32_e32 v34, v81, v37
	v_fmac_f32_e32 v34, v85, v35
	v_mul_f32_e32 v32, v44, v32
	v_mul_f32_e32 v33, v36, v33
	v_cmp_gt_i32_e32 vcc, s88, v215
	v_mul_f32_e32 v38, v47, v38
	v_mul_f32_e32 v39, v45, v39
	v_mul_f32_e32 v32, v40, v32
	v_mul_f32_e32 v33, v34, v33
	v_cvt_pk_bf16_f32 v116, v38, v39
	v_cvt_pk_bf16_f32 v117, v32, v33
	s_and_saveexec_b64 s[0:1], vcc
	s_cbranch_execz .LBB0_2951
	v_mov_b64_e32 v[32:33], s[12:13]
	v_mad_i64_i32 v[32:33], s[2:3], v217, s86, v[32:33]
	v_lshl_add_u64 v[32:33], v[178:179], 1, v[32:33]
	global_store_dwordx4 v[32:33], v[114:117], off sc1

; __device__ __forceinline__ unsigned cvt_pk_bf16(float lo, float hi) { unsigned r; asm volatile("v_cvt_pk_bf16_f32 %0, %1, %2" : "=v"(r) : "v"(lo), "v"(hi)); return r; }
; __device__ __forceinline__ float dpp_up1(float x) { return __builtin_bit_cast(float, __builtin_amdgcn_update_dpp(0, __builtin_bit_cast(int, x), 0x111, 0xf, 0xf, true)); }
;     __device__ __forceinline__ void operator()(const f32x4 (&acc)[2][2][4][2], const Unit& u, int wr, int wc, int fr, int fq) const {
;     ...
;                 f32x4 pg2, pg3, pv2, pv3;
; #pragma unroll
;                 for (int e = 0; e < 4; ++e) { pg2[e] = dpp_up1(xg[2][e]); pg3[e] = dpp_up1(xg[3][e]); pv2[e] = dpp_up1(xv[2][e]); pv3[e] = dpp_up1(xv[3][e]); }
; #pragma unroll
;                 for (int m = 0; m < 4; ++m) {
;                     u32x2_t w; float o[4];
; #pragma unroll
;                     for (int e = 0; e < 4; ++e) {
;                         const float g1 = m >= 1 ? xg[m - (m >= 1 ? 1 : 0)][e] : pg3[e], g2 = m >= 2 ? xg[m - (m >= 2 ? 2 : 0)][e] : (m == 1 ? pg3[e] : pg2[e]);
;                         const float v1 = m >= 1 ? xv[m - (m >= 1 ? 1 : 0)][e] : pv3[e], v2 = m >= 2 ? xv[m - (m >= 2 ? 2 : 0)][e] : (m == 1 ? pv3[e] : pv2[e]);
;                         const float cg_ = bg[e] + w0g[e] * g2 + w1g[e] * g1 + w2g[e] * xg[m][e];
;                         const float cv_ = bv[e] + w0v[e] * v2 + w1v[e] * v1 + w2v[e] * xv[m][e];
;                         o[e] = cg_ * __builtin_amdgcn_rcpf(1.0f + __expf(-cg_)) * cv_;
;                     }
;                     w.x = cvt_pk_bf16(o[0], o[1]); w.y = cvt_pk_bf16(o[2], o[3]);
;                     const int g = g0 + m;
;                     if (n == 0) stash[ai][m] = w;
;                     else if ((fr > 0 || m >= 2) && g < TT) { u32x4 ww; ww.x = stash[ai][m].x; ww.y = stash[ai][m].y; ww.z = w.x; ww.w = w.y; *(u32x4*)(G + (size_t)g * DFF_ + f0 - 4) = ww; }
.LBB0_2953:
	v_mov_b32_dpp v40, v26 row_shr:1 row_mask:0xf bank_mask:0xf bound_ctrl:1
	v_mov_b32_dpp v39, v12 row_shr:1 row_mask:0xf bank_mask:0xf bound_ctrl:1
	v_fma_f32 v40, v98, v40, v70
	v_fmac_f32_e32 v40, v90, v39
	v_fmac_f32_e32 v40, v94, v34
	v_mul_f32_e32 v48, 0xbfb8aa3b, v40
	v_exp_f32_e32 v48, v48
	v_mov_b32_dpp v41, v20 row_shr:1 row_mask:0xf bank_mask:0xf bound_ctrl:1
	v_mov_b32_dpp v38, v6 row_shr:1 row_mask:0xf bank_mask:0xf bound_ctrl:1
	v_fma_f32 v41, v74, v41, v86
	v_add_f32_e32 v48, 1.0, v48
	v_rcp_f32_e32 v48, v48
	v_fmac_f32_e32 v41, v78, v38
	v_mov_b32_dpp v42, v27 row_shr:1 row_mask:0xf bank_mask:0xf bound_ctrl:1
	v_fmac_f32_e32 v41, v82, v32
	v_mul_f32_e32 v40, v40, v48
	v_mov_b32_dpp v37, v13 row_shr:1 row_mask:0xf bank_mask:0xf bound_ctrl:1
	v_mul_f32_e32 v40, v41, v40
	v_fma_f32 v41, v99, v42, v71
	v_fmac_f32_e32 v41, v91, v37
	v_mov_b32_dpp v43, v21 row_shr:1 row_mask:0xf bank_mask:0xf bound_ctrl:1
	v_fmac_f32_e32 v41, v95, v35
	v_fma_f32 v42, v75, v43, v87
	v_mul_f32_e32 v43, 0xbfb8aa3b, v41
	v_exp_f32_e32 v43, v43
	v_mov_b32_dpp v36, v7 row_shr:1 row_mask:0xf bank_mask:0xf bound_ctrl:1
	v_fmac_f32_e32 v42, v79, v36
	v_mov_b32_dpp v44, v10 row_shr:1 row_mask:0xf bank_mask:0xf bound_ctrl:1
	v_add_f32_e32 v43, 1.0, v43
	v_rcp_f32_e32 v43, v43
	v_fmac_f32_e32 v42, v83, v33
	v_mov_b32_dpp v23, v0 row_shr:1 row_mask:0xf bank_mask:0xf bound_ctrl:1
	v_mov_b32_dpp v45, v4 row_shr:1 row_mask:0xf bank_mask:0xf bound_ctrl:1
	v_mul_f32_e32 v41, v41, v43
	v_mul_f32_e32 v41, v42, v41
	v_fma_f32 v42, v100, v44, v72
	v_fmac_f32_e32 v42, v92, v23
	v_fmac_f32_e32 v42, v96, v30
	v_mul_f32_e32 v44, 0xbfb8aa3b, v42
	v_exp_f32_e32 v44, v44
	v_mov_b32_dpp v22, v2 row_shr:1 row_mask:0xf bank_mask:0xf bound_ctrl:1
	v_fma_f32 v43, v76, v45, v88
	v_fmac_f32_e32 v43, v80, v22
	v_add_f32_e32 v44, 1.0, v44
	v_rcp_f32_e32 v44, v44
	v_mov_b32_dpp v46, v11 row_shr:1 row_mask:0xf bank_mask:0xf bound_ctrl:1
	v_fmac_f32_e32 v43, v84, v28
	v_mov_b32_dpp v15, v1 row_shr:1 row_mask:0xf bank_mask:0xf bound_ctrl:1
	v_mul_f32_e32 v42, v42, v44
	v_mul_f32_e32 v42, v43, v42
	v_fma_f32 v43, v101, v46, v73
	v_fmac_f32_e32 v43, v93, v15
	v_fmac_f32_e32 v43, v97, v31
	v_mul_f32_e32 v45, 0xbfb8aa3b, v43
	v_exp_f32_e32 v45, v45
	v_mov_b32_dpp v47, v5 row_shr:1 row_mask:0xf bank_mask:0xf bound_ctrl:1
	v_mov_b32_dpp v14, v3 row_shr:1 row_mask:0xf bank_mask:0xf bound_ctrl:1
	v_fma_f32 v44, v77, v47, v89
	v_add_f32_e32 v45, 1.0, v45
	v_rcp_f32_e32 v45, v45
	v_fmac_f32_e32 v44, v81, v14
	v_cmp_gt_i32_e32 vcc, s79, v211
	v_fmac_f32_e32 v44, v85, v29
	v_mul_f32_e32 v43, v43, v45
	s_and_b64 s[2:3], s[6:7], vcc
	v_mul_f32_e32 v43, v44, v43
	v_cvt_pk_bf16_f32 v106, v40, v41
	v_cvt_pk_bf16_f32 v107, v42, v43
	s_and_saveexec_b64 s[0:1], s[2:3]
	s_cbranch_execz .LBB0_2955
	v_mov_b64_e32 v[40:41], s[12:13]
	v_mad_i64_i32 v[40:41], s[2:3], v211, s86, v[40:41]
	v_lshl_add_u64 v[40:41], v[178:179], 1, v[40:41]
	global_store_dwordx4 v[40:41], v[104:107], off sc1
.LBB0_2955:
	s_or_b64 exec, exec, s[0:1]
	v_fma_f32 v39, v98, v39, v70
	v_fmac_f32_e32 v39, v90, v34
	v_fmac_f32_e32 v39, v94, v24
	v_mul_f32_e32 v40, 0xbfb8aa3b, v39
	v_exp_f32_e32 v40, v40
	v_fma_f32 v38, v74, v38, v86
	v_fma_f32 v37, v99, v37, v71
	v_fmac_f32_e32 v38, v78, v32
	v_add_f32_e32 v40, 1.0, v40
	v_rcp_f32_e32 v40, v40
	v_fmac_f32_e32 v37, v91, v35
	v_fmac_f32_e32 v38, v82, v18
	v_fmac_f32_e32 v37, v95, v25
	v_mul_f32_e32 v39, v39, v40
	v_mul_f32_e32 v38, v38, v39
	v_mul_f32_e32 v39, 0xbfb8aa3b, v37
	v_exp_f32_e32 v39, v39
	v_fma_f32 v36, v75, v36, v87
	v_fma_f32 v23, v100, v23, v72
	v_fmac_f32_e32 v36, v79, v33
	v_add_f32_e32 v39, 1.0, v39
	v_rcp_f32_e32 v39, v39
	v_fmac_f32_e32 v23, v92, v30
	v_fmac_f32_e32 v36, v83, v19
	v_fmac_f32_e32 v23, v96, v16
	v_mul_f32_e32 v37, v37, v39
	v_mul_f32_e32 v36, v36, v37
	v_mul_f32_e32 v37, 0xbfb8aa3b, v23
	v_exp_f32_e32 v37, v37
	v_fma_f32 v22, v76, v22, v88
	v_fma_f32 v15, v101, v15, v73
	v_fmac_f32_e32 v22, v80, v28
	v_add_f32_e32 v37, 1.0, v37
	v_rcp_f32_e32 v37, v37
	v_fmac_f32_e32 v15, v93, v31
	v_fmac_f32_e32 v22, v84, v8
	v_fmac_f32_e32 v15, v97, v17
	v_mul_f32_e32 v23, v23, v37
	v_mul_f32_e32 v22, v22, v23
	v_mul_f32_e32 v23, 0xbfb8aa3b, v15
	v_exp_f32_e32 v23, v23
	v_fma_f32 v14, v77, v14, v89
	v_fmac_f32_e32 v14, v81, v29
	v_cmp_gt_i32_e32 vcc, s79, v213
	v_add_f32_e32 v23, 1.0, v23
	v_rcp_f32_e32 v23, v23
	v_fmac_f32_e32 v14, v85, v9
	s_and_b64 s[2:3], s[6:7], vcc
	v_cvt_pk_bf16_f32 v104, v38, v36
	v_mul_f32_e32 v15, v15, v23
	v_mul_f32_e32 v14, v14, v15
	v_cvt_pk_bf16_f32 v105, v22, v14
	s_and_saveexec_b64 s[0:1], s[2:3]
	s_cbranch_execz .LBB0_2957
	v_mov_b64_e32 v[14:15], s[12:13]
	v_mad_i64_i32 v[14:15], s[2:3], v213, s86, v[14:15]
	v_lshl_add_u64 v[14:15], v[178:179], 1, v[14:15]
	global_store_dwordx4 v[14:15], v[102:105], off sc1
; __device__ __forceinline__ unsigned cvt_pk_bf16(float lo, float hi) { unsigned r; asm volatile("v_cvt_pk_bf16_f32 %0, %1, %2" : "=v"(r) : "v"(lo), "v"(hi)); return r; }
;     __device__ __forceinline__ void operator()(const f32x4 (&acc)[2][2][4][2], const Unit& u, int wr, int wc, int fr, int fq) const {
;     ...
;                 for (int m = 0; m < 4; ++m) {
;                     u32x2_t w; float o[4];
; #pragma unroll
;                     for (int e = 0; e < 4; ++e) {
;                         const float g1 = m >= 1 ? xg[m - (m >= 1 ? 1 : 0)][e] : pg3[e], g2 = m >= 2 ? xg[m - (m >= 2 ? 2 : 0)][e] : (m == 1 ? pg3[e] : pg2[e]);
;                         const float v1 = m >= 1 ? xv[m - (m >= 1 ? 1 : 0)][e] : pv3[e], v2 = m >= 2 ? xv[m - (m >= 2 ? 2 : 0)][e] : (m == 1 ? pv3[e] : pv2[e]);
;                         const float cg_ = bg[e] + w0g[e] * g2 + w1g[e] * g1 + w2g[e] * xg[m][e];
;                         const float cv_ = bv[e] + w0v[e] * v2 + w1v[e] * v1 + w2v[e] * xv[m][e];
;                         o[e] = cg_ * __builtin_amdgcn_rcpf(1.0f + __expf(-cg_)) * cv_;
;                     }
;                     w.x = cvt_pk_bf16(o[0], o[1]); w.y = cvt_pk_bf16(o[2], o[3]);
;                     const int g = g0 + m;
;                     if (n == 0) stash[ai][m] = w;
;                     else if ((fr > 0 || m >= 2) && g < TT) { u32x4 ww; ww.x = stash[ai][m].x; ww.y = stash[ai][m].y; ww.z = w.x; ww.w = w.y; *(u32x4*)(G + (size_t)g * DFF_ + f0 - 4) = ww; }
.LBB0_2957:
	s_or_b64 exec, exec, s[0:1]
	v_fma_f32 v14, v98, v34, v70
	v_fmac_f32_e32 v14, v90, v24
	v_fmac_f32_e32 v14, v94, v26
	v_mul_f32_e32 v22, 0xbfb8aa3b, v14
	v_exp_f32_e32 v22, v22
	v_fma_f32 v15, v74, v32, v86
	v_fmac_f32_e32 v15, v78, v18
	v_fmac_f32_e32 v15, v82, v20
	v_add_f32_e32 v22, 1.0, v22
	v_rcp_f32_e32 v22, v22
	v_cmp_gt_i32_e32 vcc, s87, v211
	v_mul_f32_e32 v14, v14, v22
	v_mul_f32_e32 v14, v15, v14
	v_fma_f32 v15, v99, v35, v71
	v_fmac_f32_e32 v15, v91, v25
	v_fmac_f32_e32 v15, v95, v27
	v_mul_f32_e32 v23, 0xbfb8aa3b, v15
	v_exp_f32_e32 v23, v23
	v_fma_f32 v22, v75, v33, v87
	v_fmac_f32_e32 v22, v79, v19
	v_fmac_f32_e32 v22, v83, v21
	v_add_f32_e32 v23, 1.0, v23
	v_rcp_f32_e32 v23, v23
	s_nop 0
	v_mul_f32_e32 v15, v15, v23
	v_mul_f32_e32 v15, v22, v15
	v_fma_f32 v22, v100, v30, v72
	v_fmac_f32_e32 v22, v92, v16
	v_fmac_f32_e32 v22, v96, v10
	v_fma_f32 v23, v76, v28, v88
	v_mul_f32_e32 v28, 0xbfb8aa3b, v22
	v_exp_f32_e32 v28, v28
	v_fmac_f32_e32 v23, v80, v8
	v_fmac_f32_e32 v23, v84, v4
	v_cvt_pk_bf16_f32 v68, v14, v15
	v_add_f32_e32 v28, 1.0, v28
	v_rcp_f32_e32 v28, v28
	s_nop 0
	v_mul_f32_e32 v22, v22, v28
	v_mul_f32_e32 v22, v23, v22
	v_fma_f32 v23, v101, v31, v73
	v_fmac_f32_e32 v23, v93, v17
	v_fmac_f32_e32 v23, v97, v11
	v_fma_f32 v28, v77, v29, v89
	v_mul_f32_e32 v29, 0xbfb8aa3b, v23
	v_exp_f32_e32 v29, v29
	v_fmac_f32_e32 v28, v81, v9
	v_fmac_f32_e32 v28, v85, v5
	v_add_f32_e32 v29, 1.0, v29
	v_rcp_f32_e32 v29, v29
	s_nop 0
	v_mul_f32_e32 v23, v23, v29
	v_mul_f32_e32 v23, v28, v23
	v_cvt_pk_bf16_f32 v69, v22, v23
	s_and_saveexec_b64 s[0:1], vcc
	s_cbranch_execz .LBB0_2959
	v_mov_b64_e32 v[14:15], s[12:13]
	v_mad_i64_i32 v[14:15], s[2:3], v212, s86, v[14:15]
	v_lshl_add_u64 v[14:15], v[178:179], 1, v[14:15]
	global_store_dwordx4 v[14:15], v[66:69], off sc1
.LBB0_2959:
	s_or_b64 exec, exec, s[0:1]
	v_fma_f32 v14, v98, v24, v70
	v_fmac_f32_e32 v14, v90, v26
	v_fmac_f32_e32 v14, v94, v12
	v_mul_f32_e32 v12, 0xbfb8aa3b, v14
	v_exp_f32_e32 v12, v12
	v_fma_f32 v15, v74, v18, v86
	v_fma_f32 v18, v99, v25, v71
	v_fmac_f32_e32 v18, v91, v27
	v_fmac_f32_e32 v18, v95, v13
	v_add_f32_e32 v12, 1.0, v12
	v_mul_f32_e32 v13, 0xbfb8aa3b, v18
	v_rcp_f32_e32 v12, v12
	v_exp_f32_e32 v13, v13
	v_fmac_f32_e32 v15, v78, v20
	v_fmac_f32_e32 v15, v82, v6
	v_mul_f32_e32 v6, v14, v12
	v_add_f32_e32 v12, 1.0, v13
	v_rcp_f32_e32 v12, v12
	v_fma_f32 v13, v75, v19, v87
	v_fmac_f32_e32 v13, v79, v21
	v_fmac_f32_e32 v13, v83, v7
	v_mul_f32_e32 v7, v18, v12
	v_fma_f32 v12, v100, v16, v72
	v_fmac_f32_e32 v73, v101, v17
	v_fmac_f32_e32 v12, v92, v10
	v_fmac_f32_e32 v73, v93, v11
	v_fmac_f32_e32 v12, v96, v0
	v_fmac_f32_e32 v73, v97, v1
	v_mul_f32_e32 v0, 0xbfb8aa3b, v12
	v_mul_f32_e32 v1, 0xbfb8aa3b, v73
	v_exp_f32_e32 v0, v0
	v_exp_f32_e32 v1, v1
	v_fma_f32 v8, v76, v8, v88
	v_fmac_f32_e32 v89, v77, v9
	v_add_f32_e32 v0, 1.0, v0
	v_add_f32_e32 v1, 1.0, v1
	v_rcp_f32_e32 v0, v0
	v_rcp_f32_e32 v1, v1
	v_fmac_f32_e32 v8, v80, v4
	v_fmac_f32_e32 v89, v81, v5
	v_fmac_f32_e32 v8, v84, v2
	v_mul_f32_e32 v0, v12, v0
	v_fmac_f32_e32 v89, v85, v3
	v_mul_f32_e32 v1, v73, v1
	v_cmp_gt_i32_e32 vcc, s88, v211
	v_mul_f32_e32 v6, v15, v6
	v_mul_f32_e32 v7, v13, v7
	v_mul_f32_e32 v0, v8, v0
	v_mul_f32_e32 v1, v89, v1
	v_cvt_pk_bf16_f32 v66, v6, v7
	v_cvt_pk_bf16_f32 v67, v0, v1
	s_and_saveexec_b64 s[0:1], vcc
	s_cbranch_execz .LBB0_2961
	v_mov_b64_e32 v[0:1], s[12:13]
	v_mad_i64_i32 v[0:1], s[2:3], v214, s86, v[0:1]
	v_lshl_add_u64 v[0:1], v[178:179], 1, v[0:1]
	global_store_dwordx4 v[0:1], v[64:67], off sc1

; __device__ __forceinline__ unsigned cvt_pk_bf16(float lo, float hi) { unsigned r; asm volatile("v_cvt_pk_bf16_f32 %0, %1, %2" : "=v"(r) : "v"(lo), "v"(hi)); return r; }
;     __device__ __forceinline__ void operator()(const f32x4 (&acc)[2][2][4][2], const Unit& u, int wr, int wc, int fr, int fq) const {
;         const int row0 = u.pm * BM + wr * 64 + fr, col0 = u.pn * BM + wc * 32 + 8 * fq;
;         f32x4 bv[2][2];
; #pragma unroll
;         for (int bj = 0; bj < 2; ++bj)
; #pragma unroll
;             for (int n = 0; n < 2; ++n) bv[bj][n] = bias ? *(const f32x4*)(bias + col0 + bj * HALF + 4 * n) : (f32x4){0.f, 0.f, 0.f, 0.f};
;         float* ssp = ssout + (size_t)(u.pn * 4 + wc);
; #pragma unroll
;         for (int ai = 0; ai < 2; ++ai) {
;             u32x4 old[4][2];
; #pragma unroll
;             for (int m = 0; m < 4; ++m)
; #pragma unroll
;                 for (int bj = 0; bj < 2; ++bj) old[m][bj] = *(const u32x4*)(HB + (size_t)(row0 + ai * HALF + m * 16) * ldc + col0 + bj * HALF);
; #pragma unroll
;             for (int m = 0; m < 4; ++m) { const int row = row0 + ai * HALF + m * 16; float ss = 0.f;
; #pragma unroll
;                 for (int bj = 0; bj < 2; ++bj) { const u32x4 ow = old[m][bj];
;                     f32x4 v0 = (acc[ai][bj][m][0] + bv[bj][0]) * accs, v1 = (acc[ai][bj][m][1] + bv[bj][1]) * accs;
;                     v0[0] += __uint_as_float(ow.x << 16); v0[1] += __uint_as_float(ow.x & 0xffff0000u); v0[2] += __uint_as_float(ow.y << 16); v0[3] += __uint_as_float(ow.y & 0xffff0000u);
;                     v1[0] += __uint_as_float(ow.z << 16); v1[1] += __uint_as_float(ow.z & 0xffff0000u); v1[2] += __uint_as_float(ow.w << 16); v1[3] += __uint_as_float(ow.w & 0xffff0000u);
;                     ss += (v0[0] * v0[0] + v0[1] * v0[1]) + (v0[2] * v0[2] + v0[3] * v0[3]) + (v1[0] * v1[0] + v1[1] * v1[1]) + (v1[2] * v1[2] + v1[3] * v1[3]);
;                     u32x4 w; w.x = cvt_pk_bf16(v0[0], v0[1]); w.y = cvt_pk_bf16(v0[2], v0[3]); w.z = cvt_pk_bf16(v1[0], v1[1]); w.w = cvt_pk_bf16(v1[2], v1[3]);
;                     *(u32x4*)(HB + (size_t)row * ldc + col0 + bj * HALF) = w; }
;                 ss += __shfl_xor(ss, 16); ss += __shfl_xor(ss, 32);
;                 if (fq == 0) ssp[(size_t)row * 32] = ss; }
.LBB0_3043:
	v_lshl_or_b32 v152, s42, 8, v166
	v_ashrrev_i32_e32 v153, 31, v152
	v_lshl_add_u32 v156, s43, 8, v164
	v_lshlrev_b64 v[178:179], 1, v[152:153]
	v_ashrrev_i32_e32 v157, 31, v156
	v_lshl_add_u64 v[154:155], s[12:13], 0, v[178:179]
	v_lshlrev_b64 v[180:181], 12, v[156:157]
	v_lshl_add_u64 v[128:129], v[154:155], 0, v[180:181]
	global_load_dwordx4 v[170:173], v[128:129], off
	global_load_dwordx4 v[174:177], v[128:129], off offset:256
	v_or_b32_e32 v162, 16, v156
	v_or_b32_e32 v160, 32, v156
	v_or_b32_e32 v158, 48, v156
	v_ashrrev_i32_e32 v163, 31, v162
	v_ashrrev_i32_e32 v161, 31, v160
	v_pk_add_f32 v[194:195], v[114:115], 0 op_sel_hi:[1,0]
	v_pk_add_f32 v[196:197], v[112:113], 0 op_sel_hi:[1,0]
	v_ashrrev_i32_e32 v159, 31, v158
	v_lshlrev_b64 v[112:113], 12, v[162:163]
	v_lshlrev_b64 v[114:115], 12, v[160:161]
	v_pk_add_f32 v[192:193], v[116:117], 0 op_sel_hi:[1,0]
	v_lshlrev_b64 v[116:117], 12, v[158:159]
	v_lshl_add_u64 v[112:113], v[154:155], 0, v[112:113]
	v_lshl_add_u64 v[114:115], v[154:155], 0, v[114:115]
	v_pk_add_f32 v[182:183], v[126:127], 0 op_sel_hi:[1,0]
	v_pk_add_f32 v[184:185], v[124:125], 0 op_sel_hi:[1,0]
	v_pk_add_f32 v[186:187], v[122:123], 0 op_sel_hi:[1,0]
	v_pk_add_f32 v[188:189], v[120:121], 0 op_sel_hi:[1,0]
	v_pk_add_f32 v[190:191], v[118:119], 0 op_sel_hi:[1,0]
	v_lshl_add_u64 v[198:199], v[154:155], 0, v[116:117]
	global_load_dwordx4 v[132:135], v[112:113], off
	global_load_dwordx4 v[128:131], v[112:113], off offset:256
	global_load_dwordx4 v[124:127], v[114:115], off
	global_load_dwordx4 v[120:123], v[114:115], off offset:256
	global_load_dwordx4 v[116:119], v[198:199], off
	s_nop 0
	global_load_dwordx4 v[112:115], v[198:199], off offset:256
	s_lshl_b32 s18, s42, 2
	s_or_b32 s18, s18, s46
	s_ashr_i32 s19, s18, 31
	s_lshl_b64 s[18:19], s[18:19], 2
	s_add_u32 s18, s44, s18
	s_addc_u32 s19, s45, s19
	s_waitcnt vmcnt(0)
	v_lshlrev_b32_e32 v198, 16, v170
	v_and_b32_e32 v170, 0xffff0000, v170
	v_lshlrev_b32_e32 v199, 16, v171
	v_and_b32_e32 v171, 0xffff0000, v171
	v_lshlrev_b32_e32 v200, 16, v172
	v_and_b32_e32 v172, 0xffff0000, v172
	v_lshlrev_b32_e32 v203, 16, v174
	v_and_b32_e32 v174, 0xffff0000, v174
	v_lshlrev_b32_e32 v205, 16, v175
	v_and_b32_e32 v175, 0xffff0000, v175
	v_lshlrev_b32_e32 v201, 16, v173
	v_and_b32_e32 v173, 0xffff0000, v173
	v_lshlrev_b32_e32 v206, 16, v176
	v_and_b32_e32 v176, 0xffff0000, v176
	v_lshlrev_b32_e32 v207, 16, v177
	v_and_b32_e32 v177, 0xffff0000, v177
	v_add_f32_e32 v170, v185, v170
	v_add_f32_e32 v171, v183, v171
	v_add_f32_e32 v185, v189, v172
	v_add_f32_e32 v189, v193, v174
	v_add_f32_e32 v191, v191, v175
	v_add_f32_e32 v184, v184, v198
	v_add_f32_e32 v182, v182, v199
	v_add_f32_e32 v183, v188, v200
	v_add_f32_e32 v187, v187, v173
	v_add_f32_e32 v188, v192, v203
	v_add_f32_e32 v190, v190, v205
	v_add_f32_e32 v193, v197, v176
	v_add_f32_e32 v195, v195, v177
	v_mul_f32_e32 v176, v170, v170
	v_mul_f32_e32 v177, v171, v171
	v_cvt_pk_bf16_f32 v172, v184, v170
	v_cvt_pk_bf16_f32 v173, v182, v171
	v_mul_f32_e32 v170, v189, v189
	v_mul_f32_e32 v171, v191, v191
	v_fmac_f32_e32 v170, v188, v188
	v_fmac_f32_e32 v171, v190, v190
	v_add_f32_e32 v192, v196, v206
	v_add_f32_e32 v170, v170, v171
	v_mul_f32_e32 v171, v193, v193
	v_mul_f32_e32 v196, v185, v185
	v_fmac_f32_e32 v176, v184, v184
	v_fmac_f32_e32 v177, v182, v182
	v_fmac_f32_e32 v171, v192, v192
	v_add_f32_e32 v186, v186, v201
	v_add_f32_e32 v194, v194, v207
	v_mul_f32_e32 v197, v187, v187
	v_fmac_f32_e32 v196, v183, v183
	v_add_f32_e32 v176, v176, v177
	v_add_f32_e32 v170, v171, v170
	v_mul_f32_e32 v171, v195, v195
	v_fmac_f32_e32 v197, v186, v186
	v_add_f32_e32 v176, v196, v176
	v_fmac_f32_e32 v171, v194, v194
	v_add_f32_e32 v176, v197, v176
	v_add_f32_e32 v170, v171, v170
	v_add_f32_e32 v171, v176, v170
	v_and_b32_e32 v176, 64, v202
	v_xor_b32_e32 v170, 16, v202
	v_add_u32_e32 v182, 64, v176
	v_cmp_lt_i32_e32 vcc, v170, v182
	v_cvt_pk_bf16_f32 v174, v183, v185
	v_lshl_add_u64 v[176:177], s[12:13], 0, v[180:181]
	v_lshl_add_u64 v[178:179], v[176:177], 0, v[178:179]
	v_cndmask_b32_e32 v170, v202, v170, vcc
	v_lshlrev_b32_e32 v170, 2, v170
	ds_bpermute_b32 v183, v170, v171
	v_cvt_pk_bf16_f32 v175, v186, v187
	global_store_dwordx4 v[178:179], v[172:175], off sc1
	s_waitcnt lgkmcnt(0)
	s_nop 0
	v_add_f32_e32 v172, v171, v183
	v_xor_b32_e32 v171, 32, v202
	v_cmp_lt_i32_e32 vcc, v171, v182
	v_cvt_pk_bf16_f32 v174, v188, v189
	v_cvt_pk_bf16_f32 v175, v190, v191
	v_cvt_pk_bf16_f32 v176, v192, v193
	v_cvt_pk_bf16_f32 v177, v194, v195
	global_store_dwordx4 v[178:179], v[174:177], off offset:256 sc1
	s_nop 0
	v_cndmask_b32_e32 v171, v202, v171, vcc
	v_lshlrev_b32_e32 v171, 2, v171
	ds_bpermute_b32 v173, v171, v172
	s_and_saveexec_b64 s[20:21], s[4:5]
	s_cbranch_execz .LBB0_3045
	v_lshlrev_b64 v[174:175], 7, v[156:157]
	v_lshl_add_u64 v[174:175], s[18:19], 0, v[174:175]
	s_waitcnt lgkmcnt(0)
	v_add_f32_e32 v157, v172, v173
	global_store_dword v[174:175], v157, off
; __device__ __forceinline__ unsigned cvt_pk_bf16(float lo, float hi) { unsigned r; asm volatile("v_cvt_pk_bf16_f32 %0, %1, %2" : "=v"(r) : "v"(lo), "v"(hi)); return r; }
;     __device__ __forceinline__ void operator()(const f32x4 (&acc)[2][2][4][2], const Unit& u, int wr, int wc, int fr, int fq) const {
;     ...
;             for (int m = 0; m < 4; ++m) { const int row = row0 + ai * HALF + m * 16; float ss = 0.f;
; #pragma unroll
;                 for (int bj = 0; bj < 2; ++bj) { const u32x4 ow = old[m][bj];
;                     f32x4 v0 = (acc[ai][bj][m][0] + bv[bj][0]) * accs, v1 = (acc[ai][bj][m][1] + bv[bj][1]) * accs;
;                     v0[0] += __uint_as_float(ow.x << 16); v0[1] += __uint_as_float(ow.x & 0xffff0000u); v0[2] += __uint_as_float(ow.y << 16); v0[3] += __uint_as_float(ow.y & 0xffff0000u);
;                     v1[0] += __uint_as_float(ow.z << 16); v1[1] += __uint_as_float(ow.z & 0xffff0000u); v1[2] += __uint_as_float(ow.w << 16); v1[3] += __uint_as_float(ow.w & 0xffff0000u);
;                     ss += (v0[0] * v0[0] + v0[1] * v0[1]) + (v0[2] * v0[2] + v0[3] * v0[3]) + (v1[0] * v1[0] + v1[1] * v1[1]) + (v1[2] * v1[2] + v1[3] * v1[3]);
;                     u32x4 w; w.x = cvt_pk_bf16(v0[0], v0[1]); w.y = cvt_pk_bf16(v0[2], v0[3]); w.z = cvt_pk_bf16(v1[0], v1[1]); w.w = cvt_pk_bf16(v1[2], v1[3]);
;                     *(u32x4*)(HB + (size_t)row * ldc + col0 + bj * HALF) = w; }
;                 ss += __shfl_xor(ss, 16); ss += __shfl_xor(ss, 32);
;                 if (fq == 0) ssp[(size_t)row * 32] = ss; }
.LBB0_3045:
	s_or_b64 exec, exec, s[20:21]
	v_pk_add_f32 v[108:109], v[108:109], 0 op_sel_hi:[1,0]
	v_lshlrev_b32_e32 v157, 16, v132
	v_and_b32_e32 v132, 0xffff0000, v132
	v_pk_add_f32 v[110:111], v[110:111], 0 op_sel_hi:[1,0]
	v_add_f32_e32 v109, v109, v132
	v_lshlrev_b32_e32 v132, 16, v133
	v_add_f32_e32 v110, v110, v132
	v_and_b32_e32 v132, 0xffff0000, v133
	v_pk_add_f32 v[104:105], v[104:105], 0 op_sel_hi:[1,0]
	v_add_f32_e32 v111, v111, v132
	v_lshlrev_b32_e32 v132, 16, v134
	v_add_f32_e32 v132, v104, v132
	v_and_b32_e32 v104, 0xffff0000, v134
	v_pk_add_f32 v[106:107], v[106:107], 0 op_sel_hi:[1,0]
	v_add_f32_e32 v133, v105, v104
	v_lshlrev_b32_e32 v104, 16, v135
	v_add_f32_e32 v134, v106, v104
	v_and_b32_e32 v104, 0xffff0000, v135
	v_add_f32_e32 v108, v108, v157
	v_add_f32_e32 v107, v107, v104
	v_mul_f32_e32 v104, v109, v109
	v_mul_f32_e32 v105, v111, v111
	v_fmac_f32_e32 v104, v108, v108
	v_fmac_f32_e32 v105, v110, v110
	v_add_f32_e32 v104, v104, v105
	v_mul_f32_e32 v105, v133, v133
	v_fmac_f32_e32 v105, v132, v132
	v_add_f32_e32 v104, v105, v104
	v_mul_f32_e32 v105, v107, v107
	v_fmac_f32_e32 v105, v134, v134
	v_add_f32_e32 v135, v105, v104
	v_cvt_pk_bf16_f32 v104, v108, v109
	v_pk_add_f32 v[100:101], v[100:101], 0 op_sel_hi:[1,0]
	v_lshlrev_b32_e32 v108, 16, v128
	v_add_f32_e32 v100, v100, v108
	v_and_b32_e32 v108, 0xffff0000, v128
	v_pk_add_f32 v[102:103], v[102:103], 0 op_sel_hi:[1,0]
	v_add_f32_e32 v101, v101, v108
	v_lshlrev_b32_e32 v108, 16, v129
	v_add_f32_e32 v108, v102, v108
	v_and_b32_e32 v102, 0xffff0000, v129
	v_pk_add_f32 v[96:97], v[96:97], 0 op_sel_hi:[1,0]
	v_add_f32_e32 v109, v103, v102
	v_lshlrev_b32_e32 v102, 16, v130
	v_cvt_pk_bf16_f32 v105, v110, v111
	v_add_f32_e32 v110, v96, v102
	v_and_b32_e32 v96, 0xffff0000, v130
	v_pk_add_f32 v[98:99], v[98:99], 0 op_sel_hi:[1,0]
	v_add_f32_e32 v111, v97, v96
	v_lshlrev_b32_e32 v96, 16, v131
	v_add_f32_e32 v128, v98, v96
	v_and_b32_e32 v96, 0xffff0000, v131
	v_add_f32_e32 v129, v99, v96
	v_mul_f32_e32 v96, v101, v101
	v_mul_f32_e32 v97, v109, v109
	v_fmac_f32_e32 v96, v100, v100
	v_fmac_f32_e32 v97, v108, v108
	v_add_f32_e32 v96, v96, v97
	v_mul_f32_e32 v97, v111, v111
	v_fmac_f32_e32 v97, v110, v110
	v_add_f32_e32 v96, v97, v96
	v_mul_f32_e32 v97, v129, v129
	v_fmac_f32_e32 v97, v128, v128
	v_add_f32_e32 v96, v97, v96
	v_add_f32_e32 v99, v135, v96
	ds_bpermute_b32 v130, v170, v99
	s_waitcnt lgkmcnt(1)
	v_lshlrev_b64 v[172:173], 11, v[162:163]
	v_lshl_add_u64 v[96:97], v[172:173], 1, s[12:13]
	v_lshl_add_u64 v[102:103], v[152:153], 1, v[96:97]
	v_cvt_pk_bf16_f32 v106, v132, v133
	s_waitcnt lgkmcnt(0)
	v_add_f32_e32 v96, v99, v130
	ds_bpermute_b32 v97, v171, v96
	v_cvt_pk_bf16_f32 v107, v134, v107
	global_store_dwordx4 v[102:103], v[104:107], off sc1
	v_cvt_pk_bf16_f32 v98, v100, v101
	v_cvt_pk_bf16_f32 v99, v108, v109
	v_cvt_pk_bf16_f32 v100, v110, v111
	v_cvt_pk_bf16_f32 v101, v128, v129
	global_store_dwordx4 v[102:103], v[98:101], off offset:256 sc1
	s_and_saveexec_b64 s[20:21], s[4:5]
	s_cbranch_execz .LBB0_3047
	v_lshlrev_b64 v[98:99], 7, v[162:163]
	v_lshl_add_u64 v[98:99], s[18:19], 0, v[98:99]
	s_waitcnt lgkmcnt(0)
	v_add_f32_e32 v96, v96, v97
	global_store_dword v[98:99], v96, off
.LBB0_3047:
	s_or_b64 exec, exec, s[20:21]
	v_pk_add_f32 v[92:93], v[92:93], 0 op_sel_hi:[1,0]
	v_lshlrev_b32_e32 v98, 16, v124
	v_add_f32_e32 v92, v92, v98
	v_and_b32_e32 v98, 0xffff0000, v124
	v_pk_add_f32 v[94:95], v[94:95], 0 op_sel_hi:[1,0]
	v_add_f32_e32 v93, v93, v98
	v_lshlrev_b32_e32 v98, 16, v125
	v_add_f32_e32 v94, v94, v98
	v_and_b32_e32 v98, 0xffff0000, v125
	v_pk_add_f32 v[88:89], v[88:89], 0 op_sel_hi:[1,0]
	v_add_f32_e32 v95, v95, v98
	v_lshlrev_b32_e32 v98, 16, v126
	v_add_f32_e32 v98, v88, v98
	v_and_b32_e32 v88, 0xffff0000, v126
	v_pk_add_f32 v[90:91], v[90:91], 0 op_sel_hi:[1,0]
	v_add_f32_e32 v99, v89, v88
	v_lshlrev_b32_e32 v88, 16, v127
	v_add_f32_e32 v100, v90, v88
	v_and_b32_e32 v88, 0xffff0000, v127
	v_add_f32_e32 v91, v91, v88
	v_mul_f32_e32 v88, v93, v93
	v_mul_f32_e32 v89, v95, v95
	v_fmac_f32_e32 v88, v92, v92
	v_fmac_f32_e32 v89, v94, v94
	v_add_f32_e32 v88, v88, v89
	v_mul_f32_e32 v89, v99, v99
	v_fmac_f32_e32 v89, v98, v98
	v_add_f32_e32 v88, v89, v88
	v_mul_f32_e32 v89, v91, v91
	v_fmac_f32_e32 v89, v100, v100
	v_add_f32_e32 v101, v89, v88
	v_cvt_pk_bf16_f32 v88, v92, v93
	v_pk_add_f32 v[84:85], v[84:85], 0 op_sel_hi:[1,0]
	v_lshlrev_b32_e32 v92, 16, v120
	v_add_f32_e32 v84, v84, v92
	v_and_b32_e32 v92, 0xffff0000, v120
	v_pk_add_f32 v[86:87], v[86:87], 0 op_sel_hi:[1,0]
	v_add_f32_e32 v85, v85, v92
	v_lshlrev_b32_e32 v92, 16, v121
	v_add_f32_e32 v92, v86, v92
	v_and_b32_e32 v86, 0xffff0000, v121
	v_pk_add_f32 v[80:81], v[80:81], 0 op_sel_hi:[1,0]
	v_add_f32_e32 v93, v87, v86
	v_lshlrev_b32_e32 v86, 16, v122
	v_cvt_pk_bf16_f32 v89, v94, v95
	v_add_f32_e32 v94, v80, v86
	v_and_b32_e32 v80, 0xffff0000, v122
	v_pk_add_f32 v[82:83], v[82:83], 0 op_sel_hi:[1,0]
	v_add_f32_e32 v95, v81, v80
	v_lshlrev_b32_e32 v80, 16, v123
	v_cvt_pk_bf16_f32 v90, v98, v99
	v_add_f32_e32 v98, v82, v80
	v_and_b32_e32 v80, 0xffff0000, v123
	v_add_f32_e32 v99, v83, v80
	v_mul_f32_e32 v80, v85, v85
	v_mul_f32_e32 v81, v93, v93
	v_fmac_f32_e32 v80, v84, v84
	v_fmac_f32_e32 v81, v92, v92
	v_add_f32_e32 v80, v80, v81
	v_mul_f32_e32 v81, v95, v95
	v_fmac_f32_e32 v81, v94, v94
	v_add_f32_e32 v80, v81, v80
	v_mul_f32_e32 v81, v99, v99
	v_fmac_f32_e32 v81, v98, v98
	v_add_f32_e32 v80, v81, v80
	v_add_f32_e32 v83, v101, v80
	v_cvt_pk_bf16_f32 v91, v100, v91
	ds_bpermute_b32 v100, v170, v83
	s_waitcnt lgkmcnt(1)
	v_lshlrev_b64 v[96:97], 11, v[160:161]
	v_lshl_add_u64 v[80:81], v[96:97], 1, s[12:13]
	v_lshl_add_u64 v[86:87], v[152:153], 1, v[80:81]
	global_store_dwordx4 v[86:87], v[88:91], off sc1
	s_waitcnt lgkmcnt(0)
	v_add_f32_e32 v80, v83, v100
	ds_bpermute_b32 v81, v171, v80
	v_cvt_pk_bf16_f32 v82, v84, v85
	v_cvt_pk_bf16_f32 v83, v92, v93
	v_cvt_pk_bf16_f32 v84, v94, v95
	v_cvt_pk_bf16_f32 v85, v98, v99
	global_store_dwordx4 v[86:87], v[82:85], off offset:256 sc1
	s_and_saveexec_b64 s[20:21], s[4:5]
	s_cbranch_execz .LBB0_3049
	v_lshlrev_b64 v[82:83], 7, v[160:161]
	v_lshl_add_u64 v[82:83], s[18:19], 0, v[82:83]
	s_waitcnt lgkmcnt(0)
	v_add_f32_e32 v80, v80, v81
	global_store_dword v[82:83], v80, off
; __device__ __forceinline__ unsigned cvt_pk_bf16(float lo, float hi) { unsigned r; asm volatile("v_cvt_pk_bf16_f32 %0, %1, %2" : "=v"(r) : "v"(lo), "v"(hi)); return r; }
;     __device__ __forceinline__ void operator()(const f32x4 (&acc)[2][2][4][2], const Unit& u, int wr, int wc, int fr, int fq) const {
;     ...
;         for (int ai = 0; ai < 2; ++ai) {
;             u32x4 old[4][2];
; #pragma unroll
;             for (int m = 0; m < 4; ++m)
; #pragma unroll
;                 for (int bj = 0; bj < 2; ++bj) old[m][bj] = *(const u32x4*)(HB + (size_t)(row0 + ai * HALF + m * 16) * ldc + col0 + bj * HALF);
; #pragma unroll
;             for (int m = 0; m < 4; ++m) { const int row = row0 + ai * HALF + m * 16; float ss = 0.f;
; #pragma unroll
;                 for (int bj = 0; bj < 2; ++bj) { const u32x4 ow = old[m][bj];
;                     f32x4 v0 = (acc[ai][bj][m][0] + bv[bj][0]) * accs, v1 = (acc[ai][bj][m][1] + bv[bj][1]) * accs;
;                     v0[0] += __uint_as_float(ow.x << 16); v0[1] += __uint_as_float(ow.x & 0xffff0000u); v0[2] += __uint_as_float(ow.y << 16); v0[3] += __uint_as_float(ow.y & 0xffff0000u);
;                     v1[0] += __uint_as_float(ow.z << 16); v1[1] += __uint_as_float(ow.z & 0xffff0000u); v1[2] += __uint_as_float(ow.w << 16); v1[3] += __uint_as_float(ow.w & 0xffff0000u);
;                     ss += (v0[0] * v0[0] + v0[1] * v0[1]) + (v0[2] * v0[2] + v0[3] * v0[3]) + (v1[0] * v1[0] + v1[1] * v1[1]) + (v1[2] * v1[2] + v1[3] * v1[3]);
;                     u32x4 w; w.x = cvt_pk_bf16(v0[0], v0[1]); w.y = cvt_pk_bf16(v0[2], v0[3]); w.z = cvt_pk_bf16(v1[0], v1[1]); w.w = cvt_pk_bf16(v1[2], v1[3]);
;                     *(u32x4*)(HB + (size_t)row * ldc + col0 + bj * HALF) = w; }
;                 ss += __shfl_xor(ss, 16); ss += __shfl_xor(ss, 32);
;                 if (fq == 0) ssp[(size_t)row * 32] = ss; }
.LBB0_3049:
	s_or_b64 exec, exec, s[20:21]
	v_pk_add_f32 v[76:77], v[76:77], 0 op_sel_hi:[1,0]
	v_lshlrev_b32_e32 v82, 16, v116
	v_add_f32_e32 v76, v76, v82
	v_and_b32_e32 v82, 0xffff0000, v116
	v_pk_add_f32 v[78:79], v[78:79], 0 op_sel_hi:[1,0]
	v_add_f32_e32 v77, v77, v82
	v_lshlrev_b32_e32 v82, 16, v117
	v_add_f32_e32 v78, v78, v82
	v_and_b32_e32 v82, 0xffff0000, v117
	v_pk_add_f32 v[72:73], v[72:73], 0 op_sel_hi:[1,0]
	v_add_f32_e32 v79, v79, v82
	v_lshlrev_b32_e32 v82, 16, v118
	v_add_f32_e32 v82, v72, v82
	v_and_b32_e32 v72, 0xffff0000, v118
	v_pk_add_f32 v[74:75], v[74:75], 0 op_sel_hi:[1,0]
	v_add_f32_e32 v83, v73, v72
	v_lshlrev_b32_e32 v72, 16, v119
	v_add_f32_e32 v84, v74, v72
	v_and_b32_e32 v72, 0xffff0000, v119
	v_add_f32_e32 v75, v75, v72
	v_mul_f32_e32 v72, v77, v77
	v_mul_f32_e32 v73, v79, v79
	v_fmac_f32_e32 v72, v76, v76
	v_fmac_f32_e32 v73, v78, v78
	v_add_f32_e32 v72, v72, v73
	v_mul_f32_e32 v73, v83, v83
	v_fmac_f32_e32 v73, v82, v82
	v_add_f32_e32 v72, v73, v72
	v_mul_f32_e32 v73, v75, v75
	v_fmac_f32_e32 v73, v84, v84
	v_add_f32_e32 v85, v73, v72
	v_cvt_pk_bf16_f32 v72, v76, v77
	v_pk_add_f32 v[68:69], v[68:69], 0 op_sel_hi:[1,0]
	v_lshlrev_b32_e32 v76, 16, v112
	v_add_f32_e32 v68, v68, v76
	v_and_b32_e32 v76, 0xffff0000, v112
	v_pk_add_f32 v[70:71], v[70:71], 0 op_sel_hi:[1,0]
	v_add_f32_e32 v69, v69, v76
	v_lshlrev_b32_e32 v76, 16, v113
	v_add_f32_e32 v76, v70, v76
	v_and_b32_e32 v70, 0xffff0000, v113
	v_pk_add_f32 v[64:65], v[64:65], 0 op_sel_hi:[1,0]
	v_add_f32_e32 v77, v71, v70
	v_lshlrev_b32_e32 v70, 16, v114
	v_cvt_pk_bf16_f32 v73, v78, v79
	v_add_f32_e32 v78, v64, v70
	v_and_b32_e32 v64, 0xffff0000, v114
	v_pk_add_f32 v[66:67], v[66:67], 0 op_sel_hi:[1,0]
	v_add_f32_e32 v79, v65, v64
	v_lshlrev_b32_e32 v64, 16, v115
	v_cvt_pk_bf16_f32 v74, v82, v83
	v_add_f32_e32 v82, v66, v64
	v_and_b32_e32 v64, 0xffff0000, v115
	v_add_f32_e32 v83, v67, v64
	v_mul_f32_e32 v64, v69, v69
	v_mul_f32_e32 v65, v77, v77
	v_fmac_f32_e32 v64, v68, v68
	v_fmac_f32_e32 v65, v76, v76
	v_add_f32_e32 v64, v64, v65
	v_mul_f32_e32 v65, v79, v79
	v_fmac_f32_e32 v65, v78, v78
	v_add_f32_e32 v64, v65, v64
	v_mul_f32_e32 v65, v83, v83
	v_fmac_f32_e32 v65, v82, v82
	v_add_f32_e32 v64, v65, v64
	v_add_f32_e32 v67, v85, v64
	v_cvt_pk_bf16_f32 v75, v84, v75
	ds_bpermute_b32 v84, v170, v67
	s_waitcnt lgkmcnt(1)
	v_lshlrev_b64 v[80:81], 11, v[158:159]
	v_lshl_add_u64 v[64:65], v[80:81], 1, s[12:13]
	v_lshl_add_u64 v[70:71], v[152:153], 1, v[64:65]
	global_store_dwordx4 v[70:71], v[72:75], off sc1
	s_waitcnt lgkmcnt(0)
	v_add_f32_e32 v64, v67, v84
	ds_bpermute_b32 v65, v171, v64
	v_cvt_pk_bf16_f32 v66, v68, v69
	v_cvt_pk_bf16_f32 v67, v76, v77
	v_cvt_pk_bf16_f32 v68, v78, v79
	v_cvt_pk_bf16_f32 v69, v82, v83
	global_store_dwordx4 v[70:71], v[66:69], off offset:256 sc1
	s_and_saveexec_b64 s[20:21], s[4:5]
	s_cbranch_execz .LBB0_3051
	v_lshlrev_b64 v[66:67], 7, v[158:159]
	v_lshl_add_u64 v[66:67], s[18:19], 0, v[66:67]
	s_waitcnt lgkmcnt(0)
	v_add_f32_e32 v64, v64, v65
	global_store_dword v[66:67], v64, off
.LBB0_3051:
	s_or_b64 exec, exec, s[20:21]
	v_add_u32_e32 v98, 0x80, v156
	v_ashrrev_i32_e32 v99, 31, v98
	v_lshlrev_b64 v[104:105], 12, v[98:99]
	s_waitcnt lgkmcnt(0)
	v_lshl_add_u64 v[64:65], v[154:155], 0, v[104:105]
	global_load_dwordx4 v[100:103], v[64:65], off
	global_load_dwordx4 v[88:91], v[64:65], off offset:256
	v_add_u32_e32 v96, 0x90, v156
	v_ashrrev_i32_e32 v97, 31, v96
	v_lshlrev_b64 v[64:65], 12, v[96:97]
	v_add_u32_e32 v94, 0xa0, v156
	v_lshl_add_u64 v[64:65], v[154:155], 0, v[64:65]
	v_ashrrev_i32_e32 v95, 31, v94
	global_load_dwordx4 v[84:87], v[64:65], off
	global_load_dwordx4 v[80:83], v[64:65], off offset:256
	v_lshlrev_b64 v[64:65], 12, v[94:95]
	v_add_u32_e32 v92, 0xb0, v156
	v_lshl_add_u64 v[64:65], v[154:155], 0, v[64:65]
	v_ashrrev_i32_e32 v93, 31, v92
	global_load_dwordx4 v[76:79], v[64:65], off
	global_load_dwordx4 v[72:75], v[64:65], off offset:256
	v_lshlrev_b64 v[64:65], 12, v[92:93]
	v_lshl_add_u64 v[64:65], v[154:155], 0, v[64:65]
	global_load_dwordx4 v[68:71], v[64:65], off
	s_nop 0
	global_load_dwordx4 v[64:67], v[64:65], off offset:256
	v_pk_add_f32 v[60:61], v[60:61], 0 op_sel_hi:[1,0]
	v_pk_add_f32 v[62:63], v[62:63], 0 op_sel_hi:[1,0]
	v_pk_add_f32 v[56:57], v[56:57], 0 op_sel_hi:[1,0]
	v_pk_add_f32 v[58:59], v[58:59], 0 op_sel_hi:[1,0]
	v_pk_add_f32 v[52:53], v[52:53], 0 op_sel_hi:[1,0]
	v_pk_add_f32 v[54:55], v[54:55], 0 op_sel_hi:[1,0]
	v_pk_add_f32 v[48:49], v[48:49], 0 op_sel_hi:[1,0]
	v_pk_add_f32 v[50:51], v[50:51], 0 op_sel_hi:[1,0]
	s_waitcnt vmcnt(7)
	v_lshlrev_b32_e32 v106, 16, v100
	v_and_b32_e32 v100, 0xffff0000, v100
	v_add_f32_e32 v61, v61, v100
	v_lshlrev_b32_e32 v100, 16, v101
	v_add_f32_e32 v62, v62, v100
	v_and_b32_e32 v100, 0xffff0000, v101
	v_add_f32_e32 v63, v63, v100
	v_lshlrev_b32_e32 v100, 16, v102
	v_add_f32_e32 v56, v56, v100
	v_and_b32_e32 v100, 0xffff0000, v102
	v_add_f32_e32 v57, v57, v100
	v_lshlrev_b32_e32 v100, 16, v103
	v_add_f32_e32 v100, v58, v100
	v_and_b32_e32 v58, 0xffff0000, v103
	v_add_f32_e32 v60, v60, v106
	v_add_f32_e32 v101, v59, v58
	v_mul_f32_e32 v58, v61, v61
	v_mul_f32_e32 v59, v63, v63
	v_fmac_f32_e32 v58, v60, v60
	v_fmac_f32_e32 v59, v62, v62
	v_add_f32_e32 v58, v58, v59
	v_mul_f32_e32 v59, v57, v57
	v_fmac_f32_e32 v59, v56, v56
	v_add_f32_e32 v58, v59, v58
	v_mul_f32_e32 v59, v101, v101
	v_fmac_f32_e32 v59, v100, v100
	v_add_f32_e32 v102, v59, v58
	v_cvt_pk_bf16_f32 v58, v60, v61
	v_cvt_pk_bf16_f32 v59, v62, v63
	v_cvt_pk_bf16_f32 v60, v56, v57
	v_lshl_add_u64 v[56:57], s[12:13], 0, v[104:105]
	v_lshl_add_u64 v[56:57], v[152:153], 1, v[56:57]
	v_cvt_pk_bf16_f32 v61, v100, v101
	global_store_dwordx4 v[56:57], v[58:61], off sc1
	s_waitcnt vmcnt(7)
	s_nop 0
	v_lshlrev_b32_e32 v58, 16, v88
	v_add_f32_e32 v52, v52, v58
	v_and_b32_e32 v58, 0xffff0000, v88
	v_add_f32_e32 v53, v53, v58
	v_lshlrev_b32_e32 v58, 16, v89
	v_add_f32_e32 v54, v54, v58
	v_and_b32_e32 v58, 0xffff0000, v89
	v_add_f32_e32 v55, v55, v58
	v_lshlrev_b32_e32 v58, 16, v90
	v_add_f32_e32 v58, v48, v58
	v_and_b32_e32 v48, 0xffff0000, v90
	v_add_f32_e32 v59, v49, v48
	v_lshlrev_b32_e32 v48, 16, v91
	v_add_f32_e32 v60, v50, v48
	v_and_b32_e32 v48, 0xffff0000, v91
	v_add_f32_e32 v51, v51, v48
	v_mul_f32_e32 v48, v53, v53
	v_mul_f32_e32 v49, v55, v55
	v_fmac_f32_e32 v48, v52, v52
	v_fmac_f32_e32 v49, v54, v54
	v_add_f32_e32 v48, v48, v49
	v_mul_f32_e32 v49, v59, v59
	v_fmac_f32_e32 v49, v58, v58
	v_add_f32_e32 v48, v49, v48
	v_mul_f32_e32 v49, v51, v51
	v_fmac_f32_e32 v49, v60, v60
	v_add_f32_e32 v48, v49, v48
	v_add_f32_e32 v61, v102, v48
	v_cvt_pk_bf16_f32 v48, v52, v53
	v_cvt_pk_bf16_f32 v49, v54, v55
	v_cvt_pk_bf16_f32 v50, v58, v59
	v_cvt_pk_bf16_f32 v51, v60, v51
	global_store_dwordx4 v[56:57], v[48:51], off offset:256 sc1
	ds_bpermute_b32 v48, v170, v61
	s_waitcnt lgkmcnt(0)
	v_add_f32_e32 v48, v61, v48
	ds_bpermute_b32 v49, v171, v48
	s_and_saveexec_b64 s[20:21], s[4:5]
	s_cbranch_execz .LBB0_3053
; __device__ __forceinline__ unsigned cvt_pk_bf16(float lo, float hi) { unsigned r; asm volatile("v_cvt_pk_bf16_f32 %0, %1, %2" : "=v"(r) : "v"(lo), "v"(hi)); return r; }
;     __device__ __forceinline__ void operator()(const f32x4 (&acc)[2][2][4][2], const Unit& u, int wr, int wc, int fr, int fq) const {
;     ...
;             for (int m = 0; m < 4; ++m) { const int row = row0 + ai * HALF + m * 16; float ss = 0.f;
; #pragma unroll
;                 for (int bj = 0; bj < 2; ++bj) { const u32x4 ow = old[m][bj];
;                     f32x4 v0 = (acc[ai][bj][m][0] + bv[bj][0]) * accs, v1 = (acc[ai][bj][m][1] + bv[bj][1]) * accs;
;                     v0[0] += __uint_as_float(ow.x << 16); v0[1] += __uint_as_float(ow.x & 0xffff0000u); v0[2] += __uint_as_float(ow.y << 16); v0[3] += __uint_as_float(ow.y & 0xffff0000u);
;                     v1[0] += __uint_as_float(ow.z << 16); v1[1] += __uint_as_float(ow.z & 0xffff0000u); v1[2] += __uint_as_float(ow.w << 16); v1[3] += __uint_as_float(ow.w & 0xffff0000u);
;                     ss += (v0[0] * v0[0] + v0[1] * v0[1]) + (v0[2] * v0[2] + v0[3] * v0[3]) + (v1[0] * v1[0] + v1[1] * v1[1]) + (v1[2] * v1[2] + v1[3] * v1[3]);
;                     u32x4 w; w.x = cvt_pk_bf16(v0[0], v0[1]); w.y = cvt_pk_bf16(v0[2], v0[3]); w.z = cvt_pk_bf16(v1[0], v1[1]); w.w = cvt_pk_bf16(v1[2], v1[3]);
;                     *(u32x4*)(HB + (size_t)row * ldc + col0 + bj * HALF) = w; }
;                 ss += __shfl_xor(ss, 16); ss += __shfl_xor(ss, 32);
;                 if (fq == 0) ssp[(size_t)row * 32] = ss; }
	v_lshlrev_b64 v[50:51], 7, v[98:99]
	v_lshl_add_u64 v[50:51], s[18:19], 0, v[50:51]
	s_waitcnt lgkmcnt(0)
	v_add_f32_e32 v48, v48, v49
	global_store_dword v[50:51], v48, off
.LBB0_3053:
	s_or_b64 exec, exec, s[20:21]
	v_pk_add_f32 v[44:45], v[44:45], 0 op_sel_hi:[1,0]
	s_waitcnt vmcnt(7)
	v_lshlrev_b32_e32 v50, 16, v84
	v_add_f32_e32 v44, v44, v50
	v_and_b32_e32 v50, 0xffff0000, v84
	v_pk_add_f32 v[46:47], v[46:47], 0 op_sel_hi:[1,0]
	v_add_f32_e32 v45, v45, v50
	v_lshlrev_b32_e32 v50, 16, v85
	v_add_f32_e32 v46, v46, v50
	v_and_b32_e32 v50, 0xffff0000, v85
	v_pk_add_f32 v[40:41], v[40:41], 0 op_sel_hi:[1,0]
	v_add_f32_e32 v47, v47, v50
	v_lshlrev_b32_e32 v50, 16, v86
	v_add_f32_e32 v50, v40, v50
	v_and_b32_e32 v40, 0xffff0000, v86
	v_pk_add_f32 v[42:43], v[42:43], 0 op_sel_hi:[1,0]
	v_add_f32_e32 v51, v41, v40
	v_lshlrev_b32_e32 v40, 16, v87
	v_add_f32_e32 v52, v42, v40
	v_and_b32_e32 v40, 0xffff0000, v87
	v_add_f32_e32 v43, v43, v40
	v_mul_f32_e32 v40, v45, v45
	v_mul_f32_e32 v41, v47, v47
	v_fmac_f32_e32 v40, v44, v44
	v_fmac_f32_e32 v41, v46, v46
	v_add_f32_e32 v40, v40, v41
	v_mul_f32_e32 v41, v51, v51
	v_fmac_f32_e32 v41, v50, v50
	v_add_f32_e32 v40, v41, v40
	v_mul_f32_e32 v41, v43, v43
	v_fmac_f32_e32 v41, v52, v52
	v_add_f32_e32 v53, v41, v40
	v_cvt_pk_bf16_f32 v40, v44, v45
	v_pk_add_f32 v[36:37], v[36:37], 0 op_sel_hi:[1,0]
	s_waitcnt vmcnt(6)
	v_lshlrev_b32_e32 v44, 16, v80
	v_add_f32_e32 v36, v36, v44
	v_and_b32_e32 v44, 0xffff0000, v80
	v_pk_add_f32 v[38:39], v[38:39], 0 op_sel_hi:[1,0]
	v_add_f32_e32 v37, v37, v44
	v_lshlrev_b32_e32 v44, 16, v81
	v_add_f32_e32 v44, v38, v44
	v_and_b32_e32 v38, 0xffff0000, v81
	v_pk_add_f32 v[32:33], v[32:33], 0 op_sel_hi:[1,0]
	v_add_f32_e32 v45, v39, v38
	v_lshlrev_b32_e32 v38, 16, v82
	v_cvt_pk_bf16_f32 v41, v46, v47
	v_add_f32_e32 v46, v32, v38
	v_and_b32_e32 v32, 0xffff0000, v82
	v_pk_add_f32 v[34:35], v[34:35], 0 op_sel_hi:[1,0]
	v_add_f32_e32 v47, v33, v32
	v_lshlrev_b32_e32 v32, 16, v83
	v_cvt_pk_bf16_f32 v42, v50, v51
	v_add_f32_e32 v50, v34, v32
	v_and_b32_e32 v32, 0xffff0000, v83
	v_add_f32_e32 v51, v35, v32
	v_mul_f32_e32 v32, v37, v37
	v_mul_f32_e32 v33, v45, v45
	v_fmac_f32_e32 v32, v36, v36
	v_fmac_f32_e32 v33, v44, v44
	v_add_f32_e32 v32, v32, v33
	v_mul_f32_e32 v33, v47, v47
	v_fmac_f32_e32 v33, v46, v46
	v_add_f32_e32 v32, v33, v32
	v_mul_f32_e32 v33, v51, v51
	v_fmac_f32_e32 v33, v50, v50
	v_add_f32_e32 v32, v33, v32
	v_add_f32_e32 v35, v53, v32
	v_cvt_pk_bf16_f32 v43, v52, v43
	ds_bpermute_b32 v52, v170, v35
	s_waitcnt lgkmcnt(1)
	v_lshlrev_b64 v[48:49], 11, v[96:97]
	v_lshl_add_u64 v[32:33], v[48:49], 1, s[12:13]
	v_lshl_add_u64 v[38:39], v[152:153], 1, v[32:33]
	global_store_dwordx4 v[38:39], v[40:43], off sc1
	s_waitcnt lgkmcnt(0)
	v_add_f32_e32 v32, v35, v52
	ds_bpermute_b32 v33, v171, v32
	v_cvt_pk_bf16_f32 v34, v36, v37
	v_cvt_pk_bf16_f32 v35, v44, v45
	v_cvt_pk_bf16_f32 v36, v46, v47
	v_cvt_pk_bf16_f32 v37, v50, v51
	global_store_dwordx4 v[38:39], v[34:37], off offset:256 sc1
	s_and_saveexec_b64 s[20:21], s[4:5]
	s_cbranch_execz .LBB0_3055
	v_lshlrev_b64 v[34:35], 7, v[96:97]
	v_lshl_add_u64 v[34:35], s[18:19], 0, v[34:35]
	s_waitcnt lgkmcnt(0)
	v_add_f32_e32 v32, v32, v33
	global_store_dword v[34:35], v32, off
; __device__ __forceinline__ unsigned cvt_pk_bf16(float lo, float hi) { unsigned r; asm volatile("v_cvt_pk_bf16_f32 %0, %1, %2" : "=v"(r) : "v"(lo), "v"(hi)); return r; }
;     __device__ __forceinline__ void operator()(const f32x4 (&acc)[2][2][4][2], const Unit& u, int wr, int wc, int fr, int fq) const {
;     ...
;             for (int m = 0; m < 4; ++m) { const int row = row0 + ai * HALF + m * 16; float ss = 0.f;
; #pragma unroll
;                 for (int bj = 0; bj < 2; ++bj) { const u32x4 ow = old[m][bj];
;                     f32x4 v0 = (acc[ai][bj][m][0] + bv[bj][0]) * accs, v1 = (acc[ai][bj][m][1] + bv[bj][1]) * accs;
;                     v0[0] += __uint_as_float(ow.x << 16); v0[1] += __uint_as_float(ow.x & 0xffff0000u); v0[2] += __uint_as_float(ow.y << 16); v0[3] += __uint_as_float(ow.y & 0xffff0000u);
;                     v1[0] += __uint_as_float(ow.z << 16); v1[1] += __uint_as_float(ow.z & 0xffff0000u); v1[2] += __uint_as_float(ow.w << 16); v1[3] += __uint_as_float(ow.w & 0xffff0000u);
;                     ss += (v0[0] * v0[0] + v0[1] * v0[1]) + (v0[2] * v0[2] + v0[3] * v0[3]) + (v1[0] * v1[0] + v1[1] * v1[1]) + (v1[2] * v1[2] + v1[3] * v1[3]);
;                     u32x4 w; w.x = cvt_pk_bf16(v0[0], v0[1]); w.y = cvt_pk_bf16(v0[2], v0[3]); w.z = cvt_pk_bf16(v1[0], v1[1]); w.w = cvt_pk_bf16(v1[2], v1[3]);
;                     *(u32x4*)(HB + (size_t)row * ldc + col0 + bj * HALF) = w; }
;                 ss += __shfl_xor(ss, 16); ss += __shfl_xor(ss, 32);
;                 if (fq == 0) ssp[(size_t)row * 32] = ss; }
.LBB0_3055:
	s_or_b64 exec, exec, s[20:21]
	v_pk_add_f32 v[28:29], v[28:29], 0 op_sel_hi:[1,0]
	s_waitcnt vmcnt(7)
	v_lshlrev_b32_e32 v34, 16, v76
	v_add_f32_e32 v28, v28, v34
	v_and_b32_e32 v34, 0xffff0000, v76
	v_pk_add_f32 v[30:31], v[30:31], 0 op_sel_hi:[1,0]
	v_add_f32_e32 v29, v29, v34
	v_lshlrev_b32_e32 v34, 16, v77
	v_add_f32_e32 v30, v30, v34
	v_and_b32_e32 v34, 0xffff0000, v77
	v_pk_add_f32 v[24:25], v[24:25], 0 op_sel_hi:[1,0]
	v_add_f32_e32 v31, v31, v34
	v_lshlrev_b32_e32 v34, 16, v78
	v_add_f32_e32 v34, v24, v34
	v_and_b32_e32 v24, 0xffff0000, v78
	v_pk_add_f32 v[26:27], v[26:27], 0 op_sel_hi:[1,0]
	v_add_f32_e32 v35, v25, v24
	v_lshlrev_b32_e32 v24, 16, v79
	v_add_f32_e32 v36, v26, v24
	v_and_b32_e32 v24, 0xffff0000, v79
	v_add_f32_e32 v27, v27, v24
	v_mul_f32_e32 v24, v29, v29
	v_mul_f32_e32 v25, v31, v31
	v_fmac_f32_e32 v24, v28, v28
	v_fmac_f32_e32 v25, v30, v30
	v_add_f32_e32 v24, v24, v25
	v_mul_f32_e32 v25, v35, v35
	v_fmac_f32_e32 v25, v34, v34
	v_add_f32_e32 v24, v25, v24
	v_mul_f32_e32 v25, v27, v27
	v_fmac_f32_e32 v25, v36, v36
	v_add_f32_e32 v37, v25, v24
	v_cvt_pk_bf16_f32 v24, v28, v29
	v_pk_add_f32 v[20:21], v[20:21], 0 op_sel_hi:[1,0]
	s_waitcnt vmcnt(6)
	v_lshlrev_b32_e32 v28, 16, v72
	v_add_f32_e32 v20, v20, v28
	v_and_b32_e32 v28, 0xffff0000, v72
	v_pk_add_f32 v[22:23], v[22:23], 0 op_sel_hi:[1,0]
	v_add_f32_e32 v21, v21, v28
	v_lshlrev_b32_e32 v28, 16, v73
	v_add_f32_e32 v28, v22, v28
	v_and_b32_e32 v22, 0xffff0000, v73
	v_pk_add_f32 v[16:17], v[16:17], 0 op_sel_hi:[1,0]
	v_add_f32_e32 v29, v23, v22
	v_lshlrev_b32_e32 v22, 16, v74
	v_cvt_pk_bf16_f32 v25, v30, v31
	v_add_f32_e32 v30, v16, v22
	v_and_b32_e32 v16, 0xffff0000, v74
	v_pk_add_f32 v[18:19], v[18:19], 0 op_sel_hi:[1,0]
	v_add_f32_e32 v31, v17, v16
	v_lshlrev_b32_e32 v16, 16, v75
	v_cvt_pk_bf16_f32 v26, v34, v35
	v_add_f32_e32 v34, v18, v16
	v_and_b32_e32 v16, 0xffff0000, v75
	v_add_f32_e32 v35, v19, v16
	v_mul_f32_e32 v16, v21, v21
	v_mul_f32_e32 v17, v29, v29
	v_fmac_f32_e32 v16, v20, v20
	v_fmac_f32_e32 v17, v28, v28
	v_add_f32_e32 v16, v16, v17
	v_mul_f32_e32 v17, v31, v31
	v_fmac_f32_e32 v17, v30, v30
	v_add_f32_e32 v16, v17, v16
	v_mul_f32_e32 v17, v35, v35
	v_fmac_f32_e32 v17, v34, v34
	v_add_f32_e32 v16, v17, v16
	v_add_f32_e32 v19, v37, v16
	v_cvt_pk_bf16_f32 v27, v36, v27
	ds_bpermute_b32 v36, v170, v19
	s_waitcnt lgkmcnt(1)
	v_lshlrev_b64 v[32:33], 11, v[94:95]
	v_lshl_add_u64 v[16:17], v[32:33], 1, s[12:13]
	v_lshl_add_u64 v[22:23], v[152:153], 1, v[16:17]
	global_store_dwordx4 v[22:23], v[24:27], off sc1
	s_waitcnt lgkmcnt(0)
	v_add_f32_e32 v16, v19, v36
	ds_bpermute_b32 v17, v171, v16
	v_cvt_pk_bf16_f32 v18, v20, v21
	v_cvt_pk_bf16_f32 v19, v28, v29
	v_cvt_pk_bf16_f32 v20, v30, v31
	v_cvt_pk_bf16_f32 v21, v34, v35
	global_store_dwordx4 v[22:23], v[18:21], off offset:256 sc1
	s_and_saveexec_b64 s[20:21], s[4:5]
	s_cbranch_execz .LBB0_3057
	v_lshlrev_b64 v[18:19], 7, v[94:95]
	v_lshl_add_u64 v[18:19], s[18:19], 0, v[18:19]
	s_waitcnt lgkmcnt(0)
	v_add_f32_e32 v16, v16, v17
	global_store_dword v[18:19], v16, off
.LBB0_3057:
	s_or_b64 exec, exec, s[20:21]
	v_pk_add_f32 v[12:13], v[12:13], 0 op_sel_hi:[1,0]
	s_waitcnt vmcnt(7)
	v_lshlrev_b32_e32 v18, 16, v68
	v_add_f32_e32 v12, v12, v18
	v_and_b32_e32 v18, 0xffff0000, v68
	v_pk_add_f32 v[14:15], v[14:15], 0 op_sel_hi:[1,0]
	v_add_f32_e32 v13, v13, v18
	v_lshlrev_b32_e32 v18, 16, v69
	v_add_f32_e32 v14, v14, v18
	v_and_b32_e32 v18, 0xffff0000, v69
	v_pk_add_f32 v[8:9], v[8:9], 0 op_sel_hi:[1,0]
	v_add_f32_e32 v15, v15, v18
	v_lshlrev_b32_e32 v18, 16, v70
	v_add_f32_e32 v18, v8, v18
	v_and_b32_e32 v8, 0xffff0000, v70
	v_pk_add_f32 v[10:11], v[10:11], 0 op_sel_hi:[1,0]
	v_add_f32_e32 v19, v9, v8
	v_lshlrev_b32_e32 v8, 16, v71
	v_add_f32_e32 v20, v10, v8
	v_and_b32_e32 v8, 0xffff0000, v71
	v_add_f32_e32 v11, v11, v8
	v_mul_f32_e32 v8, v13, v13
	v_mul_f32_e32 v9, v15, v15
	v_fmac_f32_e32 v8, v12, v12
	v_fmac_f32_e32 v9, v14, v14
	v_add_f32_e32 v8, v8, v9
	v_mul_f32_e32 v9, v19, v19
	v_fmac_f32_e32 v9, v18, v18
	v_add_f32_e32 v8, v9, v8
	v_mul_f32_e32 v9, v11, v11
	v_fmac_f32_e32 v9, v20, v20
	v_add_f32_e32 v21, v9, v8
	v_cvt_pk_bf16_f32 v8, v12, v13
	v_pk_add_f32 v[4:5], v[4:5], 0 op_sel_hi:[1,0]
	s_waitcnt vmcnt(6)
	v_lshlrev_b32_e32 v12, 16, v64
	v_add_f32_e32 v4, v4, v12
	v_and_b32_e32 v12, 0xffff0000, v64
	v_pk_add_f32 v[6:7], v[6:7], 0 op_sel_hi:[1,0]
	v_add_f32_e32 v5, v5, v12
	v_lshlrev_b32_e32 v12, 16, v65
	v_add_f32_e32 v12, v6, v12
	v_and_b32_e32 v6, 0xffff0000, v65
	v_pk_add_f32 v[0:1], v[0:1], 0 op_sel_hi:[1,0]
	v_add_f32_e32 v13, v7, v6
	v_lshlrev_b32_e32 v6, 16, v66
	v_cvt_pk_bf16_f32 v9, v14, v15
	v_add_f32_e32 v14, v0, v6
	v_and_b32_e32 v0, 0xffff0000, v66
	v_pk_add_f32 v[2:3], v[2:3], 0 op_sel_hi:[1,0]
	v_add_f32_e32 v15, v1, v0
	v_lshlrev_b32_e32 v0, 16, v67
	v_cvt_pk_bf16_f32 v10, v18, v19
	v_add_f32_e32 v18, v2, v0
	v_and_b32_e32 v0, 0xffff0000, v67
	v_add_f32_e32 v19, v3, v0
	v_mul_f32_e32 v0, v5, v5
	v_mul_f32_e32 v1, v13, v13
	v_fmac_f32_e32 v0, v4, v4
	v_fmac_f32_e32 v1, v12, v12
	v_add_f32_e32 v0, v0, v1
	v_mul_f32_e32 v1, v15, v15
	v_fmac_f32_e32 v1, v14, v14
	v_add_f32_e32 v0, v1, v0
	v_mul_f32_e32 v1, v19, v19
	v_fmac_f32_e32 v1, v18, v18
	v_add_f32_e32 v0, v1, v0
	v_add_f32_e32 v3, v21, v0
	v_cvt_pk_bf16_f32 v11, v20, v11
	ds_bpermute_b32 v20, v170, v3
	s_waitcnt lgkmcnt(1)
	v_lshlrev_b64 v[16:17], 11, v[92:93]
	v_lshl_add_u64 v[0:1], v[16:17], 1, s[12:13]
	v_lshl_add_u64 v[6:7], v[152:153], 1, v[0:1]
	global_store_dwordx4 v[6:7], v[8:11], off sc1
	s_waitcnt lgkmcnt(0)
	v_add_f32_e32 v0, v3, v20
	ds_bpermute_b32 v1, v171, v0
	v_cvt_pk_bf16_f32 v2, v4, v5
	v_cvt_pk_bf16_f32 v3, v12, v13
	v_cvt_pk_bf16_f32 v4, v14, v15
	v_cvt_pk_bf16_f32 v5, v18, v19
	global_store_dwordx4 v[6:7], v[2:5], off offset:256 sc1
	s_and_saveexec_b64 s[20:21], s[4:5]
	s_cbranch_execz .LBB0_3059
	v_lshlrev_b64 v[2:3], 7, v[92:93]
	v_lshl_add_u64 v[2:3], s[18:19], 0, v[2:3]
	s_waitcnt lgkmcnt(0)
	v_add_f32_e32 v0, v0, v1
	global_store_dword v[2:3], v0, off

; #define SSP(k) (WSP(float, WS_SS) + (size_t)(k) * T * 32)
; __device__ __forceinline__ void final_row(const bf16_t* hrow, const float* gain, const float* ssrow, float* orow, int lane) {
;     const float ss = wave_sum(lane < 32 ? ssrow[lane] : 0.f);
;     const float r = 1.0f / sqrtf(ss * (1.f / D) + EPS);
; #pragma unroll
;     for (int j = 0; j < 8; ++j) { const u32x2 hw = *(const u32x2*)(hrow + 4 * lane + 256 * j); const f32x4 g = *(const f32x4*)(gain + 4 * lane + 256 * j);
;         f32x4 o; o.x = __uint_as_float(hw.x << 16) * r * g.x; o.y = __uint_as_float(hw.x & 0xffff0000u) * r * g.y; o.z = __uint_as_float(hw.y << 16) * r * g.z; o.w = __uint_as_float(hw.y & 0xffff0000u) * r * g.w;
;         *(f32x4*)(orow + 4 * lane + 256 * j) = o; }
; __global__ void __launch_bounds__(512) mega_fwd(Params p_unused) {
;     ...
;     { IDS; KParams P = kparams(); const bf16_t* H = WSP(bf16_t, WS_XN); const float* fn = P->final_norm; float* out = P->out; const float* ss = SSP(8);
;       for (int row = gw; row < T; row += NGW) final_row(H + (size_t)row * D, fn, ss + (size_t)row * 32, out + (size_t)row * D, lane); }
.LBB0_3117:
	s_or_b64 exec, exec, s[2:3]
	v_lshl_add_u64 v[26:27], s[10:11], 0, v[14:15]
	v_add_co_u32_e32 v30, vcc, s14, v26
	s_waitcnt vmcnt(0)
	ds_bpermute_b32 v25, v16, v24
	v_addc_co_u32_e32 v31, vcc, 0, v27, vcc
	global_load_dwordx2 v[32:33], v[30:31], off
	global_load_dwordx4 v[26:29], v[0:1], off
	s_waitcnt lgkmcnt(0)
	v_add_f32_e32 v24, v24, v25
	ds_bpermute_b32 v25, v17, v24
	s_add_i32 s8, s8, s72
	v_lshl_add_u64 v[10:11], v[10:11], 0, s[4:5]
	s_cmpk_gt_i32 s8, 0x1fff
	v_lshl_add_u64 v[14:15], v[14:15], 0, s[12:13]
	s_waitcnt lgkmcnt(0)
	v_add_f32_e32 v24, v24, v25
	ds_bpermute_b32 v25, v18, v24
	s_waitcnt lgkmcnt(0)
	v_add_f32_e32 v24, v24, v25
	ds_bpermute_b32 v25, v19, v24
	s_waitcnt lgkmcnt(0)
	v_add_f32_e32 v24, v24, v25
	ds_bpermute_b32 v25, v20, v24
	s_waitcnt lgkmcnt(0)
	v_add_f32_e32 v24, v24, v25
	ds_bpermute_b32 v25, v21, v24
	s_waitcnt lgkmcnt(0)
	v_add_f32_e32 v24, v24, v25
	v_fmamk_f32 v24, v24, 0x3a000000, v22
	v_mul_f32_e32 v25, 0x4f800000, v24
	v_cmp_gt_f32_e32 vcc, s9, v24
	s_nop 1
	v_cndmask_b32_e32 v24, v24, v25, vcc
	v_sqrt_f32_e32 v25, v24
	s_nop 0
	v_add_u32_e32 v34, -1, v25
	v_add_u32_e32 v35, 1, v25
	v_fma_f32 v36, -v34, v25, v24
	v_fma_f32 v37, -v35, v25, v24
	v_cmp_ge_f32_e64 s[2:3], 0, v36
	s_nop 1
	v_cndmask_b32_e64 v25, v25, v34, s[2:3]
	v_cmp_lt_f32_e64 s[2:3], 0, v37
	s_nop 1
	v_cndmask_b32_e64 v25, v25, v35, s[2:3]
	v_mul_f32_e32 v34, 0x37800000, v25
	v_cndmask_b32_e32 v25, v25, v34, vcc
	v_cmp_class_f32_e32 vcc, v24, v23
	s_nop 1
	v_cndmask_b32_e32 v24, v25, v24, vcc
	v_div_scale_f32 v25, s[2:3], v24, v24, 1.0
	v_rcp_f32_e32 v36, v25
	v_add_co_u32_e32 v34, vcc, s15, v12
	v_fma_f32 v38, -v25, v36, 1.0
	s_nop 0
	v_addc_co_u32_e32 v35, vcc, -1, v13, vcc
	v_div_scale_f32 v37, vcc, 1.0, v24, 1.0
	v_fmac_f32_e32 v36, v38, v36
	v_mul_f32_e32 v38, v37, v36
	v_fma_f32 v39, -v25, v38, v37
	v_fmac_f32_e32 v38, v39, v36
	v_fma_f32 v25, -v25, v38, v37
	v_div_fmas_f32 v25, v25, v36, v38
	v_div_fixup_f32 v36, v25, v24, 1.0
	s_waitcnt vmcnt(1)
	v_lshlrev_b32_e32 v24, 16, v32
	v_and_b32_e32 v25, 0xffff0000, v32
	v_lshlrev_b32_e32 v32, 16, v33
	v_and_b32_e32 v33, 0xffff0000, v33
	v_pk_mul_f32 v[24:25], v[36:37], v[24:25] op_sel_hi:[0,1]
	v_pk_mul_f32 v[32:33], v[36:37], v[32:33] op_sel_hi:[0,1]
	s_waitcnt vmcnt(0)
	v_pk_mul_f32 v[24:25], v[26:27], v[24:25]
	v_pk_mul_f32 v[26:27], v[28:29], v[32:33]
	global_store_dwordx4 v[34:35], v[24:27], off offset:-3072 sc1
	global_load_dwordx2 v[28:29], v[30:31], off offset:512
	s_nop 0
	global_load_dwordx4 v[24:27], v[0:1], off offset:1024
	s_waitcnt vmcnt(1)
	v_lshlrev_b32_e32 v32, 16, v28
	v_and_b32_e32 v33, 0xffff0000, v28
	v_lshlrev_b32_e32 v28, 16, v29
	v_and_b32_e32 v29, 0xffff0000, v29
	v_pk_mul_f32 v[32:33], v[36:37], v[32:33] op_sel_hi:[0,1]
	v_pk_mul_f32 v[28:29], v[36:37], v[28:29] op_sel_hi:[0,1]
	s_waitcnt vmcnt(0)
	v_pk_mul_f32 v[24:25], v[24:25], v[32:33]
	v_pk_mul_f32 v[26:27], v[26:27], v[28:29]
	global_store_dwordx4 v[34:35], v[24:27], off offset:-2048 sc1
	global_load_dwordx2 v[28:29], v[30:31], off offset:1024
	s_nop 0
	global_load_dwordx4 v[24:27], v[0:1], off offset:2048
	s_waitcnt vmcnt(1)
	v_lshlrev_b32_e32 v32, 16, v28
	v_and_b32_e32 v33, 0xffff0000, v28
	v_lshlrev_b32_e32 v28, 16, v29
	v_and_b32_e32 v29, 0xffff0000, v29
	v_pk_mul_f32 v[32:33], v[36:37], v[32:33] op_sel_hi:[0,1]
	v_pk_mul_f32 v[28:29], v[36:37], v[28:29] op_sel_hi:[0,1]
	s_waitcnt vmcnt(0)
	v_pk_mul_f32 v[24:25], v[24:25], v[32:33]
	v_pk_mul_f32 v[26:27], v[26:27], v[28:29]
	global_store_dwordx4 v[34:35], v[24:27], off offset:-1024 sc1
	global_load_dwordx2 v[28:29], v[30:31], off offset:1536
	s_nop 0
	global_load_dwordx4 v[24:27], v[0:1], off offset:3072
	s_waitcnt vmcnt(1)
	v_lshlrev_b32_e32 v32, 16, v28
	v_and_b32_e32 v33, 0xffff0000, v28
	v_lshlrev_b32_e32 v28, 16, v29
	v_and_b32_e32 v29, 0xffff0000, v29
	v_pk_mul_f32 v[32:33], v[36:37], v[32:33] op_sel_hi:[0,1]
	v_pk_mul_f32 v[28:29], v[36:37], v[28:29] op_sel_hi:[0,1]
	s_waitcnt vmcnt(0)
	v_pk_mul_f32 v[24:25], v[24:25], v[32:33]
	v_pk_mul_f32 v[26:27], v[26:27], v[28:29]
	global_store_dwordx4 v[12:13], v[24:27], off offset:-4096 sc1
	global_load_dwordx2 v[28:29], v[30:31], off offset:2048
	s_nop 0
	global_load_dwordx4 v[24:27], v[2:3], off
	s_waitcnt vmcnt(1)
	v_lshlrev_b32_e32 v32, 16, v28
	v_and_b32_e32 v33, 0xffff0000, v28
	v_lshlrev_b32_e32 v28, 16, v29
	v_and_b32_e32 v29, 0xffff0000, v29
	v_pk_mul_f32 v[32:33], v[36:37], v[32:33] op_sel_hi:[0,1]
	v_pk_mul_f32 v[28:29], v[36:37], v[28:29] op_sel_hi:[0,1]
	s_waitcnt vmcnt(0)
	v_pk_mul_f32 v[24:25], v[24:25], v[32:33]
	v_pk_mul_f32 v[26:27], v[26:27], v[28:29]
	global_store_dwordx4 v[12:13], v[24:27], off offset:-3072 sc1
	global_load_dwordx2 v[28:29], v[30:31], off offset:2560
	s_nop 0
	global_load_dwordx4 v[24:27], v[4:5], off
	s_waitcnt vmcnt(1)
	v_lshlrev_b32_e32 v32, 16, v28
	v_and_b32_e32 v33, 0xffff0000, v28
	v_lshlrev_b32_e32 v28, 16, v29
	v_and_b32_e32 v29, 0xffff0000, v29
	v_pk_mul_f32 v[32:33], v[36:37], v[32:33] op_sel_hi:[0,1]
	v_pk_mul_f32 v[28:29], v[36:37], v[28:29] op_sel_hi:[0,1]
	s_waitcnt vmcnt(0)
	v_pk_mul_f32 v[24:25], v[24:25], v[32:33]
	v_pk_mul_f32 v[26:27], v[26:27], v[28:29]
	global_store_dwordx4 v[12:13], v[24:27], off offset:-2048 sc1
	global_load_dwordx2 v[28:29], v[30:31], off offset:3072
	s_nop 0
	global_load_dwordx4 v[24:27], v[6:7], off
	s_waitcnt vmcnt(1)
	v_lshlrev_b32_e32 v32, 16, v28
	v_and_b32_e32 v33, 0xffff0000, v28
	v_lshlrev_b32_e32 v28, 16, v29
	v_and_b32_e32 v29, 0xffff0000, v29
	v_pk_mul_f32 v[32:33], v[36:37], v[32:33] op_sel_hi:[0,1]
	v_pk_mul_f32 v[28:29], v[36:37], v[28:29] op_sel_hi:[0,1]
	s_waitcnt vmcnt(0)
	v_pk_mul_f32 v[24:25], v[24:25], v[32:33]
	v_pk_mul_f32 v[26:27], v[26:27], v[28:29]
	global_store_dwordx4 v[12:13], v[24:27], off offset:-1024 sc1
	global_load_dwordx2 v[28:29], v[30:31], off offset:3584
	s_nop 0
	global_load_dwordx4 v[24:27], v[8:9], off
	s_waitcnt vmcnt(1)
	v_lshlrev_b32_e32 v30, 16, v28
	v_and_b32_e32 v31, 0xffff0000, v28
	v_lshlrev_b32_e32 v28, 16, v29
	v_and_b32_e32 v29, 0xffff0000, v29
	v_pk_mul_f32 v[30:31], v[36:37], v[30:31] op_sel_hi:[0,1]
	v_pk_mul_f32 v[28:29], v[36:37], v[28:29] op_sel_hi:[0,1]
	s_waitcnt vmcnt(0)
	v_pk_mul_f32 v[24:25], v[24:25], v[30:31]
	v_pk_mul_f32 v[26:27], v[26:27], v[28:29]
	global_store_dwordx4 v[12:13], v[24:27], off sc1
	v_lshl_add_u64 v[12:13], v[12:13], 0, s[6:7]
	s_cbranch_scc1 .LBB0_3120
